# pipelined dil loop: exp split 2 before global-load wait, 2 before LDS wait, 3 between each dependent QK MFMA
# baseline (speedup 1.0000x reference)
; #define LAS __attribute__((address_space(3)))
; #define GAS __attribute__((address_space(1)))
; __device__ __forceinline__ void dil_unit(LAS unsigned char* lds, bf16_t* proj, int seq, int hd, int T0, int rho) {
;     int tid_ = threadIdx.x; asm volatile("" : "+v"(tid_));
;     const int tid = tid_, lane = tid & 63, r32 = lane & 31, hi = lane >> 5, wid = __builtin_amdgcn_readfirstlane(tid >> 6);
;     bf16_t* base = proj + (size_t)seq * SEQ * NIN;
;     LAS unsigned char* wbuf = lds + wid * 4096;
;     const LAS unsigned char* vp = wbuf + ((lane >> 4) & 1) * 32 + (lane & 3) * 8 + (4 * hi + ((lane & 15) >> 2)) * 64;
;     const int P0 = T0 + rho;
;     bf16x8 qr[4];
; #pragma unroll
;     for (int ks = 0; ks < 4; ++ks) qr[ks] = *(const GAS bf16x8*)(base + (size_t)(P0 + 16 * r32) * NIN + PC_LQ + hd * 64 + 16 * ks + 8 * hi);
;     f32x16 o0 = {}, o1 = {}; float l = 0.f;
;     const bool bound = (T0 < 1024) || (T0 >= 15360);
.LBB0_554:
	s_lshr_b32 s82, s33, 8
	s_mul_i32 s82, s82, 13
	s_add_i32 s82, s82, s33
	s_ashr_i32 s2, s33, 6
	s_mul_hi_i32 s7, s2, 0x2aaaaaab
	s_lshl_b32 s3, s82, 8
	s_lshr_b32 s8, s7, 31
	s_and_b32 s6, s3, 0x3e00
	s_lshl_b32 s3, s82, 3
	s_add_i32 s7, s7, s8
	s_and_b32 s3, s3, 8
	s_mul_i32 s8, s7, 6
	s_add_i32 s3, s3, s64
	s_sub_i32 s8, s2, s8
	s_mul_hi_i32 s2, s7, 0x6000000
	s_mul_i32 s7, s7, 0x6000000
	v_mov_b32_e32 v2, v154
	s_add_u32 s56, s48, s7
	s_addc_u32 s57, s49, s2
	v_and_b32_e32 v105, 31, v2
	s_add_i32 s76, s3, s6
	v_lshl_add_u32 v3, v105, 4, s76
	v_mov_b64_e32 v[0:1], s[56:57]
	s_lshl_b32 s58, s8, 6
	v_bfe_u32 v106, v2, 5, 1
	v_mad_u64_u32 v[0:1], s[2:3], v3, s65, v[0:1]
	s_ashr_i32 s59, s58, 31
	v_lshl_add_u64 v[0:1], s[58:59], 1, v[0:1]
	v_lshlrev_b32_e32 v80, 4, v106
	v_lshl_add_u64 v[0:1], v[0:1], 0, v[80:81]
	global_load_dwordx4 v[48:51], v[0:1], off offset:1280
	global_load_dwordx4 v[52:55], v[0:1], off offset:1312
	global_load_dwordx4 v[56:59], v[0:1], off offset:1344
	global_load_dwordx4 v[60:63], v[0:1], off offset:1376
	v_readfirstlane_b32 s2, v2
	s_lshl_b32 s2, s2, 6
	s_and_b32 s2, s2, 0xfffff000
	v_lshlrev_b32_e32 v0, 1, v2
	v_lshlrev_b32_e32 v104, 3, v2
	v_lshlrev_b32_e32 v107, 2, v106
	v_lshrrev_b32_e32 v1, 2, v2
	v_and_b32_e32 v103, 63, v2
	v_and_b32_e32 v0, 32, v0
	v_and_b32_e32 v98, 24, v104
	v_and_or_b32 v1, v1, 3, v107
	s_add_i32 s77, s2, 0
	v_lshlrev_b32_e32 v108, 6, v1
	v_lshlrev_b32_e32 v1, 3, v106
	v_add3_u32 v109, s77, v0, v98
	s_addk_i32 s6, 0xc400
	v_lshrrev_b32_e32 v110, 2, v103
	v_lshlrev_b32_e32 v0, 4, v103
	s_mov_b64 s[2:3], -1
	s_cmp_gt_u32 s6, 0xffffc7ff
	v_lshlrev_b32_e32 v100, 1, v98
	s_mul_i32 s6, s8, 0x1c00
	v_lshlrev_b32_e32 v82, 1, v1
	v_or_b32_e32 v111, 16, v110
	v_add_u32_e32 v112, s77, v0
	s_cbranch_scc0 .LBB0_558
	s_movk_i32 s100, 0x1800
	s_add_i32 s101, s6, 0x15c00
	s_lshl_b32 s90, s58, 1
	s_add_u32 s82, s56, s90
	s_addc_u32 s83, s57, 0
	s_add_u32 s82, s82, 0x1200
	s_addc_u32 s83, s83, 0
	s_sub_i32 s90, s76, 64
	s_mul_i32 s90, s90, 0x1800
	s_add_u32 s84, s82, s90
	s_addc_u32 s85, s83, 0
	s_sub_i32 s90, s76, 256
	s_mul_i32 s90, s90, 0x1800
	s_add_u32 s86, s82, s90
	s_addc_u32 s87, s83, 0
	s_sub_i32 s90, s76, 1024
	s_mul_i32 s90, s90, 0x1800
	s_add_u32 s88, s82, s90
	s_addc_u32 s89, s83, 0
	v_lshlrev_b32_e32 v153, 1, v98
	v_mad_u32_u24 v80, v105, s100, v82
	v_mad_u32_u24 v100, v110, s100, v153
	v_add_u32_e32 v149, 0x18000, v100
	v_lshlrev_b32_e32 v83, 2, v105
	v_mad_u32_u24 v83, v83, s100, v82
	v_lshlrev_b32_e32 v101, 2, v110
	v_mad_u32_u24 v101, v101, s100, v153
	v_add_u32_e32 v150, 0x60000, v101
	v_lshlrev_b32_e32 v99, 4, v105
	v_mad_u32_u24 v99, v99, s100, v82
	v_lshlrev_b32_e32 v148, 4, v110
	v_mad_u32_u24 v148, v148, s100, v153
	v_add_u32_e32 v151, 0x180000, v148
	v_lshrrev_b32_e32 v249, 3, v103
	v_and_b32_e32 v250, 7, v103
	v_lshlrev_b32_e32 v250, 4, v250
	v_add_u32_e32 v235, 0, v249
	v_mad_u32_u24 v235, v235, s100, v250
	v_add_u32_e32 v236, 8, v249
	v_mad_u32_u24 v236, v236, s100, v250
	v_add_u32_e32 v237, 16, v249
	v_mad_u32_u24 v237, v237, s100, v250
	v_add_u32_e32 v238, 24, v249
	v_mad_u32_u24 v238, v238, s100, v250
	v_add_u32_e32 v239, 0, v249
	v_lshlrev_b32_e32 v239, 2, v239
	v_mad_u32_u24 v239, v239, s100, v250
	v_add_u32_e32 v240, 8, v249
	v_lshlrev_b32_e32 v240, 2, v240
	v_mad_u32_u24 v240, v240, s100, v250
	v_add_u32_e32 v241, 16, v249
	v_lshlrev_b32_e32 v241, 2, v241
	v_mad_u32_u24 v241, v241, s100, v250
	v_add_u32_e32 v242, 24, v249
	v_lshlrev_b32_e32 v242, 2, v242
	v_mad_u32_u24 v242, v242, s100, v250
	v_add_u32_e32 v243, 0, v249
	v_lshlrev_b32_e32 v243, 4, v243
	v_mad_u32_u24 v243, v243, s100, v250
	v_add_u32_e32 v244, 8, v249
	v_lshlrev_b32_e32 v244, 4, v244
	v_mad_u32_u24 v244, v244, s100, v250
	v_add_u32_e32 v245, 16, v249
	v_lshlrev_b32_e32 v245, 4, v245
	v_mad_u32_u24 v245, v245, s100, v250
	v_add_u32_e32 v246, 24, v249
	v_lshlrev_b32_e32 v246, 4, v246
	v_mad_u32_u24 v246, v246, s100, v250
	v_and_b32_e32 v247, 7, v249
	v_lshlrev_b32_e32 v247, 4, v247
	v_xor_b32_e32 v247, v247, v112
	v_and_b32_e32 v153, 7, v105
	v_or_b32_e32 v248, 0, v106
	v_xor_b32_e32 v248, v248, v153
	v_lshlrev_b32_e32 v248, 4, v248
	v_lshl_add_u32 v248, v105, 7, v248
	v_add_u32_e32 v248, s77, v248
	v_or_b32_e32 v249, 2, v106
	v_xor_b32_e32 v249, v249, v153
	v_lshlrev_b32_e32 v249, 4, v249
	v_lshl_add_u32 v249, v105, 7, v249
	v_add_u32_e32 v249, s77, v249
	v_or_b32_e32 v250, 4, v106
	v_xor_b32_e32 v250, v250, v153
	v_lshlrev_b32_e32 v250, 4, v250
	v_lshl_add_u32 v250, v105, 7, v250
	v_add_u32_e32 v250, s77, v250
	v_or_b32_e32 v251, 6, v106
	v_xor_b32_e32 v251, v251, v153
	v_lshlrev_b32_e32 v251, 4, v251
	v_lshl_add_u32 v251, v105, 7, v251
	v_add_u32_e32 v251, s77, v251
	v_lshlrev_b32_e32 v153, 1, v98
	v_mul_u32_u24_e32 v228, 17, v105
	v_sub_u32_e32 v228, v107, v228
	s_mul_i32 s90, s58, 153
	s_lshr_b32 s90, s90, 1
	s_add_i32 s90, s90, 34876
	v_lshl_add_u32 v228, v228, 2, s90
	v_lshlrev_b32_e32 v229, 2, v105
	v_sub_u32_e32 v229, v107, v229
	s_add_i32 s90, s101, 5104
	v_lshl_add_u32 v229, v229, 2, s90
	v_sub_u32_e32 v230, v107, v105
	s_add_i32 s90, s101, 6364
	v_lshl_add_u32 v230, v230, 2, s90
	v_add_u32_e32 v231, v109, v108
	v_mov_b64_e32 v[232:233], 0
	v_mov_b64_e32 v[0:1], 0
	v_mov_b64_e32 v[2:3], 0
	v_mov_b64_e32 v[4:5], 0
	v_mov_b64_e32 v[6:7], 0
	v_mov_b64_e32 v[8:9], 0
	v_mov_b64_e32 v[10:11], 0
	v_mov_b64_e32 v[12:13], 0
	v_mov_b64_e32 v[14:15], 0
	v_mov_b64_e32 v[16:17], 0
	v_mov_b64_e32 v[18:19], 0
	v_mov_b64_e32 v[20:21], 0
	v_mov_b64_e32 v[22:23], 0
	v_mov_b64_e32 v[24:25], 0
	v_mov_b64_e32 v[26:27], 0
	v_mov_b64_e32 v[28:29], 0
	v_mov_b64_e32 v[30:31], 0
	global_load_dwordx4 v[116:119], v235, s[84:85]
	global_load_dwordx4 v[120:123], v236, s[84:85]
	global_load_dwordx4 v[124:127], v237, s[84:85]
	global_load_dwordx4 v[128:131], v238, s[84:85]
	global_load_dwordx4 v[132:135], v100, s[84:85] offset:768
	global_load_dwordx4 v[136:139], v149, s[84:85] offset:768
	global_load_dwordx4 v[140:143], v100, s[84:85] offset:832
	global_load_dwordx4 v[144:147], v149, s[84:85] offset:832
	s_add_u32 s84, s84, 0x30000
	s_addc_u32 s85, s85, 0
	global_load_dwordx4 v[156:159], v235, s[84:85]
	global_load_dwordx4 v[160:163], v236, s[84:85]
	global_load_dwordx4 v[164:167], v237, s[84:85]
	global_load_dwordx4 v[168:171], v238, s[84:85]
	global_load_dwordx4 v[172:175], v100, s[84:85] offset:768
	global_load_dwordx4 v[176:179], v149, s[84:85] offset:768
	global_load_dwordx4 v[180:183], v100, s[84:85] offset:832
	global_load_dwordx4 v[184:187], v149, s[84:85] offset:832
	s_add_u32 s84, s84, 0x30000
	s_addc_u32 s85, s85, 0
	v_mov_b32_e32 v115, v228
	ds_read2_b32 v[32:33], v115 offset0:0 offset1:1
	ds_read2_b32 v[34:35], v115 offset0:2 offset1:3
	ds_read2_b32 v[36:37], v115 offset0:8 offset1:9
	ds_read2_b32 v[38:39], v115 offset0:10 offset1:11
	ds_read2_b32 v[40:41], v115 offset0:17 offset1:18
	ds_read2_b32 v[42:43], v115 offset0:19 offset1:20
	ds_read2_b32 v[44:45], v115 offset0:25 offset1:26
	ds_read2_b32 v[46:47], v115 offset0:27 offset1:28
	s_waitcnt vmcnt(8)
	ds_write_b128 v247, v[116:119]
	ds_write_b128 v247, v[120:123] offset:1024
	ds_write_b128 v247, v[124:127] offset:2048
	ds_write_b128 v247, v[128:131] offset:3072
	ds_read_b128 v[116:119], v248
	ds_read_b128 v[120:123], v249
	ds_read_b128 v[124:127], v250
	ds_read_b128 v[128:131], v251
	ds_write_b128 v112, v[132:135]
	ds_write_b128 v112, v[136:139] offset:1024
	ds_write_b128 v112, v[140:143] offset:2048
	ds_write_b128 v112, v[144:147] offset:3072
	s_waitcnt lgkmcnt(4)
	v_mfma_f32_32x32x16_bf16 v[32:47], v[116:119], v[48:51], v[32:47]
	v_mfma_f32_32x32x16_bf16 v[32:47], v[120:123], v[52:55], v[32:47]
	v_mfma_f32_32x32x16_bf16 v[32:47], v[124:127], v[56:59], v[32:47]
	v_mfma_f32_32x32x16_bf16 v[32:47], v[128:131], v[60:63], v[32:47]
	ds_read2_b32 v[188:189], v115 offset0:34 offset1:35
	ds_read2_b32 v[190:191], v115 offset0:36 offset1:37
	ds_read2_b32 v[192:193], v115 offset0:42 offset1:43
	ds_read2_b32 v[194:195], v115 offset0:44 offset1:45
	ds_read2_b32 v[196:197], v115 offset0:51 offset1:52
	ds_read2_b32 v[198:199], v115 offset0:53 offset1:54
	ds_read2_b32 v[200:201], v115 offset0:59 offset1:60
	ds_read2_b32 v[202:203], v115 offset0:61 offset1:62
	global_load_dwordx4 v[116:119], v235, s[84:85]
	global_load_dwordx4 v[120:123], v236, s[84:85]
	global_load_dwordx4 v[124:127], v237, s[84:85]
	global_load_dwordx4 v[128:131], v238, s[84:85]
	global_load_dwordx4 v[132:135], v100, s[84:85] offset:768
	global_load_dwordx4 v[136:139], v149, s[84:85] offset:768
	global_load_dwordx4 v[140:143], v100, s[84:85] offset:832
	global_load_dwordx4 v[144:147], v149, s[84:85] offset:832
	s_add_u32 s84, s84, 0x30000
	s_addc_u32 s85, s85, 0
	ds_read_b64_tr_b16 v[72:73], v231
	ds_read_b64_tr_b16 v[74:75], v231 offset:512
	ds_read_b64_tr_b16 v[76:77], v231 offset:2048
	ds_read_b64_tr_b16 v[78:79], v231 offset:2560
	ds_read_b64_tr_b16 v[220:221], v231 offset:1024
	ds_read_b64_tr_b16 v[222:223], v231 offset:1536
	ds_read_b64_tr_b16 v[224:225], v231 offset:3072
	ds_read_b64_tr_b16 v[226:227], v231 offset:3584
	v_exp_f32_e32 v32, v32
	v_exp_f32_e32 v33, v33
	s_waitcnt vmcnt(8)
	ds_write_b128 v247, v[156:159]
	ds_write_b128 v247, v[160:163] offset:1024
	ds_write_b128 v247, v[164:167] offset:2048
	ds_write_b128 v247, v[168:171] offset:3072
	ds_read_b128 v[156:159], v248
	ds_read_b128 v[160:163], v249
	ds_read_b128 v[164:167], v250
	ds_read_b128 v[168:171], v251
	ds_write_b128 v112, v[172:175]
	ds_write_b128 v112, v[176:179] offset:1024
	ds_write_b128 v112, v[180:183] offset:2048
	ds_write_b128 v112, v[184:187] offset:3072
	v_exp_f32_e32 v34, v34
	v_exp_f32_e32 v35, v35
	s_waitcnt lgkmcnt(4)
	v_mfma_f32_32x32x16_bf16 v[188:203], v[156:159], v[48:51], v[188:203]
	v_exp_f32_e32 v36, v36
	v_exp_f32_e32 v37, v37
	v_exp_f32_e32 v38, v38
	v_mfma_f32_32x32x16_bf16 v[188:203], v[160:163], v[52:55], v[188:203]
	v_exp_f32_e32 v39, v39
	v_exp_f32_e32 v40, v40
	v_exp_f32_e32 v41, v41
	v_mfma_f32_32x32x16_bf16 v[188:203], v[164:167], v[56:59], v[188:203]
	v_exp_f32_e32 v42, v42
	v_exp_f32_e32 v43, v43
	v_exp_f32_e32 v44, v44
	v_mfma_f32_32x32x16_bf16 v[188:203], v[168:171], v[60:63], v[188:203]
	v_exp_f32_e32 v45, v45
	v_exp_f32_e32 v46, v46
	v_exp_f32_e32 v47, v47
	v_cvt_pk_bf16_f32 v64, v32, v33
	v_cvt_pk_bf16_f32 v65, v34, v35
	v_cvt_pk_bf16_f32 v66, v36, v37
	v_cvt_pk_bf16_f32 v67, v38, v39
	v_cvt_pk_bf16_f32 v68, v40, v41
	v_cvt_pk_bf16_f32 v69, v42, v43
	v_cvt_pk_bf16_f32 v70, v44, v45
	v_cvt_pk_bf16_f32 v71, v46, v47
	v_pk_add_f32 v[232:233], v[232:233], v[32:33]
	v_pk_add_f32 v[232:233], v[232:233], v[34:35]
	v_pk_add_f32 v[232:233], v[232:233], v[36:37]
	v_pk_add_f32 v[232:233], v[232:233], v[38:39]
	v_pk_add_f32 v[232:233], v[232:233], v[40:41]
	v_pk_add_f32 v[232:233], v[232:233], v[42:43]
	v_pk_add_f32 v[232:233], v[232:233], v[44:45]
	v_pk_add_f32 v[232:233], v[232:233], v[46:47]
	ds_read2_b32 v[32:33], v115 offset0:68 offset1:69
	ds_read2_b32 v[34:35], v115 offset0:70 offset1:71
	ds_read2_b32 v[36:37], v115 offset0:76 offset1:77
	ds_read2_b32 v[38:39], v115 offset0:78 offset1:79
	ds_read2_b32 v[40:41], v115 offset0:85 offset1:86
	ds_read2_b32 v[42:43], v115 offset0:87 offset1:88
	ds_read2_b32 v[44:45], v115 offset0:93 offset1:94
	ds_read2_b32 v[46:47], v115 offset0:95 offset1:96
	v_mfma_f32_32x32x16_bf16 v[0:15], v[64:67], v[72:75], v[0:15]
	v_mfma_f32_32x32x16_bf16 v[16:31], v[64:67], v[76:79], v[16:31]
	v_mfma_f32_32x32x16_bf16 v[0:15], v[68:71], v[220:223], v[0:15]
	v_mfma_f32_32x32x16_bf16 v[16:31], v[68:71], v[224:227], v[16:31]
	global_load_dwordx4 v[156:159], v235, s[84:85]
	global_load_dwordx4 v[160:163], v236, s[84:85]
	global_load_dwordx4 v[164:167], v237, s[84:85]
	global_load_dwordx4 v[168:171], v238, s[84:85]
	global_load_dwordx4 v[172:175], v100, s[84:85] offset:768
	global_load_dwordx4 v[176:179], v149, s[84:85] offset:768
	global_load_dwordx4 v[180:183], v100, s[84:85] offset:832
	global_load_dwordx4 v[184:187], v149, s[84:85] offset:832
	s_add_u32 s84, s84, 0x30000
	s_addc_u32 s85, s85, 0
	ds_read_b64_tr_b16 v[72:73], v231
	ds_read_b64_tr_b16 v[74:75], v231 offset:512
	ds_read_b64_tr_b16 v[76:77], v231 offset:2048
	ds_read_b64_tr_b16 v[78:79], v231 offset:2560
	ds_read_b64_tr_b16 v[220:221], v231 offset:1024
	ds_read_b64_tr_b16 v[222:223], v231 offset:1536
	ds_read_b64_tr_b16 v[224:225], v231 offset:3072
	ds_read_b64_tr_b16 v[226:227], v231 offset:3584
	v_exp_f32_e32 v188, v188
	v_exp_f32_e32 v189, v189
	s_waitcnt vmcnt(8)
	ds_write_b128 v247, v[116:119]
	ds_write_b128 v247, v[120:123] offset:1024
	ds_write_b128 v247, v[124:127] offset:2048
	ds_write_b128 v247, v[128:131] offset:3072
	ds_read_b128 v[116:119], v248
	ds_read_b128 v[120:123], v249
	ds_read_b128 v[124:127], v250
	ds_read_b128 v[128:131], v251
	ds_write_b128 v112, v[132:135]
	ds_write_b128 v112, v[136:139] offset:1024
	ds_write_b128 v112, v[140:143] offset:2048
	ds_write_b128 v112, v[144:147] offset:3072
	v_exp_f32_e32 v190, v190
	v_exp_f32_e32 v191, v191
	s_waitcnt lgkmcnt(4)
	v_mfma_f32_32x32x16_bf16 v[32:47], v[116:119], v[48:51], v[32:47]
	v_exp_f32_e32 v192, v192
	v_exp_f32_e32 v193, v193
	v_exp_f32_e32 v194, v194
	v_mfma_f32_32x32x16_bf16 v[32:47], v[120:123], v[52:55], v[32:47]
	v_exp_f32_e32 v195, v195
	v_exp_f32_e32 v196, v196
	v_exp_f32_e32 v197, v197
	v_mfma_f32_32x32x16_bf16 v[32:47], v[124:127], v[56:59], v[32:47]
	v_exp_f32_e32 v198, v198
	v_exp_f32_e32 v199, v199
	v_exp_f32_e32 v200, v200
	v_mfma_f32_32x32x16_bf16 v[32:47], v[128:131], v[60:63], v[32:47]
	v_exp_f32_e32 v201, v201
	v_exp_f32_e32 v202, v202
	v_exp_f32_e32 v203, v203
	v_cvt_pk_bf16_f32 v64, v188, v189
	v_cvt_pk_bf16_f32 v65, v190, v191
	v_cvt_pk_bf16_f32 v66, v192, v193
	v_cvt_pk_bf16_f32 v67, v194, v195
	v_cvt_pk_bf16_f32 v68, v196, v197
	v_cvt_pk_bf16_f32 v69, v198, v199
	v_cvt_pk_bf16_f32 v70, v200, v201
	v_cvt_pk_bf16_f32 v71, v202, v203
	v_pk_add_f32 v[232:233], v[232:233], v[188:189]
	v_pk_add_f32 v[232:233], v[232:233], v[190:191]
	v_pk_add_f32 v[232:233], v[232:233], v[192:193]
	v_pk_add_f32 v[232:233], v[232:233], v[194:195]
	v_pk_add_f32 v[232:233], v[232:233], v[196:197]
	v_pk_add_f32 v[232:233], v[232:233], v[198:199]
	v_pk_add_f32 v[232:233], v[232:233], v[200:201]
	v_pk_add_f32 v[232:233], v[232:233], v[202:203]
	ds_read2_b32 v[188:189], v115 offset0:102 offset1:103
	ds_read2_b32 v[190:191], v115 offset0:104 offset1:105
	ds_read2_b32 v[192:193], v115 offset0:110 offset1:111
	ds_read2_b32 v[194:195], v115 offset0:112 offset1:113
	ds_read2_b32 v[196:197], v115 offset0:119 offset1:120
	ds_read2_b32 v[198:199], v115 offset0:121 offset1:122
	ds_read2_b32 v[200:201], v115 offset0:127 offset1:128
	ds_read2_b32 v[202:203], v115 offset0:129 offset1:130
	v_mfma_f32_32x32x16_bf16 v[0:15], v[64:67], v[72:75], v[0:15]
	v_mfma_f32_32x32x16_bf16 v[16:31], v[64:67], v[76:79], v[16:31]
	v_mfma_f32_32x32x16_bf16 v[0:15], v[68:71], v[220:223], v[0:15]
	v_mfma_f32_32x32x16_bf16 v[16:31], v[68:71], v[224:227], v[16:31]
	global_load_dwordx4 v[116:119], v235, s[84:85]
	global_load_dwordx4 v[120:123], v236, s[84:85]
	global_load_dwordx4 v[124:127], v237, s[84:85]
	global_load_dwordx4 v[128:131], v238, s[84:85]
	global_load_dwordx4 v[132:135], v100, s[84:85] offset:768
	global_load_dwordx4 v[136:139], v149, s[84:85] offset:768
	global_load_dwordx4 v[140:143], v100, s[84:85] offset:832
	global_load_dwordx4 v[144:147], v149, s[84:85] offset:832
	s_add_u32 s84, s84, 0x30000
	s_addc_u32 s85, s85, 0
	ds_read_b64_tr_b16 v[72:73], v231
	ds_read_b64_tr_b16 v[74:75], v231 offset:512
	ds_read_b64_tr_b16 v[76:77], v231 offset:2048
	ds_read_b64_tr_b16 v[78:79], v231 offset:2560
	ds_read_b64_tr_b16 v[220:221], v231 offset:1024
	ds_read_b64_tr_b16 v[222:223], v231 offset:1536
	ds_read_b64_tr_b16 v[224:225], v231 offset:3072
	ds_read_b64_tr_b16 v[226:227], v231 offset:3584
	v_exp_f32_e32 v32, v32
	v_exp_f32_e32 v33, v33
	s_waitcnt vmcnt(8)
	ds_write_b128 v247, v[156:159]
	ds_write_b128 v247, v[160:163] offset:1024
	ds_write_b128 v247, v[164:167] offset:2048
	ds_write_b128 v247, v[168:171] offset:3072
	ds_read_b128 v[156:159], v248
	ds_read_b128 v[160:163], v249
	ds_read_b128 v[164:167], v250
	ds_read_b128 v[168:171], v251
	ds_write_b128 v112, v[172:175]
	ds_write_b128 v112, v[176:179] offset:1024
	ds_write_b128 v112, v[180:183] offset:2048
	ds_write_b128 v112, v[184:187] offset:3072
	v_exp_f32_e32 v34, v34
	v_exp_f32_e32 v35, v35
	s_waitcnt lgkmcnt(4)
	v_mfma_f32_32x32x16_bf16 v[188:203], v[156:159], v[48:51], v[188:203]
	v_exp_f32_e32 v36, v36
	v_exp_f32_e32 v37, v37
	v_exp_f32_e32 v38, v38
	v_mfma_f32_32x32x16_bf16 v[188:203], v[160:163], v[52:55], v[188:203]
	v_exp_f32_e32 v39, v39
	v_exp_f32_e32 v40, v40
	v_exp_f32_e32 v41, v41
	v_mfma_f32_32x32x16_bf16 v[188:203], v[164:167], v[56:59], v[188:203]
	v_exp_f32_e32 v42, v42
	v_exp_f32_e32 v43, v43
	v_exp_f32_e32 v44, v44
	v_mfma_f32_32x32x16_bf16 v[188:203], v[168:171], v[60:63], v[188:203]
	v_exp_f32_e32 v45, v45
	v_exp_f32_e32 v46, v46
	v_exp_f32_e32 v47, v47
	v_cvt_pk_bf16_f32 v64, v32, v33
	v_cvt_pk_bf16_f32 v65, v34, v35
	v_cvt_pk_bf16_f32 v66, v36, v37
	v_cvt_pk_bf16_f32 v67, v38, v39
	v_cvt_pk_bf16_f32 v68, v40, v41
	v_cvt_pk_bf16_f32 v69, v42, v43
	v_cvt_pk_bf16_f32 v70, v44, v45
	v_cvt_pk_bf16_f32 v71, v46, v47
	v_pk_add_f32 v[232:233], v[232:233], v[32:33]
	v_pk_add_f32 v[232:233], v[232:233], v[34:35]
	v_pk_add_f32 v[232:233], v[232:233], v[36:37]
	v_pk_add_f32 v[232:233], v[232:233], v[38:39]
	v_pk_add_f32 v[232:233], v[232:233], v[40:41]
	v_pk_add_f32 v[232:233], v[232:233], v[42:43]
	v_pk_add_f32 v[232:233], v[232:233], v[44:45]
	v_pk_add_f32 v[232:233], v[232:233], v[46:47]
	ds_read2_b32 v[32:33], v115 offset0:136 offset1:137
	ds_read2_b32 v[34:35], v115 offset0:138 offset1:139
	ds_read2_b32 v[36:37], v115 offset0:144 offset1:145
	ds_read2_b32 v[38:39], v115 offset0:146 offset1:147
	ds_read2_b32 v[40:41], v115 offset0:153 offset1:154
	ds_read2_b32 v[42:43], v115 offset0:155 offset1:156
	ds_read2_b32 v[44:45], v115 offset0:161 offset1:162
	ds_read2_b32 v[46:47], v115 offset0:163 offset1:164
	v_mfma_f32_32x32x16_bf16 v[0:15], v[64:67], v[72:75], v[0:15]
	v_mfma_f32_32x32x16_bf16 v[16:31], v[64:67], v[76:79], v[16:31]
	v_mfma_f32_32x32x16_bf16 v[0:15], v[68:71], v[220:223], v[0:15]
	v_mfma_f32_32x32x16_bf16 v[16:31], v[68:71], v[224:227], v[16:31]
	global_load_dwordx4 v[156:159], v235, s[84:85]
	global_load_dwordx4 v[160:163], v236, s[84:85]
	global_load_dwordx4 v[164:167], v237, s[84:85]
	global_load_dwordx4 v[168:171], v238, s[84:85]
	global_load_dwordx4 v[172:175], v100, s[84:85] offset:768
	global_load_dwordx4 v[176:179], v149, s[84:85] offset:768
	global_load_dwordx4 v[180:183], v100, s[84:85] offset:832
	global_load_dwordx4 v[184:187], v149, s[84:85] offset:832
	s_add_u32 s84, s84, 0x30000
	s_addc_u32 s85, s85, 0
	ds_read_b64_tr_b16 v[72:73], v231
	ds_read_b64_tr_b16 v[74:75], v231 offset:512
	ds_read_b64_tr_b16 v[76:77], v231 offset:2048
	ds_read_b64_tr_b16 v[78:79], v231 offset:2560
	ds_read_b64_tr_b16 v[220:221], v231 offset:1024
	ds_read_b64_tr_b16 v[222:223], v231 offset:1536
	ds_read_b64_tr_b16 v[224:225], v231 offset:3072
	ds_read_b64_tr_b16 v[226:227], v231 offset:3584
	v_exp_f32_e32 v188, v188
	v_exp_f32_e32 v189, v189
	s_waitcnt vmcnt(8)
	ds_write_b128 v247, v[116:119]
	ds_write_b128 v247, v[120:123] offset:1024
	ds_write_b128 v247, v[124:127] offset:2048
	ds_write_b128 v247, v[128:131] offset:3072
	ds_read_b128 v[116:119], v248
	ds_read_b128 v[120:123], v249
	ds_read_b128 v[124:127], v250
	ds_read_b128 v[128:131], v251
	ds_write_b128 v112, v[132:135]
	ds_write_b128 v112, v[136:139] offset:1024
	ds_write_b128 v112, v[140:143] offset:2048
	ds_write_b128 v112, v[144:147] offset:3072
	v_exp_f32_e32 v190, v190
	v_exp_f32_e32 v191, v191
	s_waitcnt lgkmcnt(4)
	v_mfma_f32_32x32x16_bf16 v[32:47], v[116:119], v[48:51], v[32:47]
	v_exp_f32_e32 v192, v192
	v_exp_f32_e32 v193, v193
	v_exp_f32_e32 v194, v194
	v_mfma_f32_32x32x16_bf16 v[32:47], v[120:123], v[52:55], v[32:47]
	v_exp_f32_e32 v195, v195
	v_exp_f32_e32 v196, v196
	v_exp_f32_e32 v197, v197
	v_mfma_f32_32x32x16_bf16 v[32:47], v[124:127], v[56:59], v[32:47]
	v_exp_f32_e32 v198, v198
	v_exp_f32_e32 v199, v199
	v_exp_f32_e32 v200, v200
	v_mfma_f32_32x32x16_bf16 v[32:47], v[128:131], v[60:63], v[32:47]
	v_exp_f32_e32 v201, v201
	v_exp_f32_e32 v202, v202
	v_exp_f32_e32 v203, v203
	v_cvt_pk_bf16_f32 v64, v188, v189
	v_cvt_pk_bf16_f32 v65, v190, v191
	v_cvt_pk_bf16_f32 v66, v192, v193
	v_cvt_pk_bf16_f32 v67, v194, v195
	v_cvt_pk_bf16_f32 v68, v196, v197
	v_cvt_pk_bf16_f32 v69, v198, v199
	v_cvt_pk_bf16_f32 v70, v200, v201
	v_cvt_pk_bf16_f32 v71, v202, v203
	v_pk_add_f32 v[232:233], v[232:233], v[188:189]
	v_pk_add_f32 v[232:233], v[232:233], v[190:191]
	v_pk_add_f32 v[232:233], v[232:233], v[192:193]
	v_pk_add_f32 v[232:233], v[232:233], v[194:195]
	v_pk_add_f32 v[232:233], v[232:233], v[196:197]
	v_pk_add_f32 v[232:233], v[232:233], v[198:199]
	v_pk_add_f32 v[232:233], v[232:233], v[200:201]
	v_pk_add_f32 v[232:233], v[232:233], v[202:203]
	ds_read2_b32 v[188:189], v115 offset0:170 offset1:171
	ds_read2_b32 v[190:191], v115 offset0:172 offset1:173
	ds_read2_b32 v[192:193], v115 offset0:178 offset1:179
	ds_read2_b32 v[194:195], v115 offset0:180 offset1:181
	ds_read2_b32 v[196:197], v115 offset0:187 offset1:188
	ds_read2_b32 v[198:199], v115 offset0:189 offset1:190
	ds_read2_b32 v[200:201], v115 offset0:195 offset1:196
	ds_read2_b32 v[202:203], v115 offset0:197 offset1:198
	v_mfma_f32_32x32x16_bf16 v[0:15], v[64:67], v[72:75], v[0:15]
	v_mfma_f32_32x32x16_bf16 v[16:31], v[64:67], v[76:79], v[16:31]
	v_mfma_f32_32x32x16_bf16 v[0:15], v[68:71], v[220:223], v[0:15]
	v_mfma_f32_32x32x16_bf16 v[16:31], v[68:71], v[224:227], v[16:31]
	global_load_dwordx4 v[116:119], v235, s[84:85]
	global_load_dwordx4 v[120:123], v236, s[84:85]
	global_load_dwordx4 v[124:127], v237, s[84:85]
	global_load_dwordx4 v[128:131], v238, s[84:85]
	global_load_dwordx4 v[132:135], v100, s[84:85] offset:768
	global_load_dwordx4 v[136:139], v149, s[84:85] offset:768
	global_load_dwordx4 v[140:143], v100, s[84:85] offset:832
	global_load_dwordx4 v[144:147], v149, s[84:85] offset:832
	s_add_u32 s84, s84, 0x30000
	s_addc_u32 s85, s85, 0
	ds_read_b64_tr_b16 v[72:73], v231
	ds_read_b64_tr_b16 v[74:75], v231 offset:512
	ds_read_b64_tr_b16 v[76:77], v231 offset:2048
	ds_read_b64_tr_b16 v[78:79], v231 offset:2560
	ds_read_b64_tr_b16 v[220:221], v231 offset:1024
	ds_read_b64_tr_b16 v[222:223], v231 offset:1536
	ds_read_b64_tr_b16 v[224:225], v231 offset:3072
	ds_read_b64_tr_b16 v[226:227], v231 offset:3584
	v_exp_f32_e32 v32, v32
	v_exp_f32_e32 v33, v33
	s_waitcnt vmcnt(8)
	ds_write_b128 v247, v[156:159]
	ds_write_b128 v247, v[160:163] offset:1024
	ds_write_b128 v247, v[164:167] offset:2048
	ds_write_b128 v247, v[168:171] offset:3072
	ds_read_b128 v[156:159], v248
	ds_read_b128 v[160:163], v249
	ds_read_b128 v[164:167], v250
	ds_read_b128 v[168:171], v251
	ds_write_b128 v112, v[172:175]
	ds_write_b128 v112, v[176:179] offset:1024
	ds_write_b128 v112, v[180:183] offset:2048
	ds_write_b128 v112, v[184:187] offset:3072
	v_exp_f32_e32 v34, v34
	v_exp_f32_e32 v35, v35
	s_waitcnt lgkmcnt(4)
	v_mfma_f32_32x32x16_bf16 v[188:203], v[156:159], v[48:51], v[188:203]
	v_exp_f32_e32 v36, v36
	v_exp_f32_e32 v37, v37
	v_exp_f32_e32 v38, v38
	v_mfma_f32_32x32x16_bf16 v[188:203], v[160:163], v[52:55], v[188:203]
	v_exp_f32_e32 v39, v39
	v_exp_f32_e32 v40, v40
	v_exp_f32_e32 v41, v41
	v_mfma_f32_32x32x16_bf16 v[188:203], v[164:167], v[56:59], v[188:203]
	v_exp_f32_e32 v42, v42
	v_exp_f32_e32 v43, v43
	v_exp_f32_e32 v44, v44
	v_mfma_f32_32x32x16_bf16 v[188:203], v[168:171], v[60:63], v[188:203]
	v_exp_f32_e32 v45, v45
	v_exp_f32_e32 v46, v46
	v_exp_f32_e32 v47, v47
	v_cvt_pk_bf16_f32 v64, v32, v33
	v_cvt_pk_bf16_f32 v65, v34, v35
	v_cvt_pk_bf16_f32 v66, v36, v37
	v_cvt_pk_bf16_f32 v67, v38, v39
	v_cvt_pk_bf16_f32 v68, v40, v41
	v_cvt_pk_bf16_f32 v69, v42, v43
	v_cvt_pk_bf16_f32 v70, v44, v45
	v_cvt_pk_bf16_f32 v71, v46, v47
	v_pk_add_f32 v[232:233], v[232:233], v[32:33]
	v_pk_add_f32 v[232:233], v[232:233], v[34:35]
	v_pk_add_f32 v[232:233], v[232:233], v[36:37]
	v_pk_add_f32 v[232:233], v[232:233], v[38:39]
	v_pk_add_f32 v[232:233], v[232:233], v[40:41]
	v_pk_add_f32 v[232:233], v[232:233], v[42:43]
	v_pk_add_f32 v[232:233], v[232:233], v[44:45]
	v_pk_add_f32 v[232:233], v[232:233], v[46:47]
	ds_read2_b32 v[32:33], v115 offset0:204 offset1:205
	ds_read2_b32 v[34:35], v115 offset0:206 offset1:207
	ds_read2_b32 v[36:37], v115 offset0:212 offset1:213
	ds_read2_b32 v[38:39], v115 offset0:214 offset1:215
	ds_read2_b32 v[40:41], v115 offset0:221 offset1:222
	ds_read2_b32 v[42:43], v115 offset0:223 offset1:224
	ds_read2_b32 v[44:45], v115 offset0:229 offset1:230
	ds_read2_b32 v[46:47], v115 offset0:231 offset1:232
	v_mfma_f32_32x32x16_bf16 v[0:15], v[64:67], v[72:75], v[0:15]
	v_mfma_f32_32x32x16_bf16 v[16:31], v[64:67], v[76:79], v[16:31]
	v_mfma_f32_32x32x16_bf16 v[0:15], v[68:71], v[220:223], v[0:15]
	v_mfma_f32_32x32x16_bf16 v[16:31], v[68:71], v[224:227], v[16:31]
	global_load_dwordx4 v[156:159], v235, s[84:85]
	global_load_dwordx4 v[160:163], v236, s[84:85]
	global_load_dwordx4 v[164:167], v237, s[84:85]
	global_load_dwordx4 v[168:171], v238, s[84:85]
	global_load_dwordx4 v[172:175], v100, s[84:85] offset:768
	global_load_dwordx4 v[176:179], v149, s[84:85] offset:768
	global_load_dwordx4 v[180:183], v100, s[84:85] offset:832
	global_load_dwordx4 v[184:187], v149, s[84:85] offset:832
	s_add_u32 s84, s84, 0x30000
	s_addc_u32 s85, s85, 0
	ds_read_b64_tr_b16 v[72:73], v231
	ds_read_b64_tr_b16 v[74:75], v231 offset:512
	ds_read_b64_tr_b16 v[76:77], v231 offset:2048
	ds_read_b64_tr_b16 v[78:79], v231 offset:2560
	ds_read_b64_tr_b16 v[220:221], v231 offset:1024
	ds_read_b64_tr_b16 v[222:223], v231 offset:1536
	ds_read_b64_tr_b16 v[224:225], v231 offset:3072
	ds_read_b64_tr_b16 v[226:227], v231 offset:3584
	v_exp_f32_e32 v188, v188
	v_exp_f32_e32 v189, v189
	s_waitcnt vmcnt(8)
	ds_write_b128 v247, v[116:119]
	ds_write_b128 v247, v[120:123] offset:1024
	ds_write_b128 v247, v[124:127] offset:2048
	ds_write_b128 v247, v[128:131] offset:3072
	ds_read_b128 v[116:119], v248
	ds_read_b128 v[120:123], v249
	ds_read_b128 v[124:127], v250
	ds_read_b128 v[128:131], v251
	ds_write_b128 v112, v[132:135]
	ds_write_b128 v112, v[136:139] offset:1024
	ds_write_b128 v112, v[140:143] offset:2048
	ds_write_b128 v112, v[144:147] offset:3072
	v_exp_f32_e32 v190, v190
	v_exp_f32_e32 v191, v191
	s_waitcnt lgkmcnt(4)
	v_mfma_f32_32x32x16_bf16 v[32:47], v[116:119], v[48:51], v[32:47]
	v_exp_f32_e32 v192, v192
	v_exp_f32_e32 v193, v193
	v_exp_f32_e32 v194, v194
	v_mfma_f32_32x32x16_bf16 v[32:47], v[120:123], v[52:55], v[32:47]
	v_exp_f32_e32 v195, v195
	v_exp_f32_e32 v196, v196
	v_exp_f32_e32 v197, v197
	v_mfma_f32_32x32x16_bf16 v[32:47], v[124:127], v[56:59], v[32:47]
	v_exp_f32_e32 v198, v198
	v_exp_f32_e32 v199, v199
	v_exp_f32_e32 v200, v200
	v_mfma_f32_32x32x16_bf16 v[32:47], v[128:131], v[60:63], v[32:47]
	v_exp_f32_e32 v201, v201
	v_exp_f32_e32 v202, v202
	v_exp_f32_e32 v203, v203
	v_cvt_pk_bf16_f32 v64, v188, v189
	v_cvt_pk_bf16_f32 v65, v190, v191
	v_cvt_pk_bf16_f32 v66, v192, v193
	v_cvt_pk_bf16_f32 v67, v194, v195
	v_cvt_pk_bf16_f32 v68, v196, v197
	v_cvt_pk_bf16_f32 v69, v198, v199
	v_cvt_pk_bf16_f32 v70, v200, v201
	v_cvt_pk_bf16_f32 v71, v202, v203
	v_pk_add_f32 v[232:233], v[232:233], v[188:189]
	v_pk_add_f32 v[232:233], v[232:233], v[190:191]
	v_pk_add_f32 v[232:233], v[232:233], v[192:193]
	v_pk_add_f32 v[232:233], v[232:233], v[194:195]
	v_pk_add_f32 v[232:233], v[232:233], v[196:197]
	v_pk_add_f32 v[232:233], v[232:233], v[198:199]
	v_pk_add_f32 v[232:233], v[232:233], v[200:201]
	v_pk_add_f32 v[232:233], v[232:233], v[202:203]
	v_add_u32_e32 v115, 952, v115
	ds_read2_b32 v[188:189], v115 offset0:0 offset1:1
	ds_read2_b32 v[190:191], v115 offset0:2 offset1:3
	ds_read2_b32 v[192:193], v115 offset0:8 offset1:9
	ds_read2_b32 v[194:195], v115 offset0:10 offset1:11
	ds_read2_b32 v[196:197], v115 offset0:17 offset1:18
	ds_read2_b32 v[198:199], v115 offset0:19 offset1:20
	ds_read2_b32 v[200:201], v115 offset0:25 offset1:26
	ds_read2_b32 v[202:203], v115 offset0:27 offset1:28
	v_mfma_f32_32x32x16_bf16 v[0:15], v[64:67], v[72:75], v[0:15]
	v_mfma_f32_32x32x16_bf16 v[16:31], v[64:67], v[76:79], v[16:31]
	v_mfma_f32_32x32x16_bf16 v[0:15], v[68:71], v[220:223], v[0:15]
	v_mfma_f32_32x32x16_bf16 v[16:31], v[68:71], v[224:227], v[16:31]
	global_load_dwordx4 v[116:119], v235, s[84:85]
	global_load_dwordx4 v[120:123], v236, s[84:85]
	global_load_dwordx4 v[124:127], v237, s[84:85]
	global_load_dwordx4 v[128:131], v238, s[84:85]
	global_load_dwordx4 v[132:135], v100, s[84:85] offset:768
	global_load_dwordx4 v[136:139], v149, s[84:85] offset:768
	global_load_dwordx4 v[140:143], v100, s[84:85] offset:832
	global_load_dwordx4 v[144:147], v149, s[84:85] offset:832
	s_add_u32 s84, s84, 0x30000
	s_addc_u32 s85, s85, 0
	ds_read_b64_tr_b16 v[72:73], v231
	ds_read_b64_tr_b16 v[74:75], v231 offset:512
	ds_read_b64_tr_b16 v[76:77], v231 offset:2048
	ds_read_b64_tr_b16 v[78:79], v231 offset:2560
	ds_read_b64_tr_b16 v[220:221], v231 offset:1024
	ds_read_b64_tr_b16 v[222:223], v231 offset:1536
	ds_read_b64_tr_b16 v[224:225], v231 offset:3072
	ds_read_b64_tr_b16 v[226:227], v231 offset:3584
	v_exp_f32_e32 v32, v32
	v_exp_f32_e32 v33, v33
	s_waitcnt vmcnt(8)
	ds_write_b128 v247, v[156:159]
	ds_write_b128 v247, v[160:163] offset:1024
	ds_write_b128 v247, v[164:167] offset:2048
	ds_write_b128 v247, v[168:171] offset:3072
	ds_read_b128 v[156:159], v248
	ds_read_b128 v[160:163], v249
	ds_read_b128 v[164:167], v250
	ds_read_b128 v[168:171], v251
	ds_write_b128 v112, v[172:175]
	ds_write_b128 v112, v[176:179] offset:1024
	ds_write_b128 v112, v[180:183] offset:2048
	ds_write_b128 v112, v[184:187] offset:3072
	v_exp_f32_e32 v34, v34
	v_exp_f32_e32 v35, v35
	s_waitcnt lgkmcnt(4)
	v_mfma_f32_32x32x16_bf16 v[188:203], v[156:159], v[48:51], v[188:203]
	v_exp_f32_e32 v36, v36
	v_exp_f32_e32 v37, v37
	v_exp_f32_e32 v38, v38
	v_mfma_f32_32x32x16_bf16 v[188:203], v[160:163], v[52:55], v[188:203]
	v_exp_f32_e32 v39, v39
	v_exp_f32_e32 v40, v40
	v_exp_f32_e32 v41, v41
	v_mfma_f32_32x32x16_bf16 v[188:203], v[164:167], v[56:59], v[188:203]
	v_exp_f32_e32 v42, v42
	v_exp_f32_e32 v43, v43
	v_exp_f32_e32 v44, v44
	v_mfma_f32_32x32x16_bf16 v[188:203], v[168:171], v[60:63], v[188:203]
	v_exp_f32_e32 v45, v45
	v_exp_f32_e32 v46, v46
	v_exp_f32_e32 v47, v47
	v_cvt_pk_bf16_f32 v64, v32, v33
	v_cvt_pk_bf16_f32 v65, v34, v35
	v_cvt_pk_bf16_f32 v66, v36, v37
	v_cvt_pk_bf16_f32 v67, v38, v39
	v_cvt_pk_bf16_f32 v68, v40, v41
	v_cvt_pk_bf16_f32 v69, v42, v43
	v_cvt_pk_bf16_f32 v70, v44, v45
	v_cvt_pk_bf16_f32 v71, v46, v47
	v_pk_add_f32 v[232:233], v[232:233], v[32:33]
	v_pk_add_f32 v[232:233], v[232:233], v[34:35]
	v_pk_add_f32 v[232:233], v[232:233], v[36:37]
	v_pk_add_f32 v[232:233], v[232:233], v[38:39]
	v_pk_add_f32 v[232:233], v[232:233], v[40:41]
	v_pk_add_f32 v[232:233], v[232:233], v[42:43]
	v_pk_add_f32 v[232:233], v[232:233], v[44:45]
	v_pk_add_f32 v[232:233], v[232:233], v[46:47]
	ds_read2_b32 v[32:33], v115 offset0:34 offset1:35
	ds_read2_b32 v[34:35], v115 offset0:36 offset1:37
	ds_read2_b32 v[36:37], v115 offset0:42 offset1:43
	ds_read2_b32 v[38:39], v115 offset0:44 offset1:45
	ds_read2_b32 v[40:41], v115 offset0:51 offset1:52
	ds_read2_b32 v[42:43], v115 offset0:53 offset1:54
	ds_read2_b32 v[44:45], v115 offset0:59 offset1:60
	ds_read2_b32 v[46:47], v115 offset0:61 offset1:62
	v_mfma_f32_32x32x16_bf16 v[0:15], v[64:67], v[72:75], v[0:15]
	v_mfma_f32_32x32x16_bf16 v[16:31], v[64:67], v[76:79], v[16:31]
	v_mfma_f32_32x32x16_bf16 v[0:15], v[68:71], v[220:223], v[0:15]
	v_mfma_f32_32x32x16_bf16 v[16:31], v[68:71], v[224:227], v[16:31]
	global_load_dwordx4 v[156:159], v235, s[84:85]
	global_load_dwordx4 v[160:163], v236, s[84:85]
	global_load_dwordx4 v[164:167], v237, s[84:85]
	global_load_dwordx4 v[168:171], v238, s[84:85]
	global_load_dwordx4 v[172:175], v100, s[84:85] offset:768
	global_load_dwordx4 v[176:179], v149, s[84:85] offset:768
	global_load_dwordx4 v[180:183], v100, s[84:85] offset:832
	global_load_dwordx4 v[184:187], v149, s[84:85] offset:832
	s_add_u32 s84, s84, 0x30000
	s_addc_u32 s85, s85, 0
	ds_read_b64_tr_b16 v[72:73], v231
	ds_read_b64_tr_b16 v[74:75], v231 offset:512
	ds_read_b64_tr_b16 v[76:77], v231 offset:2048
	ds_read_b64_tr_b16 v[78:79], v231 offset:2560
	ds_read_b64_tr_b16 v[220:221], v231 offset:1024
	ds_read_b64_tr_b16 v[222:223], v231 offset:1536
	ds_read_b64_tr_b16 v[224:225], v231 offset:3072
	ds_read_b64_tr_b16 v[226:227], v231 offset:3584
	v_exp_f32_e32 v188, v188
	v_exp_f32_e32 v189, v189
	s_waitcnt vmcnt(8)
	ds_write_b128 v247, v[116:119]
	ds_write_b128 v247, v[120:123] offset:1024
	ds_write_b128 v247, v[124:127] offset:2048
	ds_write_b128 v247, v[128:131] offset:3072
	ds_read_b128 v[116:119], v248
	ds_read_b128 v[120:123], v249
	ds_read_b128 v[124:127], v250
	ds_read_b128 v[128:131], v251
	ds_write_b128 v112, v[132:135]
	ds_write_b128 v112, v[136:139] offset:1024
	ds_write_b128 v112, v[140:143] offset:2048
	ds_write_b128 v112, v[144:147] offset:3072
	v_exp_f32_e32 v190, v190
	v_exp_f32_e32 v191, v191
	s_waitcnt lgkmcnt(4)
	v_mfma_f32_32x32x16_bf16 v[32:47], v[116:119], v[48:51], v[32:47]
	v_exp_f32_e32 v192, v192
	v_exp_f32_e32 v193, v193
	v_exp_f32_e32 v194, v194
	v_mfma_f32_32x32x16_bf16 v[32:47], v[120:123], v[52:55], v[32:47]
	v_exp_f32_e32 v195, v195
	v_exp_f32_e32 v196, v196
	v_exp_f32_e32 v197, v197
	v_mfma_f32_32x32x16_bf16 v[32:47], v[124:127], v[56:59], v[32:47]
	v_exp_f32_e32 v198, v198
	v_exp_f32_e32 v199, v199
	v_exp_f32_e32 v200, v200
	v_mfma_f32_32x32x16_bf16 v[32:47], v[128:131], v[60:63], v[32:47]
	v_exp_f32_e32 v201, v201
	v_exp_f32_e32 v202, v202
	v_exp_f32_e32 v203, v203
	v_cvt_pk_bf16_f32 v64, v188, v189
	v_cvt_pk_bf16_f32 v65, v190, v191
	v_cvt_pk_bf16_f32 v66, v192, v193
	v_cvt_pk_bf16_f32 v67, v194, v195
	v_cvt_pk_bf16_f32 v68, v196, v197
	v_cvt_pk_bf16_f32 v69, v198, v199
	v_cvt_pk_bf16_f32 v70, v200, v201
	v_cvt_pk_bf16_f32 v71, v202, v203
	v_pk_add_f32 v[232:233], v[232:233], v[188:189]
	v_pk_add_f32 v[232:233], v[232:233], v[190:191]
	v_pk_add_f32 v[232:233], v[232:233], v[192:193]
	v_pk_add_f32 v[232:233], v[232:233], v[194:195]
	v_pk_add_f32 v[232:233], v[232:233], v[196:197]
	v_pk_add_f32 v[232:233], v[232:233], v[198:199]
	v_pk_add_f32 v[232:233], v[232:233], v[200:201]
	v_pk_add_f32 v[232:233], v[232:233], v[202:203]
	ds_read2_b32 v[188:189], v115 offset0:68 offset1:69
	ds_read2_b32 v[190:191], v115 offset0:70 offset1:71
	ds_read2_b32 v[192:193], v115 offset0:76 offset1:77
	ds_read2_b32 v[194:195], v115 offset0:78 offset1:79
	ds_read2_b32 v[196:197], v115 offset0:85 offset1:86
	ds_read2_b32 v[198:199], v115 offset0:87 offset1:88
	ds_read2_b32 v[200:201], v115 offset0:93 offset1:94
	ds_read2_b32 v[202:203], v115 offset0:95 offset1:96
	v_mfma_f32_32x32x16_bf16 v[0:15], v[64:67], v[72:75], v[0:15]
	v_mfma_f32_32x32x16_bf16 v[16:31], v[64:67], v[76:79], v[16:31]
	v_mfma_f32_32x32x16_bf16 v[0:15], v[68:71], v[220:223], v[0:15]
	v_mfma_f32_32x32x16_bf16 v[16:31], v[68:71], v[224:227], v[16:31]
	global_load_dwordx4 v[116:119], v235, s[84:85]
	global_load_dwordx4 v[120:123], v236, s[84:85]
	global_load_dwordx4 v[124:127], v237, s[84:85]
	global_load_dwordx4 v[128:131], v238, s[84:85]
	global_load_dwordx4 v[132:135], v100, s[84:85] offset:768
	global_load_dwordx4 v[136:139], v149, s[84:85] offset:768
	global_load_dwordx4 v[140:143], v100, s[84:85] offset:832
	global_load_dwordx4 v[144:147], v149, s[84:85] offset:832
	s_add_u32 s84, s84, 0x30000
	s_addc_u32 s85, s85, 0
	ds_read_b64_tr_b16 v[72:73], v231
	ds_read_b64_tr_b16 v[74:75], v231 offset:512
	ds_read_b64_tr_b16 v[76:77], v231 offset:2048
	ds_read_b64_tr_b16 v[78:79], v231 offset:2560
	ds_read_b64_tr_b16 v[220:221], v231 offset:1024
	ds_read_b64_tr_b16 v[222:223], v231 offset:1536
	ds_read_b64_tr_b16 v[224:225], v231 offset:3072
	ds_read_b64_tr_b16 v[226:227], v231 offset:3584
	v_exp_f32_e32 v32, v32
	v_exp_f32_e32 v33, v33
	s_waitcnt vmcnt(8)
	ds_write_b128 v247, v[156:159]
	ds_write_b128 v247, v[160:163] offset:1024
	ds_write_b128 v247, v[164:167] offset:2048
	ds_write_b128 v247, v[168:171] offset:3072
	ds_read_b128 v[156:159], v248
	ds_read_b128 v[160:163], v249
	ds_read_b128 v[164:167], v250
	ds_read_b128 v[168:171], v251
	ds_write_b128 v112, v[172:175]
	ds_write_b128 v112, v[176:179] offset:1024
	ds_write_b128 v112, v[180:183] offset:2048
	ds_write_b128 v112, v[184:187] offset:3072
	v_exp_f32_e32 v34, v34
	v_exp_f32_e32 v35, v35
	s_waitcnt lgkmcnt(4)
	v_mfma_f32_32x32x16_bf16 v[188:203], v[156:159], v[48:51], v[188:203]
	v_exp_f32_e32 v36, v36
	v_exp_f32_e32 v37, v37
	v_exp_f32_e32 v38, v38
	v_mfma_f32_32x32x16_bf16 v[188:203], v[160:163], v[52:55], v[188:203]
	v_exp_f32_e32 v39, v39
	v_exp_f32_e32 v40, v40
	v_exp_f32_e32 v41, v41
	v_mfma_f32_32x32x16_bf16 v[188:203], v[164:167], v[56:59], v[188:203]
	v_exp_f32_e32 v42, v42
	v_exp_f32_e32 v43, v43
	v_exp_f32_e32 v44, v44
	v_mfma_f32_32x32x16_bf16 v[188:203], v[168:171], v[60:63], v[188:203]
	v_exp_f32_e32 v45, v45
	v_exp_f32_e32 v46, v46
	v_exp_f32_e32 v47, v47
	v_cvt_pk_bf16_f32 v64, v32, v33
	v_cvt_pk_bf16_f32 v65, v34, v35
	v_cvt_pk_bf16_f32 v66, v36, v37
	v_cvt_pk_bf16_f32 v67, v38, v39
	v_cvt_pk_bf16_f32 v68, v40, v41
	v_cvt_pk_bf16_f32 v69, v42, v43
	v_cvt_pk_bf16_f32 v70, v44, v45
	v_cvt_pk_bf16_f32 v71, v46, v47
	v_pk_add_f32 v[232:233], v[232:233], v[32:33]
	v_pk_add_f32 v[232:233], v[232:233], v[34:35]
	v_pk_add_f32 v[232:233], v[232:233], v[36:37]
	v_pk_add_f32 v[232:233], v[232:233], v[38:39]
	v_pk_add_f32 v[232:233], v[232:233], v[40:41]
	v_pk_add_f32 v[232:233], v[232:233], v[42:43]
	v_pk_add_f32 v[232:233], v[232:233], v[44:45]
	v_pk_add_f32 v[232:233], v[232:233], v[46:47]
	ds_read2_b32 v[32:33], v115 offset0:102 offset1:103
	ds_read2_b32 v[34:35], v115 offset0:104 offset1:105
	ds_read2_b32 v[36:37], v115 offset0:110 offset1:111
	ds_read2_b32 v[38:39], v115 offset0:112 offset1:113
	ds_read2_b32 v[40:41], v115 offset0:119 offset1:120
	ds_read2_b32 v[42:43], v115 offset0:121 offset1:122
	ds_read2_b32 v[44:45], v115 offset0:127 offset1:128
	ds_read2_b32 v[46:47], v115 offset0:129 offset1:130
	v_mfma_f32_32x32x16_bf16 v[0:15], v[64:67], v[72:75], v[0:15]
	v_mfma_f32_32x32x16_bf16 v[16:31], v[64:67], v[76:79], v[16:31]
	v_mfma_f32_32x32x16_bf16 v[0:15], v[68:71], v[220:223], v[0:15]
	v_mfma_f32_32x32x16_bf16 v[16:31], v[68:71], v[224:227], v[16:31]
	global_load_dwordx4 v[156:159], v235, s[84:85]
	global_load_dwordx4 v[160:163], v236, s[84:85]
	global_load_dwordx4 v[164:167], v237, s[84:85]
	global_load_dwordx4 v[168:171], v238, s[84:85]
	global_load_dwordx4 v[172:175], v100, s[84:85] offset:768
	global_load_dwordx4 v[176:179], v149, s[84:85] offset:768
	global_load_dwordx4 v[180:183], v100, s[84:85] offset:832
	global_load_dwordx4 v[184:187], v149, s[84:85] offset:832
	s_add_u32 s84, s84, 0x30000
	s_addc_u32 s85, s85, 0
	ds_read_b64_tr_b16 v[72:73], v231
	ds_read_b64_tr_b16 v[74:75], v231 offset:512
	ds_read_b64_tr_b16 v[76:77], v231 offset:2048
	ds_read_b64_tr_b16 v[78:79], v231 offset:2560
	ds_read_b64_tr_b16 v[220:221], v231 offset:1024
	ds_read_b64_tr_b16 v[222:223], v231 offset:1536
	ds_read_b64_tr_b16 v[224:225], v231 offset:3072
	ds_read_b64_tr_b16 v[226:227], v231 offset:3584
	v_exp_f32_e32 v188, v188
	v_exp_f32_e32 v189, v189
	s_waitcnt vmcnt(8)
	ds_write_b128 v247, v[116:119]
	ds_write_b128 v247, v[120:123] offset:1024
	ds_write_b128 v247, v[124:127] offset:2048
	ds_write_b128 v247, v[128:131] offset:3072
	ds_read_b128 v[116:119], v248
	ds_read_b128 v[120:123], v249
	ds_read_b128 v[124:127], v250
	ds_read_b128 v[128:131], v251
	ds_write_b128 v112, v[132:135]
	ds_write_b128 v112, v[136:139] offset:1024
	ds_write_b128 v112, v[140:143] offset:2048
	ds_write_b128 v112, v[144:147] offset:3072
	v_exp_f32_e32 v190, v190
	v_exp_f32_e32 v191, v191
	s_waitcnt lgkmcnt(4)
	v_mfma_f32_32x32x16_bf16 v[32:47], v[116:119], v[48:51], v[32:47]
	v_exp_f32_e32 v192, v192
	v_exp_f32_e32 v193, v193
	v_exp_f32_e32 v194, v194
	v_mfma_f32_32x32x16_bf16 v[32:47], v[120:123], v[52:55], v[32:47]
	v_exp_f32_e32 v195, v195
	v_exp_f32_e32 v196, v196
	v_exp_f32_e32 v197, v197
	v_mfma_f32_32x32x16_bf16 v[32:47], v[124:127], v[56:59], v[32:47]
	v_exp_f32_e32 v198, v198
	v_exp_f32_e32 v199, v199
	v_exp_f32_e32 v200, v200
	v_mfma_f32_32x32x16_bf16 v[32:47], v[128:131], v[60:63], v[32:47]
	v_exp_f32_e32 v201, v201
	v_exp_f32_e32 v202, v202
	v_exp_f32_e32 v203, v203
	v_cvt_pk_bf16_f32 v64, v188, v189
	v_cvt_pk_bf16_f32 v65, v190, v191
	v_cvt_pk_bf16_f32 v66, v192, v193
	v_cvt_pk_bf16_f32 v67, v194, v195
	v_cvt_pk_bf16_f32 v68, v196, v197
	v_cvt_pk_bf16_f32 v69, v198, v199
	v_cvt_pk_bf16_f32 v70, v200, v201
	v_cvt_pk_bf16_f32 v71, v202, v203
	v_pk_add_f32 v[232:233], v[232:233], v[188:189]
	v_pk_add_f32 v[232:233], v[232:233], v[190:191]
	v_pk_add_f32 v[232:233], v[232:233], v[192:193]
	v_pk_add_f32 v[232:233], v[232:233], v[194:195]
	v_pk_add_f32 v[232:233], v[232:233], v[196:197]
	v_pk_add_f32 v[232:233], v[232:233], v[198:199]
	v_pk_add_f32 v[232:233], v[232:233], v[200:201]
	v_pk_add_f32 v[232:233], v[232:233], v[202:203]
	ds_read2_b32 v[188:189], v115 offset0:136 offset1:137
	ds_read2_b32 v[190:191], v115 offset0:138 offset1:139
	ds_read2_b32 v[192:193], v115 offset0:144 offset1:145
	ds_read2_b32 v[194:195], v115 offset0:146 offset1:147
	ds_read2_b32 v[196:197], v115 offset0:153 offset1:154
	ds_read2_b32 v[198:199], v115 offset0:155 offset1:156
	ds_read2_b32 v[200:201], v115 offset0:161 offset1:162
	ds_read2_b32 v[202:203], v115 offset0:163 offset1:164
	v_mfma_f32_32x32x16_bf16 v[0:15], v[64:67], v[72:75], v[0:15]
	v_mfma_f32_32x32x16_bf16 v[16:31], v[64:67], v[76:79], v[16:31]
	v_mfma_f32_32x32x16_bf16 v[0:15], v[68:71], v[220:223], v[0:15]
	v_mfma_f32_32x32x16_bf16 v[16:31], v[68:71], v[224:227], v[16:31]
	global_load_dwordx4 v[116:119], v235, s[84:85]
	global_load_dwordx4 v[120:123], v236, s[84:85]
	global_load_dwordx4 v[124:127], v237, s[84:85]
	global_load_dwordx4 v[128:131], v238, s[84:85]
	global_load_dwordx4 v[132:135], v100, s[84:85] offset:768
	global_load_dwordx4 v[136:139], v149, s[84:85] offset:768
	global_load_dwordx4 v[140:143], v100, s[84:85] offset:832
	global_load_dwordx4 v[144:147], v149, s[84:85] offset:832
	s_add_u32 s84, s84, 0x30000
	s_addc_u32 s85, s85, 0
	ds_read_b64_tr_b16 v[72:73], v231
	ds_read_b64_tr_b16 v[74:75], v231 offset:512
	ds_read_b64_tr_b16 v[76:77], v231 offset:2048
	ds_read_b64_tr_b16 v[78:79], v231 offset:2560
	ds_read_b64_tr_b16 v[220:221], v231 offset:1024
	ds_read_b64_tr_b16 v[222:223], v231 offset:1536
	ds_read_b64_tr_b16 v[224:225], v231 offset:3072
	ds_read_b64_tr_b16 v[226:227], v231 offset:3584
	v_exp_f32_e32 v32, v32
	v_exp_f32_e32 v33, v33
	s_waitcnt vmcnt(8)
	ds_write_b128 v247, v[156:159]
	ds_write_b128 v247, v[160:163] offset:1024
	ds_write_b128 v247, v[164:167] offset:2048
	ds_write_b128 v247, v[168:171] offset:3072
	ds_read_b128 v[156:159], v248
	ds_read_b128 v[160:163], v249
	ds_read_b128 v[164:167], v250
	ds_read_b128 v[168:171], v251
	ds_write_b128 v112, v[172:175]
	ds_write_b128 v112, v[176:179] offset:1024
	ds_write_b128 v112, v[180:183] offset:2048
	ds_write_b128 v112, v[184:187] offset:3072
	v_exp_f32_e32 v34, v34
	v_exp_f32_e32 v35, v35
	s_waitcnt lgkmcnt(4)
	v_mfma_f32_32x32x16_bf16 v[188:203], v[156:159], v[48:51], v[188:203]
	v_exp_f32_e32 v36, v36
	v_exp_f32_e32 v37, v37
	v_exp_f32_e32 v38, v38
	v_mfma_f32_32x32x16_bf16 v[188:203], v[160:163], v[52:55], v[188:203]
	v_exp_f32_e32 v39, v39
	v_exp_f32_e32 v40, v40
	v_exp_f32_e32 v41, v41
	v_mfma_f32_32x32x16_bf16 v[188:203], v[164:167], v[56:59], v[188:203]
	v_exp_f32_e32 v42, v42
	v_exp_f32_e32 v43, v43
	v_exp_f32_e32 v44, v44
	v_mfma_f32_32x32x16_bf16 v[188:203], v[168:171], v[60:63], v[188:203]
	v_exp_f32_e32 v45, v45
	v_exp_f32_e32 v46, v46
	v_exp_f32_e32 v47, v47
	v_cvt_pk_bf16_f32 v64, v32, v33
	v_cvt_pk_bf16_f32 v65, v34, v35
	v_cvt_pk_bf16_f32 v66, v36, v37
	v_cvt_pk_bf16_f32 v67, v38, v39
	v_cvt_pk_bf16_f32 v68, v40, v41
	v_cvt_pk_bf16_f32 v69, v42, v43
	v_cvt_pk_bf16_f32 v70, v44, v45
	v_cvt_pk_bf16_f32 v71, v46, v47
	v_pk_add_f32 v[232:233], v[232:233], v[32:33]
	v_pk_add_f32 v[232:233], v[232:233], v[34:35]
	v_pk_add_f32 v[232:233], v[232:233], v[36:37]
	v_pk_add_f32 v[232:233], v[232:233], v[38:39]
	v_pk_add_f32 v[232:233], v[232:233], v[40:41]
	v_pk_add_f32 v[232:233], v[232:233], v[42:43]
	v_pk_add_f32 v[232:233], v[232:233], v[44:45]
	v_pk_add_f32 v[232:233], v[232:233], v[46:47]
	ds_read2_b32 v[32:33], v115 offset0:170 offset1:171
	ds_read2_b32 v[34:35], v115 offset0:172 offset1:173
	ds_read2_b32 v[36:37], v115 offset0:178 offset1:179
	ds_read2_b32 v[38:39], v115 offset0:180 offset1:181
	ds_read2_b32 v[40:41], v115 offset0:187 offset1:188
	ds_read2_b32 v[42:43], v115 offset0:189 offset1:190
	ds_read2_b32 v[44:45], v115 offset0:195 offset1:196
	ds_read2_b32 v[46:47], v115 offset0:197 offset1:198
	v_mfma_f32_32x32x16_bf16 v[0:15], v[64:67], v[72:75], v[0:15]
	v_mfma_f32_32x32x16_bf16 v[16:31], v[64:67], v[76:79], v[16:31]
	v_mfma_f32_32x32x16_bf16 v[0:15], v[68:71], v[220:223], v[0:15]
	v_mfma_f32_32x32x16_bf16 v[16:31], v[68:71], v[224:227], v[16:31]
	global_load_dwordx4 v[156:159], v235, s[84:85]
	global_load_dwordx4 v[160:163], v236, s[84:85]
	global_load_dwordx4 v[164:167], v237, s[84:85]
	global_load_dwordx4 v[168:171], v238, s[84:85]
	global_load_dwordx4 v[172:175], v100, s[84:85] offset:768
	global_load_dwordx4 v[176:179], v149, s[84:85] offset:768
	global_load_dwordx4 v[180:183], v100, s[84:85] offset:832
	global_load_dwordx4 v[184:187], v149, s[84:85] offset:832
	s_add_u32 s84, s84, 0x30000
	s_addc_u32 s85, s85, 0
	ds_read_b64_tr_b16 v[72:73], v231
	ds_read_b64_tr_b16 v[74:75], v231 offset:512
	ds_read_b64_tr_b16 v[76:77], v231 offset:2048
	ds_read_b64_tr_b16 v[78:79], v231 offset:2560
	ds_read_b64_tr_b16 v[220:221], v231 offset:1024
	ds_read_b64_tr_b16 v[222:223], v231 offset:1536
	ds_read_b64_tr_b16 v[224:225], v231 offset:3072
	ds_read_b64_tr_b16 v[226:227], v231 offset:3584
	v_exp_f32_e32 v188, v188
	v_exp_f32_e32 v189, v189
	s_waitcnt vmcnt(8)
	ds_write_b128 v247, v[116:119]
	ds_write_b128 v247, v[120:123] offset:1024
	ds_write_b128 v247, v[124:127] offset:2048
	ds_write_b128 v247, v[128:131] offset:3072
	ds_read_b128 v[116:119], v248
	ds_read_b128 v[120:123], v249
	ds_read_b128 v[124:127], v250
	ds_read_b128 v[128:131], v251
	ds_write_b128 v112, v[132:135]
	ds_write_b128 v112, v[136:139] offset:1024
	ds_write_b128 v112, v[140:143] offset:2048
	ds_write_b128 v112, v[144:147] offset:3072
	v_exp_f32_e32 v190, v190
	v_exp_f32_e32 v191, v191
	s_waitcnt lgkmcnt(4)
	v_mfma_f32_32x32x16_bf16 v[32:47], v[116:119], v[48:51], v[32:47]
	v_exp_f32_e32 v192, v192
	v_exp_f32_e32 v193, v193
	v_exp_f32_e32 v194, v194
	v_mfma_f32_32x32x16_bf16 v[32:47], v[120:123], v[52:55], v[32:47]
	v_exp_f32_e32 v195, v195
	v_exp_f32_e32 v196, v196
	v_exp_f32_e32 v197, v197
	v_mfma_f32_32x32x16_bf16 v[32:47], v[124:127], v[56:59], v[32:47]
	v_exp_f32_e32 v198, v198
	v_exp_f32_e32 v199, v199
	v_exp_f32_e32 v200, v200
	v_mfma_f32_32x32x16_bf16 v[32:47], v[128:131], v[60:63], v[32:47]
	v_exp_f32_e32 v201, v201
	v_exp_f32_e32 v202, v202
	v_exp_f32_e32 v203, v203
	v_cvt_pk_bf16_f32 v64, v188, v189
	v_cvt_pk_bf16_f32 v65, v190, v191
	v_cvt_pk_bf16_f32 v66, v192, v193
	v_cvt_pk_bf16_f32 v67, v194, v195
	v_cvt_pk_bf16_f32 v68, v196, v197
	v_cvt_pk_bf16_f32 v69, v198, v199
	v_cvt_pk_bf16_f32 v70, v200, v201
	v_cvt_pk_bf16_f32 v71, v202, v203
	v_pk_add_f32 v[232:233], v[232:233], v[188:189]
	v_pk_add_f32 v[232:233], v[232:233], v[190:191]
	v_pk_add_f32 v[232:233], v[232:233], v[192:193]
	v_pk_add_f32 v[232:233], v[232:233], v[194:195]
	v_pk_add_f32 v[232:233], v[232:233], v[196:197]
	v_pk_add_f32 v[232:233], v[232:233], v[198:199]
	v_pk_add_f32 v[232:233], v[232:233], v[200:201]
	v_pk_add_f32 v[232:233], v[232:233], v[202:203]
	ds_read2_b32 v[188:189], v115 offset0:204 offset1:205
	ds_read2_b32 v[190:191], v115 offset0:206 offset1:207
	ds_read2_b32 v[192:193], v115 offset0:212 offset1:213
	ds_read2_b32 v[194:195], v115 offset0:214 offset1:215
	ds_read2_b32 v[196:197], v115 offset0:221 offset1:222
	ds_read2_b32 v[198:199], v115 offset0:223 offset1:224
	ds_read2_b32 v[200:201], v115 offset0:229 offset1:230
	ds_read2_b32 v[202:203], v115 offset0:231 offset1:232
	v_mfma_f32_32x32x16_bf16 v[0:15], v[64:67], v[72:75], v[0:15]
	v_mfma_f32_32x32x16_bf16 v[16:31], v[64:67], v[76:79], v[16:31]
	v_mfma_f32_32x32x16_bf16 v[0:15], v[68:71], v[220:223], v[0:15]
	v_mfma_f32_32x32x16_bf16 v[16:31], v[68:71], v[224:227], v[16:31]
	global_load_dwordx4 v[116:119], v235, s[84:85]
	global_load_dwordx4 v[120:123], v236, s[84:85]
	global_load_dwordx4 v[124:127], v237, s[84:85]
	global_load_dwordx4 v[128:131], v238, s[84:85]
	global_load_dwordx4 v[132:135], v100, s[84:85] offset:768
	global_load_dwordx4 v[136:139], v149, s[84:85] offset:768
	global_load_dwordx4 v[140:143], v100, s[84:85] offset:832
	global_load_dwordx4 v[144:147], v149, s[84:85] offset:832
	s_add_u32 s84, s84, 0x30000
	s_addc_u32 s85, s85, 0
	ds_read_b64_tr_b16 v[72:73], v231
	ds_read_b64_tr_b16 v[74:75], v231 offset:512
	ds_read_b64_tr_b16 v[76:77], v231 offset:2048
	ds_read_b64_tr_b16 v[78:79], v231 offset:2560
	ds_read_b64_tr_b16 v[220:221], v231 offset:1024
	ds_read_b64_tr_b16 v[222:223], v231 offset:1536
	ds_read_b64_tr_b16 v[224:225], v231 offset:3072
	ds_read_b64_tr_b16 v[226:227], v231 offset:3584
	v_exp_f32_e32 v32, v32
	v_exp_f32_e32 v33, v33
	s_waitcnt vmcnt(8)
	ds_write_b128 v247, v[156:159]
	ds_write_b128 v247, v[160:163] offset:1024
	ds_write_b128 v247, v[164:167] offset:2048
	ds_write_b128 v247, v[168:171] offset:3072
	ds_read_b128 v[156:159], v248
	ds_read_b128 v[160:163], v249
	ds_read_b128 v[164:167], v250
	ds_read_b128 v[168:171], v251
	ds_write_b128 v112, v[172:175]
	ds_write_b128 v112, v[176:179] offset:1024
	ds_write_b128 v112, v[180:183] offset:2048
	ds_write_b128 v112, v[184:187] offset:3072
	v_exp_f32_e32 v34, v34
	v_exp_f32_e32 v35, v35
	s_waitcnt lgkmcnt(4)
	v_mfma_f32_32x32x16_bf16 v[188:203], v[156:159], v[48:51], v[188:203]
	v_exp_f32_e32 v36, v36
	v_exp_f32_e32 v37, v37
	v_exp_f32_e32 v38, v38
	v_mfma_f32_32x32x16_bf16 v[188:203], v[160:163], v[52:55], v[188:203]
	v_exp_f32_e32 v39, v39
	v_exp_f32_e32 v40, v40
	v_exp_f32_e32 v41, v41
	v_mfma_f32_32x32x16_bf16 v[188:203], v[164:167], v[56:59], v[188:203]
	v_exp_f32_e32 v42, v42
	v_exp_f32_e32 v43, v43
	v_exp_f32_e32 v44, v44
	v_mfma_f32_32x32x16_bf16 v[188:203], v[168:171], v[60:63], v[188:203]
	v_exp_f32_e32 v45, v45
	v_exp_f32_e32 v46, v46
	v_exp_f32_e32 v47, v47
	v_cvt_pk_bf16_f32 v64, v32, v33
	v_cvt_pk_bf16_f32 v65, v34, v35
	v_cvt_pk_bf16_f32 v66, v36, v37
	v_cvt_pk_bf16_f32 v67, v38, v39
	v_cvt_pk_bf16_f32 v68, v40, v41
	v_cvt_pk_bf16_f32 v69, v42, v43
	v_cvt_pk_bf16_f32 v70, v44, v45
	v_cvt_pk_bf16_f32 v71, v46, v47
	v_pk_add_f32 v[232:233], v[232:233], v[32:33]
	v_pk_add_f32 v[232:233], v[232:233], v[34:35]
	v_pk_add_f32 v[232:233], v[232:233], v[36:37]
	v_pk_add_f32 v[232:233], v[232:233], v[38:39]
	v_pk_add_f32 v[232:233], v[232:233], v[40:41]
	v_pk_add_f32 v[232:233], v[232:233], v[42:43]
	v_pk_add_f32 v[232:233], v[232:233], v[44:45]
	v_pk_add_f32 v[232:233], v[232:233], v[46:47]
	v_add_u32_e32 v115, 952, v115
	ds_read2_b32 v[32:33], v115 offset0:0 offset1:1
	ds_read2_b32 v[34:35], v115 offset0:2 offset1:3
	ds_read2_b32 v[36:37], v115 offset0:8 offset1:9
	ds_read2_b32 v[38:39], v115 offset0:10 offset1:11
	ds_read2_b32 v[40:41], v115 offset0:17 offset1:18
	ds_read2_b32 v[42:43], v115 offset0:19 offset1:20
	ds_read2_b32 v[44:45], v115 offset0:25 offset1:26
	ds_read2_b32 v[46:47], v115 offset0:27 offset1:28
	v_mfma_f32_32x32x16_bf16 v[0:15], v[64:67], v[72:75], v[0:15]
	v_mfma_f32_32x32x16_bf16 v[16:31], v[64:67], v[76:79], v[16:31]
	v_mfma_f32_32x32x16_bf16 v[0:15], v[68:71], v[220:223], v[0:15]
	v_mfma_f32_32x32x16_bf16 v[16:31], v[68:71], v[224:227], v[16:31]
	global_load_dwordx4 v[156:159], v235, s[84:85]
	global_load_dwordx4 v[160:163], v236, s[84:85]
	global_load_dwordx4 v[164:167], v237, s[84:85]
	global_load_dwordx4 v[168:171], v238, s[84:85]
	global_load_dwordx4 v[172:175], v100, s[84:85] offset:768
	global_load_dwordx4 v[176:179], v149, s[84:85] offset:768
	global_load_dwordx4 v[180:183], v100, s[84:85] offset:832
	global_load_dwordx4 v[184:187], v149, s[84:85] offset:832
	s_add_u32 s84, s84, 0x30000
	s_addc_u32 s85, s85, 0
	ds_read_b64_tr_b16 v[72:73], v231
	ds_read_b64_tr_b16 v[74:75], v231 offset:512
	ds_read_b64_tr_b16 v[76:77], v231 offset:2048
	ds_read_b64_tr_b16 v[78:79], v231 offset:2560
	ds_read_b64_tr_b16 v[220:221], v231 offset:1024
	ds_read_b64_tr_b16 v[222:223], v231 offset:1536
	ds_read_b64_tr_b16 v[224:225], v231 offset:3072
	ds_read_b64_tr_b16 v[226:227], v231 offset:3584
	v_exp_f32_e32 v188, v188
	v_exp_f32_e32 v189, v189
	s_waitcnt vmcnt(8)
	ds_write_b128 v247, v[116:119]
	ds_write_b128 v247, v[120:123] offset:1024
	ds_write_b128 v247, v[124:127] offset:2048
	ds_write_b128 v247, v[128:131] offset:3072
	ds_read_b128 v[116:119], v248
	ds_read_b128 v[120:123], v249
	ds_read_b128 v[124:127], v250
	ds_read_b128 v[128:131], v251
	ds_write_b128 v112, v[132:135]
	ds_write_b128 v112, v[136:139] offset:1024
	ds_write_b128 v112, v[140:143] offset:2048
	ds_write_b128 v112, v[144:147] offset:3072
	v_exp_f32_e32 v190, v190
	v_exp_f32_e32 v191, v191
	s_waitcnt lgkmcnt(4)
	v_mfma_f32_32x32x16_bf16 v[32:47], v[116:119], v[48:51], v[32:47]
	v_exp_f32_e32 v192, v192
	v_exp_f32_e32 v193, v193
	v_exp_f32_e32 v194, v194
	v_mfma_f32_32x32x16_bf16 v[32:47], v[120:123], v[52:55], v[32:47]
	v_exp_f32_e32 v195, v195
	v_exp_f32_e32 v196, v196
	v_exp_f32_e32 v197, v197
	v_mfma_f32_32x32x16_bf16 v[32:47], v[124:127], v[56:59], v[32:47]
	v_exp_f32_e32 v198, v198
	v_exp_f32_e32 v199, v199
	v_exp_f32_e32 v200, v200
	v_mfma_f32_32x32x16_bf16 v[32:47], v[128:131], v[60:63], v[32:47]
	v_exp_f32_e32 v201, v201
	v_exp_f32_e32 v202, v202
	v_exp_f32_e32 v203, v203
	v_cvt_pk_bf16_f32 v64, v188, v189
	v_cvt_pk_bf16_f32 v65, v190, v191
	v_cvt_pk_bf16_f32 v66, v192, v193
	v_cvt_pk_bf16_f32 v67, v194, v195
	v_cvt_pk_bf16_f32 v68, v196, v197
	v_cvt_pk_bf16_f32 v69, v198, v199
	v_cvt_pk_bf16_f32 v70, v200, v201
	v_cvt_pk_bf16_f32 v71, v202, v203
	v_pk_add_f32 v[232:233], v[232:233], v[188:189]
	v_pk_add_f32 v[232:233], v[232:233], v[190:191]
	v_pk_add_f32 v[232:233], v[232:233], v[192:193]
	v_pk_add_f32 v[232:233], v[232:233], v[194:195]
	v_pk_add_f32 v[232:233], v[232:233], v[196:197]
	v_pk_add_f32 v[232:233], v[232:233], v[198:199]
	v_pk_add_f32 v[232:233], v[232:233], v[200:201]
	v_pk_add_f32 v[232:233], v[232:233], v[202:203]
	ds_read2_b32 v[188:189], v115 offset0:34 offset1:35
	ds_read2_b32 v[190:191], v115 offset0:36 offset1:37
	ds_read2_b32 v[192:193], v115 offset0:42 offset1:43
	ds_read2_b32 v[194:195], v115 offset0:44 offset1:45
	ds_read2_b32 v[196:197], v115 offset0:51 offset1:52
	ds_read2_b32 v[198:199], v115 offset0:53 offset1:54
	ds_read2_b32 v[200:201], v115 offset0:59 offset1:60
	ds_read2_b32 v[202:203], v115 offset0:61 offset1:62
	v_mfma_f32_32x32x16_bf16 v[0:15], v[64:67], v[72:75], v[0:15]
	v_mfma_f32_32x32x16_bf16 v[16:31], v[64:67], v[76:79], v[16:31]
	v_mfma_f32_32x32x16_bf16 v[0:15], v[68:71], v[220:223], v[0:15]
	v_mfma_f32_32x32x16_bf16 v[16:31], v[68:71], v[224:227], v[16:31]
	global_load_dwordx4 v[116:119], v235, s[84:85]
	global_load_dwordx4 v[120:123], v236, s[84:85]
	global_load_dwordx4 v[124:127], v237, s[84:85]
	global_load_dwordx4 v[128:131], v238, s[84:85]
	global_load_dwordx4 v[132:135], v100, s[84:85] offset:768
	global_load_dwordx4 v[136:139], v149, s[84:85] offset:768
	global_load_dwordx4 v[140:143], v100, s[84:85] offset:832
	global_load_dwordx4 v[144:147], v149, s[84:85] offset:832
	s_add_u32 s84, s84, 0x30000
	s_addc_u32 s85, s85, 0
	ds_read_b64_tr_b16 v[72:73], v231
	ds_read_b64_tr_b16 v[74:75], v231 offset:512
	ds_read_b64_tr_b16 v[76:77], v231 offset:2048
	ds_read_b64_tr_b16 v[78:79], v231 offset:2560
	ds_read_b64_tr_b16 v[220:221], v231 offset:1024
	ds_read_b64_tr_b16 v[222:223], v231 offset:1536
	ds_read_b64_tr_b16 v[224:225], v231 offset:3072
	ds_read_b64_tr_b16 v[226:227], v231 offset:3584
	v_exp_f32_e32 v32, v32
	v_exp_f32_e32 v33, v33
	s_waitcnt vmcnt(8)
	ds_write_b128 v247, v[156:159]
	ds_write_b128 v247, v[160:163] offset:1024
	ds_write_b128 v247, v[164:167] offset:2048
	ds_write_b128 v247, v[168:171] offset:3072
	ds_read_b128 v[156:159], v248
	ds_read_b128 v[160:163], v249
	ds_read_b128 v[164:167], v250
	ds_read_b128 v[168:171], v251
	ds_write_b128 v112, v[172:175]
	ds_write_b128 v112, v[176:179] offset:1024
	ds_write_b128 v112, v[180:183] offset:2048
	ds_write_b128 v112, v[184:187] offset:3072
	v_exp_f32_e32 v34, v34
	v_exp_f32_e32 v35, v35
	s_waitcnt lgkmcnt(4)
	v_mfma_f32_32x32x16_bf16 v[188:203], v[156:159], v[48:51], v[188:203]
	v_exp_f32_e32 v36, v36
	v_exp_f32_e32 v37, v37
	v_exp_f32_e32 v38, v38
	v_mfma_f32_32x32x16_bf16 v[188:203], v[160:163], v[52:55], v[188:203]
	v_exp_f32_e32 v39, v39
	v_exp_f32_e32 v40, v40
	v_exp_f32_e32 v41, v41
	v_mfma_f32_32x32x16_bf16 v[188:203], v[164:167], v[56:59], v[188:203]
	v_exp_f32_e32 v42, v42
	v_exp_f32_e32 v43, v43
	v_exp_f32_e32 v44, v44
	v_mfma_f32_32x32x16_bf16 v[188:203], v[168:171], v[60:63], v[188:203]
	v_exp_f32_e32 v45, v45
	v_exp_f32_e32 v46, v46
	v_exp_f32_e32 v47, v47
	v_cvt_pk_bf16_f32 v64, v32, v33
	v_cvt_pk_bf16_f32 v65, v34, v35
	v_cvt_pk_bf16_f32 v66, v36, v37
	v_cvt_pk_bf16_f32 v67, v38, v39
	v_cvt_pk_bf16_f32 v68, v40, v41
	v_cvt_pk_bf16_f32 v69, v42, v43
	v_cvt_pk_bf16_f32 v70, v44, v45
	v_cvt_pk_bf16_f32 v71, v46, v47
	v_pk_add_f32 v[232:233], v[232:233], v[32:33]
	v_pk_add_f32 v[232:233], v[232:233], v[34:35]
	v_pk_add_f32 v[232:233], v[232:233], v[36:37]
	v_pk_add_f32 v[232:233], v[232:233], v[38:39]
	v_pk_add_f32 v[232:233], v[232:233], v[40:41]
	v_pk_add_f32 v[232:233], v[232:233], v[42:43]
	v_pk_add_f32 v[232:233], v[232:233], v[44:45]
	v_pk_add_f32 v[232:233], v[232:233], v[46:47]
	ds_read2_b32 v[32:33], v115 offset0:68 offset1:69
	ds_read2_b32 v[34:35], v115 offset0:70 offset1:71
	ds_read2_b32 v[36:37], v115 offset0:76 offset1:77
	ds_read2_b32 v[38:39], v115 offset0:78 offset1:79
	ds_read2_b32 v[40:41], v115 offset0:85 offset1:86
	ds_read2_b32 v[42:43], v115 offset0:87 offset1:88
	ds_read2_b32 v[44:45], v115 offset0:93 offset1:94
	ds_read2_b32 v[46:47], v115 offset0:95 offset1:96
	v_mfma_f32_32x32x16_bf16 v[0:15], v[64:67], v[72:75], v[0:15]
	v_mfma_f32_32x32x16_bf16 v[16:31], v[64:67], v[76:79], v[16:31]
	v_mfma_f32_32x32x16_bf16 v[0:15], v[68:71], v[220:223], v[0:15]
	v_mfma_f32_32x32x16_bf16 v[16:31], v[68:71], v[224:227], v[16:31]
	global_load_dwordx4 v[156:159], v235, s[84:85]
	global_load_dwordx4 v[160:163], v236, s[84:85]
	global_load_dwordx4 v[164:167], v237, s[84:85]
	global_load_dwordx4 v[168:171], v238, s[84:85]
	global_load_dwordx4 v[172:175], v100, s[84:85] offset:768
	global_load_dwordx4 v[176:179], v149, s[84:85] offset:768
	global_load_dwordx4 v[180:183], v100, s[84:85] offset:832
	global_load_dwordx4 v[184:187], v149, s[84:85] offset:832
	s_add_u32 s84, s84, 0x30000
	s_addc_u32 s85, s85, 0
	ds_read_b64_tr_b16 v[72:73], v231
	ds_read_b64_tr_b16 v[74:75], v231 offset:512
	ds_read_b64_tr_b16 v[76:77], v231 offset:2048
	ds_read_b64_tr_b16 v[78:79], v231 offset:2560
	ds_read_b64_tr_b16 v[220:221], v231 offset:1024
	ds_read_b64_tr_b16 v[222:223], v231 offset:1536
	ds_read_b64_tr_b16 v[224:225], v231 offset:3072
	ds_read_b64_tr_b16 v[226:227], v231 offset:3584
	v_exp_f32_e32 v188, v188
	v_exp_f32_e32 v189, v189
	s_waitcnt vmcnt(8)
	ds_write_b128 v247, v[116:119]
	ds_write_b128 v247, v[120:123] offset:1024
	ds_write_b128 v247, v[124:127] offset:2048
	ds_write_b128 v247, v[128:131] offset:3072
	ds_read_b128 v[116:119], v248
	ds_read_b128 v[120:123], v249
	ds_read_b128 v[124:127], v250
	ds_read_b128 v[128:131], v251
	ds_write_b128 v112, v[132:135]
	ds_write_b128 v112, v[136:139] offset:1024
	ds_write_b128 v112, v[140:143] offset:2048
	ds_write_b128 v112, v[144:147] offset:3072
	v_exp_f32_e32 v190, v190
	v_exp_f32_e32 v191, v191
	s_waitcnt lgkmcnt(4)
	v_mfma_f32_32x32x16_bf16 v[32:47], v[116:119], v[48:51], v[32:47]
	v_exp_f32_e32 v192, v192
	v_exp_f32_e32 v193, v193
	v_exp_f32_e32 v194, v194
	v_mfma_f32_32x32x16_bf16 v[32:47], v[120:123], v[52:55], v[32:47]
	v_exp_f32_e32 v195, v195
	v_exp_f32_e32 v196, v196
	v_exp_f32_e32 v197, v197
	v_mfma_f32_32x32x16_bf16 v[32:47], v[124:127], v[56:59], v[32:47]
	v_exp_f32_e32 v198, v198
	v_exp_f32_e32 v199, v199
	v_exp_f32_e32 v200, v200
	v_mfma_f32_32x32x16_bf16 v[32:47], v[128:131], v[60:63], v[32:47]
	v_exp_f32_e32 v201, v201
	v_exp_f32_e32 v202, v202
	v_exp_f32_e32 v203, v203
	v_cvt_pk_bf16_f32 v64, v188, v189
	v_cvt_pk_bf16_f32 v65, v190, v191
	v_cvt_pk_bf16_f32 v66, v192, v193
	v_cvt_pk_bf16_f32 v67, v194, v195
	v_cvt_pk_bf16_f32 v68, v196, v197
	v_cvt_pk_bf16_f32 v69, v198, v199
	v_cvt_pk_bf16_f32 v70, v200, v201
	v_cvt_pk_bf16_f32 v71, v202, v203
	v_pk_add_f32 v[232:233], v[232:233], v[188:189]
	v_pk_add_f32 v[232:233], v[232:233], v[190:191]
	v_pk_add_f32 v[232:233], v[232:233], v[192:193]
	v_pk_add_f32 v[232:233], v[232:233], v[194:195]
	v_pk_add_f32 v[232:233], v[232:233], v[196:197]
	v_pk_add_f32 v[232:233], v[232:233], v[198:199]
	v_pk_add_f32 v[232:233], v[232:233], v[200:201]
	v_pk_add_f32 v[232:233], v[232:233], v[202:203]
	ds_read2_b32 v[188:189], v115 offset0:102 offset1:103
	ds_read2_b32 v[190:191], v115 offset0:104 offset1:105
	ds_read2_b32 v[192:193], v115 offset0:110 offset1:111
	ds_read2_b32 v[194:195], v115 offset0:112 offset1:113
	ds_read2_b32 v[196:197], v115 offset0:119 offset1:120
	ds_read2_b32 v[198:199], v115 offset0:121 offset1:122
	ds_read2_b32 v[200:201], v115 offset0:127 offset1:128
	ds_read2_b32 v[202:203], v115 offset0:129 offset1:130
	v_mfma_f32_32x32x16_bf16 v[0:15], v[64:67], v[72:75], v[0:15]
	v_mfma_f32_32x32x16_bf16 v[16:31], v[64:67], v[76:79], v[16:31]
	v_mfma_f32_32x32x16_bf16 v[0:15], v[68:71], v[220:223], v[0:15]
	v_mfma_f32_32x32x16_bf16 v[16:31], v[68:71], v[224:227], v[16:31]
	global_load_dwordx4 v[116:119], v235, s[84:85]
	global_load_dwordx4 v[120:123], v236, s[84:85]
	global_load_dwordx4 v[124:127], v237, s[84:85]
	global_load_dwordx4 v[128:131], v238, s[84:85]
	global_load_dwordx4 v[132:135], v100, s[84:85] offset:768
	global_load_dwordx4 v[136:139], v149, s[84:85] offset:768
	global_load_dwordx4 v[140:143], v100, s[84:85] offset:832
	global_load_dwordx4 v[144:147], v149, s[84:85] offset:832
	s_add_u32 s84, s84, 0x30000
	s_addc_u32 s85, s85, 0
	ds_read_b64_tr_b16 v[72:73], v231
	ds_read_b64_tr_b16 v[74:75], v231 offset:512
	ds_read_b64_tr_b16 v[76:77], v231 offset:2048
	ds_read_b64_tr_b16 v[78:79], v231 offset:2560
	ds_read_b64_tr_b16 v[220:221], v231 offset:1024
	ds_read_b64_tr_b16 v[222:223], v231 offset:1536
	ds_read_b64_tr_b16 v[224:225], v231 offset:3072
	ds_read_b64_tr_b16 v[226:227], v231 offset:3584
	v_exp_f32_e32 v32, v32
	v_exp_f32_e32 v33, v33
	s_waitcnt vmcnt(8)
	ds_write_b128 v247, v[156:159]
	ds_write_b128 v247, v[160:163] offset:1024
	ds_write_b128 v247, v[164:167] offset:2048
	ds_write_b128 v247, v[168:171] offset:3072
	ds_read_b128 v[156:159], v248
	ds_read_b128 v[160:163], v249
	ds_read_b128 v[164:167], v250
	ds_read_b128 v[168:171], v251
	ds_write_b128 v112, v[172:175]
	ds_write_b128 v112, v[176:179] offset:1024
	ds_write_b128 v112, v[180:183] offset:2048
	ds_write_b128 v112, v[184:187] offset:3072
	v_exp_f32_e32 v34, v34
	v_exp_f32_e32 v35, v35
	s_waitcnt lgkmcnt(4)
	v_mfma_f32_32x32x16_bf16 v[188:203], v[156:159], v[48:51], v[188:203]
	v_exp_f32_e32 v36, v36
	v_exp_f32_e32 v37, v37
	v_exp_f32_e32 v38, v38
	v_mfma_f32_32x32x16_bf16 v[188:203], v[160:163], v[52:55], v[188:203]
	v_exp_f32_e32 v39, v39
	v_exp_f32_e32 v40, v40
	v_exp_f32_e32 v41, v41
	v_mfma_f32_32x32x16_bf16 v[188:203], v[164:167], v[56:59], v[188:203]
	v_exp_f32_e32 v42, v42
	v_exp_f32_e32 v43, v43
	v_exp_f32_e32 v44, v44
	v_mfma_f32_32x32x16_bf16 v[188:203], v[168:171], v[60:63], v[188:203]
	v_exp_f32_e32 v45, v45
	v_exp_f32_e32 v46, v46
	v_exp_f32_e32 v47, v47
	v_cvt_pk_bf16_f32 v64, v32, v33
	v_cvt_pk_bf16_f32 v65, v34, v35
	v_cvt_pk_bf16_f32 v66, v36, v37
	v_cvt_pk_bf16_f32 v67, v38, v39
	v_cvt_pk_bf16_f32 v68, v40, v41
	v_cvt_pk_bf16_f32 v69, v42, v43
	v_cvt_pk_bf16_f32 v70, v44, v45
	v_cvt_pk_bf16_f32 v71, v46, v47
	v_pk_add_f32 v[232:233], v[232:233], v[32:33]
	v_pk_add_f32 v[232:233], v[232:233], v[34:35]
	v_pk_add_f32 v[232:233], v[232:233], v[36:37]
	v_pk_add_f32 v[232:233], v[232:233], v[38:39]
	v_pk_add_f32 v[232:233], v[232:233], v[40:41]
	v_pk_add_f32 v[232:233], v[232:233], v[42:43]
	v_pk_add_f32 v[232:233], v[232:233], v[44:45]
	v_pk_add_f32 v[232:233], v[232:233], v[46:47]
	ds_read2_b32 v[32:33], v115 offset0:136 offset1:137
	ds_read2_b32 v[34:35], v115 offset0:138 offset1:139
	ds_read2_b32 v[36:37], v115 offset0:144 offset1:145
	ds_read2_b32 v[38:39], v115 offset0:146 offset1:147
	ds_read2_b32 v[40:41], v115 offset0:153 offset1:154
	ds_read2_b32 v[42:43], v115 offset0:155 offset1:156
	ds_read2_b32 v[44:45], v115 offset0:161 offset1:162
	ds_read2_b32 v[46:47], v115 offset0:163 offset1:164
	v_mfma_f32_32x32x16_bf16 v[0:15], v[64:67], v[72:75], v[0:15]
	v_mfma_f32_32x32x16_bf16 v[16:31], v[64:67], v[76:79], v[16:31]
	v_mfma_f32_32x32x16_bf16 v[0:15], v[68:71], v[220:223], v[0:15]
	v_mfma_f32_32x32x16_bf16 v[16:31], v[68:71], v[224:227], v[16:31]
	global_load_dwordx4 v[156:159], v235, s[84:85]
	global_load_dwordx4 v[160:163], v236, s[84:85]
	global_load_dwordx4 v[164:167], v237, s[84:85]
	global_load_dwordx4 v[168:171], v238, s[84:85]
	global_load_dwordx4 v[172:175], v100, s[84:85] offset:768
	global_load_dwordx4 v[176:179], v149, s[84:85] offset:768
	global_load_dwordx4 v[180:183], v100, s[84:85] offset:832
	global_load_dwordx4 v[184:187], v149, s[84:85] offset:832
	ds_read_b64_tr_b16 v[72:73], v231
	ds_read_b64_tr_b16 v[74:75], v231 offset:512
	ds_read_b64_tr_b16 v[76:77], v231 offset:2048
	ds_read_b64_tr_b16 v[78:79], v231 offset:2560
	ds_read_b64_tr_b16 v[220:221], v231 offset:1024
	ds_read_b64_tr_b16 v[222:223], v231 offset:1536
	ds_read_b64_tr_b16 v[224:225], v231 offset:3072
	ds_read_b64_tr_b16 v[226:227], v231 offset:3584
	v_exp_f32_e32 v188, v188
	v_exp_f32_e32 v189, v189
	s_waitcnt vmcnt(8)
	ds_write_b128 v247, v[116:119]
	ds_write_b128 v247, v[120:123] offset:1024
	ds_write_b128 v247, v[124:127] offset:2048
	ds_write_b128 v247, v[128:131] offset:3072
	ds_read_b128 v[116:119], v248
	ds_read_b128 v[120:123], v249
	ds_read_b128 v[124:127], v250
	ds_read_b128 v[128:131], v251
	ds_write_b128 v112, v[132:135]
	ds_write_b128 v112, v[136:139] offset:1024
	ds_write_b128 v112, v[140:143] offset:2048
	ds_write_b128 v112, v[144:147] offset:3072
	v_exp_f32_e32 v190, v190
	v_exp_f32_e32 v191, v191
	s_waitcnt lgkmcnt(4)
	v_mfma_f32_32x32x16_bf16 v[32:47], v[116:119], v[48:51], v[32:47]
	v_exp_f32_e32 v192, v192
	v_exp_f32_e32 v193, v193
	v_exp_f32_e32 v194, v194
	v_mfma_f32_32x32x16_bf16 v[32:47], v[120:123], v[52:55], v[32:47]
	v_exp_f32_e32 v195, v195
	v_exp_f32_e32 v196, v196
	v_exp_f32_e32 v197, v197
	v_mfma_f32_32x32x16_bf16 v[32:47], v[124:127], v[56:59], v[32:47]
	v_exp_f32_e32 v198, v198
	v_exp_f32_e32 v199, v199
	v_exp_f32_e32 v200, v200
	v_mfma_f32_32x32x16_bf16 v[32:47], v[128:131], v[60:63], v[32:47]
	v_exp_f32_e32 v201, v201
	v_exp_f32_e32 v202, v202
	v_exp_f32_e32 v203, v203
	v_cvt_pk_bf16_f32 v64, v188, v189
	v_cvt_pk_bf16_f32 v65, v190, v191
	v_cvt_pk_bf16_f32 v66, v192, v193
	v_cvt_pk_bf16_f32 v67, v194, v195
	v_cvt_pk_bf16_f32 v68, v196, v197
	v_cvt_pk_bf16_f32 v69, v198, v199
	v_cvt_pk_bf16_f32 v70, v200, v201
	v_cvt_pk_bf16_f32 v71, v202, v203
	v_pk_add_f32 v[232:233], v[232:233], v[188:189]
	v_pk_add_f32 v[232:233], v[232:233], v[190:191]
	v_pk_add_f32 v[232:233], v[232:233], v[192:193]
	v_pk_add_f32 v[232:233], v[232:233], v[194:195]
	v_pk_add_f32 v[232:233], v[232:233], v[196:197]
	v_pk_add_f32 v[232:233], v[232:233], v[198:199]
	v_pk_add_f32 v[232:233], v[232:233], v[200:201]
	v_pk_add_f32 v[232:233], v[232:233], v[202:203]
	ds_read2_b32 v[188:189], v115 offset0:170 offset1:171
	ds_read2_b32 v[190:191], v115 offset0:172 offset1:173
	ds_read2_b32 v[192:193], v115 offset0:178 offset1:179
	ds_read2_b32 v[194:195], v115 offset0:180 offset1:181
	ds_read2_b32 v[196:197], v115 offset0:187 offset1:188
	ds_read2_b32 v[198:199], v115 offset0:189 offset1:190
	ds_read2_b32 v[200:201], v115 offset0:195 offset1:196
	ds_read2_b32 v[202:203], v115 offset0:197 offset1:198
	v_mfma_f32_32x32x16_bf16 v[0:15], v[64:67], v[72:75], v[0:15]
	v_mfma_f32_32x32x16_bf16 v[16:31], v[64:67], v[76:79], v[16:31]
	v_mfma_f32_32x32x16_bf16 v[0:15], v[68:71], v[220:223], v[0:15]
	v_mfma_f32_32x32x16_bf16 v[16:31], v[68:71], v[224:227], v[16:31]
	global_load_dwordx4 v[116:119], v239, s[86:87]
	global_load_dwordx4 v[120:123], v240, s[86:87]
	global_load_dwordx4 v[124:127], v241, s[86:87]
	global_load_dwordx4 v[128:131], v242, s[86:87]
	global_load_dwordx4 v[132:135], v101, s[86:87] offset:768
	global_load_dwordx4 v[136:139], v150, s[86:87] offset:768
	global_load_dwordx4 v[140:143], v101, s[86:87] offset:832
	global_load_dwordx4 v[144:147], v150, s[86:87] offset:832
	s_add_u32 s86, s86, 0xc0000
	s_addc_u32 s87, s87, 0
	ds_read_b64_tr_b16 v[72:73], v231
	ds_read_b64_tr_b16 v[74:75], v231 offset:512
	ds_read_b64_tr_b16 v[76:77], v231 offset:2048
	ds_read_b64_tr_b16 v[78:79], v231 offset:2560
	ds_read_b64_tr_b16 v[220:221], v231 offset:1024
	ds_read_b64_tr_b16 v[222:223], v231 offset:1536
	ds_read_b64_tr_b16 v[224:225], v231 offset:3072
	ds_read_b64_tr_b16 v[226:227], v231 offset:3584
	v_exp_f32_e32 v32, v32
	v_exp_f32_e32 v33, v33
	s_waitcnt vmcnt(8)
	ds_write_b128 v247, v[156:159]
	ds_write_b128 v247, v[160:163] offset:1024
	ds_write_b128 v247, v[164:167] offset:2048
	ds_write_b128 v247, v[168:171] offset:3072
	ds_read_b128 v[156:159], v248
	ds_read_b128 v[160:163], v249
	ds_read_b128 v[164:167], v250
	ds_read_b128 v[168:171], v251
	ds_write_b128 v112, v[172:175]
	ds_write_b128 v112, v[176:179] offset:1024
	ds_write_b128 v112, v[180:183] offset:2048
	ds_write_b128 v112, v[184:187] offset:3072
	v_exp_f32_e32 v34, v34
	v_exp_f32_e32 v35, v35
	s_waitcnt lgkmcnt(4)
	v_mfma_f32_32x32x16_bf16 v[188:203], v[156:159], v[48:51], v[188:203]
	v_exp_f32_e32 v36, v36
	v_exp_f32_e32 v37, v37
	v_exp_f32_e32 v38, v38
	v_mfma_f32_32x32x16_bf16 v[188:203], v[160:163], v[52:55], v[188:203]
	v_exp_f32_e32 v39, v39
	v_exp_f32_e32 v40, v40
	v_exp_f32_e32 v41, v41
	v_mfma_f32_32x32x16_bf16 v[188:203], v[164:167], v[56:59], v[188:203]
	v_exp_f32_e32 v42, v42
	v_exp_f32_e32 v43, v43
	v_exp_f32_e32 v44, v44
	v_mfma_f32_32x32x16_bf16 v[188:203], v[168:171], v[60:63], v[188:203]
	v_exp_f32_e32 v45, v45
	v_exp_f32_e32 v46, v46
	v_exp_f32_e32 v47, v47
	v_cvt_pk_bf16_f32 v64, v32, v33
	v_cvt_pk_bf16_f32 v65, v34, v35
	v_cvt_pk_bf16_f32 v66, v36, v37
	v_cvt_pk_bf16_f32 v67, v38, v39
	v_cvt_pk_bf16_f32 v68, v40, v41
	v_cvt_pk_bf16_f32 v69, v42, v43
	v_cvt_pk_bf16_f32 v70, v44, v45
	v_cvt_pk_bf16_f32 v71, v46, v47
	v_pk_add_f32 v[232:233], v[232:233], v[32:33]
	v_pk_add_f32 v[232:233], v[232:233], v[34:35]
	v_pk_add_f32 v[232:233], v[232:233], v[36:37]
	v_pk_add_f32 v[232:233], v[232:233], v[38:39]
	v_pk_add_f32 v[232:233], v[232:233], v[40:41]
	v_pk_add_f32 v[232:233], v[232:233], v[42:43]
	v_pk_add_f32 v[232:233], v[232:233], v[44:45]
	v_pk_add_f32 v[232:233], v[232:233], v[46:47]
	v_mov_b32_e32 v115, v229
	ds_read2_b32 v[32:33], v115 offset0:0 offset1:1
	ds_read2_b32 v[34:35], v115 offset0:2 offset1:3
	ds_read2_b32 v[36:37], v115 offset0:8 offset1:9
	ds_read2_b32 v[38:39], v115 offset0:10 offset1:11
	ds_read2_b32 v[40:41], v115 offset0:16 offset1:17
	ds_read2_b32 v[42:43], v115 offset0:18 offset1:19
	ds_read2_b32 v[44:45], v115 offset0:24 offset1:25
	ds_read2_b32 v[46:47], v115 offset0:26 offset1:27
	v_mfma_f32_32x32x16_bf16 v[0:15], v[64:67], v[72:75], v[0:15]
	v_mfma_f32_32x32x16_bf16 v[16:31], v[64:67], v[76:79], v[16:31]
	v_mfma_f32_32x32x16_bf16 v[0:15], v[68:71], v[220:223], v[0:15]
	v_mfma_f32_32x32x16_bf16 v[16:31], v[68:71], v[224:227], v[16:31]
	global_load_dwordx4 v[156:159], v239, s[86:87]
	global_load_dwordx4 v[160:163], v240, s[86:87]
	global_load_dwordx4 v[164:167], v241, s[86:87]
	global_load_dwordx4 v[168:171], v242, s[86:87]
	global_load_dwordx4 v[172:175], v101, s[86:87] offset:768
	global_load_dwordx4 v[176:179], v150, s[86:87] offset:768
	global_load_dwordx4 v[180:183], v101, s[86:87] offset:832
	global_load_dwordx4 v[184:187], v150, s[86:87] offset:832
	s_add_u32 s86, s86, 0xc0000
	s_addc_u32 s87, s87, 0
	ds_read_b64_tr_b16 v[72:73], v231
	ds_read_b64_tr_b16 v[74:75], v231 offset:512
	ds_read_b64_tr_b16 v[76:77], v231 offset:2048
	ds_read_b64_tr_b16 v[78:79], v231 offset:2560
	ds_read_b64_tr_b16 v[220:221], v231 offset:1024
	ds_read_b64_tr_b16 v[222:223], v231 offset:1536
	ds_read_b64_tr_b16 v[224:225], v231 offset:3072
	ds_read_b64_tr_b16 v[226:227], v231 offset:3584
	v_exp_f32_e32 v188, v188
	v_exp_f32_e32 v189, v189
	s_waitcnt vmcnt(8)
	ds_write_b128 v247, v[116:119]
	ds_write_b128 v247, v[120:123] offset:1024
	ds_write_b128 v247, v[124:127] offset:2048
	ds_write_b128 v247, v[128:131] offset:3072
	ds_read_b128 v[116:119], v248
	ds_read_b128 v[120:123], v249
	ds_read_b128 v[124:127], v250
	ds_read_b128 v[128:131], v251
	ds_write_b128 v112, v[132:135]
	ds_write_b128 v112, v[136:139] offset:1024
	ds_write_b128 v112, v[140:143] offset:2048
	ds_write_b128 v112, v[144:147] offset:3072
	v_exp_f32_e32 v190, v190
	v_exp_f32_e32 v191, v191
	s_waitcnt lgkmcnt(4)
	v_mfma_f32_32x32x16_bf16 v[32:47], v[116:119], v[48:51], v[32:47]
	v_exp_f32_e32 v192, v192
	v_exp_f32_e32 v193, v193
	v_exp_f32_e32 v194, v194
	v_mfma_f32_32x32x16_bf16 v[32:47], v[120:123], v[52:55], v[32:47]
	v_exp_f32_e32 v195, v195
	v_exp_f32_e32 v196, v196
	v_exp_f32_e32 v197, v197
	v_mfma_f32_32x32x16_bf16 v[32:47], v[124:127], v[56:59], v[32:47]
	v_exp_f32_e32 v198, v198
	v_exp_f32_e32 v199, v199
	v_exp_f32_e32 v200, v200
	v_mfma_f32_32x32x16_bf16 v[32:47], v[128:131], v[60:63], v[32:47]
	v_exp_f32_e32 v201, v201
	v_exp_f32_e32 v202, v202
	v_exp_f32_e32 v203, v203
	v_cvt_pk_bf16_f32 v64, v188, v189
	v_cvt_pk_bf16_f32 v65, v190, v191
	v_cvt_pk_bf16_f32 v66, v192, v193
	v_cvt_pk_bf16_f32 v67, v194, v195
	v_cvt_pk_bf16_f32 v68, v196, v197
	v_cvt_pk_bf16_f32 v69, v198, v199
	v_cvt_pk_bf16_f32 v70, v200, v201
	v_cvt_pk_bf16_f32 v71, v202, v203
	v_pk_add_f32 v[232:233], v[232:233], v[188:189]
	v_pk_add_f32 v[232:233], v[232:233], v[190:191]
	v_pk_add_f32 v[232:233], v[232:233], v[192:193]
	v_pk_add_f32 v[232:233], v[232:233], v[194:195]
	v_pk_add_f32 v[232:233], v[232:233], v[196:197]
	v_pk_add_f32 v[232:233], v[232:233], v[198:199]
	v_pk_add_f32 v[232:233], v[232:233], v[200:201]
	v_pk_add_f32 v[232:233], v[232:233], v[202:203]
	ds_read2_b32 v[188:189], v115 offset0:32 offset1:33
	ds_read2_b32 v[190:191], v115 offset0:34 offset1:35
	ds_read2_b32 v[192:193], v115 offset0:40 offset1:41
	ds_read2_b32 v[194:195], v115 offset0:42 offset1:43
	ds_read2_b32 v[196:197], v115 offset0:48 offset1:49
	ds_read2_b32 v[198:199], v115 offset0:50 offset1:51
	ds_read2_b32 v[200:201], v115 offset0:56 offset1:57
	ds_read2_b32 v[202:203], v115 offset0:58 offset1:59
	v_mfma_f32_32x32x16_bf16 v[0:15], v[64:67], v[72:75], v[0:15]
	v_mfma_f32_32x32x16_bf16 v[16:31], v[64:67], v[76:79], v[16:31]
	v_mfma_f32_32x32x16_bf16 v[0:15], v[68:71], v[220:223], v[0:15]
	v_mfma_f32_32x32x16_bf16 v[16:31], v[68:71], v[224:227], v[16:31]
	global_load_dwordx4 v[116:119], v239, s[86:87]
	global_load_dwordx4 v[120:123], v240, s[86:87]
	global_load_dwordx4 v[124:127], v241, s[86:87]
	global_load_dwordx4 v[128:131], v242, s[86:87]
	global_load_dwordx4 v[132:135], v101, s[86:87] offset:768
	global_load_dwordx4 v[136:139], v150, s[86:87] offset:768
	global_load_dwordx4 v[140:143], v101, s[86:87] offset:832
	global_load_dwordx4 v[144:147], v150, s[86:87] offset:832
	s_add_u32 s86, s86, 0xc0000
	s_addc_u32 s87, s87, 0
	ds_read_b64_tr_b16 v[72:73], v231
	ds_read_b64_tr_b16 v[74:75], v231 offset:512
	ds_read_b64_tr_b16 v[76:77], v231 offset:2048
	ds_read_b64_tr_b16 v[78:79], v231 offset:2560
	ds_read_b64_tr_b16 v[220:221], v231 offset:1024
	ds_read_b64_tr_b16 v[222:223], v231 offset:1536
	ds_read_b64_tr_b16 v[224:225], v231 offset:3072
	ds_read_b64_tr_b16 v[226:227], v231 offset:3584
	v_exp_f32_e32 v32, v32
	v_exp_f32_e32 v33, v33
	s_waitcnt vmcnt(8)
	ds_write_b128 v247, v[156:159]
	ds_write_b128 v247, v[160:163] offset:1024
	ds_write_b128 v247, v[164:167] offset:2048
	ds_write_b128 v247, v[168:171] offset:3072
	ds_read_b128 v[156:159], v248
	ds_read_b128 v[160:163], v249
	ds_read_b128 v[164:167], v250
	ds_read_b128 v[168:171], v251
	ds_write_b128 v112, v[172:175]
	ds_write_b128 v112, v[176:179] offset:1024
	ds_write_b128 v112, v[180:183] offset:2048
	ds_write_b128 v112, v[184:187] offset:3072
	v_exp_f32_e32 v34, v34
	v_exp_f32_e32 v35, v35
	s_waitcnt lgkmcnt(4)
	v_mfma_f32_32x32x16_bf16 v[188:203], v[156:159], v[48:51], v[188:203]
	v_exp_f32_e32 v36, v36
	v_exp_f32_e32 v37, v37
	v_exp_f32_e32 v38, v38
	v_mfma_f32_32x32x16_bf16 v[188:203], v[160:163], v[52:55], v[188:203]
	v_exp_f32_e32 v39, v39
	v_exp_f32_e32 v40, v40
	v_exp_f32_e32 v41, v41
	v_mfma_f32_32x32x16_bf16 v[188:203], v[164:167], v[56:59], v[188:203]
	v_exp_f32_e32 v42, v42
	v_exp_f32_e32 v43, v43
	v_exp_f32_e32 v44, v44
	v_mfma_f32_32x32x16_bf16 v[188:203], v[168:171], v[60:63], v[188:203]
	v_exp_f32_e32 v45, v45
	v_exp_f32_e32 v46, v46
	v_exp_f32_e32 v47, v47
	v_cvt_pk_bf16_f32 v64, v32, v33
	v_cvt_pk_bf16_f32 v65, v34, v35
	v_cvt_pk_bf16_f32 v66, v36, v37
	v_cvt_pk_bf16_f32 v67, v38, v39
	v_cvt_pk_bf16_f32 v68, v40, v41
	v_cvt_pk_bf16_f32 v69, v42, v43
	v_cvt_pk_bf16_f32 v70, v44, v45
	v_cvt_pk_bf16_f32 v71, v46, v47
	v_pk_add_f32 v[232:233], v[232:233], v[32:33]
	v_pk_add_f32 v[232:233], v[232:233], v[34:35]
	v_pk_add_f32 v[232:233], v[232:233], v[36:37]
	v_pk_add_f32 v[232:233], v[232:233], v[38:39]
	v_pk_add_f32 v[232:233], v[232:233], v[40:41]
	v_pk_add_f32 v[232:233], v[232:233], v[42:43]
	v_pk_add_f32 v[232:233], v[232:233], v[44:45]
	v_pk_add_f32 v[232:233], v[232:233], v[46:47]
	ds_read2_b32 v[32:33], v115 offset0:64 offset1:65
	ds_read2_b32 v[34:35], v115 offset0:66 offset1:67
	ds_read2_b32 v[36:37], v115 offset0:72 offset1:73
	ds_read2_b32 v[38:39], v115 offset0:74 offset1:75
	ds_read2_b32 v[40:41], v115 offset0:80 offset1:81
	ds_read2_b32 v[42:43], v115 offset0:82 offset1:83
	ds_read2_b32 v[44:45], v115 offset0:88 offset1:89
	ds_read2_b32 v[46:47], v115 offset0:90 offset1:91
	v_mfma_f32_32x32x16_bf16 v[0:15], v[64:67], v[72:75], v[0:15]
	v_mfma_f32_32x32x16_bf16 v[16:31], v[64:67], v[76:79], v[16:31]
	v_mfma_f32_32x32x16_bf16 v[0:15], v[68:71], v[220:223], v[0:15]
	v_mfma_f32_32x32x16_bf16 v[16:31], v[68:71], v[224:227], v[16:31]
	global_load_dwordx4 v[156:159], v239, s[86:87]
	global_load_dwordx4 v[160:163], v240, s[86:87]
	global_load_dwordx4 v[164:167], v241, s[86:87]
	global_load_dwordx4 v[168:171], v242, s[86:87]
	global_load_dwordx4 v[172:175], v101, s[86:87] offset:768
	global_load_dwordx4 v[176:179], v150, s[86:87] offset:768
	global_load_dwordx4 v[180:183], v101, s[86:87] offset:832
	global_load_dwordx4 v[184:187], v150, s[86:87] offset:832
	s_add_u32 s86, s86, 0xc0000
	s_addc_u32 s87, s87, 0
	ds_read_b64_tr_b16 v[72:73], v231
	ds_read_b64_tr_b16 v[74:75], v231 offset:512
	ds_read_b64_tr_b16 v[76:77], v231 offset:2048
	ds_read_b64_tr_b16 v[78:79], v231 offset:2560
	ds_read_b64_tr_b16 v[220:221], v231 offset:1024
	ds_read_b64_tr_b16 v[222:223], v231 offset:1536
	ds_read_b64_tr_b16 v[224:225], v231 offset:3072
	ds_read_b64_tr_b16 v[226:227], v231 offset:3584
	v_exp_f32_e32 v188, v188
	v_exp_f32_e32 v189, v189
	s_waitcnt vmcnt(8)
	ds_write_b128 v247, v[116:119]
	ds_write_b128 v247, v[120:123] offset:1024
	ds_write_b128 v247, v[124:127] offset:2048
	ds_write_b128 v247, v[128:131] offset:3072
	ds_read_b128 v[116:119], v248
	ds_read_b128 v[120:123], v249
	ds_read_b128 v[124:127], v250
	ds_read_b128 v[128:131], v251
	ds_write_b128 v112, v[132:135]
	ds_write_b128 v112, v[136:139] offset:1024
	ds_write_b128 v112, v[140:143] offset:2048
	ds_write_b128 v112, v[144:147] offset:3072
	v_exp_f32_e32 v190, v190
	v_exp_f32_e32 v191, v191
	s_waitcnt lgkmcnt(4)
	v_mfma_f32_32x32x16_bf16 v[32:47], v[116:119], v[48:51], v[32:47]
	v_exp_f32_e32 v192, v192
	v_exp_f32_e32 v193, v193
	v_exp_f32_e32 v194, v194
	v_mfma_f32_32x32x16_bf16 v[32:47], v[120:123], v[52:55], v[32:47]
	v_exp_f32_e32 v195, v195
	v_exp_f32_e32 v196, v196
	v_exp_f32_e32 v197, v197
	v_mfma_f32_32x32x16_bf16 v[32:47], v[124:127], v[56:59], v[32:47]
	v_exp_f32_e32 v198, v198
	v_exp_f32_e32 v199, v199
	v_exp_f32_e32 v200, v200
	v_mfma_f32_32x32x16_bf16 v[32:47], v[128:131], v[60:63], v[32:47]
	v_exp_f32_e32 v201, v201
	v_exp_f32_e32 v202, v202
	v_exp_f32_e32 v203, v203
	v_cvt_pk_bf16_f32 v64, v188, v189
	v_cvt_pk_bf16_f32 v65, v190, v191
	v_cvt_pk_bf16_f32 v66, v192, v193
	v_cvt_pk_bf16_f32 v67, v194, v195
	v_cvt_pk_bf16_f32 v68, v196, v197
	v_cvt_pk_bf16_f32 v69, v198, v199
	v_cvt_pk_bf16_f32 v70, v200, v201
	v_cvt_pk_bf16_f32 v71, v202, v203
	v_pk_add_f32 v[232:233], v[232:233], v[188:189]
	v_pk_add_f32 v[232:233], v[232:233], v[190:191]
	v_pk_add_f32 v[232:233], v[232:233], v[192:193]
	v_pk_add_f32 v[232:233], v[232:233], v[194:195]
	v_pk_add_f32 v[232:233], v[232:233], v[196:197]
	v_pk_add_f32 v[232:233], v[232:233], v[198:199]
	v_pk_add_f32 v[232:233], v[232:233], v[200:201]
	v_pk_add_f32 v[232:233], v[232:233], v[202:203]
	ds_read2_b32 v[188:189], v115 offset0:96 offset1:97
	ds_read2_b32 v[190:191], v115 offset0:98 offset1:99
	ds_read2_b32 v[192:193], v115 offset0:104 offset1:105
	ds_read2_b32 v[194:195], v115 offset0:106 offset1:107
	ds_read2_b32 v[196:197], v115 offset0:112 offset1:113
	ds_read2_b32 v[198:199], v115 offset0:114 offset1:115
	ds_read2_b32 v[200:201], v115 offset0:120 offset1:121
	ds_read2_b32 v[202:203], v115 offset0:122 offset1:123
	v_mfma_f32_32x32x16_bf16 v[0:15], v[64:67], v[72:75], v[0:15]
	v_mfma_f32_32x32x16_bf16 v[16:31], v[64:67], v[76:79], v[16:31]
	v_mfma_f32_32x32x16_bf16 v[0:15], v[68:71], v[220:223], v[0:15]
	v_mfma_f32_32x32x16_bf16 v[16:31], v[68:71], v[224:227], v[16:31]
	global_load_dwordx4 v[116:119], v239, s[86:87]
	global_load_dwordx4 v[120:123], v240, s[86:87]
	global_load_dwordx4 v[124:127], v241, s[86:87]
	global_load_dwordx4 v[128:131], v242, s[86:87]
	global_load_dwordx4 v[132:135], v101, s[86:87] offset:768
	global_load_dwordx4 v[136:139], v150, s[86:87] offset:768
	global_load_dwordx4 v[140:143], v101, s[86:87] offset:832
	global_load_dwordx4 v[144:147], v150, s[86:87] offset:832
	s_add_u32 s86, s86, 0xc0000
	s_addc_u32 s87, s87, 0
	ds_read_b64_tr_b16 v[72:73], v231
	ds_read_b64_tr_b16 v[74:75], v231 offset:512
	ds_read_b64_tr_b16 v[76:77], v231 offset:2048
	ds_read_b64_tr_b16 v[78:79], v231 offset:2560
	ds_read_b64_tr_b16 v[220:221], v231 offset:1024
	ds_read_b64_tr_b16 v[222:223], v231 offset:1536
	ds_read_b64_tr_b16 v[224:225], v231 offset:3072
	ds_read_b64_tr_b16 v[226:227], v231 offset:3584
	v_exp_f32_e32 v32, v32
	v_exp_f32_e32 v33, v33
	s_waitcnt vmcnt(8)
	ds_write_b128 v247, v[156:159]
	ds_write_b128 v247, v[160:163] offset:1024
	ds_write_b128 v247, v[164:167] offset:2048
	ds_write_b128 v247, v[168:171] offset:3072
	ds_read_b128 v[156:159], v248
	ds_read_b128 v[160:163], v249
	ds_read_b128 v[164:167], v250
	ds_read_b128 v[168:171], v251
	ds_write_b128 v112, v[172:175]
	ds_write_b128 v112, v[176:179] offset:1024
	ds_write_b128 v112, v[180:183] offset:2048
	ds_write_b128 v112, v[184:187] offset:3072
	v_exp_f32_e32 v34, v34
	v_exp_f32_e32 v35, v35
	s_waitcnt lgkmcnt(4)
	v_mfma_f32_32x32x16_bf16 v[188:203], v[156:159], v[48:51], v[188:203]
	v_exp_f32_e32 v36, v36
	v_exp_f32_e32 v37, v37
	v_exp_f32_e32 v38, v38
	v_mfma_f32_32x32x16_bf16 v[188:203], v[160:163], v[52:55], v[188:203]
	v_exp_f32_e32 v39, v39
	v_exp_f32_e32 v40, v40
	v_exp_f32_e32 v41, v41
	v_mfma_f32_32x32x16_bf16 v[188:203], v[164:167], v[56:59], v[188:203]
	v_exp_f32_e32 v42, v42
	v_exp_f32_e32 v43, v43
	v_exp_f32_e32 v44, v44
	v_mfma_f32_32x32x16_bf16 v[188:203], v[168:171], v[60:63], v[188:203]
	v_exp_f32_e32 v45, v45
	v_exp_f32_e32 v46, v46
	v_exp_f32_e32 v47, v47
	v_cvt_pk_bf16_f32 v64, v32, v33
	v_cvt_pk_bf16_f32 v65, v34, v35
	v_cvt_pk_bf16_f32 v66, v36, v37
	v_cvt_pk_bf16_f32 v67, v38, v39
	v_cvt_pk_bf16_f32 v68, v40, v41
	v_cvt_pk_bf16_f32 v69, v42, v43
	v_cvt_pk_bf16_f32 v70, v44, v45
	v_cvt_pk_bf16_f32 v71, v46, v47
	v_pk_add_f32 v[232:233], v[232:233], v[32:33]
	v_pk_add_f32 v[232:233], v[232:233], v[34:35]
	v_pk_add_f32 v[232:233], v[232:233], v[36:37]
	v_pk_add_f32 v[232:233], v[232:233], v[38:39]
	v_pk_add_f32 v[232:233], v[232:233], v[40:41]
	v_pk_add_f32 v[232:233], v[232:233], v[42:43]
	v_pk_add_f32 v[232:233], v[232:233], v[44:45]
	v_pk_add_f32 v[232:233], v[232:233], v[46:47]
	ds_read2_b32 v[32:33], v115 offset0:128 offset1:129
	ds_read2_b32 v[34:35], v115 offset0:130 offset1:131
	ds_read2_b32 v[36:37], v115 offset0:136 offset1:137
	ds_read2_b32 v[38:39], v115 offset0:138 offset1:139
	ds_read2_b32 v[40:41], v115 offset0:144 offset1:145
	ds_read2_b32 v[42:43], v115 offset0:146 offset1:147
	ds_read2_b32 v[44:45], v115 offset0:152 offset1:153
	ds_read2_b32 v[46:47], v115 offset0:154 offset1:155
	v_mfma_f32_32x32x16_bf16 v[0:15], v[64:67], v[72:75], v[0:15]
	v_mfma_f32_32x32x16_bf16 v[16:31], v[64:67], v[76:79], v[16:31]
	v_mfma_f32_32x32x16_bf16 v[0:15], v[68:71], v[220:223], v[0:15]
	v_mfma_f32_32x32x16_bf16 v[16:31], v[68:71], v[224:227], v[16:31]
	global_load_dwordx4 v[156:159], v239, s[86:87]
	global_load_dwordx4 v[160:163], v240, s[86:87]
	global_load_dwordx4 v[164:167], v241, s[86:87]
	global_load_dwordx4 v[168:171], v242, s[86:87]
	global_load_dwordx4 v[172:175], v101, s[86:87] offset:768
	global_load_dwordx4 v[176:179], v150, s[86:87] offset:768
	global_load_dwordx4 v[180:183], v101, s[86:87] offset:832
	global_load_dwordx4 v[184:187], v150, s[86:87] offset:832
	s_add_u32 s86, s86, 0xc0000
	s_addc_u32 s87, s87, 0
	ds_read_b64_tr_b16 v[72:73], v231
	ds_read_b64_tr_b16 v[74:75], v231 offset:512
	ds_read_b64_tr_b16 v[76:77], v231 offset:2048
	ds_read_b64_tr_b16 v[78:79], v231 offset:2560
	ds_read_b64_tr_b16 v[220:221], v231 offset:1024
	ds_read_b64_tr_b16 v[222:223], v231 offset:1536
	ds_read_b64_tr_b16 v[224:225], v231 offset:3072
	ds_read_b64_tr_b16 v[226:227], v231 offset:3584
	v_exp_f32_e32 v188, v188
	v_exp_f32_e32 v189, v189
	s_waitcnt vmcnt(8)
	ds_write_b128 v247, v[116:119]
	ds_write_b128 v247, v[120:123] offset:1024
	ds_write_b128 v247, v[124:127] offset:2048
	ds_write_b128 v247, v[128:131] offset:3072
	ds_read_b128 v[116:119], v248
	ds_read_b128 v[120:123], v249
	ds_read_b128 v[124:127], v250
	ds_read_b128 v[128:131], v251
	ds_write_b128 v112, v[132:135]
	ds_write_b128 v112, v[136:139] offset:1024
	ds_write_b128 v112, v[140:143] offset:2048
	ds_write_b128 v112, v[144:147] offset:3072
	v_exp_f32_e32 v190, v190
	v_exp_f32_e32 v191, v191
	s_waitcnt lgkmcnt(4)
	v_mfma_f32_32x32x16_bf16 v[32:47], v[116:119], v[48:51], v[32:47]
	v_exp_f32_e32 v192, v192
	v_exp_f32_e32 v193, v193
	v_exp_f32_e32 v194, v194
	v_mfma_f32_32x32x16_bf16 v[32:47], v[120:123], v[52:55], v[32:47]
	v_exp_f32_e32 v195, v195
	v_exp_f32_e32 v196, v196
	v_exp_f32_e32 v197, v197
	v_mfma_f32_32x32x16_bf16 v[32:47], v[124:127], v[56:59], v[32:47]
	v_exp_f32_e32 v198, v198
	v_exp_f32_e32 v199, v199
	v_exp_f32_e32 v200, v200
	v_mfma_f32_32x32x16_bf16 v[32:47], v[128:131], v[60:63], v[32:47]
	v_exp_f32_e32 v201, v201
	v_exp_f32_e32 v202, v202
	v_exp_f32_e32 v203, v203
	v_cvt_pk_bf16_f32 v64, v188, v189
	v_cvt_pk_bf16_f32 v65, v190, v191
	v_cvt_pk_bf16_f32 v66, v192, v193
	v_cvt_pk_bf16_f32 v67, v194, v195
	v_cvt_pk_bf16_f32 v68, v196, v197
	v_cvt_pk_bf16_f32 v69, v198, v199
	v_cvt_pk_bf16_f32 v70, v200, v201
	v_cvt_pk_bf16_f32 v71, v202, v203
	v_pk_add_f32 v[232:233], v[232:233], v[188:189]
	v_pk_add_f32 v[232:233], v[232:233], v[190:191]
	v_pk_add_f32 v[232:233], v[232:233], v[192:193]
	v_pk_add_f32 v[232:233], v[232:233], v[194:195]
	v_pk_add_f32 v[232:233], v[232:233], v[196:197]
	v_pk_add_f32 v[232:233], v[232:233], v[198:199]
	v_pk_add_f32 v[232:233], v[232:233], v[200:201]
	v_pk_add_f32 v[232:233], v[232:233], v[202:203]
	ds_read2_b32 v[188:189], v115 offset0:160 offset1:161
	ds_read2_b32 v[190:191], v115 offset0:162 offset1:163
	ds_read2_b32 v[192:193], v115 offset0:168 offset1:169
	ds_read2_b32 v[194:195], v115 offset0:170 offset1:171
	ds_read2_b32 v[196:197], v115 offset0:176 offset1:177
	ds_read2_b32 v[198:199], v115 offset0:178 offset1:179
	ds_read2_b32 v[200:201], v115 offset0:184 offset1:185
	ds_read2_b32 v[202:203], v115 offset0:186 offset1:187
	v_mfma_f32_32x32x16_bf16 v[0:15], v[64:67], v[72:75], v[0:15]
	v_mfma_f32_32x32x16_bf16 v[16:31], v[64:67], v[76:79], v[16:31]
	v_mfma_f32_32x32x16_bf16 v[0:15], v[68:71], v[220:223], v[0:15]
	v_mfma_f32_32x32x16_bf16 v[16:31], v[68:71], v[224:227], v[16:31]
	global_load_dwordx4 v[116:119], v239, s[86:87]
	global_load_dwordx4 v[120:123], v240, s[86:87]
	global_load_dwordx4 v[124:127], v241, s[86:87]
	global_load_dwordx4 v[128:131], v242, s[86:87]
	global_load_dwordx4 v[132:135], v101, s[86:87] offset:768
	global_load_dwordx4 v[136:139], v150, s[86:87] offset:768
	global_load_dwordx4 v[140:143], v101, s[86:87] offset:832
	global_load_dwordx4 v[144:147], v150, s[86:87] offset:832
	s_add_u32 s86, s86, 0xc0000
	s_addc_u32 s87, s87, 0
	ds_read_b64_tr_b16 v[72:73], v231
	ds_read_b64_tr_b16 v[74:75], v231 offset:512
	ds_read_b64_tr_b16 v[76:77], v231 offset:2048
	ds_read_b64_tr_b16 v[78:79], v231 offset:2560
	ds_read_b64_tr_b16 v[220:221], v231 offset:1024
	ds_read_b64_tr_b16 v[222:223], v231 offset:1536
	ds_read_b64_tr_b16 v[224:225], v231 offset:3072
	ds_read_b64_tr_b16 v[226:227], v231 offset:3584
	v_exp_f32_e32 v32, v32
	v_exp_f32_e32 v33, v33
	s_waitcnt vmcnt(8)
	ds_write_b128 v247, v[156:159]
	ds_write_b128 v247, v[160:163] offset:1024
	ds_write_b128 v247, v[164:167] offset:2048
	ds_write_b128 v247, v[168:171] offset:3072
	ds_read_b128 v[156:159], v248
	ds_read_b128 v[160:163], v249
	ds_read_b128 v[164:167], v250
	ds_read_b128 v[168:171], v251
	ds_write_b128 v112, v[172:175]
	ds_write_b128 v112, v[176:179] offset:1024
	ds_write_b128 v112, v[180:183] offset:2048
	ds_write_b128 v112, v[184:187] offset:3072
	v_exp_f32_e32 v34, v34
	v_exp_f32_e32 v35, v35
	s_waitcnt lgkmcnt(4)
	v_mfma_f32_32x32x16_bf16 v[188:203], v[156:159], v[48:51], v[188:203]
	v_exp_f32_e32 v36, v36
	v_exp_f32_e32 v37, v37
	v_exp_f32_e32 v38, v38
	v_mfma_f32_32x32x16_bf16 v[188:203], v[160:163], v[52:55], v[188:203]
	v_exp_f32_e32 v39, v39
	v_exp_f32_e32 v40, v40
	v_exp_f32_e32 v41, v41
	v_mfma_f32_32x32x16_bf16 v[188:203], v[164:167], v[56:59], v[188:203]
	v_exp_f32_e32 v42, v42
	v_exp_f32_e32 v43, v43
	v_exp_f32_e32 v44, v44
	v_mfma_f32_32x32x16_bf16 v[188:203], v[168:171], v[60:63], v[188:203]
	v_exp_f32_e32 v45, v45
	v_exp_f32_e32 v46, v46
	v_exp_f32_e32 v47, v47
	v_cvt_pk_bf16_f32 v64, v32, v33
	v_cvt_pk_bf16_f32 v65, v34, v35
	v_cvt_pk_bf16_f32 v66, v36, v37
	v_cvt_pk_bf16_f32 v67, v38, v39
	v_cvt_pk_bf16_f32 v68, v40, v41
	v_cvt_pk_bf16_f32 v69, v42, v43
	v_cvt_pk_bf16_f32 v70, v44, v45
	v_cvt_pk_bf16_f32 v71, v46, v47
	v_pk_add_f32 v[232:233], v[232:233], v[32:33]
	v_pk_add_f32 v[232:233], v[232:233], v[34:35]
	v_pk_add_f32 v[232:233], v[232:233], v[36:37]
	v_pk_add_f32 v[232:233], v[232:233], v[38:39]
	v_pk_add_f32 v[232:233], v[232:233], v[40:41]
	v_pk_add_f32 v[232:233], v[232:233], v[42:43]
	v_pk_add_f32 v[232:233], v[232:233], v[44:45]
	v_pk_add_f32 v[232:233], v[232:233], v[46:47]
	ds_read2_b32 v[32:33], v115 offset0:192 offset1:193
	ds_read2_b32 v[34:35], v115 offset0:194 offset1:195
	ds_read2_b32 v[36:37], v115 offset0:200 offset1:201
	ds_read2_b32 v[38:39], v115 offset0:202 offset1:203
	ds_read2_b32 v[40:41], v115 offset0:208 offset1:209
	ds_read2_b32 v[42:43], v115 offset0:210 offset1:211
	ds_read2_b32 v[44:45], v115 offset0:216 offset1:217
	ds_read2_b32 v[46:47], v115 offset0:218 offset1:219
	v_mfma_f32_32x32x16_bf16 v[0:15], v[64:67], v[72:75], v[0:15]
	v_mfma_f32_32x32x16_bf16 v[16:31], v[64:67], v[76:79], v[16:31]
	v_mfma_f32_32x32x16_bf16 v[0:15], v[68:71], v[220:223], v[0:15]
	v_mfma_f32_32x32x16_bf16 v[16:31], v[68:71], v[224:227], v[16:31]
	global_load_dwordx4 v[156:159], v239, s[86:87]
	global_load_dwordx4 v[160:163], v240, s[86:87]
	global_load_dwordx4 v[164:167], v241, s[86:87]
	global_load_dwordx4 v[168:171], v242, s[86:87]
	global_load_dwordx4 v[172:175], v101, s[86:87] offset:768
	global_load_dwordx4 v[176:179], v150, s[86:87] offset:768
	global_load_dwordx4 v[180:183], v101, s[86:87] offset:832
	global_load_dwordx4 v[184:187], v150, s[86:87] offset:832
	ds_read_b64_tr_b16 v[72:73], v231
	ds_read_b64_tr_b16 v[74:75], v231 offset:512
	ds_read_b64_tr_b16 v[76:77], v231 offset:2048
	ds_read_b64_tr_b16 v[78:79], v231 offset:2560
	ds_read_b64_tr_b16 v[220:221], v231 offset:1024
	ds_read_b64_tr_b16 v[222:223], v231 offset:1536
	ds_read_b64_tr_b16 v[224:225], v231 offset:3072
	ds_read_b64_tr_b16 v[226:227], v231 offset:3584
	v_exp_f32_e32 v188, v188
	v_exp_f32_e32 v189, v189
	s_waitcnt vmcnt(8)
	ds_write_b128 v247, v[116:119]
	ds_write_b128 v247, v[120:123] offset:1024
	ds_write_b128 v247, v[124:127] offset:2048
	ds_write_b128 v247, v[128:131] offset:3072
	ds_read_b128 v[116:119], v248
	ds_read_b128 v[120:123], v249
	ds_read_b128 v[124:127], v250
	ds_read_b128 v[128:131], v251
	ds_write_b128 v112, v[132:135]
	ds_write_b128 v112, v[136:139] offset:1024
	ds_write_b128 v112, v[140:143] offset:2048
	ds_write_b128 v112, v[144:147] offset:3072
	v_exp_f32_e32 v190, v190
	v_exp_f32_e32 v191, v191
	s_waitcnt lgkmcnt(4)
	v_mfma_f32_32x32x16_bf16 v[32:47], v[116:119], v[48:51], v[32:47]
	v_exp_f32_e32 v192, v192
	v_exp_f32_e32 v193, v193
	v_exp_f32_e32 v194, v194
	v_mfma_f32_32x32x16_bf16 v[32:47], v[120:123], v[52:55], v[32:47]
	v_exp_f32_e32 v195, v195
	v_exp_f32_e32 v196, v196
	v_exp_f32_e32 v197, v197
	v_mfma_f32_32x32x16_bf16 v[32:47], v[124:127], v[56:59], v[32:47]
	v_exp_f32_e32 v198, v198
	v_exp_f32_e32 v199, v199
	v_exp_f32_e32 v200, v200
	v_mfma_f32_32x32x16_bf16 v[32:47], v[128:131], v[60:63], v[32:47]
	v_exp_f32_e32 v201, v201
	v_exp_f32_e32 v202, v202
	v_exp_f32_e32 v203, v203
	v_cvt_pk_bf16_f32 v64, v188, v189
	v_cvt_pk_bf16_f32 v65, v190, v191
	v_cvt_pk_bf16_f32 v66, v192, v193
	v_cvt_pk_bf16_f32 v67, v194, v195
	v_cvt_pk_bf16_f32 v68, v196, v197
	v_cvt_pk_bf16_f32 v69, v198, v199
	v_cvt_pk_bf16_f32 v70, v200, v201
	v_cvt_pk_bf16_f32 v71, v202, v203
	v_pk_add_f32 v[232:233], v[232:233], v[188:189]
	v_pk_add_f32 v[232:233], v[232:233], v[190:191]
	v_pk_add_f32 v[232:233], v[232:233], v[192:193]
	v_pk_add_f32 v[232:233], v[232:233], v[194:195]
	v_pk_add_f32 v[232:233], v[232:233], v[196:197]
	v_pk_add_f32 v[232:233], v[232:233], v[198:199]
	v_pk_add_f32 v[232:233], v[232:233], v[200:201]
	v_pk_add_f32 v[232:233], v[232:233], v[202:203]
	ds_read2_b32 v[188:189], v115 offset0:224 offset1:225
	ds_read2_b32 v[190:191], v115 offset0:226 offset1:227
	ds_read2_b32 v[192:193], v115 offset0:232 offset1:233
	ds_read2_b32 v[194:195], v115 offset0:234 offset1:235
	ds_read2_b32 v[196:197], v115 offset0:240 offset1:241
	ds_read2_b32 v[198:199], v115 offset0:242 offset1:243
	ds_read2_b32 v[200:201], v115 offset0:248 offset1:249
	ds_read2_b32 v[202:203], v115 offset0:250 offset1:251
	v_mfma_f32_32x32x16_bf16 v[0:15], v[64:67], v[72:75], v[0:15]
	v_mfma_f32_32x32x16_bf16 v[16:31], v[64:67], v[76:79], v[16:31]
	v_mfma_f32_32x32x16_bf16 v[0:15], v[68:71], v[220:223], v[0:15]
	v_mfma_f32_32x32x16_bf16 v[16:31], v[68:71], v[224:227], v[16:31]
	global_load_dwordx4 v[116:119], v243, s[88:89]
	global_load_dwordx4 v[120:123], v244, s[88:89]
	global_load_dwordx4 v[124:127], v245, s[88:89]
	global_load_dwordx4 v[128:131], v246, s[88:89]
	global_load_dwordx4 v[132:135], v148, s[88:89] offset:768
	global_load_dwordx4 v[136:139], v151, s[88:89] offset:768
	global_load_dwordx4 v[140:143], v148, s[88:89] offset:832
	global_load_dwordx4 v[144:147], v151, s[88:89] offset:832
	s_add_u32 s88, s88, 0x300000
	s_addc_u32 s89, s89, 0
	ds_read_b64_tr_b16 v[72:73], v231
	ds_read_b64_tr_b16 v[74:75], v231 offset:512
	ds_read_b64_tr_b16 v[76:77], v231 offset:2048
	ds_read_b64_tr_b16 v[78:79], v231 offset:2560
	ds_read_b64_tr_b16 v[220:221], v231 offset:1024
	ds_read_b64_tr_b16 v[222:223], v231 offset:1536
	ds_read_b64_tr_b16 v[224:225], v231 offset:3072
	ds_read_b64_tr_b16 v[226:227], v231 offset:3584
	v_exp_f32_e32 v32, v32
	v_exp_f32_e32 v33, v33
	s_waitcnt vmcnt(8)
	ds_write_b128 v247, v[156:159]
	ds_write_b128 v247, v[160:163] offset:1024
	ds_write_b128 v247, v[164:167] offset:2048
	ds_write_b128 v247, v[168:171] offset:3072
	ds_read_b128 v[156:159], v248
	ds_read_b128 v[160:163], v249
	ds_read_b128 v[164:167], v250
	ds_read_b128 v[168:171], v251
	ds_write_b128 v112, v[172:175]
	ds_write_b128 v112, v[176:179] offset:1024
	ds_write_b128 v112, v[180:183] offset:2048
	ds_write_b128 v112, v[184:187] offset:3072
	v_exp_f32_e32 v34, v34
	v_exp_f32_e32 v35, v35
	s_waitcnt lgkmcnt(4)
	v_mfma_f32_32x32x16_bf16 v[188:203], v[156:159], v[48:51], v[188:203]
	v_exp_f32_e32 v36, v36
	v_exp_f32_e32 v37, v37
	v_exp_f32_e32 v38, v38
	v_mfma_f32_32x32x16_bf16 v[188:203], v[160:163], v[52:55], v[188:203]
	v_exp_f32_e32 v39, v39
	v_exp_f32_e32 v40, v40
	v_exp_f32_e32 v41, v41
	v_mfma_f32_32x32x16_bf16 v[188:203], v[164:167], v[56:59], v[188:203]
	v_exp_f32_e32 v42, v42
	v_exp_f32_e32 v43, v43
	v_exp_f32_e32 v44, v44
	v_mfma_f32_32x32x16_bf16 v[188:203], v[168:171], v[60:63], v[188:203]
	v_exp_f32_e32 v45, v45
	v_exp_f32_e32 v46, v46
	v_exp_f32_e32 v47, v47
	v_cvt_pk_bf16_f32 v64, v32, v33
	v_cvt_pk_bf16_f32 v65, v34, v35
	v_cvt_pk_bf16_f32 v66, v36, v37
	v_cvt_pk_bf16_f32 v67, v38, v39
	v_cvt_pk_bf16_f32 v68, v40, v41
	v_cvt_pk_bf16_f32 v69, v42, v43
	v_cvt_pk_bf16_f32 v70, v44, v45
	v_cvt_pk_bf16_f32 v71, v46, v47
	v_pk_add_f32 v[232:233], v[232:233], v[32:33]
	v_pk_add_f32 v[232:233], v[232:233], v[34:35]
	v_pk_add_f32 v[232:233], v[232:233], v[36:37]
	v_pk_add_f32 v[232:233], v[232:233], v[38:39]
	v_pk_add_f32 v[232:233], v[232:233], v[40:41]
	v_pk_add_f32 v[232:233], v[232:233], v[42:43]
	v_pk_add_f32 v[232:233], v[232:233], v[44:45]
	v_pk_add_f32 v[232:233], v[232:233], v[46:47]
	v_mov_b32_e32 v115, v230
	ds_read2_b32 v[32:33], v115 offset0:0 offset1:1
	ds_read2_b32 v[34:35], v115 offset0:2 offset1:3
	ds_read2_b32 v[36:37], v115 offset0:8 offset1:9
	ds_read2_b32 v[38:39], v115 offset0:10 offset1:11
	ds_read2_b32 v[40:41], v115 offset0:16 offset1:17
	ds_read2_b32 v[42:43], v115 offset0:18 offset1:19
	ds_read2_b32 v[44:45], v115 offset0:24 offset1:25
	ds_read2_b32 v[46:47], v115 offset0:26 offset1:27
	v_mfma_f32_32x32x16_bf16 v[0:15], v[64:67], v[72:75], v[0:15]
	v_mfma_f32_32x32x16_bf16 v[16:31], v[64:67], v[76:79], v[16:31]
	v_mfma_f32_32x32x16_bf16 v[0:15], v[68:71], v[220:223], v[0:15]
	v_mfma_f32_32x32x16_bf16 v[16:31], v[68:71], v[224:227], v[16:31]
	global_load_dwordx4 v[156:159], v243, s[88:89]
	global_load_dwordx4 v[160:163], v244, s[88:89]
	global_load_dwordx4 v[164:167], v245, s[88:89]
	global_load_dwordx4 v[168:171], v246, s[88:89]
	global_load_dwordx4 v[172:175], v148, s[88:89] offset:768
	global_load_dwordx4 v[176:179], v151, s[88:89] offset:768
	global_load_dwordx4 v[180:183], v148, s[88:89] offset:832
	global_load_dwordx4 v[184:187], v151, s[88:89] offset:832
	s_add_u32 s88, s88, 0x300000
	s_addc_u32 s89, s89, 0
	ds_read_b64_tr_b16 v[72:73], v231
	ds_read_b64_tr_b16 v[74:75], v231 offset:512
	ds_read_b64_tr_b16 v[76:77], v231 offset:2048
	ds_read_b64_tr_b16 v[78:79], v231 offset:2560
	ds_read_b64_tr_b16 v[220:221], v231 offset:1024
	ds_read_b64_tr_b16 v[222:223], v231 offset:1536
	ds_read_b64_tr_b16 v[224:225], v231 offset:3072
	ds_read_b64_tr_b16 v[226:227], v231 offset:3584
	v_exp_f32_e32 v188, v188
	v_exp_f32_e32 v189, v189
	s_waitcnt vmcnt(8)
	ds_write_b128 v247, v[116:119]
	ds_write_b128 v247, v[120:123] offset:1024
	ds_write_b128 v247, v[124:127] offset:2048
	ds_write_b128 v247, v[128:131] offset:3072
	ds_read_b128 v[116:119], v248
	ds_read_b128 v[120:123], v249
	ds_read_b128 v[124:127], v250
	ds_read_b128 v[128:131], v251
	ds_write_b128 v112, v[132:135]
	ds_write_b128 v112, v[136:139] offset:1024
	ds_write_b128 v112, v[140:143] offset:2048
	ds_write_b128 v112, v[144:147] offset:3072
	v_exp_f32_e32 v190, v190
	v_exp_f32_e32 v191, v191
	s_waitcnt lgkmcnt(4)
	v_mfma_f32_32x32x16_bf16 v[32:47], v[116:119], v[48:51], v[32:47]
	v_exp_f32_e32 v192, v192
	v_exp_f32_e32 v193, v193
	v_exp_f32_e32 v194, v194
	v_mfma_f32_32x32x16_bf16 v[32:47], v[120:123], v[52:55], v[32:47]
	v_exp_f32_e32 v195, v195
	v_exp_f32_e32 v196, v196
	v_exp_f32_e32 v197, v197
	v_mfma_f32_32x32x16_bf16 v[32:47], v[124:127], v[56:59], v[32:47]
	v_exp_f32_e32 v198, v198
	v_exp_f32_e32 v199, v199
	v_exp_f32_e32 v200, v200
	v_mfma_f32_32x32x16_bf16 v[32:47], v[128:131], v[60:63], v[32:47]
	v_exp_f32_e32 v201, v201
	v_exp_f32_e32 v202, v202
	v_exp_f32_e32 v203, v203
	v_cvt_pk_bf16_f32 v64, v188, v189
	v_cvt_pk_bf16_f32 v65, v190, v191
	v_cvt_pk_bf16_f32 v66, v192, v193
	v_cvt_pk_bf16_f32 v67, v194, v195
	v_cvt_pk_bf16_f32 v68, v196, v197
	v_cvt_pk_bf16_f32 v69, v198, v199
	v_cvt_pk_bf16_f32 v70, v200, v201
	v_cvt_pk_bf16_f32 v71, v202, v203
	v_pk_add_f32 v[232:233], v[232:233], v[188:189]
	v_pk_add_f32 v[232:233], v[232:233], v[190:191]
	v_pk_add_f32 v[232:233], v[232:233], v[192:193]
	v_pk_add_f32 v[232:233], v[232:233], v[194:195]
	v_pk_add_f32 v[232:233], v[232:233], v[196:197]
	v_pk_add_f32 v[232:233], v[232:233], v[198:199]
	v_pk_add_f32 v[232:233], v[232:233], v[200:201]
	v_pk_add_f32 v[232:233], v[232:233], v[202:203]
	ds_read2_b32 v[188:189], v115 offset0:32 offset1:33
	ds_read2_b32 v[190:191], v115 offset0:34 offset1:35
	ds_read2_b32 v[192:193], v115 offset0:40 offset1:41
	ds_read2_b32 v[194:195], v115 offset0:42 offset1:43
	ds_read2_b32 v[196:197], v115 offset0:48 offset1:49
	ds_read2_b32 v[198:199], v115 offset0:50 offset1:51
	ds_read2_b32 v[200:201], v115 offset0:56 offset1:57
	ds_read2_b32 v[202:203], v115 offset0:58 offset1:59
	v_mfma_f32_32x32x16_bf16 v[0:15], v[64:67], v[72:75], v[0:15]
	v_mfma_f32_32x32x16_bf16 v[16:31], v[64:67], v[76:79], v[16:31]
	v_mfma_f32_32x32x16_bf16 v[0:15], v[68:71], v[220:223], v[0:15]
	v_mfma_f32_32x32x16_bf16 v[16:31], v[68:71], v[224:227], v[16:31]
	global_load_dwordx4 v[116:119], v243, s[88:89]
	global_load_dwordx4 v[120:123], v244, s[88:89]
	global_load_dwordx4 v[124:127], v245, s[88:89]
	global_load_dwordx4 v[128:131], v246, s[88:89]
	global_load_dwordx4 v[132:135], v148, s[88:89] offset:768
	global_load_dwordx4 v[136:139], v151, s[88:89] offset:768
	global_load_dwordx4 v[140:143], v148, s[88:89] offset:832
	global_load_dwordx4 v[144:147], v151, s[88:89] offset:832
	s_add_u32 s88, s88, 0x300000
	s_addc_u32 s89, s89, 0
	ds_read_b64_tr_b16 v[72:73], v231
	ds_read_b64_tr_b16 v[74:75], v231 offset:512
	ds_read_b64_tr_b16 v[76:77], v231 offset:2048
	ds_read_b64_tr_b16 v[78:79], v231 offset:2560
	ds_read_b64_tr_b16 v[220:221], v231 offset:1024
	ds_read_b64_tr_b16 v[222:223], v231 offset:1536
	ds_read_b64_tr_b16 v[224:225], v231 offset:3072
	ds_read_b64_tr_b16 v[226:227], v231 offset:3584
	v_exp_f32_e32 v32, v32
	v_exp_f32_e32 v33, v33
	s_waitcnt vmcnt(8)
	ds_write_b128 v247, v[156:159]
	ds_write_b128 v247, v[160:163] offset:1024
	ds_write_b128 v247, v[164:167] offset:2048
	ds_write_b128 v247, v[168:171] offset:3072
	ds_read_b128 v[156:159], v248
	ds_read_b128 v[160:163], v249
	ds_read_b128 v[164:167], v250
	ds_read_b128 v[168:171], v251
	ds_write_b128 v112, v[172:175]
	ds_write_b128 v112, v[176:179] offset:1024
	ds_write_b128 v112, v[180:183] offset:2048
	ds_write_b128 v112, v[184:187] offset:3072
	v_exp_f32_e32 v34, v34
	v_exp_f32_e32 v35, v35
	s_waitcnt lgkmcnt(4)
	v_mfma_f32_32x32x16_bf16 v[188:203], v[156:159], v[48:51], v[188:203]
	v_exp_f32_e32 v36, v36
	v_exp_f32_e32 v37, v37
	v_exp_f32_e32 v38, v38
	v_mfma_f32_32x32x16_bf16 v[188:203], v[160:163], v[52:55], v[188:203]
	v_exp_f32_e32 v39, v39
	v_exp_f32_e32 v40, v40
	v_exp_f32_e32 v41, v41
	v_mfma_f32_32x32x16_bf16 v[188:203], v[164:167], v[56:59], v[188:203]
	v_exp_f32_e32 v42, v42
	v_exp_f32_e32 v43, v43
	v_exp_f32_e32 v44, v44
	v_mfma_f32_32x32x16_bf16 v[188:203], v[168:171], v[60:63], v[188:203]
	v_exp_f32_e32 v45, v45
	v_exp_f32_e32 v46, v46
	v_exp_f32_e32 v47, v47
	v_cvt_pk_bf16_f32 v64, v32, v33
	v_cvt_pk_bf16_f32 v65, v34, v35
	v_cvt_pk_bf16_f32 v66, v36, v37
	v_cvt_pk_bf16_f32 v67, v38, v39
	v_cvt_pk_bf16_f32 v68, v40, v41
	v_cvt_pk_bf16_f32 v69, v42, v43
	v_cvt_pk_bf16_f32 v70, v44, v45
	v_cvt_pk_bf16_f32 v71, v46, v47
	v_pk_add_f32 v[232:233], v[232:233], v[32:33]
	v_pk_add_f32 v[232:233], v[232:233], v[34:35]
	v_pk_add_f32 v[232:233], v[232:233], v[36:37]
	v_pk_add_f32 v[232:233], v[232:233], v[38:39]
	v_pk_add_f32 v[232:233], v[232:233], v[40:41]
	v_pk_add_f32 v[232:233], v[232:233], v[42:43]
	v_pk_add_f32 v[232:233], v[232:233], v[44:45]
	v_pk_add_f32 v[232:233], v[232:233], v[46:47]
	ds_read2_b32 v[32:33], v115 offset0:64 offset1:65
	ds_read2_b32 v[34:35], v115 offset0:66 offset1:67
	ds_read2_b32 v[36:37], v115 offset0:72 offset1:73
	ds_read2_b32 v[38:39], v115 offset0:74 offset1:75
	ds_read2_b32 v[40:41], v115 offset0:80 offset1:81
	ds_read2_b32 v[42:43], v115 offset0:82 offset1:83
	ds_read2_b32 v[44:45], v115 offset0:88 offset1:89
	ds_read2_b32 v[46:47], v115 offset0:90 offset1:91
	v_mfma_f32_32x32x16_bf16 v[0:15], v[64:67], v[72:75], v[0:15]
	v_mfma_f32_32x32x16_bf16 v[16:31], v[64:67], v[76:79], v[16:31]
	v_mfma_f32_32x32x16_bf16 v[0:15], v[68:71], v[220:223], v[0:15]
	v_mfma_f32_32x32x16_bf16 v[16:31], v[68:71], v[224:227], v[16:31]
	global_load_dwordx4 v[156:159], v243, s[88:89]
	global_load_dwordx4 v[160:163], v244, s[88:89]
	global_load_dwordx4 v[164:167], v245, s[88:89]
	global_load_dwordx4 v[168:171], v246, s[88:89]
	global_load_dwordx4 v[172:175], v148, s[88:89] offset:768
	global_load_dwordx4 v[176:179], v151, s[88:89] offset:768
	global_load_dwordx4 v[180:183], v148, s[88:89] offset:832
	global_load_dwordx4 v[184:187], v151, s[88:89] offset:832
	s_add_u32 s88, s88, 0x300000
	s_addc_u32 s89, s89, 0
	ds_read_b64_tr_b16 v[72:73], v231
	ds_read_b64_tr_b16 v[74:75], v231 offset:512
	ds_read_b64_tr_b16 v[76:77], v231 offset:2048
	ds_read_b64_tr_b16 v[78:79], v231 offset:2560
	ds_read_b64_tr_b16 v[220:221], v231 offset:1024
	ds_read_b64_tr_b16 v[222:223], v231 offset:1536
	ds_read_b64_tr_b16 v[224:225], v231 offset:3072
	ds_read_b64_tr_b16 v[226:227], v231 offset:3584
	v_exp_f32_e32 v188, v188
	v_exp_f32_e32 v189, v189
	s_waitcnt vmcnt(8)
	ds_write_b128 v247, v[116:119]
	ds_write_b128 v247, v[120:123] offset:1024
	ds_write_b128 v247, v[124:127] offset:2048
	ds_write_b128 v247, v[128:131] offset:3072
	ds_read_b128 v[116:119], v248
	ds_read_b128 v[120:123], v249
	ds_read_b128 v[124:127], v250
	ds_read_b128 v[128:131], v251
	ds_write_b128 v112, v[132:135]
	ds_write_b128 v112, v[136:139] offset:1024
	ds_write_b128 v112, v[140:143] offset:2048
	ds_write_b128 v112, v[144:147] offset:3072
	v_exp_f32_e32 v190, v190
	v_exp_f32_e32 v191, v191
	s_waitcnt lgkmcnt(4)
	v_mfma_f32_32x32x16_bf16 v[32:47], v[116:119], v[48:51], v[32:47]
	v_exp_f32_e32 v192, v192
	v_exp_f32_e32 v193, v193
	v_exp_f32_e32 v194, v194
	v_mfma_f32_32x32x16_bf16 v[32:47], v[120:123], v[52:55], v[32:47]
	v_exp_f32_e32 v195, v195
	v_exp_f32_e32 v196, v196
	v_exp_f32_e32 v197, v197
	v_mfma_f32_32x32x16_bf16 v[32:47], v[124:127], v[56:59], v[32:47]
	v_exp_f32_e32 v198, v198
	v_exp_f32_e32 v199, v199
	v_exp_f32_e32 v200, v200
	v_mfma_f32_32x32x16_bf16 v[32:47], v[128:131], v[60:63], v[32:47]
	v_exp_f32_e32 v201, v201
	v_exp_f32_e32 v202, v202
	v_exp_f32_e32 v203, v203
	v_cvt_pk_bf16_f32 v64, v188, v189
	v_cvt_pk_bf16_f32 v65, v190, v191
	v_cvt_pk_bf16_f32 v66, v192, v193
	v_cvt_pk_bf16_f32 v67, v194, v195
	v_cvt_pk_bf16_f32 v68, v196, v197
	v_cvt_pk_bf16_f32 v69, v198, v199
	v_cvt_pk_bf16_f32 v70, v200, v201
	v_cvt_pk_bf16_f32 v71, v202, v203
	v_pk_add_f32 v[232:233], v[232:233], v[188:189]
	v_pk_add_f32 v[232:233], v[232:233], v[190:191]
	v_pk_add_f32 v[232:233], v[232:233], v[192:193]
	v_pk_add_f32 v[232:233], v[232:233], v[194:195]
	v_pk_add_f32 v[232:233], v[232:233], v[196:197]
	v_pk_add_f32 v[232:233], v[232:233], v[198:199]
	v_pk_add_f32 v[232:233], v[232:233], v[200:201]
	v_pk_add_f32 v[232:233], v[232:233], v[202:203]
	ds_read2_b32 v[188:189], v115 offset0:96 offset1:97
	ds_read2_b32 v[190:191], v115 offset0:98 offset1:99
	ds_read2_b32 v[192:193], v115 offset0:104 offset1:105
	ds_read2_b32 v[194:195], v115 offset0:106 offset1:107
	ds_read2_b32 v[196:197], v115 offset0:112 offset1:113
	ds_read2_b32 v[198:199], v115 offset0:114 offset1:115
	ds_read2_b32 v[200:201], v115 offset0:120 offset1:121
	ds_read2_b32 v[202:203], v115 offset0:122 offset1:123
	v_mfma_f32_32x32x16_bf16 v[0:15], v[64:67], v[72:75], v[0:15]
	v_mfma_f32_32x32x16_bf16 v[16:31], v[64:67], v[76:79], v[16:31]
	v_mfma_f32_32x32x16_bf16 v[0:15], v[68:71], v[220:223], v[0:15]
	v_mfma_f32_32x32x16_bf16 v[16:31], v[68:71], v[224:227], v[16:31]
	global_load_dwordx4 v[116:119], v243, s[88:89]
	global_load_dwordx4 v[120:123], v244, s[88:89]
	global_load_dwordx4 v[124:127], v245, s[88:89]
	global_load_dwordx4 v[128:131], v246, s[88:89]
	global_load_dwordx4 v[132:135], v148, s[88:89] offset:768
	global_load_dwordx4 v[136:139], v151, s[88:89] offset:768
	global_load_dwordx4 v[140:143], v148, s[88:89] offset:832
	global_load_dwordx4 v[144:147], v151, s[88:89] offset:832
	ds_read_b64_tr_b16 v[72:73], v231
	ds_read_b64_tr_b16 v[74:75], v231 offset:512
	ds_read_b64_tr_b16 v[76:77], v231 offset:2048
	ds_read_b64_tr_b16 v[78:79], v231 offset:2560
	ds_read_b64_tr_b16 v[220:221], v231 offset:1024
	ds_read_b64_tr_b16 v[222:223], v231 offset:1536
	ds_read_b64_tr_b16 v[224:225], v231 offset:3072
	ds_read_b64_tr_b16 v[226:227], v231 offset:3584
	v_exp_f32_e32 v32, v32
	v_exp_f32_e32 v33, v33
	s_waitcnt vmcnt(8)
	ds_write_b128 v247, v[156:159]
	ds_write_b128 v247, v[160:163] offset:1024
	ds_write_b128 v247, v[164:167] offset:2048
	ds_write_b128 v247, v[168:171] offset:3072
	ds_read_b128 v[156:159], v248
	ds_read_b128 v[160:163], v249
	ds_read_b128 v[164:167], v250
	ds_read_b128 v[168:171], v251
	ds_write_b128 v112, v[172:175]
	ds_write_b128 v112, v[176:179] offset:1024
	ds_write_b128 v112, v[180:183] offset:2048
	ds_write_b128 v112, v[184:187] offset:3072
	v_exp_f32_e32 v34, v34
	v_exp_f32_e32 v35, v35
	s_waitcnt lgkmcnt(4)
	v_mfma_f32_32x32x16_bf16 v[188:203], v[156:159], v[48:51], v[188:203]
	v_exp_f32_e32 v36, v36
	v_exp_f32_e32 v37, v37
	v_exp_f32_e32 v38, v38
	v_mfma_f32_32x32x16_bf16 v[188:203], v[160:163], v[52:55], v[188:203]
	v_exp_f32_e32 v39, v39
	v_exp_f32_e32 v40, v40
	v_exp_f32_e32 v41, v41
	v_mfma_f32_32x32x16_bf16 v[188:203], v[164:167], v[56:59], v[188:203]
	v_exp_f32_e32 v42, v42
	v_exp_f32_e32 v43, v43
	v_exp_f32_e32 v44, v44
	v_mfma_f32_32x32x16_bf16 v[188:203], v[168:171], v[60:63], v[188:203]
	v_exp_f32_e32 v45, v45
	v_exp_f32_e32 v46, v46
	v_exp_f32_e32 v47, v47
	v_cvt_pk_bf16_f32 v64, v32, v33
	v_cvt_pk_bf16_f32 v65, v34, v35
	v_cvt_pk_bf16_f32 v66, v36, v37
	v_cvt_pk_bf16_f32 v67, v38, v39
	v_cvt_pk_bf16_f32 v68, v40, v41
	v_cvt_pk_bf16_f32 v69, v42, v43
	v_cvt_pk_bf16_f32 v70, v44, v45
	v_cvt_pk_bf16_f32 v71, v46, v47
	v_pk_add_f32 v[232:233], v[232:233], v[32:33]
	v_pk_add_f32 v[232:233], v[232:233], v[34:35]
	v_pk_add_f32 v[232:233], v[232:233], v[36:37]
	v_pk_add_f32 v[232:233], v[232:233], v[38:39]
	v_pk_add_f32 v[232:233], v[232:233], v[40:41]
	v_pk_add_f32 v[232:233], v[232:233], v[42:43]
	v_pk_add_f32 v[232:233], v[232:233], v[44:45]
	v_pk_add_f32 v[232:233], v[232:233], v[46:47]
	ds_read2_b32 v[32:33], v115 offset0:128 offset1:129
	ds_read2_b32 v[34:35], v115 offset0:130 offset1:131
	ds_read2_b32 v[36:37], v115 offset0:136 offset1:137
	ds_read2_b32 v[38:39], v115 offset0:138 offset1:139
	ds_read2_b32 v[40:41], v115 offset0:144 offset1:145
	ds_read2_b32 v[42:43], v115 offset0:146 offset1:147
	ds_read2_b32 v[44:45], v115 offset0:152 offset1:153
	ds_read2_b32 v[46:47], v115 offset0:154 offset1:155
	v_mfma_f32_32x32x16_bf16 v[0:15], v[64:67], v[72:75], v[0:15]
	v_mfma_f32_32x32x16_bf16 v[16:31], v[64:67], v[76:79], v[16:31]
	v_mfma_f32_32x32x16_bf16 v[0:15], v[68:71], v[220:223], v[0:15]
	v_mfma_f32_32x32x16_bf16 v[16:31], v[68:71], v[224:227], v[16:31]
	ds_read_b64_tr_b16 v[72:73], v231
	ds_read_b64_tr_b16 v[74:75], v231 offset:512
	ds_read_b64_tr_b16 v[76:77], v231 offset:2048
	ds_read_b64_tr_b16 v[78:79], v231 offset:2560
	ds_read_b64_tr_b16 v[220:221], v231 offset:1024
	ds_read_b64_tr_b16 v[222:223], v231 offset:1536
	ds_read_b64_tr_b16 v[224:225], v231 offset:3072
	ds_read_b64_tr_b16 v[226:227], v231 offset:3584
	v_exp_f32_e32 v188, v188
	v_exp_f32_e32 v189, v189
	s_waitcnt vmcnt(0)
; #define LAS __attribute__((address_space(3)))
; #define GAS __attribute__((address_space(1)))
; __device__ __forceinline__ void dil_unit(LAS unsigned char* lds, bf16_t* proj, int seq, int hd, int T0, int rho) {
;     ...
;     const int tid = tid_, lane = tid & 63, r32 = lane & 31, hi = lane >> 5, wid = __builtin_amdgcn_readfirstlane(tid >> 6);
;     bf16_t* base = proj + (size_t)seq * SEQ * NIN;
;     LAS unsigned char* wbuf = lds + wid * 4096;
;     const LAS unsigned char* vp = wbuf + ((lane >> 4) & 1) * 32 + (lane & 3) * 8 + (4 * hi + ((lane & 15) >> 2)) * 64;
;     const int P0 = T0 + rho;
;     bf16x8 qr[4];
; #pragma unroll
;     for (int ks = 0; ks < 4; ++ks) qr[ks] = *(const GAS bf16x8*)(base + (size_t)(P0 + 16 * r32) * NIN + PC_LQ + hd * 64 + 16 * ks + 8 * hi);
;     f32x16 o0 = {}, o1 = {}; float l = 0.f;
;     const bool bound = (T0 < 1024) || (T0 >= 15360);
	ds_write_b128 v247, v[116:119]
	ds_write_b128 v247, v[120:123] offset:1024
	ds_write_b128 v247, v[124:127] offset:2048
	ds_write_b128 v247, v[128:131] offset:3072
	ds_read_b128 v[116:119], v248
	ds_read_b128 v[120:123], v249
	ds_read_b128 v[124:127], v250
	ds_read_b128 v[128:131], v251
	ds_write_b128 v112, v[132:135]
	ds_write_b128 v112, v[136:139] offset:1024
	ds_write_b128 v112, v[140:143] offset:2048
	ds_write_b128 v112, v[144:147] offset:3072
	v_exp_f32_e32 v190, v190
	v_exp_f32_e32 v191, v191
	s_waitcnt lgkmcnt(4)
	v_mfma_f32_32x32x16_bf16 v[32:47], v[116:119], v[48:51], v[32:47]
	v_exp_f32_e32 v192, v192
	v_exp_f32_e32 v193, v193
	v_exp_f32_e32 v194, v194
	v_mfma_f32_32x32x16_bf16 v[32:47], v[120:123], v[52:55], v[32:47]
	v_exp_f32_e32 v195, v195
	v_exp_f32_e32 v196, v196
	v_exp_f32_e32 v197, v197
	v_mfma_f32_32x32x16_bf16 v[32:47], v[124:127], v[56:59], v[32:47]
	v_exp_f32_e32 v198, v198
	v_exp_f32_e32 v199, v199
	v_exp_f32_e32 v200, v200
	v_mfma_f32_32x32x16_bf16 v[32:47], v[128:131], v[60:63], v[32:47]
	v_exp_f32_e32 v201, v201
	v_exp_f32_e32 v202, v202
	v_exp_f32_e32 v203, v203
	v_cvt_pk_bf16_f32 v64, v188, v189
	v_cvt_pk_bf16_f32 v65, v190, v191
	v_cvt_pk_bf16_f32 v66, v192, v193
	v_cvt_pk_bf16_f32 v67, v194, v195
	v_cvt_pk_bf16_f32 v68, v196, v197
	v_cvt_pk_bf16_f32 v69, v198, v199
	v_cvt_pk_bf16_f32 v70, v200, v201
	v_cvt_pk_bf16_f32 v71, v202, v203
	v_pk_add_f32 v[232:233], v[232:233], v[188:189]
	v_pk_add_f32 v[232:233], v[232:233], v[190:191]
	v_pk_add_f32 v[232:233], v[232:233], v[192:193]
	v_pk_add_f32 v[232:233], v[232:233], v[194:195]
	v_pk_add_f32 v[232:233], v[232:233], v[196:197]
	v_pk_add_f32 v[232:233], v[232:233], v[198:199]
	v_pk_add_f32 v[232:233], v[232:233], v[200:201]
	v_pk_add_f32 v[232:233], v[232:233], v[202:203]
	v_mfma_f32_32x32x16_bf16 v[0:15], v[64:67], v[72:75], v[0:15]
	v_mfma_f32_32x32x16_bf16 v[16:31], v[64:67], v[76:79], v[16:31]
	v_mfma_f32_32x32x16_bf16 v[0:15], v[68:71], v[220:223], v[0:15]
	v_mfma_f32_32x32x16_bf16 v[16:31], v[68:71], v[224:227], v[16:31]
	ds_read_b64_tr_b16 v[72:73], v231
	ds_read_b64_tr_b16 v[74:75], v231 offset:512
	ds_read_b64_tr_b16 v[76:77], v231 offset:2048
	ds_read_b64_tr_b16 v[78:79], v231 offset:2560
	ds_read_b64_tr_b16 v[220:221], v231 offset:1024
	ds_read_b64_tr_b16 v[222:223], v231 offset:1536
	ds_read_b64_tr_b16 v[224:225], v231 offset:3072
	ds_read_b64_tr_b16 v[226:227], v231 offset:3584
	s_waitcnt lgkmcnt(0)
	v_exp_f32_e32 v32, v32
	v_exp_f32_e32 v33, v33
	v_exp_f32_e32 v34, v34
	v_exp_f32_e32 v35, v35
	v_exp_f32_e32 v36, v36
	v_exp_f32_e32 v37, v37
	v_exp_f32_e32 v38, v38
	v_exp_f32_e32 v39, v39
	v_exp_f32_e32 v40, v40
	v_exp_f32_e32 v41, v41
	v_exp_f32_e32 v42, v42
	v_exp_f32_e32 v43, v43
	v_exp_f32_e32 v44, v44
	v_exp_f32_e32 v45, v45
	v_exp_f32_e32 v46, v46
	v_exp_f32_e32 v47, v47
	v_cvt_pk_bf16_f32 v64, v32, v33
	v_cvt_pk_bf16_f32 v65, v34, v35
	v_cvt_pk_bf16_f32 v66, v36, v37
	v_cvt_pk_bf16_f32 v67, v38, v39
	v_cvt_pk_bf16_f32 v68, v40, v41
	v_cvt_pk_bf16_f32 v69, v42, v43
	v_cvt_pk_bf16_f32 v70, v44, v45
	v_cvt_pk_bf16_f32 v71, v46, v47
	v_pk_add_f32 v[232:233], v[232:233], v[32:33]
	v_pk_add_f32 v[232:233], v[232:233], v[34:35]
	v_pk_add_f32 v[232:233], v[232:233], v[36:37]
	v_pk_add_f32 v[232:233], v[232:233], v[38:39]
	v_pk_add_f32 v[232:233], v[232:233], v[40:41]
	v_pk_add_f32 v[232:233], v[232:233], v[42:43]
	v_pk_add_f32 v[232:233], v[232:233], v[44:45]
	v_pk_add_f32 v[232:233], v[232:233], v[46:47]
	v_mfma_f32_32x32x16_bf16 v[0:15], v[64:67], v[72:75], v[0:15]
	v_mfma_f32_32x32x16_bf16 v[16:31], v[64:67], v[76:79], v[16:31]
	v_mfma_f32_32x32x16_bf16 v[0:15], v[68:71], v[220:223], v[0:15]
	v_mfma_f32_32x32x16_bf16 v[16:31], v[68:71], v[224:227], v[16:31]
	v_add_f32_e32 v113, v232, v233
	v_or_b32_e32 v114, 1, v107
	v_or_b32_e32 v97, 2, v107
	v_or_b32_e32 v96, 3, v107
	v_or_b32_e32 v95, 8, v107
	v_or_b32_e32 v94, 9, v107
	v_or_b32_e32 v93, 10, v107
	v_or_b32_e32 v92, 11, v107
	v_or_b32_e32 v91, 16, v107
	v_or_b32_e32 v90, 17, v107
	v_or_b32_e32 v89, 18, v107
	v_or_b32_e32 v88, 19, v107
	v_or_b32_e32 v87, 24, v107
	v_or_b32_e32 v86, 25, v107
	v_or_b32_e32 v85, 26, v107
	v_or_b32_e32 v84, 27, v107
	s_nop 11
	s_branch .LBB0_553
.LBB0_558:
	s_movk_i32 s100, 0x1800
	s_add_i32 s101, s6, 0x15c00
	s_lshl_b32 s90, s58, 1
	s_add_u32 s82, s56, s90
	s_addc_u32 s83, s57, 0
	s_add_u32 s82, s82, 0x1200
	s_addc_u32 s83, s83, 0
	s_sub_i32 s90, s76, 64
	s_mul_i32 s90, s90, 0x1800
	s_add_u32 s84, s82, s90
	s_addc_u32 s85, s83, 0
	s_sub_i32 s90, s76, 256
	s_mul_i32 s90, s90, 0x1800
	s_add_u32 s86, s82, s90
	s_addc_u32 s87, s83, 0
	s_sub_i32 s90, s76, 1024
	s_mul_i32 s90, s90, 0x1800
	s_add_u32 s88, s82, s90
	s_addc_u32 s89, s83, 0
	v_lshlrev_b32_e32 v153, 1, v98
	v_mad_u32_u24 v80, v105, s100, v82
	v_mad_u32_u24 v100, v110, s100, v153
	v_add_u32_e32 v149, 0x18000, v100
	v_lshlrev_b32_e32 v83, 2, v105
	v_mad_u32_u24 v83, v83, s100, v82
	v_lshlrev_b32_e32 v101, 2, v110
	v_mad_u32_u24 v101, v101, s100, v153
	v_add_u32_e32 v150, 0x60000, v101
	v_lshlrev_b32_e32 v99, 4, v105
	v_mad_u32_u24 v99, v99, s100, v82
	v_lshlrev_b32_e32 v148, 4, v110
	v_mad_u32_u24 v148, v148, s100, v153
	v_add_u32_e32 v151, 0x180000, v148
	v_lshrrev_b32_e32 v249, 3, v103
	v_and_b32_e32 v250, 7, v103
	v_lshlrev_b32_e32 v250, 4, v250
	v_add_u32_e32 v235, 0, v249
	v_add_u32_e32 v236, 8, v249
	v_add_u32_e32 v237, 16, v249
	v_add_u32_e32 v238, 24, v249
	v_add_u32_e32 v239, 0, v249
	v_lshlrev_b32_e32 v239, 2, v239
	v_add_u32_e32 v240, 8, v249
	v_lshlrev_b32_e32 v240, 2, v240
	v_add_u32_e32 v241, 16, v249
	v_lshlrev_b32_e32 v241, 2, v241
	v_add_u32_e32 v242, 24, v249
	v_lshlrev_b32_e32 v242, 2, v242
; #define LAS __attribute__((address_space(3)))
; #define GAS __attribute__((address_space(1)))
; __device__ __forceinline__ void dil_unit(LAS unsigned char* lds, bf16_t* proj, int seq, int hd, int T0, int rho) {
;     ...
;     const int tid = tid_, lane = tid & 63, r32 = lane & 31, hi = lane >> 5, wid = __builtin_amdgcn_readfirstlane(tid >> 6);
;     bf16_t* base = proj + (size_t)seq * SEQ * NIN;
;     LAS unsigned char* wbuf = lds + wid * 4096;
;     const LAS unsigned char* vp = wbuf + ((lane >> 4) & 1) * 32 + (lane & 3) * 8 + (4 * hi + ((lane & 15) >> 2)) * 64;
;     const int P0 = T0 + rho;
;     bf16x8 qr[4];
; #pragma unroll
;     for (int ks = 0; ks < 4; ++ks) qr[ks] = *(const GAS bf16x8*)(base + (size_t)(P0 + 16 * r32) * NIN + PC_LQ + hd * 64 + 16 * ks + 8 * hi);
;     f32x16 o0 = {}, o1 = {}; float l = 0.f;
;     const bool bound = (T0 < 1024) || (T0 >= 15360);
	v_add_u32_e32 v243, 0, v249
	v_lshlrev_b32_e32 v243, 4, v243
	v_add_u32_e32 v244, 8, v249
	v_lshlrev_b32_e32 v244, 4, v244
	v_add_u32_e32 v245, 16, v249
	v_lshlrev_b32_e32 v245, 4, v245
	v_add_u32_e32 v246, 24, v249
	v_lshlrev_b32_e32 v246, 4, v246
	v_mov_b32_e32 v252, v250
	v_mov_b32_e32 v100, v110
	v_add_u32_e32 v149, 16, v100
	v_lshlrev_b32_e32 v101, 2, v110
	v_add_u32_e32 v150, 64, v101
	v_lshlrev_b32_e32 v148, 4, v110
	v_add_u32_e32 v151, 256, v148
	s_mov_b32 s98, 0x4000
	s_mov_b32 s99, 0x3fff
	v_and_b32_e32 v247, 7, v249
	v_lshlrev_b32_e32 v247, 4, v247
	v_xor_b32_e32 v247, v247, v112
	v_and_b32_e32 v153, 7, v105
	v_or_b32_e32 v248, 0, v106
	v_xor_b32_e32 v248, v248, v153
	v_lshlrev_b32_e32 v248, 4, v248
	v_lshl_add_u32 v248, v105, 7, v248
	v_add_u32_e32 v248, s77, v248
	v_or_b32_e32 v249, 2, v106
	v_xor_b32_e32 v249, v249, v153
	v_lshlrev_b32_e32 v249, 4, v249
	v_lshl_add_u32 v249, v105, 7, v249
	v_add_u32_e32 v249, s77, v249
	v_or_b32_e32 v250, 4, v106
	v_xor_b32_e32 v250, v250, v153
	v_lshlrev_b32_e32 v250, 4, v250
	v_lshl_add_u32 v250, v105, 7, v250
	v_add_u32_e32 v250, s77, v250
	v_or_b32_e32 v251, 6, v106
	v_xor_b32_e32 v251, v251, v153
	v_lshlrev_b32_e32 v251, 4, v251
	v_lshl_add_u32 v251, v105, 7, v251
	v_add_u32_e32 v251, s77, v251
	v_lshlrev_b32_e32 v153, 1, v98
	v_mul_u32_u24_e32 v228, 17, v105
	v_sub_u32_e32 v228, v107, v228
	s_mul_i32 s90, s58, 153
	s_lshr_b32 s90, s90, 1
	s_add_i32 s90, s90, 34876
	v_lshl_add_u32 v228, v228, 2, s90
	v_lshlrev_b32_e32 v229, 2, v105
	v_sub_u32_e32 v229, v107, v229
	s_add_i32 s90, s101, 5104
	v_lshl_add_u32 v229, v229, 2, s90
	v_sub_u32_e32 v230, v107, v105
	s_add_i32 s90, s101, 6364
	v_lshl_add_u32 v230, v230, 2, s90
	v_add_u32_e32 v231, v109, v108
	v_mov_b64_e32 v[232:233], 0
	v_mov_b64_e32 v[0:1], 0
	v_mov_b64_e32 v[2:3], 0
	v_mov_b64_e32 v[4:5], 0
	v_mov_b64_e32 v[6:7], 0
	v_mov_b64_e32 v[8:9], 0
	v_mov_b64_e32 v[10:11], 0
	v_mov_b64_e32 v[12:13], 0
	v_mov_b64_e32 v[14:15], 0
	v_mov_b64_e32 v[16:17], 0
	v_mov_b64_e32 v[18:19], 0
	v_mov_b64_e32 v[20:21], 0
	v_mov_b64_e32 v[22:23], 0
	v_mov_b64_e32 v[24:25], 0
	v_mov_b64_e32 v[26:27], 0
	v_mov_b64_e32 v[28:29], 0
	v_mov_b64_e32 v[30:31], 0
	s_add_i32 s90, s76, -64
	v_add_u32_e32 v80, s90, v235
	v_add_u32_e32 v83, s90, v236
	v_add_u32_e32 v99, s90, v237
	v_add_u32_e32 v253, s90, v238
	v_add_u32_e32 v254, s90, v100
	v_add_u32_e32 v255, s90, v149
	v_med3_i32 v80, v80, 0, s99
	v_med3_i32 v83, v83, 0, s99
	v_med3_i32 v99, v99, 0, s99
	v_med3_i32 v253, v253, 0, s99
	v_med3_i32 v254, v254, 0, s99
	v_med3_i32 v255, v255, 0, s99
	v_mad_u32_u24 v80, v80, s100, v252
	v_mad_u32_u24 v83, v83, s100, v252
	v_mad_u32_u24 v99, v99, s100, v252
	v_mad_u32_u24 v253, v253, s100, v252
	v_mad_u32_u24 v254, v254, s100, v153
	v_mad_u32_u24 v255, v255, s100, v153
	global_load_dwordx4 v[116:119], v80, s[82:83]
	global_load_dwordx4 v[120:123], v83, s[82:83]
	global_load_dwordx4 v[124:127], v99, s[82:83]
	global_load_dwordx4 v[128:131], v253, s[82:83]
	global_load_dwordx4 v[132:135], v254, s[82:83] offset:768
	global_load_dwordx4 v[136:139], v255, s[82:83] offset:768
	global_load_dwordx4 v[140:143], v254, s[82:83] offset:832
	global_load_dwordx4 v[144:147], v255, s[82:83] offset:832
	s_add_i32 s90, s76, -32
	v_add_u32_e32 v80, s90, v235
	v_add_u32_e32 v83, s90, v236
	v_add_u32_e32 v99, s90, v237
	v_add_u32_e32 v253, s90, v238
	v_add_u32_e32 v254, s90, v100
	v_add_u32_e32 v255, s90, v149
	v_med3_i32 v80, v80, 0, s99
	v_med3_i32 v83, v83, 0, s99
	v_med3_i32 v99, v99, 0, s99
	v_med3_i32 v253, v253, 0, s99
	v_med3_i32 v254, v254, 0, s99
	v_med3_i32 v255, v255, 0, s99
	v_mad_u32_u24 v80, v80, s100, v252
	v_mad_u32_u24 v83, v83, s100, v252
	v_mad_u32_u24 v99, v99, s100, v252
	v_mad_u32_u24 v253, v253, s100, v252
	v_mad_u32_u24 v254, v254, s100, v153
	v_mad_u32_u24 v255, v255, s100, v153
	global_load_dwordx4 v[156:159], v80, s[82:83]
	global_load_dwordx4 v[160:163], v83, s[82:83]
	global_load_dwordx4 v[164:167], v99, s[82:83]
	global_load_dwordx4 v[168:171], v253, s[82:83]
	global_load_dwordx4 v[172:175], v254, s[82:83] offset:768
	global_load_dwordx4 v[176:179], v255, s[82:83] offset:768
	global_load_dwordx4 v[180:183], v254, s[82:83] offset:832
	global_load_dwordx4 v[184:187], v255, s[82:83] offset:832
	v_mov_b32_e32 v115, v228
	ds_read2_b32 v[32:33], v115 offset0:0 offset1:1
	ds_read2_b32 v[34:35], v115 offset0:2 offset1:3
	ds_read2_b32 v[36:37], v115 offset0:8 offset1:9
	ds_read2_b32 v[38:39], v115 offset0:10 offset1:11
	ds_read2_b32 v[40:41], v115 offset0:17 offset1:18
	ds_read2_b32 v[42:43], v115 offset0:19 offset1:20
	ds_read2_b32 v[44:45], v115 offset0:25 offset1:26
	ds_read2_b32 v[46:47], v115 offset0:27 offset1:28
	s_waitcnt vmcnt(8)
	ds_write_b128 v247, v[116:119]
	ds_write_b128 v247, v[120:123] offset:1024
	ds_write_b128 v247, v[124:127] offset:2048
	ds_write_b128 v247, v[128:131] offset:3072
	ds_read_b128 v[116:119], v248
	ds_read_b128 v[120:123], v249
	ds_read_b128 v[124:127], v250
	ds_read_b128 v[128:131], v251
	ds_write_b128 v112, v[132:135]
	ds_write_b128 v112, v[136:139] offset:1024
	ds_write_b128 v112, v[140:143] offset:2048
	ds_write_b128 v112, v[144:147] offset:3072
	s_waitcnt lgkmcnt(4)
	v_mfma_f32_32x32x16_bf16 v[32:47], v[116:119], v[48:51], v[32:47]
	v_mfma_f32_32x32x16_bf16 v[32:47], v[120:123], v[52:55], v[32:47]
	v_mfma_f32_32x32x16_bf16 v[32:47], v[124:127], v[56:59], v[32:47]
	v_mfma_f32_32x32x16_bf16 v[32:47], v[128:131], v[60:63], v[32:47]
	ds_read2_b32 v[188:189], v115 offset0:34 offset1:35
	ds_read2_b32 v[190:191], v115 offset0:36 offset1:37
	ds_read2_b32 v[192:193], v115 offset0:42 offset1:43
	ds_read2_b32 v[194:195], v115 offset0:44 offset1:45
	ds_read2_b32 v[196:197], v115 offset0:51 offset1:52
	ds_read2_b32 v[198:199], v115 offset0:53 offset1:54
	ds_read2_b32 v[200:201], v115 offset0:59 offset1:60
	ds_read2_b32 v[202:203], v115 offset0:61 offset1:62
	s_add_i32 s90, s76, 0
	v_add_u32_e32 v80, s90, v235
	v_add_u32_e32 v83, s90, v236
	v_add_u32_e32 v99, s90, v237
	v_add_u32_e32 v253, s90, v238
	v_add_u32_e32 v254, s90, v100
	v_add_u32_e32 v255, s90, v149
	v_med3_i32 v80, v80, 0, s99
	v_med3_i32 v83, v83, 0, s99
	v_med3_i32 v99, v99, 0, s99
	v_med3_i32 v253, v253, 0, s99
	v_med3_i32 v254, v254, 0, s99
	v_med3_i32 v255, v255, 0, s99
	v_mad_u32_u24 v80, v80, s100, v252
	v_mad_u32_u24 v83, v83, s100, v252
	v_mad_u32_u24 v99, v99, s100, v252
	v_mad_u32_u24 v253, v253, s100, v252
	v_mad_u32_u24 v254, v254, s100, v153
	v_mad_u32_u24 v255, v255, s100, v153
	global_load_dwordx4 v[116:119], v80, s[82:83]
	global_load_dwordx4 v[120:123], v83, s[82:83]
	global_load_dwordx4 v[124:127], v99, s[82:83]
	global_load_dwordx4 v[128:131], v253, s[82:83]
	global_load_dwordx4 v[132:135], v254, s[82:83] offset:768
	global_load_dwordx4 v[136:139], v255, s[82:83] offset:768
	global_load_dwordx4 v[140:143], v254, s[82:83] offset:832
	global_load_dwordx4 v[144:147], v255, s[82:83] offset:832
	ds_read_b64_tr_b16 v[72:73], v231
	ds_read_b64_tr_b16 v[74:75], v231 offset:512
	ds_read_b64_tr_b16 v[76:77], v231 offset:2048
	ds_read_b64_tr_b16 v[78:79], v231 offset:2560
	ds_read_b64_tr_b16 v[220:221], v231 offset:1024
	ds_read_b64_tr_b16 v[222:223], v231 offset:1536
	ds_read_b64_tr_b16 v[224:225], v231 offset:3072
	ds_read_b64_tr_b16 v[226:227], v231 offset:3584
	v_exp_f32_e32 v32, v32
	v_exp_f32_e32 v33, v33
	s_waitcnt vmcnt(8)
	ds_write_b128 v247, v[156:159]
	ds_write_b128 v247, v[160:163] offset:1024
	ds_write_b128 v247, v[164:167] offset:2048
	ds_write_b128 v247, v[168:171] offset:3072
	ds_read_b128 v[156:159], v248
	ds_read_b128 v[160:163], v249
	ds_read_b128 v[164:167], v250
	ds_read_b128 v[168:171], v251
	ds_write_b128 v112, v[172:175]
	ds_write_b128 v112, v[176:179] offset:1024
	ds_write_b128 v112, v[180:183] offset:2048
	ds_write_b128 v112, v[184:187] offset:3072
	v_exp_f32_e32 v34, v34
	v_exp_f32_e32 v35, v35
	s_waitcnt lgkmcnt(4)
	v_mfma_f32_32x32x16_bf16 v[188:203], v[156:159], v[48:51], v[188:203]
	v_exp_f32_e32 v36, v36
	v_exp_f32_e32 v37, v37
	v_exp_f32_e32 v38, v38
	v_mfma_f32_32x32x16_bf16 v[188:203], v[160:163], v[52:55], v[188:203]
	v_exp_f32_e32 v39, v39
	v_exp_f32_e32 v40, v40
	v_exp_f32_e32 v41, v41
	v_mfma_f32_32x32x16_bf16 v[188:203], v[164:167], v[56:59], v[188:203]
	v_exp_f32_e32 v42, v42
	v_exp_f32_e32 v43, v43
	v_exp_f32_e32 v44, v44
	v_mfma_f32_32x32x16_bf16 v[188:203], v[168:171], v[60:63], v[188:203]
	v_exp_f32_e32 v45, v45
	v_exp_f32_e32 v46, v46
	v_exp_f32_e32 v47, v47
	s_add_i32 s90, s76, -64
	v_add_u32_e32 v84, s90, v107
	v_add_u32_e32 v85, 0, v84
	v_add_u32_e32 v86, 1, v84
	v_add_u32_e32 v87, 2, v84
	v_add_u32_e32 v88, 3, v84
	v_cmp_gt_u32_e64 s[30:31], s98, v85
	v_cmp_gt_u32_e64 s[36:37], s98, v86
	v_cmp_gt_u32_e64 s[78:79], s98, v87
	v_cmp_gt_u32_e64 s[50:51], s98, v88
	v_cndmask_b32_e64 v32, 0, v32, s[30:31]
	v_add_u32_e32 v85, 8, v84
	v_cmp_gt_u32_e64 s[30:31], s98, v85
	v_cndmask_b32_e64 v33, 0, v33, s[36:37]
	v_add_u32_e32 v86, 9, v84
	v_cmp_gt_u32_e64 s[36:37], s98, v86
	v_cndmask_b32_e64 v34, 0, v34, s[78:79]
	v_add_u32_e32 v87, 10, v84
	v_cmp_gt_u32_e64 s[78:79], s98, v87
	v_cndmask_b32_e64 v35, 0, v35, s[50:51]
	v_add_u32_e32 v88, 11, v84
	v_cmp_gt_u32_e64 s[50:51], s98, v88
	v_cndmask_b32_e64 v36, 0, v36, s[30:31]
	v_add_u32_e32 v85, 16, v84
	v_cmp_gt_u32_e64 s[30:31], s98, v85
	v_cndmask_b32_e64 v37, 0, v37, s[36:37]
	v_add_u32_e32 v86, 17, v84
	v_cmp_gt_u32_e64 s[36:37], s98, v86
	v_cndmask_b32_e64 v38, 0, v38, s[78:79]
	v_add_u32_e32 v87, 18, v84
	v_cmp_gt_u32_e64 s[78:79], s98, v87
	v_cndmask_b32_e64 v39, 0, v39, s[50:51]
	v_add_u32_e32 v88, 19, v84
	v_cmp_gt_u32_e64 s[50:51], s98, v88
	v_cndmask_b32_e64 v40, 0, v40, s[30:31]
	v_add_u32_e32 v85, 24, v84
	v_cmp_gt_u32_e64 s[30:31], s98, v85
	v_cndmask_b32_e64 v41, 0, v41, s[36:37]
	v_add_u32_e32 v86, 25, v84
	v_cmp_gt_u32_e64 s[36:37], s98, v86
	v_cndmask_b32_e64 v42, 0, v42, s[78:79]
	v_add_u32_e32 v87, 26, v84
	v_cmp_gt_u32_e64 s[78:79], s98, v87
	v_cndmask_b32_e64 v43, 0, v43, s[50:51]
	v_add_u32_e32 v88, 27, v84
	v_cmp_gt_u32_e64 s[50:51], s98, v88
	v_nop
	v_cndmask_b32_e64 v44, 0, v44, s[30:31]
	v_cndmask_b32_e64 v45, 0, v45, s[36:37]
	v_cndmask_b32_e64 v46, 0, v46, s[78:79]
	v_cndmask_b32_e64 v47, 0, v47, s[50:51]
	v_cvt_pk_bf16_f32 v64, v32, v33
	v_cvt_pk_bf16_f32 v65, v34, v35
	v_cvt_pk_bf16_f32 v66, v36, v37
	v_cvt_pk_bf16_f32 v67, v38, v39
	v_cvt_pk_bf16_f32 v68, v40, v41
	v_cvt_pk_bf16_f32 v69, v42, v43
	v_cvt_pk_bf16_f32 v70, v44, v45
	v_cvt_pk_bf16_f32 v71, v46, v47
	v_pk_add_f32 v[232:233], v[232:233], v[32:33]
	v_pk_add_f32 v[232:233], v[232:233], v[34:35]
	v_pk_add_f32 v[232:233], v[232:233], v[36:37]
	v_pk_add_f32 v[232:233], v[232:233], v[38:39]
	v_pk_add_f32 v[232:233], v[232:233], v[40:41]
	v_pk_add_f32 v[232:233], v[232:233], v[42:43]
	v_pk_add_f32 v[232:233], v[232:233], v[44:45]
	v_pk_add_f32 v[232:233], v[232:233], v[46:47]
	ds_read2_b32 v[32:33], v115 offset0:68 offset1:69
	ds_read2_b32 v[34:35], v115 offset0:70 offset1:71
	ds_read2_b32 v[36:37], v115 offset0:76 offset1:77
	ds_read2_b32 v[38:39], v115 offset0:78 offset1:79
	ds_read2_b32 v[40:41], v115 offset0:85 offset1:86
	ds_read2_b32 v[42:43], v115 offset0:87 offset1:88
	ds_read2_b32 v[44:45], v115 offset0:93 offset1:94
	ds_read2_b32 v[46:47], v115 offset0:95 offset1:96
	v_mfma_f32_32x32x16_bf16 v[0:15], v[64:67], v[72:75], v[0:15]
	v_mfma_f32_32x32x16_bf16 v[16:31], v[64:67], v[76:79], v[16:31]
	v_mfma_f32_32x32x16_bf16 v[0:15], v[68:71], v[220:223], v[0:15]
	v_mfma_f32_32x32x16_bf16 v[16:31], v[68:71], v[224:227], v[16:31]
	s_add_i32 s90, s76, 32
	v_add_u32_e32 v80, s90, v235
	v_add_u32_e32 v83, s90, v236
	v_add_u32_e32 v99, s90, v237
	v_add_u32_e32 v253, s90, v238
	v_add_u32_e32 v254, s90, v100
	v_add_u32_e32 v255, s90, v149
	v_med3_i32 v80, v80, 0, s99
	v_med3_i32 v83, v83, 0, s99
	v_med3_i32 v99, v99, 0, s99
	v_med3_i32 v253, v253, 0, s99
	v_med3_i32 v254, v254, 0, s99
	v_med3_i32 v255, v255, 0, s99
	v_mad_u32_u24 v80, v80, s100, v252
	v_mad_u32_u24 v83, v83, s100, v252
	v_mad_u32_u24 v99, v99, s100, v252
	v_mad_u32_u24 v253, v253, s100, v252
	v_mad_u32_u24 v254, v254, s100, v153
	v_mad_u32_u24 v255, v255, s100, v153
	global_load_dwordx4 v[156:159], v80, s[82:83]
	global_load_dwordx4 v[160:163], v83, s[82:83]
	global_load_dwordx4 v[164:167], v99, s[82:83]
	global_load_dwordx4 v[168:171], v253, s[82:83]
	global_load_dwordx4 v[172:175], v254, s[82:83] offset:768
	global_load_dwordx4 v[176:179], v255, s[82:83] offset:768
	global_load_dwordx4 v[180:183], v254, s[82:83] offset:832
	global_load_dwordx4 v[184:187], v255, s[82:83] offset:832
	ds_read_b64_tr_b16 v[72:73], v231
	ds_read_b64_tr_b16 v[74:75], v231 offset:512
	ds_read_b64_tr_b16 v[76:77], v231 offset:2048
	ds_read_b64_tr_b16 v[78:79], v231 offset:2560
	ds_read_b64_tr_b16 v[220:221], v231 offset:1024
	ds_read_b64_tr_b16 v[222:223], v231 offset:1536
	ds_read_b64_tr_b16 v[224:225], v231 offset:3072
	ds_read_b64_tr_b16 v[226:227], v231 offset:3584
	v_exp_f32_e32 v188, v188
	v_exp_f32_e32 v189, v189
	s_waitcnt vmcnt(8)
	ds_write_b128 v247, v[116:119]
	ds_write_b128 v247, v[120:123] offset:1024
	ds_write_b128 v247, v[124:127] offset:2048
	ds_write_b128 v247, v[128:131] offset:3072
	ds_read_b128 v[116:119], v248
	ds_read_b128 v[120:123], v249
	ds_read_b128 v[124:127], v250
	ds_read_b128 v[128:131], v251
	ds_write_b128 v112, v[132:135]
	ds_write_b128 v112, v[136:139] offset:1024
	ds_write_b128 v112, v[140:143] offset:2048
	ds_write_b128 v112, v[144:147] offset:3072
	v_exp_f32_e32 v190, v190
	v_exp_f32_e32 v191, v191
	s_waitcnt lgkmcnt(4)
	v_mfma_f32_32x32x16_bf16 v[32:47], v[116:119], v[48:51], v[32:47]
	v_exp_f32_e32 v192, v192
	v_exp_f32_e32 v193, v193
	v_exp_f32_e32 v194, v194
	v_mfma_f32_32x32x16_bf16 v[32:47], v[120:123], v[52:55], v[32:47]
	v_exp_f32_e32 v195, v195
	v_exp_f32_e32 v196, v196
	v_exp_f32_e32 v197, v197
	v_mfma_f32_32x32x16_bf16 v[32:47], v[124:127], v[56:59], v[32:47]
	v_exp_f32_e32 v198, v198
	v_exp_f32_e32 v199, v199
	v_exp_f32_e32 v200, v200
	v_mfma_f32_32x32x16_bf16 v[32:47], v[128:131], v[60:63], v[32:47]
	v_exp_f32_e32 v201, v201
	v_exp_f32_e32 v202, v202
	v_exp_f32_e32 v203, v203
	s_add_i32 s90, s76, -32
	v_add_u32_e32 v84, s90, v107
	v_add_u32_e32 v85, 0, v84
	v_add_u32_e32 v86, 1, v84
	v_add_u32_e32 v87, 2, v84
	v_add_u32_e32 v88, 3, v84
	v_cmp_gt_u32_e64 s[30:31], s98, v85
	v_cmp_gt_u32_e64 s[36:37], s98, v86
	v_cmp_gt_u32_e64 s[78:79], s98, v87
	v_cmp_gt_u32_e64 s[50:51], s98, v88
	v_cndmask_b32_e64 v188, 0, v188, s[30:31]
	v_add_u32_e32 v85, 8, v84
	v_cmp_gt_u32_e64 s[30:31], s98, v85
	v_cndmask_b32_e64 v189, 0, v189, s[36:37]
	v_add_u32_e32 v86, 9, v84
	v_cmp_gt_u32_e64 s[36:37], s98, v86
	v_cndmask_b32_e64 v190, 0, v190, s[78:79]
	v_add_u32_e32 v87, 10, v84
	v_cmp_gt_u32_e64 s[78:79], s98, v87
	v_cndmask_b32_e64 v191, 0, v191, s[50:51]
	v_add_u32_e32 v88, 11, v84
	v_cmp_gt_u32_e64 s[50:51], s98, v88
	v_cndmask_b32_e64 v192, 0, v192, s[30:31]
	v_add_u32_e32 v85, 16, v84
	v_cmp_gt_u32_e64 s[30:31], s98, v85
	v_cndmask_b32_e64 v193, 0, v193, s[36:37]
	v_add_u32_e32 v86, 17, v84
	v_cmp_gt_u32_e64 s[36:37], s98, v86
	v_cndmask_b32_e64 v194, 0, v194, s[78:79]
	v_add_u32_e32 v87, 18, v84
	v_cmp_gt_u32_e64 s[78:79], s98, v87
	v_cndmask_b32_e64 v195, 0, v195, s[50:51]
	v_add_u32_e32 v88, 19, v84
	v_cmp_gt_u32_e64 s[50:51], s98, v88
	v_cndmask_b32_e64 v196, 0, v196, s[30:31]
	v_add_u32_e32 v85, 24, v84
	v_cmp_gt_u32_e64 s[30:31], s98, v85
	v_cndmask_b32_e64 v197, 0, v197, s[36:37]
	v_add_u32_e32 v86, 25, v84
	v_cmp_gt_u32_e64 s[36:37], s98, v86
	v_cndmask_b32_e64 v198, 0, v198, s[78:79]
	v_add_u32_e32 v87, 26, v84
	v_cmp_gt_u32_e64 s[78:79], s98, v87
	v_cndmask_b32_e64 v199, 0, v199, s[50:51]
	v_add_u32_e32 v88, 27, v84
	v_cmp_gt_u32_e64 s[50:51], s98, v88
	v_nop
	v_cndmask_b32_e64 v200, 0, v200, s[30:31]
	v_cndmask_b32_e64 v201, 0, v201, s[36:37]
	v_cndmask_b32_e64 v202, 0, v202, s[78:79]
	v_cndmask_b32_e64 v203, 0, v203, s[50:51]
	v_cvt_pk_bf16_f32 v64, v188, v189
	v_cvt_pk_bf16_f32 v65, v190, v191
	v_cvt_pk_bf16_f32 v66, v192, v193
	v_cvt_pk_bf16_f32 v67, v194, v195
	v_cvt_pk_bf16_f32 v68, v196, v197
	v_cvt_pk_bf16_f32 v69, v198, v199
	v_cvt_pk_bf16_f32 v70, v200, v201
	v_cvt_pk_bf16_f32 v71, v202, v203
	v_pk_add_f32 v[232:233], v[232:233], v[188:189]
	v_pk_add_f32 v[232:233], v[232:233], v[190:191]
	v_pk_add_f32 v[232:233], v[232:233], v[192:193]
	v_pk_add_f32 v[232:233], v[232:233], v[194:195]
	v_pk_add_f32 v[232:233], v[232:233], v[196:197]
	v_pk_add_f32 v[232:233], v[232:233], v[198:199]
	v_pk_add_f32 v[232:233], v[232:233], v[200:201]
	v_pk_add_f32 v[232:233], v[232:233], v[202:203]
	ds_read2_b32 v[188:189], v115 offset0:102 offset1:103
	ds_read2_b32 v[190:191], v115 offset0:104 offset1:105
	ds_read2_b32 v[192:193], v115 offset0:110 offset1:111
	ds_read2_b32 v[194:195], v115 offset0:112 offset1:113
	ds_read2_b32 v[196:197], v115 offset0:119 offset1:120
	ds_read2_b32 v[198:199], v115 offset0:121 offset1:122
	ds_read2_b32 v[200:201], v115 offset0:127 offset1:128
	ds_read2_b32 v[202:203], v115 offset0:129 offset1:130
	v_mfma_f32_32x32x16_bf16 v[0:15], v[64:67], v[72:75], v[0:15]
	v_mfma_f32_32x32x16_bf16 v[16:31], v[64:67], v[76:79], v[16:31]
	v_mfma_f32_32x32x16_bf16 v[0:15], v[68:71], v[220:223], v[0:15]
	v_mfma_f32_32x32x16_bf16 v[16:31], v[68:71], v[224:227], v[16:31]
	s_add_i32 s90, s76, 64
	v_add_u32_e32 v80, s90, v235
	v_add_u32_e32 v83, s90, v236
	v_add_u32_e32 v99, s90, v237
	v_add_u32_e32 v253, s90, v238
	v_add_u32_e32 v254, s90, v100
	v_add_u32_e32 v255, s90, v149
	v_med3_i32 v80, v80, 0, s99
	v_med3_i32 v83, v83, 0, s99
	v_med3_i32 v99, v99, 0, s99
	v_med3_i32 v253, v253, 0, s99
	v_med3_i32 v254, v254, 0, s99
	v_med3_i32 v255, v255, 0, s99
	v_mad_u32_u24 v80, v80, s100, v252
	v_mad_u32_u24 v83, v83, s100, v252
	v_mad_u32_u24 v99, v99, s100, v252
	v_mad_u32_u24 v253, v253, s100, v252
	v_mad_u32_u24 v254, v254, s100, v153
	v_mad_u32_u24 v255, v255, s100, v153
	global_load_dwordx4 v[116:119], v80, s[82:83]
	global_load_dwordx4 v[120:123], v83, s[82:83]
	global_load_dwordx4 v[124:127], v99, s[82:83]
	global_load_dwordx4 v[128:131], v253, s[82:83]
	global_load_dwordx4 v[132:135], v254, s[82:83] offset:768
	global_load_dwordx4 v[136:139], v255, s[82:83] offset:768
	global_load_dwordx4 v[140:143], v254, s[82:83] offset:832
	global_load_dwordx4 v[144:147], v255, s[82:83] offset:832
	ds_read_b64_tr_b16 v[72:73], v231
	ds_read_b64_tr_b16 v[74:75], v231 offset:512
	ds_read_b64_tr_b16 v[76:77], v231 offset:2048
	ds_read_b64_tr_b16 v[78:79], v231 offset:2560
	ds_read_b64_tr_b16 v[220:221], v231 offset:1024
	ds_read_b64_tr_b16 v[222:223], v231 offset:1536
	ds_read_b64_tr_b16 v[224:225], v231 offset:3072
	ds_read_b64_tr_b16 v[226:227], v231 offset:3584
	v_exp_f32_e32 v32, v32
	v_exp_f32_e32 v33, v33
	s_waitcnt vmcnt(8)
	ds_write_b128 v247, v[156:159]
	ds_write_b128 v247, v[160:163] offset:1024
	ds_write_b128 v247, v[164:167] offset:2048
	ds_write_b128 v247, v[168:171] offset:3072
	ds_read_b128 v[156:159], v248
	ds_read_b128 v[160:163], v249
	ds_read_b128 v[164:167], v250
	ds_read_b128 v[168:171], v251
	ds_write_b128 v112, v[172:175]
	ds_write_b128 v112, v[176:179] offset:1024
	ds_write_b128 v112, v[180:183] offset:2048
	ds_write_b128 v112, v[184:187] offset:3072
	v_exp_f32_e32 v34, v34
	v_exp_f32_e32 v35, v35
	s_waitcnt lgkmcnt(4)
	v_mfma_f32_32x32x16_bf16 v[188:203], v[156:159], v[48:51], v[188:203]
	v_exp_f32_e32 v36, v36
	v_exp_f32_e32 v37, v37
	v_exp_f32_e32 v38, v38
	v_mfma_f32_32x32x16_bf16 v[188:203], v[160:163], v[52:55], v[188:203]
	v_exp_f32_e32 v39, v39
	v_exp_f32_e32 v40, v40
	v_exp_f32_e32 v41, v41
	v_mfma_f32_32x32x16_bf16 v[188:203], v[164:167], v[56:59], v[188:203]
	v_exp_f32_e32 v42, v42
	v_exp_f32_e32 v43, v43
	v_exp_f32_e32 v44, v44
	v_mfma_f32_32x32x16_bf16 v[188:203], v[168:171], v[60:63], v[188:203]
	v_exp_f32_e32 v45, v45
	v_exp_f32_e32 v46, v46
	v_exp_f32_e32 v47, v47
	s_add_i32 s90, s76, 0
	v_add_u32_e32 v84, s90, v107
	v_add_u32_e32 v85, 0, v84
	v_add_u32_e32 v86, 1, v84
	v_add_u32_e32 v87, 2, v84
	v_add_u32_e32 v88, 3, v84
	v_cmp_gt_u32_e64 s[30:31], s98, v85
	v_cmp_gt_u32_e64 s[36:37], s98, v86
	v_cmp_gt_u32_e64 s[78:79], s98, v87
	v_cmp_gt_u32_e64 s[50:51], s98, v88
	v_cndmask_b32_e64 v32, 0, v32, s[30:31]
	v_add_u32_e32 v85, 8, v84
	v_cmp_gt_u32_e64 s[30:31], s98, v85
	v_cndmask_b32_e64 v33, 0, v33, s[36:37]
	v_add_u32_e32 v86, 9, v84
	v_cmp_gt_u32_e64 s[36:37], s98, v86
	v_cndmask_b32_e64 v34, 0, v34, s[78:79]
	v_add_u32_e32 v87, 10, v84
	v_cmp_gt_u32_e64 s[78:79], s98, v87
	v_cndmask_b32_e64 v35, 0, v35, s[50:51]
	v_add_u32_e32 v88, 11, v84
	v_cmp_gt_u32_e64 s[50:51], s98, v88
	v_cndmask_b32_e64 v36, 0, v36, s[30:31]
	v_add_u32_e32 v85, 16, v84
	v_cmp_gt_u32_e64 s[30:31], s98, v85
	v_cndmask_b32_e64 v37, 0, v37, s[36:37]
	v_add_u32_e32 v86, 17, v84
	v_cmp_gt_u32_e64 s[36:37], s98, v86
	v_cndmask_b32_e64 v38, 0, v38, s[78:79]
	v_add_u32_e32 v87, 18, v84
	v_cmp_gt_u32_e64 s[78:79], s98, v87
	v_cndmask_b32_e64 v39, 0, v39, s[50:51]
	v_add_u32_e32 v88, 19, v84
	v_cmp_gt_u32_e64 s[50:51], s98, v88
	v_cndmask_b32_e64 v40, 0, v40, s[30:31]
	v_add_u32_e32 v85, 24, v84
	v_cmp_gt_u32_e64 s[30:31], s98, v85
	v_cndmask_b32_e64 v41, 0, v41, s[36:37]
	v_add_u32_e32 v86, 25, v84
	v_cmp_gt_u32_e64 s[36:37], s98, v86
	v_cndmask_b32_e64 v42, 0, v42, s[78:79]
	v_add_u32_e32 v87, 26, v84
	v_cmp_gt_u32_e64 s[78:79], s98, v87
	v_cndmask_b32_e64 v43, 0, v43, s[50:51]
	v_add_u32_e32 v88, 27, v84
	v_cmp_gt_u32_e64 s[50:51], s98, v88
	v_nop
	v_cndmask_b32_e64 v44, 0, v44, s[30:31]
	v_cndmask_b32_e64 v45, 0, v45, s[36:37]
	v_cndmask_b32_e64 v46, 0, v46, s[78:79]
	v_cndmask_b32_e64 v47, 0, v47, s[50:51]
	v_cvt_pk_bf16_f32 v64, v32, v33
	v_cvt_pk_bf16_f32 v65, v34, v35
	v_cvt_pk_bf16_f32 v66, v36, v37
	v_cvt_pk_bf16_f32 v67, v38, v39
	v_cvt_pk_bf16_f32 v68, v40, v41
	v_cvt_pk_bf16_f32 v69, v42, v43
	v_cvt_pk_bf16_f32 v70, v44, v45
	v_cvt_pk_bf16_f32 v71, v46, v47
	v_pk_add_f32 v[232:233], v[232:233], v[32:33]
	v_pk_add_f32 v[232:233], v[232:233], v[34:35]
	v_pk_add_f32 v[232:233], v[232:233], v[36:37]
	v_pk_add_f32 v[232:233], v[232:233], v[38:39]
	v_pk_add_f32 v[232:233], v[232:233], v[40:41]
	v_pk_add_f32 v[232:233], v[232:233], v[42:43]
	v_pk_add_f32 v[232:233], v[232:233], v[44:45]
	v_pk_add_f32 v[232:233], v[232:233], v[46:47]
	ds_read2_b32 v[32:33], v115 offset0:136 offset1:137
	ds_read2_b32 v[34:35], v115 offset0:138 offset1:139
	ds_read2_b32 v[36:37], v115 offset0:144 offset1:145
	ds_read2_b32 v[38:39], v115 offset0:146 offset1:147
	ds_read2_b32 v[40:41], v115 offset0:153 offset1:154
	ds_read2_b32 v[42:43], v115 offset0:155 offset1:156
	ds_read2_b32 v[44:45], v115 offset0:161 offset1:162
	ds_read2_b32 v[46:47], v115 offset0:163 offset1:164
	v_mfma_f32_32x32x16_bf16 v[0:15], v[64:67], v[72:75], v[0:15]
	v_mfma_f32_32x32x16_bf16 v[16:31], v[64:67], v[76:79], v[16:31]
	v_mfma_f32_32x32x16_bf16 v[0:15], v[68:71], v[220:223], v[0:15]
	v_mfma_f32_32x32x16_bf16 v[16:31], v[68:71], v[224:227], v[16:31]
	s_add_i32 s90, s76, 96
	v_add_u32_e32 v80, s90, v235
	v_add_u32_e32 v83, s90, v236
	v_add_u32_e32 v99, s90, v237
	v_add_u32_e32 v253, s90, v238
	v_add_u32_e32 v254, s90, v100
	v_add_u32_e32 v255, s90, v149
	v_med3_i32 v80, v80, 0, s99
	v_med3_i32 v83, v83, 0, s99
	v_med3_i32 v99, v99, 0, s99
	v_med3_i32 v253, v253, 0, s99
	v_med3_i32 v254, v254, 0, s99
	v_med3_i32 v255, v255, 0, s99
	v_mad_u32_u24 v80, v80, s100, v252
	v_mad_u32_u24 v83, v83, s100, v252
	v_mad_u32_u24 v99, v99, s100, v252
	v_mad_u32_u24 v253, v253, s100, v252
	v_mad_u32_u24 v254, v254, s100, v153
	v_mad_u32_u24 v255, v255, s100, v153
	global_load_dwordx4 v[156:159], v80, s[82:83]
	global_load_dwordx4 v[160:163], v83, s[82:83]
	global_load_dwordx4 v[164:167], v99, s[82:83]
	global_load_dwordx4 v[168:171], v253, s[82:83]
	global_load_dwordx4 v[172:175], v254, s[82:83] offset:768
	global_load_dwordx4 v[176:179], v255, s[82:83] offset:768
	global_load_dwordx4 v[180:183], v254, s[82:83] offset:832
	global_load_dwordx4 v[184:187], v255, s[82:83] offset:832
	ds_read_b64_tr_b16 v[72:73], v231
	ds_read_b64_tr_b16 v[74:75], v231 offset:512
	ds_read_b64_tr_b16 v[76:77], v231 offset:2048
	ds_read_b64_tr_b16 v[78:79], v231 offset:2560
	ds_read_b64_tr_b16 v[220:221], v231 offset:1024
	ds_read_b64_tr_b16 v[222:223], v231 offset:1536
	ds_read_b64_tr_b16 v[224:225], v231 offset:3072
	ds_read_b64_tr_b16 v[226:227], v231 offset:3584
	v_exp_f32_e32 v188, v188
	v_exp_f32_e32 v189, v189
	s_waitcnt vmcnt(8)
	ds_write_b128 v247, v[116:119]
	ds_write_b128 v247, v[120:123] offset:1024
	ds_write_b128 v247, v[124:127] offset:2048
	ds_write_b128 v247, v[128:131] offset:3072
	ds_read_b128 v[116:119], v248
	ds_read_b128 v[120:123], v249
	ds_read_b128 v[124:127], v250
	ds_read_b128 v[128:131], v251
	ds_write_b128 v112, v[132:135]
	ds_write_b128 v112, v[136:139] offset:1024
	ds_write_b128 v112, v[140:143] offset:2048
	ds_write_b128 v112, v[144:147] offset:3072
	v_exp_f32_e32 v190, v190
	v_exp_f32_e32 v191, v191
	s_waitcnt lgkmcnt(4)
	v_mfma_f32_32x32x16_bf16 v[32:47], v[116:119], v[48:51], v[32:47]
	v_exp_f32_e32 v192, v192
	v_exp_f32_e32 v193, v193
	v_exp_f32_e32 v194, v194
	v_mfma_f32_32x32x16_bf16 v[32:47], v[120:123], v[52:55], v[32:47]
	v_exp_f32_e32 v195, v195
	v_exp_f32_e32 v196, v196
	v_exp_f32_e32 v197, v197
	v_mfma_f32_32x32x16_bf16 v[32:47], v[124:127], v[56:59], v[32:47]
	v_exp_f32_e32 v198, v198
	v_exp_f32_e32 v199, v199
	v_exp_f32_e32 v200, v200
	v_mfma_f32_32x32x16_bf16 v[32:47], v[128:131], v[60:63], v[32:47]
	v_exp_f32_e32 v201, v201
	v_exp_f32_e32 v202, v202
	v_exp_f32_e32 v203, v203
	s_add_i32 s90, s76, 32
	v_add_u32_e32 v84, s90, v107
	v_add_u32_e32 v85, 0, v84
	v_add_u32_e32 v86, 1, v84
	v_add_u32_e32 v87, 2, v84
	v_add_u32_e32 v88, 3, v84
	v_cmp_gt_u32_e64 s[30:31], s98, v85
	v_cmp_gt_u32_e64 s[36:37], s98, v86
	v_cmp_gt_u32_e64 s[78:79], s98, v87
	v_cmp_gt_u32_e64 s[50:51], s98, v88
	v_cndmask_b32_e64 v188, 0, v188, s[30:31]
	v_add_u32_e32 v85, 8, v84
	v_cmp_gt_u32_e64 s[30:31], s98, v85
	v_cndmask_b32_e64 v189, 0, v189, s[36:37]
	v_add_u32_e32 v86, 9, v84
	v_cmp_gt_u32_e64 s[36:37], s98, v86
	v_cndmask_b32_e64 v190, 0, v190, s[78:79]
	v_add_u32_e32 v87, 10, v84
	v_cmp_gt_u32_e64 s[78:79], s98, v87
	v_cndmask_b32_e64 v191, 0, v191, s[50:51]
	v_add_u32_e32 v88, 11, v84
	v_cmp_gt_u32_e64 s[50:51], s98, v88
	v_cndmask_b32_e64 v192, 0, v192, s[30:31]
	v_add_u32_e32 v85, 16, v84
	v_cmp_gt_u32_e64 s[30:31], s98, v85
	v_cndmask_b32_e64 v193, 0, v193, s[36:37]
	v_add_u32_e32 v86, 17, v84
	v_cmp_gt_u32_e64 s[36:37], s98, v86
	v_cndmask_b32_e64 v194, 0, v194, s[78:79]
	v_add_u32_e32 v87, 18, v84
	v_cmp_gt_u32_e64 s[78:79], s98, v87
	v_cndmask_b32_e64 v195, 0, v195, s[50:51]
	v_add_u32_e32 v88, 19, v84
	v_cmp_gt_u32_e64 s[50:51], s98, v88
	v_cndmask_b32_e64 v196, 0, v196, s[30:31]
	v_add_u32_e32 v85, 24, v84
	v_cmp_gt_u32_e64 s[30:31], s98, v85
	v_cndmask_b32_e64 v197, 0, v197, s[36:37]
	v_add_u32_e32 v86, 25, v84
	v_cmp_gt_u32_e64 s[36:37], s98, v86
	v_cndmask_b32_e64 v198, 0, v198, s[78:79]
	v_add_u32_e32 v87, 26, v84
	v_cmp_gt_u32_e64 s[78:79], s98, v87
	v_cndmask_b32_e64 v199, 0, v199, s[50:51]
	v_add_u32_e32 v88, 27, v84
	v_cmp_gt_u32_e64 s[50:51], s98, v88
	v_nop
	v_cndmask_b32_e64 v200, 0, v200, s[30:31]
	v_cndmask_b32_e64 v201, 0, v201, s[36:37]
	v_cndmask_b32_e64 v202, 0, v202, s[78:79]
	v_cndmask_b32_e64 v203, 0, v203, s[50:51]
	v_cvt_pk_bf16_f32 v64, v188, v189
	v_cvt_pk_bf16_f32 v65, v190, v191
	v_cvt_pk_bf16_f32 v66, v192, v193
	v_cvt_pk_bf16_f32 v67, v194, v195
	v_cvt_pk_bf16_f32 v68, v196, v197
	v_cvt_pk_bf16_f32 v69, v198, v199
	v_cvt_pk_bf16_f32 v70, v200, v201
	v_cvt_pk_bf16_f32 v71, v202, v203
	v_pk_add_f32 v[232:233], v[232:233], v[188:189]
	v_pk_add_f32 v[232:233], v[232:233], v[190:191]
	v_pk_add_f32 v[232:233], v[232:233], v[192:193]
	v_pk_add_f32 v[232:233], v[232:233], v[194:195]
	v_pk_add_f32 v[232:233], v[232:233], v[196:197]
	v_pk_add_f32 v[232:233], v[232:233], v[198:199]
	v_pk_add_f32 v[232:233], v[232:233], v[200:201]
	v_pk_add_f32 v[232:233], v[232:233], v[202:203]
	ds_read2_b32 v[188:189], v115 offset0:170 offset1:171
	ds_read2_b32 v[190:191], v115 offset0:172 offset1:173
	ds_read2_b32 v[192:193], v115 offset0:178 offset1:179
	ds_read2_b32 v[194:195], v115 offset0:180 offset1:181
	ds_read2_b32 v[196:197], v115 offset0:187 offset1:188
	ds_read2_b32 v[198:199], v115 offset0:189 offset1:190
	ds_read2_b32 v[200:201], v115 offset0:195 offset1:196
	ds_read2_b32 v[202:203], v115 offset0:197 offset1:198
	v_mfma_f32_32x32x16_bf16 v[0:15], v[64:67], v[72:75], v[0:15]
	v_mfma_f32_32x32x16_bf16 v[16:31], v[64:67], v[76:79], v[16:31]
	v_mfma_f32_32x32x16_bf16 v[0:15], v[68:71], v[220:223], v[0:15]
	v_mfma_f32_32x32x16_bf16 v[16:31], v[68:71], v[224:227], v[16:31]
	s_add_i32 s90, s76, 128
	v_add_u32_e32 v80, s90, v235
	v_add_u32_e32 v83, s90, v236
	v_add_u32_e32 v99, s90, v237
	v_add_u32_e32 v253, s90, v238
	v_add_u32_e32 v254, s90, v100
	v_add_u32_e32 v255, s90, v149
	v_med3_i32 v80, v80, 0, s99
	v_med3_i32 v83, v83, 0, s99
	v_med3_i32 v99, v99, 0, s99
	v_med3_i32 v253, v253, 0, s99
	v_med3_i32 v254, v254, 0, s99
	v_med3_i32 v255, v255, 0, s99
	v_mad_u32_u24 v80, v80, s100, v252
	v_mad_u32_u24 v83, v83, s100, v252
	v_mad_u32_u24 v99, v99, s100, v252
	v_mad_u32_u24 v253, v253, s100, v252
	v_mad_u32_u24 v254, v254, s100, v153
	v_mad_u32_u24 v255, v255, s100, v153
	global_load_dwordx4 v[116:119], v80, s[82:83]
	global_load_dwordx4 v[120:123], v83, s[82:83]
	global_load_dwordx4 v[124:127], v99, s[82:83]
	global_load_dwordx4 v[128:131], v253, s[82:83]
	global_load_dwordx4 v[132:135], v254, s[82:83] offset:768
	global_load_dwordx4 v[136:139], v255, s[82:83] offset:768
	global_load_dwordx4 v[140:143], v254, s[82:83] offset:832
	global_load_dwordx4 v[144:147], v255, s[82:83] offset:832
	ds_read_b64_tr_b16 v[72:73], v231
	ds_read_b64_tr_b16 v[74:75], v231 offset:512
	ds_read_b64_tr_b16 v[76:77], v231 offset:2048
	ds_read_b64_tr_b16 v[78:79], v231 offset:2560
	ds_read_b64_tr_b16 v[220:221], v231 offset:1024
	ds_read_b64_tr_b16 v[222:223], v231 offset:1536
	ds_read_b64_tr_b16 v[224:225], v231 offset:3072
	ds_read_b64_tr_b16 v[226:227], v231 offset:3584
	v_exp_f32_e32 v32, v32
	v_exp_f32_e32 v33, v33
	s_waitcnt vmcnt(8)
	ds_write_b128 v247, v[156:159]
	ds_write_b128 v247, v[160:163] offset:1024
	ds_write_b128 v247, v[164:167] offset:2048
	ds_write_b128 v247, v[168:171] offset:3072
	ds_read_b128 v[156:159], v248
	ds_read_b128 v[160:163], v249
	ds_read_b128 v[164:167], v250
	ds_read_b128 v[168:171], v251
	ds_write_b128 v112, v[172:175]
	ds_write_b128 v112, v[176:179] offset:1024
	ds_write_b128 v112, v[180:183] offset:2048
	ds_write_b128 v112, v[184:187] offset:3072
	v_exp_f32_e32 v34, v34
	v_exp_f32_e32 v35, v35
	s_waitcnt lgkmcnt(4)
	v_mfma_f32_32x32x16_bf16 v[188:203], v[156:159], v[48:51], v[188:203]
	v_exp_f32_e32 v36, v36
	v_exp_f32_e32 v37, v37
	v_exp_f32_e32 v38, v38
	v_mfma_f32_32x32x16_bf16 v[188:203], v[160:163], v[52:55], v[188:203]
	v_exp_f32_e32 v39, v39
	v_exp_f32_e32 v40, v40
	v_exp_f32_e32 v41, v41
	v_mfma_f32_32x32x16_bf16 v[188:203], v[164:167], v[56:59], v[188:203]
	v_exp_f32_e32 v42, v42
	v_exp_f32_e32 v43, v43
	v_exp_f32_e32 v44, v44
	v_mfma_f32_32x32x16_bf16 v[188:203], v[168:171], v[60:63], v[188:203]
	v_exp_f32_e32 v45, v45
	v_exp_f32_e32 v46, v46
	v_exp_f32_e32 v47, v47
	s_add_i32 s90, s76, 64
	v_add_u32_e32 v84, s90, v107
	v_add_u32_e32 v85, 0, v84
	v_add_u32_e32 v86, 1, v84
	v_add_u32_e32 v87, 2, v84
	v_add_u32_e32 v88, 3, v84
	v_cmp_gt_u32_e64 s[30:31], s98, v85
	v_cmp_gt_u32_e64 s[36:37], s98, v86
	v_cmp_gt_u32_e64 s[78:79], s98, v87
	v_cmp_gt_u32_e64 s[50:51], s98, v88
	v_cndmask_b32_e64 v32, 0, v32, s[30:31]
	v_add_u32_e32 v85, 8, v84
	v_cmp_gt_u32_e64 s[30:31], s98, v85
	v_cndmask_b32_e64 v33, 0, v33, s[36:37]
	v_add_u32_e32 v86, 9, v84
	v_cmp_gt_u32_e64 s[36:37], s98, v86
	v_cndmask_b32_e64 v34, 0, v34, s[78:79]
	v_add_u32_e32 v87, 10, v84
	v_cmp_gt_u32_e64 s[78:79], s98, v87
	v_cndmask_b32_e64 v35, 0, v35, s[50:51]
	v_add_u32_e32 v88, 11, v84
	v_cmp_gt_u32_e64 s[50:51], s98, v88
	v_cndmask_b32_e64 v36, 0, v36, s[30:31]
	v_add_u32_e32 v85, 16, v84
	v_cmp_gt_u32_e64 s[30:31], s98, v85
	v_cndmask_b32_e64 v37, 0, v37, s[36:37]
	v_add_u32_e32 v86, 17, v84
	v_cmp_gt_u32_e64 s[36:37], s98, v86
	v_cndmask_b32_e64 v38, 0, v38, s[78:79]
	v_add_u32_e32 v87, 18, v84
	v_cmp_gt_u32_e64 s[78:79], s98, v87
	v_cndmask_b32_e64 v39, 0, v39, s[50:51]
	v_add_u32_e32 v88, 19, v84
	v_cmp_gt_u32_e64 s[50:51], s98, v88
	v_cndmask_b32_e64 v40, 0, v40, s[30:31]
	v_add_u32_e32 v85, 24, v84
	v_cmp_gt_u32_e64 s[30:31], s98, v85
	v_cndmask_b32_e64 v41, 0, v41, s[36:37]
	v_add_u32_e32 v86, 25, v84
	v_cmp_gt_u32_e64 s[36:37], s98, v86
	v_cndmask_b32_e64 v42, 0, v42, s[78:79]
	v_add_u32_e32 v87, 26, v84
	v_cmp_gt_u32_e64 s[78:79], s98, v87
	v_cndmask_b32_e64 v43, 0, v43, s[50:51]
	v_add_u32_e32 v88, 27, v84
	v_cmp_gt_u32_e64 s[50:51], s98, v88
	v_nop
	v_cndmask_b32_e64 v44, 0, v44, s[30:31]
	v_cndmask_b32_e64 v45, 0, v45, s[36:37]
	v_cndmask_b32_e64 v46, 0, v46, s[78:79]
	v_cndmask_b32_e64 v47, 0, v47, s[50:51]
	v_cvt_pk_bf16_f32 v64, v32, v33
	v_cvt_pk_bf16_f32 v65, v34, v35
	v_cvt_pk_bf16_f32 v66, v36, v37
	v_cvt_pk_bf16_f32 v67, v38, v39
	v_cvt_pk_bf16_f32 v68, v40, v41
	v_cvt_pk_bf16_f32 v69, v42, v43
	v_cvt_pk_bf16_f32 v70, v44, v45
	v_cvt_pk_bf16_f32 v71, v46, v47
	v_pk_add_f32 v[232:233], v[232:233], v[32:33]
	v_pk_add_f32 v[232:233], v[232:233], v[34:35]
	v_pk_add_f32 v[232:233], v[232:233], v[36:37]
	v_pk_add_f32 v[232:233], v[232:233], v[38:39]
	v_pk_add_f32 v[232:233], v[232:233], v[40:41]
	v_pk_add_f32 v[232:233], v[232:233], v[42:43]
	v_pk_add_f32 v[232:233], v[232:233], v[44:45]
	v_pk_add_f32 v[232:233], v[232:233], v[46:47]
	ds_read2_b32 v[32:33], v115 offset0:204 offset1:205
	ds_read2_b32 v[34:35], v115 offset0:206 offset1:207
	ds_read2_b32 v[36:37], v115 offset0:212 offset1:213
	ds_read2_b32 v[38:39], v115 offset0:214 offset1:215
	ds_read2_b32 v[40:41], v115 offset0:221 offset1:222
	ds_read2_b32 v[42:43], v115 offset0:223 offset1:224
	ds_read2_b32 v[44:45], v115 offset0:229 offset1:230
	ds_read2_b32 v[46:47], v115 offset0:231 offset1:232
	v_mfma_f32_32x32x16_bf16 v[0:15], v[64:67], v[72:75], v[0:15]
	v_mfma_f32_32x32x16_bf16 v[16:31], v[64:67], v[76:79], v[16:31]
	v_mfma_f32_32x32x16_bf16 v[0:15], v[68:71], v[220:223], v[0:15]
	v_mfma_f32_32x32x16_bf16 v[16:31], v[68:71], v[224:227], v[16:31]
	s_add_i32 s90, s76, 160
	v_add_u32_e32 v80, s90, v235
	v_add_u32_e32 v83, s90, v236
	v_add_u32_e32 v99, s90, v237
	v_add_u32_e32 v253, s90, v238
	v_add_u32_e32 v254, s90, v100
	v_add_u32_e32 v255, s90, v149
	v_med3_i32 v80, v80, 0, s99
	v_med3_i32 v83, v83, 0, s99
	v_med3_i32 v99, v99, 0, s99
	v_med3_i32 v253, v253, 0, s99
	v_med3_i32 v254, v254, 0, s99
	v_med3_i32 v255, v255, 0, s99
	v_mad_u32_u24 v80, v80, s100, v252
	v_mad_u32_u24 v83, v83, s100, v252
	v_mad_u32_u24 v99, v99, s100, v252
	v_mad_u32_u24 v253, v253, s100, v252
	v_mad_u32_u24 v254, v254, s100, v153
	v_mad_u32_u24 v255, v255, s100, v153
	global_load_dwordx4 v[156:159], v80, s[82:83]
	global_load_dwordx4 v[160:163], v83, s[82:83]
	global_load_dwordx4 v[164:167], v99, s[82:83]
	global_load_dwordx4 v[168:171], v253, s[82:83]
	global_load_dwordx4 v[172:175], v254, s[82:83] offset:768
	global_load_dwordx4 v[176:179], v255, s[82:83] offset:768
	global_load_dwordx4 v[180:183], v254, s[82:83] offset:832
	global_load_dwordx4 v[184:187], v255, s[82:83] offset:832
	ds_read_b64_tr_b16 v[72:73], v231
	ds_read_b64_tr_b16 v[74:75], v231 offset:512
	ds_read_b64_tr_b16 v[76:77], v231 offset:2048
	ds_read_b64_tr_b16 v[78:79], v231 offset:2560
	ds_read_b64_tr_b16 v[220:221], v231 offset:1024
	ds_read_b64_tr_b16 v[222:223], v231 offset:1536
	ds_read_b64_tr_b16 v[224:225], v231 offset:3072
	ds_read_b64_tr_b16 v[226:227], v231 offset:3584
	v_exp_f32_e32 v188, v188
	v_exp_f32_e32 v189, v189
	s_waitcnt vmcnt(8)
	ds_write_b128 v247, v[116:119]
	ds_write_b128 v247, v[120:123] offset:1024
	ds_write_b128 v247, v[124:127] offset:2048
	ds_write_b128 v247, v[128:131] offset:3072
	ds_read_b128 v[116:119], v248
	ds_read_b128 v[120:123], v249
	ds_read_b128 v[124:127], v250
	ds_read_b128 v[128:131], v251
	ds_write_b128 v112, v[132:135]
	ds_write_b128 v112, v[136:139] offset:1024
	ds_write_b128 v112, v[140:143] offset:2048
	ds_write_b128 v112, v[144:147] offset:3072
	v_exp_f32_e32 v190, v190
	v_exp_f32_e32 v191, v191
	s_waitcnt lgkmcnt(4)
	v_mfma_f32_32x32x16_bf16 v[32:47], v[116:119], v[48:51], v[32:47]
	v_exp_f32_e32 v192, v192
	v_exp_f32_e32 v193, v193
	v_exp_f32_e32 v194, v194
	v_mfma_f32_32x32x16_bf16 v[32:47], v[120:123], v[52:55], v[32:47]
	v_exp_f32_e32 v195, v195
	v_exp_f32_e32 v196, v196
	v_exp_f32_e32 v197, v197
	v_mfma_f32_32x32x16_bf16 v[32:47], v[124:127], v[56:59], v[32:47]
	v_exp_f32_e32 v198, v198
	v_exp_f32_e32 v199, v199
	v_exp_f32_e32 v200, v200
	v_mfma_f32_32x32x16_bf16 v[32:47], v[128:131], v[60:63], v[32:47]
	v_exp_f32_e32 v201, v201
	v_exp_f32_e32 v202, v202
	v_exp_f32_e32 v203, v203
	s_add_i32 s90, s76, 96
	v_add_u32_e32 v84, s90, v107
	v_add_u32_e32 v85, 0, v84
	v_add_u32_e32 v86, 1, v84
	v_add_u32_e32 v87, 2, v84
	v_add_u32_e32 v88, 3, v84
	v_cmp_gt_u32_e64 s[30:31], s98, v85
	v_cmp_gt_u32_e64 s[36:37], s98, v86
	v_cmp_gt_u32_e64 s[78:79], s98, v87
	v_cmp_gt_u32_e64 s[50:51], s98, v88
	v_cndmask_b32_e64 v188, 0, v188, s[30:31]
	v_add_u32_e32 v85, 8, v84
	v_cmp_gt_u32_e64 s[30:31], s98, v85
	v_cndmask_b32_e64 v189, 0, v189, s[36:37]
	v_add_u32_e32 v86, 9, v84
	v_cmp_gt_u32_e64 s[36:37], s98, v86
	v_cndmask_b32_e64 v190, 0, v190, s[78:79]
	v_add_u32_e32 v87, 10, v84
	v_cmp_gt_u32_e64 s[78:79], s98, v87
	v_cndmask_b32_e64 v191, 0, v191, s[50:51]
	v_add_u32_e32 v88, 11, v84
	v_cmp_gt_u32_e64 s[50:51], s98, v88
	v_cndmask_b32_e64 v192, 0, v192, s[30:31]
	v_add_u32_e32 v85, 16, v84
	v_cmp_gt_u32_e64 s[30:31], s98, v85
	v_cndmask_b32_e64 v193, 0, v193, s[36:37]
	v_add_u32_e32 v86, 17, v84
	v_cmp_gt_u32_e64 s[36:37], s98, v86
	v_cndmask_b32_e64 v194, 0, v194, s[78:79]
	v_add_u32_e32 v87, 18, v84
	v_cmp_gt_u32_e64 s[78:79], s98, v87
	v_cndmask_b32_e64 v195, 0, v195, s[50:51]
	v_add_u32_e32 v88, 19, v84
	v_cmp_gt_u32_e64 s[50:51], s98, v88
	v_cndmask_b32_e64 v196, 0, v196, s[30:31]
	v_add_u32_e32 v85, 24, v84
	v_cmp_gt_u32_e64 s[30:31], s98, v85
	v_cndmask_b32_e64 v197, 0, v197, s[36:37]
	v_add_u32_e32 v86, 25, v84
	v_cmp_gt_u32_e64 s[36:37], s98, v86
	v_cndmask_b32_e64 v198, 0, v198, s[78:79]
	v_add_u32_e32 v87, 26, v84
	v_cmp_gt_u32_e64 s[78:79], s98, v87
	v_cndmask_b32_e64 v199, 0, v199, s[50:51]
	v_add_u32_e32 v88, 27, v84
	v_cmp_gt_u32_e64 s[50:51], s98, v88
	v_nop
	v_cndmask_b32_e64 v200, 0, v200, s[30:31]
	v_cndmask_b32_e64 v201, 0, v201, s[36:37]
	v_cndmask_b32_e64 v202, 0, v202, s[78:79]
	v_cndmask_b32_e64 v203, 0, v203, s[50:51]
	v_cvt_pk_bf16_f32 v64, v188, v189
	v_cvt_pk_bf16_f32 v65, v190, v191
	v_cvt_pk_bf16_f32 v66, v192, v193
	v_cvt_pk_bf16_f32 v67, v194, v195
	v_cvt_pk_bf16_f32 v68, v196, v197
	v_cvt_pk_bf16_f32 v69, v198, v199
	v_cvt_pk_bf16_f32 v70, v200, v201
	v_cvt_pk_bf16_f32 v71, v202, v203
	v_pk_add_f32 v[232:233], v[232:233], v[188:189]
	v_pk_add_f32 v[232:233], v[232:233], v[190:191]
	v_pk_add_f32 v[232:233], v[232:233], v[192:193]
	v_pk_add_f32 v[232:233], v[232:233], v[194:195]
	v_pk_add_f32 v[232:233], v[232:233], v[196:197]
	v_pk_add_f32 v[232:233], v[232:233], v[198:199]
	v_pk_add_f32 v[232:233], v[232:233], v[200:201]
	v_pk_add_f32 v[232:233], v[232:233], v[202:203]
	v_add_u32_e32 v115, 952, v115
	ds_read2_b32 v[188:189], v115 offset0:0 offset1:1
	ds_read2_b32 v[190:191], v115 offset0:2 offset1:3
	ds_read2_b32 v[192:193], v115 offset0:8 offset1:9
	ds_read2_b32 v[194:195], v115 offset0:10 offset1:11
	ds_read2_b32 v[196:197], v115 offset0:17 offset1:18
	ds_read2_b32 v[198:199], v115 offset0:19 offset1:20
	ds_read2_b32 v[200:201], v115 offset0:25 offset1:26
	ds_read2_b32 v[202:203], v115 offset0:27 offset1:28
	v_mfma_f32_32x32x16_bf16 v[0:15], v[64:67], v[72:75], v[0:15]
	v_mfma_f32_32x32x16_bf16 v[16:31], v[64:67], v[76:79], v[16:31]
	v_mfma_f32_32x32x16_bf16 v[0:15], v[68:71], v[220:223], v[0:15]
	v_mfma_f32_32x32x16_bf16 v[16:31], v[68:71], v[224:227], v[16:31]
	s_add_i32 s90, s76, 192
	v_add_u32_e32 v80, s90, v235
	v_add_u32_e32 v83, s90, v236
	v_add_u32_e32 v99, s90, v237
	v_add_u32_e32 v253, s90, v238
	v_add_u32_e32 v254, s90, v100
	v_add_u32_e32 v255, s90, v149
	v_med3_i32 v80, v80, 0, s99
	v_med3_i32 v83, v83, 0, s99
	v_med3_i32 v99, v99, 0, s99
	v_med3_i32 v253, v253, 0, s99
	v_med3_i32 v254, v254, 0, s99
	v_med3_i32 v255, v255, 0, s99
	v_mad_u32_u24 v80, v80, s100, v252
	v_mad_u32_u24 v83, v83, s100, v252
	v_mad_u32_u24 v99, v99, s100, v252
	v_mad_u32_u24 v253, v253, s100, v252
	v_mad_u32_u24 v254, v254, s100, v153
	v_mad_u32_u24 v255, v255, s100, v153
	global_load_dwordx4 v[116:119], v80, s[82:83]
	global_load_dwordx4 v[120:123], v83, s[82:83]
	global_load_dwordx4 v[124:127], v99, s[82:83]
	global_load_dwordx4 v[128:131], v253, s[82:83]
	global_load_dwordx4 v[132:135], v254, s[82:83] offset:768
	global_load_dwordx4 v[136:139], v255, s[82:83] offset:768
	global_load_dwordx4 v[140:143], v254, s[82:83] offset:832
	global_load_dwordx4 v[144:147], v255, s[82:83] offset:832
	ds_read_b64_tr_b16 v[72:73], v231
	ds_read_b64_tr_b16 v[74:75], v231 offset:512
	ds_read_b64_tr_b16 v[76:77], v231 offset:2048
	ds_read_b64_tr_b16 v[78:79], v231 offset:2560
	ds_read_b64_tr_b16 v[220:221], v231 offset:1024
	ds_read_b64_tr_b16 v[222:223], v231 offset:1536
	ds_read_b64_tr_b16 v[224:225], v231 offset:3072
	ds_read_b64_tr_b16 v[226:227], v231 offset:3584
	v_exp_f32_e32 v32, v32
	v_exp_f32_e32 v33, v33
	s_waitcnt vmcnt(8)
	ds_write_b128 v247, v[156:159]
	ds_write_b128 v247, v[160:163] offset:1024
	ds_write_b128 v247, v[164:167] offset:2048
	ds_write_b128 v247, v[168:171] offset:3072
	ds_read_b128 v[156:159], v248
	ds_read_b128 v[160:163], v249
	ds_read_b128 v[164:167], v250
	ds_read_b128 v[168:171], v251
	ds_write_b128 v112, v[172:175]
	ds_write_b128 v112, v[176:179] offset:1024
	ds_write_b128 v112, v[180:183] offset:2048
	ds_write_b128 v112, v[184:187] offset:3072
	v_exp_f32_e32 v34, v34
	v_exp_f32_e32 v35, v35
	s_waitcnt lgkmcnt(4)
	v_mfma_f32_32x32x16_bf16 v[188:203], v[156:159], v[48:51], v[188:203]
	v_exp_f32_e32 v36, v36
	v_exp_f32_e32 v37, v37
	v_exp_f32_e32 v38, v38
	v_mfma_f32_32x32x16_bf16 v[188:203], v[160:163], v[52:55], v[188:203]
	v_exp_f32_e32 v39, v39
	v_exp_f32_e32 v40, v40
	v_exp_f32_e32 v41, v41
	v_mfma_f32_32x32x16_bf16 v[188:203], v[164:167], v[56:59], v[188:203]
	v_exp_f32_e32 v42, v42
	v_exp_f32_e32 v43, v43
	v_exp_f32_e32 v44, v44
	v_mfma_f32_32x32x16_bf16 v[188:203], v[168:171], v[60:63], v[188:203]
	v_exp_f32_e32 v45, v45
	v_exp_f32_e32 v46, v46
	v_exp_f32_e32 v47, v47
	s_add_i32 s90, s76, 128
	v_add_u32_e32 v84, s90, v107
	v_add_u32_e32 v85, 0, v84
	v_add_u32_e32 v86, 1, v84
	v_add_u32_e32 v87, 2, v84
	v_add_u32_e32 v88, 3, v84
	v_cmp_gt_u32_e64 s[30:31], s98, v85
	v_cmp_gt_u32_e64 s[36:37], s98, v86
	v_cmp_gt_u32_e64 s[78:79], s98, v87
	v_cmp_gt_u32_e64 s[50:51], s98, v88
	v_cndmask_b32_e64 v32, 0, v32, s[30:31]
	v_add_u32_e32 v85, 8, v84
	v_cmp_gt_u32_e64 s[30:31], s98, v85
	v_cndmask_b32_e64 v33, 0, v33, s[36:37]
	v_add_u32_e32 v86, 9, v84
	v_cmp_gt_u32_e64 s[36:37], s98, v86
	v_cndmask_b32_e64 v34, 0, v34, s[78:79]
	v_add_u32_e32 v87, 10, v84
	v_cmp_gt_u32_e64 s[78:79], s98, v87
	v_cndmask_b32_e64 v35, 0, v35, s[50:51]
	v_add_u32_e32 v88, 11, v84
	v_cmp_gt_u32_e64 s[50:51], s98, v88
	v_cndmask_b32_e64 v36, 0, v36, s[30:31]
	v_add_u32_e32 v85, 16, v84
	v_cmp_gt_u32_e64 s[30:31], s98, v85
	v_cndmask_b32_e64 v37, 0, v37, s[36:37]
	v_add_u32_e32 v86, 17, v84
	v_cmp_gt_u32_e64 s[36:37], s98, v86
	v_cndmask_b32_e64 v38, 0, v38, s[78:79]
	v_add_u32_e32 v87, 18, v84
	v_cmp_gt_u32_e64 s[78:79], s98, v87
	v_cndmask_b32_e64 v39, 0, v39, s[50:51]
	v_add_u32_e32 v88, 19, v84
	v_cmp_gt_u32_e64 s[50:51], s98, v88
	v_cndmask_b32_e64 v40, 0, v40, s[30:31]
	v_add_u32_e32 v85, 24, v84
	v_cmp_gt_u32_e64 s[30:31], s98, v85
	v_cndmask_b32_e64 v41, 0, v41, s[36:37]
	v_add_u32_e32 v86, 25, v84
	v_cmp_gt_u32_e64 s[36:37], s98, v86
	v_cndmask_b32_e64 v42, 0, v42, s[78:79]
	v_add_u32_e32 v87, 26, v84
	v_cmp_gt_u32_e64 s[78:79], s98, v87
	v_cndmask_b32_e64 v43, 0, v43, s[50:51]
	v_add_u32_e32 v88, 27, v84
	v_cmp_gt_u32_e64 s[50:51], s98, v88
	v_nop
	v_cndmask_b32_e64 v44, 0, v44, s[30:31]
	v_cndmask_b32_e64 v45, 0, v45, s[36:37]
	v_cndmask_b32_e64 v46, 0, v46, s[78:79]
	v_cndmask_b32_e64 v47, 0, v47, s[50:51]
	v_cvt_pk_bf16_f32 v64, v32, v33
	v_cvt_pk_bf16_f32 v65, v34, v35
	v_cvt_pk_bf16_f32 v66, v36, v37
	v_cvt_pk_bf16_f32 v67, v38, v39
	v_cvt_pk_bf16_f32 v68, v40, v41
	v_cvt_pk_bf16_f32 v69, v42, v43
	v_cvt_pk_bf16_f32 v70, v44, v45
	v_cvt_pk_bf16_f32 v71, v46, v47
	v_pk_add_f32 v[232:233], v[232:233], v[32:33]
	v_pk_add_f32 v[232:233], v[232:233], v[34:35]
	v_pk_add_f32 v[232:233], v[232:233], v[36:37]
	v_pk_add_f32 v[232:233], v[232:233], v[38:39]
	v_pk_add_f32 v[232:233], v[232:233], v[40:41]
	v_pk_add_f32 v[232:233], v[232:233], v[42:43]
	v_pk_add_f32 v[232:233], v[232:233], v[44:45]
	v_pk_add_f32 v[232:233], v[232:233], v[46:47]
	ds_read2_b32 v[32:33], v115 offset0:34 offset1:35
	ds_read2_b32 v[34:35], v115 offset0:36 offset1:37
	ds_read2_b32 v[36:37], v115 offset0:42 offset1:43
	ds_read2_b32 v[38:39], v115 offset0:44 offset1:45
	ds_read2_b32 v[40:41], v115 offset0:51 offset1:52
	ds_read2_b32 v[42:43], v115 offset0:53 offset1:54
	ds_read2_b32 v[44:45], v115 offset0:59 offset1:60
	ds_read2_b32 v[46:47], v115 offset0:61 offset1:62
	v_mfma_f32_32x32x16_bf16 v[0:15], v[64:67], v[72:75], v[0:15]
	v_mfma_f32_32x32x16_bf16 v[16:31], v[64:67], v[76:79], v[16:31]
	v_mfma_f32_32x32x16_bf16 v[0:15], v[68:71], v[220:223], v[0:15]
	v_mfma_f32_32x32x16_bf16 v[16:31], v[68:71], v[224:227], v[16:31]
	s_add_i32 s90, s76, 224
	v_add_u32_e32 v80, s90, v235
	v_add_u32_e32 v83, s90, v236
	v_add_u32_e32 v99, s90, v237
	v_add_u32_e32 v253, s90, v238
	v_add_u32_e32 v254, s90, v100
	v_add_u32_e32 v255, s90, v149
	v_med3_i32 v80, v80, 0, s99
	v_med3_i32 v83, v83, 0, s99
	v_med3_i32 v99, v99, 0, s99
	v_med3_i32 v253, v253, 0, s99
	v_med3_i32 v254, v254, 0, s99
	v_med3_i32 v255, v255, 0, s99
	v_mad_u32_u24 v80, v80, s100, v252
	v_mad_u32_u24 v83, v83, s100, v252
	v_mad_u32_u24 v99, v99, s100, v252
	v_mad_u32_u24 v253, v253, s100, v252
	v_mad_u32_u24 v254, v254, s100, v153
	v_mad_u32_u24 v255, v255, s100, v153
	global_load_dwordx4 v[156:159], v80, s[82:83]
	global_load_dwordx4 v[160:163], v83, s[82:83]
	global_load_dwordx4 v[164:167], v99, s[82:83]
	global_load_dwordx4 v[168:171], v253, s[82:83]
	global_load_dwordx4 v[172:175], v254, s[82:83] offset:768
	global_load_dwordx4 v[176:179], v255, s[82:83] offset:768
	global_load_dwordx4 v[180:183], v254, s[82:83] offset:832
	global_load_dwordx4 v[184:187], v255, s[82:83] offset:832
	ds_read_b64_tr_b16 v[72:73], v231
	ds_read_b64_tr_b16 v[74:75], v231 offset:512
	ds_read_b64_tr_b16 v[76:77], v231 offset:2048
	ds_read_b64_tr_b16 v[78:79], v231 offset:2560
	ds_read_b64_tr_b16 v[220:221], v231 offset:1024
	ds_read_b64_tr_b16 v[222:223], v231 offset:1536
	ds_read_b64_tr_b16 v[224:225], v231 offset:3072
	ds_read_b64_tr_b16 v[226:227], v231 offset:3584
	v_exp_f32_e32 v188, v188
	v_exp_f32_e32 v189, v189
	s_waitcnt vmcnt(8)
	ds_write_b128 v247, v[116:119]
	ds_write_b128 v247, v[120:123] offset:1024
	ds_write_b128 v247, v[124:127] offset:2048
	ds_write_b128 v247, v[128:131] offset:3072
	ds_read_b128 v[116:119], v248
	ds_read_b128 v[120:123], v249
	ds_read_b128 v[124:127], v250
	ds_read_b128 v[128:131], v251
	ds_write_b128 v112, v[132:135]
	ds_write_b128 v112, v[136:139] offset:1024
	ds_write_b128 v112, v[140:143] offset:2048
	ds_write_b128 v112, v[144:147] offset:3072
	v_exp_f32_e32 v190, v190
	v_exp_f32_e32 v191, v191
	s_waitcnt lgkmcnt(4)
	v_mfma_f32_32x32x16_bf16 v[32:47], v[116:119], v[48:51], v[32:47]
	v_exp_f32_e32 v192, v192
	v_exp_f32_e32 v193, v193
	v_exp_f32_e32 v194, v194
	v_mfma_f32_32x32x16_bf16 v[32:47], v[120:123], v[52:55], v[32:47]
	v_exp_f32_e32 v195, v195
	v_exp_f32_e32 v196, v196
	v_exp_f32_e32 v197, v197
	v_mfma_f32_32x32x16_bf16 v[32:47], v[124:127], v[56:59], v[32:47]
	v_exp_f32_e32 v198, v198
	v_exp_f32_e32 v199, v199
	v_exp_f32_e32 v200, v200
	v_mfma_f32_32x32x16_bf16 v[32:47], v[128:131], v[60:63], v[32:47]
	v_exp_f32_e32 v201, v201
	v_exp_f32_e32 v202, v202
	v_exp_f32_e32 v203, v203
	s_add_i32 s90, s76, 160
	v_add_u32_e32 v84, s90, v107
	v_add_u32_e32 v85, 0, v84
	v_add_u32_e32 v86, 1, v84
	v_add_u32_e32 v87, 2, v84
	v_add_u32_e32 v88, 3, v84
	v_cmp_gt_u32_e64 s[30:31], s98, v85
	v_cmp_gt_u32_e64 s[36:37], s98, v86
	v_cmp_gt_u32_e64 s[78:79], s98, v87
	v_cmp_gt_u32_e64 s[50:51], s98, v88
	v_cndmask_b32_e64 v188, 0, v188, s[30:31]
	v_add_u32_e32 v85, 8, v84
	v_cmp_gt_u32_e64 s[30:31], s98, v85
	v_cndmask_b32_e64 v189, 0, v189, s[36:37]
	v_add_u32_e32 v86, 9, v84
	v_cmp_gt_u32_e64 s[36:37], s98, v86
	v_cndmask_b32_e64 v190, 0, v190, s[78:79]
	v_add_u32_e32 v87, 10, v84
	v_cmp_gt_u32_e64 s[78:79], s98, v87
	v_cndmask_b32_e64 v191, 0, v191, s[50:51]
	v_add_u32_e32 v88, 11, v84
	v_cmp_gt_u32_e64 s[50:51], s98, v88
	v_cndmask_b32_e64 v192, 0, v192, s[30:31]
	v_add_u32_e32 v85, 16, v84
	v_cmp_gt_u32_e64 s[30:31], s98, v85
	v_cndmask_b32_e64 v193, 0, v193, s[36:37]
	v_add_u32_e32 v86, 17, v84
	v_cmp_gt_u32_e64 s[36:37], s98, v86
	v_cndmask_b32_e64 v194, 0, v194, s[78:79]
	v_add_u32_e32 v87, 18, v84
	v_cmp_gt_u32_e64 s[78:79], s98, v87
	v_cndmask_b32_e64 v195, 0, v195, s[50:51]
	v_add_u32_e32 v88, 19, v84
	v_cmp_gt_u32_e64 s[50:51], s98, v88
	v_cndmask_b32_e64 v196, 0, v196, s[30:31]
	v_add_u32_e32 v85, 24, v84
	v_cmp_gt_u32_e64 s[30:31], s98, v85
	v_cndmask_b32_e64 v197, 0, v197, s[36:37]
	v_add_u32_e32 v86, 25, v84
	v_cmp_gt_u32_e64 s[36:37], s98, v86
	v_cndmask_b32_e64 v198, 0, v198, s[78:79]
	v_add_u32_e32 v87, 26, v84
	v_cmp_gt_u32_e64 s[78:79], s98, v87
	v_cndmask_b32_e64 v199, 0, v199, s[50:51]
	v_add_u32_e32 v88, 27, v84
	v_cmp_gt_u32_e64 s[50:51], s98, v88
	v_nop
	v_cndmask_b32_e64 v200, 0, v200, s[30:31]
	v_cndmask_b32_e64 v201, 0, v201, s[36:37]
	v_cndmask_b32_e64 v202, 0, v202, s[78:79]
	v_cndmask_b32_e64 v203, 0, v203, s[50:51]
	v_cvt_pk_bf16_f32 v64, v188, v189
	v_cvt_pk_bf16_f32 v65, v190, v191
	v_cvt_pk_bf16_f32 v66, v192, v193
	v_cvt_pk_bf16_f32 v67, v194, v195
	v_cvt_pk_bf16_f32 v68, v196, v197
	v_cvt_pk_bf16_f32 v69, v198, v199
	v_cvt_pk_bf16_f32 v70, v200, v201
	v_cvt_pk_bf16_f32 v71, v202, v203
	v_pk_add_f32 v[232:233], v[232:233], v[188:189]
	v_pk_add_f32 v[232:233], v[232:233], v[190:191]
	v_pk_add_f32 v[232:233], v[232:233], v[192:193]
	v_pk_add_f32 v[232:233], v[232:233], v[194:195]
	v_pk_add_f32 v[232:233], v[232:233], v[196:197]
	v_pk_add_f32 v[232:233], v[232:233], v[198:199]
	v_pk_add_f32 v[232:233], v[232:233], v[200:201]
	v_pk_add_f32 v[232:233], v[232:233], v[202:203]
	ds_read2_b32 v[188:189], v115 offset0:68 offset1:69
	ds_read2_b32 v[190:191], v115 offset0:70 offset1:71
	ds_read2_b32 v[192:193], v115 offset0:76 offset1:77
	ds_read2_b32 v[194:195], v115 offset0:78 offset1:79
	ds_read2_b32 v[196:197], v115 offset0:85 offset1:86
	ds_read2_b32 v[198:199], v115 offset0:87 offset1:88
	ds_read2_b32 v[200:201], v115 offset0:93 offset1:94
	ds_read2_b32 v[202:203], v115 offset0:95 offset1:96
	v_mfma_f32_32x32x16_bf16 v[0:15], v[64:67], v[72:75], v[0:15]
	v_mfma_f32_32x32x16_bf16 v[16:31], v[64:67], v[76:79], v[16:31]
	v_mfma_f32_32x32x16_bf16 v[0:15], v[68:71], v[220:223], v[0:15]
	v_mfma_f32_32x32x16_bf16 v[16:31], v[68:71], v[224:227], v[16:31]
	s_add_i32 s90, s76, 256
	v_add_u32_e32 v80, s90, v235
	v_add_u32_e32 v83, s90, v236
	v_add_u32_e32 v99, s90, v237
	v_add_u32_e32 v253, s90, v238
	v_add_u32_e32 v254, s90, v100
	v_add_u32_e32 v255, s90, v149
	v_med3_i32 v80, v80, 0, s99
	v_med3_i32 v83, v83, 0, s99
	v_med3_i32 v99, v99, 0, s99
	v_med3_i32 v253, v253, 0, s99
	v_med3_i32 v254, v254, 0, s99
	v_med3_i32 v255, v255, 0, s99
	v_mad_u32_u24 v80, v80, s100, v252
	v_mad_u32_u24 v83, v83, s100, v252
	v_mad_u32_u24 v99, v99, s100, v252
	v_mad_u32_u24 v253, v253, s100, v252
	v_mad_u32_u24 v254, v254, s100, v153
	v_mad_u32_u24 v255, v255, s100, v153
	global_load_dwordx4 v[116:119], v80, s[82:83]
	global_load_dwordx4 v[120:123], v83, s[82:83]
	global_load_dwordx4 v[124:127], v99, s[82:83]
	global_load_dwordx4 v[128:131], v253, s[82:83]
	global_load_dwordx4 v[132:135], v254, s[82:83] offset:768
	global_load_dwordx4 v[136:139], v255, s[82:83] offset:768
	global_load_dwordx4 v[140:143], v254, s[82:83] offset:832
	global_load_dwordx4 v[144:147], v255, s[82:83] offset:832
	ds_read_b64_tr_b16 v[72:73], v231
	ds_read_b64_tr_b16 v[74:75], v231 offset:512
	ds_read_b64_tr_b16 v[76:77], v231 offset:2048
	ds_read_b64_tr_b16 v[78:79], v231 offset:2560
	ds_read_b64_tr_b16 v[220:221], v231 offset:1024
	ds_read_b64_tr_b16 v[222:223], v231 offset:1536
	ds_read_b64_tr_b16 v[224:225], v231 offset:3072
	ds_read_b64_tr_b16 v[226:227], v231 offset:3584
	v_exp_f32_e32 v32, v32
	v_exp_f32_e32 v33, v33
	s_waitcnt vmcnt(8)
	ds_write_b128 v247, v[156:159]
	ds_write_b128 v247, v[160:163] offset:1024
	ds_write_b128 v247, v[164:167] offset:2048
	ds_write_b128 v247, v[168:171] offset:3072
	ds_read_b128 v[156:159], v248
	ds_read_b128 v[160:163], v249
	ds_read_b128 v[164:167], v250
	ds_read_b128 v[168:171], v251
	ds_write_b128 v112, v[172:175]
	ds_write_b128 v112, v[176:179] offset:1024
	ds_write_b128 v112, v[180:183] offset:2048
	ds_write_b128 v112, v[184:187] offset:3072
	v_exp_f32_e32 v34, v34
	v_exp_f32_e32 v35, v35
	s_waitcnt lgkmcnt(4)
	v_mfma_f32_32x32x16_bf16 v[188:203], v[156:159], v[48:51], v[188:203]
	v_exp_f32_e32 v36, v36
	v_exp_f32_e32 v37, v37
	v_exp_f32_e32 v38, v38
	v_mfma_f32_32x32x16_bf16 v[188:203], v[160:163], v[52:55], v[188:203]
	v_exp_f32_e32 v39, v39
	v_exp_f32_e32 v40, v40
	v_exp_f32_e32 v41, v41
	v_mfma_f32_32x32x16_bf16 v[188:203], v[164:167], v[56:59], v[188:203]
	v_exp_f32_e32 v42, v42
	v_exp_f32_e32 v43, v43
	v_exp_f32_e32 v44, v44
	v_mfma_f32_32x32x16_bf16 v[188:203], v[168:171], v[60:63], v[188:203]
	v_exp_f32_e32 v45, v45
	v_exp_f32_e32 v46, v46
	v_exp_f32_e32 v47, v47
	s_add_i32 s90, s76, 192
	v_add_u32_e32 v84, s90, v107
	v_add_u32_e32 v85, 0, v84
	v_add_u32_e32 v86, 1, v84
	v_add_u32_e32 v87, 2, v84
	v_add_u32_e32 v88, 3, v84
	v_cmp_gt_u32_e64 s[30:31], s98, v85
	v_cmp_gt_u32_e64 s[36:37], s98, v86
	v_cmp_gt_u32_e64 s[78:79], s98, v87
	v_cmp_gt_u32_e64 s[50:51], s98, v88
	v_cndmask_b32_e64 v32, 0, v32, s[30:31]
	v_add_u32_e32 v85, 8, v84
	v_cmp_gt_u32_e64 s[30:31], s98, v85
	v_cndmask_b32_e64 v33, 0, v33, s[36:37]
	v_add_u32_e32 v86, 9, v84
	v_cmp_gt_u32_e64 s[36:37], s98, v86
	v_cndmask_b32_e64 v34, 0, v34, s[78:79]
	v_add_u32_e32 v87, 10, v84
	v_cmp_gt_u32_e64 s[78:79], s98, v87
	v_cndmask_b32_e64 v35, 0, v35, s[50:51]
	v_add_u32_e32 v88, 11, v84
	v_cmp_gt_u32_e64 s[50:51], s98, v88
	v_cndmask_b32_e64 v36, 0, v36, s[30:31]
	v_add_u32_e32 v85, 16, v84
	v_cmp_gt_u32_e64 s[30:31], s98, v85
	v_cndmask_b32_e64 v37, 0, v37, s[36:37]
	v_add_u32_e32 v86, 17, v84
	v_cmp_gt_u32_e64 s[36:37], s98, v86
	v_cndmask_b32_e64 v38, 0, v38, s[78:79]
	v_add_u32_e32 v87, 18, v84
	v_cmp_gt_u32_e64 s[78:79], s98, v87
	v_cndmask_b32_e64 v39, 0, v39, s[50:51]
	v_add_u32_e32 v88, 19, v84
	v_cmp_gt_u32_e64 s[50:51], s98, v88
	v_cndmask_b32_e64 v40, 0, v40, s[30:31]
	v_add_u32_e32 v85, 24, v84
	v_cmp_gt_u32_e64 s[30:31], s98, v85
	v_cndmask_b32_e64 v41, 0, v41, s[36:37]
	v_add_u32_e32 v86, 25, v84
	v_cmp_gt_u32_e64 s[36:37], s98, v86
	v_cndmask_b32_e64 v42, 0, v42, s[78:79]
	v_add_u32_e32 v87, 26, v84
	v_cmp_gt_u32_e64 s[78:79], s98, v87
	v_cndmask_b32_e64 v43, 0, v43, s[50:51]
	v_add_u32_e32 v88, 27, v84
	v_cmp_gt_u32_e64 s[50:51], s98, v88
	v_nop
	v_cndmask_b32_e64 v44, 0, v44, s[30:31]
	v_cndmask_b32_e64 v45, 0, v45, s[36:37]
	v_cndmask_b32_e64 v46, 0, v46, s[78:79]
	v_cndmask_b32_e64 v47, 0, v47, s[50:51]
	v_cvt_pk_bf16_f32 v64, v32, v33
	v_cvt_pk_bf16_f32 v65, v34, v35
	v_cvt_pk_bf16_f32 v66, v36, v37
	v_cvt_pk_bf16_f32 v67, v38, v39
	v_cvt_pk_bf16_f32 v68, v40, v41
	v_cvt_pk_bf16_f32 v69, v42, v43
	v_cvt_pk_bf16_f32 v70, v44, v45
	v_cvt_pk_bf16_f32 v71, v46, v47
	v_pk_add_f32 v[232:233], v[232:233], v[32:33]
	v_pk_add_f32 v[232:233], v[232:233], v[34:35]
	v_pk_add_f32 v[232:233], v[232:233], v[36:37]
	v_pk_add_f32 v[232:233], v[232:233], v[38:39]
	v_pk_add_f32 v[232:233], v[232:233], v[40:41]
	v_pk_add_f32 v[232:233], v[232:233], v[42:43]
	v_pk_add_f32 v[232:233], v[232:233], v[44:45]
	v_pk_add_f32 v[232:233], v[232:233], v[46:47]
	ds_read2_b32 v[32:33], v115 offset0:102 offset1:103
	ds_read2_b32 v[34:35], v115 offset0:104 offset1:105
	ds_read2_b32 v[36:37], v115 offset0:110 offset1:111
	ds_read2_b32 v[38:39], v115 offset0:112 offset1:113
	ds_read2_b32 v[40:41], v115 offset0:119 offset1:120
	ds_read2_b32 v[42:43], v115 offset0:121 offset1:122
	ds_read2_b32 v[44:45], v115 offset0:127 offset1:128
	ds_read2_b32 v[46:47], v115 offset0:129 offset1:130
	v_mfma_f32_32x32x16_bf16 v[0:15], v[64:67], v[72:75], v[0:15]
	v_mfma_f32_32x32x16_bf16 v[16:31], v[64:67], v[76:79], v[16:31]
	v_mfma_f32_32x32x16_bf16 v[0:15], v[68:71], v[220:223], v[0:15]
	v_mfma_f32_32x32x16_bf16 v[16:31], v[68:71], v[224:227], v[16:31]
	s_add_i32 s90, s76, 288
	v_add_u32_e32 v80, s90, v235
	v_add_u32_e32 v83, s90, v236
	v_add_u32_e32 v99, s90, v237
	v_add_u32_e32 v253, s90, v238
	v_add_u32_e32 v254, s90, v100
	v_add_u32_e32 v255, s90, v149
	v_med3_i32 v80, v80, 0, s99
	v_med3_i32 v83, v83, 0, s99
	v_med3_i32 v99, v99, 0, s99
	v_med3_i32 v253, v253, 0, s99
	v_med3_i32 v254, v254, 0, s99
	v_med3_i32 v255, v255, 0, s99
	v_mad_u32_u24 v80, v80, s100, v252
	v_mad_u32_u24 v83, v83, s100, v252
	v_mad_u32_u24 v99, v99, s100, v252
	v_mad_u32_u24 v253, v253, s100, v252
	v_mad_u32_u24 v254, v254, s100, v153
	v_mad_u32_u24 v255, v255, s100, v153
	global_load_dwordx4 v[156:159], v80, s[82:83]
	global_load_dwordx4 v[160:163], v83, s[82:83]
	global_load_dwordx4 v[164:167], v99, s[82:83]
	global_load_dwordx4 v[168:171], v253, s[82:83]
	global_load_dwordx4 v[172:175], v254, s[82:83] offset:768
	global_load_dwordx4 v[176:179], v255, s[82:83] offset:768
	global_load_dwordx4 v[180:183], v254, s[82:83] offset:832
	global_load_dwordx4 v[184:187], v255, s[82:83] offset:832
	ds_read_b64_tr_b16 v[72:73], v231
	ds_read_b64_tr_b16 v[74:75], v231 offset:512
	ds_read_b64_tr_b16 v[76:77], v231 offset:2048
	ds_read_b64_tr_b16 v[78:79], v231 offset:2560
	ds_read_b64_tr_b16 v[220:221], v231 offset:1024
	ds_read_b64_tr_b16 v[222:223], v231 offset:1536
	ds_read_b64_tr_b16 v[224:225], v231 offset:3072
	ds_read_b64_tr_b16 v[226:227], v231 offset:3584
	v_exp_f32_e32 v188, v188
	v_exp_f32_e32 v189, v189
	s_waitcnt vmcnt(8)
	ds_write_b128 v247, v[116:119]
	ds_write_b128 v247, v[120:123] offset:1024
	ds_write_b128 v247, v[124:127] offset:2048
	ds_write_b128 v247, v[128:131] offset:3072
	ds_read_b128 v[116:119], v248
	ds_read_b128 v[120:123], v249
	ds_read_b128 v[124:127], v250
	ds_read_b128 v[128:131], v251
	ds_write_b128 v112, v[132:135]
	ds_write_b128 v112, v[136:139] offset:1024
	ds_write_b128 v112, v[140:143] offset:2048
	ds_write_b128 v112, v[144:147] offset:3072
	v_exp_f32_e32 v190, v190
	v_exp_f32_e32 v191, v191
	s_waitcnt lgkmcnt(4)
	v_mfma_f32_32x32x16_bf16 v[32:47], v[116:119], v[48:51], v[32:47]
	v_exp_f32_e32 v192, v192
	v_exp_f32_e32 v193, v193
	v_exp_f32_e32 v194, v194
	v_mfma_f32_32x32x16_bf16 v[32:47], v[120:123], v[52:55], v[32:47]
	v_exp_f32_e32 v195, v195
	v_exp_f32_e32 v196, v196
	v_exp_f32_e32 v197, v197
	v_mfma_f32_32x32x16_bf16 v[32:47], v[124:127], v[56:59], v[32:47]
	v_exp_f32_e32 v198, v198
	v_exp_f32_e32 v199, v199
	v_exp_f32_e32 v200, v200
	v_mfma_f32_32x32x16_bf16 v[32:47], v[128:131], v[60:63], v[32:47]
	v_exp_f32_e32 v201, v201
	v_exp_f32_e32 v202, v202
	v_exp_f32_e32 v203, v203
	s_add_i32 s90, s76, 224
	v_add_u32_e32 v84, s90, v107
	v_add_u32_e32 v85, 0, v84
	v_add_u32_e32 v86, 1, v84
	v_add_u32_e32 v87, 2, v84
	v_add_u32_e32 v88, 3, v84
	v_cmp_gt_u32_e64 s[30:31], s98, v85
	v_cmp_gt_u32_e64 s[36:37], s98, v86
	v_cmp_gt_u32_e64 s[78:79], s98, v87
	v_cmp_gt_u32_e64 s[50:51], s98, v88
	v_cndmask_b32_e64 v188, 0, v188, s[30:31]
	v_add_u32_e32 v85, 8, v84
	v_cmp_gt_u32_e64 s[30:31], s98, v85
	v_cndmask_b32_e64 v189, 0, v189, s[36:37]
	v_add_u32_e32 v86, 9, v84
	v_cmp_gt_u32_e64 s[36:37], s98, v86
	v_cndmask_b32_e64 v190, 0, v190, s[78:79]
	v_add_u32_e32 v87, 10, v84
	v_cmp_gt_u32_e64 s[78:79], s98, v87
	v_cndmask_b32_e64 v191, 0, v191, s[50:51]
	v_add_u32_e32 v88, 11, v84
	v_cmp_gt_u32_e64 s[50:51], s98, v88
	v_cndmask_b32_e64 v192, 0, v192, s[30:31]
	v_add_u32_e32 v85, 16, v84
	v_cmp_gt_u32_e64 s[30:31], s98, v85
	v_cndmask_b32_e64 v193, 0, v193, s[36:37]
	v_add_u32_e32 v86, 17, v84
	v_cmp_gt_u32_e64 s[36:37], s98, v86
	v_cndmask_b32_e64 v194, 0, v194, s[78:79]
	v_add_u32_e32 v87, 18, v84
	v_cmp_gt_u32_e64 s[78:79], s98, v87
	v_cndmask_b32_e64 v195, 0, v195, s[50:51]
	v_add_u32_e32 v88, 19, v84
	v_cmp_gt_u32_e64 s[50:51], s98, v88
	v_cndmask_b32_e64 v196, 0, v196, s[30:31]
	v_add_u32_e32 v85, 24, v84
	v_cmp_gt_u32_e64 s[30:31], s98, v85
	v_cndmask_b32_e64 v197, 0, v197, s[36:37]
	v_add_u32_e32 v86, 25, v84
	v_cmp_gt_u32_e64 s[36:37], s98, v86
	v_cndmask_b32_e64 v198, 0, v198, s[78:79]
	v_add_u32_e32 v87, 26, v84
	v_cmp_gt_u32_e64 s[78:79], s98, v87
	v_cndmask_b32_e64 v199, 0, v199, s[50:51]
	v_add_u32_e32 v88, 27, v84
	v_cmp_gt_u32_e64 s[50:51], s98, v88
	v_nop
	v_cndmask_b32_e64 v200, 0, v200, s[30:31]
	v_cndmask_b32_e64 v201, 0, v201, s[36:37]
	v_cndmask_b32_e64 v202, 0, v202, s[78:79]
	v_cndmask_b32_e64 v203, 0, v203, s[50:51]
	v_cvt_pk_bf16_f32 v64, v188, v189
	v_cvt_pk_bf16_f32 v65, v190, v191
	v_cvt_pk_bf16_f32 v66, v192, v193
	v_cvt_pk_bf16_f32 v67, v194, v195
	v_cvt_pk_bf16_f32 v68, v196, v197
	v_cvt_pk_bf16_f32 v69, v198, v199
	v_cvt_pk_bf16_f32 v70, v200, v201
	v_cvt_pk_bf16_f32 v71, v202, v203
	v_pk_add_f32 v[232:233], v[232:233], v[188:189]
	v_pk_add_f32 v[232:233], v[232:233], v[190:191]
	v_pk_add_f32 v[232:233], v[232:233], v[192:193]
	v_pk_add_f32 v[232:233], v[232:233], v[194:195]
	v_pk_add_f32 v[232:233], v[232:233], v[196:197]
	v_pk_add_f32 v[232:233], v[232:233], v[198:199]
	v_pk_add_f32 v[232:233], v[232:233], v[200:201]
	v_pk_add_f32 v[232:233], v[232:233], v[202:203]
	ds_read2_b32 v[188:189], v115 offset0:136 offset1:137
	ds_read2_b32 v[190:191], v115 offset0:138 offset1:139
	ds_read2_b32 v[192:193], v115 offset0:144 offset1:145
	ds_read2_b32 v[194:195], v115 offset0:146 offset1:147
	ds_read2_b32 v[196:197], v115 offset0:153 offset1:154
	ds_read2_b32 v[198:199], v115 offset0:155 offset1:156
	ds_read2_b32 v[200:201], v115 offset0:161 offset1:162
	ds_read2_b32 v[202:203], v115 offset0:163 offset1:164
	v_mfma_f32_32x32x16_bf16 v[0:15], v[64:67], v[72:75], v[0:15]
	v_mfma_f32_32x32x16_bf16 v[16:31], v[64:67], v[76:79], v[16:31]
	v_mfma_f32_32x32x16_bf16 v[0:15], v[68:71], v[220:223], v[0:15]
	v_mfma_f32_32x32x16_bf16 v[16:31], v[68:71], v[224:227], v[16:31]
	s_add_i32 s90, s76, 320
	v_add_u32_e32 v80, s90, v235
	v_add_u32_e32 v83, s90, v236
	v_add_u32_e32 v99, s90, v237
	v_add_u32_e32 v253, s90, v238
	v_add_u32_e32 v254, s90, v100
	v_add_u32_e32 v255, s90, v149
	v_med3_i32 v80, v80, 0, s99
	v_med3_i32 v83, v83, 0, s99
	v_med3_i32 v99, v99, 0, s99
	v_med3_i32 v253, v253, 0, s99
	v_med3_i32 v254, v254, 0, s99
	v_med3_i32 v255, v255, 0, s99
	v_mad_u32_u24 v80, v80, s100, v252
	v_mad_u32_u24 v83, v83, s100, v252
	v_mad_u32_u24 v99, v99, s100, v252
	v_mad_u32_u24 v253, v253, s100, v252
	v_mad_u32_u24 v254, v254, s100, v153
	v_mad_u32_u24 v255, v255, s100, v153
	global_load_dwordx4 v[116:119], v80, s[82:83]
	global_load_dwordx4 v[120:123], v83, s[82:83]
	global_load_dwordx4 v[124:127], v99, s[82:83]
	global_load_dwordx4 v[128:131], v253, s[82:83]
	global_load_dwordx4 v[132:135], v254, s[82:83] offset:768
	global_load_dwordx4 v[136:139], v255, s[82:83] offset:768
	global_load_dwordx4 v[140:143], v254, s[82:83] offset:832
	global_load_dwordx4 v[144:147], v255, s[82:83] offset:832
	ds_read_b64_tr_b16 v[72:73], v231
	ds_read_b64_tr_b16 v[74:75], v231 offset:512
	ds_read_b64_tr_b16 v[76:77], v231 offset:2048
	ds_read_b64_tr_b16 v[78:79], v231 offset:2560
	ds_read_b64_tr_b16 v[220:221], v231 offset:1024
	ds_read_b64_tr_b16 v[222:223], v231 offset:1536
	ds_read_b64_tr_b16 v[224:225], v231 offset:3072
	ds_read_b64_tr_b16 v[226:227], v231 offset:3584
	v_exp_f32_e32 v32, v32
	v_exp_f32_e32 v33, v33
	s_waitcnt vmcnt(8)
	ds_write_b128 v247, v[156:159]
	ds_write_b128 v247, v[160:163] offset:1024
	ds_write_b128 v247, v[164:167] offset:2048
	ds_write_b128 v247, v[168:171] offset:3072
	ds_read_b128 v[156:159], v248
	ds_read_b128 v[160:163], v249
	ds_read_b128 v[164:167], v250
	ds_read_b128 v[168:171], v251
	ds_write_b128 v112, v[172:175]
	ds_write_b128 v112, v[176:179] offset:1024
	ds_write_b128 v112, v[180:183] offset:2048
	ds_write_b128 v112, v[184:187] offset:3072
	v_exp_f32_e32 v34, v34
	v_exp_f32_e32 v35, v35
	s_waitcnt lgkmcnt(4)
	v_mfma_f32_32x32x16_bf16 v[188:203], v[156:159], v[48:51], v[188:203]
	v_exp_f32_e32 v36, v36
	v_exp_f32_e32 v37, v37
	v_exp_f32_e32 v38, v38
	v_mfma_f32_32x32x16_bf16 v[188:203], v[160:163], v[52:55], v[188:203]
	v_exp_f32_e32 v39, v39
	v_exp_f32_e32 v40, v40
	v_exp_f32_e32 v41, v41
	v_mfma_f32_32x32x16_bf16 v[188:203], v[164:167], v[56:59], v[188:203]
	v_exp_f32_e32 v42, v42
	v_exp_f32_e32 v43, v43
	v_exp_f32_e32 v44, v44
	v_mfma_f32_32x32x16_bf16 v[188:203], v[168:171], v[60:63], v[188:203]
	v_exp_f32_e32 v45, v45
	v_exp_f32_e32 v46, v46
	v_exp_f32_e32 v47, v47
	s_add_i32 s90, s76, 256
	v_add_u32_e32 v84, s90, v107
	v_add_u32_e32 v85, 0, v84
	v_add_u32_e32 v86, 1, v84
	v_add_u32_e32 v87, 2, v84
	v_add_u32_e32 v88, 3, v84
	v_cmp_gt_u32_e64 s[30:31], s98, v85
	v_cmp_gt_u32_e64 s[36:37], s98, v86
	v_cmp_gt_u32_e64 s[78:79], s98, v87
	v_cmp_gt_u32_e64 s[50:51], s98, v88
	v_cndmask_b32_e64 v32, 0, v32, s[30:31]
	v_add_u32_e32 v85, 8, v84
	v_cmp_gt_u32_e64 s[30:31], s98, v85
	v_cndmask_b32_e64 v33, 0, v33, s[36:37]
	v_add_u32_e32 v86, 9, v84
	v_cmp_gt_u32_e64 s[36:37], s98, v86
	v_cndmask_b32_e64 v34, 0, v34, s[78:79]
	v_add_u32_e32 v87, 10, v84
	v_cmp_gt_u32_e64 s[78:79], s98, v87
	v_cndmask_b32_e64 v35, 0, v35, s[50:51]
	v_add_u32_e32 v88, 11, v84
	v_cmp_gt_u32_e64 s[50:51], s98, v88
	v_cndmask_b32_e64 v36, 0, v36, s[30:31]
	v_add_u32_e32 v85, 16, v84
	v_cmp_gt_u32_e64 s[30:31], s98, v85
	v_cndmask_b32_e64 v37, 0, v37, s[36:37]
	v_add_u32_e32 v86, 17, v84
	v_cmp_gt_u32_e64 s[36:37], s98, v86
	v_cndmask_b32_e64 v38, 0, v38, s[78:79]
	v_add_u32_e32 v87, 18, v84
	v_cmp_gt_u32_e64 s[78:79], s98, v87
	v_cndmask_b32_e64 v39, 0, v39, s[50:51]
	v_add_u32_e32 v88, 19, v84
	v_cmp_gt_u32_e64 s[50:51], s98, v88
	v_cndmask_b32_e64 v40, 0, v40, s[30:31]
	v_add_u32_e32 v85, 24, v84
	v_cmp_gt_u32_e64 s[30:31], s98, v85
	v_cndmask_b32_e64 v41, 0, v41, s[36:37]
	v_add_u32_e32 v86, 25, v84
	v_cmp_gt_u32_e64 s[36:37], s98, v86
	v_cndmask_b32_e64 v42, 0, v42, s[78:79]
	v_add_u32_e32 v87, 26, v84
	v_cmp_gt_u32_e64 s[78:79], s98, v87
	v_cndmask_b32_e64 v43, 0, v43, s[50:51]
	v_add_u32_e32 v88, 27, v84
	v_cmp_gt_u32_e64 s[50:51], s98, v88
	v_nop
	v_cndmask_b32_e64 v44, 0, v44, s[30:31]
	v_cndmask_b32_e64 v45, 0, v45, s[36:37]
	v_cndmask_b32_e64 v46, 0, v46, s[78:79]
	v_cndmask_b32_e64 v47, 0, v47, s[50:51]
	v_cvt_pk_bf16_f32 v64, v32, v33
	v_cvt_pk_bf16_f32 v65, v34, v35
	v_cvt_pk_bf16_f32 v66, v36, v37
	v_cvt_pk_bf16_f32 v67, v38, v39
	v_cvt_pk_bf16_f32 v68, v40, v41
	v_cvt_pk_bf16_f32 v69, v42, v43
	v_cvt_pk_bf16_f32 v70, v44, v45
	v_cvt_pk_bf16_f32 v71, v46, v47
	v_pk_add_f32 v[232:233], v[232:233], v[32:33]
	v_pk_add_f32 v[232:233], v[232:233], v[34:35]
	v_pk_add_f32 v[232:233], v[232:233], v[36:37]
	v_pk_add_f32 v[232:233], v[232:233], v[38:39]
	v_pk_add_f32 v[232:233], v[232:233], v[40:41]
	v_pk_add_f32 v[232:233], v[232:233], v[42:43]
	v_pk_add_f32 v[232:233], v[232:233], v[44:45]
	v_pk_add_f32 v[232:233], v[232:233], v[46:47]
	ds_read2_b32 v[32:33], v115 offset0:170 offset1:171
	ds_read2_b32 v[34:35], v115 offset0:172 offset1:173
	ds_read2_b32 v[36:37], v115 offset0:178 offset1:179
	ds_read2_b32 v[38:39], v115 offset0:180 offset1:181
	ds_read2_b32 v[40:41], v115 offset0:187 offset1:188
	ds_read2_b32 v[42:43], v115 offset0:189 offset1:190
	ds_read2_b32 v[44:45], v115 offset0:195 offset1:196
	ds_read2_b32 v[46:47], v115 offset0:197 offset1:198
	v_mfma_f32_32x32x16_bf16 v[0:15], v[64:67], v[72:75], v[0:15]
	v_mfma_f32_32x32x16_bf16 v[16:31], v[64:67], v[76:79], v[16:31]
	v_mfma_f32_32x32x16_bf16 v[0:15], v[68:71], v[220:223], v[0:15]
	v_mfma_f32_32x32x16_bf16 v[16:31], v[68:71], v[224:227], v[16:31]
	s_add_i32 s90, s76, 352
	v_add_u32_e32 v80, s90, v235
	v_add_u32_e32 v83, s90, v236
	v_add_u32_e32 v99, s90, v237
	v_add_u32_e32 v253, s90, v238
	v_add_u32_e32 v254, s90, v100
	v_add_u32_e32 v255, s90, v149
	v_med3_i32 v80, v80, 0, s99
	v_med3_i32 v83, v83, 0, s99
	v_med3_i32 v99, v99, 0, s99
	v_med3_i32 v253, v253, 0, s99
	v_med3_i32 v254, v254, 0, s99
	v_med3_i32 v255, v255, 0, s99
	v_mad_u32_u24 v80, v80, s100, v252
	v_mad_u32_u24 v83, v83, s100, v252
	v_mad_u32_u24 v99, v99, s100, v252
	v_mad_u32_u24 v253, v253, s100, v252
	v_mad_u32_u24 v254, v254, s100, v153
	v_mad_u32_u24 v255, v255, s100, v153
	global_load_dwordx4 v[156:159], v80, s[82:83]
	global_load_dwordx4 v[160:163], v83, s[82:83]
	global_load_dwordx4 v[164:167], v99, s[82:83]
	global_load_dwordx4 v[168:171], v253, s[82:83]
	global_load_dwordx4 v[172:175], v254, s[82:83] offset:768
	global_load_dwordx4 v[176:179], v255, s[82:83] offset:768
	global_load_dwordx4 v[180:183], v254, s[82:83] offset:832
	global_load_dwordx4 v[184:187], v255, s[82:83] offset:832
	ds_read_b64_tr_b16 v[72:73], v231
	ds_read_b64_tr_b16 v[74:75], v231 offset:512
	ds_read_b64_tr_b16 v[76:77], v231 offset:2048
	ds_read_b64_tr_b16 v[78:79], v231 offset:2560
	ds_read_b64_tr_b16 v[220:221], v231 offset:1024
	ds_read_b64_tr_b16 v[222:223], v231 offset:1536
	ds_read_b64_tr_b16 v[224:225], v231 offset:3072
	ds_read_b64_tr_b16 v[226:227], v231 offset:3584
	v_exp_f32_e32 v188, v188
	v_exp_f32_e32 v189, v189
	s_waitcnt vmcnt(8)
	ds_write_b128 v247, v[116:119]
	ds_write_b128 v247, v[120:123] offset:1024
	ds_write_b128 v247, v[124:127] offset:2048
	ds_write_b128 v247, v[128:131] offset:3072
	ds_read_b128 v[116:119], v248
	ds_read_b128 v[120:123], v249
	ds_read_b128 v[124:127], v250
	ds_read_b128 v[128:131], v251
	ds_write_b128 v112, v[132:135]
	ds_write_b128 v112, v[136:139] offset:1024
	ds_write_b128 v112, v[140:143] offset:2048
	ds_write_b128 v112, v[144:147] offset:3072
	v_exp_f32_e32 v190, v190
	v_exp_f32_e32 v191, v191
	s_waitcnt lgkmcnt(4)
	v_mfma_f32_32x32x16_bf16 v[32:47], v[116:119], v[48:51], v[32:47]
	v_exp_f32_e32 v192, v192
	v_exp_f32_e32 v193, v193
	v_exp_f32_e32 v194, v194
	v_mfma_f32_32x32x16_bf16 v[32:47], v[120:123], v[52:55], v[32:47]
	v_exp_f32_e32 v195, v195
	v_exp_f32_e32 v196, v196
	v_exp_f32_e32 v197, v197
	v_mfma_f32_32x32x16_bf16 v[32:47], v[124:127], v[56:59], v[32:47]
	v_exp_f32_e32 v198, v198
	v_exp_f32_e32 v199, v199
	v_exp_f32_e32 v200, v200
	v_mfma_f32_32x32x16_bf16 v[32:47], v[128:131], v[60:63], v[32:47]
	v_exp_f32_e32 v201, v201
	v_exp_f32_e32 v202, v202
	v_exp_f32_e32 v203, v203
	s_add_i32 s90, s76, 288
	v_add_u32_e32 v84, s90, v107
	v_add_u32_e32 v85, 0, v84
	v_add_u32_e32 v86, 1, v84
	v_add_u32_e32 v87, 2, v84
	v_add_u32_e32 v88, 3, v84
	v_cmp_gt_u32_e64 s[30:31], s98, v85
	v_cmp_gt_u32_e64 s[36:37], s98, v86
	v_cmp_gt_u32_e64 s[78:79], s98, v87
	v_cmp_gt_u32_e64 s[50:51], s98, v88
	v_cndmask_b32_e64 v188, 0, v188, s[30:31]
	v_add_u32_e32 v85, 8, v84
	v_cmp_gt_u32_e64 s[30:31], s98, v85
	v_cndmask_b32_e64 v189, 0, v189, s[36:37]
	v_add_u32_e32 v86, 9, v84
	v_cmp_gt_u32_e64 s[36:37], s98, v86
	v_cndmask_b32_e64 v190, 0, v190, s[78:79]
	v_add_u32_e32 v87, 10, v84
	v_cmp_gt_u32_e64 s[78:79], s98, v87
	v_cndmask_b32_e64 v191, 0, v191, s[50:51]
	v_add_u32_e32 v88, 11, v84
	v_cmp_gt_u32_e64 s[50:51], s98, v88
	v_cndmask_b32_e64 v192, 0, v192, s[30:31]
	v_add_u32_e32 v85, 16, v84
	v_cmp_gt_u32_e64 s[30:31], s98, v85
	v_cndmask_b32_e64 v193, 0, v193, s[36:37]
	v_add_u32_e32 v86, 17, v84
	v_cmp_gt_u32_e64 s[36:37], s98, v86
	v_cndmask_b32_e64 v194, 0, v194, s[78:79]
	v_add_u32_e32 v87, 18, v84
	v_cmp_gt_u32_e64 s[78:79], s98, v87
	v_cndmask_b32_e64 v195, 0, v195, s[50:51]
	v_add_u32_e32 v88, 19, v84
	v_cmp_gt_u32_e64 s[50:51], s98, v88
	v_cndmask_b32_e64 v196, 0, v196, s[30:31]
	v_add_u32_e32 v85, 24, v84
	v_cmp_gt_u32_e64 s[30:31], s98, v85
	v_cndmask_b32_e64 v197, 0, v197, s[36:37]
	v_add_u32_e32 v86, 25, v84
	v_cmp_gt_u32_e64 s[36:37], s98, v86
	v_cndmask_b32_e64 v198, 0, v198, s[78:79]
	v_add_u32_e32 v87, 26, v84
	v_cmp_gt_u32_e64 s[78:79], s98, v87
	v_cndmask_b32_e64 v199, 0, v199, s[50:51]
	v_add_u32_e32 v88, 27, v84
	v_cmp_gt_u32_e64 s[50:51], s98, v88
	v_nop
	v_cndmask_b32_e64 v200, 0, v200, s[30:31]
	v_cndmask_b32_e64 v201, 0, v201, s[36:37]
	v_cndmask_b32_e64 v202, 0, v202, s[78:79]
	v_cndmask_b32_e64 v203, 0, v203, s[50:51]
	v_cvt_pk_bf16_f32 v64, v188, v189
	v_cvt_pk_bf16_f32 v65, v190, v191
	v_cvt_pk_bf16_f32 v66, v192, v193
	v_cvt_pk_bf16_f32 v67, v194, v195
	v_cvt_pk_bf16_f32 v68, v196, v197
	v_cvt_pk_bf16_f32 v69, v198, v199
	v_cvt_pk_bf16_f32 v70, v200, v201
	v_cvt_pk_bf16_f32 v71, v202, v203
	v_pk_add_f32 v[232:233], v[232:233], v[188:189]
	v_pk_add_f32 v[232:233], v[232:233], v[190:191]
	v_pk_add_f32 v[232:233], v[232:233], v[192:193]
	v_pk_add_f32 v[232:233], v[232:233], v[194:195]
	v_pk_add_f32 v[232:233], v[232:233], v[196:197]
	v_pk_add_f32 v[232:233], v[232:233], v[198:199]
	v_pk_add_f32 v[232:233], v[232:233], v[200:201]
	v_pk_add_f32 v[232:233], v[232:233], v[202:203]
	ds_read2_b32 v[188:189], v115 offset0:204 offset1:205
	ds_read2_b32 v[190:191], v115 offset0:206 offset1:207
	ds_read2_b32 v[192:193], v115 offset0:212 offset1:213
	ds_read2_b32 v[194:195], v115 offset0:214 offset1:215
	ds_read2_b32 v[196:197], v115 offset0:221 offset1:222
	ds_read2_b32 v[198:199], v115 offset0:223 offset1:224
	ds_read2_b32 v[200:201], v115 offset0:229 offset1:230
	ds_read2_b32 v[202:203], v115 offset0:231 offset1:232
	v_mfma_f32_32x32x16_bf16 v[0:15], v[64:67], v[72:75], v[0:15]
	v_mfma_f32_32x32x16_bf16 v[16:31], v[64:67], v[76:79], v[16:31]
	v_mfma_f32_32x32x16_bf16 v[0:15], v[68:71], v[220:223], v[0:15]
	v_mfma_f32_32x32x16_bf16 v[16:31], v[68:71], v[224:227], v[16:31]
	s_add_i32 s90, s76, 384
	v_add_u32_e32 v80, s90, v235
	v_add_u32_e32 v83, s90, v236
	v_add_u32_e32 v99, s90, v237
	v_add_u32_e32 v253, s90, v238
	v_add_u32_e32 v254, s90, v100
	v_add_u32_e32 v255, s90, v149
	v_med3_i32 v80, v80, 0, s99
	v_med3_i32 v83, v83, 0, s99
	v_med3_i32 v99, v99, 0, s99
	v_med3_i32 v253, v253, 0, s99
	v_med3_i32 v254, v254, 0, s99
	v_med3_i32 v255, v255, 0, s99
	v_mad_u32_u24 v80, v80, s100, v252
	v_mad_u32_u24 v83, v83, s100, v252
	v_mad_u32_u24 v99, v99, s100, v252
	v_mad_u32_u24 v253, v253, s100, v252
	v_mad_u32_u24 v254, v254, s100, v153
	v_mad_u32_u24 v255, v255, s100, v153
	global_load_dwordx4 v[116:119], v80, s[82:83]
	global_load_dwordx4 v[120:123], v83, s[82:83]
	global_load_dwordx4 v[124:127], v99, s[82:83]
	global_load_dwordx4 v[128:131], v253, s[82:83]
	global_load_dwordx4 v[132:135], v254, s[82:83] offset:768
	global_load_dwordx4 v[136:139], v255, s[82:83] offset:768
	global_load_dwordx4 v[140:143], v254, s[82:83] offset:832
	global_load_dwordx4 v[144:147], v255, s[82:83] offset:832
	ds_read_b64_tr_b16 v[72:73], v231
	ds_read_b64_tr_b16 v[74:75], v231 offset:512
	ds_read_b64_tr_b16 v[76:77], v231 offset:2048
	ds_read_b64_tr_b16 v[78:79], v231 offset:2560
	ds_read_b64_tr_b16 v[220:221], v231 offset:1024
	ds_read_b64_tr_b16 v[222:223], v231 offset:1536
	ds_read_b64_tr_b16 v[224:225], v231 offset:3072
	ds_read_b64_tr_b16 v[226:227], v231 offset:3584
	v_exp_f32_e32 v32, v32
	v_exp_f32_e32 v33, v33
	s_waitcnt vmcnt(8)
	ds_write_b128 v247, v[156:159]
	ds_write_b128 v247, v[160:163] offset:1024
	ds_write_b128 v247, v[164:167] offset:2048
	ds_write_b128 v247, v[168:171] offset:3072
	ds_read_b128 v[156:159], v248
	ds_read_b128 v[160:163], v249
	ds_read_b128 v[164:167], v250
	ds_read_b128 v[168:171], v251
	ds_write_b128 v112, v[172:175]
	ds_write_b128 v112, v[176:179] offset:1024
	ds_write_b128 v112, v[180:183] offset:2048
	ds_write_b128 v112, v[184:187] offset:3072
	v_exp_f32_e32 v34, v34
	v_exp_f32_e32 v35, v35
	s_waitcnt lgkmcnt(4)
	v_mfma_f32_32x32x16_bf16 v[188:203], v[156:159], v[48:51], v[188:203]
	v_exp_f32_e32 v36, v36
	v_exp_f32_e32 v37, v37
	v_exp_f32_e32 v38, v38
	v_mfma_f32_32x32x16_bf16 v[188:203], v[160:163], v[52:55], v[188:203]
	v_exp_f32_e32 v39, v39
	v_exp_f32_e32 v40, v40
	v_exp_f32_e32 v41, v41
	v_mfma_f32_32x32x16_bf16 v[188:203], v[164:167], v[56:59], v[188:203]
	v_exp_f32_e32 v42, v42
	v_exp_f32_e32 v43, v43
	v_exp_f32_e32 v44, v44
	v_mfma_f32_32x32x16_bf16 v[188:203], v[168:171], v[60:63], v[188:203]
	v_exp_f32_e32 v45, v45
	v_exp_f32_e32 v46, v46
	v_exp_f32_e32 v47, v47
	s_add_i32 s90, s76, 320
	v_add_u32_e32 v84, s90, v107
	v_add_u32_e32 v85, 0, v84
	v_add_u32_e32 v86, 1, v84
	v_add_u32_e32 v87, 2, v84
	v_add_u32_e32 v88, 3, v84
	v_cmp_gt_u32_e64 s[30:31], s98, v85
	v_cmp_gt_u32_e64 s[36:37], s98, v86
	v_cmp_gt_u32_e64 s[78:79], s98, v87
	v_cmp_gt_u32_e64 s[50:51], s98, v88
	v_cndmask_b32_e64 v32, 0, v32, s[30:31]
	v_add_u32_e32 v85, 8, v84
	v_cmp_gt_u32_e64 s[30:31], s98, v85
	v_cndmask_b32_e64 v33, 0, v33, s[36:37]
	v_add_u32_e32 v86, 9, v84
	v_cmp_gt_u32_e64 s[36:37], s98, v86
	v_cndmask_b32_e64 v34, 0, v34, s[78:79]
	v_add_u32_e32 v87, 10, v84
	v_cmp_gt_u32_e64 s[78:79], s98, v87
	v_cndmask_b32_e64 v35, 0, v35, s[50:51]
	v_add_u32_e32 v88, 11, v84
	v_cmp_gt_u32_e64 s[50:51], s98, v88
	v_cndmask_b32_e64 v36, 0, v36, s[30:31]
	v_add_u32_e32 v85, 16, v84
	v_cmp_gt_u32_e64 s[30:31], s98, v85
	v_cndmask_b32_e64 v37, 0, v37, s[36:37]
	v_add_u32_e32 v86, 17, v84
	v_cmp_gt_u32_e64 s[36:37], s98, v86
	v_cndmask_b32_e64 v38, 0, v38, s[78:79]
	v_add_u32_e32 v87, 18, v84
	v_cmp_gt_u32_e64 s[78:79], s98, v87
	v_cndmask_b32_e64 v39, 0, v39, s[50:51]
	v_add_u32_e32 v88, 19, v84
	v_cmp_gt_u32_e64 s[50:51], s98, v88
	v_cndmask_b32_e64 v40, 0, v40, s[30:31]
	v_add_u32_e32 v85, 24, v84
	v_cmp_gt_u32_e64 s[30:31], s98, v85
	v_cndmask_b32_e64 v41, 0, v41, s[36:37]
	v_add_u32_e32 v86, 25, v84
	v_cmp_gt_u32_e64 s[36:37], s98, v86
	v_cndmask_b32_e64 v42, 0, v42, s[78:79]
	v_add_u32_e32 v87, 26, v84
	v_cmp_gt_u32_e64 s[78:79], s98, v87
	v_cndmask_b32_e64 v43, 0, v43, s[50:51]
	v_add_u32_e32 v88, 27, v84
	v_cmp_gt_u32_e64 s[50:51], s98, v88
	v_nop
	v_cndmask_b32_e64 v44, 0, v44, s[30:31]
	v_cndmask_b32_e64 v45, 0, v45, s[36:37]
	v_cndmask_b32_e64 v46, 0, v46, s[78:79]
	v_cndmask_b32_e64 v47, 0, v47, s[50:51]
	v_cvt_pk_bf16_f32 v64, v32, v33
	v_cvt_pk_bf16_f32 v65, v34, v35
	v_cvt_pk_bf16_f32 v66, v36, v37
	v_cvt_pk_bf16_f32 v67, v38, v39
	v_cvt_pk_bf16_f32 v68, v40, v41
	v_cvt_pk_bf16_f32 v69, v42, v43
	v_cvt_pk_bf16_f32 v70, v44, v45
	v_cvt_pk_bf16_f32 v71, v46, v47
	v_pk_add_f32 v[232:233], v[232:233], v[32:33]
	v_pk_add_f32 v[232:233], v[232:233], v[34:35]
	v_pk_add_f32 v[232:233], v[232:233], v[36:37]
	v_pk_add_f32 v[232:233], v[232:233], v[38:39]
	v_pk_add_f32 v[232:233], v[232:233], v[40:41]
	v_pk_add_f32 v[232:233], v[232:233], v[42:43]
	v_pk_add_f32 v[232:233], v[232:233], v[44:45]
	v_pk_add_f32 v[232:233], v[232:233], v[46:47]
	v_add_u32_e32 v115, 952, v115
	ds_read2_b32 v[32:33], v115 offset0:0 offset1:1
	ds_read2_b32 v[34:35], v115 offset0:2 offset1:3
	ds_read2_b32 v[36:37], v115 offset0:8 offset1:9
	ds_read2_b32 v[38:39], v115 offset0:10 offset1:11
	ds_read2_b32 v[40:41], v115 offset0:17 offset1:18
	ds_read2_b32 v[42:43], v115 offset0:19 offset1:20
	ds_read2_b32 v[44:45], v115 offset0:25 offset1:26
	ds_read2_b32 v[46:47], v115 offset0:27 offset1:28
	v_mfma_f32_32x32x16_bf16 v[0:15], v[64:67], v[72:75], v[0:15]
	v_mfma_f32_32x32x16_bf16 v[16:31], v[64:67], v[76:79], v[16:31]
	v_mfma_f32_32x32x16_bf16 v[0:15], v[68:71], v[220:223], v[0:15]
	v_mfma_f32_32x32x16_bf16 v[16:31], v[68:71], v[224:227], v[16:31]
	s_add_i32 s90, s76, 416
	v_add_u32_e32 v80, s90, v235
	v_add_u32_e32 v83, s90, v236
	v_add_u32_e32 v99, s90, v237
	v_add_u32_e32 v253, s90, v238
	v_add_u32_e32 v254, s90, v100
	v_add_u32_e32 v255, s90, v149
	v_med3_i32 v80, v80, 0, s99
	v_med3_i32 v83, v83, 0, s99
	v_med3_i32 v99, v99, 0, s99
	v_med3_i32 v253, v253, 0, s99
	v_med3_i32 v254, v254, 0, s99
	v_med3_i32 v255, v255, 0, s99
	v_mad_u32_u24 v80, v80, s100, v252
	v_mad_u32_u24 v83, v83, s100, v252
	v_mad_u32_u24 v99, v99, s100, v252
	v_mad_u32_u24 v253, v253, s100, v252
	v_mad_u32_u24 v254, v254, s100, v153
	v_mad_u32_u24 v255, v255, s100, v153
	global_load_dwordx4 v[156:159], v80, s[82:83]
	global_load_dwordx4 v[160:163], v83, s[82:83]
	global_load_dwordx4 v[164:167], v99, s[82:83]
	global_load_dwordx4 v[168:171], v253, s[82:83]
	global_load_dwordx4 v[172:175], v254, s[82:83] offset:768
	global_load_dwordx4 v[176:179], v255, s[82:83] offset:768
	global_load_dwordx4 v[180:183], v254, s[82:83] offset:832
	global_load_dwordx4 v[184:187], v255, s[82:83] offset:832
	ds_read_b64_tr_b16 v[72:73], v231
	ds_read_b64_tr_b16 v[74:75], v231 offset:512
	ds_read_b64_tr_b16 v[76:77], v231 offset:2048
	ds_read_b64_tr_b16 v[78:79], v231 offset:2560
	ds_read_b64_tr_b16 v[220:221], v231 offset:1024
	ds_read_b64_tr_b16 v[222:223], v231 offset:1536
	ds_read_b64_tr_b16 v[224:225], v231 offset:3072
	ds_read_b64_tr_b16 v[226:227], v231 offset:3584
	v_exp_f32_e32 v188, v188
	v_exp_f32_e32 v189, v189
	s_waitcnt vmcnt(8)
	ds_write_b128 v247, v[116:119]
	ds_write_b128 v247, v[120:123] offset:1024
	ds_write_b128 v247, v[124:127] offset:2048
	ds_write_b128 v247, v[128:131] offset:3072
	ds_read_b128 v[116:119], v248
	ds_read_b128 v[120:123], v249
	ds_read_b128 v[124:127], v250
	ds_read_b128 v[128:131], v251
	ds_write_b128 v112, v[132:135]
	ds_write_b128 v112, v[136:139] offset:1024
	ds_write_b128 v112, v[140:143] offset:2048
	ds_write_b128 v112, v[144:147] offset:3072
	v_exp_f32_e32 v190, v190
	v_exp_f32_e32 v191, v191
	s_waitcnt lgkmcnt(4)
	v_mfma_f32_32x32x16_bf16 v[32:47], v[116:119], v[48:51], v[32:47]
	v_exp_f32_e32 v192, v192
	v_exp_f32_e32 v193, v193
	v_exp_f32_e32 v194, v194
	v_mfma_f32_32x32x16_bf16 v[32:47], v[120:123], v[52:55], v[32:47]
	v_exp_f32_e32 v195, v195
	v_exp_f32_e32 v196, v196
	v_exp_f32_e32 v197, v197
	v_mfma_f32_32x32x16_bf16 v[32:47], v[124:127], v[56:59], v[32:47]
	v_exp_f32_e32 v198, v198
	v_exp_f32_e32 v199, v199
	v_exp_f32_e32 v200, v200
	v_mfma_f32_32x32x16_bf16 v[32:47], v[128:131], v[60:63], v[32:47]
	v_exp_f32_e32 v201, v201
	v_exp_f32_e32 v202, v202
	v_exp_f32_e32 v203, v203
	s_add_i32 s90, s76, 352
	v_add_u32_e32 v84, s90, v107
	v_add_u32_e32 v85, 0, v84
	v_add_u32_e32 v86, 1, v84
	v_add_u32_e32 v87, 2, v84
	v_add_u32_e32 v88, 3, v84
	v_cmp_gt_u32_e64 s[30:31], s98, v85
	v_cmp_gt_u32_e64 s[36:37], s98, v86
	v_cmp_gt_u32_e64 s[78:79], s98, v87
	v_cmp_gt_u32_e64 s[50:51], s98, v88
	v_cndmask_b32_e64 v188, 0, v188, s[30:31]
	v_add_u32_e32 v85, 8, v84
	v_cmp_gt_u32_e64 s[30:31], s98, v85
	v_cndmask_b32_e64 v189, 0, v189, s[36:37]
	v_add_u32_e32 v86, 9, v84
	v_cmp_gt_u32_e64 s[36:37], s98, v86
	v_cndmask_b32_e64 v190, 0, v190, s[78:79]
	v_add_u32_e32 v87, 10, v84
	v_cmp_gt_u32_e64 s[78:79], s98, v87
	v_cndmask_b32_e64 v191, 0, v191, s[50:51]
	v_add_u32_e32 v88, 11, v84
	v_cmp_gt_u32_e64 s[50:51], s98, v88
	v_cndmask_b32_e64 v192, 0, v192, s[30:31]
	v_add_u32_e32 v85, 16, v84
	v_cmp_gt_u32_e64 s[30:31], s98, v85
	v_cndmask_b32_e64 v193, 0, v193, s[36:37]
	v_add_u32_e32 v86, 17, v84
	v_cmp_gt_u32_e64 s[36:37], s98, v86
	v_cndmask_b32_e64 v194, 0, v194, s[78:79]
	v_add_u32_e32 v87, 18, v84
	v_cmp_gt_u32_e64 s[78:79], s98, v87
	v_cndmask_b32_e64 v195, 0, v195, s[50:51]
	v_add_u32_e32 v88, 19, v84
	v_cmp_gt_u32_e64 s[50:51], s98, v88
	v_cndmask_b32_e64 v196, 0, v196, s[30:31]
	v_add_u32_e32 v85, 24, v84
	v_cmp_gt_u32_e64 s[30:31], s98, v85
	v_cndmask_b32_e64 v197, 0, v197, s[36:37]
	v_add_u32_e32 v86, 25, v84
	v_cmp_gt_u32_e64 s[36:37], s98, v86
	v_cndmask_b32_e64 v198, 0, v198, s[78:79]
	v_add_u32_e32 v87, 26, v84
	v_cmp_gt_u32_e64 s[78:79], s98, v87
	v_cndmask_b32_e64 v199, 0, v199, s[50:51]
	v_add_u32_e32 v88, 27, v84
	v_cmp_gt_u32_e64 s[50:51], s98, v88
	v_nop
	v_cndmask_b32_e64 v200, 0, v200, s[30:31]
	v_cndmask_b32_e64 v201, 0, v201, s[36:37]
	v_cndmask_b32_e64 v202, 0, v202, s[78:79]
	v_cndmask_b32_e64 v203, 0, v203, s[50:51]
	v_cvt_pk_bf16_f32 v64, v188, v189
	v_cvt_pk_bf16_f32 v65, v190, v191
	v_cvt_pk_bf16_f32 v66, v192, v193
	v_cvt_pk_bf16_f32 v67, v194, v195
	v_cvt_pk_bf16_f32 v68, v196, v197
	v_cvt_pk_bf16_f32 v69, v198, v199
	v_cvt_pk_bf16_f32 v70, v200, v201
	v_cvt_pk_bf16_f32 v71, v202, v203
	v_pk_add_f32 v[232:233], v[232:233], v[188:189]
	v_pk_add_f32 v[232:233], v[232:233], v[190:191]
	v_pk_add_f32 v[232:233], v[232:233], v[192:193]
	v_pk_add_f32 v[232:233], v[232:233], v[194:195]
	v_pk_add_f32 v[232:233], v[232:233], v[196:197]
	v_pk_add_f32 v[232:233], v[232:233], v[198:199]
	v_pk_add_f32 v[232:233], v[232:233], v[200:201]
	v_pk_add_f32 v[232:233], v[232:233], v[202:203]
	ds_read2_b32 v[188:189], v115 offset0:34 offset1:35
	ds_read2_b32 v[190:191], v115 offset0:36 offset1:37
	ds_read2_b32 v[192:193], v115 offset0:42 offset1:43
	ds_read2_b32 v[194:195], v115 offset0:44 offset1:45
	ds_read2_b32 v[196:197], v115 offset0:51 offset1:52
	ds_read2_b32 v[198:199], v115 offset0:53 offset1:54
	ds_read2_b32 v[200:201], v115 offset0:59 offset1:60
	ds_read2_b32 v[202:203], v115 offset0:61 offset1:62
	v_mfma_f32_32x32x16_bf16 v[0:15], v[64:67], v[72:75], v[0:15]
	v_mfma_f32_32x32x16_bf16 v[16:31], v[64:67], v[76:79], v[16:31]
	v_mfma_f32_32x32x16_bf16 v[0:15], v[68:71], v[220:223], v[0:15]
	v_mfma_f32_32x32x16_bf16 v[16:31], v[68:71], v[224:227], v[16:31]
	s_add_i32 s90, s76, 448
	v_add_u32_e32 v80, s90, v235
	v_add_u32_e32 v83, s90, v236
	v_add_u32_e32 v99, s90, v237
	v_add_u32_e32 v253, s90, v238
	v_add_u32_e32 v254, s90, v100
	v_add_u32_e32 v255, s90, v149
	v_med3_i32 v80, v80, 0, s99
	v_med3_i32 v83, v83, 0, s99
	v_med3_i32 v99, v99, 0, s99
	v_med3_i32 v253, v253, 0, s99
	v_med3_i32 v254, v254, 0, s99
	v_med3_i32 v255, v255, 0, s99
	v_mad_u32_u24 v80, v80, s100, v252
	v_mad_u32_u24 v83, v83, s100, v252
	v_mad_u32_u24 v99, v99, s100, v252
	v_mad_u32_u24 v253, v253, s100, v252
	v_mad_u32_u24 v254, v254, s100, v153
	v_mad_u32_u24 v255, v255, s100, v153
	global_load_dwordx4 v[116:119], v80, s[82:83]
	global_load_dwordx4 v[120:123], v83, s[82:83]
	global_load_dwordx4 v[124:127], v99, s[82:83]
	global_load_dwordx4 v[128:131], v253, s[82:83]
	global_load_dwordx4 v[132:135], v254, s[82:83] offset:768
	global_load_dwordx4 v[136:139], v255, s[82:83] offset:768
	global_load_dwordx4 v[140:143], v254, s[82:83] offset:832
	global_load_dwordx4 v[144:147], v255, s[82:83] offset:832
	ds_read_b64_tr_b16 v[72:73], v231
	ds_read_b64_tr_b16 v[74:75], v231 offset:512
	ds_read_b64_tr_b16 v[76:77], v231 offset:2048
	ds_read_b64_tr_b16 v[78:79], v231 offset:2560
	ds_read_b64_tr_b16 v[220:221], v231 offset:1024
	ds_read_b64_tr_b16 v[222:223], v231 offset:1536
	ds_read_b64_tr_b16 v[224:225], v231 offset:3072
	ds_read_b64_tr_b16 v[226:227], v231 offset:3584
	v_exp_f32_e32 v32, v32
	v_exp_f32_e32 v33, v33
	s_waitcnt vmcnt(8)
	ds_write_b128 v247, v[156:159]
	ds_write_b128 v247, v[160:163] offset:1024
	ds_write_b128 v247, v[164:167] offset:2048
	ds_write_b128 v247, v[168:171] offset:3072
	ds_read_b128 v[156:159], v248
	ds_read_b128 v[160:163], v249
	ds_read_b128 v[164:167], v250
	ds_read_b128 v[168:171], v251
	ds_write_b128 v112, v[172:175]
	ds_write_b128 v112, v[176:179] offset:1024
	ds_write_b128 v112, v[180:183] offset:2048
	ds_write_b128 v112, v[184:187] offset:3072
	v_exp_f32_e32 v34, v34
	v_exp_f32_e32 v35, v35
	s_waitcnt lgkmcnt(4)
	v_mfma_f32_32x32x16_bf16 v[188:203], v[156:159], v[48:51], v[188:203]
	v_exp_f32_e32 v36, v36
	v_exp_f32_e32 v37, v37
	v_exp_f32_e32 v38, v38
	v_mfma_f32_32x32x16_bf16 v[188:203], v[160:163], v[52:55], v[188:203]
	v_exp_f32_e32 v39, v39
	v_exp_f32_e32 v40, v40
	v_exp_f32_e32 v41, v41
	v_mfma_f32_32x32x16_bf16 v[188:203], v[164:167], v[56:59], v[188:203]
	v_exp_f32_e32 v42, v42
	v_exp_f32_e32 v43, v43
	v_exp_f32_e32 v44, v44
	v_mfma_f32_32x32x16_bf16 v[188:203], v[168:171], v[60:63], v[188:203]
	v_exp_f32_e32 v45, v45
	v_exp_f32_e32 v46, v46
	v_exp_f32_e32 v47, v47
	s_add_i32 s90, s76, 384
	v_add_u32_e32 v84, s90, v107
	v_add_u32_e32 v85, 0, v84
	v_add_u32_e32 v86, 1, v84
	v_add_u32_e32 v87, 2, v84
	v_add_u32_e32 v88, 3, v84
	v_cmp_gt_u32_e64 s[30:31], s98, v85
	v_cmp_gt_u32_e64 s[36:37], s98, v86
	v_cmp_gt_u32_e64 s[78:79], s98, v87
	v_cmp_gt_u32_e64 s[50:51], s98, v88
	v_cndmask_b32_e64 v32, 0, v32, s[30:31]
	v_add_u32_e32 v85, 8, v84
	v_cmp_gt_u32_e64 s[30:31], s98, v85
	v_cndmask_b32_e64 v33, 0, v33, s[36:37]
	v_add_u32_e32 v86, 9, v84
	v_cmp_gt_u32_e64 s[36:37], s98, v86
	v_cndmask_b32_e64 v34, 0, v34, s[78:79]
	v_add_u32_e32 v87, 10, v84
	v_cmp_gt_u32_e64 s[78:79], s98, v87
	v_cndmask_b32_e64 v35, 0, v35, s[50:51]
	v_add_u32_e32 v88, 11, v84
	v_cmp_gt_u32_e64 s[50:51], s98, v88
	v_cndmask_b32_e64 v36, 0, v36, s[30:31]
	v_add_u32_e32 v85, 16, v84
	v_cmp_gt_u32_e64 s[30:31], s98, v85
	v_cndmask_b32_e64 v37, 0, v37, s[36:37]
	v_add_u32_e32 v86, 17, v84
	v_cmp_gt_u32_e64 s[36:37], s98, v86
	v_cndmask_b32_e64 v38, 0, v38, s[78:79]
	v_add_u32_e32 v87, 18, v84
	v_cmp_gt_u32_e64 s[78:79], s98, v87
	v_cndmask_b32_e64 v39, 0, v39, s[50:51]
	v_add_u32_e32 v88, 19, v84
	v_cmp_gt_u32_e64 s[50:51], s98, v88
	v_cndmask_b32_e64 v40, 0, v40, s[30:31]
	v_add_u32_e32 v85, 24, v84
	v_cmp_gt_u32_e64 s[30:31], s98, v85
	v_cndmask_b32_e64 v41, 0, v41, s[36:37]
	v_add_u32_e32 v86, 25, v84
	v_cmp_gt_u32_e64 s[36:37], s98, v86
	v_cndmask_b32_e64 v42, 0, v42, s[78:79]
	v_add_u32_e32 v87, 26, v84
	v_cmp_gt_u32_e64 s[78:79], s98, v87
	v_cndmask_b32_e64 v43, 0, v43, s[50:51]
	v_add_u32_e32 v88, 27, v84
	v_cmp_gt_u32_e64 s[50:51], s98, v88
	v_nop
	v_cndmask_b32_e64 v44, 0, v44, s[30:31]
	v_cndmask_b32_e64 v45, 0, v45, s[36:37]
	v_cndmask_b32_e64 v46, 0, v46, s[78:79]
	v_cndmask_b32_e64 v47, 0, v47, s[50:51]
	v_cvt_pk_bf16_f32 v64, v32, v33
	v_cvt_pk_bf16_f32 v65, v34, v35
	v_cvt_pk_bf16_f32 v66, v36, v37
	v_cvt_pk_bf16_f32 v67, v38, v39
	v_cvt_pk_bf16_f32 v68, v40, v41
	v_cvt_pk_bf16_f32 v69, v42, v43
	v_cvt_pk_bf16_f32 v70, v44, v45
	v_cvt_pk_bf16_f32 v71, v46, v47
	v_pk_add_f32 v[232:233], v[232:233], v[32:33]
	v_pk_add_f32 v[232:233], v[232:233], v[34:35]
	v_pk_add_f32 v[232:233], v[232:233], v[36:37]
	v_pk_add_f32 v[232:233], v[232:233], v[38:39]
	v_pk_add_f32 v[232:233], v[232:233], v[40:41]
	v_pk_add_f32 v[232:233], v[232:233], v[42:43]
	v_pk_add_f32 v[232:233], v[232:233], v[44:45]
	v_pk_add_f32 v[232:233], v[232:233], v[46:47]
	ds_read2_b32 v[32:33], v115 offset0:68 offset1:69
	ds_read2_b32 v[34:35], v115 offset0:70 offset1:71
	ds_read2_b32 v[36:37], v115 offset0:76 offset1:77
	ds_read2_b32 v[38:39], v115 offset0:78 offset1:79
	ds_read2_b32 v[40:41], v115 offset0:85 offset1:86
	ds_read2_b32 v[42:43], v115 offset0:87 offset1:88
	ds_read2_b32 v[44:45], v115 offset0:93 offset1:94
	ds_read2_b32 v[46:47], v115 offset0:95 offset1:96
	v_mfma_f32_32x32x16_bf16 v[0:15], v[64:67], v[72:75], v[0:15]
	v_mfma_f32_32x32x16_bf16 v[16:31], v[64:67], v[76:79], v[16:31]
	v_mfma_f32_32x32x16_bf16 v[0:15], v[68:71], v[220:223], v[0:15]
	v_mfma_f32_32x32x16_bf16 v[16:31], v[68:71], v[224:227], v[16:31]
	s_add_i32 s90, s76, 480
	v_add_u32_e32 v80, s90, v235
	v_add_u32_e32 v83, s90, v236
	v_add_u32_e32 v99, s90, v237
	v_add_u32_e32 v253, s90, v238
	v_add_u32_e32 v254, s90, v100
	v_add_u32_e32 v255, s90, v149
	v_med3_i32 v80, v80, 0, s99
	v_med3_i32 v83, v83, 0, s99
	v_med3_i32 v99, v99, 0, s99
	v_med3_i32 v253, v253, 0, s99
	v_med3_i32 v254, v254, 0, s99
	v_med3_i32 v255, v255, 0, s99
	v_mad_u32_u24 v80, v80, s100, v252
	v_mad_u32_u24 v83, v83, s100, v252
	v_mad_u32_u24 v99, v99, s100, v252
	v_mad_u32_u24 v253, v253, s100, v252
	v_mad_u32_u24 v254, v254, s100, v153
	v_mad_u32_u24 v255, v255, s100, v153
	global_load_dwordx4 v[156:159], v80, s[82:83]
	global_load_dwordx4 v[160:163], v83, s[82:83]
	global_load_dwordx4 v[164:167], v99, s[82:83]
	global_load_dwordx4 v[168:171], v253, s[82:83]
	global_load_dwordx4 v[172:175], v254, s[82:83] offset:768
	global_load_dwordx4 v[176:179], v255, s[82:83] offset:768
	global_load_dwordx4 v[180:183], v254, s[82:83] offset:832
	global_load_dwordx4 v[184:187], v255, s[82:83] offset:832
	ds_read_b64_tr_b16 v[72:73], v231
	ds_read_b64_tr_b16 v[74:75], v231 offset:512
	ds_read_b64_tr_b16 v[76:77], v231 offset:2048
	ds_read_b64_tr_b16 v[78:79], v231 offset:2560
	ds_read_b64_tr_b16 v[220:221], v231 offset:1024
	ds_read_b64_tr_b16 v[222:223], v231 offset:1536
	ds_read_b64_tr_b16 v[224:225], v231 offset:3072
	ds_read_b64_tr_b16 v[226:227], v231 offset:3584
	v_exp_f32_e32 v188, v188
	v_exp_f32_e32 v189, v189
	s_waitcnt vmcnt(8)
	ds_write_b128 v247, v[116:119]
	ds_write_b128 v247, v[120:123] offset:1024
	ds_write_b128 v247, v[124:127] offset:2048
	ds_write_b128 v247, v[128:131] offset:3072
	ds_read_b128 v[116:119], v248
	ds_read_b128 v[120:123], v249
	ds_read_b128 v[124:127], v250
	ds_read_b128 v[128:131], v251
	ds_write_b128 v112, v[132:135]
	ds_write_b128 v112, v[136:139] offset:1024
	ds_write_b128 v112, v[140:143] offset:2048
	ds_write_b128 v112, v[144:147] offset:3072
	v_exp_f32_e32 v190, v190
	v_exp_f32_e32 v191, v191
	s_waitcnt lgkmcnt(4)
	v_mfma_f32_32x32x16_bf16 v[32:47], v[116:119], v[48:51], v[32:47]
	v_exp_f32_e32 v192, v192
	v_exp_f32_e32 v193, v193
	v_exp_f32_e32 v194, v194
	v_mfma_f32_32x32x16_bf16 v[32:47], v[120:123], v[52:55], v[32:47]
	v_exp_f32_e32 v195, v195
	v_exp_f32_e32 v196, v196
	v_exp_f32_e32 v197, v197
	v_mfma_f32_32x32x16_bf16 v[32:47], v[124:127], v[56:59], v[32:47]
	v_exp_f32_e32 v198, v198
	v_exp_f32_e32 v199, v199
	v_exp_f32_e32 v200, v200
	v_mfma_f32_32x32x16_bf16 v[32:47], v[128:131], v[60:63], v[32:47]
	v_exp_f32_e32 v201, v201
	v_exp_f32_e32 v202, v202
	v_exp_f32_e32 v203, v203
	s_add_i32 s90, s76, 416
	v_add_u32_e32 v84, s90, v107
	v_add_u32_e32 v85, 0, v84
	v_add_u32_e32 v86, 1, v84
	v_add_u32_e32 v87, 2, v84
	v_add_u32_e32 v88, 3, v84
	v_cmp_gt_u32_e64 s[30:31], s98, v85
	v_cmp_gt_u32_e64 s[36:37], s98, v86
	v_cmp_gt_u32_e64 s[78:79], s98, v87
	v_cmp_gt_u32_e64 s[50:51], s98, v88
	v_cndmask_b32_e64 v188, 0, v188, s[30:31]
	v_add_u32_e32 v85, 8, v84
	v_cmp_gt_u32_e64 s[30:31], s98, v85
	v_cndmask_b32_e64 v189, 0, v189, s[36:37]
	v_add_u32_e32 v86, 9, v84
	v_cmp_gt_u32_e64 s[36:37], s98, v86
	v_cndmask_b32_e64 v190, 0, v190, s[78:79]
	v_add_u32_e32 v87, 10, v84
	v_cmp_gt_u32_e64 s[78:79], s98, v87
	v_cndmask_b32_e64 v191, 0, v191, s[50:51]
	v_add_u32_e32 v88, 11, v84
	v_cmp_gt_u32_e64 s[50:51], s98, v88
	v_cndmask_b32_e64 v192, 0, v192, s[30:31]
	v_add_u32_e32 v85, 16, v84
	v_cmp_gt_u32_e64 s[30:31], s98, v85
	v_cndmask_b32_e64 v193, 0, v193, s[36:37]
	v_add_u32_e32 v86, 17, v84
	v_cmp_gt_u32_e64 s[36:37], s98, v86
	v_cndmask_b32_e64 v194, 0, v194, s[78:79]
	v_add_u32_e32 v87, 18, v84
	v_cmp_gt_u32_e64 s[78:79], s98, v87
	v_cndmask_b32_e64 v195, 0, v195, s[50:51]
	v_add_u32_e32 v88, 19, v84
	v_cmp_gt_u32_e64 s[50:51], s98, v88
	v_cndmask_b32_e64 v196, 0, v196, s[30:31]
	v_add_u32_e32 v85, 24, v84
	v_cmp_gt_u32_e64 s[30:31], s98, v85
	v_cndmask_b32_e64 v197, 0, v197, s[36:37]
	v_add_u32_e32 v86, 25, v84
	v_cmp_gt_u32_e64 s[36:37], s98, v86
	v_cndmask_b32_e64 v198, 0, v198, s[78:79]
	v_add_u32_e32 v87, 26, v84
	v_cmp_gt_u32_e64 s[78:79], s98, v87
	v_cndmask_b32_e64 v199, 0, v199, s[50:51]
	v_add_u32_e32 v88, 27, v84
	v_cmp_gt_u32_e64 s[50:51], s98, v88
	v_nop
	v_cndmask_b32_e64 v200, 0, v200, s[30:31]
	v_cndmask_b32_e64 v201, 0, v201, s[36:37]
	v_cndmask_b32_e64 v202, 0, v202, s[78:79]
	v_cndmask_b32_e64 v203, 0, v203, s[50:51]
	v_cvt_pk_bf16_f32 v64, v188, v189
	v_cvt_pk_bf16_f32 v65, v190, v191
	v_cvt_pk_bf16_f32 v66, v192, v193
	v_cvt_pk_bf16_f32 v67, v194, v195
	v_cvt_pk_bf16_f32 v68, v196, v197
	v_cvt_pk_bf16_f32 v69, v198, v199
	v_cvt_pk_bf16_f32 v70, v200, v201
	v_cvt_pk_bf16_f32 v71, v202, v203
	v_pk_add_f32 v[232:233], v[232:233], v[188:189]
	v_pk_add_f32 v[232:233], v[232:233], v[190:191]
	v_pk_add_f32 v[232:233], v[232:233], v[192:193]
	v_pk_add_f32 v[232:233], v[232:233], v[194:195]
	v_pk_add_f32 v[232:233], v[232:233], v[196:197]
	v_pk_add_f32 v[232:233], v[232:233], v[198:199]
	v_pk_add_f32 v[232:233], v[232:233], v[200:201]
	v_pk_add_f32 v[232:233], v[232:233], v[202:203]
	ds_read2_b32 v[188:189], v115 offset0:102 offset1:103
	ds_read2_b32 v[190:191], v115 offset0:104 offset1:105
	ds_read2_b32 v[192:193], v115 offset0:110 offset1:111
	ds_read2_b32 v[194:195], v115 offset0:112 offset1:113
	ds_read2_b32 v[196:197], v115 offset0:119 offset1:120
	ds_read2_b32 v[198:199], v115 offset0:121 offset1:122
	ds_read2_b32 v[200:201], v115 offset0:127 offset1:128
	ds_read2_b32 v[202:203], v115 offset0:129 offset1:130
	v_mfma_f32_32x32x16_bf16 v[0:15], v[64:67], v[72:75], v[0:15]
	v_mfma_f32_32x32x16_bf16 v[16:31], v[64:67], v[76:79], v[16:31]
	v_mfma_f32_32x32x16_bf16 v[0:15], v[68:71], v[220:223], v[0:15]
	v_mfma_f32_32x32x16_bf16 v[16:31], v[68:71], v[224:227], v[16:31]
	s_add_i32 s90, s76, 512
	v_add_u32_e32 v80, s90, v235
	v_add_u32_e32 v83, s90, v236
	v_add_u32_e32 v99, s90, v237
	v_add_u32_e32 v253, s90, v238
	v_add_u32_e32 v254, s90, v100
	v_add_u32_e32 v255, s90, v149
	v_med3_i32 v80, v80, 0, s99
	v_med3_i32 v83, v83, 0, s99
	v_med3_i32 v99, v99, 0, s99
	v_med3_i32 v253, v253, 0, s99
	v_med3_i32 v254, v254, 0, s99
	v_med3_i32 v255, v255, 0, s99
	v_mad_u32_u24 v80, v80, s100, v252
	v_mad_u32_u24 v83, v83, s100, v252
	v_mad_u32_u24 v99, v99, s100, v252
	v_mad_u32_u24 v253, v253, s100, v252
	v_mad_u32_u24 v254, v254, s100, v153
	v_mad_u32_u24 v255, v255, s100, v153
	global_load_dwordx4 v[116:119], v80, s[82:83]
	global_load_dwordx4 v[120:123], v83, s[82:83]
	global_load_dwordx4 v[124:127], v99, s[82:83]
	global_load_dwordx4 v[128:131], v253, s[82:83]
	global_load_dwordx4 v[132:135], v254, s[82:83] offset:768
	global_load_dwordx4 v[136:139], v255, s[82:83] offset:768
	global_load_dwordx4 v[140:143], v254, s[82:83] offset:832
	global_load_dwordx4 v[144:147], v255, s[82:83] offset:832
	ds_read_b64_tr_b16 v[72:73], v231
	ds_read_b64_tr_b16 v[74:75], v231 offset:512
	ds_read_b64_tr_b16 v[76:77], v231 offset:2048
	ds_read_b64_tr_b16 v[78:79], v231 offset:2560
	ds_read_b64_tr_b16 v[220:221], v231 offset:1024
	ds_read_b64_tr_b16 v[222:223], v231 offset:1536
	ds_read_b64_tr_b16 v[224:225], v231 offset:3072
	ds_read_b64_tr_b16 v[226:227], v231 offset:3584
	v_exp_f32_e32 v32, v32
	v_exp_f32_e32 v33, v33
	s_waitcnt vmcnt(8)
	ds_write_b128 v247, v[156:159]
	ds_write_b128 v247, v[160:163] offset:1024
	ds_write_b128 v247, v[164:167] offset:2048
	ds_write_b128 v247, v[168:171] offset:3072
	ds_read_b128 v[156:159], v248
	ds_read_b128 v[160:163], v249
	ds_read_b128 v[164:167], v250
	ds_read_b128 v[168:171], v251
	ds_write_b128 v112, v[172:175]
	ds_write_b128 v112, v[176:179] offset:1024
	ds_write_b128 v112, v[180:183] offset:2048
	ds_write_b128 v112, v[184:187] offset:3072
	v_exp_f32_e32 v34, v34
	v_exp_f32_e32 v35, v35
	s_waitcnt lgkmcnt(4)
	v_mfma_f32_32x32x16_bf16 v[188:203], v[156:159], v[48:51], v[188:203]
	v_exp_f32_e32 v36, v36
	v_exp_f32_e32 v37, v37
	v_exp_f32_e32 v38, v38
	v_mfma_f32_32x32x16_bf16 v[188:203], v[160:163], v[52:55], v[188:203]
	v_exp_f32_e32 v39, v39
	v_exp_f32_e32 v40, v40
	v_exp_f32_e32 v41, v41
	v_mfma_f32_32x32x16_bf16 v[188:203], v[164:167], v[56:59], v[188:203]
	v_exp_f32_e32 v42, v42
	v_exp_f32_e32 v43, v43
	v_exp_f32_e32 v44, v44
	v_mfma_f32_32x32x16_bf16 v[188:203], v[168:171], v[60:63], v[188:203]
	v_exp_f32_e32 v45, v45
	v_exp_f32_e32 v46, v46
	v_exp_f32_e32 v47, v47
	s_add_i32 s90, s76, 448
	v_add_u32_e32 v84, s90, v107
	v_add_u32_e32 v85, 0, v84
	v_add_u32_e32 v86, 1, v84
	v_add_u32_e32 v87, 2, v84
	v_add_u32_e32 v88, 3, v84
	v_cmp_gt_u32_e64 s[30:31], s98, v85
	v_cmp_gt_u32_e64 s[36:37], s98, v86
	v_cmp_gt_u32_e64 s[78:79], s98, v87
	v_cmp_gt_u32_e64 s[50:51], s98, v88
	v_cndmask_b32_e64 v32, 0, v32, s[30:31]
	v_add_u32_e32 v85, 8, v84
	v_cmp_gt_u32_e64 s[30:31], s98, v85
	v_cndmask_b32_e64 v33, 0, v33, s[36:37]
	v_add_u32_e32 v86, 9, v84
	v_cmp_gt_u32_e64 s[36:37], s98, v86
	v_cndmask_b32_e64 v34, 0, v34, s[78:79]
	v_add_u32_e32 v87, 10, v84
	v_cmp_gt_u32_e64 s[78:79], s98, v87
	v_cndmask_b32_e64 v35, 0, v35, s[50:51]
	v_add_u32_e32 v88, 11, v84
	v_cmp_gt_u32_e64 s[50:51], s98, v88
	v_cndmask_b32_e64 v36, 0, v36, s[30:31]
	v_add_u32_e32 v85, 16, v84
	v_cmp_gt_u32_e64 s[30:31], s98, v85
	v_cndmask_b32_e64 v37, 0, v37, s[36:37]
	v_add_u32_e32 v86, 17, v84
	v_cmp_gt_u32_e64 s[36:37], s98, v86
	v_cndmask_b32_e64 v38, 0, v38, s[78:79]
	v_add_u32_e32 v87, 18, v84
	v_cmp_gt_u32_e64 s[78:79], s98, v87
	v_cndmask_b32_e64 v39, 0, v39, s[50:51]
	v_add_u32_e32 v88, 19, v84
	v_cmp_gt_u32_e64 s[50:51], s98, v88
	v_cndmask_b32_e64 v40, 0, v40, s[30:31]
	v_add_u32_e32 v85, 24, v84
	v_cmp_gt_u32_e64 s[30:31], s98, v85
	v_cndmask_b32_e64 v41, 0, v41, s[36:37]
	v_add_u32_e32 v86, 25, v84
	v_cmp_gt_u32_e64 s[36:37], s98, v86
	v_cndmask_b32_e64 v42, 0, v42, s[78:79]
	v_add_u32_e32 v87, 26, v84
	v_cmp_gt_u32_e64 s[78:79], s98, v87
	v_cndmask_b32_e64 v43, 0, v43, s[50:51]
	v_add_u32_e32 v88, 27, v84
	v_cmp_gt_u32_e64 s[50:51], s98, v88
	v_nop
	v_cndmask_b32_e64 v44, 0, v44, s[30:31]
	v_cndmask_b32_e64 v45, 0, v45, s[36:37]
	v_cndmask_b32_e64 v46, 0, v46, s[78:79]
	v_cndmask_b32_e64 v47, 0, v47, s[50:51]
	v_cvt_pk_bf16_f32 v64, v32, v33
	v_cvt_pk_bf16_f32 v65, v34, v35
	v_cvt_pk_bf16_f32 v66, v36, v37
	v_cvt_pk_bf16_f32 v67, v38, v39
	v_cvt_pk_bf16_f32 v68, v40, v41
	v_cvt_pk_bf16_f32 v69, v42, v43
	v_cvt_pk_bf16_f32 v70, v44, v45
	v_cvt_pk_bf16_f32 v71, v46, v47
	v_pk_add_f32 v[232:233], v[232:233], v[32:33]
	v_pk_add_f32 v[232:233], v[232:233], v[34:35]
	v_pk_add_f32 v[232:233], v[232:233], v[36:37]
	v_pk_add_f32 v[232:233], v[232:233], v[38:39]
	v_pk_add_f32 v[232:233], v[232:233], v[40:41]
	v_pk_add_f32 v[232:233], v[232:233], v[42:43]
	v_pk_add_f32 v[232:233], v[232:233], v[44:45]
	v_pk_add_f32 v[232:233], v[232:233], v[46:47]
	ds_read2_b32 v[32:33], v115 offset0:136 offset1:137
	ds_read2_b32 v[34:35], v115 offset0:138 offset1:139
	ds_read2_b32 v[36:37], v115 offset0:144 offset1:145
	ds_read2_b32 v[38:39], v115 offset0:146 offset1:147
	ds_read2_b32 v[40:41], v115 offset0:153 offset1:154
	ds_read2_b32 v[42:43], v115 offset0:155 offset1:156
	ds_read2_b32 v[44:45], v115 offset0:161 offset1:162
	ds_read2_b32 v[46:47], v115 offset0:163 offset1:164
	v_mfma_f32_32x32x16_bf16 v[0:15], v[64:67], v[72:75], v[0:15]
	v_mfma_f32_32x32x16_bf16 v[16:31], v[64:67], v[76:79], v[16:31]
	v_mfma_f32_32x32x16_bf16 v[0:15], v[68:71], v[220:223], v[0:15]
	v_mfma_f32_32x32x16_bf16 v[16:31], v[68:71], v[224:227], v[16:31]
	s_add_i32 s90, s76, 544
	v_add_u32_e32 v80, s90, v235
	v_add_u32_e32 v83, s90, v236
	v_add_u32_e32 v99, s90, v237
	v_add_u32_e32 v253, s90, v238
	v_add_u32_e32 v254, s90, v100
	v_add_u32_e32 v255, s90, v149
	v_med3_i32 v80, v80, 0, s99
	v_med3_i32 v83, v83, 0, s99
	v_med3_i32 v99, v99, 0, s99
	v_med3_i32 v253, v253, 0, s99
	v_med3_i32 v254, v254, 0, s99
	v_med3_i32 v255, v255, 0, s99
	v_mad_u32_u24 v80, v80, s100, v252
	v_mad_u32_u24 v83, v83, s100, v252
	v_mad_u32_u24 v99, v99, s100, v252
	v_mad_u32_u24 v253, v253, s100, v252
	v_mad_u32_u24 v254, v254, s100, v153
	v_mad_u32_u24 v255, v255, s100, v153
	global_load_dwordx4 v[156:159], v80, s[82:83]
	global_load_dwordx4 v[160:163], v83, s[82:83]
	global_load_dwordx4 v[164:167], v99, s[82:83]
	global_load_dwordx4 v[168:171], v253, s[82:83]
	global_load_dwordx4 v[172:175], v254, s[82:83] offset:768
	global_load_dwordx4 v[176:179], v255, s[82:83] offset:768
	global_load_dwordx4 v[180:183], v254, s[82:83] offset:832
	global_load_dwordx4 v[184:187], v255, s[82:83] offset:832
	ds_read_b64_tr_b16 v[72:73], v231
	ds_read_b64_tr_b16 v[74:75], v231 offset:512
	ds_read_b64_tr_b16 v[76:77], v231 offset:2048
	ds_read_b64_tr_b16 v[78:79], v231 offset:2560
	ds_read_b64_tr_b16 v[220:221], v231 offset:1024
	ds_read_b64_tr_b16 v[222:223], v231 offset:1536
	ds_read_b64_tr_b16 v[224:225], v231 offset:3072
	ds_read_b64_tr_b16 v[226:227], v231 offset:3584
	v_exp_f32_e32 v188, v188
	v_exp_f32_e32 v189, v189
	s_waitcnt vmcnt(8)
	ds_write_b128 v247, v[116:119]
	ds_write_b128 v247, v[120:123] offset:1024
	ds_write_b128 v247, v[124:127] offset:2048
	ds_write_b128 v247, v[128:131] offset:3072
	ds_read_b128 v[116:119], v248
	ds_read_b128 v[120:123], v249
	ds_read_b128 v[124:127], v250
	ds_read_b128 v[128:131], v251
	ds_write_b128 v112, v[132:135]
	ds_write_b128 v112, v[136:139] offset:1024
	ds_write_b128 v112, v[140:143] offset:2048
	ds_write_b128 v112, v[144:147] offset:3072
	v_exp_f32_e32 v190, v190
	v_exp_f32_e32 v191, v191
	s_waitcnt lgkmcnt(4)
	v_mfma_f32_32x32x16_bf16 v[32:47], v[116:119], v[48:51], v[32:47]
	v_exp_f32_e32 v192, v192
	v_exp_f32_e32 v193, v193
	v_exp_f32_e32 v194, v194
	v_mfma_f32_32x32x16_bf16 v[32:47], v[120:123], v[52:55], v[32:47]
	v_exp_f32_e32 v195, v195
	v_exp_f32_e32 v196, v196
	v_exp_f32_e32 v197, v197
	v_mfma_f32_32x32x16_bf16 v[32:47], v[124:127], v[56:59], v[32:47]
	v_exp_f32_e32 v198, v198
	v_exp_f32_e32 v199, v199
	v_exp_f32_e32 v200, v200
	v_mfma_f32_32x32x16_bf16 v[32:47], v[128:131], v[60:63], v[32:47]
	v_exp_f32_e32 v201, v201
	v_exp_f32_e32 v202, v202
	v_exp_f32_e32 v203, v203
	s_add_i32 s90, s76, 480
	v_add_u32_e32 v84, s90, v107
	v_add_u32_e32 v85, 0, v84
	v_add_u32_e32 v86, 1, v84
	v_add_u32_e32 v87, 2, v84
	v_add_u32_e32 v88, 3, v84
	v_cmp_gt_u32_e64 s[30:31], s98, v85
	v_cmp_gt_u32_e64 s[36:37], s98, v86
	v_cmp_gt_u32_e64 s[78:79], s98, v87
	v_cmp_gt_u32_e64 s[50:51], s98, v88
	v_cndmask_b32_e64 v188, 0, v188, s[30:31]
	v_add_u32_e32 v85, 8, v84
	v_cmp_gt_u32_e64 s[30:31], s98, v85
	v_cndmask_b32_e64 v189, 0, v189, s[36:37]
	v_add_u32_e32 v86, 9, v84
	v_cmp_gt_u32_e64 s[36:37], s98, v86
	v_cndmask_b32_e64 v190, 0, v190, s[78:79]
	v_add_u32_e32 v87, 10, v84
	v_cmp_gt_u32_e64 s[78:79], s98, v87
	v_cndmask_b32_e64 v191, 0, v191, s[50:51]
	v_add_u32_e32 v88, 11, v84
	v_cmp_gt_u32_e64 s[50:51], s98, v88
	v_cndmask_b32_e64 v192, 0, v192, s[30:31]
	v_add_u32_e32 v85, 16, v84
	v_cmp_gt_u32_e64 s[30:31], s98, v85
	v_cndmask_b32_e64 v193, 0, v193, s[36:37]
	v_add_u32_e32 v86, 17, v84
	v_cmp_gt_u32_e64 s[36:37], s98, v86
	v_cndmask_b32_e64 v194, 0, v194, s[78:79]
	v_add_u32_e32 v87, 18, v84
	v_cmp_gt_u32_e64 s[78:79], s98, v87
	v_cndmask_b32_e64 v195, 0, v195, s[50:51]
	v_add_u32_e32 v88, 19, v84
	v_cmp_gt_u32_e64 s[50:51], s98, v88
	v_cndmask_b32_e64 v196, 0, v196, s[30:31]
	v_add_u32_e32 v85, 24, v84
	v_cmp_gt_u32_e64 s[30:31], s98, v85
	v_cndmask_b32_e64 v197, 0, v197, s[36:37]
	v_add_u32_e32 v86, 25, v84
	v_cmp_gt_u32_e64 s[36:37], s98, v86
	v_cndmask_b32_e64 v198, 0, v198, s[78:79]
	v_add_u32_e32 v87, 26, v84
	v_cmp_gt_u32_e64 s[78:79], s98, v87
	v_cndmask_b32_e64 v199, 0, v199, s[50:51]
	v_add_u32_e32 v88, 27, v84
	v_cmp_gt_u32_e64 s[50:51], s98, v88
	v_nop
	v_cndmask_b32_e64 v200, 0, v200, s[30:31]
	v_cndmask_b32_e64 v201, 0, v201, s[36:37]
	v_cndmask_b32_e64 v202, 0, v202, s[78:79]
	v_cndmask_b32_e64 v203, 0, v203, s[50:51]
	v_cvt_pk_bf16_f32 v64, v188, v189
	v_cvt_pk_bf16_f32 v65, v190, v191
	v_cvt_pk_bf16_f32 v66, v192, v193
	v_cvt_pk_bf16_f32 v67, v194, v195
	v_cvt_pk_bf16_f32 v68, v196, v197
	v_cvt_pk_bf16_f32 v69, v198, v199
	v_cvt_pk_bf16_f32 v70, v200, v201
	v_cvt_pk_bf16_f32 v71, v202, v203
	v_pk_add_f32 v[232:233], v[232:233], v[188:189]
	v_pk_add_f32 v[232:233], v[232:233], v[190:191]
	v_pk_add_f32 v[232:233], v[232:233], v[192:193]
	v_pk_add_f32 v[232:233], v[232:233], v[194:195]
	v_pk_add_f32 v[232:233], v[232:233], v[196:197]
	v_pk_add_f32 v[232:233], v[232:233], v[198:199]
	v_pk_add_f32 v[232:233], v[232:233], v[200:201]
	v_pk_add_f32 v[232:233], v[232:233], v[202:203]
	ds_read2_b32 v[188:189], v115 offset0:170 offset1:171
	ds_read2_b32 v[190:191], v115 offset0:172 offset1:173
	ds_read2_b32 v[192:193], v115 offset0:178 offset1:179
	ds_read2_b32 v[194:195], v115 offset0:180 offset1:181
	ds_read2_b32 v[196:197], v115 offset0:187 offset1:188
	ds_read2_b32 v[198:199], v115 offset0:189 offset1:190
	ds_read2_b32 v[200:201], v115 offset0:195 offset1:196
	ds_read2_b32 v[202:203], v115 offset0:197 offset1:198
	v_mfma_f32_32x32x16_bf16 v[0:15], v[64:67], v[72:75], v[0:15]
	v_mfma_f32_32x32x16_bf16 v[16:31], v[64:67], v[76:79], v[16:31]
	v_mfma_f32_32x32x16_bf16 v[0:15], v[68:71], v[220:223], v[0:15]
	v_mfma_f32_32x32x16_bf16 v[16:31], v[68:71], v[224:227], v[16:31]
	s_add_i32 s90, s76, -256
	v_add_u32_e32 v80, s90, v239
	v_add_u32_e32 v83, s90, v240
	v_add_u32_e32 v99, s90, v241
	v_add_u32_e32 v253, s90, v242
	v_add_u32_e32 v254, s90, v101
	v_add_u32_e32 v255, s90, v150
	v_med3_i32 v80, v80, 0, s99
	v_med3_i32 v83, v83, 0, s99
	v_med3_i32 v99, v99, 0, s99
	v_med3_i32 v253, v253, 0, s99
	v_med3_i32 v254, v254, 0, s99
	v_med3_i32 v255, v255, 0, s99
	v_mad_u32_u24 v80, v80, s100, v252
	v_mad_u32_u24 v83, v83, s100, v252
	v_mad_u32_u24 v99, v99, s100, v252
	v_mad_u32_u24 v253, v253, s100, v252
	v_mad_u32_u24 v254, v254, s100, v153
	v_mad_u32_u24 v255, v255, s100, v153
	global_load_dwordx4 v[116:119], v80, s[82:83]
	global_load_dwordx4 v[120:123], v83, s[82:83]
	global_load_dwordx4 v[124:127], v99, s[82:83]
	global_load_dwordx4 v[128:131], v253, s[82:83]
	global_load_dwordx4 v[132:135], v254, s[82:83] offset:768
	global_load_dwordx4 v[136:139], v255, s[82:83] offset:768
	global_load_dwordx4 v[140:143], v254, s[82:83] offset:832
	global_load_dwordx4 v[144:147], v255, s[82:83] offset:832
	ds_read_b64_tr_b16 v[72:73], v231
	ds_read_b64_tr_b16 v[74:75], v231 offset:512
	ds_read_b64_tr_b16 v[76:77], v231 offset:2048
	ds_read_b64_tr_b16 v[78:79], v231 offset:2560
	ds_read_b64_tr_b16 v[220:221], v231 offset:1024
	ds_read_b64_tr_b16 v[222:223], v231 offset:1536
	ds_read_b64_tr_b16 v[224:225], v231 offset:3072
	ds_read_b64_tr_b16 v[226:227], v231 offset:3584
	v_exp_f32_e32 v32, v32
	v_exp_f32_e32 v33, v33
	s_waitcnt vmcnt(8)
	ds_write_b128 v247, v[156:159]
	ds_write_b128 v247, v[160:163] offset:1024
	ds_write_b128 v247, v[164:167] offset:2048
	ds_write_b128 v247, v[168:171] offset:3072
	ds_read_b128 v[156:159], v248
	ds_read_b128 v[160:163], v249
	ds_read_b128 v[164:167], v250
	ds_read_b128 v[168:171], v251
	ds_write_b128 v112, v[172:175]
	ds_write_b128 v112, v[176:179] offset:1024
	ds_write_b128 v112, v[180:183] offset:2048
	ds_write_b128 v112, v[184:187] offset:3072
	v_exp_f32_e32 v34, v34
	v_exp_f32_e32 v35, v35
	s_waitcnt lgkmcnt(4)
	v_mfma_f32_32x32x16_bf16 v[188:203], v[156:159], v[48:51], v[188:203]
	v_exp_f32_e32 v36, v36
	v_exp_f32_e32 v37, v37
	v_exp_f32_e32 v38, v38
	v_mfma_f32_32x32x16_bf16 v[188:203], v[160:163], v[52:55], v[188:203]
	v_exp_f32_e32 v39, v39
	v_exp_f32_e32 v40, v40
	v_exp_f32_e32 v41, v41
	v_mfma_f32_32x32x16_bf16 v[188:203], v[164:167], v[56:59], v[188:203]
	v_exp_f32_e32 v42, v42
	v_exp_f32_e32 v43, v43
	v_exp_f32_e32 v44, v44
	v_mfma_f32_32x32x16_bf16 v[188:203], v[168:171], v[60:63], v[188:203]
	v_exp_f32_e32 v45, v45
	v_exp_f32_e32 v46, v46
	v_exp_f32_e32 v47, v47
	s_add_i32 s90, s76, 512
	v_add_u32_e32 v84, s90, v107
	v_add_u32_e32 v85, 0, v84
	v_add_u32_e32 v86, 1, v84
	v_add_u32_e32 v87, 2, v84
	v_add_u32_e32 v88, 3, v84
	v_cmp_gt_u32_e64 s[30:31], s98, v85
	v_cmp_gt_u32_e64 s[36:37], s98, v86
	v_cmp_gt_u32_e64 s[78:79], s98, v87
	v_cmp_gt_u32_e64 s[50:51], s98, v88
	v_cndmask_b32_e64 v32, 0, v32, s[30:31]
	v_add_u32_e32 v85, 8, v84
	v_cmp_gt_u32_e64 s[30:31], s98, v85
	v_cndmask_b32_e64 v33, 0, v33, s[36:37]
	v_add_u32_e32 v86, 9, v84
	v_cmp_gt_u32_e64 s[36:37], s98, v86
	v_cndmask_b32_e64 v34, 0, v34, s[78:79]
	v_add_u32_e32 v87, 10, v84
	v_cmp_gt_u32_e64 s[78:79], s98, v87
	v_cndmask_b32_e64 v35, 0, v35, s[50:51]
	v_add_u32_e32 v88, 11, v84
	v_cmp_gt_u32_e64 s[50:51], s98, v88
	v_cndmask_b32_e64 v36, 0, v36, s[30:31]
	v_add_u32_e32 v85, 16, v84
	v_cmp_gt_u32_e64 s[30:31], s98, v85
	v_cndmask_b32_e64 v37, 0, v37, s[36:37]
	v_add_u32_e32 v86, 17, v84
	v_cmp_gt_u32_e64 s[36:37], s98, v86
	v_cndmask_b32_e64 v38, 0, v38, s[78:79]
	v_add_u32_e32 v87, 18, v84
	v_cmp_gt_u32_e64 s[78:79], s98, v87
	v_cndmask_b32_e64 v39, 0, v39, s[50:51]
	v_add_u32_e32 v88, 19, v84
	v_cmp_gt_u32_e64 s[50:51], s98, v88
	v_cndmask_b32_e64 v40, 0, v40, s[30:31]
	v_add_u32_e32 v85, 24, v84
	v_cmp_gt_u32_e64 s[30:31], s98, v85
	v_cndmask_b32_e64 v41, 0, v41, s[36:37]
	v_add_u32_e32 v86, 25, v84
	v_cmp_gt_u32_e64 s[36:37], s98, v86
	v_cndmask_b32_e64 v42, 0, v42, s[78:79]
	v_add_u32_e32 v87, 26, v84
	v_cmp_gt_u32_e64 s[78:79], s98, v87
	v_cndmask_b32_e64 v43, 0, v43, s[50:51]
	v_add_u32_e32 v88, 27, v84
	v_cmp_gt_u32_e64 s[50:51], s98, v88
	v_nop
	v_cndmask_b32_e64 v44, 0, v44, s[30:31]
	v_cndmask_b32_e64 v45, 0, v45, s[36:37]
	v_cndmask_b32_e64 v46, 0, v46, s[78:79]
	v_cndmask_b32_e64 v47, 0, v47, s[50:51]
	v_cvt_pk_bf16_f32 v64, v32, v33
	v_cvt_pk_bf16_f32 v65, v34, v35
	v_cvt_pk_bf16_f32 v66, v36, v37
	v_cvt_pk_bf16_f32 v67, v38, v39
	v_cvt_pk_bf16_f32 v68, v40, v41
	v_cvt_pk_bf16_f32 v69, v42, v43
	v_cvt_pk_bf16_f32 v70, v44, v45
	v_cvt_pk_bf16_f32 v71, v46, v47
	v_pk_add_f32 v[232:233], v[232:233], v[32:33]
	v_pk_add_f32 v[232:233], v[232:233], v[34:35]
	v_pk_add_f32 v[232:233], v[232:233], v[36:37]
	v_pk_add_f32 v[232:233], v[232:233], v[38:39]
	v_pk_add_f32 v[232:233], v[232:233], v[40:41]
	v_pk_add_f32 v[232:233], v[232:233], v[42:43]
	v_pk_add_f32 v[232:233], v[232:233], v[44:45]
	v_pk_add_f32 v[232:233], v[232:233], v[46:47]
	v_mov_b32_e32 v115, v229
	ds_read2_b32 v[32:33], v115 offset0:0 offset1:1
	ds_read2_b32 v[34:35], v115 offset0:2 offset1:3
	ds_read2_b32 v[36:37], v115 offset0:8 offset1:9
	ds_read2_b32 v[38:39], v115 offset0:10 offset1:11
	ds_read2_b32 v[40:41], v115 offset0:16 offset1:17
	ds_read2_b32 v[42:43], v115 offset0:18 offset1:19
	ds_read2_b32 v[44:45], v115 offset0:24 offset1:25
	ds_read2_b32 v[46:47], v115 offset0:26 offset1:27
	v_mfma_f32_32x32x16_bf16 v[0:15], v[64:67], v[72:75], v[0:15]
	v_mfma_f32_32x32x16_bf16 v[16:31], v[64:67], v[76:79], v[16:31]
	v_mfma_f32_32x32x16_bf16 v[0:15], v[68:71], v[220:223], v[0:15]
	v_mfma_f32_32x32x16_bf16 v[16:31], v[68:71], v[224:227], v[16:31]
	s_add_i32 s90, s76, -128
	v_add_u32_e32 v80, s90, v239
	v_add_u32_e32 v83, s90, v240
	v_add_u32_e32 v99, s90, v241
	v_add_u32_e32 v253, s90, v242
	v_add_u32_e32 v254, s90, v101
	v_add_u32_e32 v255, s90, v150
	v_med3_i32 v80, v80, 0, s99
	v_med3_i32 v83, v83, 0, s99
	v_med3_i32 v99, v99, 0, s99
	v_med3_i32 v253, v253, 0, s99
	v_med3_i32 v254, v254, 0, s99
	v_med3_i32 v255, v255, 0, s99
	v_mad_u32_u24 v80, v80, s100, v252
	v_mad_u32_u24 v83, v83, s100, v252
	v_mad_u32_u24 v99, v99, s100, v252
	v_mad_u32_u24 v253, v253, s100, v252
	v_mad_u32_u24 v254, v254, s100, v153
	v_mad_u32_u24 v255, v255, s100, v153
	global_load_dwordx4 v[156:159], v80, s[82:83]
	global_load_dwordx4 v[160:163], v83, s[82:83]
	global_load_dwordx4 v[164:167], v99, s[82:83]
	global_load_dwordx4 v[168:171], v253, s[82:83]
	global_load_dwordx4 v[172:175], v254, s[82:83] offset:768
	global_load_dwordx4 v[176:179], v255, s[82:83] offset:768
	global_load_dwordx4 v[180:183], v254, s[82:83] offset:832
	global_load_dwordx4 v[184:187], v255, s[82:83] offset:832
	ds_read_b64_tr_b16 v[72:73], v231
	ds_read_b64_tr_b16 v[74:75], v231 offset:512
	ds_read_b64_tr_b16 v[76:77], v231 offset:2048
	ds_read_b64_tr_b16 v[78:79], v231 offset:2560
	ds_read_b64_tr_b16 v[220:221], v231 offset:1024
	ds_read_b64_tr_b16 v[222:223], v231 offset:1536
	ds_read_b64_tr_b16 v[224:225], v231 offset:3072
	ds_read_b64_tr_b16 v[226:227], v231 offset:3584
	v_exp_f32_e32 v188, v188
	v_exp_f32_e32 v189, v189
	s_waitcnt vmcnt(8)
	ds_write_b128 v247, v[116:119]
	ds_write_b128 v247, v[120:123] offset:1024
	ds_write_b128 v247, v[124:127] offset:2048
	ds_write_b128 v247, v[128:131] offset:3072
	ds_read_b128 v[116:119], v248
	ds_read_b128 v[120:123], v249
	ds_read_b128 v[124:127], v250
	ds_read_b128 v[128:131], v251
	ds_write_b128 v112, v[132:135]
	ds_write_b128 v112, v[136:139] offset:1024
	ds_write_b128 v112, v[140:143] offset:2048
	ds_write_b128 v112, v[144:147] offset:3072
	v_exp_f32_e32 v190, v190
	v_exp_f32_e32 v191, v191
	s_waitcnt lgkmcnt(4)
	v_mfma_f32_32x32x16_bf16 v[32:47], v[116:119], v[48:51], v[32:47]
	v_exp_f32_e32 v192, v192
	v_exp_f32_e32 v193, v193
	v_exp_f32_e32 v194, v194
	v_mfma_f32_32x32x16_bf16 v[32:47], v[120:123], v[52:55], v[32:47]
	v_exp_f32_e32 v195, v195
	v_exp_f32_e32 v196, v196
	v_exp_f32_e32 v197, v197
	v_mfma_f32_32x32x16_bf16 v[32:47], v[124:127], v[56:59], v[32:47]
	v_exp_f32_e32 v198, v198
	v_exp_f32_e32 v199, v199
	v_exp_f32_e32 v200, v200
	v_mfma_f32_32x32x16_bf16 v[32:47], v[128:131], v[60:63], v[32:47]
	v_exp_f32_e32 v201, v201
	v_exp_f32_e32 v202, v202
	v_exp_f32_e32 v203, v203
	s_add_i32 s90, s76, 544
	v_add_u32_e32 v84, s90, v107
	v_add_u32_e32 v85, 0, v84
	v_add_u32_e32 v86, 1, v84
	v_add_u32_e32 v87, 2, v84
	v_add_u32_e32 v88, 3, v84
	v_cmp_gt_u32_e64 s[30:31], s98, v85
	v_cmp_gt_u32_e64 s[36:37], s98, v86
	v_cmp_gt_u32_e64 s[78:79], s98, v87
	v_cmp_gt_u32_e64 s[50:51], s98, v88
	v_cndmask_b32_e64 v188, 0, v188, s[30:31]
	v_add_u32_e32 v85, 8, v84
	v_cmp_gt_u32_e64 s[30:31], s98, v85
	v_cndmask_b32_e64 v189, 0, v189, s[36:37]
	v_add_u32_e32 v86, 9, v84
	v_cmp_gt_u32_e64 s[36:37], s98, v86
	v_cndmask_b32_e64 v190, 0, v190, s[78:79]
	v_add_u32_e32 v87, 10, v84
	v_cmp_gt_u32_e64 s[78:79], s98, v87
	v_cndmask_b32_e64 v191, 0, v191, s[50:51]
	v_add_u32_e32 v88, 11, v84
	v_cmp_gt_u32_e64 s[50:51], s98, v88
	v_cndmask_b32_e64 v192, 0, v192, s[30:31]
	v_add_u32_e32 v85, 16, v84
	v_cmp_gt_u32_e64 s[30:31], s98, v85
	v_cndmask_b32_e64 v193, 0, v193, s[36:37]
	v_add_u32_e32 v86, 17, v84
	v_cmp_gt_u32_e64 s[36:37], s98, v86
	v_cndmask_b32_e64 v194, 0, v194, s[78:79]
	v_add_u32_e32 v87, 18, v84
	v_cmp_gt_u32_e64 s[78:79], s98, v87
	v_cndmask_b32_e64 v195, 0, v195, s[50:51]
	v_add_u32_e32 v88, 19, v84
	v_cmp_gt_u32_e64 s[50:51], s98, v88
	v_cndmask_b32_e64 v196, 0, v196, s[30:31]
	v_add_u32_e32 v85, 24, v84
	v_cmp_gt_u32_e64 s[30:31], s98, v85
	v_cndmask_b32_e64 v197, 0, v197, s[36:37]
	v_add_u32_e32 v86, 25, v84
	v_cmp_gt_u32_e64 s[36:37], s98, v86
	v_cndmask_b32_e64 v198, 0, v198, s[78:79]
	v_add_u32_e32 v87, 26, v84
	v_cmp_gt_u32_e64 s[78:79], s98, v87
	v_cndmask_b32_e64 v199, 0, v199, s[50:51]
	v_add_u32_e32 v88, 27, v84
	v_cmp_gt_u32_e64 s[50:51], s98, v88
	v_nop
	v_cndmask_b32_e64 v200, 0, v200, s[30:31]
	v_cndmask_b32_e64 v201, 0, v201, s[36:37]
	v_cndmask_b32_e64 v202, 0, v202, s[78:79]
	v_cndmask_b32_e64 v203, 0, v203, s[50:51]
	v_cvt_pk_bf16_f32 v64, v188, v189
	v_cvt_pk_bf16_f32 v65, v190, v191
	v_cvt_pk_bf16_f32 v66, v192, v193
	v_cvt_pk_bf16_f32 v67, v194, v195
	v_cvt_pk_bf16_f32 v68, v196, v197
	v_cvt_pk_bf16_f32 v69, v198, v199
	v_cvt_pk_bf16_f32 v70, v200, v201
	v_cvt_pk_bf16_f32 v71, v202, v203
	v_pk_add_f32 v[232:233], v[232:233], v[188:189]
	v_pk_add_f32 v[232:233], v[232:233], v[190:191]
	v_pk_add_f32 v[232:233], v[232:233], v[192:193]
	v_pk_add_f32 v[232:233], v[232:233], v[194:195]
	v_pk_add_f32 v[232:233], v[232:233], v[196:197]
	v_pk_add_f32 v[232:233], v[232:233], v[198:199]
	v_pk_add_f32 v[232:233], v[232:233], v[200:201]
	v_pk_add_f32 v[232:233], v[232:233], v[202:203]
	ds_read2_b32 v[188:189], v115 offset0:32 offset1:33
	ds_read2_b32 v[190:191], v115 offset0:34 offset1:35
	ds_read2_b32 v[192:193], v115 offset0:40 offset1:41
	ds_read2_b32 v[194:195], v115 offset0:42 offset1:43
	ds_read2_b32 v[196:197], v115 offset0:48 offset1:49
	ds_read2_b32 v[198:199], v115 offset0:50 offset1:51
	ds_read2_b32 v[200:201], v115 offset0:56 offset1:57
	ds_read2_b32 v[202:203], v115 offset0:58 offset1:59
	v_mfma_f32_32x32x16_bf16 v[0:15], v[64:67], v[72:75], v[0:15]
	v_mfma_f32_32x32x16_bf16 v[16:31], v[64:67], v[76:79], v[16:31]
	v_mfma_f32_32x32x16_bf16 v[0:15], v[68:71], v[220:223], v[0:15]
	v_mfma_f32_32x32x16_bf16 v[16:31], v[68:71], v[224:227], v[16:31]
	s_add_i32 s90, s76, 0
	v_add_u32_e32 v80, s90, v239
	v_add_u32_e32 v83, s90, v240
	v_add_u32_e32 v99, s90, v241
	v_add_u32_e32 v253, s90, v242
	v_add_u32_e32 v254, s90, v101
	v_add_u32_e32 v255, s90, v150
	v_med3_i32 v80, v80, 0, s99
	v_med3_i32 v83, v83, 0, s99
	v_med3_i32 v99, v99, 0, s99
	v_med3_i32 v253, v253, 0, s99
	v_med3_i32 v254, v254, 0, s99
	v_med3_i32 v255, v255, 0, s99
	v_mad_u32_u24 v80, v80, s100, v252
	v_mad_u32_u24 v83, v83, s100, v252
	v_mad_u32_u24 v99, v99, s100, v252
	v_mad_u32_u24 v253, v253, s100, v252
	v_mad_u32_u24 v254, v254, s100, v153
	v_mad_u32_u24 v255, v255, s100, v153
	global_load_dwordx4 v[116:119], v80, s[82:83]
	global_load_dwordx4 v[120:123], v83, s[82:83]
	global_load_dwordx4 v[124:127], v99, s[82:83]
	global_load_dwordx4 v[128:131], v253, s[82:83]
	global_load_dwordx4 v[132:135], v254, s[82:83] offset:768
	global_load_dwordx4 v[136:139], v255, s[82:83] offset:768
	global_load_dwordx4 v[140:143], v254, s[82:83] offset:832
	global_load_dwordx4 v[144:147], v255, s[82:83] offset:832
	ds_read_b64_tr_b16 v[72:73], v231
	ds_read_b64_tr_b16 v[74:75], v231 offset:512
	ds_read_b64_tr_b16 v[76:77], v231 offset:2048
	ds_read_b64_tr_b16 v[78:79], v231 offset:2560
	ds_read_b64_tr_b16 v[220:221], v231 offset:1024
	ds_read_b64_tr_b16 v[222:223], v231 offset:1536
	ds_read_b64_tr_b16 v[224:225], v231 offset:3072
	ds_read_b64_tr_b16 v[226:227], v231 offset:3584
	v_exp_f32_e32 v32, v32
	v_exp_f32_e32 v33, v33
	s_waitcnt vmcnt(8)
	ds_write_b128 v247, v[156:159]
	ds_write_b128 v247, v[160:163] offset:1024
	ds_write_b128 v247, v[164:167] offset:2048
	ds_write_b128 v247, v[168:171] offset:3072
	ds_read_b128 v[156:159], v248
	ds_read_b128 v[160:163], v249
	ds_read_b128 v[164:167], v250
	ds_read_b128 v[168:171], v251
	ds_write_b128 v112, v[172:175]
	ds_write_b128 v112, v[176:179] offset:1024
	ds_write_b128 v112, v[180:183] offset:2048
	ds_write_b128 v112, v[184:187] offset:3072
	v_exp_f32_e32 v34, v34
	v_exp_f32_e32 v35, v35
	s_waitcnt lgkmcnt(4)
	v_mfma_f32_32x32x16_bf16 v[188:203], v[156:159], v[48:51], v[188:203]
	v_exp_f32_e32 v36, v36
	v_exp_f32_e32 v37, v37
	v_exp_f32_e32 v38, v38
	v_mfma_f32_32x32x16_bf16 v[188:203], v[160:163], v[52:55], v[188:203]
	v_exp_f32_e32 v39, v39
	v_exp_f32_e32 v40, v40
	v_exp_f32_e32 v41, v41
	v_mfma_f32_32x32x16_bf16 v[188:203], v[164:167], v[56:59], v[188:203]
	v_exp_f32_e32 v42, v42
	v_exp_f32_e32 v43, v43
	v_exp_f32_e32 v44, v44
	v_mfma_f32_32x32x16_bf16 v[188:203], v[168:171], v[60:63], v[188:203]
	v_exp_f32_e32 v45, v45
	v_exp_f32_e32 v46, v46
	v_exp_f32_e32 v47, v47
	s_add_i32 s90, s76, -256
	v_lshlrev_b32_e32 v84, 2, v107
	v_add_u32_e32 v84, s90, v84
	v_add_u32_e32 v85, 0, v84
	v_add_u32_e32 v86, 4, v84
	v_add_u32_e32 v87, 8, v84
	v_add_u32_e32 v88, 12, v84
	v_cmp_gt_u32_e64 s[30:31], s98, v85
	v_cmp_gt_u32_e64 s[36:37], s98, v86
	v_cmp_gt_u32_e64 s[78:79], s98, v87
	v_cmp_gt_u32_e64 s[50:51], s98, v88
	v_cndmask_b32_e64 v32, 0, v32, s[30:31]
	v_add_u32_e32 v85, 32, v84
	v_cmp_gt_u32_e64 s[30:31], s98, v85
	v_cndmask_b32_e64 v33, 0, v33, s[36:37]
	v_add_u32_e32 v86, 36, v84
	v_cmp_gt_u32_e64 s[36:37], s98, v86
	v_cndmask_b32_e64 v34, 0, v34, s[78:79]
	v_add_u32_e32 v87, 40, v84
	v_cmp_gt_u32_e64 s[78:79], s98, v87
	v_cndmask_b32_e64 v35, 0, v35, s[50:51]
	v_add_u32_e32 v88, 44, v84
	v_cmp_gt_u32_e64 s[50:51], s98, v88
	v_cndmask_b32_e64 v36, 0, v36, s[30:31]
	v_add_u32_e32 v85, 64, v84
	v_cmp_gt_u32_e64 s[30:31], s98, v85
	v_cndmask_b32_e64 v37, 0, v37, s[36:37]
	v_add_u32_e32 v86, 68, v84
	v_cmp_gt_u32_e64 s[36:37], s98, v86
	v_cndmask_b32_e64 v38, 0, v38, s[78:79]
	v_add_u32_e32 v87, 72, v84
	v_cmp_gt_u32_e64 s[78:79], s98, v87
	v_cndmask_b32_e64 v39, 0, v39, s[50:51]
	v_add_u32_e32 v88, 76, v84
	v_cmp_gt_u32_e64 s[50:51], s98, v88
	v_cndmask_b32_e64 v40, 0, v40, s[30:31]
	v_add_u32_e32 v85, 96, v84
	v_cmp_gt_u32_e64 s[30:31], s98, v85
	v_cndmask_b32_e64 v41, 0, v41, s[36:37]
	v_add_u32_e32 v86, 100, v84
	v_cmp_gt_u32_e64 s[36:37], s98, v86
	v_cndmask_b32_e64 v42, 0, v42, s[78:79]
	v_add_u32_e32 v87, 104, v84
	v_cmp_gt_u32_e64 s[78:79], s98, v87
	v_cndmask_b32_e64 v43, 0, v43, s[50:51]
	v_add_u32_e32 v88, 108, v84
	v_cmp_gt_u32_e64 s[50:51], s98, v88
	v_nop
	v_cndmask_b32_e64 v44, 0, v44, s[30:31]
	v_cndmask_b32_e64 v45, 0, v45, s[36:37]
	v_cndmask_b32_e64 v46, 0, v46, s[78:79]
	v_cndmask_b32_e64 v47, 0, v47, s[50:51]
	v_cvt_pk_bf16_f32 v64, v32, v33
	v_cvt_pk_bf16_f32 v65, v34, v35
	v_cvt_pk_bf16_f32 v66, v36, v37
	v_cvt_pk_bf16_f32 v67, v38, v39
	v_cvt_pk_bf16_f32 v68, v40, v41
	v_cvt_pk_bf16_f32 v69, v42, v43
	v_cvt_pk_bf16_f32 v70, v44, v45
	v_cvt_pk_bf16_f32 v71, v46, v47
	v_pk_add_f32 v[232:233], v[232:233], v[32:33]
	v_pk_add_f32 v[232:233], v[232:233], v[34:35]
	v_pk_add_f32 v[232:233], v[232:233], v[36:37]
	v_pk_add_f32 v[232:233], v[232:233], v[38:39]
	v_pk_add_f32 v[232:233], v[232:233], v[40:41]
	v_pk_add_f32 v[232:233], v[232:233], v[42:43]
	v_pk_add_f32 v[232:233], v[232:233], v[44:45]
	v_pk_add_f32 v[232:233], v[232:233], v[46:47]
	ds_read2_b32 v[32:33], v115 offset0:64 offset1:65
	ds_read2_b32 v[34:35], v115 offset0:66 offset1:67
	ds_read2_b32 v[36:37], v115 offset0:72 offset1:73
	ds_read2_b32 v[38:39], v115 offset0:74 offset1:75
	ds_read2_b32 v[40:41], v115 offset0:80 offset1:81
	ds_read2_b32 v[42:43], v115 offset0:82 offset1:83
	ds_read2_b32 v[44:45], v115 offset0:88 offset1:89
	ds_read2_b32 v[46:47], v115 offset0:90 offset1:91
	v_mfma_f32_32x32x16_bf16 v[0:15], v[64:67], v[72:75], v[0:15]
	v_mfma_f32_32x32x16_bf16 v[16:31], v[64:67], v[76:79], v[16:31]
	v_mfma_f32_32x32x16_bf16 v[0:15], v[68:71], v[220:223], v[0:15]
	v_mfma_f32_32x32x16_bf16 v[16:31], v[68:71], v[224:227], v[16:31]
	s_add_i32 s90, s76, 128
	v_add_u32_e32 v80, s90, v239
	v_add_u32_e32 v83, s90, v240
	v_add_u32_e32 v99, s90, v241
	v_add_u32_e32 v253, s90, v242
	v_add_u32_e32 v254, s90, v101
	v_add_u32_e32 v255, s90, v150
	v_med3_i32 v80, v80, 0, s99
	v_med3_i32 v83, v83, 0, s99
	v_med3_i32 v99, v99, 0, s99
	v_med3_i32 v253, v253, 0, s99
	v_med3_i32 v254, v254, 0, s99
	v_med3_i32 v255, v255, 0, s99
	v_mad_u32_u24 v80, v80, s100, v252
	v_mad_u32_u24 v83, v83, s100, v252
	v_mad_u32_u24 v99, v99, s100, v252
	v_mad_u32_u24 v253, v253, s100, v252
	v_mad_u32_u24 v254, v254, s100, v153
	v_mad_u32_u24 v255, v255, s100, v153
	global_load_dwordx4 v[156:159], v80, s[82:83]
	global_load_dwordx4 v[160:163], v83, s[82:83]
	global_load_dwordx4 v[164:167], v99, s[82:83]
	global_load_dwordx4 v[168:171], v253, s[82:83]
	global_load_dwordx4 v[172:175], v254, s[82:83] offset:768
	global_load_dwordx4 v[176:179], v255, s[82:83] offset:768
	global_load_dwordx4 v[180:183], v254, s[82:83] offset:832
	global_load_dwordx4 v[184:187], v255, s[82:83] offset:832
	ds_read_b64_tr_b16 v[72:73], v231
	ds_read_b64_tr_b16 v[74:75], v231 offset:512
	ds_read_b64_tr_b16 v[76:77], v231 offset:2048
	ds_read_b64_tr_b16 v[78:79], v231 offset:2560
	ds_read_b64_tr_b16 v[220:221], v231 offset:1024
	ds_read_b64_tr_b16 v[222:223], v231 offset:1536
	ds_read_b64_tr_b16 v[224:225], v231 offset:3072
	ds_read_b64_tr_b16 v[226:227], v231 offset:3584
	v_exp_f32_e32 v188, v188
	v_exp_f32_e32 v189, v189
	s_waitcnt vmcnt(8)
	ds_write_b128 v247, v[116:119]
	ds_write_b128 v247, v[120:123] offset:1024
	ds_write_b128 v247, v[124:127] offset:2048
	ds_write_b128 v247, v[128:131] offset:3072
	ds_read_b128 v[116:119], v248
	ds_read_b128 v[120:123], v249
	ds_read_b128 v[124:127], v250
	ds_read_b128 v[128:131], v251
	ds_write_b128 v112, v[132:135]
	ds_write_b128 v112, v[136:139] offset:1024
	ds_write_b128 v112, v[140:143] offset:2048
	ds_write_b128 v112, v[144:147] offset:3072
	v_exp_f32_e32 v190, v190
	v_exp_f32_e32 v191, v191
	s_waitcnt lgkmcnt(4)
	v_mfma_f32_32x32x16_bf16 v[32:47], v[116:119], v[48:51], v[32:47]
	v_exp_f32_e32 v192, v192
	v_exp_f32_e32 v193, v193
	v_exp_f32_e32 v194, v194
	v_mfma_f32_32x32x16_bf16 v[32:47], v[120:123], v[52:55], v[32:47]
	v_exp_f32_e32 v195, v195
	v_exp_f32_e32 v196, v196
	v_exp_f32_e32 v197, v197
	v_mfma_f32_32x32x16_bf16 v[32:47], v[124:127], v[56:59], v[32:47]
	v_exp_f32_e32 v198, v198
	v_exp_f32_e32 v199, v199
	v_exp_f32_e32 v200, v200
	v_mfma_f32_32x32x16_bf16 v[32:47], v[128:131], v[60:63], v[32:47]
	v_exp_f32_e32 v201, v201
	v_exp_f32_e32 v202, v202
	v_exp_f32_e32 v203, v203
	s_add_i32 s90, s76, -128
	v_lshlrev_b32_e32 v84, 2, v107
	v_add_u32_e32 v84, s90, v84
	v_add_u32_e32 v85, 0, v84
	v_add_u32_e32 v86, 4, v84
	v_add_u32_e32 v87, 8, v84
	v_add_u32_e32 v88, 12, v84
	v_cmp_gt_u32_e64 s[30:31], s98, v85
	v_cmp_gt_u32_e64 s[36:37], s98, v86
	v_cmp_gt_u32_e64 s[78:79], s98, v87
	v_cmp_gt_u32_e64 s[50:51], s98, v88
	v_cndmask_b32_e64 v188, 0, v188, s[30:31]
	v_add_u32_e32 v85, 32, v84
	v_cmp_gt_u32_e64 s[30:31], s98, v85
	v_cndmask_b32_e64 v189, 0, v189, s[36:37]
	v_add_u32_e32 v86, 36, v84
	v_cmp_gt_u32_e64 s[36:37], s98, v86
	v_cndmask_b32_e64 v190, 0, v190, s[78:79]
	v_add_u32_e32 v87, 40, v84
	v_cmp_gt_u32_e64 s[78:79], s98, v87
	v_cndmask_b32_e64 v191, 0, v191, s[50:51]
	v_add_u32_e32 v88, 44, v84
	v_cmp_gt_u32_e64 s[50:51], s98, v88
	v_cndmask_b32_e64 v192, 0, v192, s[30:31]
	v_add_u32_e32 v85, 64, v84
	v_cmp_gt_u32_e64 s[30:31], s98, v85
	v_cndmask_b32_e64 v193, 0, v193, s[36:37]
	v_add_u32_e32 v86, 68, v84
	v_cmp_gt_u32_e64 s[36:37], s98, v86
	v_cndmask_b32_e64 v194, 0, v194, s[78:79]
	v_add_u32_e32 v87, 72, v84
	v_cmp_gt_u32_e64 s[78:79], s98, v87
	v_cndmask_b32_e64 v195, 0, v195, s[50:51]
	v_add_u32_e32 v88, 76, v84
	v_cmp_gt_u32_e64 s[50:51], s98, v88
	v_cndmask_b32_e64 v196, 0, v196, s[30:31]
	v_add_u32_e32 v85, 96, v84
	v_cmp_gt_u32_e64 s[30:31], s98, v85
	v_cndmask_b32_e64 v197, 0, v197, s[36:37]
	v_add_u32_e32 v86, 100, v84
	v_cmp_gt_u32_e64 s[36:37], s98, v86
	v_cndmask_b32_e64 v198, 0, v198, s[78:79]
	v_add_u32_e32 v87, 104, v84
	v_cmp_gt_u32_e64 s[78:79], s98, v87
	v_cndmask_b32_e64 v199, 0, v199, s[50:51]
	v_add_u32_e32 v88, 108, v84
	v_cmp_gt_u32_e64 s[50:51], s98, v88
	v_nop
	v_cndmask_b32_e64 v200, 0, v200, s[30:31]
	v_cndmask_b32_e64 v201, 0, v201, s[36:37]
	v_cndmask_b32_e64 v202, 0, v202, s[78:79]
	v_cndmask_b32_e64 v203, 0, v203, s[50:51]
	v_cvt_pk_bf16_f32 v64, v188, v189
	v_cvt_pk_bf16_f32 v65, v190, v191
	v_cvt_pk_bf16_f32 v66, v192, v193
	v_cvt_pk_bf16_f32 v67, v194, v195
	v_cvt_pk_bf16_f32 v68, v196, v197
	v_cvt_pk_bf16_f32 v69, v198, v199
	v_cvt_pk_bf16_f32 v70, v200, v201
	v_cvt_pk_bf16_f32 v71, v202, v203
	v_pk_add_f32 v[232:233], v[232:233], v[188:189]
	v_pk_add_f32 v[232:233], v[232:233], v[190:191]
	v_pk_add_f32 v[232:233], v[232:233], v[192:193]
	v_pk_add_f32 v[232:233], v[232:233], v[194:195]
	v_pk_add_f32 v[232:233], v[232:233], v[196:197]
	v_pk_add_f32 v[232:233], v[232:233], v[198:199]
	v_pk_add_f32 v[232:233], v[232:233], v[200:201]
	v_pk_add_f32 v[232:233], v[232:233], v[202:203]
	ds_read2_b32 v[188:189], v115 offset0:96 offset1:97
	ds_read2_b32 v[190:191], v115 offset0:98 offset1:99
	ds_read2_b32 v[192:193], v115 offset0:104 offset1:105
	ds_read2_b32 v[194:195], v115 offset0:106 offset1:107
	ds_read2_b32 v[196:197], v115 offset0:112 offset1:113
	ds_read2_b32 v[198:199], v115 offset0:114 offset1:115
	ds_read2_b32 v[200:201], v115 offset0:120 offset1:121
	ds_read2_b32 v[202:203], v115 offset0:122 offset1:123
	v_mfma_f32_32x32x16_bf16 v[0:15], v[64:67], v[72:75], v[0:15]
	v_mfma_f32_32x32x16_bf16 v[16:31], v[64:67], v[76:79], v[16:31]
	v_mfma_f32_32x32x16_bf16 v[0:15], v[68:71], v[220:223], v[0:15]
	v_mfma_f32_32x32x16_bf16 v[16:31], v[68:71], v[224:227], v[16:31]
	s_add_i32 s90, s76, 256
	v_add_u32_e32 v80, s90, v239
	v_add_u32_e32 v83, s90, v240
	v_add_u32_e32 v99, s90, v241
	v_add_u32_e32 v253, s90, v242
	v_add_u32_e32 v254, s90, v101
	v_add_u32_e32 v255, s90, v150
	v_med3_i32 v80, v80, 0, s99
	v_med3_i32 v83, v83, 0, s99
	v_med3_i32 v99, v99, 0, s99
	v_med3_i32 v253, v253, 0, s99
	v_med3_i32 v254, v254, 0, s99
	v_med3_i32 v255, v255, 0, s99
	v_mad_u32_u24 v80, v80, s100, v252
	v_mad_u32_u24 v83, v83, s100, v252
	v_mad_u32_u24 v99, v99, s100, v252
	v_mad_u32_u24 v253, v253, s100, v252
	v_mad_u32_u24 v254, v254, s100, v153
	v_mad_u32_u24 v255, v255, s100, v153
	global_load_dwordx4 v[116:119], v80, s[82:83]
	global_load_dwordx4 v[120:123], v83, s[82:83]
	global_load_dwordx4 v[124:127], v99, s[82:83]
	global_load_dwordx4 v[128:131], v253, s[82:83]
	global_load_dwordx4 v[132:135], v254, s[82:83] offset:768
	global_load_dwordx4 v[136:139], v255, s[82:83] offset:768
	global_load_dwordx4 v[140:143], v254, s[82:83] offset:832
	global_load_dwordx4 v[144:147], v255, s[82:83] offset:832
	ds_read_b64_tr_b16 v[72:73], v231
	ds_read_b64_tr_b16 v[74:75], v231 offset:512
	ds_read_b64_tr_b16 v[76:77], v231 offset:2048
	ds_read_b64_tr_b16 v[78:79], v231 offset:2560
	ds_read_b64_tr_b16 v[220:221], v231 offset:1024
	ds_read_b64_tr_b16 v[222:223], v231 offset:1536
	ds_read_b64_tr_b16 v[224:225], v231 offset:3072
	ds_read_b64_tr_b16 v[226:227], v231 offset:3584
	v_exp_f32_e32 v32, v32
	v_exp_f32_e32 v33, v33
	s_waitcnt vmcnt(8)
	ds_write_b128 v247, v[156:159]
	ds_write_b128 v247, v[160:163] offset:1024
	ds_write_b128 v247, v[164:167] offset:2048
	ds_write_b128 v247, v[168:171] offset:3072
	ds_read_b128 v[156:159], v248
	ds_read_b128 v[160:163], v249
	ds_read_b128 v[164:167], v250
	ds_read_b128 v[168:171], v251
	ds_write_b128 v112, v[172:175]
	ds_write_b128 v112, v[176:179] offset:1024
	ds_write_b128 v112, v[180:183] offset:2048
	ds_write_b128 v112, v[184:187] offset:3072
	v_exp_f32_e32 v34, v34
	v_exp_f32_e32 v35, v35
	s_waitcnt lgkmcnt(4)
	v_mfma_f32_32x32x16_bf16 v[188:203], v[156:159], v[48:51], v[188:203]
	v_exp_f32_e32 v36, v36
	v_exp_f32_e32 v37, v37
	v_exp_f32_e32 v38, v38
	v_mfma_f32_32x32x16_bf16 v[188:203], v[160:163], v[52:55], v[188:203]
	v_exp_f32_e32 v39, v39
	v_exp_f32_e32 v40, v40
	v_exp_f32_e32 v41, v41
	v_mfma_f32_32x32x16_bf16 v[188:203], v[164:167], v[56:59], v[188:203]
	v_exp_f32_e32 v42, v42
	v_exp_f32_e32 v43, v43
	v_exp_f32_e32 v44, v44
	v_mfma_f32_32x32x16_bf16 v[188:203], v[168:171], v[60:63], v[188:203]
	v_exp_f32_e32 v45, v45
	v_exp_f32_e32 v46, v46
	v_exp_f32_e32 v47, v47
	s_add_i32 s90, s76, 0
	v_lshlrev_b32_e32 v84, 2, v107
	v_add_u32_e32 v84, s90, v84
	v_add_u32_e32 v85, 0, v84
	v_add_u32_e32 v86, 4, v84
	v_add_u32_e32 v87, 8, v84
	v_add_u32_e32 v88, 12, v84
	v_cmp_gt_u32_e64 s[30:31], s98, v85
	v_cmp_gt_u32_e64 s[36:37], s98, v86
	v_cmp_gt_u32_e64 s[78:79], s98, v87
	v_cmp_gt_u32_e64 s[50:51], s98, v88
	v_cndmask_b32_e64 v32, 0, v32, s[30:31]
	v_add_u32_e32 v85, 32, v84
	v_cmp_gt_u32_e64 s[30:31], s98, v85
	v_cndmask_b32_e64 v33, 0, v33, s[36:37]
	v_add_u32_e32 v86, 36, v84
	v_cmp_gt_u32_e64 s[36:37], s98, v86
	v_cndmask_b32_e64 v34, 0, v34, s[78:79]
	v_add_u32_e32 v87, 40, v84
	v_cmp_gt_u32_e64 s[78:79], s98, v87
	v_cndmask_b32_e64 v35, 0, v35, s[50:51]
	v_add_u32_e32 v88, 44, v84
	v_cmp_gt_u32_e64 s[50:51], s98, v88
	v_cndmask_b32_e64 v36, 0, v36, s[30:31]
	v_add_u32_e32 v85, 64, v84
	v_cmp_gt_u32_e64 s[30:31], s98, v85
	v_cndmask_b32_e64 v37, 0, v37, s[36:37]
	v_add_u32_e32 v86, 68, v84
	v_cmp_gt_u32_e64 s[36:37], s98, v86
	v_cndmask_b32_e64 v38, 0, v38, s[78:79]
	v_add_u32_e32 v87, 72, v84
	v_cmp_gt_u32_e64 s[78:79], s98, v87
	v_cndmask_b32_e64 v39, 0, v39, s[50:51]
	v_add_u32_e32 v88, 76, v84
	v_cmp_gt_u32_e64 s[50:51], s98, v88
	v_cndmask_b32_e64 v40, 0, v40, s[30:31]
	v_add_u32_e32 v85, 96, v84
	v_cmp_gt_u32_e64 s[30:31], s98, v85
	v_cndmask_b32_e64 v41, 0, v41, s[36:37]
	v_add_u32_e32 v86, 100, v84
	v_cmp_gt_u32_e64 s[36:37], s98, v86
	v_cndmask_b32_e64 v42, 0, v42, s[78:79]
	v_add_u32_e32 v87, 104, v84
	v_cmp_gt_u32_e64 s[78:79], s98, v87
	v_cndmask_b32_e64 v43, 0, v43, s[50:51]
	v_add_u32_e32 v88, 108, v84
	v_cmp_gt_u32_e64 s[50:51], s98, v88
	v_nop
	v_cndmask_b32_e64 v44, 0, v44, s[30:31]
	v_cndmask_b32_e64 v45, 0, v45, s[36:37]
	v_cndmask_b32_e64 v46, 0, v46, s[78:79]
	v_cndmask_b32_e64 v47, 0, v47, s[50:51]
	v_cvt_pk_bf16_f32 v64, v32, v33
	v_cvt_pk_bf16_f32 v65, v34, v35
	v_cvt_pk_bf16_f32 v66, v36, v37
	v_cvt_pk_bf16_f32 v67, v38, v39
	v_cvt_pk_bf16_f32 v68, v40, v41
	v_cvt_pk_bf16_f32 v69, v42, v43
	v_cvt_pk_bf16_f32 v70, v44, v45
	v_cvt_pk_bf16_f32 v71, v46, v47
	v_pk_add_f32 v[232:233], v[232:233], v[32:33]
	v_pk_add_f32 v[232:233], v[232:233], v[34:35]
	v_pk_add_f32 v[232:233], v[232:233], v[36:37]
	v_pk_add_f32 v[232:233], v[232:233], v[38:39]
	v_pk_add_f32 v[232:233], v[232:233], v[40:41]
	v_pk_add_f32 v[232:233], v[232:233], v[42:43]
	v_pk_add_f32 v[232:233], v[232:233], v[44:45]
	v_pk_add_f32 v[232:233], v[232:233], v[46:47]
	ds_read2_b32 v[32:33], v115 offset0:128 offset1:129
	ds_read2_b32 v[34:35], v115 offset0:130 offset1:131
	ds_read2_b32 v[36:37], v115 offset0:136 offset1:137
	ds_read2_b32 v[38:39], v115 offset0:138 offset1:139
	ds_read2_b32 v[40:41], v115 offset0:144 offset1:145
	ds_read2_b32 v[42:43], v115 offset0:146 offset1:147
	ds_read2_b32 v[44:45], v115 offset0:152 offset1:153
	ds_read2_b32 v[46:47], v115 offset0:154 offset1:155
	v_mfma_f32_32x32x16_bf16 v[0:15], v[64:67], v[72:75], v[0:15]
	v_mfma_f32_32x32x16_bf16 v[16:31], v[64:67], v[76:79], v[16:31]
	v_mfma_f32_32x32x16_bf16 v[0:15], v[68:71], v[220:223], v[0:15]
	v_mfma_f32_32x32x16_bf16 v[16:31], v[68:71], v[224:227], v[16:31]
	s_add_i32 s90, s76, 384
	v_add_u32_e32 v80, s90, v239
	v_add_u32_e32 v83, s90, v240
	v_add_u32_e32 v99, s90, v241
	v_add_u32_e32 v253, s90, v242
	v_add_u32_e32 v254, s90, v101
	v_add_u32_e32 v255, s90, v150
	v_med3_i32 v80, v80, 0, s99
	v_med3_i32 v83, v83, 0, s99
	v_med3_i32 v99, v99, 0, s99
	v_med3_i32 v253, v253, 0, s99
	v_med3_i32 v254, v254, 0, s99
	v_med3_i32 v255, v255, 0, s99
	v_mad_u32_u24 v80, v80, s100, v252
	v_mad_u32_u24 v83, v83, s100, v252
	v_mad_u32_u24 v99, v99, s100, v252
	v_mad_u32_u24 v253, v253, s100, v252
	v_mad_u32_u24 v254, v254, s100, v153
	v_mad_u32_u24 v255, v255, s100, v153
	global_load_dwordx4 v[156:159], v80, s[82:83]
	global_load_dwordx4 v[160:163], v83, s[82:83]
	global_load_dwordx4 v[164:167], v99, s[82:83]
	global_load_dwordx4 v[168:171], v253, s[82:83]
	global_load_dwordx4 v[172:175], v254, s[82:83] offset:768
	global_load_dwordx4 v[176:179], v255, s[82:83] offset:768
	global_load_dwordx4 v[180:183], v254, s[82:83] offset:832
	global_load_dwordx4 v[184:187], v255, s[82:83] offset:832
	ds_read_b64_tr_b16 v[72:73], v231
	ds_read_b64_tr_b16 v[74:75], v231 offset:512
	ds_read_b64_tr_b16 v[76:77], v231 offset:2048
	ds_read_b64_tr_b16 v[78:79], v231 offset:2560
	ds_read_b64_tr_b16 v[220:221], v231 offset:1024
	ds_read_b64_tr_b16 v[222:223], v231 offset:1536
	ds_read_b64_tr_b16 v[224:225], v231 offset:3072
	ds_read_b64_tr_b16 v[226:227], v231 offset:3584
	v_exp_f32_e32 v188, v188
	v_exp_f32_e32 v189, v189
	s_waitcnt vmcnt(8)
	ds_write_b128 v247, v[116:119]
	ds_write_b128 v247, v[120:123] offset:1024
	ds_write_b128 v247, v[124:127] offset:2048
	ds_write_b128 v247, v[128:131] offset:3072
	ds_read_b128 v[116:119], v248
	ds_read_b128 v[120:123], v249
	ds_read_b128 v[124:127], v250
	ds_read_b128 v[128:131], v251
	ds_write_b128 v112, v[132:135]
	ds_write_b128 v112, v[136:139] offset:1024
	ds_write_b128 v112, v[140:143] offset:2048
	ds_write_b128 v112, v[144:147] offset:3072
	v_exp_f32_e32 v190, v190
	v_exp_f32_e32 v191, v191
	s_waitcnt lgkmcnt(4)
	v_mfma_f32_32x32x16_bf16 v[32:47], v[116:119], v[48:51], v[32:47]
	v_exp_f32_e32 v192, v192
	v_exp_f32_e32 v193, v193
	v_exp_f32_e32 v194, v194
	v_mfma_f32_32x32x16_bf16 v[32:47], v[120:123], v[52:55], v[32:47]
	v_exp_f32_e32 v195, v195
	v_exp_f32_e32 v196, v196
	v_exp_f32_e32 v197, v197
	v_mfma_f32_32x32x16_bf16 v[32:47], v[124:127], v[56:59], v[32:47]
	v_exp_f32_e32 v198, v198
	v_exp_f32_e32 v199, v199
	v_exp_f32_e32 v200, v200
	v_mfma_f32_32x32x16_bf16 v[32:47], v[128:131], v[60:63], v[32:47]
	v_exp_f32_e32 v201, v201
	v_exp_f32_e32 v202, v202
	v_exp_f32_e32 v203, v203
	s_add_i32 s90, s76, 128
	v_lshlrev_b32_e32 v84, 2, v107
	v_add_u32_e32 v84, s90, v84
	v_add_u32_e32 v85, 0, v84
	v_add_u32_e32 v86, 4, v84
	v_add_u32_e32 v87, 8, v84
	v_add_u32_e32 v88, 12, v84
	v_cmp_gt_u32_e64 s[30:31], s98, v85
	v_cmp_gt_u32_e64 s[36:37], s98, v86
	v_cmp_gt_u32_e64 s[78:79], s98, v87
	v_cmp_gt_u32_e64 s[50:51], s98, v88
	v_cndmask_b32_e64 v188, 0, v188, s[30:31]
	v_add_u32_e32 v85, 32, v84
	v_cmp_gt_u32_e64 s[30:31], s98, v85
	v_cndmask_b32_e64 v189, 0, v189, s[36:37]
	v_add_u32_e32 v86, 36, v84
	v_cmp_gt_u32_e64 s[36:37], s98, v86
	v_cndmask_b32_e64 v190, 0, v190, s[78:79]
	v_add_u32_e32 v87, 40, v84
	v_cmp_gt_u32_e64 s[78:79], s98, v87
	v_cndmask_b32_e64 v191, 0, v191, s[50:51]
	v_add_u32_e32 v88, 44, v84
	v_cmp_gt_u32_e64 s[50:51], s98, v88
	v_cndmask_b32_e64 v192, 0, v192, s[30:31]
	v_add_u32_e32 v85, 64, v84
	v_cmp_gt_u32_e64 s[30:31], s98, v85
	v_cndmask_b32_e64 v193, 0, v193, s[36:37]
	v_add_u32_e32 v86, 68, v84
	v_cmp_gt_u32_e64 s[36:37], s98, v86
	v_cndmask_b32_e64 v194, 0, v194, s[78:79]
	v_add_u32_e32 v87, 72, v84
	v_cmp_gt_u32_e64 s[78:79], s98, v87
	v_cndmask_b32_e64 v195, 0, v195, s[50:51]
	v_add_u32_e32 v88, 76, v84
	v_cmp_gt_u32_e64 s[50:51], s98, v88
	v_cndmask_b32_e64 v196, 0, v196, s[30:31]
	v_add_u32_e32 v85, 96, v84
	v_cmp_gt_u32_e64 s[30:31], s98, v85
	v_cndmask_b32_e64 v197, 0, v197, s[36:37]
	v_add_u32_e32 v86, 100, v84
	v_cmp_gt_u32_e64 s[36:37], s98, v86
	v_cndmask_b32_e64 v198, 0, v198, s[78:79]
	v_add_u32_e32 v87, 104, v84
	v_cmp_gt_u32_e64 s[78:79], s98, v87
	v_cndmask_b32_e64 v199, 0, v199, s[50:51]
	v_add_u32_e32 v88, 108, v84
	v_cmp_gt_u32_e64 s[50:51], s98, v88
	v_nop
	v_cndmask_b32_e64 v200, 0, v200, s[30:31]
	v_cndmask_b32_e64 v201, 0, v201, s[36:37]
	v_cndmask_b32_e64 v202, 0, v202, s[78:79]
	v_cndmask_b32_e64 v203, 0, v203, s[50:51]
	v_cvt_pk_bf16_f32 v64, v188, v189
	v_cvt_pk_bf16_f32 v65, v190, v191
	v_cvt_pk_bf16_f32 v66, v192, v193
	v_cvt_pk_bf16_f32 v67, v194, v195
	v_cvt_pk_bf16_f32 v68, v196, v197
	v_cvt_pk_bf16_f32 v69, v198, v199
	v_cvt_pk_bf16_f32 v70, v200, v201
	v_cvt_pk_bf16_f32 v71, v202, v203
	v_pk_add_f32 v[232:233], v[232:233], v[188:189]
	v_pk_add_f32 v[232:233], v[232:233], v[190:191]
	v_pk_add_f32 v[232:233], v[232:233], v[192:193]
	v_pk_add_f32 v[232:233], v[232:233], v[194:195]
	v_pk_add_f32 v[232:233], v[232:233], v[196:197]
	v_pk_add_f32 v[232:233], v[232:233], v[198:199]
	v_pk_add_f32 v[232:233], v[232:233], v[200:201]
	v_pk_add_f32 v[232:233], v[232:233], v[202:203]
	ds_read2_b32 v[188:189], v115 offset0:160 offset1:161
	ds_read2_b32 v[190:191], v115 offset0:162 offset1:163
	ds_read2_b32 v[192:193], v115 offset0:168 offset1:169
	ds_read2_b32 v[194:195], v115 offset0:170 offset1:171
	ds_read2_b32 v[196:197], v115 offset0:176 offset1:177
	ds_read2_b32 v[198:199], v115 offset0:178 offset1:179
	ds_read2_b32 v[200:201], v115 offset0:184 offset1:185
	ds_read2_b32 v[202:203], v115 offset0:186 offset1:187
	v_mfma_f32_32x32x16_bf16 v[0:15], v[64:67], v[72:75], v[0:15]
	v_mfma_f32_32x32x16_bf16 v[16:31], v[64:67], v[76:79], v[16:31]
	v_mfma_f32_32x32x16_bf16 v[0:15], v[68:71], v[220:223], v[0:15]
	v_mfma_f32_32x32x16_bf16 v[16:31], v[68:71], v[224:227], v[16:31]
	s_add_i32 s90, s76, 512
	v_add_u32_e32 v80, s90, v239
	v_add_u32_e32 v83, s90, v240
	v_add_u32_e32 v99, s90, v241
	v_add_u32_e32 v253, s90, v242
	v_add_u32_e32 v254, s90, v101
	v_add_u32_e32 v255, s90, v150
	v_med3_i32 v80, v80, 0, s99
	v_med3_i32 v83, v83, 0, s99
	v_med3_i32 v99, v99, 0, s99
	v_med3_i32 v253, v253, 0, s99
	v_med3_i32 v254, v254, 0, s99
	v_med3_i32 v255, v255, 0, s99
	v_mad_u32_u24 v80, v80, s100, v252
	v_mad_u32_u24 v83, v83, s100, v252
	v_mad_u32_u24 v99, v99, s100, v252
	v_mad_u32_u24 v253, v253, s100, v252
	v_mad_u32_u24 v254, v254, s100, v153
	v_mad_u32_u24 v255, v255, s100, v153
	global_load_dwordx4 v[116:119], v80, s[82:83]
	global_load_dwordx4 v[120:123], v83, s[82:83]
	global_load_dwordx4 v[124:127], v99, s[82:83]
	global_load_dwordx4 v[128:131], v253, s[82:83]
	global_load_dwordx4 v[132:135], v254, s[82:83] offset:768
	global_load_dwordx4 v[136:139], v255, s[82:83] offset:768
	global_load_dwordx4 v[140:143], v254, s[82:83] offset:832
	global_load_dwordx4 v[144:147], v255, s[82:83] offset:832
	ds_read_b64_tr_b16 v[72:73], v231
	ds_read_b64_tr_b16 v[74:75], v231 offset:512
	ds_read_b64_tr_b16 v[76:77], v231 offset:2048
	ds_read_b64_tr_b16 v[78:79], v231 offset:2560
	ds_read_b64_tr_b16 v[220:221], v231 offset:1024
	ds_read_b64_tr_b16 v[222:223], v231 offset:1536
	ds_read_b64_tr_b16 v[224:225], v231 offset:3072
	ds_read_b64_tr_b16 v[226:227], v231 offset:3584
	v_exp_f32_e32 v32, v32
	v_exp_f32_e32 v33, v33
	s_waitcnt vmcnt(8)
	ds_write_b128 v247, v[156:159]
	ds_write_b128 v247, v[160:163] offset:1024
	ds_write_b128 v247, v[164:167] offset:2048
	ds_write_b128 v247, v[168:171] offset:3072
	ds_read_b128 v[156:159], v248
	ds_read_b128 v[160:163], v249
	ds_read_b128 v[164:167], v250
	ds_read_b128 v[168:171], v251
	ds_write_b128 v112, v[172:175]
	ds_write_b128 v112, v[176:179] offset:1024
	ds_write_b128 v112, v[180:183] offset:2048
	ds_write_b128 v112, v[184:187] offset:3072
	v_exp_f32_e32 v34, v34
	v_exp_f32_e32 v35, v35
	s_waitcnt lgkmcnt(4)
	v_mfma_f32_32x32x16_bf16 v[188:203], v[156:159], v[48:51], v[188:203]
	v_exp_f32_e32 v36, v36
	v_exp_f32_e32 v37, v37
	v_exp_f32_e32 v38, v38
	v_mfma_f32_32x32x16_bf16 v[188:203], v[160:163], v[52:55], v[188:203]
	v_exp_f32_e32 v39, v39
	v_exp_f32_e32 v40, v40
	v_exp_f32_e32 v41, v41
	v_mfma_f32_32x32x16_bf16 v[188:203], v[164:167], v[56:59], v[188:203]
	v_exp_f32_e32 v42, v42
	v_exp_f32_e32 v43, v43
	v_exp_f32_e32 v44, v44
	v_mfma_f32_32x32x16_bf16 v[188:203], v[168:171], v[60:63], v[188:203]
	v_exp_f32_e32 v45, v45
	v_exp_f32_e32 v46, v46
	v_exp_f32_e32 v47, v47
	s_add_i32 s90, s76, 256
	v_lshlrev_b32_e32 v84, 2, v107
	v_add_u32_e32 v84, s90, v84
	v_add_u32_e32 v85, 0, v84
	v_add_u32_e32 v86, 4, v84
	v_add_u32_e32 v87, 8, v84
	v_add_u32_e32 v88, 12, v84
	v_cmp_gt_u32_e64 s[30:31], s98, v85
	v_cmp_gt_u32_e64 s[36:37], s98, v86
	v_cmp_gt_u32_e64 s[78:79], s98, v87
	v_cmp_gt_u32_e64 s[50:51], s98, v88
	v_cndmask_b32_e64 v32, 0, v32, s[30:31]
	v_add_u32_e32 v85, 32, v84
	v_cmp_gt_u32_e64 s[30:31], s98, v85
	v_cndmask_b32_e64 v33, 0, v33, s[36:37]
	v_add_u32_e32 v86, 36, v84
	v_cmp_gt_u32_e64 s[36:37], s98, v86
	v_cndmask_b32_e64 v34, 0, v34, s[78:79]
	v_add_u32_e32 v87, 40, v84
	v_cmp_gt_u32_e64 s[78:79], s98, v87
	v_cndmask_b32_e64 v35, 0, v35, s[50:51]
	v_add_u32_e32 v88, 44, v84
	v_cmp_gt_u32_e64 s[50:51], s98, v88
	v_cndmask_b32_e64 v36, 0, v36, s[30:31]
	v_add_u32_e32 v85, 64, v84
	v_cmp_gt_u32_e64 s[30:31], s98, v85
	v_cndmask_b32_e64 v37, 0, v37, s[36:37]
	v_add_u32_e32 v86, 68, v84
	v_cmp_gt_u32_e64 s[36:37], s98, v86
	v_cndmask_b32_e64 v38, 0, v38, s[78:79]
	v_add_u32_e32 v87, 72, v84
	v_cmp_gt_u32_e64 s[78:79], s98, v87
	v_cndmask_b32_e64 v39, 0, v39, s[50:51]
	v_add_u32_e32 v88, 76, v84
	v_cmp_gt_u32_e64 s[50:51], s98, v88
	v_cndmask_b32_e64 v40, 0, v40, s[30:31]
	v_add_u32_e32 v85, 96, v84
	v_cmp_gt_u32_e64 s[30:31], s98, v85
	v_cndmask_b32_e64 v41, 0, v41, s[36:37]
	v_add_u32_e32 v86, 100, v84
	v_cmp_gt_u32_e64 s[36:37], s98, v86
	v_cndmask_b32_e64 v42, 0, v42, s[78:79]
	v_add_u32_e32 v87, 104, v84
	v_cmp_gt_u32_e64 s[78:79], s98, v87
	v_cndmask_b32_e64 v43, 0, v43, s[50:51]
	v_add_u32_e32 v88, 108, v84
	v_cmp_gt_u32_e64 s[50:51], s98, v88
	v_nop
	v_cndmask_b32_e64 v44, 0, v44, s[30:31]
	v_cndmask_b32_e64 v45, 0, v45, s[36:37]
	v_cndmask_b32_e64 v46, 0, v46, s[78:79]
	v_cndmask_b32_e64 v47, 0, v47, s[50:51]
	v_cvt_pk_bf16_f32 v64, v32, v33
	v_cvt_pk_bf16_f32 v65, v34, v35
	v_cvt_pk_bf16_f32 v66, v36, v37
	v_cvt_pk_bf16_f32 v67, v38, v39
	v_cvt_pk_bf16_f32 v68, v40, v41
	v_cvt_pk_bf16_f32 v69, v42, v43
	v_cvt_pk_bf16_f32 v70, v44, v45
	v_cvt_pk_bf16_f32 v71, v46, v47
	v_pk_add_f32 v[232:233], v[232:233], v[32:33]
	v_pk_add_f32 v[232:233], v[232:233], v[34:35]
	v_pk_add_f32 v[232:233], v[232:233], v[36:37]
	v_pk_add_f32 v[232:233], v[232:233], v[38:39]
	v_pk_add_f32 v[232:233], v[232:233], v[40:41]
	v_pk_add_f32 v[232:233], v[232:233], v[42:43]
	v_pk_add_f32 v[232:233], v[232:233], v[44:45]
	v_pk_add_f32 v[232:233], v[232:233], v[46:47]
	ds_read2_b32 v[32:33], v115 offset0:192 offset1:193
	ds_read2_b32 v[34:35], v115 offset0:194 offset1:195
	ds_read2_b32 v[36:37], v115 offset0:200 offset1:201
	ds_read2_b32 v[38:39], v115 offset0:202 offset1:203
	ds_read2_b32 v[40:41], v115 offset0:208 offset1:209
	ds_read2_b32 v[42:43], v115 offset0:210 offset1:211
	ds_read2_b32 v[44:45], v115 offset0:216 offset1:217
	ds_read2_b32 v[46:47], v115 offset0:218 offset1:219
	v_mfma_f32_32x32x16_bf16 v[0:15], v[64:67], v[72:75], v[0:15]
	v_mfma_f32_32x32x16_bf16 v[16:31], v[64:67], v[76:79], v[16:31]
	v_mfma_f32_32x32x16_bf16 v[0:15], v[68:71], v[220:223], v[0:15]
	v_mfma_f32_32x32x16_bf16 v[16:31], v[68:71], v[224:227], v[16:31]
	s_add_i32 s90, s76, 640
	v_add_u32_e32 v80, s90, v239
	v_add_u32_e32 v83, s90, v240
	v_add_u32_e32 v99, s90, v241
	v_add_u32_e32 v253, s90, v242
	v_add_u32_e32 v254, s90, v101
	v_add_u32_e32 v255, s90, v150
	v_med3_i32 v80, v80, 0, s99
	v_med3_i32 v83, v83, 0, s99
	v_med3_i32 v99, v99, 0, s99
	v_med3_i32 v253, v253, 0, s99
	v_med3_i32 v254, v254, 0, s99
	v_med3_i32 v255, v255, 0, s99
	v_mad_u32_u24 v80, v80, s100, v252
	v_mad_u32_u24 v83, v83, s100, v252
	v_mad_u32_u24 v99, v99, s100, v252
	v_mad_u32_u24 v253, v253, s100, v252
	v_mad_u32_u24 v254, v254, s100, v153
	v_mad_u32_u24 v255, v255, s100, v153
	global_load_dwordx4 v[156:159], v80, s[82:83]
	global_load_dwordx4 v[160:163], v83, s[82:83]
	global_load_dwordx4 v[164:167], v99, s[82:83]
	global_load_dwordx4 v[168:171], v253, s[82:83]
	global_load_dwordx4 v[172:175], v254, s[82:83] offset:768
	global_load_dwordx4 v[176:179], v255, s[82:83] offset:768
	global_load_dwordx4 v[180:183], v254, s[82:83] offset:832
	global_load_dwordx4 v[184:187], v255, s[82:83] offset:832
	ds_read_b64_tr_b16 v[72:73], v231
	ds_read_b64_tr_b16 v[74:75], v231 offset:512
	ds_read_b64_tr_b16 v[76:77], v231 offset:2048
	ds_read_b64_tr_b16 v[78:79], v231 offset:2560
	ds_read_b64_tr_b16 v[220:221], v231 offset:1024
	ds_read_b64_tr_b16 v[222:223], v231 offset:1536
	ds_read_b64_tr_b16 v[224:225], v231 offset:3072
	ds_read_b64_tr_b16 v[226:227], v231 offset:3584
	v_exp_f32_e32 v188, v188
	v_exp_f32_e32 v189, v189
	s_waitcnt vmcnt(8)
	ds_write_b128 v247, v[116:119]
	ds_write_b128 v247, v[120:123] offset:1024
	ds_write_b128 v247, v[124:127] offset:2048
	ds_write_b128 v247, v[128:131] offset:3072
	ds_read_b128 v[116:119], v248
	ds_read_b128 v[120:123], v249
	ds_read_b128 v[124:127], v250
	ds_read_b128 v[128:131], v251
	ds_write_b128 v112, v[132:135]
	ds_write_b128 v112, v[136:139] offset:1024
	ds_write_b128 v112, v[140:143] offset:2048
	ds_write_b128 v112, v[144:147] offset:3072
	v_exp_f32_e32 v190, v190
	v_exp_f32_e32 v191, v191
	s_waitcnt lgkmcnt(4)
	v_mfma_f32_32x32x16_bf16 v[32:47], v[116:119], v[48:51], v[32:47]
	v_exp_f32_e32 v192, v192
	v_exp_f32_e32 v193, v193
	v_exp_f32_e32 v194, v194
	v_mfma_f32_32x32x16_bf16 v[32:47], v[120:123], v[52:55], v[32:47]
	v_exp_f32_e32 v195, v195
	v_exp_f32_e32 v196, v196
	v_exp_f32_e32 v197, v197
	v_mfma_f32_32x32x16_bf16 v[32:47], v[124:127], v[56:59], v[32:47]
	v_exp_f32_e32 v198, v198
	v_exp_f32_e32 v199, v199
	v_exp_f32_e32 v200, v200
	v_mfma_f32_32x32x16_bf16 v[32:47], v[128:131], v[60:63], v[32:47]
	v_exp_f32_e32 v201, v201
	v_exp_f32_e32 v202, v202
	v_exp_f32_e32 v203, v203
	s_add_i32 s90, s76, 384
	v_lshlrev_b32_e32 v84, 2, v107
	v_add_u32_e32 v84, s90, v84
	v_add_u32_e32 v85, 0, v84
	v_add_u32_e32 v86, 4, v84
	v_add_u32_e32 v87, 8, v84
	v_add_u32_e32 v88, 12, v84
	v_cmp_gt_u32_e64 s[30:31], s98, v85
	v_cmp_gt_u32_e64 s[36:37], s98, v86
	v_cmp_gt_u32_e64 s[78:79], s98, v87
	v_cmp_gt_u32_e64 s[50:51], s98, v88
	v_cndmask_b32_e64 v188, 0, v188, s[30:31]
	v_add_u32_e32 v85, 32, v84
	v_cmp_gt_u32_e64 s[30:31], s98, v85
	v_cndmask_b32_e64 v189, 0, v189, s[36:37]
	v_add_u32_e32 v86, 36, v84
	v_cmp_gt_u32_e64 s[36:37], s98, v86
	v_cndmask_b32_e64 v190, 0, v190, s[78:79]
	v_add_u32_e32 v87, 40, v84
	v_cmp_gt_u32_e64 s[78:79], s98, v87
	v_cndmask_b32_e64 v191, 0, v191, s[50:51]
	v_add_u32_e32 v88, 44, v84
	v_cmp_gt_u32_e64 s[50:51], s98, v88
	v_cndmask_b32_e64 v192, 0, v192, s[30:31]
	v_add_u32_e32 v85, 64, v84
	v_cmp_gt_u32_e64 s[30:31], s98, v85
	v_cndmask_b32_e64 v193, 0, v193, s[36:37]
	v_add_u32_e32 v86, 68, v84
	v_cmp_gt_u32_e64 s[36:37], s98, v86
	v_cndmask_b32_e64 v194, 0, v194, s[78:79]
	v_add_u32_e32 v87, 72, v84
	v_cmp_gt_u32_e64 s[78:79], s98, v87
	v_cndmask_b32_e64 v195, 0, v195, s[50:51]
	v_add_u32_e32 v88, 76, v84
	v_cmp_gt_u32_e64 s[50:51], s98, v88
	v_cndmask_b32_e64 v196, 0, v196, s[30:31]
	v_add_u32_e32 v85, 96, v84
	v_cmp_gt_u32_e64 s[30:31], s98, v85
	v_cndmask_b32_e64 v197, 0, v197, s[36:37]
	v_add_u32_e32 v86, 100, v84
	v_cmp_gt_u32_e64 s[36:37], s98, v86
	v_cndmask_b32_e64 v198, 0, v198, s[78:79]
	v_add_u32_e32 v87, 104, v84
	v_cmp_gt_u32_e64 s[78:79], s98, v87
	v_cndmask_b32_e64 v199, 0, v199, s[50:51]
	v_add_u32_e32 v88, 108, v84
	v_cmp_gt_u32_e64 s[50:51], s98, v88
	v_nop
	v_cndmask_b32_e64 v200, 0, v200, s[30:31]
	v_cndmask_b32_e64 v201, 0, v201, s[36:37]
	v_cndmask_b32_e64 v202, 0, v202, s[78:79]
	v_cndmask_b32_e64 v203, 0, v203, s[50:51]
	v_cvt_pk_bf16_f32 v64, v188, v189
	v_cvt_pk_bf16_f32 v65, v190, v191
	v_cvt_pk_bf16_f32 v66, v192, v193
	v_cvt_pk_bf16_f32 v67, v194, v195
	v_cvt_pk_bf16_f32 v68, v196, v197
	v_cvt_pk_bf16_f32 v69, v198, v199
	v_cvt_pk_bf16_f32 v70, v200, v201
	v_cvt_pk_bf16_f32 v71, v202, v203
	v_pk_add_f32 v[232:233], v[232:233], v[188:189]
	v_pk_add_f32 v[232:233], v[232:233], v[190:191]
	v_pk_add_f32 v[232:233], v[232:233], v[192:193]
	v_pk_add_f32 v[232:233], v[232:233], v[194:195]
	v_pk_add_f32 v[232:233], v[232:233], v[196:197]
	v_pk_add_f32 v[232:233], v[232:233], v[198:199]
	v_pk_add_f32 v[232:233], v[232:233], v[200:201]
	v_pk_add_f32 v[232:233], v[232:233], v[202:203]
	ds_read2_b32 v[188:189], v115 offset0:224 offset1:225
	ds_read2_b32 v[190:191], v115 offset0:226 offset1:227
	ds_read2_b32 v[192:193], v115 offset0:232 offset1:233
	ds_read2_b32 v[194:195], v115 offset0:234 offset1:235
	ds_read2_b32 v[196:197], v115 offset0:240 offset1:241
	ds_read2_b32 v[198:199], v115 offset0:242 offset1:243
	ds_read2_b32 v[200:201], v115 offset0:248 offset1:249
	ds_read2_b32 v[202:203], v115 offset0:250 offset1:251
	v_mfma_f32_32x32x16_bf16 v[0:15], v[64:67], v[72:75], v[0:15]
	v_mfma_f32_32x32x16_bf16 v[16:31], v[64:67], v[76:79], v[16:31]
	v_mfma_f32_32x32x16_bf16 v[0:15], v[68:71], v[220:223], v[0:15]
	v_mfma_f32_32x32x16_bf16 v[16:31], v[68:71], v[224:227], v[16:31]
	s_add_i32 s90, s76, -1024
	v_add_u32_e32 v80, s90, v243
	v_add_u32_e32 v83, s90, v244
	v_add_u32_e32 v99, s90, v245
	v_add_u32_e32 v253, s90, v246
	v_add_u32_e32 v254, s90, v148
	v_add_u32_e32 v255, s90, v151
	v_med3_i32 v80, v80, 0, s99
	v_med3_i32 v83, v83, 0, s99
	v_med3_i32 v99, v99, 0, s99
	v_med3_i32 v253, v253, 0, s99
	v_med3_i32 v254, v254, 0, s99
	v_med3_i32 v255, v255, 0, s99
	v_mad_u32_u24 v80, v80, s100, v252
	v_mad_u32_u24 v83, v83, s100, v252
	v_mad_u32_u24 v99, v99, s100, v252
	v_mad_u32_u24 v253, v253, s100, v252
	v_mad_u32_u24 v254, v254, s100, v153
	v_mad_u32_u24 v255, v255, s100, v153
	global_load_dwordx4 v[116:119], v80, s[82:83]
	global_load_dwordx4 v[120:123], v83, s[82:83]
	global_load_dwordx4 v[124:127], v99, s[82:83]
	global_load_dwordx4 v[128:131], v253, s[82:83]
	global_load_dwordx4 v[132:135], v254, s[82:83] offset:768
	global_load_dwordx4 v[136:139], v255, s[82:83] offset:768
	global_load_dwordx4 v[140:143], v254, s[82:83] offset:832
	global_load_dwordx4 v[144:147], v255, s[82:83] offset:832
	ds_read_b64_tr_b16 v[72:73], v231
	ds_read_b64_tr_b16 v[74:75], v231 offset:512
	ds_read_b64_tr_b16 v[76:77], v231 offset:2048
	ds_read_b64_tr_b16 v[78:79], v231 offset:2560
	ds_read_b64_tr_b16 v[220:221], v231 offset:1024
	ds_read_b64_tr_b16 v[222:223], v231 offset:1536
	ds_read_b64_tr_b16 v[224:225], v231 offset:3072
	ds_read_b64_tr_b16 v[226:227], v231 offset:3584
	v_exp_f32_e32 v32, v32
	v_exp_f32_e32 v33, v33
	s_waitcnt vmcnt(8)
	ds_write_b128 v247, v[156:159]
	ds_write_b128 v247, v[160:163] offset:1024
	ds_write_b128 v247, v[164:167] offset:2048
	ds_write_b128 v247, v[168:171] offset:3072
	ds_read_b128 v[156:159], v248
	ds_read_b128 v[160:163], v249
	ds_read_b128 v[164:167], v250
	ds_read_b128 v[168:171], v251
	ds_write_b128 v112, v[172:175]
	ds_write_b128 v112, v[176:179] offset:1024
	ds_write_b128 v112, v[180:183] offset:2048
	ds_write_b128 v112, v[184:187] offset:3072
	v_exp_f32_e32 v34, v34
	v_exp_f32_e32 v35, v35
	s_waitcnt lgkmcnt(4)
	v_mfma_f32_32x32x16_bf16 v[188:203], v[156:159], v[48:51], v[188:203]
	v_exp_f32_e32 v36, v36
	v_exp_f32_e32 v37, v37
	v_exp_f32_e32 v38, v38
	v_mfma_f32_32x32x16_bf16 v[188:203], v[160:163], v[52:55], v[188:203]
	v_exp_f32_e32 v39, v39
	v_exp_f32_e32 v40, v40
	v_exp_f32_e32 v41, v41
	v_mfma_f32_32x32x16_bf16 v[188:203], v[164:167], v[56:59], v[188:203]
	v_exp_f32_e32 v42, v42
	v_exp_f32_e32 v43, v43
	v_exp_f32_e32 v44, v44
	v_mfma_f32_32x32x16_bf16 v[188:203], v[168:171], v[60:63], v[188:203]
	v_exp_f32_e32 v45, v45
	v_exp_f32_e32 v46, v46
	v_exp_f32_e32 v47, v47
	s_add_i32 s90, s76, 512
	v_lshlrev_b32_e32 v84, 2, v107
	v_add_u32_e32 v84, s90, v84
	v_add_u32_e32 v85, 0, v84
	v_add_u32_e32 v86, 4, v84
	v_add_u32_e32 v87, 8, v84
	v_add_u32_e32 v88, 12, v84
	v_cmp_gt_u32_e64 s[30:31], s98, v85
	v_cmp_gt_u32_e64 s[36:37], s98, v86
	v_cmp_gt_u32_e64 s[78:79], s98, v87
	v_cmp_gt_u32_e64 s[50:51], s98, v88
	v_cndmask_b32_e64 v32, 0, v32, s[30:31]
	v_add_u32_e32 v85, 32, v84
	v_cmp_gt_u32_e64 s[30:31], s98, v85
	v_cndmask_b32_e64 v33, 0, v33, s[36:37]
	v_add_u32_e32 v86, 36, v84
	v_cmp_gt_u32_e64 s[36:37], s98, v86
	v_cndmask_b32_e64 v34, 0, v34, s[78:79]
	v_add_u32_e32 v87, 40, v84
	v_cmp_gt_u32_e64 s[78:79], s98, v87
	v_cndmask_b32_e64 v35, 0, v35, s[50:51]
	v_add_u32_e32 v88, 44, v84
	v_cmp_gt_u32_e64 s[50:51], s98, v88
	v_cndmask_b32_e64 v36, 0, v36, s[30:31]
	v_add_u32_e32 v85, 64, v84
	v_cmp_gt_u32_e64 s[30:31], s98, v85
	v_cndmask_b32_e64 v37, 0, v37, s[36:37]
	v_add_u32_e32 v86, 68, v84
	v_cmp_gt_u32_e64 s[36:37], s98, v86
	v_cndmask_b32_e64 v38, 0, v38, s[78:79]
	v_add_u32_e32 v87, 72, v84
	v_cmp_gt_u32_e64 s[78:79], s98, v87
	v_cndmask_b32_e64 v39, 0, v39, s[50:51]
	v_add_u32_e32 v88, 76, v84
	v_cmp_gt_u32_e64 s[50:51], s98, v88
	v_cndmask_b32_e64 v40, 0, v40, s[30:31]
	v_add_u32_e32 v85, 96, v84
	v_cmp_gt_u32_e64 s[30:31], s98, v85
	v_cndmask_b32_e64 v41, 0, v41, s[36:37]
	v_add_u32_e32 v86, 100, v84
	v_cmp_gt_u32_e64 s[36:37], s98, v86
	v_cndmask_b32_e64 v42, 0, v42, s[78:79]
	v_add_u32_e32 v87, 104, v84
	v_cmp_gt_u32_e64 s[78:79], s98, v87
	v_cndmask_b32_e64 v43, 0, v43, s[50:51]
	v_add_u32_e32 v88, 108, v84
	v_cmp_gt_u32_e64 s[50:51], s98, v88
	v_nop
	v_cndmask_b32_e64 v44, 0, v44, s[30:31]
	v_cndmask_b32_e64 v45, 0, v45, s[36:37]
	v_cndmask_b32_e64 v46, 0, v46, s[78:79]
	v_cndmask_b32_e64 v47, 0, v47, s[50:51]
	v_cvt_pk_bf16_f32 v64, v32, v33
	v_cvt_pk_bf16_f32 v65, v34, v35
	v_cvt_pk_bf16_f32 v66, v36, v37
	v_cvt_pk_bf16_f32 v67, v38, v39
	v_cvt_pk_bf16_f32 v68, v40, v41
	v_cvt_pk_bf16_f32 v69, v42, v43
	v_cvt_pk_bf16_f32 v70, v44, v45
	v_cvt_pk_bf16_f32 v71, v46, v47
	v_pk_add_f32 v[232:233], v[232:233], v[32:33]
	v_pk_add_f32 v[232:233], v[232:233], v[34:35]
	v_pk_add_f32 v[232:233], v[232:233], v[36:37]
	v_pk_add_f32 v[232:233], v[232:233], v[38:39]
	v_pk_add_f32 v[232:233], v[232:233], v[40:41]
	v_pk_add_f32 v[232:233], v[232:233], v[42:43]
	v_pk_add_f32 v[232:233], v[232:233], v[44:45]
	v_pk_add_f32 v[232:233], v[232:233], v[46:47]
	v_mov_b32_e32 v115, v230
	ds_read2_b32 v[32:33], v115 offset0:0 offset1:1
	ds_read2_b32 v[34:35], v115 offset0:2 offset1:3
	ds_read2_b32 v[36:37], v115 offset0:8 offset1:9
	ds_read2_b32 v[38:39], v115 offset0:10 offset1:11
	ds_read2_b32 v[40:41], v115 offset0:16 offset1:17
	ds_read2_b32 v[42:43], v115 offset0:18 offset1:19
	ds_read2_b32 v[44:45], v115 offset0:24 offset1:25
	ds_read2_b32 v[46:47], v115 offset0:26 offset1:27
	v_mfma_f32_32x32x16_bf16 v[0:15], v[64:67], v[72:75], v[0:15]
	v_mfma_f32_32x32x16_bf16 v[16:31], v[64:67], v[76:79], v[16:31]
	v_mfma_f32_32x32x16_bf16 v[0:15], v[68:71], v[220:223], v[0:15]
	v_mfma_f32_32x32x16_bf16 v[16:31], v[68:71], v[224:227], v[16:31]
	s_add_i32 s90, s76, -512
	v_add_u32_e32 v80, s90, v243
	v_add_u32_e32 v83, s90, v244
	v_add_u32_e32 v99, s90, v245
	v_add_u32_e32 v253, s90, v246
	v_add_u32_e32 v254, s90, v148
	v_add_u32_e32 v255, s90, v151
	v_med3_i32 v80, v80, 0, s99
	v_med3_i32 v83, v83, 0, s99
	v_med3_i32 v99, v99, 0, s99
	v_med3_i32 v253, v253, 0, s99
	v_med3_i32 v254, v254, 0, s99
	v_med3_i32 v255, v255, 0, s99
	v_mad_u32_u24 v80, v80, s100, v252
	v_mad_u32_u24 v83, v83, s100, v252
	v_mad_u32_u24 v99, v99, s100, v252
	v_mad_u32_u24 v253, v253, s100, v252
	v_mad_u32_u24 v254, v254, s100, v153
	v_mad_u32_u24 v255, v255, s100, v153
	global_load_dwordx4 v[156:159], v80, s[82:83]
	global_load_dwordx4 v[160:163], v83, s[82:83]
	global_load_dwordx4 v[164:167], v99, s[82:83]
	global_load_dwordx4 v[168:171], v253, s[82:83]
	global_load_dwordx4 v[172:175], v254, s[82:83] offset:768
	global_load_dwordx4 v[176:179], v255, s[82:83] offset:768
	global_load_dwordx4 v[180:183], v254, s[82:83] offset:832
	global_load_dwordx4 v[184:187], v255, s[82:83] offset:832
	ds_read_b64_tr_b16 v[72:73], v231
	ds_read_b64_tr_b16 v[74:75], v231 offset:512
	ds_read_b64_tr_b16 v[76:77], v231 offset:2048
	ds_read_b64_tr_b16 v[78:79], v231 offset:2560
	ds_read_b64_tr_b16 v[220:221], v231 offset:1024
	ds_read_b64_tr_b16 v[222:223], v231 offset:1536
	ds_read_b64_tr_b16 v[224:225], v231 offset:3072
	ds_read_b64_tr_b16 v[226:227], v231 offset:3584
	v_exp_f32_e32 v188, v188
	v_exp_f32_e32 v189, v189
	s_waitcnt vmcnt(8)
	ds_write_b128 v247, v[116:119]
	ds_write_b128 v247, v[120:123] offset:1024
	ds_write_b128 v247, v[124:127] offset:2048
	ds_write_b128 v247, v[128:131] offset:3072
	ds_read_b128 v[116:119], v248
	ds_read_b128 v[120:123], v249
	ds_read_b128 v[124:127], v250
	ds_read_b128 v[128:131], v251
	ds_write_b128 v112, v[132:135]
	ds_write_b128 v112, v[136:139] offset:1024
	ds_write_b128 v112, v[140:143] offset:2048
	ds_write_b128 v112, v[144:147] offset:3072
	v_exp_f32_e32 v190, v190
	v_exp_f32_e32 v191, v191
	s_waitcnt lgkmcnt(4)
	v_mfma_f32_32x32x16_bf16 v[32:47], v[116:119], v[48:51], v[32:47]
	v_exp_f32_e32 v192, v192
	v_exp_f32_e32 v193, v193
	v_exp_f32_e32 v194, v194
	v_mfma_f32_32x32x16_bf16 v[32:47], v[120:123], v[52:55], v[32:47]
	v_exp_f32_e32 v195, v195
	v_exp_f32_e32 v196, v196
	v_exp_f32_e32 v197, v197
	v_mfma_f32_32x32x16_bf16 v[32:47], v[124:127], v[56:59], v[32:47]
	v_exp_f32_e32 v198, v198
	v_exp_f32_e32 v199, v199
	v_exp_f32_e32 v200, v200
	v_mfma_f32_32x32x16_bf16 v[32:47], v[128:131], v[60:63], v[32:47]
	v_exp_f32_e32 v201, v201
	v_exp_f32_e32 v202, v202
	v_exp_f32_e32 v203, v203
	s_add_i32 s90, s76, 640
	v_lshlrev_b32_e32 v84, 2, v107
	v_add_u32_e32 v84, s90, v84
	v_add_u32_e32 v85, 0, v84
	v_add_u32_e32 v86, 4, v84
	v_add_u32_e32 v87, 8, v84
	v_add_u32_e32 v88, 12, v84
	v_cmp_gt_u32_e64 s[30:31], s98, v85
	v_cmp_gt_u32_e64 s[36:37], s98, v86
	v_cmp_gt_u32_e64 s[78:79], s98, v87
	v_cmp_gt_u32_e64 s[50:51], s98, v88
	v_cndmask_b32_e64 v188, 0, v188, s[30:31]
	v_add_u32_e32 v85, 32, v84
	v_cmp_gt_u32_e64 s[30:31], s98, v85
	v_cndmask_b32_e64 v189, 0, v189, s[36:37]
	v_add_u32_e32 v86, 36, v84
	v_cmp_gt_u32_e64 s[36:37], s98, v86
	v_cndmask_b32_e64 v190, 0, v190, s[78:79]
	v_add_u32_e32 v87, 40, v84
	v_cmp_gt_u32_e64 s[78:79], s98, v87
	v_cndmask_b32_e64 v191, 0, v191, s[50:51]
	v_add_u32_e32 v88, 44, v84
	v_cmp_gt_u32_e64 s[50:51], s98, v88
	v_cndmask_b32_e64 v192, 0, v192, s[30:31]
	v_add_u32_e32 v85, 64, v84
	v_cmp_gt_u32_e64 s[30:31], s98, v85
	v_cndmask_b32_e64 v193, 0, v193, s[36:37]
	v_add_u32_e32 v86, 68, v84
	v_cmp_gt_u32_e64 s[36:37], s98, v86
	v_cndmask_b32_e64 v194, 0, v194, s[78:79]
	v_add_u32_e32 v87, 72, v84
	v_cmp_gt_u32_e64 s[78:79], s98, v87
	v_cndmask_b32_e64 v195, 0, v195, s[50:51]
	v_add_u32_e32 v88, 76, v84
	v_cmp_gt_u32_e64 s[50:51], s98, v88
	v_cndmask_b32_e64 v196, 0, v196, s[30:31]
	v_add_u32_e32 v85, 96, v84
	v_cmp_gt_u32_e64 s[30:31], s98, v85
	v_cndmask_b32_e64 v197, 0, v197, s[36:37]
	v_add_u32_e32 v86, 100, v84
	v_cmp_gt_u32_e64 s[36:37], s98, v86
	v_cndmask_b32_e64 v198, 0, v198, s[78:79]
	v_add_u32_e32 v87, 104, v84
	v_cmp_gt_u32_e64 s[78:79], s98, v87
	v_cndmask_b32_e64 v199, 0, v199, s[50:51]
	v_add_u32_e32 v88, 108, v84
	v_cmp_gt_u32_e64 s[50:51], s98, v88
	v_nop
	v_cndmask_b32_e64 v200, 0, v200, s[30:31]
	v_cndmask_b32_e64 v201, 0, v201, s[36:37]
	v_cndmask_b32_e64 v202, 0, v202, s[78:79]
	v_cndmask_b32_e64 v203, 0, v203, s[50:51]
	v_cvt_pk_bf16_f32 v64, v188, v189
	v_cvt_pk_bf16_f32 v65, v190, v191
	v_cvt_pk_bf16_f32 v66, v192, v193
	v_cvt_pk_bf16_f32 v67, v194, v195
	v_cvt_pk_bf16_f32 v68, v196, v197
	v_cvt_pk_bf16_f32 v69, v198, v199
	v_cvt_pk_bf16_f32 v70, v200, v201
	v_cvt_pk_bf16_f32 v71, v202, v203
	v_pk_add_f32 v[232:233], v[232:233], v[188:189]
	v_pk_add_f32 v[232:233], v[232:233], v[190:191]
	v_pk_add_f32 v[232:233], v[232:233], v[192:193]
	v_pk_add_f32 v[232:233], v[232:233], v[194:195]
	v_pk_add_f32 v[232:233], v[232:233], v[196:197]
	v_pk_add_f32 v[232:233], v[232:233], v[198:199]
	v_pk_add_f32 v[232:233], v[232:233], v[200:201]
	v_pk_add_f32 v[232:233], v[232:233], v[202:203]
	ds_read2_b32 v[188:189], v115 offset0:32 offset1:33
	ds_read2_b32 v[190:191], v115 offset0:34 offset1:35
	ds_read2_b32 v[192:193], v115 offset0:40 offset1:41
	ds_read2_b32 v[194:195], v115 offset0:42 offset1:43
	ds_read2_b32 v[196:197], v115 offset0:48 offset1:49
	ds_read2_b32 v[198:199], v115 offset0:50 offset1:51
	ds_read2_b32 v[200:201], v115 offset0:56 offset1:57
	ds_read2_b32 v[202:203], v115 offset0:58 offset1:59
	v_mfma_f32_32x32x16_bf16 v[0:15], v[64:67], v[72:75], v[0:15]
	v_mfma_f32_32x32x16_bf16 v[16:31], v[64:67], v[76:79], v[16:31]
	v_mfma_f32_32x32x16_bf16 v[0:15], v[68:71], v[220:223], v[0:15]
	v_mfma_f32_32x32x16_bf16 v[16:31], v[68:71], v[224:227], v[16:31]
	s_add_i32 s90, s76, 0
	v_add_u32_e32 v80, s90, v243
	v_add_u32_e32 v83, s90, v244
	v_add_u32_e32 v99, s90, v245
	v_add_u32_e32 v253, s90, v246
	v_add_u32_e32 v254, s90, v148
	v_add_u32_e32 v255, s90, v151
	v_med3_i32 v80, v80, 0, s99
	v_med3_i32 v83, v83, 0, s99
	v_med3_i32 v99, v99, 0, s99
	v_med3_i32 v253, v253, 0, s99
	v_med3_i32 v254, v254, 0, s99
	v_med3_i32 v255, v255, 0, s99
	v_mad_u32_u24 v80, v80, s100, v252
	v_mad_u32_u24 v83, v83, s100, v252
	v_mad_u32_u24 v99, v99, s100, v252
	v_mad_u32_u24 v253, v253, s100, v252
	v_mad_u32_u24 v254, v254, s100, v153
	v_mad_u32_u24 v255, v255, s100, v153
	global_load_dwordx4 v[116:119], v80, s[82:83]
	global_load_dwordx4 v[120:123], v83, s[82:83]
	global_load_dwordx4 v[124:127], v99, s[82:83]
	global_load_dwordx4 v[128:131], v253, s[82:83]
	global_load_dwordx4 v[132:135], v254, s[82:83] offset:768
	global_load_dwordx4 v[136:139], v255, s[82:83] offset:768
	global_load_dwordx4 v[140:143], v254, s[82:83] offset:832
	global_load_dwordx4 v[144:147], v255, s[82:83] offset:832
	ds_read_b64_tr_b16 v[72:73], v231
	ds_read_b64_tr_b16 v[74:75], v231 offset:512
	ds_read_b64_tr_b16 v[76:77], v231 offset:2048
	ds_read_b64_tr_b16 v[78:79], v231 offset:2560
	ds_read_b64_tr_b16 v[220:221], v231 offset:1024
	ds_read_b64_tr_b16 v[222:223], v231 offset:1536
	ds_read_b64_tr_b16 v[224:225], v231 offset:3072
	ds_read_b64_tr_b16 v[226:227], v231 offset:3584
	v_exp_f32_e32 v32, v32
	v_exp_f32_e32 v33, v33
	s_waitcnt vmcnt(8)
	ds_write_b128 v247, v[156:159]
	ds_write_b128 v247, v[160:163] offset:1024
	ds_write_b128 v247, v[164:167] offset:2048
	ds_write_b128 v247, v[168:171] offset:3072
	ds_read_b128 v[156:159], v248
	ds_read_b128 v[160:163], v249
	ds_read_b128 v[164:167], v250
	ds_read_b128 v[168:171], v251
	ds_write_b128 v112, v[172:175]
	ds_write_b128 v112, v[176:179] offset:1024
	ds_write_b128 v112, v[180:183] offset:2048
	ds_write_b128 v112, v[184:187] offset:3072
	v_exp_f32_e32 v34, v34
	v_exp_f32_e32 v35, v35
	s_waitcnt lgkmcnt(4)
	v_mfma_f32_32x32x16_bf16 v[188:203], v[156:159], v[48:51], v[188:203]
	v_exp_f32_e32 v36, v36
	v_exp_f32_e32 v37, v37
	v_exp_f32_e32 v38, v38
	v_mfma_f32_32x32x16_bf16 v[188:203], v[160:163], v[52:55], v[188:203]
	v_exp_f32_e32 v39, v39
	v_exp_f32_e32 v40, v40
	v_exp_f32_e32 v41, v41
	v_mfma_f32_32x32x16_bf16 v[188:203], v[164:167], v[56:59], v[188:203]
	v_exp_f32_e32 v42, v42
	v_exp_f32_e32 v43, v43
	v_exp_f32_e32 v44, v44
	v_mfma_f32_32x32x16_bf16 v[188:203], v[168:171], v[60:63], v[188:203]
	v_exp_f32_e32 v45, v45
	v_exp_f32_e32 v46, v46
	v_exp_f32_e32 v47, v47
	s_add_i32 s90, s76, -1024
	v_lshlrev_b32_e32 v84, 4, v107
	v_add_u32_e32 v84, s90, v84
	v_add_u32_e32 v85, 0, v84
	v_add_u32_e32 v86, 16, v84
	v_add_u32_e32 v87, 32, v84
	v_add_u32_e32 v88, 48, v84
	v_cmp_gt_u32_e64 s[30:31], s98, v85
	v_cmp_gt_u32_e64 s[36:37], s98, v86
	v_cmp_gt_u32_e64 s[78:79], s98, v87
	v_cmp_gt_u32_e64 s[50:51], s98, v88
	v_cndmask_b32_e64 v32, 0, v32, s[30:31]
	v_add_u32_e32 v85, 128, v84
	v_cmp_gt_u32_e64 s[30:31], s98, v85
	v_cndmask_b32_e64 v33, 0, v33, s[36:37]
	v_add_u32_e32 v86, 144, v84
	v_cmp_gt_u32_e64 s[36:37], s98, v86
	v_cndmask_b32_e64 v34, 0, v34, s[78:79]
	v_add_u32_e32 v87, 160, v84
	v_cmp_gt_u32_e64 s[78:79], s98, v87
	v_cndmask_b32_e64 v35, 0, v35, s[50:51]
	v_add_u32_e32 v88, 176, v84
	v_cmp_gt_u32_e64 s[50:51], s98, v88
	v_cndmask_b32_e64 v36, 0, v36, s[30:31]
	v_add_u32_e32 v85, 256, v84
	v_cmp_gt_u32_e64 s[30:31], s98, v85
	v_cndmask_b32_e64 v37, 0, v37, s[36:37]
	v_add_u32_e32 v86, 272, v84
	v_cmp_gt_u32_e64 s[36:37], s98, v86
	v_cndmask_b32_e64 v38, 0, v38, s[78:79]
	v_add_u32_e32 v87, 288, v84
	v_cmp_gt_u32_e64 s[78:79], s98, v87
	v_cndmask_b32_e64 v39, 0, v39, s[50:51]
	v_add_u32_e32 v88, 304, v84
	v_cmp_gt_u32_e64 s[50:51], s98, v88
	v_cndmask_b32_e64 v40, 0, v40, s[30:31]
	v_add_u32_e32 v85, 384, v84
	v_cmp_gt_u32_e64 s[30:31], s98, v85
	v_cndmask_b32_e64 v41, 0, v41, s[36:37]
	v_add_u32_e32 v86, 400, v84
	v_cmp_gt_u32_e64 s[36:37], s98, v86
	v_cndmask_b32_e64 v42, 0, v42, s[78:79]
	v_add_u32_e32 v87, 416, v84
	v_cmp_gt_u32_e64 s[78:79], s98, v87
	v_cndmask_b32_e64 v43, 0, v43, s[50:51]
	v_add_u32_e32 v88, 432, v84
	v_cmp_gt_u32_e64 s[50:51], s98, v88
	v_nop
	v_cndmask_b32_e64 v44, 0, v44, s[30:31]
	v_cndmask_b32_e64 v45, 0, v45, s[36:37]
	v_cndmask_b32_e64 v46, 0, v46, s[78:79]
	v_cndmask_b32_e64 v47, 0, v47, s[50:51]
	v_cvt_pk_bf16_f32 v64, v32, v33
	v_cvt_pk_bf16_f32 v65, v34, v35
	v_cvt_pk_bf16_f32 v66, v36, v37
	v_cvt_pk_bf16_f32 v67, v38, v39
	v_cvt_pk_bf16_f32 v68, v40, v41
	v_cvt_pk_bf16_f32 v69, v42, v43
	v_cvt_pk_bf16_f32 v70, v44, v45
	v_cvt_pk_bf16_f32 v71, v46, v47
	v_pk_add_f32 v[232:233], v[232:233], v[32:33]
	v_pk_add_f32 v[232:233], v[232:233], v[34:35]
	v_pk_add_f32 v[232:233], v[232:233], v[36:37]
	v_pk_add_f32 v[232:233], v[232:233], v[38:39]
	v_pk_add_f32 v[232:233], v[232:233], v[40:41]
	v_pk_add_f32 v[232:233], v[232:233], v[42:43]
	v_pk_add_f32 v[232:233], v[232:233], v[44:45]
	v_pk_add_f32 v[232:233], v[232:233], v[46:47]
	ds_read2_b32 v[32:33], v115 offset0:64 offset1:65
	ds_read2_b32 v[34:35], v115 offset0:66 offset1:67
	ds_read2_b32 v[36:37], v115 offset0:72 offset1:73
	ds_read2_b32 v[38:39], v115 offset0:74 offset1:75
	ds_read2_b32 v[40:41], v115 offset0:80 offset1:81
	ds_read2_b32 v[42:43], v115 offset0:82 offset1:83
	ds_read2_b32 v[44:45], v115 offset0:88 offset1:89
	ds_read2_b32 v[46:47], v115 offset0:90 offset1:91
	v_mfma_f32_32x32x16_bf16 v[0:15], v[64:67], v[72:75], v[0:15]
	v_mfma_f32_32x32x16_bf16 v[16:31], v[64:67], v[76:79], v[16:31]
	v_mfma_f32_32x32x16_bf16 v[0:15], v[68:71], v[220:223], v[0:15]
	v_mfma_f32_32x32x16_bf16 v[16:31], v[68:71], v[224:227], v[16:31]
	s_add_i32 s90, s76, 512
	v_add_u32_e32 v80, s90, v243
	v_add_u32_e32 v83, s90, v244
	v_add_u32_e32 v99, s90, v245
	v_add_u32_e32 v253, s90, v246
	v_add_u32_e32 v254, s90, v148
	v_add_u32_e32 v255, s90, v151
	v_med3_i32 v80, v80, 0, s99
	v_med3_i32 v83, v83, 0, s99
	v_med3_i32 v99, v99, 0, s99
	v_med3_i32 v253, v253, 0, s99
	v_med3_i32 v254, v254, 0, s99
	v_med3_i32 v255, v255, 0, s99
	v_mad_u32_u24 v80, v80, s100, v252
	v_mad_u32_u24 v83, v83, s100, v252
	v_mad_u32_u24 v99, v99, s100, v252
	v_mad_u32_u24 v253, v253, s100, v252
	v_mad_u32_u24 v254, v254, s100, v153
	v_mad_u32_u24 v255, v255, s100, v153
	global_load_dwordx4 v[156:159], v80, s[82:83]
	global_load_dwordx4 v[160:163], v83, s[82:83]
	global_load_dwordx4 v[164:167], v99, s[82:83]
	global_load_dwordx4 v[168:171], v253, s[82:83]
	global_load_dwordx4 v[172:175], v254, s[82:83] offset:768
	global_load_dwordx4 v[176:179], v255, s[82:83] offset:768
	global_load_dwordx4 v[180:183], v254, s[82:83] offset:832
	global_load_dwordx4 v[184:187], v255, s[82:83] offset:832
	ds_read_b64_tr_b16 v[72:73], v231
	ds_read_b64_tr_b16 v[74:75], v231 offset:512
	ds_read_b64_tr_b16 v[76:77], v231 offset:2048
	ds_read_b64_tr_b16 v[78:79], v231 offset:2560
	ds_read_b64_tr_b16 v[220:221], v231 offset:1024
	ds_read_b64_tr_b16 v[222:223], v231 offset:1536
	ds_read_b64_tr_b16 v[224:225], v231 offset:3072
	ds_read_b64_tr_b16 v[226:227], v231 offset:3584
	v_exp_f32_e32 v188, v188
	v_exp_f32_e32 v189, v189
	s_waitcnt vmcnt(8)
	ds_write_b128 v247, v[116:119]
	ds_write_b128 v247, v[120:123] offset:1024
	ds_write_b128 v247, v[124:127] offset:2048
	ds_write_b128 v247, v[128:131] offset:3072
	ds_read_b128 v[116:119], v248
	ds_read_b128 v[120:123], v249
	ds_read_b128 v[124:127], v250
	ds_read_b128 v[128:131], v251
	ds_write_b128 v112, v[132:135]
	ds_write_b128 v112, v[136:139] offset:1024
	ds_write_b128 v112, v[140:143] offset:2048
	ds_write_b128 v112, v[144:147] offset:3072
	v_exp_f32_e32 v190, v190
	v_exp_f32_e32 v191, v191
	s_waitcnt lgkmcnt(4)
	v_mfma_f32_32x32x16_bf16 v[32:47], v[116:119], v[48:51], v[32:47]
	v_exp_f32_e32 v192, v192
	v_exp_f32_e32 v193, v193
	v_exp_f32_e32 v194, v194
	v_mfma_f32_32x32x16_bf16 v[32:47], v[120:123], v[52:55], v[32:47]
	v_exp_f32_e32 v195, v195
	v_exp_f32_e32 v196, v196
	v_exp_f32_e32 v197, v197
	v_mfma_f32_32x32x16_bf16 v[32:47], v[124:127], v[56:59], v[32:47]
	v_exp_f32_e32 v198, v198
	v_exp_f32_e32 v199, v199
	v_exp_f32_e32 v200, v200
	v_mfma_f32_32x32x16_bf16 v[32:47], v[128:131], v[60:63], v[32:47]
	v_exp_f32_e32 v201, v201
	v_exp_f32_e32 v202, v202
	v_exp_f32_e32 v203, v203
	s_add_i32 s90, s76, -512
	v_lshlrev_b32_e32 v84, 4, v107
	v_add_u32_e32 v84, s90, v84
	v_add_u32_e32 v85, 0, v84
	v_add_u32_e32 v86, 16, v84
	v_add_u32_e32 v87, 32, v84
	v_add_u32_e32 v88, 48, v84
	v_cmp_gt_u32_e64 s[30:31], s98, v85
	v_cmp_gt_u32_e64 s[36:37], s98, v86
	v_cmp_gt_u32_e64 s[78:79], s98, v87
	v_cmp_gt_u32_e64 s[50:51], s98, v88
	v_cndmask_b32_e64 v188, 0, v188, s[30:31]
	v_add_u32_e32 v85, 128, v84
	v_cmp_gt_u32_e64 s[30:31], s98, v85
	v_cndmask_b32_e64 v189, 0, v189, s[36:37]
	v_add_u32_e32 v86, 144, v84
	v_cmp_gt_u32_e64 s[36:37], s98, v86
	v_cndmask_b32_e64 v190, 0, v190, s[78:79]
	v_add_u32_e32 v87, 160, v84
	v_cmp_gt_u32_e64 s[78:79], s98, v87
	v_cndmask_b32_e64 v191, 0, v191, s[50:51]
	v_add_u32_e32 v88, 176, v84
	v_cmp_gt_u32_e64 s[50:51], s98, v88
	v_cndmask_b32_e64 v192, 0, v192, s[30:31]
	v_add_u32_e32 v85, 256, v84
	v_cmp_gt_u32_e64 s[30:31], s98, v85
	v_cndmask_b32_e64 v193, 0, v193, s[36:37]
	v_add_u32_e32 v86, 272, v84
	v_cmp_gt_u32_e64 s[36:37], s98, v86
	v_cndmask_b32_e64 v194, 0, v194, s[78:79]
	v_add_u32_e32 v87, 288, v84
	v_cmp_gt_u32_e64 s[78:79], s98, v87
	v_cndmask_b32_e64 v195, 0, v195, s[50:51]
	v_add_u32_e32 v88, 304, v84
	v_cmp_gt_u32_e64 s[50:51], s98, v88
	v_cndmask_b32_e64 v196, 0, v196, s[30:31]
	v_add_u32_e32 v85, 384, v84
	v_cmp_gt_u32_e64 s[30:31], s98, v85
	v_cndmask_b32_e64 v197, 0, v197, s[36:37]
	v_add_u32_e32 v86, 400, v84
	v_cmp_gt_u32_e64 s[36:37], s98, v86
	v_cndmask_b32_e64 v198, 0, v198, s[78:79]
	v_add_u32_e32 v87, 416, v84
	v_cmp_gt_u32_e64 s[78:79], s98, v87
	v_cndmask_b32_e64 v199, 0, v199, s[50:51]
	v_add_u32_e32 v88, 432, v84
	v_cmp_gt_u32_e64 s[50:51], s98, v88
	v_nop
	v_cndmask_b32_e64 v200, 0, v200, s[30:31]
	v_cndmask_b32_e64 v201, 0, v201, s[36:37]
	v_cndmask_b32_e64 v202, 0, v202, s[78:79]
	v_cndmask_b32_e64 v203, 0, v203, s[50:51]
	v_cvt_pk_bf16_f32 v64, v188, v189
	v_cvt_pk_bf16_f32 v65, v190, v191
	v_cvt_pk_bf16_f32 v66, v192, v193
	v_cvt_pk_bf16_f32 v67, v194, v195
	v_cvt_pk_bf16_f32 v68, v196, v197
	v_cvt_pk_bf16_f32 v69, v198, v199
	v_cvt_pk_bf16_f32 v70, v200, v201
	v_cvt_pk_bf16_f32 v71, v202, v203
	v_pk_add_f32 v[232:233], v[232:233], v[188:189]
	v_pk_add_f32 v[232:233], v[232:233], v[190:191]
	v_pk_add_f32 v[232:233], v[232:233], v[192:193]
	v_pk_add_f32 v[232:233], v[232:233], v[194:195]
	v_pk_add_f32 v[232:233], v[232:233], v[196:197]
	v_pk_add_f32 v[232:233], v[232:233], v[198:199]
	v_pk_add_f32 v[232:233], v[232:233], v[200:201]
	v_pk_add_f32 v[232:233], v[232:233], v[202:203]
	ds_read2_b32 v[188:189], v115 offset0:96 offset1:97
	ds_read2_b32 v[190:191], v115 offset0:98 offset1:99
	ds_read2_b32 v[192:193], v115 offset0:104 offset1:105
	ds_read2_b32 v[194:195], v115 offset0:106 offset1:107
	ds_read2_b32 v[196:197], v115 offset0:112 offset1:113
	ds_read2_b32 v[198:199], v115 offset0:114 offset1:115
	ds_read2_b32 v[200:201], v115 offset0:120 offset1:121
	ds_read2_b32 v[202:203], v115 offset0:122 offset1:123
	v_mfma_f32_32x32x16_bf16 v[0:15], v[64:67], v[72:75], v[0:15]
	v_mfma_f32_32x32x16_bf16 v[16:31], v[64:67], v[76:79], v[16:31]
	v_mfma_f32_32x32x16_bf16 v[0:15], v[68:71], v[220:223], v[0:15]
	v_mfma_f32_32x32x16_bf16 v[16:31], v[68:71], v[224:227], v[16:31]
	s_add_i32 s90, s76, 1024
	v_add_u32_e32 v80, s90, v243
	v_add_u32_e32 v83, s90, v244
	v_add_u32_e32 v99, s90, v245
	v_add_u32_e32 v253, s90, v246
	v_add_u32_e32 v254, s90, v148
	v_add_u32_e32 v255, s90, v151
	v_med3_i32 v80, v80, 0, s99
	v_med3_i32 v83, v83, 0, s99
	v_med3_i32 v99, v99, 0, s99
	v_med3_i32 v253, v253, 0, s99
	v_med3_i32 v254, v254, 0, s99
	v_med3_i32 v255, v255, 0, s99
	v_mad_u32_u24 v80, v80, s100, v252
	v_mad_u32_u24 v83, v83, s100, v252
	v_mad_u32_u24 v99, v99, s100, v252
	v_mad_u32_u24 v253, v253, s100, v252
	v_mad_u32_u24 v254, v254, s100, v153
	v_mad_u32_u24 v255, v255, s100, v153
	global_load_dwordx4 v[116:119], v80, s[82:83]
	global_load_dwordx4 v[120:123], v83, s[82:83]
	global_load_dwordx4 v[124:127], v99, s[82:83]
	global_load_dwordx4 v[128:131], v253, s[82:83]
	global_load_dwordx4 v[132:135], v254, s[82:83] offset:768
	global_load_dwordx4 v[136:139], v255, s[82:83] offset:768
	global_load_dwordx4 v[140:143], v254, s[82:83] offset:832
	global_load_dwordx4 v[144:147], v255, s[82:83] offset:832
	ds_read_b64_tr_b16 v[72:73], v231
	ds_read_b64_tr_b16 v[74:75], v231 offset:512
	ds_read_b64_tr_b16 v[76:77], v231 offset:2048
	ds_read_b64_tr_b16 v[78:79], v231 offset:2560
	ds_read_b64_tr_b16 v[220:221], v231 offset:1024
	ds_read_b64_tr_b16 v[222:223], v231 offset:1536
	ds_read_b64_tr_b16 v[224:225], v231 offset:3072
	ds_read_b64_tr_b16 v[226:227], v231 offset:3584
	v_exp_f32_e32 v32, v32
	v_exp_f32_e32 v33, v33
	s_waitcnt vmcnt(8)
	ds_write_b128 v247, v[156:159]
	ds_write_b128 v247, v[160:163] offset:1024
	ds_write_b128 v247, v[164:167] offset:2048
	ds_write_b128 v247, v[168:171] offset:3072
	ds_read_b128 v[156:159], v248
	ds_read_b128 v[160:163], v249
	ds_read_b128 v[164:167], v250
	ds_read_b128 v[168:171], v251
	ds_write_b128 v112, v[172:175]
	ds_write_b128 v112, v[176:179] offset:1024
	ds_write_b128 v112, v[180:183] offset:2048
	ds_write_b128 v112, v[184:187] offset:3072
	v_exp_f32_e32 v34, v34
	v_exp_f32_e32 v35, v35
	s_waitcnt lgkmcnt(4)
	v_mfma_f32_32x32x16_bf16 v[188:203], v[156:159], v[48:51], v[188:203]
	v_exp_f32_e32 v36, v36
	v_exp_f32_e32 v37, v37
	v_exp_f32_e32 v38, v38
	v_mfma_f32_32x32x16_bf16 v[188:203], v[160:163], v[52:55], v[188:203]
	v_exp_f32_e32 v39, v39
	v_exp_f32_e32 v40, v40
	v_exp_f32_e32 v41, v41
	v_mfma_f32_32x32x16_bf16 v[188:203], v[164:167], v[56:59], v[188:203]
	v_exp_f32_e32 v42, v42
	v_exp_f32_e32 v43, v43
	v_exp_f32_e32 v44, v44
	v_mfma_f32_32x32x16_bf16 v[188:203], v[168:171], v[60:63], v[188:203]
	v_exp_f32_e32 v45, v45
	v_exp_f32_e32 v46, v46
	v_exp_f32_e32 v47, v47
	s_add_i32 s90, s76, 0
	v_lshlrev_b32_e32 v84, 4, v107
	v_add_u32_e32 v84, s90, v84
	v_add_u32_e32 v85, 0, v84
	v_add_u32_e32 v86, 16, v84
	v_add_u32_e32 v87, 32, v84
	v_add_u32_e32 v88, 48, v84
	v_cmp_gt_u32_e64 s[30:31], s98, v85
	v_cmp_gt_u32_e64 s[36:37], s98, v86
	v_cmp_gt_u32_e64 s[78:79], s98, v87
	v_cmp_gt_u32_e64 s[50:51], s98, v88
	v_cndmask_b32_e64 v32, 0, v32, s[30:31]
	v_add_u32_e32 v85, 128, v84
	v_cmp_gt_u32_e64 s[30:31], s98, v85
	v_cndmask_b32_e64 v33, 0, v33, s[36:37]
	v_add_u32_e32 v86, 144, v84
	v_cmp_gt_u32_e64 s[36:37], s98, v86
	v_cndmask_b32_e64 v34, 0, v34, s[78:79]
	v_add_u32_e32 v87, 160, v84
	v_cmp_gt_u32_e64 s[78:79], s98, v87
	v_cndmask_b32_e64 v35, 0, v35, s[50:51]
	v_add_u32_e32 v88, 176, v84
	v_cmp_gt_u32_e64 s[50:51], s98, v88
	v_cndmask_b32_e64 v36, 0, v36, s[30:31]
	v_add_u32_e32 v85, 256, v84
	v_cmp_gt_u32_e64 s[30:31], s98, v85
	v_cndmask_b32_e64 v37, 0, v37, s[36:37]
	v_add_u32_e32 v86, 272, v84
	v_cmp_gt_u32_e64 s[36:37], s98, v86
	v_cndmask_b32_e64 v38, 0, v38, s[78:79]
	v_add_u32_e32 v87, 288, v84
	v_cmp_gt_u32_e64 s[78:79], s98, v87
	v_cndmask_b32_e64 v39, 0, v39, s[50:51]
	v_add_u32_e32 v88, 304, v84
	v_cmp_gt_u32_e64 s[50:51], s98, v88
	v_cndmask_b32_e64 v40, 0, v40, s[30:31]
	v_add_u32_e32 v85, 384, v84
	v_cmp_gt_u32_e64 s[30:31], s98, v85
	v_cndmask_b32_e64 v41, 0, v41, s[36:37]
	v_add_u32_e32 v86, 400, v84
	v_cmp_gt_u32_e64 s[36:37], s98, v86
	v_cndmask_b32_e64 v42, 0, v42, s[78:79]
	v_add_u32_e32 v87, 416, v84
	v_cmp_gt_u32_e64 s[78:79], s98, v87
	v_cndmask_b32_e64 v43, 0, v43, s[50:51]
	v_add_u32_e32 v88, 432, v84
	v_cmp_gt_u32_e64 s[50:51], s98, v88
	v_nop
	v_cndmask_b32_e64 v44, 0, v44, s[30:31]
	v_cndmask_b32_e64 v45, 0, v45, s[36:37]
	v_cndmask_b32_e64 v46, 0, v46, s[78:79]
	v_cndmask_b32_e64 v47, 0, v47, s[50:51]
	v_cvt_pk_bf16_f32 v64, v32, v33
	v_cvt_pk_bf16_f32 v65, v34, v35
	v_cvt_pk_bf16_f32 v66, v36, v37
	v_cvt_pk_bf16_f32 v67, v38, v39
	v_cvt_pk_bf16_f32 v68, v40, v41
	v_cvt_pk_bf16_f32 v69, v42, v43
	v_cvt_pk_bf16_f32 v70, v44, v45
	v_cvt_pk_bf16_f32 v71, v46, v47
	v_pk_add_f32 v[232:233], v[232:233], v[32:33]
	v_pk_add_f32 v[232:233], v[232:233], v[34:35]
	v_pk_add_f32 v[232:233], v[232:233], v[36:37]
	v_pk_add_f32 v[232:233], v[232:233], v[38:39]
	v_pk_add_f32 v[232:233], v[232:233], v[40:41]
	v_pk_add_f32 v[232:233], v[232:233], v[42:43]
	v_pk_add_f32 v[232:233], v[232:233], v[44:45]
	v_pk_add_f32 v[232:233], v[232:233], v[46:47]
	ds_read2_b32 v[32:33], v115 offset0:128 offset1:129
	ds_read2_b32 v[34:35], v115 offset0:130 offset1:131
	ds_read2_b32 v[36:37], v115 offset0:136 offset1:137
	ds_read2_b32 v[38:39], v115 offset0:138 offset1:139
	ds_read2_b32 v[40:41], v115 offset0:144 offset1:145
	ds_read2_b32 v[42:43], v115 offset0:146 offset1:147
	ds_read2_b32 v[44:45], v115 offset0:152 offset1:153
	ds_read2_b32 v[46:47], v115 offset0:154 offset1:155
	v_mfma_f32_32x32x16_bf16 v[0:15], v[64:67], v[72:75], v[0:15]
	v_mfma_f32_32x32x16_bf16 v[16:31], v[64:67], v[76:79], v[16:31]
	v_mfma_f32_32x32x16_bf16 v[0:15], v[68:71], v[220:223], v[0:15]
	v_mfma_f32_32x32x16_bf16 v[16:31], v[68:71], v[224:227], v[16:31]
	ds_read_b64_tr_b16 v[72:73], v231
	ds_read_b64_tr_b16 v[74:75], v231 offset:512
	ds_read_b64_tr_b16 v[76:77], v231 offset:2048
	ds_read_b64_tr_b16 v[78:79], v231 offset:2560
	ds_read_b64_tr_b16 v[220:221], v231 offset:1024
	ds_read_b64_tr_b16 v[222:223], v231 offset:1536
	ds_read_b64_tr_b16 v[224:225], v231 offset:3072
	ds_read_b64_tr_b16 v[226:227], v231 offset:3584
	v_exp_f32_e32 v188, v188
	v_exp_f32_e32 v189, v189
	s_waitcnt vmcnt(0)
	ds_write_b128 v247, v[116:119]
	ds_write_b128 v247, v[120:123] offset:1024
	ds_write_b128 v247, v[124:127] offset:2048
	ds_write_b128 v247, v[128:131] offset:3072
	ds_read_b128 v[116:119], v248
	ds_read_b128 v[120:123], v249
	ds_read_b128 v[124:127], v250
	ds_read_b128 v[128:131], v251
	ds_write_b128 v112, v[132:135]
	ds_write_b128 v112, v[136:139] offset:1024
	ds_write_b128 v112, v[140:143] offset:2048
	ds_write_b128 v112, v[144:147] offset:3072
	v_exp_f32_e32 v190, v190
	v_exp_f32_e32 v191, v191
	s_waitcnt lgkmcnt(4)
	v_mfma_f32_32x32x16_bf16 v[32:47], v[116:119], v[48:51], v[32:47]
	v_exp_f32_e32 v192, v192
	v_exp_f32_e32 v193, v193
	v_exp_f32_e32 v194, v194
	v_mfma_f32_32x32x16_bf16 v[32:47], v[120:123], v[52:55], v[32:47]
	v_exp_f32_e32 v195, v195
	v_exp_f32_e32 v196, v196
	v_exp_f32_e32 v197, v197
	v_mfma_f32_32x32x16_bf16 v[32:47], v[124:127], v[56:59], v[32:47]
	v_exp_f32_e32 v198, v198
	v_exp_f32_e32 v199, v199
	v_exp_f32_e32 v200, v200
	v_mfma_f32_32x32x16_bf16 v[32:47], v[128:131], v[60:63], v[32:47]
	v_exp_f32_e32 v201, v201
	v_exp_f32_e32 v202, v202
	v_exp_f32_e32 v203, v203
	s_add_i32 s90, s76, 512
	v_lshlrev_b32_e32 v84, 4, v107
	v_add_u32_e32 v84, s90, v84
	v_add_u32_e32 v85, 0, v84
	v_add_u32_e32 v86, 16, v84
	v_add_u32_e32 v87, 32, v84
	v_add_u32_e32 v88, 48, v84
	v_cmp_gt_u32_e64 s[30:31], s98, v85
	v_cmp_gt_u32_e64 s[36:37], s98, v86
	v_cmp_gt_u32_e64 s[78:79], s98, v87
	v_cmp_gt_u32_e64 s[50:51], s98, v88
	v_cndmask_b32_e64 v188, 0, v188, s[30:31]
	v_add_u32_e32 v85, 128, v84
	v_cmp_gt_u32_e64 s[30:31], s98, v85
	v_cndmask_b32_e64 v189, 0, v189, s[36:37]
	v_add_u32_e32 v86, 144, v84
	v_cmp_gt_u32_e64 s[36:37], s98, v86
	v_cndmask_b32_e64 v190, 0, v190, s[78:79]
	v_add_u32_e32 v87, 160, v84
	v_cmp_gt_u32_e64 s[78:79], s98, v87
	v_cndmask_b32_e64 v191, 0, v191, s[50:51]
	v_add_u32_e32 v88, 176, v84
	v_cmp_gt_u32_e64 s[50:51], s98, v88
	v_cndmask_b32_e64 v192, 0, v192, s[30:31]
	v_add_u32_e32 v85, 256, v84
	v_cmp_gt_u32_e64 s[30:31], s98, v85
	v_cndmask_b32_e64 v193, 0, v193, s[36:37]
	v_add_u32_e32 v86, 272, v84
	v_cmp_gt_u32_e64 s[36:37], s98, v86
	v_cndmask_b32_e64 v194, 0, v194, s[78:79]
	v_add_u32_e32 v87, 288, v84
	v_cmp_gt_u32_e64 s[78:79], s98, v87
	v_cndmask_b32_e64 v195, 0, v195, s[50:51]
	v_add_u32_e32 v88, 304, v84
	v_cmp_gt_u32_e64 s[50:51], s98, v88
	v_cndmask_b32_e64 v196, 0, v196, s[30:31]
	v_add_u32_e32 v85, 384, v84
	v_cmp_gt_u32_e64 s[30:31], s98, v85
	v_cndmask_b32_e64 v197, 0, v197, s[36:37]
	v_add_u32_e32 v86, 400, v84
	v_cmp_gt_u32_e64 s[36:37], s98, v86
	v_cndmask_b32_e64 v198, 0, v198, s[78:79]
	v_add_u32_e32 v87, 416, v84
	v_cmp_gt_u32_e64 s[78:79], s98, v87
	v_cndmask_b32_e64 v199, 0, v199, s[50:51]
	v_add_u32_e32 v88, 432, v84
	v_cmp_gt_u32_e64 s[50:51], s98, v88
	v_nop
	v_cndmask_b32_e64 v200, 0, v200, s[30:31]
	v_cndmask_b32_e64 v201, 0, v201, s[36:37]
	v_cndmask_b32_e64 v202, 0, v202, s[78:79]
	v_cndmask_b32_e64 v203, 0, v203, s[50:51]
	v_cvt_pk_bf16_f32 v64, v188, v189
	v_cvt_pk_bf16_f32 v65, v190, v191
	v_cvt_pk_bf16_f32 v66, v192, v193
	v_cvt_pk_bf16_f32 v67, v194, v195
	v_cvt_pk_bf16_f32 v68, v196, v197
	v_cvt_pk_bf16_f32 v69, v198, v199
	v_cvt_pk_bf16_f32 v70, v200, v201
	v_cvt_pk_bf16_f32 v71, v202, v203
	v_pk_add_f32 v[232:233], v[232:233], v[188:189]
	v_pk_add_f32 v[232:233], v[232:233], v[190:191]
	v_pk_add_f32 v[232:233], v[232:233], v[192:193]
	v_pk_add_f32 v[232:233], v[232:233], v[194:195]
	v_pk_add_f32 v[232:233], v[232:233], v[196:197]
	v_pk_add_f32 v[232:233], v[232:233], v[198:199]
	v_pk_add_f32 v[232:233], v[232:233], v[200:201]
	v_pk_add_f32 v[232:233], v[232:233], v[202:203]
	v_mfma_f32_32x32x16_bf16 v[0:15], v[64:67], v[72:75], v[0:15]
	v_mfma_f32_32x32x16_bf16 v[16:31], v[64:67], v[76:79], v[16:31]
	v_mfma_f32_32x32x16_bf16 v[0:15], v[68:71], v[220:223], v[0:15]
	v_mfma_f32_32x32x16_bf16 v[16:31], v[68:71], v[224:227], v[16:31]
	ds_read_b64_tr_b16 v[72:73], v231
	ds_read_b64_tr_b16 v[74:75], v231 offset:512
	ds_read_b64_tr_b16 v[76:77], v231 offset:2048
	ds_read_b64_tr_b16 v[78:79], v231 offset:2560
	ds_read_b64_tr_b16 v[220:221], v231 offset:1024
	ds_read_b64_tr_b16 v[222:223], v231 offset:1536
	ds_read_b64_tr_b16 v[224:225], v231 offset:3072
	ds_read_b64_tr_b16 v[226:227], v231 offset:3584
	s_waitcnt lgkmcnt(0)
; __device__ __forceinline__ int crow(int r, int hi) { return (r & 3) + 8 * (r >> 2) + 4 * hi; }
; __device__ __forceinline__ void dil_unit(LAS unsigned char* lds, bf16_t* proj, int seq, int hd, int T0, int rho) {
;     ...
;     l += __shfl_xor(l, 32);
; #pragma unroll
;     for (int rr = 0; rr < 16; ++rr) {
;         const int j = crow(rr, hi);
	v_exp_f32_e32 v32, v32
	v_exp_f32_e32 v33, v33
	v_exp_f32_e32 v34, v34
	v_exp_f32_e32 v35, v35
	v_exp_f32_e32 v36, v36
	v_exp_f32_e32 v37, v37
	v_exp_f32_e32 v38, v38
	v_exp_f32_e32 v39, v39
	v_exp_f32_e32 v40, v40
	v_exp_f32_e32 v41, v41
	v_exp_f32_e32 v42, v42
	v_exp_f32_e32 v43, v43
	v_exp_f32_e32 v44, v44
	v_exp_f32_e32 v45, v45
	v_exp_f32_e32 v46, v46
	v_exp_f32_e32 v47, v47
	s_add_i32 s90, s76, 1024
	v_lshlrev_b32_e32 v84, 4, v107
	v_add_u32_e32 v84, s90, v84
	v_add_u32_e32 v85, 0, v84
	v_add_u32_e32 v86, 16, v84
	v_add_u32_e32 v87, 32, v84
	v_add_u32_e32 v88, 48, v84
	v_cmp_gt_u32_e64 s[30:31], s98, v85
	v_cmp_gt_u32_e64 s[36:37], s98, v86
	v_cmp_gt_u32_e64 s[78:79], s98, v87
	v_cmp_gt_u32_e64 s[50:51], s98, v88
	v_cndmask_b32_e64 v32, 0, v32, s[30:31]
	v_add_u32_e32 v85, 128, v84
	v_cmp_gt_u32_e64 s[30:31], s98, v85
	v_cndmask_b32_e64 v33, 0, v33, s[36:37]
	v_add_u32_e32 v86, 144, v84
	v_cmp_gt_u32_e64 s[36:37], s98, v86
	v_cndmask_b32_e64 v34, 0, v34, s[78:79]
	v_add_u32_e32 v87, 160, v84
	v_cmp_gt_u32_e64 s[78:79], s98, v87
	v_cndmask_b32_e64 v35, 0, v35, s[50:51]
	v_add_u32_e32 v88, 176, v84
	v_cmp_gt_u32_e64 s[50:51], s98, v88
	v_cndmask_b32_e64 v36, 0, v36, s[30:31]
	v_add_u32_e32 v85, 256, v84
	v_cmp_gt_u32_e64 s[30:31], s98, v85
	v_cndmask_b32_e64 v37, 0, v37, s[36:37]
	v_add_u32_e32 v86, 272, v84
	v_cmp_gt_u32_e64 s[36:37], s98, v86
	v_cndmask_b32_e64 v38, 0, v38, s[78:79]
	v_add_u32_e32 v87, 288, v84
	v_cmp_gt_u32_e64 s[78:79], s98, v87
	v_cndmask_b32_e64 v39, 0, v39, s[50:51]
	v_add_u32_e32 v88, 304, v84
	v_cmp_gt_u32_e64 s[50:51], s98, v88
	v_cndmask_b32_e64 v40, 0, v40, s[30:31]
	v_add_u32_e32 v85, 384, v84
	v_cmp_gt_u32_e64 s[30:31], s98, v85
	v_cndmask_b32_e64 v41, 0, v41, s[36:37]
	v_add_u32_e32 v86, 400, v84
	v_cmp_gt_u32_e64 s[36:37], s98, v86
	v_cndmask_b32_e64 v42, 0, v42, s[78:79]
	v_add_u32_e32 v87, 416, v84
	v_cmp_gt_u32_e64 s[78:79], s98, v87
	v_cndmask_b32_e64 v43, 0, v43, s[50:51]
	v_add_u32_e32 v88, 432, v84
	v_cmp_gt_u32_e64 s[50:51], s98, v88
	v_nop
	v_cndmask_b32_e64 v44, 0, v44, s[30:31]
	v_cndmask_b32_e64 v45, 0, v45, s[36:37]
	v_cndmask_b32_e64 v46, 0, v46, s[78:79]
	v_cndmask_b32_e64 v47, 0, v47, s[50:51]
	v_cvt_pk_bf16_f32 v64, v32, v33
	v_cvt_pk_bf16_f32 v65, v34, v35
	v_cvt_pk_bf16_f32 v66, v36, v37
	v_cvt_pk_bf16_f32 v67, v38, v39
	v_cvt_pk_bf16_f32 v68, v40, v41
	v_cvt_pk_bf16_f32 v69, v42, v43
	v_cvt_pk_bf16_f32 v70, v44, v45
	v_cvt_pk_bf16_f32 v71, v46, v47
	v_pk_add_f32 v[232:233], v[232:233], v[32:33]
	v_pk_add_f32 v[232:233], v[232:233], v[34:35]
	v_pk_add_f32 v[232:233], v[232:233], v[36:37]
	v_pk_add_f32 v[232:233], v[232:233], v[38:39]
	v_pk_add_f32 v[232:233], v[232:233], v[40:41]
	v_pk_add_f32 v[232:233], v[232:233], v[42:43]
	v_pk_add_f32 v[232:233], v[232:233], v[44:45]
	v_pk_add_f32 v[232:233], v[232:233], v[46:47]
	v_mfma_f32_32x32x16_bf16 v[0:15], v[64:67], v[72:75], v[0:15]
	v_mfma_f32_32x32x16_bf16 v[16:31], v[64:67], v[76:79], v[16:31]
	v_mfma_f32_32x32x16_bf16 v[0:15], v[68:71], v[220:223], v[0:15]
	v_mfma_f32_32x32x16_bf16 v[16:31], v[68:71], v[224:227], v[16:31]
	v_add_f32_e32 v113, v232, v233
	v_or_b32_e32 v114, 1, v107
	v_or_b32_e32 v97, 2, v107
	v_or_b32_e32 v96, 3, v107
	v_or_b32_e32 v95, 8, v107
	v_or_b32_e32 v94, 9, v107
	v_or_b32_e32 v93, 10, v107
	v_or_b32_e32 v92, 11, v107
	v_or_b32_e32 v91, 16, v107
	v_or_b32_e32 v90, 17, v107
	v_or_b32_e32 v89, 18, v107
	v_or_b32_e32 v88, 19, v107
	v_or_b32_e32 v87, 24, v107
	v_or_b32_e32 v86, 25, v107
	v_or_b32_e32 v85, 26, v107
	v_or_b32_e32 v84, 27, v107
	s_nop 11
	s_branch .LBB0_553

; #define LAS __attribute__((address_space(3)))
; #define GAS __attribute__((address_space(1)))
; __device__ __forceinline__ void dil_unit(LAS unsigned char* lds, bf16_t* proj, int seq, int hd, int T0, int rho) {
;     int tid_ = threadIdx.x; asm volatile("" : "+v"(tid_));
;     const int tid = tid_, lane = tid & 63, r32 = lane & 31, hi = lane >> 5, wid = __builtin_amdgcn_readfirstlane(tid >> 6);
;     bf16_t* base = proj + (size_t)seq * SEQ * NIN;
;     LAS unsigned char* wbuf = lds + wid * 4096;
;     const LAS unsigned char* vp = wbuf + ((lane >> 4) & 1) * 32 + (lane & 3) * 8 + (4 * hi + ((lane & 15) >> 2)) * 64;
;     const int P0 = T0 + rho;
;     bf16x8 qr[4];
; #pragma unroll
;     for (int ks = 0; ks < 4; ++ks) qr[ks] = *(const GAS bf16x8*)(base + (size_t)(P0 + 16 * r32) * NIN + PC_LQ + hd * 64 + 16 * ks + 8 * hi);
;     f32x16 o0 = {}, o1 = {}; float l = 0.f;
;     const bool bound = (T0 < 1024) || (T0 >= 15360);
; __device__ __forceinline__ void attn_phase(unsigned char* ws, int l, LAS unsigned char* lds, int G) {
;     ...
;     for (int bu = vb; bu < 1152; bu += G) {
;         const int sh = bu >> 6, rem = bu & 63, T0 = (rem >> 1) * 512, rho = (rem & 1) * 8 + wid;
;         dil_unit(lds, proj, sh / 6, sh % 6, T0, rho);
.LBB0_1266:
	s_lshr_b32 s82, s60, 8
	s_mul_i32 s82, s82, 13
	s_add_i32 s82, s82, s60
	s_ashr_i32 s4, s60, 6
	s_mul_hi_i32 s9, s4, 0x2aaaaaab
	s_lshl_b32 s5, s82, 8
	s_lshr_b32 s10, s9, 31
	s_and_b32 s8, s5, 0x3e00
	s_lshl_b32 s5, s82, 3
	s_add_i32 s9, s9, s10
	s_and_b32 s5, s5, 8
	s_mul_i32 s10, s9, 6
	s_add_i32 s5, s5, s61
	s_sub_i32 s10, s4, s10
	s_mul_hi_i32 s4, s9, 0x6000000
	s_mul_i32 s9, s9, 0x6000000
	v_mov_b32_e32 v2, v154
	s_add_u32 s52, s44, s9
	s_addc_u32 s53, s45, s4
	v_and_b32_e32 v105, 31, v2
	s_add_i32 s67, s5, s8
	v_lshl_add_u32 v3, v105, 4, s67
	v_mov_b64_e32 v[0:1], s[52:53]
	s_lshl_b32 s54, s10, 6
	v_bfe_u32 v106, v2, 5, 1
	v_mad_u64_u32 v[0:1], s[4:5], v3, s62, v[0:1]
	s_ashr_i32 s55, s54, 31
	v_lshl_add_u64 v[0:1], s[54:55], 1, v[0:1]
	v_lshlrev_b32_e32 v80, 4, v106
	v_lshl_add_u64 v[0:1], v[0:1], 0, v[80:81]
	global_load_dwordx4 v[48:51], v[0:1], off offset:1280
	global_load_dwordx4 v[52:55], v[0:1], off offset:1312
	global_load_dwordx4 v[56:59], v[0:1], off offset:1344
	global_load_dwordx4 v[60:63], v[0:1], off offset:1376
	v_readfirstlane_b32 s4, v2
	s_lshl_b32 s4, s4, 6
	s_and_b32 s4, s4, 0xfffff000
	v_lshlrev_b32_e32 v0, 1, v2
	v_lshlrev_b32_e32 v104, 3, v2
	v_lshlrev_b32_e32 v107, 2, v106
	v_lshrrev_b32_e32 v1, 2, v2
	v_and_b32_e32 v103, 63, v2
	v_and_b32_e32 v0, 32, v0
	v_and_b32_e32 v98, 24, v104
	v_and_or_b32 v1, v1, 3, v107
	s_add_i32 s69, s4, 0
	v_lshlrev_b32_e32 v108, 6, v1
	v_lshlrev_b32_e32 v1, 3, v106
	v_add3_u32 v109, s69, v0, v98
	s_addk_i32 s8, 0xc400
	v_lshrrev_b32_e32 v110, 2, v103
	v_lshlrev_b32_e32 v0, 4, v103
	s_mov_b64 s[4:5], -1
	s_cmp_gt_u32 s8, 0xffffc7ff
	v_lshlrev_b32_e32 v100, 1, v98
	s_mul_i32 s8, s10, 0x1c00
	v_lshlrev_b32_e32 v82, 1, v1
	v_or_b32_e32 v111, 16, v110
	v_add_u32_e32 v112, s69, v0
	s_cbranch_scc0 .LBB0_1270
	s_movk_i32 s100, 0x1800
	s_add_i32 s101, s8, 0x15c00
	s_lshl_b32 s90, s54, 1
	s_add_u32 s82, s52, s90
	s_addc_u32 s83, s53, 0
	s_add_u32 s82, s82, 0x1200
	s_addc_u32 s83, s83, 0
	s_sub_i32 s90, s67, 64
	s_mul_i32 s90, s90, 0x1800
	s_add_u32 s84, s82, s90
	s_addc_u32 s85, s83, 0
	s_sub_i32 s90, s67, 256
	s_mul_i32 s90, s90, 0x1800
	s_add_u32 s86, s82, s90
	s_addc_u32 s87, s83, 0
	s_sub_i32 s90, s67, 1024
	s_mul_i32 s90, s90, 0x1800
	s_add_u32 s88, s82, s90
	s_addc_u32 s89, s83, 0
	v_lshlrev_b32_e32 v153, 1, v98
	v_mad_u32_u24 v80, v105, s100, v82
	v_mad_u32_u24 v100, v110, s100, v153
	v_add_u32_e32 v149, 0x18000, v100
	v_lshlrev_b32_e32 v83, 2, v105
	v_mad_u32_u24 v83, v83, s100, v82
	v_lshlrev_b32_e32 v101, 2, v110
	v_mad_u32_u24 v101, v101, s100, v153
	v_add_u32_e32 v150, 0x60000, v101
	v_lshlrev_b32_e32 v99, 4, v105
	v_mad_u32_u24 v99, v99, s100, v82
	v_lshlrev_b32_e32 v148, 4, v110
	v_mad_u32_u24 v148, v148, s100, v153
	v_add_u32_e32 v151, 0x180000, v148
	v_lshrrev_b32_e32 v249, 3, v103
	v_and_b32_e32 v250, 7, v103
	v_lshlrev_b32_e32 v250, 4, v250
	v_add_u32_e32 v235, 0, v249
	v_mad_u32_u24 v235, v235, s100, v250
	v_add_u32_e32 v236, 8, v249
	v_mad_u32_u24 v236, v236, s100, v250
	v_add_u32_e32 v237, 16, v249
	v_mad_u32_u24 v237, v237, s100, v250
	v_add_u32_e32 v238, 24, v249
	v_mad_u32_u24 v238, v238, s100, v250
	v_add_u32_e32 v239, 0, v249
	v_lshlrev_b32_e32 v239, 2, v239
	v_mad_u32_u24 v239, v239, s100, v250
	v_add_u32_e32 v240, 8, v249
	v_lshlrev_b32_e32 v240, 2, v240
	v_mad_u32_u24 v240, v240, s100, v250
	v_add_u32_e32 v241, 16, v249
	v_lshlrev_b32_e32 v241, 2, v241
	v_mad_u32_u24 v241, v241, s100, v250
	v_add_u32_e32 v242, 24, v249
	v_lshlrev_b32_e32 v242, 2, v242
	v_mad_u32_u24 v242, v242, s100, v250
	v_add_u32_e32 v243, 0, v249
	v_lshlrev_b32_e32 v243, 4, v243
	v_mad_u32_u24 v243, v243, s100, v250
	v_add_u32_e32 v244, 8, v249
	v_lshlrev_b32_e32 v244, 4, v244
	v_mad_u32_u24 v244, v244, s100, v250
	v_add_u32_e32 v245, 16, v249
	v_lshlrev_b32_e32 v245, 4, v245
	v_mad_u32_u24 v245, v245, s100, v250
	v_add_u32_e32 v246, 24, v249
	v_lshlrev_b32_e32 v246, 4, v246
	v_mad_u32_u24 v246, v246, s100, v250
	v_and_b32_e32 v247, 7, v249
	v_lshlrev_b32_e32 v247, 4, v247
	v_xor_b32_e32 v247, v247, v112
	v_and_b32_e32 v153, 7, v105
	v_or_b32_e32 v248, 0, v106
	v_xor_b32_e32 v248, v248, v153
	v_lshlrev_b32_e32 v248, 4, v248
	v_lshl_add_u32 v248, v105, 7, v248
	v_add_u32_e32 v248, s69, v248
	v_or_b32_e32 v249, 2, v106
	v_xor_b32_e32 v249, v249, v153
	v_lshlrev_b32_e32 v249, 4, v249
	v_lshl_add_u32 v249, v105, 7, v249
	v_add_u32_e32 v249, s69, v249
	v_or_b32_e32 v250, 4, v106
	v_xor_b32_e32 v250, v250, v153
	v_lshlrev_b32_e32 v250, 4, v250
	v_lshl_add_u32 v250, v105, 7, v250
	v_add_u32_e32 v250, s69, v250
	v_or_b32_e32 v251, 6, v106
	v_xor_b32_e32 v251, v251, v153
	v_lshlrev_b32_e32 v251, 4, v251
	v_lshl_add_u32 v251, v105, 7, v251
	v_add_u32_e32 v251, s69, v251
	v_lshlrev_b32_e32 v153, 1, v98
	v_mul_u32_u24_e32 v228, 17, v105
	v_sub_u32_e32 v228, v107, v228
	s_mul_i32 s90, s54, 153
	s_lshr_b32 s90, s90, 1
	s_add_i32 s90, s90, 34876
	v_lshl_add_u32 v228, v228, 2, s90
	v_lshlrev_b32_e32 v229, 2, v105
	v_sub_u32_e32 v229, v107, v229
	s_add_i32 s90, s101, 5104
	v_lshl_add_u32 v229, v229, 2, s90
	v_sub_u32_e32 v230, v107, v105
	s_add_i32 s90, s101, 6364
	v_lshl_add_u32 v230, v230, 2, s90
	v_add_u32_e32 v231, v109, v108
	v_mov_b64_e32 v[232:233], 0
	v_mov_b64_e32 v[0:1], 0
	v_mov_b64_e32 v[2:3], 0
	v_mov_b64_e32 v[4:5], 0
	v_mov_b64_e32 v[6:7], 0
	v_mov_b64_e32 v[8:9], 0
	v_mov_b64_e32 v[10:11], 0
	v_mov_b64_e32 v[12:13], 0
	v_mov_b64_e32 v[14:15], 0
	v_mov_b64_e32 v[16:17], 0
	v_mov_b64_e32 v[18:19], 0
	v_mov_b64_e32 v[20:21], 0
	v_mov_b64_e32 v[22:23], 0
	v_mov_b64_e32 v[24:25], 0
	v_mov_b64_e32 v[26:27], 0
	v_mov_b64_e32 v[28:29], 0
	v_mov_b64_e32 v[30:31], 0
	global_load_dwordx4 v[116:119], v235, s[84:85]
	global_load_dwordx4 v[120:123], v236, s[84:85]
	global_load_dwordx4 v[124:127], v237, s[84:85]
	global_load_dwordx4 v[128:131], v238, s[84:85]
	global_load_dwordx4 v[132:135], v100, s[84:85] offset:768
	global_load_dwordx4 v[136:139], v149, s[84:85] offset:768
	global_load_dwordx4 v[140:143], v100, s[84:85] offset:832
	global_load_dwordx4 v[144:147], v149, s[84:85] offset:832
	s_add_u32 s84, s84, 0x30000
	s_addc_u32 s85, s85, 0
	global_load_dwordx4 v[156:159], v235, s[84:85]
	global_load_dwordx4 v[160:163], v236, s[84:85]
	global_load_dwordx4 v[164:167], v237, s[84:85]
	global_load_dwordx4 v[168:171], v238, s[84:85]
	global_load_dwordx4 v[172:175], v100, s[84:85] offset:768
	global_load_dwordx4 v[176:179], v149, s[84:85] offset:768
	global_load_dwordx4 v[180:183], v100, s[84:85] offset:832
	global_load_dwordx4 v[184:187], v149, s[84:85] offset:832
	s_add_u32 s84, s84, 0x30000
	s_addc_u32 s85, s85, 0
	v_mov_b32_e32 v115, v228
	ds_read2_b32 v[32:33], v115 offset0:0 offset1:1
	ds_read2_b32 v[34:35], v115 offset0:2 offset1:3
	ds_read2_b32 v[36:37], v115 offset0:8 offset1:9
	ds_read2_b32 v[38:39], v115 offset0:10 offset1:11
	ds_read2_b32 v[40:41], v115 offset0:17 offset1:18
	ds_read2_b32 v[42:43], v115 offset0:19 offset1:20
	ds_read2_b32 v[44:45], v115 offset0:25 offset1:26
	ds_read2_b32 v[46:47], v115 offset0:27 offset1:28
	s_waitcnt vmcnt(8)
	ds_write_b128 v247, v[116:119]
	ds_write_b128 v247, v[120:123] offset:1024
	ds_write_b128 v247, v[124:127] offset:2048
	ds_write_b128 v247, v[128:131] offset:3072
	ds_read_b128 v[116:119], v248
	ds_read_b128 v[120:123], v249
	ds_read_b128 v[124:127], v250
	ds_read_b128 v[128:131], v251
	ds_write_b128 v112, v[132:135]
	ds_write_b128 v112, v[136:139] offset:1024
	ds_write_b128 v112, v[140:143] offset:2048
	ds_write_b128 v112, v[144:147] offset:3072
	s_waitcnt lgkmcnt(4)
	v_mfma_f32_32x32x16_bf16 v[32:47], v[116:119], v[48:51], v[32:47]
	v_mfma_f32_32x32x16_bf16 v[32:47], v[120:123], v[52:55], v[32:47]
	v_mfma_f32_32x32x16_bf16 v[32:47], v[124:127], v[56:59], v[32:47]
	v_mfma_f32_32x32x16_bf16 v[32:47], v[128:131], v[60:63], v[32:47]
	ds_read2_b32 v[188:189], v115 offset0:34 offset1:35
	ds_read2_b32 v[190:191], v115 offset0:36 offset1:37
	ds_read2_b32 v[192:193], v115 offset0:42 offset1:43
	ds_read2_b32 v[194:195], v115 offset0:44 offset1:45
	ds_read2_b32 v[196:197], v115 offset0:51 offset1:52
	ds_read2_b32 v[198:199], v115 offset0:53 offset1:54
	ds_read2_b32 v[200:201], v115 offset0:59 offset1:60
	ds_read2_b32 v[202:203], v115 offset0:61 offset1:62
	global_load_dwordx4 v[116:119], v235, s[84:85]
	global_load_dwordx4 v[120:123], v236, s[84:85]
	global_load_dwordx4 v[124:127], v237, s[84:85]
	global_load_dwordx4 v[128:131], v238, s[84:85]
	global_load_dwordx4 v[132:135], v100, s[84:85] offset:768
	global_load_dwordx4 v[136:139], v149, s[84:85] offset:768
	global_load_dwordx4 v[140:143], v100, s[84:85] offset:832
	global_load_dwordx4 v[144:147], v149, s[84:85] offset:832
	s_add_u32 s84, s84, 0x30000
	s_addc_u32 s85, s85, 0
	ds_read_b64_tr_b16 v[72:73], v231
	ds_read_b64_tr_b16 v[74:75], v231 offset:512
	ds_read_b64_tr_b16 v[76:77], v231 offset:2048
	ds_read_b64_tr_b16 v[78:79], v231 offset:2560
	ds_read_b64_tr_b16 v[220:221], v231 offset:1024
	ds_read_b64_tr_b16 v[222:223], v231 offset:1536
	ds_read_b64_tr_b16 v[224:225], v231 offset:3072
	ds_read_b64_tr_b16 v[226:227], v231 offset:3584
	v_exp_f32_e32 v32, v32
	v_exp_f32_e32 v33, v33
	s_waitcnt vmcnt(8)
	ds_write_b128 v247, v[156:159]
	ds_write_b128 v247, v[160:163] offset:1024
	ds_write_b128 v247, v[164:167] offset:2048
	ds_write_b128 v247, v[168:171] offset:3072
	ds_read_b128 v[156:159], v248
	ds_read_b128 v[160:163], v249
	ds_read_b128 v[164:167], v250
	ds_read_b128 v[168:171], v251
	ds_write_b128 v112, v[172:175]
	ds_write_b128 v112, v[176:179] offset:1024
	ds_write_b128 v112, v[180:183] offset:2048
	ds_write_b128 v112, v[184:187] offset:3072
	v_exp_f32_e32 v34, v34
	v_exp_f32_e32 v35, v35
	s_waitcnt lgkmcnt(4)
	v_mfma_f32_32x32x16_bf16 v[188:203], v[156:159], v[48:51], v[188:203]
	v_exp_f32_e32 v36, v36
	v_exp_f32_e32 v37, v37
	v_exp_f32_e32 v38, v38
	v_mfma_f32_32x32x16_bf16 v[188:203], v[160:163], v[52:55], v[188:203]
	v_exp_f32_e32 v39, v39
	v_exp_f32_e32 v40, v40
	v_exp_f32_e32 v41, v41
	v_mfma_f32_32x32x16_bf16 v[188:203], v[164:167], v[56:59], v[188:203]
	v_exp_f32_e32 v42, v42
	v_exp_f32_e32 v43, v43
	v_exp_f32_e32 v44, v44
	v_mfma_f32_32x32x16_bf16 v[188:203], v[168:171], v[60:63], v[188:203]
	v_exp_f32_e32 v45, v45
	v_exp_f32_e32 v46, v46
	v_exp_f32_e32 v47, v47
	v_cvt_pk_bf16_f32 v64, v32, v33
	v_cvt_pk_bf16_f32 v65, v34, v35
	v_cvt_pk_bf16_f32 v66, v36, v37
	v_cvt_pk_bf16_f32 v67, v38, v39
	v_cvt_pk_bf16_f32 v68, v40, v41
	v_cvt_pk_bf16_f32 v69, v42, v43
	v_cvt_pk_bf16_f32 v70, v44, v45
	v_cvt_pk_bf16_f32 v71, v46, v47
	v_pk_add_f32 v[232:233], v[232:233], v[32:33]
	v_pk_add_f32 v[232:233], v[232:233], v[34:35]
	v_pk_add_f32 v[232:233], v[232:233], v[36:37]
	v_pk_add_f32 v[232:233], v[232:233], v[38:39]
	v_pk_add_f32 v[232:233], v[232:233], v[40:41]
	v_pk_add_f32 v[232:233], v[232:233], v[42:43]
	v_pk_add_f32 v[232:233], v[232:233], v[44:45]
	v_pk_add_f32 v[232:233], v[232:233], v[46:47]
	ds_read2_b32 v[32:33], v115 offset0:68 offset1:69
	ds_read2_b32 v[34:35], v115 offset0:70 offset1:71
	ds_read2_b32 v[36:37], v115 offset0:76 offset1:77
	ds_read2_b32 v[38:39], v115 offset0:78 offset1:79
	ds_read2_b32 v[40:41], v115 offset0:85 offset1:86
	ds_read2_b32 v[42:43], v115 offset0:87 offset1:88
	ds_read2_b32 v[44:45], v115 offset0:93 offset1:94
	ds_read2_b32 v[46:47], v115 offset0:95 offset1:96
	v_mfma_f32_32x32x16_bf16 v[0:15], v[64:67], v[72:75], v[0:15]
	v_mfma_f32_32x32x16_bf16 v[16:31], v[64:67], v[76:79], v[16:31]
	v_mfma_f32_32x32x16_bf16 v[0:15], v[68:71], v[220:223], v[0:15]
	v_mfma_f32_32x32x16_bf16 v[16:31], v[68:71], v[224:227], v[16:31]
	global_load_dwordx4 v[156:159], v235, s[84:85]
	global_load_dwordx4 v[160:163], v236, s[84:85]
	global_load_dwordx4 v[164:167], v237, s[84:85]
	global_load_dwordx4 v[168:171], v238, s[84:85]
	global_load_dwordx4 v[172:175], v100, s[84:85] offset:768
	global_load_dwordx4 v[176:179], v149, s[84:85] offset:768
	global_load_dwordx4 v[180:183], v100, s[84:85] offset:832
	global_load_dwordx4 v[184:187], v149, s[84:85] offset:832
	s_add_u32 s84, s84, 0x30000
	s_addc_u32 s85, s85, 0
	ds_read_b64_tr_b16 v[72:73], v231
	ds_read_b64_tr_b16 v[74:75], v231 offset:512
	ds_read_b64_tr_b16 v[76:77], v231 offset:2048
	ds_read_b64_tr_b16 v[78:79], v231 offset:2560
	ds_read_b64_tr_b16 v[220:221], v231 offset:1024
	ds_read_b64_tr_b16 v[222:223], v231 offset:1536
	ds_read_b64_tr_b16 v[224:225], v231 offset:3072
	ds_read_b64_tr_b16 v[226:227], v231 offset:3584
	v_exp_f32_e32 v188, v188
	v_exp_f32_e32 v189, v189
	s_waitcnt vmcnt(8)
	ds_write_b128 v247, v[116:119]
	ds_write_b128 v247, v[120:123] offset:1024
	ds_write_b128 v247, v[124:127] offset:2048
	ds_write_b128 v247, v[128:131] offset:3072
	ds_read_b128 v[116:119], v248
	ds_read_b128 v[120:123], v249
	ds_read_b128 v[124:127], v250
	ds_read_b128 v[128:131], v251
	ds_write_b128 v112, v[132:135]
	ds_write_b128 v112, v[136:139] offset:1024
	ds_write_b128 v112, v[140:143] offset:2048
	ds_write_b128 v112, v[144:147] offset:3072
	v_exp_f32_e32 v190, v190
	v_exp_f32_e32 v191, v191
	s_waitcnt lgkmcnt(4)
	v_mfma_f32_32x32x16_bf16 v[32:47], v[116:119], v[48:51], v[32:47]
	v_exp_f32_e32 v192, v192
	v_exp_f32_e32 v193, v193
	v_exp_f32_e32 v194, v194
	v_mfma_f32_32x32x16_bf16 v[32:47], v[120:123], v[52:55], v[32:47]
	v_exp_f32_e32 v195, v195
	v_exp_f32_e32 v196, v196
	v_exp_f32_e32 v197, v197
	v_mfma_f32_32x32x16_bf16 v[32:47], v[124:127], v[56:59], v[32:47]
	v_exp_f32_e32 v198, v198
	v_exp_f32_e32 v199, v199
	v_exp_f32_e32 v200, v200
	v_mfma_f32_32x32x16_bf16 v[32:47], v[128:131], v[60:63], v[32:47]
	v_exp_f32_e32 v201, v201
	v_exp_f32_e32 v202, v202
	v_exp_f32_e32 v203, v203
	v_cvt_pk_bf16_f32 v64, v188, v189
	v_cvt_pk_bf16_f32 v65, v190, v191
	v_cvt_pk_bf16_f32 v66, v192, v193
	v_cvt_pk_bf16_f32 v67, v194, v195
	v_cvt_pk_bf16_f32 v68, v196, v197
	v_cvt_pk_bf16_f32 v69, v198, v199
	v_cvt_pk_bf16_f32 v70, v200, v201
	v_cvt_pk_bf16_f32 v71, v202, v203
	v_pk_add_f32 v[232:233], v[232:233], v[188:189]
	v_pk_add_f32 v[232:233], v[232:233], v[190:191]
	v_pk_add_f32 v[232:233], v[232:233], v[192:193]
	v_pk_add_f32 v[232:233], v[232:233], v[194:195]
	v_pk_add_f32 v[232:233], v[232:233], v[196:197]
	v_pk_add_f32 v[232:233], v[232:233], v[198:199]
	v_pk_add_f32 v[232:233], v[232:233], v[200:201]
	v_pk_add_f32 v[232:233], v[232:233], v[202:203]
	ds_read2_b32 v[188:189], v115 offset0:102 offset1:103
	ds_read2_b32 v[190:191], v115 offset0:104 offset1:105
	ds_read2_b32 v[192:193], v115 offset0:110 offset1:111
	ds_read2_b32 v[194:195], v115 offset0:112 offset1:113
	ds_read2_b32 v[196:197], v115 offset0:119 offset1:120
	ds_read2_b32 v[198:199], v115 offset0:121 offset1:122
	ds_read2_b32 v[200:201], v115 offset0:127 offset1:128
	ds_read2_b32 v[202:203], v115 offset0:129 offset1:130
	v_mfma_f32_32x32x16_bf16 v[0:15], v[64:67], v[72:75], v[0:15]
	v_mfma_f32_32x32x16_bf16 v[16:31], v[64:67], v[76:79], v[16:31]
	v_mfma_f32_32x32x16_bf16 v[0:15], v[68:71], v[220:223], v[0:15]
	v_mfma_f32_32x32x16_bf16 v[16:31], v[68:71], v[224:227], v[16:31]
	global_load_dwordx4 v[116:119], v235, s[84:85]
	global_load_dwordx4 v[120:123], v236, s[84:85]
	global_load_dwordx4 v[124:127], v237, s[84:85]
	global_load_dwordx4 v[128:131], v238, s[84:85]
	global_load_dwordx4 v[132:135], v100, s[84:85] offset:768
	global_load_dwordx4 v[136:139], v149, s[84:85] offset:768
	global_load_dwordx4 v[140:143], v100, s[84:85] offset:832
	global_load_dwordx4 v[144:147], v149, s[84:85] offset:832
	s_add_u32 s84, s84, 0x30000
	s_addc_u32 s85, s85, 0
	ds_read_b64_tr_b16 v[72:73], v231
	ds_read_b64_tr_b16 v[74:75], v231 offset:512
	ds_read_b64_tr_b16 v[76:77], v231 offset:2048
	ds_read_b64_tr_b16 v[78:79], v231 offset:2560
	ds_read_b64_tr_b16 v[220:221], v231 offset:1024
	ds_read_b64_tr_b16 v[222:223], v231 offset:1536
	ds_read_b64_tr_b16 v[224:225], v231 offset:3072
	ds_read_b64_tr_b16 v[226:227], v231 offset:3584
	v_exp_f32_e32 v32, v32
	v_exp_f32_e32 v33, v33
	s_waitcnt vmcnt(8)
	ds_write_b128 v247, v[156:159]
	ds_write_b128 v247, v[160:163] offset:1024
	ds_write_b128 v247, v[164:167] offset:2048
	ds_write_b128 v247, v[168:171] offset:3072
	ds_read_b128 v[156:159], v248
	ds_read_b128 v[160:163], v249
	ds_read_b128 v[164:167], v250
	ds_read_b128 v[168:171], v251
	ds_write_b128 v112, v[172:175]
	ds_write_b128 v112, v[176:179] offset:1024
	ds_write_b128 v112, v[180:183] offset:2048
	ds_write_b128 v112, v[184:187] offset:3072
	v_exp_f32_e32 v34, v34
	v_exp_f32_e32 v35, v35
	s_waitcnt lgkmcnt(4)
	v_mfma_f32_32x32x16_bf16 v[188:203], v[156:159], v[48:51], v[188:203]
	v_exp_f32_e32 v36, v36
	v_exp_f32_e32 v37, v37
	v_exp_f32_e32 v38, v38
	v_mfma_f32_32x32x16_bf16 v[188:203], v[160:163], v[52:55], v[188:203]
	v_exp_f32_e32 v39, v39
	v_exp_f32_e32 v40, v40
	v_exp_f32_e32 v41, v41
	v_mfma_f32_32x32x16_bf16 v[188:203], v[164:167], v[56:59], v[188:203]
	v_exp_f32_e32 v42, v42
	v_exp_f32_e32 v43, v43
	v_exp_f32_e32 v44, v44
	v_mfma_f32_32x32x16_bf16 v[188:203], v[168:171], v[60:63], v[188:203]
	v_exp_f32_e32 v45, v45
	v_exp_f32_e32 v46, v46
	v_exp_f32_e32 v47, v47
	v_cvt_pk_bf16_f32 v64, v32, v33
	v_cvt_pk_bf16_f32 v65, v34, v35
	v_cvt_pk_bf16_f32 v66, v36, v37
	v_cvt_pk_bf16_f32 v67, v38, v39
	v_cvt_pk_bf16_f32 v68, v40, v41
	v_cvt_pk_bf16_f32 v69, v42, v43
	v_cvt_pk_bf16_f32 v70, v44, v45
	v_cvt_pk_bf16_f32 v71, v46, v47
	v_pk_add_f32 v[232:233], v[232:233], v[32:33]
	v_pk_add_f32 v[232:233], v[232:233], v[34:35]
	v_pk_add_f32 v[232:233], v[232:233], v[36:37]
	v_pk_add_f32 v[232:233], v[232:233], v[38:39]
	v_pk_add_f32 v[232:233], v[232:233], v[40:41]
	v_pk_add_f32 v[232:233], v[232:233], v[42:43]
	v_pk_add_f32 v[232:233], v[232:233], v[44:45]
	v_pk_add_f32 v[232:233], v[232:233], v[46:47]
	ds_read2_b32 v[32:33], v115 offset0:136 offset1:137
	ds_read2_b32 v[34:35], v115 offset0:138 offset1:139
	ds_read2_b32 v[36:37], v115 offset0:144 offset1:145
	ds_read2_b32 v[38:39], v115 offset0:146 offset1:147
	ds_read2_b32 v[40:41], v115 offset0:153 offset1:154
	ds_read2_b32 v[42:43], v115 offset0:155 offset1:156
	ds_read2_b32 v[44:45], v115 offset0:161 offset1:162
	ds_read2_b32 v[46:47], v115 offset0:163 offset1:164
	v_mfma_f32_32x32x16_bf16 v[0:15], v[64:67], v[72:75], v[0:15]
	v_mfma_f32_32x32x16_bf16 v[16:31], v[64:67], v[76:79], v[16:31]
	v_mfma_f32_32x32x16_bf16 v[0:15], v[68:71], v[220:223], v[0:15]
	v_mfma_f32_32x32x16_bf16 v[16:31], v[68:71], v[224:227], v[16:31]
	global_load_dwordx4 v[156:159], v235, s[84:85]
	global_load_dwordx4 v[160:163], v236, s[84:85]
	global_load_dwordx4 v[164:167], v237, s[84:85]
	global_load_dwordx4 v[168:171], v238, s[84:85]
	global_load_dwordx4 v[172:175], v100, s[84:85] offset:768
	global_load_dwordx4 v[176:179], v149, s[84:85] offset:768
	global_load_dwordx4 v[180:183], v100, s[84:85] offset:832
	global_load_dwordx4 v[184:187], v149, s[84:85] offset:832
	s_add_u32 s84, s84, 0x30000
	s_addc_u32 s85, s85, 0
	ds_read_b64_tr_b16 v[72:73], v231
	ds_read_b64_tr_b16 v[74:75], v231 offset:512
	ds_read_b64_tr_b16 v[76:77], v231 offset:2048
	ds_read_b64_tr_b16 v[78:79], v231 offset:2560
	ds_read_b64_tr_b16 v[220:221], v231 offset:1024
	ds_read_b64_tr_b16 v[222:223], v231 offset:1536
	ds_read_b64_tr_b16 v[224:225], v231 offset:3072
	ds_read_b64_tr_b16 v[226:227], v231 offset:3584
	v_exp_f32_e32 v188, v188
	v_exp_f32_e32 v189, v189
	s_waitcnt vmcnt(8)
	ds_write_b128 v247, v[116:119]
	ds_write_b128 v247, v[120:123] offset:1024
	ds_write_b128 v247, v[124:127] offset:2048
	ds_write_b128 v247, v[128:131] offset:3072
	ds_read_b128 v[116:119], v248
	ds_read_b128 v[120:123], v249
	ds_read_b128 v[124:127], v250
	ds_read_b128 v[128:131], v251
	ds_write_b128 v112, v[132:135]
	ds_write_b128 v112, v[136:139] offset:1024
	ds_write_b128 v112, v[140:143] offset:2048
	ds_write_b128 v112, v[144:147] offset:3072
	v_exp_f32_e32 v190, v190
	v_exp_f32_e32 v191, v191
	s_waitcnt lgkmcnt(4)
	v_mfma_f32_32x32x16_bf16 v[32:47], v[116:119], v[48:51], v[32:47]
	v_exp_f32_e32 v192, v192
	v_exp_f32_e32 v193, v193
	v_exp_f32_e32 v194, v194
	v_mfma_f32_32x32x16_bf16 v[32:47], v[120:123], v[52:55], v[32:47]
	v_exp_f32_e32 v195, v195
	v_exp_f32_e32 v196, v196
	v_exp_f32_e32 v197, v197
	v_mfma_f32_32x32x16_bf16 v[32:47], v[124:127], v[56:59], v[32:47]
	v_exp_f32_e32 v198, v198
	v_exp_f32_e32 v199, v199
	v_exp_f32_e32 v200, v200
	v_mfma_f32_32x32x16_bf16 v[32:47], v[128:131], v[60:63], v[32:47]
	v_exp_f32_e32 v201, v201
	v_exp_f32_e32 v202, v202
	v_exp_f32_e32 v203, v203
	v_cvt_pk_bf16_f32 v64, v188, v189
	v_cvt_pk_bf16_f32 v65, v190, v191
	v_cvt_pk_bf16_f32 v66, v192, v193
	v_cvt_pk_bf16_f32 v67, v194, v195
	v_cvt_pk_bf16_f32 v68, v196, v197
	v_cvt_pk_bf16_f32 v69, v198, v199
	v_cvt_pk_bf16_f32 v70, v200, v201
	v_cvt_pk_bf16_f32 v71, v202, v203
	v_pk_add_f32 v[232:233], v[232:233], v[188:189]
	v_pk_add_f32 v[232:233], v[232:233], v[190:191]
	v_pk_add_f32 v[232:233], v[232:233], v[192:193]
	v_pk_add_f32 v[232:233], v[232:233], v[194:195]
	v_pk_add_f32 v[232:233], v[232:233], v[196:197]
	v_pk_add_f32 v[232:233], v[232:233], v[198:199]
	v_pk_add_f32 v[232:233], v[232:233], v[200:201]
	v_pk_add_f32 v[232:233], v[232:233], v[202:203]
	ds_read2_b32 v[188:189], v115 offset0:170 offset1:171
	ds_read2_b32 v[190:191], v115 offset0:172 offset1:173
	ds_read2_b32 v[192:193], v115 offset0:178 offset1:179
	ds_read2_b32 v[194:195], v115 offset0:180 offset1:181
	ds_read2_b32 v[196:197], v115 offset0:187 offset1:188
	ds_read2_b32 v[198:199], v115 offset0:189 offset1:190
	ds_read2_b32 v[200:201], v115 offset0:195 offset1:196
	ds_read2_b32 v[202:203], v115 offset0:197 offset1:198
	v_mfma_f32_32x32x16_bf16 v[0:15], v[64:67], v[72:75], v[0:15]
	v_mfma_f32_32x32x16_bf16 v[16:31], v[64:67], v[76:79], v[16:31]
	v_mfma_f32_32x32x16_bf16 v[0:15], v[68:71], v[220:223], v[0:15]
	v_mfma_f32_32x32x16_bf16 v[16:31], v[68:71], v[224:227], v[16:31]
	global_load_dwordx4 v[116:119], v235, s[84:85]
	global_load_dwordx4 v[120:123], v236, s[84:85]
	global_load_dwordx4 v[124:127], v237, s[84:85]
	global_load_dwordx4 v[128:131], v238, s[84:85]
	global_load_dwordx4 v[132:135], v100, s[84:85] offset:768
	global_load_dwordx4 v[136:139], v149, s[84:85] offset:768
	global_load_dwordx4 v[140:143], v100, s[84:85] offset:832
	global_load_dwordx4 v[144:147], v149, s[84:85] offset:832
	s_add_u32 s84, s84, 0x30000
	s_addc_u32 s85, s85, 0
	ds_read_b64_tr_b16 v[72:73], v231
	ds_read_b64_tr_b16 v[74:75], v231 offset:512
	ds_read_b64_tr_b16 v[76:77], v231 offset:2048
	ds_read_b64_tr_b16 v[78:79], v231 offset:2560
	ds_read_b64_tr_b16 v[220:221], v231 offset:1024
	ds_read_b64_tr_b16 v[222:223], v231 offset:1536
	ds_read_b64_tr_b16 v[224:225], v231 offset:3072
	ds_read_b64_tr_b16 v[226:227], v231 offset:3584
	v_exp_f32_e32 v32, v32
	v_exp_f32_e32 v33, v33
	s_waitcnt vmcnt(8)
	ds_write_b128 v247, v[156:159]
	ds_write_b128 v247, v[160:163] offset:1024
	ds_write_b128 v247, v[164:167] offset:2048
	ds_write_b128 v247, v[168:171] offset:3072
	ds_read_b128 v[156:159], v248
	ds_read_b128 v[160:163], v249
	ds_read_b128 v[164:167], v250
	ds_read_b128 v[168:171], v251
	ds_write_b128 v112, v[172:175]
	ds_write_b128 v112, v[176:179] offset:1024
	ds_write_b128 v112, v[180:183] offset:2048
	ds_write_b128 v112, v[184:187] offset:3072
	v_exp_f32_e32 v34, v34
	v_exp_f32_e32 v35, v35
	s_waitcnt lgkmcnt(4)
	v_mfma_f32_32x32x16_bf16 v[188:203], v[156:159], v[48:51], v[188:203]
	v_exp_f32_e32 v36, v36
	v_exp_f32_e32 v37, v37
	v_exp_f32_e32 v38, v38
	v_mfma_f32_32x32x16_bf16 v[188:203], v[160:163], v[52:55], v[188:203]
	v_exp_f32_e32 v39, v39
	v_exp_f32_e32 v40, v40
	v_exp_f32_e32 v41, v41
	v_mfma_f32_32x32x16_bf16 v[188:203], v[164:167], v[56:59], v[188:203]
	v_exp_f32_e32 v42, v42
	v_exp_f32_e32 v43, v43
	v_exp_f32_e32 v44, v44
	v_mfma_f32_32x32x16_bf16 v[188:203], v[168:171], v[60:63], v[188:203]
	v_exp_f32_e32 v45, v45
	v_exp_f32_e32 v46, v46
	v_exp_f32_e32 v47, v47
	v_cvt_pk_bf16_f32 v64, v32, v33
	v_cvt_pk_bf16_f32 v65, v34, v35
	v_cvt_pk_bf16_f32 v66, v36, v37
	v_cvt_pk_bf16_f32 v67, v38, v39
	v_cvt_pk_bf16_f32 v68, v40, v41
	v_cvt_pk_bf16_f32 v69, v42, v43
	v_cvt_pk_bf16_f32 v70, v44, v45
	v_cvt_pk_bf16_f32 v71, v46, v47
	v_pk_add_f32 v[232:233], v[232:233], v[32:33]
	v_pk_add_f32 v[232:233], v[232:233], v[34:35]
	v_pk_add_f32 v[232:233], v[232:233], v[36:37]
	v_pk_add_f32 v[232:233], v[232:233], v[38:39]
	v_pk_add_f32 v[232:233], v[232:233], v[40:41]
	v_pk_add_f32 v[232:233], v[232:233], v[42:43]
	v_pk_add_f32 v[232:233], v[232:233], v[44:45]
	v_pk_add_f32 v[232:233], v[232:233], v[46:47]
	ds_read2_b32 v[32:33], v115 offset0:204 offset1:205
	ds_read2_b32 v[34:35], v115 offset0:206 offset1:207
	ds_read2_b32 v[36:37], v115 offset0:212 offset1:213
	ds_read2_b32 v[38:39], v115 offset0:214 offset1:215
	ds_read2_b32 v[40:41], v115 offset0:221 offset1:222
	ds_read2_b32 v[42:43], v115 offset0:223 offset1:224
	ds_read2_b32 v[44:45], v115 offset0:229 offset1:230
	ds_read2_b32 v[46:47], v115 offset0:231 offset1:232
	v_mfma_f32_32x32x16_bf16 v[0:15], v[64:67], v[72:75], v[0:15]
	v_mfma_f32_32x32x16_bf16 v[16:31], v[64:67], v[76:79], v[16:31]
	v_mfma_f32_32x32x16_bf16 v[0:15], v[68:71], v[220:223], v[0:15]
	v_mfma_f32_32x32x16_bf16 v[16:31], v[68:71], v[224:227], v[16:31]
	global_load_dwordx4 v[156:159], v235, s[84:85]
	global_load_dwordx4 v[160:163], v236, s[84:85]
	global_load_dwordx4 v[164:167], v237, s[84:85]
	global_load_dwordx4 v[168:171], v238, s[84:85]
	global_load_dwordx4 v[172:175], v100, s[84:85] offset:768
	global_load_dwordx4 v[176:179], v149, s[84:85] offset:768
	global_load_dwordx4 v[180:183], v100, s[84:85] offset:832
	global_load_dwordx4 v[184:187], v149, s[84:85] offset:832
	s_add_u32 s84, s84, 0x30000
	s_addc_u32 s85, s85, 0
	ds_read_b64_tr_b16 v[72:73], v231
	ds_read_b64_tr_b16 v[74:75], v231 offset:512
	ds_read_b64_tr_b16 v[76:77], v231 offset:2048
	ds_read_b64_tr_b16 v[78:79], v231 offset:2560
	ds_read_b64_tr_b16 v[220:221], v231 offset:1024
	ds_read_b64_tr_b16 v[222:223], v231 offset:1536
	ds_read_b64_tr_b16 v[224:225], v231 offset:3072
	ds_read_b64_tr_b16 v[226:227], v231 offset:3584
	v_exp_f32_e32 v188, v188
	v_exp_f32_e32 v189, v189
	s_waitcnt vmcnt(8)
	ds_write_b128 v247, v[116:119]
	ds_write_b128 v247, v[120:123] offset:1024
	ds_write_b128 v247, v[124:127] offset:2048
	ds_write_b128 v247, v[128:131] offset:3072
	ds_read_b128 v[116:119], v248
	ds_read_b128 v[120:123], v249
	ds_read_b128 v[124:127], v250
	ds_read_b128 v[128:131], v251
	ds_write_b128 v112, v[132:135]
	ds_write_b128 v112, v[136:139] offset:1024
	ds_write_b128 v112, v[140:143] offset:2048
	ds_write_b128 v112, v[144:147] offset:3072
	v_exp_f32_e32 v190, v190
	v_exp_f32_e32 v191, v191
	s_waitcnt lgkmcnt(4)
	v_mfma_f32_32x32x16_bf16 v[32:47], v[116:119], v[48:51], v[32:47]
	v_exp_f32_e32 v192, v192
	v_exp_f32_e32 v193, v193
	v_exp_f32_e32 v194, v194
	v_mfma_f32_32x32x16_bf16 v[32:47], v[120:123], v[52:55], v[32:47]
	v_exp_f32_e32 v195, v195
	v_exp_f32_e32 v196, v196
	v_exp_f32_e32 v197, v197
	v_mfma_f32_32x32x16_bf16 v[32:47], v[124:127], v[56:59], v[32:47]
	v_exp_f32_e32 v198, v198
	v_exp_f32_e32 v199, v199
	v_exp_f32_e32 v200, v200
	v_mfma_f32_32x32x16_bf16 v[32:47], v[128:131], v[60:63], v[32:47]
	v_exp_f32_e32 v201, v201
	v_exp_f32_e32 v202, v202
	v_exp_f32_e32 v203, v203
	v_cvt_pk_bf16_f32 v64, v188, v189
	v_cvt_pk_bf16_f32 v65, v190, v191
	v_cvt_pk_bf16_f32 v66, v192, v193
	v_cvt_pk_bf16_f32 v67, v194, v195
	v_cvt_pk_bf16_f32 v68, v196, v197
	v_cvt_pk_bf16_f32 v69, v198, v199
	v_cvt_pk_bf16_f32 v70, v200, v201
	v_cvt_pk_bf16_f32 v71, v202, v203
	v_pk_add_f32 v[232:233], v[232:233], v[188:189]
	v_pk_add_f32 v[232:233], v[232:233], v[190:191]
	v_pk_add_f32 v[232:233], v[232:233], v[192:193]
	v_pk_add_f32 v[232:233], v[232:233], v[194:195]
	v_pk_add_f32 v[232:233], v[232:233], v[196:197]
	v_pk_add_f32 v[232:233], v[232:233], v[198:199]
	v_pk_add_f32 v[232:233], v[232:233], v[200:201]
	v_pk_add_f32 v[232:233], v[232:233], v[202:203]
	v_add_u32_e32 v115, 952, v115
	ds_read2_b32 v[188:189], v115 offset0:0 offset1:1
	ds_read2_b32 v[190:191], v115 offset0:2 offset1:3
	ds_read2_b32 v[192:193], v115 offset0:8 offset1:9
	ds_read2_b32 v[194:195], v115 offset0:10 offset1:11
	ds_read2_b32 v[196:197], v115 offset0:17 offset1:18
	ds_read2_b32 v[198:199], v115 offset0:19 offset1:20
	ds_read2_b32 v[200:201], v115 offset0:25 offset1:26
	ds_read2_b32 v[202:203], v115 offset0:27 offset1:28
	v_mfma_f32_32x32x16_bf16 v[0:15], v[64:67], v[72:75], v[0:15]
	v_mfma_f32_32x32x16_bf16 v[16:31], v[64:67], v[76:79], v[16:31]
	v_mfma_f32_32x32x16_bf16 v[0:15], v[68:71], v[220:223], v[0:15]
	v_mfma_f32_32x32x16_bf16 v[16:31], v[68:71], v[224:227], v[16:31]
	global_load_dwordx4 v[116:119], v235, s[84:85]
	global_load_dwordx4 v[120:123], v236, s[84:85]
	global_load_dwordx4 v[124:127], v237, s[84:85]
	global_load_dwordx4 v[128:131], v238, s[84:85]
	global_load_dwordx4 v[132:135], v100, s[84:85] offset:768
	global_load_dwordx4 v[136:139], v149, s[84:85] offset:768
	global_load_dwordx4 v[140:143], v100, s[84:85] offset:832
	global_load_dwordx4 v[144:147], v149, s[84:85] offset:832
	s_add_u32 s84, s84, 0x30000
	s_addc_u32 s85, s85, 0
	ds_read_b64_tr_b16 v[72:73], v231
	ds_read_b64_tr_b16 v[74:75], v231 offset:512
	ds_read_b64_tr_b16 v[76:77], v231 offset:2048
	ds_read_b64_tr_b16 v[78:79], v231 offset:2560
	ds_read_b64_tr_b16 v[220:221], v231 offset:1024
	ds_read_b64_tr_b16 v[222:223], v231 offset:1536
	ds_read_b64_tr_b16 v[224:225], v231 offset:3072
	ds_read_b64_tr_b16 v[226:227], v231 offset:3584
	v_exp_f32_e32 v32, v32
	v_exp_f32_e32 v33, v33
	s_waitcnt vmcnt(8)
	ds_write_b128 v247, v[156:159]
	ds_write_b128 v247, v[160:163] offset:1024
	ds_write_b128 v247, v[164:167] offset:2048
	ds_write_b128 v247, v[168:171] offset:3072
	ds_read_b128 v[156:159], v248
	ds_read_b128 v[160:163], v249
	ds_read_b128 v[164:167], v250
	ds_read_b128 v[168:171], v251
	ds_write_b128 v112, v[172:175]
	ds_write_b128 v112, v[176:179] offset:1024
	ds_write_b128 v112, v[180:183] offset:2048
	ds_write_b128 v112, v[184:187] offset:3072
	v_exp_f32_e32 v34, v34
	v_exp_f32_e32 v35, v35
	s_waitcnt lgkmcnt(4)
	v_mfma_f32_32x32x16_bf16 v[188:203], v[156:159], v[48:51], v[188:203]
	v_exp_f32_e32 v36, v36
	v_exp_f32_e32 v37, v37
	v_exp_f32_e32 v38, v38
	v_mfma_f32_32x32x16_bf16 v[188:203], v[160:163], v[52:55], v[188:203]
	v_exp_f32_e32 v39, v39
	v_exp_f32_e32 v40, v40
	v_exp_f32_e32 v41, v41
	v_mfma_f32_32x32x16_bf16 v[188:203], v[164:167], v[56:59], v[188:203]
	v_exp_f32_e32 v42, v42
	v_exp_f32_e32 v43, v43
	v_exp_f32_e32 v44, v44
	v_mfma_f32_32x32x16_bf16 v[188:203], v[168:171], v[60:63], v[188:203]
	v_exp_f32_e32 v45, v45
	v_exp_f32_e32 v46, v46
	v_exp_f32_e32 v47, v47
	v_cvt_pk_bf16_f32 v64, v32, v33
	v_cvt_pk_bf16_f32 v65, v34, v35
	v_cvt_pk_bf16_f32 v66, v36, v37
	v_cvt_pk_bf16_f32 v67, v38, v39
	v_cvt_pk_bf16_f32 v68, v40, v41
	v_cvt_pk_bf16_f32 v69, v42, v43
	v_cvt_pk_bf16_f32 v70, v44, v45
	v_cvt_pk_bf16_f32 v71, v46, v47
	v_pk_add_f32 v[232:233], v[232:233], v[32:33]
	v_pk_add_f32 v[232:233], v[232:233], v[34:35]
	v_pk_add_f32 v[232:233], v[232:233], v[36:37]
	v_pk_add_f32 v[232:233], v[232:233], v[38:39]
	v_pk_add_f32 v[232:233], v[232:233], v[40:41]
	v_pk_add_f32 v[232:233], v[232:233], v[42:43]
	v_pk_add_f32 v[232:233], v[232:233], v[44:45]
	v_pk_add_f32 v[232:233], v[232:233], v[46:47]
	ds_read2_b32 v[32:33], v115 offset0:34 offset1:35
	ds_read2_b32 v[34:35], v115 offset0:36 offset1:37
	ds_read2_b32 v[36:37], v115 offset0:42 offset1:43
	ds_read2_b32 v[38:39], v115 offset0:44 offset1:45
	ds_read2_b32 v[40:41], v115 offset0:51 offset1:52
	ds_read2_b32 v[42:43], v115 offset0:53 offset1:54
	ds_read2_b32 v[44:45], v115 offset0:59 offset1:60
	ds_read2_b32 v[46:47], v115 offset0:61 offset1:62
	v_mfma_f32_32x32x16_bf16 v[0:15], v[64:67], v[72:75], v[0:15]
	v_mfma_f32_32x32x16_bf16 v[16:31], v[64:67], v[76:79], v[16:31]
	v_mfma_f32_32x32x16_bf16 v[0:15], v[68:71], v[220:223], v[0:15]
	v_mfma_f32_32x32x16_bf16 v[16:31], v[68:71], v[224:227], v[16:31]
	global_load_dwordx4 v[156:159], v235, s[84:85]
	global_load_dwordx4 v[160:163], v236, s[84:85]
	global_load_dwordx4 v[164:167], v237, s[84:85]
	global_load_dwordx4 v[168:171], v238, s[84:85]
	global_load_dwordx4 v[172:175], v100, s[84:85] offset:768
	global_load_dwordx4 v[176:179], v149, s[84:85] offset:768
	global_load_dwordx4 v[180:183], v100, s[84:85] offset:832
	global_load_dwordx4 v[184:187], v149, s[84:85] offset:832
	s_add_u32 s84, s84, 0x30000
	s_addc_u32 s85, s85, 0
	ds_read_b64_tr_b16 v[72:73], v231
	ds_read_b64_tr_b16 v[74:75], v231 offset:512
	ds_read_b64_tr_b16 v[76:77], v231 offset:2048
	ds_read_b64_tr_b16 v[78:79], v231 offset:2560
	ds_read_b64_tr_b16 v[220:221], v231 offset:1024
	ds_read_b64_tr_b16 v[222:223], v231 offset:1536
	ds_read_b64_tr_b16 v[224:225], v231 offset:3072
	ds_read_b64_tr_b16 v[226:227], v231 offset:3584
	v_exp_f32_e32 v188, v188
	v_exp_f32_e32 v189, v189
	s_waitcnt vmcnt(8)
	ds_write_b128 v247, v[116:119]
	ds_write_b128 v247, v[120:123] offset:1024
	ds_write_b128 v247, v[124:127] offset:2048
	ds_write_b128 v247, v[128:131] offset:3072
	ds_read_b128 v[116:119], v248
	ds_read_b128 v[120:123], v249
	ds_read_b128 v[124:127], v250
	ds_read_b128 v[128:131], v251
	ds_write_b128 v112, v[132:135]
	ds_write_b128 v112, v[136:139] offset:1024
	ds_write_b128 v112, v[140:143] offset:2048
	ds_write_b128 v112, v[144:147] offset:3072
	v_exp_f32_e32 v190, v190
	v_exp_f32_e32 v191, v191
	s_waitcnt lgkmcnt(4)
	v_mfma_f32_32x32x16_bf16 v[32:47], v[116:119], v[48:51], v[32:47]
	v_exp_f32_e32 v192, v192
	v_exp_f32_e32 v193, v193
	v_exp_f32_e32 v194, v194
	v_mfma_f32_32x32x16_bf16 v[32:47], v[120:123], v[52:55], v[32:47]
	v_exp_f32_e32 v195, v195
	v_exp_f32_e32 v196, v196
	v_exp_f32_e32 v197, v197
	v_mfma_f32_32x32x16_bf16 v[32:47], v[124:127], v[56:59], v[32:47]
	v_exp_f32_e32 v198, v198
	v_exp_f32_e32 v199, v199
	v_exp_f32_e32 v200, v200
	v_mfma_f32_32x32x16_bf16 v[32:47], v[128:131], v[60:63], v[32:47]
	v_exp_f32_e32 v201, v201
	v_exp_f32_e32 v202, v202
	v_exp_f32_e32 v203, v203
	v_cvt_pk_bf16_f32 v64, v188, v189
	v_cvt_pk_bf16_f32 v65, v190, v191
	v_cvt_pk_bf16_f32 v66, v192, v193
	v_cvt_pk_bf16_f32 v67, v194, v195
	v_cvt_pk_bf16_f32 v68, v196, v197
	v_cvt_pk_bf16_f32 v69, v198, v199
	v_cvt_pk_bf16_f32 v70, v200, v201
	v_cvt_pk_bf16_f32 v71, v202, v203
	v_pk_add_f32 v[232:233], v[232:233], v[188:189]
	v_pk_add_f32 v[232:233], v[232:233], v[190:191]
	v_pk_add_f32 v[232:233], v[232:233], v[192:193]
	v_pk_add_f32 v[232:233], v[232:233], v[194:195]
	v_pk_add_f32 v[232:233], v[232:233], v[196:197]
	v_pk_add_f32 v[232:233], v[232:233], v[198:199]
	v_pk_add_f32 v[232:233], v[232:233], v[200:201]
	v_pk_add_f32 v[232:233], v[232:233], v[202:203]
	ds_read2_b32 v[188:189], v115 offset0:68 offset1:69
	ds_read2_b32 v[190:191], v115 offset0:70 offset1:71
	ds_read2_b32 v[192:193], v115 offset0:76 offset1:77
	ds_read2_b32 v[194:195], v115 offset0:78 offset1:79
	ds_read2_b32 v[196:197], v115 offset0:85 offset1:86
	ds_read2_b32 v[198:199], v115 offset0:87 offset1:88
	ds_read2_b32 v[200:201], v115 offset0:93 offset1:94
	ds_read2_b32 v[202:203], v115 offset0:95 offset1:96
	v_mfma_f32_32x32x16_bf16 v[0:15], v[64:67], v[72:75], v[0:15]
	v_mfma_f32_32x32x16_bf16 v[16:31], v[64:67], v[76:79], v[16:31]
	v_mfma_f32_32x32x16_bf16 v[0:15], v[68:71], v[220:223], v[0:15]
	v_mfma_f32_32x32x16_bf16 v[16:31], v[68:71], v[224:227], v[16:31]
	global_load_dwordx4 v[116:119], v235, s[84:85]
	global_load_dwordx4 v[120:123], v236, s[84:85]
	global_load_dwordx4 v[124:127], v237, s[84:85]
	global_load_dwordx4 v[128:131], v238, s[84:85]
	global_load_dwordx4 v[132:135], v100, s[84:85] offset:768
	global_load_dwordx4 v[136:139], v149, s[84:85] offset:768
	global_load_dwordx4 v[140:143], v100, s[84:85] offset:832
	global_load_dwordx4 v[144:147], v149, s[84:85] offset:832
	s_add_u32 s84, s84, 0x30000
	s_addc_u32 s85, s85, 0
	ds_read_b64_tr_b16 v[72:73], v231
	ds_read_b64_tr_b16 v[74:75], v231 offset:512
	ds_read_b64_tr_b16 v[76:77], v231 offset:2048
	ds_read_b64_tr_b16 v[78:79], v231 offset:2560
	ds_read_b64_tr_b16 v[220:221], v231 offset:1024
	ds_read_b64_tr_b16 v[222:223], v231 offset:1536
	ds_read_b64_tr_b16 v[224:225], v231 offset:3072
	ds_read_b64_tr_b16 v[226:227], v231 offset:3584
	v_exp_f32_e32 v32, v32
	v_exp_f32_e32 v33, v33
	s_waitcnt vmcnt(8)
	ds_write_b128 v247, v[156:159]
	ds_write_b128 v247, v[160:163] offset:1024
	ds_write_b128 v247, v[164:167] offset:2048
	ds_write_b128 v247, v[168:171] offset:3072
	ds_read_b128 v[156:159], v248
	ds_read_b128 v[160:163], v249
	ds_read_b128 v[164:167], v250
	ds_read_b128 v[168:171], v251
	ds_write_b128 v112, v[172:175]
	ds_write_b128 v112, v[176:179] offset:1024
	ds_write_b128 v112, v[180:183] offset:2048
	ds_write_b128 v112, v[184:187] offset:3072
	v_exp_f32_e32 v34, v34
	v_exp_f32_e32 v35, v35
	s_waitcnt lgkmcnt(4)
	v_mfma_f32_32x32x16_bf16 v[188:203], v[156:159], v[48:51], v[188:203]
	v_exp_f32_e32 v36, v36
	v_exp_f32_e32 v37, v37
	v_exp_f32_e32 v38, v38
	v_mfma_f32_32x32x16_bf16 v[188:203], v[160:163], v[52:55], v[188:203]
	v_exp_f32_e32 v39, v39
	v_exp_f32_e32 v40, v40
	v_exp_f32_e32 v41, v41
	v_mfma_f32_32x32x16_bf16 v[188:203], v[164:167], v[56:59], v[188:203]
	v_exp_f32_e32 v42, v42
	v_exp_f32_e32 v43, v43
	v_exp_f32_e32 v44, v44
	v_mfma_f32_32x32x16_bf16 v[188:203], v[168:171], v[60:63], v[188:203]
	v_exp_f32_e32 v45, v45
	v_exp_f32_e32 v46, v46
	v_exp_f32_e32 v47, v47
	v_cvt_pk_bf16_f32 v64, v32, v33
	v_cvt_pk_bf16_f32 v65, v34, v35
	v_cvt_pk_bf16_f32 v66, v36, v37
	v_cvt_pk_bf16_f32 v67, v38, v39
	v_cvt_pk_bf16_f32 v68, v40, v41
	v_cvt_pk_bf16_f32 v69, v42, v43
	v_cvt_pk_bf16_f32 v70, v44, v45
	v_cvt_pk_bf16_f32 v71, v46, v47
	v_pk_add_f32 v[232:233], v[232:233], v[32:33]
	v_pk_add_f32 v[232:233], v[232:233], v[34:35]
	v_pk_add_f32 v[232:233], v[232:233], v[36:37]
	v_pk_add_f32 v[232:233], v[232:233], v[38:39]
	v_pk_add_f32 v[232:233], v[232:233], v[40:41]
	v_pk_add_f32 v[232:233], v[232:233], v[42:43]
	v_pk_add_f32 v[232:233], v[232:233], v[44:45]
	v_pk_add_f32 v[232:233], v[232:233], v[46:47]
	ds_read2_b32 v[32:33], v115 offset0:102 offset1:103
	ds_read2_b32 v[34:35], v115 offset0:104 offset1:105
	ds_read2_b32 v[36:37], v115 offset0:110 offset1:111
	ds_read2_b32 v[38:39], v115 offset0:112 offset1:113
	ds_read2_b32 v[40:41], v115 offset0:119 offset1:120
	ds_read2_b32 v[42:43], v115 offset0:121 offset1:122
	ds_read2_b32 v[44:45], v115 offset0:127 offset1:128
	ds_read2_b32 v[46:47], v115 offset0:129 offset1:130
	v_mfma_f32_32x32x16_bf16 v[0:15], v[64:67], v[72:75], v[0:15]
	v_mfma_f32_32x32x16_bf16 v[16:31], v[64:67], v[76:79], v[16:31]
	v_mfma_f32_32x32x16_bf16 v[0:15], v[68:71], v[220:223], v[0:15]
	v_mfma_f32_32x32x16_bf16 v[16:31], v[68:71], v[224:227], v[16:31]
	global_load_dwordx4 v[156:159], v235, s[84:85]
	global_load_dwordx4 v[160:163], v236, s[84:85]
	global_load_dwordx4 v[164:167], v237, s[84:85]
	global_load_dwordx4 v[168:171], v238, s[84:85]
	global_load_dwordx4 v[172:175], v100, s[84:85] offset:768
	global_load_dwordx4 v[176:179], v149, s[84:85] offset:768
	global_load_dwordx4 v[180:183], v100, s[84:85] offset:832
	global_load_dwordx4 v[184:187], v149, s[84:85] offset:832
	s_add_u32 s84, s84, 0x30000
	s_addc_u32 s85, s85, 0
	ds_read_b64_tr_b16 v[72:73], v231
	ds_read_b64_tr_b16 v[74:75], v231 offset:512
	ds_read_b64_tr_b16 v[76:77], v231 offset:2048
	ds_read_b64_tr_b16 v[78:79], v231 offset:2560
	ds_read_b64_tr_b16 v[220:221], v231 offset:1024
	ds_read_b64_tr_b16 v[222:223], v231 offset:1536
	ds_read_b64_tr_b16 v[224:225], v231 offset:3072
	ds_read_b64_tr_b16 v[226:227], v231 offset:3584
	v_exp_f32_e32 v188, v188
	v_exp_f32_e32 v189, v189
	s_waitcnt vmcnt(8)
	ds_write_b128 v247, v[116:119]
	ds_write_b128 v247, v[120:123] offset:1024
	ds_write_b128 v247, v[124:127] offset:2048
	ds_write_b128 v247, v[128:131] offset:3072
	ds_read_b128 v[116:119], v248
	ds_read_b128 v[120:123], v249
	ds_read_b128 v[124:127], v250
	ds_read_b128 v[128:131], v251
	ds_write_b128 v112, v[132:135]
	ds_write_b128 v112, v[136:139] offset:1024
	ds_write_b128 v112, v[140:143] offset:2048
	ds_write_b128 v112, v[144:147] offset:3072
	v_exp_f32_e32 v190, v190
	v_exp_f32_e32 v191, v191
	s_waitcnt lgkmcnt(4)
	v_mfma_f32_32x32x16_bf16 v[32:47], v[116:119], v[48:51], v[32:47]
	v_exp_f32_e32 v192, v192
	v_exp_f32_e32 v193, v193
	v_exp_f32_e32 v194, v194
	v_mfma_f32_32x32x16_bf16 v[32:47], v[120:123], v[52:55], v[32:47]
	v_exp_f32_e32 v195, v195
	v_exp_f32_e32 v196, v196
	v_exp_f32_e32 v197, v197
	v_mfma_f32_32x32x16_bf16 v[32:47], v[124:127], v[56:59], v[32:47]
	v_exp_f32_e32 v198, v198
	v_exp_f32_e32 v199, v199
	v_exp_f32_e32 v200, v200
	v_mfma_f32_32x32x16_bf16 v[32:47], v[128:131], v[60:63], v[32:47]
	v_exp_f32_e32 v201, v201
	v_exp_f32_e32 v202, v202
	v_exp_f32_e32 v203, v203
	v_cvt_pk_bf16_f32 v64, v188, v189
	v_cvt_pk_bf16_f32 v65, v190, v191
	v_cvt_pk_bf16_f32 v66, v192, v193
	v_cvt_pk_bf16_f32 v67, v194, v195
	v_cvt_pk_bf16_f32 v68, v196, v197
	v_cvt_pk_bf16_f32 v69, v198, v199
	v_cvt_pk_bf16_f32 v70, v200, v201
	v_cvt_pk_bf16_f32 v71, v202, v203
	v_pk_add_f32 v[232:233], v[232:233], v[188:189]
	v_pk_add_f32 v[232:233], v[232:233], v[190:191]
	v_pk_add_f32 v[232:233], v[232:233], v[192:193]
	v_pk_add_f32 v[232:233], v[232:233], v[194:195]
	v_pk_add_f32 v[232:233], v[232:233], v[196:197]
	v_pk_add_f32 v[232:233], v[232:233], v[198:199]
	v_pk_add_f32 v[232:233], v[232:233], v[200:201]
	v_pk_add_f32 v[232:233], v[232:233], v[202:203]
	ds_read2_b32 v[188:189], v115 offset0:136 offset1:137
	ds_read2_b32 v[190:191], v115 offset0:138 offset1:139
	ds_read2_b32 v[192:193], v115 offset0:144 offset1:145
	ds_read2_b32 v[194:195], v115 offset0:146 offset1:147
	ds_read2_b32 v[196:197], v115 offset0:153 offset1:154
	ds_read2_b32 v[198:199], v115 offset0:155 offset1:156
	ds_read2_b32 v[200:201], v115 offset0:161 offset1:162
	ds_read2_b32 v[202:203], v115 offset0:163 offset1:164
	v_mfma_f32_32x32x16_bf16 v[0:15], v[64:67], v[72:75], v[0:15]
	v_mfma_f32_32x32x16_bf16 v[16:31], v[64:67], v[76:79], v[16:31]
	v_mfma_f32_32x32x16_bf16 v[0:15], v[68:71], v[220:223], v[0:15]
	v_mfma_f32_32x32x16_bf16 v[16:31], v[68:71], v[224:227], v[16:31]
	global_load_dwordx4 v[116:119], v235, s[84:85]
	global_load_dwordx4 v[120:123], v236, s[84:85]
	global_load_dwordx4 v[124:127], v237, s[84:85]
	global_load_dwordx4 v[128:131], v238, s[84:85]
	global_load_dwordx4 v[132:135], v100, s[84:85] offset:768
	global_load_dwordx4 v[136:139], v149, s[84:85] offset:768
	global_load_dwordx4 v[140:143], v100, s[84:85] offset:832
	global_load_dwordx4 v[144:147], v149, s[84:85] offset:832
	s_add_u32 s84, s84, 0x30000
	s_addc_u32 s85, s85, 0
	ds_read_b64_tr_b16 v[72:73], v231
	ds_read_b64_tr_b16 v[74:75], v231 offset:512
	ds_read_b64_tr_b16 v[76:77], v231 offset:2048
	ds_read_b64_tr_b16 v[78:79], v231 offset:2560
	ds_read_b64_tr_b16 v[220:221], v231 offset:1024
	ds_read_b64_tr_b16 v[222:223], v231 offset:1536
	ds_read_b64_tr_b16 v[224:225], v231 offset:3072
	ds_read_b64_tr_b16 v[226:227], v231 offset:3584
	v_exp_f32_e32 v32, v32
	v_exp_f32_e32 v33, v33
	s_waitcnt vmcnt(8)
	ds_write_b128 v247, v[156:159]
	ds_write_b128 v247, v[160:163] offset:1024
	ds_write_b128 v247, v[164:167] offset:2048
	ds_write_b128 v247, v[168:171] offset:3072
	ds_read_b128 v[156:159], v248
	ds_read_b128 v[160:163], v249
	ds_read_b128 v[164:167], v250
	ds_read_b128 v[168:171], v251
	ds_write_b128 v112, v[172:175]
	ds_write_b128 v112, v[176:179] offset:1024
	ds_write_b128 v112, v[180:183] offset:2048
	ds_write_b128 v112, v[184:187] offset:3072
	v_exp_f32_e32 v34, v34
	v_exp_f32_e32 v35, v35
	s_waitcnt lgkmcnt(4)
	v_mfma_f32_32x32x16_bf16 v[188:203], v[156:159], v[48:51], v[188:203]
	v_exp_f32_e32 v36, v36
	v_exp_f32_e32 v37, v37
	v_exp_f32_e32 v38, v38
	v_mfma_f32_32x32x16_bf16 v[188:203], v[160:163], v[52:55], v[188:203]
	v_exp_f32_e32 v39, v39
	v_exp_f32_e32 v40, v40
	v_exp_f32_e32 v41, v41
	v_mfma_f32_32x32x16_bf16 v[188:203], v[164:167], v[56:59], v[188:203]
	v_exp_f32_e32 v42, v42
	v_exp_f32_e32 v43, v43
	v_exp_f32_e32 v44, v44
	v_mfma_f32_32x32x16_bf16 v[188:203], v[168:171], v[60:63], v[188:203]
	v_exp_f32_e32 v45, v45
	v_exp_f32_e32 v46, v46
	v_exp_f32_e32 v47, v47
	v_cvt_pk_bf16_f32 v64, v32, v33
	v_cvt_pk_bf16_f32 v65, v34, v35
	v_cvt_pk_bf16_f32 v66, v36, v37
	v_cvt_pk_bf16_f32 v67, v38, v39
	v_cvt_pk_bf16_f32 v68, v40, v41
	v_cvt_pk_bf16_f32 v69, v42, v43
	v_cvt_pk_bf16_f32 v70, v44, v45
	v_cvt_pk_bf16_f32 v71, v46, v47
	v_pk_add_f32 v[232:233], v[232:233], v[32:33]
	v_pk_add_f32 v[232:233], v[232:233], v[34:35]
	v_pk_add_f32 v[232:233], v[232:233], v[36:37]
	v_pk_add_f32 v[232:233], v[232:233], v[38:39]
	v_pk_add_f32 v[232:233], v[232:233], v[40:41]
	v_pk_add_f32 v[232:233], v[232:233], v[42:43]
	v_pk_add_f32 v[232:233], v[232:233], v[44:45]
	v_pk_add_f32 v[232:233], v[232:233], v[46:47]
	ds_read2_b32 v[32:33], v115 offset0:170 offset1:171
	ds_read2_b32 v[34:35], v115 offset0:172 offset1:173
	ds_read2_b32 v[36:37], v115 offset0:178 offset1:179
	ds_read2_b32 v[38:39], v115 offset0:180 offset1:181
	ds_read2_b32 v[40:41], v115 offset0:187 offset1:188
	ds_read2_b32 v[42:43], v115 offset0:189 offset1:190
	ds_read2_b32 v[44:45], v115 offset0:195 offset1:196
	ds_read2_b32 v[46:47], v115 offset0:197 offset1:198
	v_mfma_f32_32x32x16_bf16 v[0:15], v[64:67], v[72:75], v[0:15]
	v_mfma_f32_32x32x16_bf16 v[16:31], v[64:67], v[76:79], v[16:31]
	v_mfma_f32_32x32x16_bf16 v[0:15], v[68:71], v[220:223], v[0:15]
	v_mfma_f32_32x32x16_bf16 v[16:31], v[68:71], v[224:227], v[16:31]
	global_load_dwordx4 v[156:159], v235, s[84:85]
	global_load_dwordx4 v[160:163], v236, s[84:85]
	global_load_dwordx4 v[164:167], v237, s[84:85]
	global_load_dwordx4 v[168:171], v238, s[84:85]
	global_load_dwordx4 v[172:175], v100, s[84:85] offset:768
	global_load_dwordx4 v[176:179], v149, s[84:85] offset:768
	global_load_dwordx4 v[180:183], v100, s[84:85] offset:832
	global_load_dwordx4 v[184:187], v149, s[84:85] offset:832
	s_add_u32 s84, s84, 0x30000
	s_addc_u32 s85, s85, 0
	ds_read_b64_tr_b16 v[72:73], v231
	ds_read_b64_tr_b16 v[74:75], v231 offset:512
	ds_read_b64_tr_b16 v[76:77], v231 offset:2048
	ds_read_b64_tr_b16 v[78:79], v231 offset:2560
	ds_read_b64_tr_b16 v[220:221], v231 offset:1024
	ds_read_b64_tr_b16 v[222:223], v231 offset:1536
	ds_read_b64_tr_b16 v[224:225], v231 offset:3072
	ds_read_b64_tr_b16 v[226:227], v231 offset:3584
	v_exp_f32_e32 v188, v188
	v_exp_f32_e32 v189, v189
	s_waitcnt vmcnt(8)
	ds_write_b128 v247, v[116:119]
	ds_write_b128 v247, v[120:123] offset:1024
	ds_write_b128 v247, v[124:127] offset:2048
	ds_write_b128 v247, v[128:131] offset:3072
	ds_read_b128 v[116:119], v248
	ds_read_b128 v[120:123], v249
	ds_read_b128 v[124:127], v250
	ds_read_b128 v[128:131], v251
	ds_write_b128 v112, v[132:135]
	ds_write_b128 v112, v[136:139] offset:1024
	ds_write_b128 v112, v[140:143] offset:2048
	ds_write_b128 v112, v[144:147] offset:3072
	v_exp_f32_e32 v190, v190
	v_exp_f32_e32 v191, v191
	s_waitcnt lgkmcnt(4)
	v_mfma_f32_32x32x16_bf16 v[32:47], v[116:119], v[48:51], v[32:47]
	v_exp_f32_e32 v192, v192
	v_exp_f32_e32 v193, v193
	v_exp_f32_e32 v194, v194
	v_mfma_f32_32x32x16_bf16 v[32:47], v[120:123], v[52:55], v[32:47]
	v_exp_f32_e32 v195, v195
	v_exp_f32_e32 v196, v196
	v_exp_f32_e32 v197, v197
	v_mfma_f32_32x32x16_bf16 v[32:47], v[124:127], v[56:59], v[32:47]
	v_exp_f32_e32 v198, v198
	v_exp_f32_e32 v199, v199
	v_exp_f32_e32 v200, v200
	v_mfma_f32_32x32x16_bf16 v[32:47], v[128:131], v[60:63], v[32:47]
	v_exp_f32_e32 v201, v201
	v_exp_f32_e32 v202, v202
	v_exp_f32_e32 v203, v203
	v_cvt_pk_bf16_f32 v64, v188, v189
	v_cvt_pk_bf16_f32 v65, v190, v191
	v_cvt_pk_bf16_f32 v66, v192, v193
	v_cvt_pk_bf16_f32 v67, v194, v195
	v_cvt_pk_bf16_f32 v68, v196, v197
	v_cvt_pk_bf16_f32 v69, v198, v199
	v_cvt_pk_bf16_f32 v70, v200, v201
	v_cvt_pk_bf16_f32 v71, v202, v203
	v_pk_add_f32 v[232:233], v[232:233], v[188:189]
	v_pk_add_f32 v[232:233], v[232:233], v[190:191]
	v_pk_add_f32 v[232:233], v[232:233], v[192:193]
	v_pk_add_f32 v[232:233], v[232:233], v[194:195]
	v_pk_add_f32 v[232:233], v[232:233], v[196:197]
	v_pk_add_f32 v[232:233], v[232:233], v[198:199]
	v_pk_add_f32 v[232:233], v[232:233], v[200:201]
	v_pk_add_f32 v[232:233], v[232:233], v[202:203]
	ds_read2_b32 v[188:189], v115 offset0:204 offset1:205
	ds_read2_b32 v[190:191], v115 offset0:206 offset1:207
	ds_read2_b32 v[192:193], v115 offset0:212 offset1:213
	ds_read2_b32 v[194:195], v115 offset0:214 offset1:215
	ds_read2_b32 v[196:197], v115 offset0:221 offset1:222
	ds_read2_b32 v[198:199], v115 offset0:223 offset1:224
	ds_read2_b32 v[200:201], v115 offset0:229 offset1:230
	ds_read2_b32 v[202:203], v115 offset0:231 offset1:232
	v_mfma_f32_32x32x16_bf16 v[0:15], v[64:67], v[72:75], v[0:15]
	v_mfma_f32_32x32x16_bf16 v[16:31], v[64:67], v[76:79], v[16:31]
	v_mfma_f32_32x32x16_bf16 v[0:15], v[68:71], v[220:223], v[0:15]
	v_mfma_f32_32x32x16_bf16 v[16:31], v[68:71], v[224:227], v[16:31]
	global_load_dwordx4 v[116:119], v235, s[84:85]
	global_load_dwordx4 v[120:123], v236, s[84:85]
	global_load_dwordx4 v[124:127], v237, s[84:85]
	global_load_dwordx4 v[128:131], v238, s[84:85]
	global_load_dwordx4 v[132:135], v100, s[84:85] offset:768
	global_load_dwordx4 v[136:139], v149, s[84:85] offset:768
	global_load_dwordx4 v[140:143], v100, s[84:85] offset:832
	global_load_dwordx4 v[144:147], v149, s[84:85] offset:832
	s_add_u32 s84, s84, 0x30000
	s_addc_u32 s85, s85, 0
	ds_read_b64_tr_b16 v[72:73], v231
	ds_read_b64_tr_b16 v[74:75], v231 offset:512
	ds_read_b64_tr_b16 v[76:77], v231 offset:2048
	ds_read_b64_tr_b16 v[78:79], v231 offset:2560
	ds_read_b64_tr_b16 v[220:221], v231 offset:1024
	ds_read_b64_tr_b16 v[222:223], v231 offset:1536
	ds_read_b64_tr_b16 v[224:225], v231 offset:3072
	ds_read_b64_tr_b16 v[226:227], v231 offset:3584
	v_exp_f32_e32 v32, v32
	v_exp_f32_e32 v33, v33
	s_waitcnt vmcnt(8)
	ds_write_b128 v247, v[156:159]
	ds_write_b128 v247, v[160:163] offset:1024
	ds_write_b128 v247, v[164:167] offset:2048
	ds_write_b128 v247, v[168:171] offset:3072
	ds_read_b128 v[156:159], v248
	ds_read_b128 v[160:163], v249
	ds_read_b128 v[164:167], v250
	ds_read_b128 v[168:171], v251
	ds_write_b128 v112, v[172:175]
	ds_write_b128 v112, v[176:179] offset:1024
	ds_write_b128 v112, v[180:183] offset:2048
	ds_write_b128 v112, v[184:187] offset:3072
	v_exp_f32_e32 v34, v34
	v_exp_f32_e32 v35, v35
	s_waitcnt lgkmcnt(4)
	v_mfma_f32_32x32x16_bf16 v[188:203], v[156:159], v[48:51], v[188:203]
	v_exp_f32_e32 v36, v36
	v_exp_f32_e32 v37, v37
	v_exp_f32_e32 v38, v38
	v_mfma_f32_32x32x16_bf16 v[188:203], v[160:163], v[52:55], v[188:203]
	v_exp_f32_e32 v39, v39
	v_exp_f32_e32 v40, v40
	v_exp_f32_e32 v41, v41
	v_mfma_f32_32x32x16_bf16 v[188:203], v[164:167], v[56:59], v[188:203]
	v_exp_f32_e32 v42, v42
	v_exp_f32_e32 v43, v43
	v_exp_f32_e32 v44, v44
	v_mfma_f32_32x32x16_bf16 v[188:203], v[168:171], v[60:63], v[188:203]
	v_exp_f32_e32 v45, v45
	v_exp_f32_e32 v46, v46
	v_exp_f32_e32 v47, v47
	v_cvt_pk_bf16_f32 v64, v32, v33
	v_cvt_pk_bf16_f32 v65, v34, v35
	v_cvt_pk_bf16_f32 v66, v36, v37
	v_cvt_pk_bf16_f32 v67, v38, v39
	v_cvt_pk_bf16_f32 v68, v40, v41
	v_cvt_pk_bf16_f32 v69, v42, v43
	v_cvt_pk_bf16_f32 v70, v44, v45
	v_cvt_pk_bf16_f32 v71, v46, v47
	v_pk_add_f32 v[232:233], v[232:233], v[32:33]
	v_pk_add_f32 v[232:233], v[232:233], v[34:35]
	v_pk_add_f32 v[232:233], v[232:233], v[36:37]
	v_pk_add_f32 v[232:233], v[232:233], v[38:39]
	v_pk_add_f32 v[232:233], v[232:233], v[40:41]
	v_pk_add_f32 v[232:233], v[232:233], v[42:43]
	v_pk_add_f32 v[232:233], v[232:233], v[44:45]
	v_pk_add_f32 v[232:233], v[232:233], v[46:47]
	v_add_u32_e32 v115, 952, v115
	ds_read2_b32 v[32:33], v115 offset0:0 offset1:1
	ds_read2_b32 v[34:35], v115 offset0:2 offset1:3
	ds_read2_b32 v[36:37], v115 offset0:8 offset1:9
	ds_read2_b32 v[38:39], v115 offset0:10 offset1:11
	ds_read2_b32 v[40:41], v115 offset0:17 offset1:18
	ds_read2_b32 v[42:43], v115 offset0:19 offset1:20
	ds_read2_b32 v[44:45], v115 offset0:25 offset1:26
	ds_read2_b32 v[46:47], v115 offset0:27 offset1:28
	v_mfma_f32_32x32x16_bf16 v[0:15], v[64:67], v[72:75], v[0:15]
	v_mfma_f32_32x32x16_bf16 v[16:31], v[64:67], v[76:79], v[16:31]
	v_mfma_f32_32x32x16_bf16 v[0:15], v[68:71], v[220:223], v[0:15]
	v_mfma_f32_32x32x16_bf16 v[16:31], v[68:71], v[224:227], v[16:31]
	global_load_dwordx4 v[156:159], v235, s[84:85]
	global_load_dwordx4 v[160:163], v236, s[84:85]
	global_load_dwordx4 v[164:167], v237, s[84:85]
	global_load_dwordx4 v[168:171], v238, s[84:85]
	global_load_dwordx4 v[172:175], v100, s[84:85] offset:768
	global_load_dwordx4 v[176:179], v149, s[84:85] offset:768
	global_load_dwordx4 v[180:183], v100, s[84:85] offset:832
	global_load_dwordx4 v[184:187], v149, s[84:85] offset:832
	s_add_u32 s84, s84, 0x30000
	s_addc_u32 s85, s85, 0
	ds_read_b64_tr_b16 v[72:73], v231
	ds_read_b64_tr_b16 v[74:75], v231 offset:512
	ds_read_b64_tr_b16 v[76:77], v231 offset:2048
	ds_read_b64_tr_b16 v[78:79], v231 offset:2560
	ds_read_b64_tr_b16 v[220:221], v231 offset:1024
	ds_read_b64_tr_b16 v[222:223], v231 offset:1536
	ds_read_b64_tr_b16 v[224:225], v231 offset:3072
	ds_read_b64_tr_b16 v[226:227], v231 offset:3584
	v_exp_f32_e32 v188, v188
	v_exp_f32_e32 v189, v189
	s_waitcnt vmcnt(8)
	ds_write_b128 v247, v[116:119]
	ds_write_b128 v247, v[120:123] offset:1024
	ds_write_b128 v247, v[124:127] offset:2048
	ds_write_b128 v247, v[128:131] offset:3072
	ds_read_b128 v[116:119], v248
	ds_read_b128 v[120:123], v249
	ds_read_b128 v[124:127], v250
	ds_read_b128 v[128:131], v251
	ds_write_b128 v112, v[132:135]
	ds_write_b128 v112, v[136:139] offset:1024
	ds_write_b128 v112, v[140:143] offset:2048
	ds_write_b128 v112, v[144:147] offset:3072
	v_exp_f32_e32 v190, v190
	v_exp_f32_e32 v191, v191
	s_waitcnt lgkmcnt(4)
	v_mfma_f32_32x32x16_bf16 v[32:47], v[116:119], v[48:51], v[32:47]
	v_exp_f32_e32 v192, v192
	v_exp_f32_e32 v193, v193
	v_exp_f32_e32 v194, v194
	v_mfma_f32_32x32x16_bf16 v[32:47], v[120:123], v[52:55], v[32:47]
	v_exp_f32_e32 v195, v195
	v_exp_f32_e32 v196, v196
	v_exp_f32_e32 v197, v197
	v_mfma_f32_32x32x16_bf16 v[32:47], v[124:127], v[56:59], v[32:47]
	v_exp_f32_e32 v198, v198
	v_exp_f32_e32 v199, v199
	v_exp_f32_e32 v200, v200
	v_mfma_f32_32x32x16_bf16 v[32:47], v[128:131], v[60:63], v[32:47]
	v_exp_f32_e32 v201, v201
	v_exp_f32_e32 v202, v202
	v_exp_f32_e32 v203, v203
	v_cvt_pk_bf16_f32 v64, v188, v189
	v_cvt_pk_bf16_f32 v65, v190, v191
	v_cvt_pk_bf16_f32 v66, v192, v193
	v_cvt_pk_bf16_f32 v67, v194, v195
	v_cvt_pk_bf16_f32 v68, v196, v197
	v_cvt_pk_bf16_f32 v69, v198, v199
	v_cvt_pk_bf16_f32 v70, v200, v201
	v_cvt_pk_bf16_f32 v71, v202, v203
	v_pk_add_f32 v[232:233], v[232:233], v[188:189]
	v_pk_add_f32 v[232:233], v[232:233], v[190:191]
	v_pk_add_f32 v[232:233], v[232:233], v[192:193]
	v_pk_add_f32 v[232:233], v[232:233], v[194:195]
	v_pk_add_f32 v[232:233], v[232:233], v[196:197]
	v_pk_add_f32 v[232:233], v[232:233], v[198:199]
	v_pk_add_f32 v[232:233], v[232:233], v[200:201]
	v_pk_add_f32 v[232:233], v[232:233], v[202:203]
	ds_read2_b32 v[188:189], v115 offset0:34 offset1:35
	ds_read2_b32 v[190:191], v115 offset0:36 offset1:37
	ds_read2_b32 v[192:193], v115 offset0:42 offset1:43
	ds_read2_b32 v[194:195], v115 offset0:44 offset1:45
	ds_read2_b32 v[196:197], v115 offset0:51 offset1:52
	ds_read2_b32 v[198:199], v115 offset0:53 offset1:54
	ds_read2_b32 v[200:201], v115 offset0:59 offset1:60
	ds_read2_b32 v[202:203], v115 offset0:61 offset1:62
	v_mfma_f32_32x32x16_bf16 v[0:15], v[64:67], v[72:75], v[0:15]
	v_mfma_f32_32x32x16_bf16 v[16:31], v[64:67], v[76:79], v[16:31]
	v_mfma_f32_32x32x16_bf16 v[0:15], v[68:71], v[220:223], v[0:15]
	v_mfma_f32_32x32x16_bf16 v[16:31], v[68:71], v[224:227], v[16:31]
	global_load_dwordx4 v[116:119], v235, s[84:85]
	global_load_dwordx4 v[120:123], v236, s[84:85]
	global_load_dwordx4 v[124:127], v237, s[84:85]
	global_load_dwordx4 v[128:131], v238, s[84:85]
	global_load_dwordx4 v[132:135], v100, s[84:85] offset:768
	global_load_dwordx4 v[136:139], v149, s[84:85] offset:768
	global_load_dwordx4 v[140:143], v100, s[84:85] offset:832
	global_load_dwordx4 v[144:147], v149, s[84:85] offset:832
	s_add_u32 s84, s84, 0x30000
	s_addc_u32 s85, s85, 0
	ds_read_b64_tr_b16 v[72:73], v231
	ds_read_b64_tr_b16 v[74:75], v231 offset:512
	ds_read_b64_tr_b16 v[76:77], v231 offset:2048
	ds_read_b64_tr_b16 v[78:79], v231 offset:2560
	ds_read_b64_tr_b16 v[220:221], v231 offset:1024
	ds_read_b64_tr_b16 v[222:223], v231 offset:1536
	ds_read_b64_tr_b16 v[224:225], v231 offset:3072
	ds_read_b64_tr_b16 v[226:227], v231 offset:3584
	v_exp_f32_e32 v32, v32
	v_exp_f32_e32 v33, v33
	s_waitcnt vmcnt(8)
	ds_write_b128 v247, v[156:159]
	ds_write_b128 v247, v[160:163] offset:1024
	ds_write_b128 v247, v[164:167] offset:2048
	ds_write_b128 v247, v[168:171] offset:3072
	ds_read_b128 v[156:159], v248
	ds_read_b128 v[160:163], v249
	ds_read_b128 v[164:167], v250
	ds_read_b128 v[168:171], v251
	ds_write_b128 v112, v[172:175]
	ds_write_b128 v112, v[176:179] offset:1024
	ds_write_b128 v112, v[180:183] offset:2048
	ds_write_b128 v112, v[184:187] offset:3072
	v_exp_f32_e32 v34, v34
	v_exp_f32_e32 v35, v35
	s_waitcnt lgkmcnt(4)
	v_mfma_f32_32x32x16_bf16 v[188:203], v[156:159], v[48:51], v[188:203]
	v_exp_f32_e32 v36, v36
	v_exp_f32_e32 v37, v37
	v_exp_f32_e32 v38, v38
	v_mfma_f32_32x32x16_bf16 v[188:203], v[160:163], v[52:55], v[188:203]
	v_exp_f32_e32 v39, v39
	v_exp_f32_e32 v40, v40
	v_exp_f32_e32 v41, v41
	v_mfma_f32_32x32x16_bf16 v[188:203], v[164:167], v[56:59], v[188:203]
	v_exp_f32_e32 v42, v42
	v_exp_f32_e32 v43, v43
	v_exp_f32_e32 v44, v44
	v_mfma_f32_32x32x16_bf16 v[188:203], v[168:171], v[60:63], v[188:203]
	v_exp_f32_e32 v45, v45
	v_exp_f32_e32 v46, v46
	v_exp_f32_e32 v47, v47
	v_cvt_pk_bf16_f32 v64, v32, v33
	v_cvt_pk_bf16_f32 v65, v34, v35
	v_cvt_pk_bf16_f32 v66, v36, v37
	v_cvt_pk_bf16_f32 v67, v38, v39
	v_cvt_pk_bf16_f32 v68, v40, v41
	v_cvt_pk_bf16_f32 v69, v42, v43
	v_cvt_pk_bf16_f32 v70, v44, v45
	v_cvt_pk_bf16_f32 v71, v46, v47
	v_pk_add_f32 v[232:233], v[232:233], v[32:33]
	v_pk_add_f32 v[232:233], v[232:233], v[34:35]
	v_pk_add_f32 v[232:233], v[232:233], v[36:37]
	v_pk_add_f32 v[232:233], v[232:233], v[38:39]
	v_pk_add_f32 v[232:233], v[232:233], v[40:41]
	v_pk_add_f32 v[232:233], v[232:233], v[42:43]
	v_pk_add_f32 v[232:233], v[232:233], v[44:45]
	v_pk_add_f32 v[232:233], v[232:233], v[46:47]
	ds_read2_b32 v[32:33], v115 offset0:68 offset1:69
	ds_read2_b32 v[34:35], v115 offset0:70 offset1:71
	ds_read2_b32 v[36:37], v115 offset0:76 offset1:77
	ds_read2_b32 v[38:39], v115 offset0:78 offset1:79
	ds_read2_b32 v[40:41], v115 offset0:85 offset1:86
	ds_read2_b32 v[42:43], v115 offset0:87 offset1:88
	ds_read2_b32 v[44:45], v115 offset0:93 offset1:94
	ds_read2_b32 v[46:47], v115 offset0:95 offset1:96
	v_mfma_f32_32x32x16_bf16 v[0:15], v[64:67], v[72:75], v[0:15]
	v_mfma_f32_32x32x16_bf16 v[16:31], v[64:67], v[76:79], v[16:31]
	v_mfma_f32_32x32x16_bf16 v[0:15], v[68:71], v[220:223], v[0:15]
	v_mfma_f32_32x32x16_bf16 v[16:31], v[68:71], v[224:227], v[16:31]
	global_load_dwordx4 v[156:159], v235, s[84:85]
	global_load_dwordx4 v[160:163], v236, s[84:85]
	global_load_dwordx4 v[164:167], v237, s[84:85]
	global_load_dwordx4 v[168:171], v238, s[84:85]
	global_load_dwordx4 v[172:175], v100, s[84:85] offset:768
	global_load_dwordx4 v[176:179], v149, s[84:85] offset:768
	global_load_dwordx4 v[180:183], v100, s[84:85] offset:832
	global_load_dwordx4 v[184:187], v149, s[84:85] offset:832
	s_add_u32 s84, s84, 0x30000
	s_addc_u32 s85, s85, 0
	ds_read_b64_tr_b16 v[72:73], v231
	ds_read_b64_tr_b16 v[74:75], v231 offset:512
	ds_read_b64_tr_b16 v[76:77], v231 offset:2048
	ds_read_b64_tr_b16 v[78:79], v231 offset:2560
	ds_read_b64_tr_b16 v[220:221], v231 offset:1024
	ds_read_b64_tr_b16 v[222:223], v231 offset:1536
	ds_read_b64_tr_b16 v[224:225], v231 offset:3072
	ds_read_b64_tr_b16 v[226:227], v231 offset:3584
	v_exp_f32_e32 v188, v188
	v_exp_f32_e32 v189, v189
	s_waitcnt vmcnt(8)
	ds_write_b128 v247, v[116:119]
	ds_write_b128 v247, v[120:123] offset:1024
	ds_write_b128 v247, v[124:127] offset:2048
	ds_write_b128 v247, v[128:131] offset:3072
	ds_read_b128 v[116:119], v248
	ds_read_b128 v[120:123], v249
	ds_read_b128 v[124:127], v250
	ds_read_b128 v[128:131], v251
	ds_write_b128 v112, v[132:135]
	ds_write_b128 v112, v[136:139] offset:1024
	ds_write_b128 v112, v[140:143] offset:2048
	ds_write_b128 v112, v[144:147] offset:3072
	v_exp_f32_e32 v190, v190
	v_exp_f32_e32 v191, v191
	s_waitcnt lgkmcnt(4)
	v_mfma_f32_32x32x16_bf16 v[32:47], v[116:119], v[48:51], v[32:47]
	v_exp_f32_e32 v192, v192
	v_exp_f32_e32 v193, v193
	v_exp_f32_e32 v194, v194
	v_mfma_f32_32x32x16_bf16 v[32:47], v[120:123], v[52:55], v[32:47]
	v_exp_f32_e32 v195, v195
	v_exp_f32_e32 v196, v196
	v_exp_f32_e32 v197, v197
	v_mfma_f32_32x32x16_bf16 v[32:47], v[124:127], v[56:59], v[32:47]
	v_exp_f32_e32 v198, v198
	v_exp_f32_e32 v199, v199
	v_exp_f32_e32 v200, v200
	v_mfma_f32_32x32x16_bf16 v[32:47], v[128:131], v[60:63], v[32:47]
	v_exp_f32_e32 v201, v201
	v_exp_f32_e32 v202, v202
	v_exp_f32_e32 v203, v203
	v_cvt_pk_bf16_f32 v64, v188, v189
	v_cvt_pk_bf16_f32 v65, v190, v191
	v_cvt_pk_bf16_f32 v66, v192, v193
	v_cvt_pk_bf16_f32 v67, v194, v195
	v_cvt_pk_bf16_f32 v68, v196, v197
	v_cvt_pk_bf16_f32 v69, v198, v199
	v_cvt_pk_bf16_f32 v70, v200, v201
	v_cvt_pk_bf16_f32 v71, v202, v203
	v_pk_add_f32 v[232:233], v[232:233], v[188:189]
	v_pk_add_f32 v[232:233], v[232:233], v[190:191]
	v_pk_add_f32 v[232:233], v[232:233], v[192:193]
	v_pk_add_f32 v[232:233], v[232:233], v[194:195]
	v_pk_add_f32 v[232:233], v[232:233], v[196:197]
	v_pk_add_f32 v[232:233], v[232:233], v[198:199]
	v_pk_add_f32 v[232:233], v[232:233], v[200:201]
	v_pk_add_f32 v[232:233], v[232:233], v[202:203]
	ds_read2_b32 v[188:189], v115 offset0:102 offset1:103
	ds_read2_b32 v[190:191], v115 offset0:104 offset1:105
	ds_read2_b32 v[192:193], v115 offset0:110 offset1:111
	ds_read2_b32 v[194:195], v115 offset0:112 offset1:113
	ds_read2_b32 v[196:197], v115 offset0:119 offset1:120
	ds_read2_b32 v[198:199], v115 offset0:121 offset1:122
	ds_read2_b32 v[200:201], v115 offset0:127 offset1:128
	ds_read2_b32 v[202:203], v115 offset0:129 offset1:130
	v_mfma_f32_32x32x16_bf16 v[0:15], v[64:67], v[72:75], v[0:15]
	v_mfma_f32_32x32x16_bf16 v[16:31], v[64:67], v[76:79], v[16:31]
	v_mfma_f32_32x32x16_bf16 v[0:15], v[68:71], v[220:223], v[0:15]
	v_mfma_f32_32x32x16_bf16 v[16:31], v[68:71], v[224:227], v[16:31]
	global_load_dwordx4 v[116:119], v235, s[84:85]
	global_load_dwordx4 v[120:123], v236, s[84:85]
	global_load_dwordx4 v[124:127], v237, s[84:85]
	global_load_dwordx4 v[128:131], v238, s[84:85]
	global_load_dwordx4 v[132:135], v100, s[84:85] offset:768
	global_load_dwordx4 v[136:139], v149, s[84:85] offset:768
	global_load_dwordx4 v[140:143], v100, s[84:85] offset:832
	global_load_dwordx4 v[144:147], v149, s[84:85] offset:832
	s_add_u32 s84, s84, 0x30000
	s_addc_u32 s85, s85, 0
	ds_read_b64_tr_b16 v[72:73], v231
	ds_read_b64_tr_b16 v[74:75], v231 offset:512
	ds_read_b64_tr_b16 v[76:77], v231 offset:2048
	ds_read_b64_tr_b16 v[78:79], v231 offset:2560
	ds_read_b64_tr_b16 v[220:221], v231 offset:1024
	ds_read_b64_tr_b16 v[222:223], v231 offset:1536
	ds_read_b64_tr_b16 v[224:225], v231 offset:3072
	ds_read_b64_tr_b16 v[226:227], v231 offset:3584
	v_exp_f32_e32 v32, v32
	v_exp_f32_e32 v33, v33
	s_waitcnt vmcnt(8)
	ds_write_b128 v247, v[156:159]
	ds_write_b128 v247, v[160:163] offset:1024
	ds_write_b128 v247, v[164:167] offset:2048
	ds_write_b128 v247, v[168:171] offset:3072
	ds_read_b128 v[156:159], v248
	ds_read_b128 v[160:163], v249
	ds_read_b128 v[164:167], v250
	ds_read_b128 v[168:171], v251
	ds_write_b128 v112, v[172:175]
	ds_write_b128 v112, v[176:179] offset:1024
	ds_write_b128 v112, v[180:183] offset:2048
	ds_write_b128 v112, v[184:187] offset:3072
	v_exp_f32_e32 v34, v34
	v_exp_f32_e32 v35, v35
	s_waitcnt lgkmcnt(4)
	v_mfma_f32_32x32x16_bf16 v[188:203], v[156:159], v[48:51], v[188:203]
	v_exp_f32_e32 v36, v36
	v_exp_f32_e32 v37, v37
	v_exp_f32_e32 v38, v38
	v_mfma_f32_32x32x16_bf16 v[188:203], v[160:163], v[52:55], v[188:203]
	v_exp_f32_e32 v39, v39
	v_exp_f32_e32 v40, v40
	v_exp_f32_e32 v41, v41
	v_mfma_f32_32x32x16_bf16 v[188:203], v[164:167], v[56:59], v[188:203]
	v_exp_f32_e32 v42, v42
	v_exp_f32_e32 v43, v43
	v_exp_f32_e32 v44, v44
	v_mfma_f32_32x32x16_bf16 v[188:203], v[168:171], v[60:63], v[188:203]
	v_exp_f32_e32 v45, v45
	v_exp_f32_e32 v46, v46
	v_exp_f32_e32 v47, v47
	v_cvt_pk_bf16_f32 v64, v32, v33
	v_cvt_pk_bf16_f32 v65, v34, v35
	v_cvt_pk_bf16_f32 v66, v36, v37
	v_cvt_pk_bf16_f32 v67, v38, v39
	v_cvt_pk_bf16_f32 v68, v40, v41
	v_cvt_pk_bf16_f32 v69, v42, v43
	v_cvt_pk_bf16_f32 v70, v44, v45
	v_cvt_pk_bf16_f32 v71, v46, v47
	v_pk_add_f32 v[232:233], v[232:233], v[32:33]
	v_pk_add_f32 v[232:233], v[232:233], v[34:35]
	v_pk_add_f32 v[232:233], v[232:233], v[36:37]
	v_pk_add_f32 v[232:233], v[232:233], v[38:39]
	v_pk_add_f32 v[232:233], v[232:233], v[40:41]
	v_pk_add_f32 v[232:233], v[232:233], v[42:43]
	v_pk_add_f32 v[232:233], v[232:233], v[44:45]
	v_pk_add_f32 v[232:233], v[232:233], v[46:47]
	ds_read2_b32 v[32:33], v115 offset0:136 offset1:137
	ds_read2_b32 v[34:35], v115 offset0:138 offset1:139
	ds_read2_b32 v[36:37], v115 offset0:144 offset1:145
	ds_read2_b32 v[38:39], v115 offset0:146 offset1:147
	ds_read2_b32 v[40:41], v115 offset0:153 offset1:154
	ds_read2_b32 v[42:43], v115 offset0:155 offset1:156
	ds_read2_b32 v[44:45], v115 offset0:161 offset1:162
	ds_read2_b32 v[46:47], v115 offset0:163 offset1:164
	v_mfma_f32_32x32x16_bf16 v[0:15], v[64:67], v[72:75], v[0:15]
	v_mfma_f32_32x32x16_bf16 v[16:31], v[64:67], v[76:79], v[16:31]
	v_mfma_f32_32x32x16_bf16 v[0:15], v[68:71], v[220:223], v[0:15]
	v_mfma_f32_32x32x16_bf16 v[16:31], v[68:71], v[224:227], v[16:31]
	global_load_dwordx4 v[156:159], v235, s[84:85]
	global_load_dwordx4 v[160:163], v236, s[84:85]
	global_load_dwordx4 v[164:167], v237, s[84:85]
	global_load_dwordx4 v[168:171], v238, s[84:85]
	global_load_dwordx4 v[172:175], v100, s[84:85] offset:768
	global_load_dwordx4 v[176:179], v149, s[84:85] offset:768
	global_load_dwordx4 v[180:183], v100, s[84:85] offset:832
	global_load_dwordx4 v[184:187], v149, s[84:85] offset:832
	ds_read_b64_tr_b16 v[72:73], v231
	ds_read_b64_tr_b16 v[74:75], v231 offset:512
	ds_read_b64_tr_b16 v[76:77], v231 offset:2048
	ds_read_b64_tr_b16 v[78:79], v231 offset:2560
	ds_read_b64_tr_b16 v[220:221], v231 offset:1024
	ds_read_b64_tr_b16 v[222:223], v231 offset:1536
	ds_read_b64_tr_b16 v[224:225], v231 offset:3072
	ds_read_b64_tr_b16 v[226:227], v231 offset:3584
	v_exp_f32_e32 v188, v188
	v_exp_f32_e32 v189, v189
	s_waitcnt vmcnt(8)
	ds_write_b128 v247, v[116:119]
	ds_write_b128 v247, v[120:123] offset:1024
	ds_write_b128 v247, v[124:127] offset:2048
	ds_write_b128 v247, v[128:131] offset:3072
	ds_read_b128 v[116:119], v248
	ds_read_b128 v[120:123], v249
	ds_read_b128 v[124:127], v250
	ds_read_b128 v[128:131], v251
	ds_write_b128 v112, v[132:135]
	ds_write_b128 v112, v[136:139] offset:1024
	ds_write_b128 v112, v[140:143] offset:2048
	ds_write_b128 v112, v[144:147] offset:3072
	v_exp_f32_e32 v190, v190
	v_exp_f32_e32 v191, v191
	s_waitcnt lgkmcnt(4)
	v_mfma_f32_32x32x16_bf16 v[32:47], v[116:119], v[48:51], v[32:47]
	v_exp_f32_e32 v192, v192
	v_exp_f32_e32 v193, v193
	v_exp_f32_e32 v194, v194
	v_mfma_f32_32x32x16_bf16 v[32:47], v[120:123], v[52:55], v[32:47]
	v_exp_f32_e32 v195, v195
	v_exp_f32_e32 v196, v196
	v_exp_f32_e32 v197, v197
	v_mfma_f32_32x32x16_bf16 v[32:47], v[124:127], v[56:59], v[32:47]
	v_exp_f32_e32 v198, v198
	v_exp_f32_e32 v199, v199
	v_exp_f32_e32 v200, v200
	v_mfma_f32_32x32x16_bf16 v[32:47], v[128:131], v[60:63], v[32:47]
	v_exp_f32_e32 v201, v201
	v_exp_f32_e32 v202, v202
	v_exp_f32_e32 v203, v203
	v_cvt_pk_bf16_f32 v64, v188, v189
	v_cvt_pk_bf16_f32 v65, v190, v191
	v_cvt_pk_bf16_f32 v66, v192, v193
	v_cvt_pk_bf16_f32 v67, v194, v195
	v_cvt_pk_bf16_f32 v68, v196, v197
	v_cvt_pk_bf16_f32 v69, v198, v199
	v_cvt_pk_bf16_f32 v70, v200, v201
	v_cvt_pk_bf16_f32 v71, v202, v203
	v_pk_add_f32 v[232:233], v[232:233], v[188:189]
	v_pk_add_f32 v[232:233], v[232:233], v[190:191]
	v_pk_add_f32 v[232:233], v[232:233], v[192:193]
	v_pk_add_f32 v[232:233], v[232:233], v[194:195]
	v_pk_add_f32 v[232:233], v[232:233], v[196:197]
	v_pk_add_f32 v[232:233], v[232:233], v[198:199]
	v_pk_add_f32 v[232:233], v[232:233], v[200:201]
	v_pk_add_f32 v[232:233], v[232:233], v[202:203]
	ds_read2_b32 v[188:189], v115 offset0:170 offset1:171
	ds_read2_b32 v[190:191], v115 offset0:172 offset1:173
	ds_read2_b32 v[192:193], v115 offset0:178 offset1:179
	ds_read2_b32 v[194:195], v115 offset0:180 offset1:181
	ds_read2_b32 v[196:197], v115 offset0:187 offset1:188
	ds_read2_b32 v[198:199], v115 offset0:189 offset1:190
	ds_read2_b32 v[200:201], v115 offset0:195 offset1:196
	ds_read2_b32 v[202:203], v115 offset0:197 offset1:198
	v_mfma_f32_32x32x16_bf16 v[0:15], v[64:67], v[72:75], v[0:15]
	v_mfma_f32_32x32x16_bf16 v[16:31], v[64:67], v[76:79], v[16:31]
	v_mfma_f32_32x32x16_bf16 v[0:15], v[68:71], v[220:223], v[0:15]
	v_mfma_f32_32x32x16_bf16 v[16:31], v[68:71], v[224:227], v[16:31]
	global_load_dwordx4 v[116:119], v239, s[86:87]
	global_load_dwordx4 v[120:123], v240, s[86:87]
	global_load_dwordx4 v[124:127], v241, s[86:87]
	global_load_dwordx4 v[128:131], v242, s[86:87]
	global_load_dwordx4 v[132:135], v101, s[86:87] offset:768
	global_load_dwordx4 v[136:139], v150, s[86:87] offset:768
	global_load_dwordx4 v[140:143], v101, s[86:87] offset:832
	global_load_dwordx4 v[144:147], v150, s[86:87] offset:832
	s_add_u32 s86, s86, 0xc0000
	s_addc_u32 s87, s87, 0
	ds_read_b64_tr_b16 v[72:73], v231
	ds_read_b64_tr_b16 v[74:75], v231 offset:512
	ds_read_b64_tr_b16 v[76:77], v231 offset:2048
	ds_read_b64_tr_b16 v[78:79], v231 offset:2560
	ds_read_b64_tr_b16 v[220:221], v231 offset:1024
	ds_read_b64_tr_b16 v[222:223], v231 offset:1536
	ds_read_b64_tr_b16 v[224:225], v231 offset:3072
	ds_read_b64_tr_b16 v[226:227], v231 offset:3584
	v_exp_f32_e32 v32, v32
	v_exp_f32_e32 v33, v33
	s_waitcnt vmcnt(8)
	ds_write_b128 v247, v[156:159]
	ds_write_b128 v247, v[160:163] offset:1024
	ds_write_b128 v247, v[164:167] offset:2048
	ds_write_b128 v247, v[168:171] offset:3072
	ds_read_b128 v[156:159], v248
	ds_read_b128 v[160:163], v249
	ds_read_b128 v[164:167], v250
	ds_read_b128 v[168:171], v251
	ds_write_b128 v112, v[172:175]
	ds_write_b128 v112, v[176:179] offset:1024
	ds_write_b128 v112, v[180:183] offset:2048
	ds_write_b128 v112, v[184:187] offset:3072
	v_exp_f32_e32 v34, v34
	v_exp_f32_e32 v35, v35
	s_waitcnt lgkmcnt(4)
	v_mfma_f32_32x32x16_bf16 v[188:203], v[156:159], v[48:51], v[188:203]
	v_exp_f32_e32 v36, v36
	v_exp_f32_e32 v37, v37
	v_exp_f32_e32 v38, v38
	v_mfma_f32_32x32x16_bf16 v[188:203], v[160:163], v[52:55], v[188:203]
	v_exp_f32_e32 v39, v39
	v_exp_f32_e32 v40, v40
	v_exp_f32_e32 v41, v41
	v_mfma_f32_32x32x16_bf16 v[188:203], v[164:167], v[56:59], v[188:203]
	v_exp_f32_e32 v42, v42
	v_exp_f32_e32 v43, v43
	v_exp_f32_e32 v44, v44
	v_mfma_f32_32x32x16_bf16 v[188:203], v[168:171], v[60:63], v[188:203]
	v_exp_f32_e32 v45, v45
	v_exp_f32_e32 v46, v46
	v_exp_f32_e32 v47, v47
	v_cvt_pk_bf16_f32 v64, v32, v33
	v_cvt_pk_bf16_f32 v65, v34, v35
	v_cvt_pk_bf16_f32 v66, v36, v37
	v_cvt_pk_bf16_f32 v67, v38, v39
	v_cvt_pk_bf16_f32 v68, v40, v41
	v_cvt_pk_bf16_f32 v69, v42, v43
	v_cvt_pk_bf16_f32 v70, v44, v45
	v_cvt_pk_bf16_f32 v71, v46, v47
	v_pk_add_f32 v[232:233], v[232:233], v[32:33]
	v_pk_add_f32 v[232:233], v[232:233], v[34:35]
	v_pk_add_f32 v[232:233], v[232:233], v[36:37]
	v_pk_add_f32 v[232:233], v[232:233], v[38:39]
	v_pk_add_f32 v[232:233], v[232:233], v[40:41]
	v_pk_add_f32 v[232:233], v[232:233], v[42:43]
	v_pk_add_f32 v[232:233], v[232:233], v[44:45]
	v_pk_add_f32 v[232:233], v[232:233], v[46:47]
	v_mov_b32_e32 v115, v229
	ds_read2_b32 v[32:33], v115 offset0:0 offset1:1
	ds_read2_b32 v[34:35], v115 offset0:2 offset1:3
	ds_read2_b32 v[36:37], v115 offset0:8 offset1:9
	ds_read2_b32 v[38:39], v115 offset0:10 offset1:11
	ds_read2_b32 v[40:41], v115 offset0:16 offset1:17
	ds_read2_b32 v[42:43], v115 offset0:18 offset1:19
	ds_read2_b32 v[44:45], v115 offset0:24 offset1:25
	ds_read2_b32 v[46:47], v115 offset0:26 offset1:27
	v_mfma_f32_32x32x16_bf16 v[0:15], v[64:67], v[72:75], v[0:15]
	v_mfma_f32_32x32x16_bf16 v[16:31], v[64:67], v[76:79], v[16:31]
	v_mfma_f32_32x32x16_bf16 v[0:15], v[68:71], v[220:223], v[0:15]
	v_mfma_f32_32x32x16_bf16 v[16:31], v[68:71], v[224:227], v[16:31]
	global_load_dwordx4 v[156:159], v239, s[86:87]
	global_load_dwordx4 v[160:163], v240, s[86:87]
	global_load_dwordx4 v[164:167], v241, s[86:87]
	global_load_dwordx4 v[168:171], v242, s[86:87]
	global_load_dwordx4 v[172:175], v101, s[86:87] offset:768
	global_load_dwordx4 v[176:179], v150, s[86:87] offset:768
	global_load_dwordx4 v[180:183], v101, s[86:87] offset:832
	global_load_dwordx4 v[184:187], v150, s[86:87] offset:832
	s_add_u32 s86, s86, 0xc0000
	s_addc_u32 s87, s87, 0
	ds_read_b64_tr_b16 v[72:73], v231
	ds_read_b64_tr_b16 v[74:75], v231 offset:512
	ds_read_b64_tr_b16 v[76:77], v231 offset:2048
	ds_read_b64_tr_b16 v[78:79], v231 offset:2560
	ds_read_b64_tr_b16 v[220:221], v231 offset:1024
	ds_read_b64_tr_b16 v[222:223], v231 offset:1536
	ds_read_b64_tr_b16 v[224:225], v231 offset:3072
	ds_read_b64_tr_b16 v[226:227], v231 offset:3584
	v_exp_f32_e32 v188, v188
	v_exp_f32_e32 v189, v189
	s_waitcnt vmcnt(8)
	ds_write_b128 v247, v[116:119]
	ds_write_b128 v247, v[120:123] offset:1024
	ds_write_b128 v247, v[124:127] offset:2048
	ds_write_b128 v247, v[128:131] offset:3072
	ds_read_b128 v[116:119], v248
	ds_read_b128 v[120:123], v249
	ds_read_b128 v[124:127], v250
	ds_read_b128 v[128:131], v251
	ds_write_b128 v112, v[132:135]
	ds_write_b128 v112, v[136:139] offset:1024
	ds_write_b128 v112, v[140:143] offset:2048
	ds_write_b128 v112, v[144:147] offset:3072
	v_exp_f32_e32 v190, v190
	v_exp_f32_e32 v191, v191
	s_waitcnt lgkmcnt(4)
	v_mfma_f32_32x32x16_bf16 v[32:47], v[116:119], v[48:51], v[32:47]
	v_exp_f32_e32 v192, v192
	v_exp_f32_e32 v193, v193
	v_exp_f32_e32 v194, v194
	v_mfma_f32_32x32x16_bf16 v[32:47], v[120:123], v[52:55], v[32:47]
	v_exp_f32_e32 v195, v195
	v_exp_f32_e32 v196, v196
	v_exp_f32_e32 v197, v197
	v_mfma_f32_32x32x16_bf16 v[32:47], v[124:127], v[56:59], v[32:47]
	v_exp_f32_e32 v198, v198
	v_exp_f32_e32 v199, v199
	v_exp_f32_e32 v200, v200
	v_mfma_f32_32x32x16_bf16 v[32:47], v[128:131], v[60:63], v[32:47]
	v_exp_f32_e32 v201, v201
	v_exp_f32_e32 v202, v202
	v_exp_f32_e32 v203, v203
	v_cvt_pk_bf16_f32 v64, v188, v189
	v_cvt_pk_bf16_f32 v65, v190, v191
	v_cvt_pk_bf16_f32 v66, v192, v193
	v_cvt_pk_bf16_f32 v67, v194, v195
	v_cvt_pk_bf16_f32 v68, v196, v197
	v_cvt_pk_bf16_f32 v69, v198, v199
	v_cvt_pk_bf16_f32 v70, v200, v201
	v_cvt_pk_bf16_f32 v71, v202, v203
	v_pk_add_f32 v[232:233], v[232:233], v[188:189]
	v_pk_add_f32 v[232:233], v[232:233], v[190:191]
	v_pk_add_f32 v[232:233], v[232:233], v[192:193]
	v_pk_add_f32 v[232:233], v[232:233], v[194:195]
	v_pk_add_f32 v[232:233], v[232:233], v[196:197]
	v_pk_add_f32 v[232:233], v[232:233], v[198:199]
	v_pk_add_f32 v[232:233], v[232:233], v[200:201]
	v_pk_add_f32 v[232:233], v[232:233], v[202:203]
	ds_read2_b32 v[188:189], v115 offset0:32 offset1:33
	ds_read2_b32 v[190:191], v115 offset0:34 offset1:35
	ds_read2_b32 v[192:193], v115 offset0:40 offset1:41
	ds_read2_b32 v[194:195], v115 offset0:42 offset1:43
	ds_read2_b32 v[196:197], v115 offset0:48 offset1:49
	ds_read2_b32 v[198:199], v115 offset0:50 offset1:51
	ds_read2_b32 v[200:201], v115 offset0:56 offset1:57
	ds_read2_b32 v[202:203], v115 offset0:58 offset1:59
	v_mfma_f32_32x32x16_bf16 v[0:15], v[64:67], v[72:75], v[0:15]
	v_mfma_f32_32x32x16_bf16 v[16:31], v[64:67], v[76:79], v[16:31]
	v_mfma_f32_32x32x16_bf16 v[0:15], v[68:71], v[220:223], v[0:15]
	v_mfma_f32_32x32x16_bf16 v[16:31], v[68:71], v[224:227], v[16:31]
	global_load_dwordx4 v[116:119], v239, s[86:87]
	global_load_dwordx4 v[120:123], v240, s[86:87]
	global_load_dwordx4 v[124:127], v241, s[86:87]
	global_load_dwordx4 v[128:131], v242, s[86:87]
	global_load_dwordx4 v[132:135], v101, s[86:87] offset:768
	global_load_dwordx4 v[136:139], v150, s[86:87] offset:768
	global_load_dwordx4 v[140:143], v101, s[86:87] offset:832
	global_load_dwordx4 v[144:147], v150, s[86:87] offset:832
	s_add_u32 s86, s86, 0xc0000
	s_addc_u32 s87, s87, 0
	ds_read_b64_tr_b16 v[72:73], v231
	ds_read_b64_tr_b16 v[74:75], v231 offset:512
	ds_read_b64_tr_b16 v[76:77], v231 offset:2048
	ds_read_b64_tr_b16 v[78:79], v231 offset:2560
	ds_read_b64_tr_b16 v[220:221], v231 offset:1024
	ds_read_b64_tr_b16 v[222:223], v231 offset:1536
	ds_read_b64_tr_b16 v[224:225], v231 offset:3072
	ds_read_b64_tr_b16 v[226:227], v231 offset:3584
	v_exp_f32_e32 v32, v32
	v_exp_f32_e32 v33, v33
	s_waitcnt vmcnt(8)
	ds_write_b128 v247, v[156:159]
	ds_write_b128 v247, v[160:163] offset:1024
	ds_write_b128 v247, v[164:167] offset:2048
	ds_write_b128 v247, v[168:171] offset:3072
	ds_read_b128 v[156:159], v248
	ds_read_b128 v[160:163], v249
	ds_read_b128 v[164:167], v250
	ds_read_b128 v[168:171], v251
	ds_write_b128 v112, v[172:175]
	ds_write_b128 v112, v[176:179] offset:1024
	ds_write_b128 v112, v[180:183] offset:2048
	ds_write_b128 v112, v[184:187] offset:3072
	v_exp_f32_e32 v34, v34
	v_exp_f32_e32 v35, v35
	s_waitcnt lgkmcnt(4)
	v_mfma_f32_32x32x16_bf16 v[188:203], v[156:159], v[48:51], v[188:203]
	v_exp_f32_e32 v36, v36
	v_exp_f32_e32 v37, v37
	v_exp_f32_e32 v38, v38
	v_mfma_f32_32x32x16_bf16 v[188:203], v[160:163], v[52:55], v[188:203]
	v_exp_f32_e32 v39, v39
	v_exp_f32_e32 v40, v40
	v_exp_f32_e32 v41, v41
	v_mfma_f32_32x32x16_bf16 v[188:203], v[164:167], v[56:59], v[188:203]
	v_exp_f32_e32 v42, v42
	v_exp_f32_e32 v43, v43
	v_exp_f32_e32 v44, v44
	v_mfma_f32_32x32x16_bf16 v[188:203], v[168:171], v[60:63], v[188:203]
	v_exp_f32_e32 v45, v45
	v_exp_f32_e32 v46, v46
	v_exp_f32_e32 v47, v47
	v_cvt_pk_bf16_f32 v64, v32, v33
	v_cvt_pk_bf16_f32 v65, v34, v35
	v_cvt_pk_bf16_f32 v66, v36, v37
	v_cvt_pk_bf16_f32 v67, v38, v39
	v_cvt_pk_bf16_f32 v68, v40, v41
	v_cvt_pk_bf16_f32 v69, v42, v43
	v_cvt_pk_bf16_f32 v70, v44, v45
	v_cvt_pk_bf16_f32 v71, v46, v47
	v_pk_add_f32 v[232:233], v[232:233], v[32:33]
	v_pk_add_f32 v[232:233], v[232:233], v[34:35]
	v_pk_add_f32 v[232:233], v[232:233], v[36:37]
	v_pk_add_f32 v[232:233], v[232:233], v[38:39]
	v_pk_add_f32 v[232:233], v[232:233], v[40:41]
	v_pk_add_f32 v[232:233], v[232:233], v[42:43]
	v_pk_add_f32 v[232:233], v[232:233], v[44:45]
	v_pk_add_f32 v[232:233], v[232:233], v[46:47]
	ds_read2_b32 v[32:33], v115 offset0:64 offset1:65
	ds_read2_b32 v[34:35], v115 offset0:66 offset1:67
	ds_read2_b32 v[36:37], v115 offset0:72 offset1:73
	ds_read2_b32 v[38:39], v115 offset0:74 offset1:75
	ds_read2_b32 v[40:41], v115 offset0:80 offset1:81
	ds_read2_b32 v[42:43], v115 offset0:82 offset1:83
	ds_read2_b32 v[44:45], v115 offset0:88 offset1:89
	ds_read2_b32 v[46:47], v115 offset0:90 offset1:91
	v_mfma_f32_32x32x16_bf16 v[0:15], v[64:67], v[72:75], v[0:15]
	v_mfma_f32_32x32x16_bf16 v[16:31], v[64:67], v[76:79], v[16:31]
	v_mfma_f32_32x32x16_bf16 v[0:15], v[68:71], v[220:223], v[0:15]
	v_mfma_f32_32x32x16_bf16 v[16:31], v[68:71], v[224:227], v[16:31]
	global_load_dwordx4 v[156:159], v239, s[86:87]
	global_load_dwordx4 v[160:163], v240, s[86:87]
	global_load_dwordx4 v[164:167], v241, s[86:87]
	global_load_dwordx4 v[168:171], v242, s[86:87]
	global_load_dwordx4 v[172:175], v101, s[86:87] offset:768
	global_load_dwordx4 v[176:179], v150, s[86:87] offset:768
	global_load_dwordx4 v[180:183], v101, s[86:87] offset:832
	global_load_dwordx4 v[184:187], v150, s[86:87] offset:832
	s_add_u32 s86, s86, 0xc0000
	s_addc_u32 s87, s87, 0
	ds_read_b64_tr_b16 v[72:73], v231
	ds_read_b64_tr_b16 v[74:75], v231 offset:512
	ds_read_b64_tr_b16 v[76:77], v231 offset:2048
	ds_read_b64_tr_b16 v[78:79], v231 offset:2560
	ds_read_b64_tr_b16 v[220:221], v231 offset:1024
	ds_read_b64_tr_b16 v[222:223], v231 offset:1536
	ds_read_b64_tr_b16 v[224:225], v231 offset:3072
	ds_read_b64_tr_b16 v[226:227], v231 offset:3584
	v_exp_f32_e32 v188, v188
	v_exp_f32_e32 v189, v189
	s_waitcnt vmcnt(8)
	ds_write_b128 v247, v[116:119]
	ds_write_b128 v247, v[120:123] offset:1024
	ds_write_b128 v247, v[124:127] offset:2048
	ds_write_b128 v247, v[128:131] offset:3072
	ds_read_b128 v[116:119], v248
	ds_read_b128 v[120:123], v249
	ds_read_b128 v[124:127], v250
	ds_read_b128 v[128:131], v251
	ds_write_b128 v112, v[132:135]
	ds_write_b128 v112, v[136:139] offset:1024
	ds_write_b128 v112, v[140:143] offset:2048
	ds_write_b128 v112, v[144:147] offset:3072
	v_exp_f32_e32 v190, v190
	v_exp_f32_e32 v191, v191
	s_waitcnt lgkmcnt(4)
	v_mfma_f32_32x32x16_bf16 v[32:47], v[116:119], v[48:51], v[32:47]
	v_exp_f32_e32 v192, v192
	v_exp_f32_e32 v193, v193
	v_exp_f32_e32 v194, v194
	v_mfma_f32_32x32x16_bf16 v[32:47], v[120:123], v[52:55], v[32:47]
	v_exp_f32_e32 v195, v195
	v_exp_f32_e32 v196, v196
	v_exp_f32_e32 v197, v197
	v_mfma_f32_32x32x16_bf16 v[32:47], v[124:127], v[56:59], v[32:47]
	v_exp_f32_e32 v198, v198
	v_exp_f32_e32 v199, v199
	v_exp_f32_e32 v200, v200
	v_mfma_f32_32x32x16_bf16 v[32:47], v[128:131], v[60:63], v[32:47]
	v_exp_f32_e32 v201, v201
	v_exp_f32_e32 v202, v202
	v_exp_f32_e32 v203, v203
	v_cvt_pk_bf16_f32 v64, v188, v189
	v_cvt_pk_bf16_f32 v65, v190, v191
	v_cvt_pk_bf16_f32 v66, v192, v193
	v_cvt_pk_bf16_f32 v67, v194, v195
	v_cvt_pk_bf16_f32 v68, v196, v197
	v_cvt_pk_bf16_f32 v69, v198, v199
	v_cvt_pk_bf16_f32 v70, v200, v201
	v_cvt_pk_bf16_f32 v71, v202, v203
	v_pk_add_f32 v[232:233], v[232:233], v[188:189]
	v_pk_add_f32 v[232:233], v[232:233], v[190:191]
	v_pk_add_f32 v[232:233], v[232:233], v[192:193]
	v_pk_add_f32 v[232:233], v[232:233], v[194:195]
	v_pk_add_f32 v[232:233], v[232:233], v[196:197]
	v_pk_add_f32 v[232:233], v[232:233], v[198:199]
	v_pk_add_f32 v[232:233], v[232:233], v[200:201]
	v_pk_add_f32 v[232:233], v[232:233], v[202:203]
	ds_read2_b32 v[188:189], v115 offset0:96 offset1:97
	ds_read2_b32 v[190:191], v115 offset0:98 offset1:99
	ds_read2_b32 v[192:193], v115 offset0:104 offset1:105
	ds_read2_b32 v[194:195], v115 offset0:106 offset1:107
	ds_read2_b32 v[196:197], v115 offset0:112 offset1:113
	ds_read2_b32 v[198:199], v115 offset0:114 offset1:115
	ds_read2_b32 v[200:201], v115 offset0:120 offset1:121
	ds_read2_b32 v[202:203], v115 offset0:122 offset1:123
	v_mfma_f32_32x32x16_bf16 v[0:15], v[64:67], v[72:75], v[0:15]
	v_mfma_f32_32x32x16_bf16 v[16:31], v[64:67], v[76:79], v[16:31]
	v_mfma_f32_32x32x16_bf16 v[0:15], v[68:71], v[220:223], v[0:15]
	v_mfma_f32_32x32x16_bf16 v[16:31], v[68:71], v[224:227], v[16:31]
	global_load_dwordx4 v[116:119], v239, s[86:87]
	global_load_dwordx4 v[120:123], v240, s[86:87]
	global_load_dwordx4 v[124:127], v241, s[86:87]
	global_load_dwordx4 v[128:131], v242, s[86:87]
	global_load_dwordx4 v[132:135], v101, s[86:87] offset:768
	global_load_dwordx4 v[136:139], v150, s[86:87] offset:768
	global_load_dwordx4 v[140:143], v101, s[86:87] offset:832
	global_load_dwordx4 v[144:147], v150, s[86:87] offset:832
	s_add_u32 s86, s86, 0xc0000
	s_addc_u32 s87, s87, 0
	ds_read_b64_tr_b16 v[72:73], v231
	ds_read_b64_tr_b16 v[74:75], v231 offset:512
	ds_read_b64_tr_b16 v[76:77], v231 offset:2048
	ds_read_b64_tr_b16 v[78:79], v231 offset:2560
	ds_read_b64_tr_b16 v[220:221], v231 offset:1024
	ds_read_b64_tr_b16 v[222:223], v231 offset:1536
	ds_read_b64_tr_b16 v[224:225], v231 offset:3072
	ds_read_b64_tr_b16 v[226:227], v231 offset:3584
	v_exp_f32_e32 v32, v32
	v_exp_f32_e32 v33, v33
	s_waitcnt vmcnt(8)
	ds_write_b128 v247, v[156:159]
	ds_write_b128 v247, v[160:163] offset:1024
	ds_write_b128 v247, v[164:167] offset:2048
	ds_write_b128 v247, v[168:171] offset:3072
	ds_read_b128 v[156:159], v248
	ds_read_b128 v[160:163], v249
	ds_read_b128 v[164:167], v250
	ds_read_b128 v[168:171], v251
	ds_write_b128 v112, v[172:175]
	ds_write_b128 v112, v[176:179] offset:1024
	ds_write_b128 v112, v[180:183] offset:2048
	ds_write_b128 v112, v[184:187] offset:3072
	v_exp_f32_e32 v34, v34
	v_exp_f32_e32 v35, v35
	s_waitcnt lgkmcnt(4)
	v_mfma_f32_32x32x16_bf16 v[188:203], v[156:159], v[48:51], v[188:203]
	v_exp_f32_e32 v36, v36
	v_exp_f32_e32 v37, v37
	v_exp_f32_e32 v38, v38
	v_mfma_f32_32x32x16_bf16 v[188:203], v[160:163], v[52:55], v[188:203]
	v_exp_f32_e32 v39, v39
	v_exp_f32_e32 v40, v40
	v_exp_f32_e32 v41, v41
	v_mfma_f32_32x32x16_bf16 v[188:203], v[164:167], v[56:59], v[188:203]
	v_exp_f32_e32 v42, v42
	v_exp_f32_e32 v43, v43
	v_exp_f32_e32 v44, v44
	v_mfma_f32_32x32x16_bf16 v[188:203], v[168:171], v[60:63], v[188:203]
	v_exp_f32_e32 v45, v45
	v_exp_f32_e32 v46, v46
	v_exp_f32_e32 v47, v47
	v_cvt_pk_bf16_f32 v64, v32, v33
	v_cvt_pk_bf16_f32 v65, v34, v35
	v_cvt_pk_bf16_f32 v66, v36, v37
	v_cvt_pk_bf16_f32 v67, v38, v39
	v_cvt_pk_bf16_f32 v68, v40, v41
	v_cvt_pk_bf16_f32 v69, v42, v43
	v_cvt_pk_bf16_f32 v70, v44, v45
	v_cvt_pk_bf16_f32 v71, v46, v47
	v_pk_add_f32 v[232:233], v[232:233], v[32:33]
	v_pk_add_f32 v[232:233], v[232:233], v[34:35]
	v_pk_add_f32 v[232:233], v[232:233], v[36:37]
	v_pk_add_f32 v[232:233], v[232:233], v[38:39]
	v_pk_add_f32 v[232:233], v[232:233], v[40:41]
	v_pk_add_f32 v[232:233], v[232:233], v[42:43]
	v_pk_add_f32 v[232:233], v[232:233], v[44:45]
	v_pk_add_f32 v[232:233], v[232:233], v[46:47]
	ds_read2_b32 v[32:33], v115 offset0:128 offset1:129
	ds_read2_b32 v[34:35], v115 offset0:130 offset1:131
	ds_read2_b32 v[36:37], v115 offset0:136 offset1:137
	ds_read2_b32 v[38:39], v115 offset0:138 offset1:139
	ds_read2_b32 v[40:41], v115 offset0:144 offset1:145
	ds_read2_b32 v[42:43], v115 offset0:146 offset1:147
	ds_read2_b32 v[44:45], v115 offset0:152 offset1:153
	ds_read2_b32 v[46:47], v115 offset0:154 offset1:155
	v_mfma_f32_32x32x16_bf16 v[0:15], v[64:67], v[72:75], v[0:15]
	v_mfma_f32_32x32x16_bf16 v[16:31], v[64:67], v[76:79], v[16:31]
	v_mfma_f32_32x32x16_bf16 v[0:15], v[68:71], v[220:223], v[0:15]
	v_mfma_f32_32x32x16_bf16 v[16:31], v[68:71], v[224:227], v[16:31]
	global_load_dwordx4 v[156:159], v239, s[86:87]
	global_load_dwordx4 v[160:163], v240, s[86:87]
	global_load_dwordx4 v[164:167], v241, s[86:87]
	global_load_dwordx4 v[168:171], v242, s[86:87]
	global_load_dwordx4 v[172:175], v101, s[86:87] offset:768
	global_load_dwordx4 v[176:179], v150, s[86:87] offset:768
	global_load_dwordx4 v[180:183], v101, s[86:87] offset:832
	global_load_dwordx4 v[184:187], v150, s[86:87] offset:832
	s_add_u32 s86, s86, 0xc0000
	s_addc_u32 s87, s87, 0
	ds_read_b64_tr_b16 v[72:73], v231
	ds_read_b64_tr_b16 v[74:75], v231 offset:512
	ds_read_b64_tr_b16 v[76:77], v231 offset:2048
	ds_read_b64_tr_b16 v[78:79], v231 offset:2560
	ds_read_b64_tr_b16 v[220:221], v231 offset:1024
	ds_read_b64_tr_b16 v[222:223], v231 offset:1536
	ds_read_b64_tr_b16 v[224:225], v231 offset:3072
	ds_read_b64_tr_b16 v[226:227], v231 offset:3584
	v_exp_f32_e32 v188, v188
	v_exp_f32_e32 v189, v189
	s_waitcnt vmcnt(8)
	ds_write_b128 v247, v[116:119]
	ds_write_b128 v247, v[120:123] offset:1024
	ds_write_b128 v247, v[124:127] offset:2048
	ds_write_b128 v247, v[128:131] offset:3072
	ds_read_b128 v[116:119], v248
	ds_read_b128 v[120:123], v249
	ds_read_b128 v[124:127], v250
	ds_read_b128 v[128:131], v251
	ds_write_b128 v112, v[132:135]
	ds_write_b128 v112, v[136:139] offset:1024
	ds_write_b128 v112, v[140:143] offset:2048
	ds_write_b128 v112, v[144:147] offset:3072
	v_exp_f32_e32 v190, v190
	v_exp_f32_e32 v191, v191
	s_waitcnt lgkmcnt(4)
	v_mfma_f32_32x32x16_bf16 v[32:47], v[116:119], v[48:51], v[32:47]
	v_exp_f32_e32 v192, v192
	v_exp_f32_e32 v193, v193
	v_exp_f32_e32 v194, v194
	v_mfma_f32_32x32x16_bf16 v[32:47], v[120:123], v[52:55], v[32:47]
	v_exp_f32_e32 v195, v195
	v_exp_f32_e32 v196, v196
	v_exp_f32_e32 v197, v197
	v_mfma_f32_32x32x16_bf16 v[32:47], v[124:127], v[56:59], v[32:47]
	v_exp_f32_e32 v198, v198
	v_exp_f32_e32 v199, v199
	v_exp_f32_e32 v200, v200
	v_mfma_f32_32x32x16_bf16 v[32:47], v[128:131], v[60:63], v[32:47]
	v_exp_f32_e32 v201, v201
	v_exp_f32_e32 v202, v202
	v_exp_f32_e32 v203, v203
	v_cvt_pk_bf16_f32 v64, v188, v189
	v_cvt_pk_bf16_f32 v65, v190, v191
	v_cvt_pk_bf16_f32 v66, v192, v193
	v_cvt_pk_bf16_f32 v67, v194, v195
	v_cvt_pk_bf16_f32 v68, v196, v197
	v_cvt_pk_bf16_f32 v69, v198, v199
	v_cvt_pk_bf16_f32 v70, v200, v201
	v_cvt_pk_bf16_f32 v71, v202, v203
	v_pk_add_f32 v[232:233], v[232:233], v[188:189]
	v_pk_add_f32 v[232:233], v[232:233], v[190:191]
	v_pk_add_f32 v[232:233], v[232:233], v[192:193]
	v_pk_add_f32 v[232:233], v[232:233], v[194:195]
	v_pk_add_f32 v[232:233], v[232:233], v[196:197]
	v_pk_add_f32 v[232:233], v[232:233], v[198:199]
	v_pk_add_f32 v[232:233], v[232:233], v[200:201]
	v_pk_add_f32 v[232:233], v[232:233], v[202:203]
	ds_read2_b32 v[188:189], v115 offset0:160 offset1:161
	ds_read2_b32 v[190:191], v115 offset0:162 offset1:163
	ds_read2_b32 v[192:193], v115 offset0:168 offset1:169
	ds_read2_b32 v[194:195], v115 offset0:170 offset1:171
	ds_read2_b32 v[196:197], v115 offset0:176 offset1:177
	ds_read2_b32 v[198:199], v115 offset0:178 offset1:179
	ds_read2_b32 v[200:201], v115 offset0:184 offset1:185
	ds_read2_b32 v[202:203], v115 offset0:186 offset1:187
	v_mfma_f32_32x32x16_bf16 v[0:15], v[64:67], v[72:75], v[0:15]
	v_mfma_f32_32x32x16_bf16 v[16:31], v[64:67], v[76:79], v[16:31]
	v_mfma_f32_32x32x16_bf16 v[0:15], v[68:71], v[220:223], v[0:15]
	v_mfma_f32_32x32x16_bf16 v[16:31], v[68:71], v[224:227], v[16:31]
	global_load_dwordx4 v[116:119], v239, s[86:87]
	global_load_dwordx4 v[120:123], v240, s[86:87]
	global_load_dwordx4 v[124:127], v241, s[86:87]
	global_load_dwordx4 v[128:131], v242, s[86:87]
	global_load_dwordx4 v[132:135], v101, s[86:87] offset:768
	global_load_dwordx4 v[136:139], v150, s[86:87] offset:768
	global_load_dwordx4 v[140:143], v101, s[86:87] offset:832
	global_load_dwordx4 v[144:147], v150, s[86:87] offset:832
	s_add_u32 s86, s86, 0xc0000
	s_addc_u32 s87, s87, 0
	ds_read_b64_tr_b16 v[72:73], v231
	ds_read_b64_tr_b16 v[74:75], v231 offset:512
	ds_read_b64_tr_b16 v[76:77], v231 offset:2048
	ds_read_b64_tr_b16 v[78:79], v231 offset:2560
	ds_read_b64_tr_b16 v[220:221], v231 offset:1024
	ds_read_b64_tr_b16 v[222:223], v231 offset:1536
	ds_read_b64_tr_b16 v[224:225], v231 offset:3072
	ds_read_b64_tr_b16 v[226:227], v231 offset:3584
	v_exp_f32_e32 v32, v32
	v_exp_f32_e32 v33, v33
	s_waitcnt vmcnt(8)
	ds_write_b128 v247, v[156:159]
	ds_write_b128 v247, v[160:163] offset:1024
	ds_write_b128 v247, v[164:167] offset:2048
	ds_write_b128 v247, v[168:171] offset:3072
	ds_read_b128 v[156:159], v248
	ds_read_b128 v[160:163], v249
	ds_read_b128 v[164:167], v250
	ds_read_b128 v[168:171], v251
	ds_write_b128 v112, v[172:175]
	ds_write_b128 v112, v[176:179] offset:1024
	ds_write_b128 v112, v[180:183] offset:2048
	ds_write_b128 v112, v[184:187] offset:3072
	v_exp_f32_e32 v34, v34
	v_exp_f32_e32 v35, v35
	s_waitcnt lgkmcnt(4)
	v_mfma_f32_32x32x16_bf16 v[188:203], v[156:159], v[48:51], v[188:203]
	v_exp_f32_e32 v36, v36
	v_exp_f32_e32 v37, v37
	v_exp_f32_e32 v38, v38
	v_mfma_f32_32x32x16_bf16 v[188:203], v[160:163], v[52:55], v[188:203]
	v_exp_f32_e32 v39, v39
	v_exp_f32_e32 v40, v40
	v_exp_f32_e32 v41, v41
	v_mfma_f32_32x32x16_bf16 v[188:203], v[164:167], v[56:59], v[188:203]
	v_exp_f32_e32 v42, v42
	v_exp_f32_e32 v43, v43
	v_exp_f32_e32 v44, v44
	v_mfma_f32_32x32x16_bf16 v[188:203], v[168:171], v[60:63], v[188:203]
	v_exp_f32_e32 v45, v45
	v_exp_f32_e32 v46, v46
	v_exp_f32_e32 v47, v47
	v_cvt_pk_bf16_f32 v64, v32, v33
	v_cvt_pk_bf16_f32 v65, v34, v35
	v_cvt_pk_bf16_f32 v66, v36, v37
	v_cvt_pk_bf16_f32 v67, v38, v39
	v_cvt_pk_bf16_f32 v68, v40, v41
	v_cvt_pk_bf16_f32 v69, v42, v43
	v_cvt_pk_bf16_f32 v70, v44, v45
	v_cvt_pk_bf16_f32 v71, v46, v47
	v_pk_add_f32 v[232:233], v[232:233], v[32:33]
	v_pk_add_f32 v[232:233], v[232:233], v[34:35]
	v_pk_add_f32 v[232:233], v[232:233], v[36:37]
	v_pk_add_f32 v[232:233], v[232:233], v[38:39]
	v_pk_add_f32 v[232:233], v[232:233], v[40:41]
	v_pk_add_f32 v[232:233], v[232:233], v[42:43]
	v_pk_add_f32 v[232:233], v[232:233], v[44:45]
	v_pk_add_f32 v[232:233], v[232:233], v[46:47]
	ds_read2_b32 v[32:33], v115 offset0:192 offset1:193
	ds_read2_b32 v[34:35], v115 offset0:194 offset1:195
	ds_read2_b32 v[36:37], v115 offset0:200 offset1:201
	ds_read2_b32 v[38:39], v115 offset0:202 offset1:203
	ds_read2_b32 v[40:41], v115 offset0:208 offset1:209
	ds_read2_b32 v[42:43], v115 offset0:210 offset1:211
	ds_read2_b32 v[44:45], v115 offset0:216 offset1:217
	ds_read2_b32 v[46:47], v115 offset0:218 offset1:219
	v_mfma_f32_32x32x16_bf16 v[0:15], v[64:67], v[72:75], v[0:15]
	v_mfma_f32_32x32x16_bf16 v[16:31], v[64:67], v[76:79], v[16:31]
	v_mfma_f32_32x32x16_bf16 v[0:15], v[68:71], v[220:223], v[0:15]
	v_mfma_f32_32x32x16_bf16 v[16:31], v[68:71], v[224:227], v[16:31]
	global_load_dwordx4 v[156:159], v239, s[86:87]
	global_load_dwordx4 v[160:163], v240, s[86:87]
	global_load_dwordx4 v[164:167], v241, s[86:87]
	global_load_dwordx4 v[168:171], v242, s[86:87]
	global_load_dwordx4 v[172:175], v101, s[86:87] offset:768
	global_load_dwordx4 v[176:179], v150, s[86:87] offset:768
	global_load_dwordx4 v[180:183], v101, s[86:87] offset:832
	global_load_dwordx4 v[184:187], v150, s[86:87] offset:832
	ds_read_b64_tr_b16 v[72:73], v231
	ds_read_b64_tr_b16 v[74:75], v231 offset:512
	ds_read_b64_tr_b16 v[76:77], v231 offset:2048
	ds_read_b64_tr_b16 v[78:79], v231 offset:2560
	ds_read_b64_tr_b16 v[220:221], v231 offset:1024
	ds_read_b64_tr_b16 v[222:223], v231 offset:1536
	ds_read_b64_tr_b16 v[224:225], v231 offset:3072
	ds_read_b64_tr_b16 v[226:227], v231 offset:3584
	v_exp_f32_e32 v188, v188
	v_exp_f32_e32 v189, v189
	s_waitcnt vmcnt(8)
	ds_write_b128 v247, v[116:119]
	ds_write_b128 v247, v[120:123] offset:1024
	ds_write_b128 v247, v[124:127] offset:2048
	ds_write_b128 v247, v[128:131] offset:3072
	ds_read_b128 v[116:119], v248
	ds_read_b128 v[120:123], v249
	ds_read_b128 v[124:127], v250
	ds_read_b128 v[128:131], v251
	ds_write_b128 v112, v[132:135]
	ds_write_b128 v112, v[136:139] offset:1024
	ds_write_b128 v112, v[140:143] offset:2048
	ds_write_b128 v112, v[144:147] offset:3072
	v_exp_f32_e32 v190, v190
	v_exp_f32_e32 v191, v191
	s_waitcnt lgkmcnt(4)
	v_mfma_f32_32x32x16_bf16 v[32:47], v[116:119], v[48:51], v[32:47]
	v_exp_f32_e32 v192, v192
	v_exp_f32_e32 v193, v193
	v_exp_f32_e32 v194, v194
	v_mfma_f32_32x32x16_bf16 v[32:47], v[120:123], v[52:55], v[32:47]
	v_exp_f32_e32 v195, v195
	v_exp_f32_e32 v196, v196
	v_exp_f32_e32 v197, v197
	v_mfma_f32_32x32x16_bf16 v[32:47], v[124:127], v[56:59], v[32:47]
	v_exp_f32_e32 v198, v198
	v_exp_f32_e32 v199, v199
	v_exp_f32_e32 v200, v200
	v_mfma_f32_32x32x16_bf16 v[32:47], v[128:131], v[60:63], v[32:47]
	v_exp_f32_e32 v201, v201
	v_exp_f32_e32 v202, v202
	v_exp_f32_e32 v203, v203
	v_cvt_pk_bf16_f32 v64, v188, v189
	v_cvt_pk_bf16_f32 v65, v190, v191
	v_cvt_pk_bf16_f32 v66, v192, v193
	v_cvt_pk_bf16_f32 v67, v194, v195
	v_cvt_pk_bf16_f32 v68, v196, v197
	v_cvt_pk_bf16_f32 v69, v198, v199
	v_cvt_pk_bf16_f32 v70, v200, v201
	v_cvt_pk_bf16_f32 v71, v202, v203
	v_pk_add_f32 v[232:233], v[232:233], v[188:189]
	v_pk_add_f32 v[232:233], v[232:233], v[190:191]
	v_pk_add_f32 v[232:233], v[232:233], v[192:193]
	v_pk_add_f32 v[232:233], v[232:233], v[194:195]
	v_pk_add_f32 v[232:233], v[232:233], v[196:197]
	v_pk_add_f32 v[232:233], v[232:233], v[198:199]
	v_pk_add_f32 v[232:233], v[232:233], v[200:201]
	v_pk_add_f32 v[232:233], v[232:233], v[202:203]
	ds_read2_b32 v[188:189], v115 offset0:224 offset1:225
	ds_read2_b32 v[190:191], v115 offset0:226 offset1:227
	ds_read2_b32 v[192:193], v115 offset0:232 offset1:233
	ds_read2_b32 v[194:195], v115 offset0:234 offset1:235
	ds_read2_b32 v[196:197], v115 offset0:240 offset1:241
	ds_read2_b32 v[198:199], v115 offset0:242 offset1:243
	ds_read2_b32 v[200:201], v115 offset0:248 offset1:249
	ds_read2_b32 v[202:203], v115 offset0:250 offset1:251
	v_mfma_f32_32x32x16_bf16 v[0:15], v[64:67], v[72:75], v[0:15]
	v_mfma_f32_32x32x16_bf16 v[16:31], v[64:67], v[76:79], v[16:31]
	v_mfma_f32_32x32x16_bf16 v[0:15], v[68:71], v[220:223], v[0:15]
	v_mfma_f32_32x32x16_bf16 v[16:31], v[68:71], v[224:227], v[16:31]
	global_load_dwordx4 v[116:119], v243, s[88:89]
	global_load_dwordx4 v[120:123], v244, s[88:89]
	global_load_dwordx4 v[124:127], v245, s[88:89]
	global_load_dwordx4 v[128:131], v246, s[88:89]
	global_load_dwordx4 v[132:135], v148, s[88:89] offset:768
	global_load_dwordx4 v[136:139], v151, s[88:89] offset:768
	global_load_dwordx4 v[140:143], v148, s[88:89] offset:832
	global_load_dwordx4 v[144:147], v151, s[88:89] offset:832
	s_add_u32 s88, s88, 0x300000
	s_addc_u32 s89, s89, 0
	ds_read_b64_tr_b16 v[72:73], v231
	ds_read_b64_tr_b16 v[74:75], v231 offset:512
	ds_read_b64_tr_b16 v[76:77], v231 offset:2048
	ds_read_b64_tr_b16 v[78:79], v231 offset:2560
	ds_read_b64_tr_b16 v[220:221], v231 offset:1024
	ds_read_b64_tr_b16 v[222:223], v231 offset:1536
	ds_read_b64_tr_b16 v[224:225], v231 offset:3072
	ds_read_b64_tr_b16 v[226:227], v231 offset:3584
	v_exp_f32_e32 v32, v32
	v_exp_f32_e32 v33, v33
	s_waitcnt vmcnt(8)
	ds_write_b128 v247, v[156:159]
	ds_write_b128 v247, v[160:163] offset:1024
	ds_write_b128 v247, v[164:167] offset:2048
	ds_write_b128 v247, v[168:171] offset:3072
	ds_read_b128 v[156:159], v248
	ds_read_b128 v[160:163], v249
	ds_read_b128 v[164:167], v250
	ds_read_b128 v[168:171], v251
	ds_write_b128 v112, v[172:175]
	ds_write_b128 v112, v[176:179] offset:1024
	ds_write_b128 v112, v[180:183] offset:2048
	ds_write_b128 v112, v[184:187] offset:3072
	v_exp_f32_e32 v34, v34
	v_exp_f32_e32 v35, v35
	s_waitcnt lgkmcnt(4)
	v_mfma_f32_32x32x16_bf16 v[188:203], v[156:159], v[48:51], v[188:203]
	v_exp_f32_e32 v36, v36
	v_exp_f32_e32 v37, v37
	v_exp_f32_e32 v38, v38
	v_mfma_f32_32x32x16_bf16 v[188:203], v[160:163], v[52:55], v[188:203]
	v_exp_f32_e32 v39, v39
	v_exp_f32_e32 v40, v40
	v_exp_f32_e32 v41, v41
	v_mfma_f32_32x32x16_bf16 v[188:203], v[164:167], v[56:59], v[188:203]
	v_exp_f32_e32 v42, v42
	v_exp_f32_e32 v43, v43
	v_exp_f32_e32 v44, v44
	v_mfma_f32_32x32x16_bf16 v[188:203], v[168:171], v[60:63], v[188:203]
	v_exp_f32_e32 v45, v45
	v_exp_f32_e32 v46, v46
	v_exp_f32_e32 v47, v47
	v_cvt_pk_bf16_f32 v64, v32, v33
	v_cvt_pk_bf16_f32 v65, v34, v35
	v_cvt_pk_bf16_f32 v66, v36, v37
	v_cvt_pk_bf16_f32 v67, v38, v39
	v_cvt_pk_bf16_f32 v68, v40, v41
	v_cvt_pk_bf16_f32 v69, v42, v43
	v_cvt_pk_bf16_f32 v70, v44, v45
	v_cvt_pk_bf16_f32 v71, v46, v47
	v_pk_add_f32 v[232:233], v[232:233], v[32:33]
	v_pk_add_f32 v[232:233], v[232:233], v[34:35]
	v_pk_add_f32 v[232:233], v[232:233], v[36:37]
	v_pk_add_f32 v[232:233], v[232:233], v[38:39]
	v_pk_add_f32 v[232:233], v[232:233], v[40:41]
	v_pk_add_f32 v[232:233], v[232:233], v[42:43]
	v_pk_add_f32 v[232:233], v[232:233], v[44:45]
	v_pk_add_f32 v[232:233], v[232:233], v[46:47]
	v_mov_b32_e32 v115, v230
	ds_read2_b32 v[32:33], v115 offset0:0 offset1:1
	ds_read2_b32 v[34:35], v115 offset0:2 offset1:3
	ds_read2_b32 v[36:37], v115 offset0:8 offset1:9
	ds_read2_b32 v[38:39], v115 offset0:10 offset1:11
	ds_read2_b32 v[40:41], v115 offset0:16 offset1:17
	ds_read2_b32 v[42:43], v115 offset0:18 offset1:19
	ds_read2_b32 v[44:45], v115 offset0:24 offset1:25
	ds_read2_b32 v[46:47], v115 offset0:26 offset1:27
	v_mfma_f32_32x32x16_bf16 v[0:15], v[64:67], v[72:75], v[0:15]
	v_mfma_f32_32x32x16_bf16 v[16:31], v[64:67], v[76:79], v[16:31]
	v_mfma_f32_32x32x16_bf16 v[0:15], v[68:71], v[220:223], v[0:15]
	v_mfma_f32_32x32x16_bf16 v[16:31], v[68:71], v[224:227], v[16:31]
	global_load_dwordx4 v[156:159], v243, s[88:89]
	global_load_dwordx4 v[160:163], v244, s[88:89]
	global_load_dwordx4 v[164:167], v245, s[88:89]
	global_load_dwordx4 v[168:171], v246, s[88:89]
	global_load_dwordx4 v[172:175], v148, s[88:89] offset:768
	global_load_dwordx4 v[176:179], v151, s[88:89] offset:768
	global_load_dwordx4 v[180:183], v148, s[88:89] offset:832
	global_load_dwordx4 v[184:187], v151, s[88:89] offset:832
	s_add_u32 s88, s88, 0x300000
	s_addc_u32 s89, s89, 0
	ds_read_b64_tr_b16 v[72:73], v231
	ds_read_b64_tr_b16 v[74:75], v231 offset:512
	ds_read_b64_tr_b16 v[76:77], v231 offset:2048
	ds_read_b64_tr_b16 v[78:79], v231 offset:2560
	ds_read_b64_tr_b16 v[220:221], v231 offset:1024
	ds_read_b64_tr_b16 v[222:223], v231 offset:1536
	ds_read_b64_tr_b16 v[224:225], v231 offset:3072
	ds_read_b64_tr_b16 v[226:227], v231 offset:3584
	v_exp_f32_e32 v188, v188
	v_exp_f32_e32 v189, v189
	s_waitcnt vmcnt(8)
	ds_write_b128 v247, v[116:119]
	ds_write_b128 v247, v[120:123] offset:1024
	ds_write_b128 v247, v[124:127] offset:2048
	ds_write_b128 v247, v[128:131] offset:3072
	ds_read_b128 v[116:119], v248
	ds_read_b128 v[120:123], v249
	ds_read_b128 v[124:127], v250
	ds_read_b128 v[128:131], v251
	ds_write_b128 v112, v[132:135]
	ds_write_b128 v112, v[136:139] offset:1024
	ds_write_b128 v112, v[140:143] offset:2048
	ds_write_b128 v112, v[144:147] offset:3072
	v_exp_f32_e32 v190, v190
	v_exp_f32_e32 v191, v191
	s_waitcnt lgkmcnt(4)
	v_mfma_f32_32x32x16_bf16 v[32:47], v[116:119], v[48:51], v[32:47]
	v_exp_f32_e32 v192, v192
	v_exp_f32_e32 v193, v193
	v_exp_f32_e32 v194, v194
	v_mfma_f32_32x32x16_bf16 v[32:47], v[120:123], v[52:55], v[32:47]
	v_exp_f32_e32 v195, v195
	v_exp_f32_e32 v196, v196
	v_exp_f32_e32 v197, v197
	v_mfma_f32_32x32x16_bf16 v[32:47], v[124:127], v[56:59], v[32:47]
	v_exp_f32_e32 v198, v198
	v_exp_f32_e32 v199, v199
	v_exp_f32_e32 v200, v200
	v_mfma_f32_32x32x16_bf16 v[32:47], v[128:131], v[60:63], v[32:47]
	v_exp_f32_e32 v201, v201
	v_exp_f32_e32 v202, v202
	v_exp_f32_e32 v203, v203
	v_cvt_pk_bf16_f32 v64, v188, v189
	v_cvt_pk_bf16_f32 v65, v190, v191
	v_cvt_pk_bf16_f32 v66, v192, v193
	v_cvt_pk_bf16_f32 v67, v194, v195
	v_cvt_pk_bf16_f32 v68, v196, v197
	v_cvt_pk_bf16_f32 v69, v198, v199
	v_cvt_pk_bf16_f32 v70, v200, v201
	v_cvt_pk_bf16_f32 v71, v202, v203
	v_pk_add_f32 v[232:233], v[232:233], v[188:189]
	v_pk_add_f32 v[232:233], v[232:233], v[190:191]
	v_pk_add_f32 v[232:233], v[232:233], v[192:193]
	v_pk_add_f32 v[232:233], v[232:233], v[194:195]
	v_pk_add_f32 v[232:233], v[232:233], v[196:197]
	v_pk_add_f32 v[232:233], v[232:233], v[198:199]
	v_pk_add_f32 v[232:233], v[232:233], v[200:201]
	v_pk_add_f32 v[232:233], v[232:233], v[202:203]
	ds_read2_b32 v[188:189], v115 offset0:32 offset1:33
	ds_read2_b32 v[190:191], v115 offset0:34 offset1:35
	ds_read2_b32 v[192:193], v115 offset0:40 offset1:41
	ds_read2_b32 v[194:195], v115 offset0:42 offset1:43
	ds_read2_b32 v[196:197], v115 offset0:48 offset1:49
	ds_read2_b32 v[198:199], v115 offset0:50 offset1:51
	ds_read2_b32 v[200:201], v115 offset0:56 offset1:57
	ds_read2_b32 v[202:203], v115 offset0:58 offset1:59
	v_mfma_f32_32x32x16_bf16 v[0:15], v[64:67], v[72:75], v[0:15]
	v_mfma_f32_32x32x16_bf16 v[16:31], v[64:67], v[76:79], v[16:31]
	v_mfma_f32_32x32x16_bf16 v[0:15], v[68:71], v[220:223], v[0:15]
	v_mfma_f32_32x32x16_bf16 v[16:31], v[68:71], v[224:227], v[16:31]
	global_load_dwordx4 v[116:119], v243, s[88:89]
	global_load_dwordx4 v[120:123], v244, s[88:89]
	global_load_dwordx4 v[124:127], v245, s[88:89]
	global_load_dwordx4 v[128:131], v246, s[88:89]
	global_load_dwordx4 v[132:135], v148, s[88:89] offset:768
	global_load_dwordx4 v[136:139], v151, s[88:89] offset:768
	global_load_dwordx4 v[140:143], v148, s[88:89] offset:832
	global_load_dwordx4 v[144:147], v151, s[88:89] offset:832
	s_add_u32 s88, s88, 0x300000
	s_addc_u32 s89, s89, 0
	ds_read_b64_tr_b16 v[72:73], v231
	ds_read_b64_tr_b16 v[74:75], v231 offset:512
	ds_read_b64_tr_b16 v[76:77], v231 offset:2048
	ds_read_b64_tr_b16 v[78:79], v231 offset:2560
	ds_read_b64_tr_b16 v[220:221], v231 offset:1024
	ds_read_b64_tr_b16 v[222:223], v231 offset:1536
	ds_read_b64_tr_b16 v[224:225], v231 offset:3072
	ds_read_b64_tr_b16 v[226:227], v231 offset:3584
	v_exp_f32_e32 v32, v32
	v_exp_f32_e32 v33, v33
	s_waitcnt vmcnt(8)
	ds_write_b128 v247, v[156:159]
	ds_write_b128 v247, v[160:163] offset:1024
	ds_write_b128 v247, v[164:167] offset:2048
	ds_write_b128 v247, v[168:171] offset:3072
	ds_read_b128 v[156:159], v248
	ds_read_b128 v[160:163], v249
	ds_read_b128 v[164:167], v250
	ds_read_b128 v[168:171], v251
	ds_write_b128 v112, v[172:175]
	ds_write_b128 v112, v[176:179] offset:1024
	ds_write_b128 v112, v[180:183] offset:2048
	ds_write_b128 v112, v[184:187] offset:3072
	v_exp_f32_e32 v34, v34
	v_exp_f32_e32 v35, v35
	s_waitcnt lgkmcnt(4)
	v_mfma_f32_32x32x16_bf16 v[188:203], v[156:159], v[48:51], v[188:203]
	v_exp_f32_e32 v36, v36
	v_exp_f32_e32 v37, v37
	v_exp_f32_e32 v38, v38
	v_mfma_f32_32x32x16_bf16 v[188:203], v[160:163], v[52:55], v[188:203]
	v_exp_f32_e32 v39, v39
	v_exp_f32_e32 v40, v40
	v_exp_f32_e32 v41, v41
	v_mfma_f32_32x32x16_bf16 v[188:203], v[164:167], v[56:59], v[188:203]
	v_exp_f32_e32 v42, v42
	v_exp_f32_e32 v43, v43
	v_exp_f32_e32 v44, v44
	v_mfma_f32_32x32x16_bf16 v[188:203], v[168:171], v[60:63], v[188:203]
	v_exp_f32_e32 v45, v45
	v_exp_f32_e32 v46, v46
	v_exp_f32_e32 v47, v47
	v_cvt_pk_bf16_f32 v64, v32, v33
	v_cvt_pk_bf16_f32 v65, v34, v35
	v_cvt_pk_bf16_f32 v66, v36, v37
	v_cvt_pk_bf16_f32 v67, v38, v39
	v_cvt_pk_bf16_f32 v68, v40, v41
	v_cvt_pk_bf16_f32 v69, v42, v43
	v_cvt_pk_bf16_f32 v70, v44, v45
	v_cvt_pk_bf16_f32 v71, v46, v47
	v_pk_add_f32 v[232:233], v[232:233], v[32:33]
	v_pk_add_f32 v[232:233], v[232:233], v[34:35]
	v_pk_add_f32 v[232:233], v[232:233], v[36:37]
	v_pk_add_f32 v[232:233], v[232:233], v[38:39]
	v_pk_add_f32 v[232:233], v[232:233], v[40:41]
	v_pk_add_f32 v[232:233], v[232:233], v[42:43]
	v_pk_add_f32 v[232:233], v[232:233], v[44:45]
	v_pk_add_f32 v[232:233], v[232:233], v[46:47]
	ds_read2_b32 v[32:33], v115 offset0:64 offset1:65
	ds_read2_b32 v[34:35], v115 offset0:66 offset1:67
	ds_read2_b32 v[36:37], v115 offset0:72 offset1:73
	ds_read2_b32 v[38:39], v115 offset0:74 offset1:75
	ds_read2_b32 v[40:41], v115 offset0:80 offset1:81
	ds_read2_b32 v[42:43], v115 offset0:82 offset1:83
	ds_read2_b32 v[44:45], v115 offset0:88 offset1:89
	ds_read2_b32 v[46:47], v115 offset0:90 offset1:91
	v_mfma_f32_32x32x16_bf16 v[0:15], v[64:67], v[72:75], v[0:15]
	v_mfma_f32_32x32x16_bf16 v[16:31], v[64:67], v[76:79], v[16:31]
	v_mfma_f32_32x32x16_bf16 v[0:15], v[68:71], v[220:223], v[0:15]
	v_mfma_f32_32x32x16_bf16 v[16:31], v[68:71], v[224:227], v[16:31]
	global_load_dwordx4 v[156:159], v243, s[88:89]
	global_load_dwordx4 v[160:163], v244, s[88:89]
	global_load_dwordx4 v[164:167], v245, s[88:89]
	global_load_dwordx4 v[168:171], v246, s[88:89]
	global_load_dwordx4 v[172:175], v148, s[88:89] offset:768
	global_load_dwordx4 v[176:179], v151, s[88:89] offset:768
	global_load_dwordx4 v[180:183], v148, s[88:89] offset:832
	global_load_dwordx4 v[184:187], v151, s[88:89] offset:832
	s_add_u32 s88, s88, 0x300000
	s_addc_u32 s89, s89, 0
	ds_read_b64_tr_b16 v[72:73], v231
	ds_read_b64_tr_b16 v[74:75], v231 offset:512
	ds_read_b64_tr_b16 v[76:77], v231 offset:2048
	ds_read_b64_tr_b16 v[78:79], v231 offset:2560
	ds_read_b64_tr_b16 v[220:221], v231 offset:1024
	ds_read_b64_tr_b16 v[222:223], v231 offset:1536
	ds_read_b64_tr_b16 v[224:225], v231 offset:3072
	ds_read_b64_tr_b16 v[226:227], v231 offset:3584
	v_exp_f32_e32 v188, v188
	v_exp_f32_e32 v189, v189
	s_waitcnt vmcnt(8)
	ds_write_b128 v247, v[116:119]
	ds_write_b128 v247, v[120:123] offset:1024
	ds_write_b128 v247, v[124:127] offset:2048
	ds_write_b128 v247, v[128:131] offset:3072
	ds_read_b128 v[116:119], v248
	ds_read_b128 v[120:123], v249
	ds_read_b128 v[124:127], v250
	ds_read_b128 v[128:131], v251
	ds_write_b128 v112, v[132:135]
	ds_write_b128 v112, v[136:139] offset:1024
	ds_write_b128 v112, v[140:143] offset:2048
	ds_write_b128 v112, v[144:147] offset:3072
	v_exp_f32_e32 v190, v190
	v_exp_f32_e32 v191, v191
	s_waitcnt lgkmcnt(4)
	v_mfma_f32_32x32x16_bf16 v[32:47], v[116:119], v[48:51], v[32:47]
	v_exp_f32_e32 v192, v192
	v_exp_f32_e32 v193, v193
	v_exp_f32_e32 v194, v194
	v_mfma_f32_32x32x16_bf16 v[32:47], v[120:123], v[52:55], v[32:47]
	v_exp_f32_e32 v195, v195
	v_exp_f32_e32 v196, v196
	v_exp_f32_e32 v197, v197
	v_mfma_f32_32x32x16_bf16 v[32:47], v[124:127], v[56:59], v[32:47]
	v_exp_f32_e32 v198, v198
	v_exp_f32_e32 v199, v199
	v_exp_f32_e32 v200, v200
	v_mfma_f32_32x32x16_bf16 v[32:47], v[128:131], v[60:63], v[32:47]
	v_exp_f32_e32 v201, v201
	v_exp_f32_e32 v202, v202
	v_exp_f32_e32 v203, v203
	v_cvt_pk_bf16_f32 v64, v188, v189
	v_cvt_pk_bf16_f32 v65, v190, v191
	v_cvt_pk_bf16_f32 v66, v192, v193
	v_cvt_pk_bf16_f32 v67, v194, v195
	v_cvt_pk_bf16_f32 v68, v196, v197
	v_cvt_pk_bf16_f32 v69, v198, v199
	v_cvt_pk_bf16_f32 v70, v200, v201
	v_cvt_pk_bf16_f32 v71, v202, v203
	v_pk_add_f32 v[232:233], v[232:233], v[188:189]
	v_pk_add_f32 v[232:233], v[232:233], v[190:191]
	v_pk_add_f32 v[232:233], v[232:233], v[192:193]
	v_pk_add_f32 v[232:233], v[232:233], v[194:195]
	v_pk_add_f32 v[232:233], v[232:233], v[196:197]
	v_pk_add_f32 v[232:233], v[232:233], v[198:199]
	v_pk_add_f32 v[232:233], v[232:233], v[200:201]
	v_pk_add_f32 v[232:233], v[232:233], v[202:203]
	ds_read2_b32 v[188:189], v115 offset0:96 offset1:97
	ds_read2_b32 v[190:191], v115 offset0:98 offset1:99
	ds_read2_b32 v[192:193], v115 offset0:104 offset1:105
	ds_read2_b32 v[194:195], v115 offset0:106 offset1:107
	ds_read2_b32 v[196:197], v115 offset0:112 offset1:113
	ds_read2_b32 v[198:199], v115 offset0:114 offset1:115
	ds_read2_b32 v[200:201], v115 offset0:120 offset1:121
	ds_read2_b32 v[202:203], v115 offset0:122 offset1:123
	v_mfma_f32_32x32x16_bf16 v[0:15], v[64:67], v[72:75], v[0:15]
	v_mfma_f32_32x32x16_bf16 v[16:31], v[64:67], v[76:79], v[16:31]
	v_mfma_f32_32x32x16_bf16 v[0:15], v[68:71], v[220:223], v[0:15]
	v_mfma_f32_32x32x16_bf16 v[16:31], v[68:71], v[224:227], v[16:31]
	global_load_dwordx4 v[116:119], v243, s[88:89]
	global_load_dwordx4 v[120:123], v244, s[88:89]
	global_load_dwordx4 v[124:127], v245, s[88:89]
	global_load_dwordx4 v[128:131], v246, s[88:89]
	global_load_dwordx4 v[132:135], v148, s[88:89] offset:768
	global_load_dwordx4 v[136:139], v151, s[88:89] offset:768
	global_load_dwordx4 v[140:143], v148, s[88:89] offset:832
	global_load_dwordx4 v[144:147], v151, s[88:89] offset:832
	ds_read_b64_tr_b16 v[72:73], v231
	ds_read_b64_tr_b16 v[74:75], v231 offset:512
	ds_read_b64_tr_b16 v[76:77], v231 offset:2048
	ds_read_b64_tr_b16 v[78:79], v231 offset:2560
	ds_read_b64_tr_b16 v[220:221], v231 offset:1024
	ds_read_b64_tr_b16 v[222:223], v231 offset:1536
	ds_read_b64_tr_b16 v[224:225], v231 offset:3072
	ds_read_b64_tr_b16 v[226:227], v231 offset:3584
	v_exp_f32_e32 v32, v32
	v_exp_f32_e32 v33, v33
	s_waitcnt vmcnt(8)
	ds_write_b128 v247, v[156:159]
	ds_write_b128 v247, v[160:163] offset:1024
	ds_write_b128 v247, v[164:167] offset:2048
	ds_write_b128 v247, v[168:171] offset:3072
	ds_read_b128 v[156:159], v248
	ds_read_b128 v[160:163], v249
	ds_read_b128 v[164:167], v250
	ds_read_b128 v[168:171], v251
	ds_write_b128 v112, v[172:175]
	ds_write_b128 v112, v[176:179] offset:1024
	ds_write_b128 v112, v[180:183] offset:2048
	ds_write_b128 v112, v[184:187] offset:3072
	v_exp_f32_e32 v34, v34
	v_exp_f32_e32 v35, v35
	s_waitcnt lgkmcnt(4)
	v_mfma_f32_32x32x16_bf16 v[188:203], v[156:159], v[48:51], v[188:203]
	v_exp_f32_e32 v36, v36
	v_exp_f32_e32 v37, v37
	v_exp_f32_e32 v38, v38
	v_mfma_f32_32x32x16_bf16 v[188:203], v[160:163], v[52:55], v[188:203]
	v_exp_f32_e32 v39, v39
	v_exp_f32_e32 v40, v40
	v_exp_f32_e32 v41, v41
	v_mfma_f32_32x32x16_bf16 v[188:203], v[164:167], v[56:59], v[188:203]
	v_exp_f32_e32 v42, v42
	v_exp_f32_e32 v43, v43
	v_exp_f32_e32 v44, v44
	v_mfma_f32_32x32x16_bf16 v[188:203], v[168:171], v[60:63], v[188:203]
	v_exp_f32_e32 v45, v45
	v_exp_f32_e32 v46, v46
	v_exp_f32_e32 v47, v47
	v_cvt_pk_bf16_f32 v64, v32, v33
	v_cvt_pk_bf16_f32 v65, v34, v35
	v_cvt_pk_bf16_f32 v66, v36, v37
	v_cvt_pk_bf16_f32 v67, v38, v39
	v_cvt_pk_bf16_f32 v68, v40, v41
	v_cvt_pk_bf16_f32 v69, v42, v43
	v_cvt_pk_bf16_f32 v70, v44, v45
	v_cvt_pk_bf16_f32 v71, v46, v47
	v_pk_add_f32 v[232:233], v[232:233], v[32:33]
	v_pk_add_f32 v[232:233], v[232:233], v[34:35]
	v_pk_add_f32 v[232:233], v[232:233], v[36:37]
	v_pk_add_f32 v[232:233], v[232:233], v[38:39]
	v_pk_add_f32 v[232:233], v[232:233], v[40:41]
	v_pk_add_f32 v[232:233], v[232:233], v[42:43]
	v_pk_add_f32 v[232:233], v[232:233], v[44:45]
	v_pk_add_f32 v[232:233], v[232:233], v[46:47]
	ds_read2_b32 v[32:33], v115 offset0:128 offset1:129
	ds_read2_b32 v[34:35], v115 offset0:130 offset1:131
	ds_read2_b32 v[36:37], v115 offset0:136 offset1:137
	ds_read2_b32 v[38:39], v115 offset0:138 offset1:139
	ds_read2_b32 v[40:41], v115 offset0:144 offset1:145
	ds_read2_b32 v[42:43], v115 offset0:146 offset1:147
	ds_read2_b32 v[44:45], v115 offset0:152 offset1:153
	ds_read2_b32 v[46:47], v115 offset0:154 offset1:155
	v_mfma_f32_32x32x16_bf16 v[0:15], v[64:67], v[72:75], v[0:15]
	v_mfma_f32_32x32x16_bf16 v[16:31], v[64:67], v[76:79], v[16:31]
	v_mfma_f32_32x32x16_bf16 v[0:15], v[68:71], v[220:223], v[0:15]
	v_mfma_f32_32x32x16_bf16 v[16:31], v[68:71], v[224:227], v[16:31]
	ds_read_b64_tr_b16 v[72:73], v231
	ds_read_b64_tr_b16 v[74:75], v231 offset:512
	ds_read_b64_tr_b16 v[76:77], v231 offset:2048
	ds_read_b64_tr_b16 v[78:79], v231 offset:2560
	ds_read_b64_tr_b16 v[220:221], v231 offset:1024
	ds_read_b64_tr_b16 v[222:223], v231 offset:1536
	ds_read_b64_tr_b16 v[224:225], v231 offset:3072
	ds_read_b64_tr_b16 v[226:227], v231 offset:3584
	v_exp_f32_e32 v188, v188
	v_exp_f32_e32 v189, v189
	s_waitcnt vmcnt(0)
; #define LAS __attribute__((address_space(3)))
; #define GAS __attribute__((address_space(1)))
; __device__ __forceinline__ void dil_unit(LAS unsigned char* lds, bf16_t* proj, int seq, int hd, int T0, int rho) {
;     ...
;     bf16_t* base = proj + (size_t)seq * SEQ * NIN;
;     LAS unsigned char* wbuf = lds + wid * 4096;
;     const LAS unsigned char* vp = wbuf + ((lane >> 4) & 1) * 32 + (lane & 3) * 8 + (4 * hi + ((lane & 15) >> 2)) * 64;
;     const int P0 = T0 + rho;
;     bf16x8 qr[4];
; #pragma unroll
;     for (int ks = 0; ks < 4; ++ks) qr[ks] = *(const GAS bf16x8*)(base + (size_t)(P0 + 16 * r32) * NIN + PC_LQ + hd * 64 + 16 * ks + 8 * hi);
;     f32x16 o0 = {}, o1 = {}; float l = 0.f;
;     const bool bound = (T0 < 1024) || (T0 >= 15360);
	ds_write_b128 v247, v[116:119]
	ds_write_b128 v247, v[120:123] offset:1024
	ds_write_b128 v247, v[124:127] offset:2048
	ds_write_b128 v247, v[128:131] offset:3072
	ds_read_b128 v[116:119], v248
	ds_read_b128 v[120:123], v249
	ds_read_b128 v[124:127], v250
	ds_read_b128 v[128:131], v251
	ds_write_b128 v112, v[132:135]
	ds_write_b128 v112, v[136:139] offset:1024
	ds_write_b128 v112, v[140:143] offset:2048
	ds_write_b128 v112, v[144:147] offset:3072
	v_exp_f32_e32 v190, v190
	v_exp_f32_e32 v191, v191
	s_waitcnt lgkmcnt(4)
	v_mfma_f32_32x32x16_bf16 v[32:47], v[116:119], v[48:51], v[32:47]
	v_exp_f32_e32 v192, v192
	v_exp_f32_e32 v193, v193
	v_exp_f32_e32 v194, v194
	v_mfma_f32_32x32x16_bf16 v[32:47], v[120:123], v[52:55], v[32:47]
	v_exp_f32_e32 v195, v195
	v_exp_f32_e32 v196, v196
	v_exp_f32_e32 v197, v197
	v_mfma_f32_32x32x16_bf16 v[32:47], v[124:127], v[56:59], v[32:47]
	v_exp_f32_e32 v198, v198
	v_exp_f32_e32 v199, v199
	v_exp_f32_e32 v200, v200
	v_mfma_f32_32x32x16_bf16 v[32:47], v[128:131], v[60:63], v[32:47]
	v_exp_f32_e32 v201, v201
	v_exp_f32_e32 v202, v202
	v_exp_f32_e32 v203, v203
	v_cvt_pk_bf16_f32 v64, v188, v189
	v_cvt_pk_bf16_f32 v65, v190, v191
	v_cvt_pk_bf16_f32 v66, v192, v193
	v_cvt_pk_bf16_f32 v67, v194, v195
	v_cvt_pk_bf16_f32 v68, v196, v197
	v_cvt_pk_bf16_f32 v69, v198, v199
	v_cvt_pk_bf16_f32 v70, v200, v201
	v_cvt_pk_bf16_f32 v71, v202, v203
	v_pk_add_f32 v[232:233], v[232:233], v[188:189]
	v_pk_add_f32 v[232:233], v[232:233], v[190:191]
	v_pk_add_f32 v[232:233], v[232:233], v[192:193]
	v_pk_add_f32 v[232:233], v[232:233], v[194:195]
	v_pk_add_f32 v[232:233], v[232:233], v[196:197]
	v_pk_add_f32 v[232:233], v[232:233], v[198:199]
	v_pk_add_f32 v[232:233], v[232:233], v[200:201]
	v_pk_add_f32 v[232:233], v[232:233], v[202:203]
	v_mfma_f32_32x32x16_bf16 v[0:15], v[64:67], v[72:75], v[0:15]
	v_mfma_f32_32x32x16_bf16 v[16:31], v[64:67], v[76:79], v[16:31]
	v_mfma_f32_32x32x16_bf16 v[0:15], v[68:71], v[220:223], v[0:15]
	v_mfma_f32_32x32x16_bf16 v[16:31], v[68:71], v[224:227], v[16:31]
	ds_read_b64_tr_b16 v[72:73], v231
	ds_read_b64_tr_b16 v[74:75], v231 offset:512
	ds_read_b64_tr_b16 v[76:77], v231 offset:2048
	ds_read_b64_tr_b16 v[78:79], v231 offset:2560
	ds_read_b64_tr_b16 v[220:221], v231 offset:1024
	ds_read_b64_tr_b16 v[222:223], v231 offset:1536
	ds_read_b64_tr_b16 v[224:225], v231 offset:3072
	ds_read_b64_tr_b16 v[226:227], v231 offset:3584
	s_waitcnt lgkmcnt(0)
	v_exp_f32_e32 v32, v32
	v_exp_f32_e32 v33, v33
	v_exp_f32_e32 v34, v34
	v_exp_f32_e32 v35, v35
	v_exp_f32_e32 v36, v36
	v_exp_f32_e32 v37, v37
	v_exp_f32_e32 v38, v38
	v_exp_f32_e32 v39, v39
	v_exp_f32_e32 v40, v40
	v_exp_f32_e32 v41, v41
	v_exp_f32_e32 v42, v42
	v_exp_f32_e32 v43, v43
	v_exp_f32_e32 v44, v44
	v_exp_f32_e32 v45, v45
	v_exp_f32_e32 v46, v46
	v_exp_f32_e32 v47, v47
	v_cvt_pk_bf16_f32 v64, v32, v33
	v_cvt_pk_bf16_f32 v65, v34, v35
	v_cvt_pk_bf16_f32 v66, v36, v37
	v_cvt_pk_bf16_f32 v67, v38, v39
	v_cvt_pk_bf16_f32 v68, v40, v41
	v_cvt_pk_bf16_f32 v69, v42, v43
	v_cvt_pk_bf16_f32 v70, v44, v45
	v_cvt_pk_bf16_f32 v71, v46, v47
	v_pk_add_f32 v[232:233], v[232:233], v[32:33]
	v_pk_add_f32 v[232:233], v[232:233], v[34:35]
	v_pk_add_f32 v[232:233], v[232:233], v[36:37]
	v_pk_add_f32 v[232:233], v[232:233], v[38:39]
	v_pk_add_f32 v[232:233], v[232:233], v[40:41]
	v_pk_add_f32 v[232:233], v[232:233], v[42:43]
	v_pk_add_f32 v[232:233], v[232:233], v[44:45]
	v_pk_add_f32 v[232:233], v[232:233], v[46:47]
	v_mfma_f32_32x32x16_bf16 v[0:15], v[64:67], v[72:75], v[0:15]
	v_mfma_f32_32x32x16_bf16 v[16:31], v[64:67], v[76:79], v[16:31]
	v_mfma_f32_32x32x16_bf16 v[0:15], v[68:71], v[220:223], v[0:15]
	v_mfma_f32_32x32x16_bf16 v[16:31], v[68:71], v[224:227], v[16:31]
	v_add_f32_e32 v113, v232, v233
	v_or_b32_e32 v114, 1, v107
	v_or_b32_e32 v97, 2, v107
	v_or_b32_e32 v96, 3, v107
	v_or_b32_e32 v95, 8, v107
	v_or_b32_e32 v94, 9, v107
	v_or_b32_e32 v93, 10, v107
	v_or_b32_e32 v92, 11, v107
	v_or_b32_e32 v91, 16, v107
	v_or_b32_e32 v90, 17, v107
	v_or_b32_e32 v89, 18, v107
	v_or_b32_e32 v88, 19, v107
	v_or_b32_e32 v87, 24, v107
	v_or_b32_e32 v86, 25, v107
	v_or_b32_e32 v85, 26, v107
	v_or_b32_e32 v84, 27, v107
	s_nop 11
	s_branch .LBB0_1265
.LBB0_1270:
	s_movk_i32 s100, 0x1800
	s_add_i32 s101, s8, 0x15c00
	s_lshl_b32 s90, s54, 1
	s_add_u32 s82, s52, s90
	s_addc_u32 s83, s53, 0
	s_add_u32 s82, s82, 0x1200
	s_addc_u32 s83, s83, 0
	s_sub_i32 s90, s67, 64
	s_mul_i32 s90, s90, 0x1800
	s_add_u32 s84, s82, s90
	s_addc_u32 s85, s83, 0
	s_sub_i32 s90, s67, 256
	s_mul_i32 s90, s90, 0x1800
	s_add_u32 s86, s82, s90
	s_addc_u32 s87, s83, 0
	s_sub_i32 s90, s67, 1024
	s_mul_i32 s90, s90, 0x1800
	s_add_u32 s88, s82, s90
	s_addc_u32 s89, s83, 0
	v_lshlrev_b32_e32 v153, 1, v98
	v_mad_u32_u24 v80, v105, s100, v82
	v_mad_u32_u24 v100, v110, s100, v153
	v_add_u32_e32 v149, 0x18000, v100
	v_lshlrev_b32_e32 v83, 2, v105
	v_mad_u32_u24 v83, v83, s100, v82
	v_lshlrev_b32_e32 v101, 2, v110
	v_mad_u32_u24 v101, v101, s100, v153
	v_add_u32_e32 v150, 0x60000, v101
	v_lshlrev_b32_e32 v99, 4, v105
	v_mad_u32_u24 v99, v99, s100, v82
	v_lshlrev_b32_e32 v148, 4, v110
	v_mad_u32_u24 v148, v148, s100, v153
	v_add_u32_e32 v151, 0x180000, v148
	v_lshrrev_b32_e32 v249, 3, v103
	v_and_b32_e32 v250, 7, v103
	v_lshlrev_b32_e32 v250, 4, v250
	v_add_u32_e32 v235, 0, v249
	v_add_u32_e32 v236, 8, v249
	v_add_u32_e32 v237, 16, v249
	v_add_u32_e32 v238, 24, v249
	v_add_u32_e32 v239, 0, v249
	v_lshlrev_b32_e32 v239, 2, v239
	v_add_u32_e32 v240, 8, v249
	v_lshlrev_b32_e32 v240, 2, v240
	v_add_u32_e32 v241, 16, v249
	v_lshlrev_b32_e32 v241, 2, v241
	v_add_u32_e32 v242, 24, v249
	v_lshlrev_b32_e32 v242, 2, v242
; #define LAS __attribute__((address_space(3)))
; #define GAS __attribute__((address_space(1)))
; __device__ __forceinline__ void dil_unit(LAS unsigned char* lds, bf16_t* proj, int seq, int hd, int T0, int rho) {
;     ...
;     LAS unsigned char* wbuf = lds + wid * 4096;
;     const LAS unsigned char* vp = wbuf + ((lane >> 4) & 1) * 32 + (lane & 3) * 8 + (4 * hi + ((lane & 15) >> 2)) * 64;
;     const int P0 = T0 + rho;
;     bf16x8 qr[4];
; #pragma unroll
;     for (int ks = 0; ks < 4; ++ks) qr[ks] = *(const GAS bf16x8*)(base + (size_t)(P0 + 16 * r32) * NIN + PC_LQ + hd * 64 + 16 * ks + 8 * hi);
;     f32x16 o0 = {}, o1 = {}; float l = 0.f;
;     const bool bound = (T0 < 1024) || (T0 >= 15360);
	v_add_u32_e32 v243, 0, v249
	v_lshlrev_b32_e32 v243, 4, v243
	v_add_u32_e32 v244, 8, v249
	v_lshlrev_b32_e32 v244, 4, v244
	v_add_u32_e32 v245, 16, v249
	v_lshlrev_b32_e32 v245, 4, v245
	v_add_u32_e32 v246, 24, v249
	v_lshlrev_b32_e32 v246, 4, v246
	v_mov_b32_e32 v252, v250
	v_mov_b32_e32 v100, v110
	v_add_u32_e32 v149, 16, v100
	v_lshlrev_b32_e32 v101, 2, v110
	v_add_u32_e32 v150, 64, v101
	v_lshlrev_b32_e32 v148, 4, v110
	v_add_u32_e32 v151, 256, v148
	s_mov_b32 s98, 0x4000
	s_mov_b32 s99, 0x3fff
	v_and_b32_e32 v247, 7, v249
	v_lshlrev_b32_e32 v247, 4, v247
	v_xor_b32_e32 v247, v247, v112
	v_and_b32_e32 v153, 7, v105
	v_or_b32_e32 v248, 0, v106
	v_xor_b32_e32 v248, v248, v153
	v_lshlrev_b32_e32 v248, 4, v248
	v_lshl_add_u32 v248, v105, 7, v248
	v_add_u32_e32 v248, s69, v248
	v_or_b32_e32 v249, 2, v106
	v_xor_b32_e32 v249, v249, v153
	v_lshlrev_b32_e32 v249, 4, v249
	v_lshl_add_u32 v249, v105, 7, v249
	v_add_u32_e32 v249, s69, v249
	v_or_b32_e32 v250, 4, v106
	v_xor_b32_e32 v250, v250, v153
	v_lshlrev_b32_e32 v250, 4, v250
	v_lshl_add_u32 v250, v105, 7, v250
	v_add_u32_e32 v250, s69, v250
	v_or_b32_e32 v251, 6, v106
	v_xor_b32_e32 v251, v251, v153
	v_lshlrev_b32_e32 v251, 4, v251
	v_lshl_add_u32 v251, v105, 7, v251
	v_add_u32_e32 v251, s69, v251
	v_lshlrev_b32_e32 v153, 1, v98
	v_mul_u32_u24_e32 v228, 17, v105
	v_sub_u32_e32 v228, v107, v228
	s_mul_i32 s90, s54, 153
	s_lshr_b32 s90, s90, 1
	s_add_i32 s90, s90, 34876
	v_lshl_add_u32 v228, v228, 2, s90
	v_lshlrev_b32_e32 v229, 2, v105
	v_sub_u32_e32 v229, v107, v229
	s_add_i32 s90, s101, 5104
	v_lshl_add_u32 v229, v229, 2, s90
	v_sub_u32_e32 v230, v107, v105
	s_add_i32 s90, s101, 6364
	v_lshl_add_u32 v230, v230, 2, s90
	v_add_u32_e32 v231, v109, v108
	v_mov_b64_e32 v[232:233], 0
	v_mov_b64_e32 v[0:1], 0
	v_mov_b64_e32 v[2:3], 0
	v_mov_b64_e32 v[4:5], 0
	v_mov_b64_e32 v[6:7], 0
	v_mov_b64_e32 v[8:9], 0
	v_mov_b64_e32 v[10:11], 0
	v_mov_b64_e32 v[12:13], 0
	v_mov_b64_e32 v[14:15], 0
	v_mov_b64_e32 v[16:17], 0
	v_mov_b64_e32 v[18:19], 0
	v_mov_b64_e32 v[20:21], 0
	v_mov_b64_e32 v[22:23], 0
	v_mov_b64_e32 v[24:25], 0
	v_mov_b64_e32 v[26:27], 0
	v_mov_b64_e32 v[28:29], 0
	v_mov_b64_e32 v[30:31], 0
	s_add_i32 s90, s67, -64
	v_add_u32_e32 v80, s90, v235
	v_add_u32_e32 v83, s90, v236
	v_add_u32_e32 v99, s90, v237
	v_add_u32_e32 v253, s90, v238
	v_add_u32_e32 v254, s90, v100
	v_add_u32_e32 v255, s90, v149
	v_med3_i32 v80, v80, 0, s99
	v_med3_i32 v83, v83, 0, s99
	v_med3_i32 v99, v99, 0, s99
	v_med3_i32 v253, v253, 0, s99
	v_med3_i32 v254, v254, 0, s99
	v_med3_i32 v255, v255, 0, s99
	v_mad_u32_u24 v80, v80, s100, v252
	v_mad_u32_u24 v83, v83, s100, v252
	v_mad_u32_u24 v99, v99, s100, v252
	v_mad_u32_u24 v253, v253, s100, v252
	v_mad_u32_u24 v254, v254, s100, v153
	v_mad_u32_u24 v255, v255, s100, v153
	global_load_dwordx4 v[116:119], v80, s[82:83]
	global_load_dwordx4 v[120:123], v83, s[82:83]
	global_load_dwordx4 v[124:127], v99, s[82:83]
	global_load_dwordx4 v[128:131], v253, s[82:83]
	global_load_dwordx4 v[132:135], v254, s[82:83] offset:768
	global_load_dwordx4 v[136:139], v255, s[82:83] offset:768
	global_load_dwordx4 v[140:143], v254, s[82:83] offset:832
	global_load_dwordx4 v[144:147], v255, s[82:83] offset:832
	s_add_i32 s90, s67, -32
	v_add_u32_e32 v80, s90, v235
	v_add_u32_e32 v83, s90, v236
	v_add_u32_e32 v99, s90, v237
	v_add_u32_e32 v253, s90, v238
	v_add_u32_e32 v254, s90, v100
	v_add_u32_e32 v255, s90, v149
	v_med3_i32 v80, v80, 0, s99
	v_med3_i32 v83, v83, 0, s99
	v_med3_i32 v99, v99, 0, s99
	v_med3_i32 v253, v253, 0, s99
	v_med3_i32 v254, v254, 0, s99
	v_med3_i32 v255, v255, 0, s99
	v_mad_u32_u24 v80, v80, s100, v252
	v_mad_u32_u24 v83, v83, s100, v252
	v_mad_u32_u24 v99, v99, s100, v252
	v_mad_u32_u24 v253, v253, s100, v252
	v_mad_u32_u24 v254, v254, s100, v153
	v_mad_u32_u24 v255, v255, s100, v153
	global_load_dwordx4 v[156:159], v80, s[82:83]
	global_load_dwordx4 v[160:163], v83, s[82:83]
	global_load_dwordx4 v[164:167], v99, s[82:83]
	global_load_dwordx4 v[168:171], v253, s[82:83]
	global_load_dwordx4 v[172:175], v254, s[82:83] offset:768
	global_load_dwordx4 v[176:179], v255, s[82:83] offset:768
	global_load_dwordx4 v[180:183], v254, s[82:83] offset:832
	global_load_dwordx4 v[184:187], v255, s[82:83] offset:832
	v_mov_b32_e32 v115, v228
	ds_read2_b32 v[32:33], v115 offset0:0 offset1:1
	ds_read2_b32 v[34:35], v115 offset0:2 offset1:3
	ds_read2_b32 v[36:37], v115 offset0:8 offset1:9
	ds_read2_b32 v[38:39], v115 offset0:10 offset1:11
	ds_read2_b32 v[40:41], v115 offset0:17 offset1:18
	ds_read2_b32 v[42:43], v115 offset0:19 offset1:20
	ds_read2_b32 v[44:45], v115 offset0:25 offset1:26
	ds_read2_b32 v[46:47], v115 offset0:27 offset1:28
	s_waitcnt vmcnt(8)
	ds_write_b128 v247, v[116:119]
	ds_write_b128 v247, v[120:123] offset:1024
	ds_write_b128 v247, v[124:127] offset:2048
	ds_write_b128 v247, v[128:131] offset:3072
	ds_read_b128 v[116:119], v248
	ds_read_b128 v[120:123], v249
	ds_read_b128 v[124:127], v250
	ds_read_b128 v[128:131], v251
	ds_write_b128 v112, v[132:135]
	ds_write_b128 v112, v[136:139] offset:1024
	ds_write_b128 v112, v[140:143] offset:2048
	ds_write_b128 v112, v[144:147] offset:3072
	s_waitcnt lgkmcnt(4)
	v_mfma_f32_32x32x16_bf16 v[32:47], v[116:119], v[48:51], v[32:47]
	v_mfma_f32_32x32x16_bf16 v[32:47], v[120:123], v[52:55], v[32:47]
	v_mfma_f32_32x32x16_bf16 v[32:47], v[124:127], v[56:59], v[32:47]
	v_mfma_f32_32x32x16_bf16 v[32:47], v[128:131], v[60:63], v[32:47]
	ds_read2_b32 v[188:189], v115 offset0:34 offset1:35
	ds_read2_b32 v[190:191], v115 offset0:36 offset1:37
	ds_read2_b32 v[192:193], v115 offset0:42 offset1:43
	ds_read2_b32 v[194:195], v115 offset0:44 offset1:45
	ds_read2_b32 v[196:197], v115 offset0:51 offset1:52
	ds_read2_b32 v[198:199], v115 offset0:53 offset1:54
	ds_read2_b32 v[200:201], v115 offset0:59 offset1:60
	ds_read2_b32 v[202:203], v115 offset0:61 offset1:62
	s_add_i32 s90, s67, 0
	v_add_u32_e32 v80, s90, v235
	v_add_u32_e32 v83, s90, v236
	v_add_u32_e32 v99, s90, v237
	v_add_u32_e32 v253, s90, v238
	v_add_u32_e32 v254, s90, v100
	v_add_u32_e32 v255, s90, v149
	v_med3_i32 v80, v80, 0, s99
	v_med3_i32 v83, v83, 0, s99
	v_med3_i32 v99, v99, 0, s99
	v_med3_i32 v253, v253, 0, s99
	v_med3_i32 v254, v254, 0, s99
	v_med3_i32 v255, v255, 0, s99
	v_mad_u32_u24 v80, v80, s100, v252
	v_mad_u32_u24 v83, v83, s100, v252
	v_mad_u32_u24 v99, v99, s100, v252
	v_mad_u32_u24 v253, v253, s100, v252
	v_mad_u32_u24 v254, v254, s100, v153
	v_mad_u32_u24 v255, v255, s100, v153
	global_load_dwordx4 v[116:119], v80, s[82:83]
	global_load_dwordx4 v[120:123], v83, s[82:83]
	global_load_dwordx4 v[124:127], v99, s[82:83]
	global_load_dwordx4 v[128:131], v253, s[82:83]
	global_load_dwordx4 v[132:135], v254, s[82:83] offset:768
	global_load_dwordx4 v[136:139], v255, s[82:83] offset:768
	global_load_dwordx4 v[140:143], v254, s[82:83] offset:832
	global_load_dwordx4 v[144:147], v255, s[82:83] offset:832
	ds_read_b64_tr_b16 v[72:73], v231
	ds_read_b64_tr_b16 v[74:75], v231 offset:512
	ds_read_b64_tr_b16 v[76:77], v231 offset:2048
	ds_read_b64_tr_b16 v[78:79], v231 offset:2560
	ds_read_b64_tr_b16 v[220:221], v231 offset:1024
	ds_read_b64_tr_b16 v[222:223], v231 offset:1536
	ds_read_b64_tr_b16 v[224:225], v231 offset:3072
	ds_read_b64_tr_b16 v[226:227], v231 offset:3584
	v_exp_f32_e32 v32, v32
	v_exp_f32_e32 v33, v33
	s_waitcnt vmcnt(8)
	ds_write_b128 v247, v[156:159]
	ds_write_b128 v247, v[160:163] offset:1024
	ds_write_b128 v247, v[164:167] offset:2048
	ds_write_b128 v247, v[168:171] offset:3072
	ds_read_b128 v[156:159], v248
	ds_read_b128 v[160:163], v249
	ds_read_b128 v[164:167], v250
	ds_read_b128 v[168:171], v251
	ds_write_b128 v112, v[172:175]
	ds_write_b128 v112, v[176:179] offset:1024
	ds_write_b128 v112, v[180:183] offset:2048
	ds_write_b128 v112, v[184:187] offset:3072
	v_exp_f32_e32 v34, v34
	v_exp_f32_e32 v35, v35
	s_waitcnt lgkmcnt(4)
	v_mfma_f32_32x32x16_bf16 v[188:203], v[156:159], v[48:51], v[188:203]
	v_exp_f32_e32 v36, v36
	v_exp_f32_e32 v37, v37
	v_exp_f32_e32 v38, v38
	v_mfma_f32_32x32x16_bf16 v[188:203], v[160:163], v[52:55], v[188:203]
	v_exp_f32_e32 v39, v39
	v_exp_f32_e32 v40, v40
	v_exp_f32_e32 v41, v41
	v_mfma_f32_32x32x16_bf16 v[188:203], v[164:167], v[56:59], v[188:203]
	v_exp_f32_e32 v42, v42
	v_exp_f32_e32 v43, v43
	v_exp_f32_e32 v44, v44
	v_mfma_f32_32x32x16_bf16 v[188:203], v[168:171], v[60:63], v[188:203]
	v_exp_f32_e32 v45, v45
	v_exp_f32_e32 v46, v46
	v_exp_f32_e32 v47, v47
	s_add_i32 s90, s67, -64
	v_add_u32_e32 v84, s90, v107
	v_add_u32_e32 v85, 0, v84
	v_add_u32_e32 v86, 1, v84
	v_add_u32_e32 v87, 2, v84
	v_add_u32_e32 v88, 3, v84
	v_cmp_gt_u32_e64 s[30:31], s98, v85
	v_cmp_gt_u32_e64 s[36:37], s98, v86
	v_cmp_gt_u32_e64 s[78:79], s98, v87
	v_cmp_gt_u32_e64 s[50:51], s98, v88
	v_cndmask_b32_e64 v32, 0, v32, s[30:31]
	v_add_u32_e32 v85, 8, v84
	v_cmp_gt_u32_e64 s[30:31], s98, v85
	v_cndmask_b32_e64 v33, 0, v33, s[36:37]
	v_add_u32_e32 v86, 9, v84
	v_cmp_gt_u32_e64 s[36:37], s98, v86
	v_cndmask_b32_e64 v34, 0, v34, s[78:79]
	v_add_u32_e32 v87, 10, v84
	v_cmp_gt_u32_e64 s[78:79], s98, v87
	v_cndmask_b32_e64 v35, 0, v35, s[50:51]
	v_add_u32_e32 v88, 11, v84
	v_cmp_gt_u32_e64 s[50:51], s98, v88
	v_cndmask_b32_e64 v36, 0, v36, s[30:31]
	v_add_u32_e32 v85, 16, v84
	v_cmp_gt_u32_e64 s[30:31], s98, v85
	v_cndmask_b32_e64 v37, 0, v37, s[36:37]
	v_add_u32_e32 v86, 17, v84
	v_cmp_gt_u32_e64 s[36:37], s98, v86
	v_cndmask_b32_e64 v38, 0, v38, s[78:79]
	v_add_u32_e32 v87, 18, v84
	v_cmp_gt_u32_e64 s[78:79], s98, v87
	v_cndmask_b32_e64 v39, 0, v39, s[50:51]
	v_add_u32_e32 v88, 19, v84
	v_cmp_gt_u32_e64 s[50:51], s98, v88
	v_cndmask_b32_e64 v40, 0, v40, s[30:31]
	v_add_u32_e32 v85, 24, v84
	v_cmp_gt_u32_e64 s[30:31], s98, v85
	v_cndmask_b32_e64 v41, 0, v41, s[36:37]
	v_add_u32_e32 v86, 25, v84
	v_cmp_gt_u32_e64 s[36:37], s98, v86
	v_cndmask_b32_e64 v42, 0, v42, s[78:79]
	v_add_u32_e32 v87, 26, v84
	v_cmp_gt_u32_e64 s[78:79], s98, v87
	v_cndmask_b32_e64 v43, 0, v43, s[50:51]
	v_add_u32_e32 v88, 27, v84
	v_cmp_gt_u32_e64 s[50:51], s98, v88
	v_nop
	v_cndmask_b32_e64 v44, 0, v44, s[30:31]
	v_cndmask_b32_e64 v45, 0, v45, s[36:37]
	v_cndmask_b32_e64 v46, 0, v46, s[78:79]
	v_cndmask_b32_e64 v47, 0, v47, s[50:51]
	v_cvt_pk_bf16_f32 v64, v32, v33
	v_cvt_pk_bf16_f32 v65, v34, v35
	v_cvt_pk_bf16_f32 v66, v36, v37
	v_cvt_pk_bf16_f32 v67, v38, v39
	v_cvt_pk_bf16_f32 v68, v40, v41
	v_cvt_pk_bf16_f32 v69, v42, v43
	v_cvt_pk_bf16_f32 v70, v44, v45
	v_cvt_pk_bf16_f32 v71, v46, v47
	v_pk_add_f32 v[232:233], v[232:233], v[32:33]
	v_pk_add_f32 v[232:233], v[232:233], v[34:35]
	v_pk_add_f32 v[232:233], v[232:233], v[36:37]
	v_pk_add_f32 v[232:233], v[232:233], v[38:39]
	v_pk_add_f32 v[232:233], v[232:233], v[40:41]
	v_pk_add_f32 v[232:233], v[232:233], v[42:43]
	v_pk_add_f32 v[232:233], v[232:233], v[44:45]
	v_pk_add_f32 v[232:233], v[232:233], v[46:47]
	ds_read2_b32 v[32:33], v115 offset0:68 offset1:69
	ds_read2_b32 v[34:35], v115 offset0:70 offset1:71
	ds_read2_b32 v[36:37], v115 offset0:76 offset1:77
	ds_read2_b32 v[38:39], v115 offset0:78 offset1:79
	ds_read2_b32 v[40:41], v115 offset0:85 offset1:86
	ds_read2_b32 v[42:43], v115 offset0:87 offset1:88
	ds_read2_b32 v[44:45], v115 offset0:93 offset1:94
	ds_read2_b32 v[46:47], v115 offset0:95 offset1:96
	v_mfma_f32_32x32x16_bf16 v[0:15], v[64:67], v[72:75], v[0:15]
	v_mfma_f32_32x32x16_bf16 v[16:31], v[64:67], v[76:79], v[16:31]
	v_mfma_f32_32x32x16_bf16 v[0:15], v[68:71], v[220:223], v[0:15]
	v_mfma_f32_32x32x16_bf16 v[16:31], v[68:71], v[224:227], v[16:31]
	s_add_i32 s90, s67, 32
	v_add_u32_e32 v80, s90, v235
	v_add_u32_e32 v83, s90, v236
	v_add_u32_e32 v99, s90, v237
	v_add_u32_e32 v253, s90, v238
	v_add_u32_e32 v254, s90, v100
	v_add_u32_e32 v255, s90, v149
	v_med3_i32 v80, v80, 0, s99
	v_med3_i32 v83, v83, 0, s99
	v_med3_i32 v99, v99, 0, s99
	v_med3_i32 v253, v253, 0, s99
	v_med3_i32 v254, v254, 0, s99
	v_med3_i32 v255, v255, 0, s99
	v_mad_u32_u24 v80, v80, s100, v252
	v_mad_u32_u24 v83, v83, s100, v252
	v_mad_u32_u24 v99, v99, s100, v252
	v_mad_u32_u24 v253, v253, s100, v252
	v_mad_u32_u24 v254, v254, s100, v153
	v_mad_u32_u24 v255, v255, s100, v153
	global_load_dwordx4 v[156:159], v80, s[82:83]
	global_load_dwordx4 v[160:163], v83, s[82:83]
	global_load_dwordx4 v[164:167], v99, s[82:83]
	global_load_dwordx4 v[168:171], v253, s[82:83]
	global_load_dwordx4 v[172:175], v254, s[82:83] offset:768
	global_load_dwordx4 v[176:179], v255, s[82:83] offset:768
	global_load_dwordx4 v[180:183], v254, s[82:83] offset:832
	global_load_dwordx4 v[184:187], v255, s[82:83] offset:832
	ds_read_b64_tr_b16 v[72:73], v231
	ds_read_b64_tr_b16 v[74:75], v231 offset:512
	ds_read_b64_tr_b16 v[76:77], v231 offset:2048
	ds_read_b64_tr_b16 v[78:79], v231 offset:2560
	ds_read_b64_tr_b16 v[220:221], v231 offset:1024
	ds_read_b64_tr_b16 v[222:223], v231 offset:1536
	ds_read_b64_tr_b16 v[224:225], v231 offset:3072
	ds_read_b64_tr_b16 v[226:227], v231 offset:3584
	v_exp_f32_e32 v188, v188
	v_exp_f32_e32 v189, v189
	s_waitcnt vmcnt(8)
	ds_write_b128 v247, v[116:119]
	ds_write_b128 v247, v[120:123] offset:1024
	ds_write_b128 v247, v[124:127] offset:2048
	ds_write_b128 v247, v[128:131] offset:3072
	ds_read_b128 v[116:119], v248
	ds_read_b128 v[120:123], v249
	ds_read_b128 v[124:127], v250
	ds_read_b128 v[128:131], v251
	ds_write_b128 v112, v[132:135]
	ds_write_b128 v112, v[136:139] offset:1024
	ds_write_b128 v112, v[140:143] offset:2048
	ds_write_b128 v112, v[144:147] offset:3072
	v_exp_f32_e32 v190, v190
	v_exp_f32_e32 v191, v191
	s_waitcnt lgkmcnt(4)
	v_mfma_f32_32x32x16_bf16 v[32:47], v[116:119], v[48:51], v[32:47]
	v_exp_f32_e32 v192, v192
	v_exp_f32_e32 v193, v193
	v_exp_f32_e32 v194, v194
	v_mfma_f32_32x32x16_bf16 v[32:47], v[120:123], v[52:55], v[32:47]
	v_exp_f32_e32 v195, v195
	v_exp_f32_e32 v196, v196
	v_exp_f32_e32 v197, v197
	v_mfma_f32_32x32x16_bf16 v[32:47], v[124:127], v[56:59], v[32:47]
	v_exp_f32_e32 v198, v198
	v_exp_f32_e32 v199, v199
	v_exp_f32_e32 v200, v200
	v_mfma_f32_32x32x16_bf16 v[32:47], v[128:131], v[60:63], v[32:47]
	v_exp_f32_e32 v201, v201
	v_exp_f32_e32 v202, v202
	v_exp_f32_e32 v203, v203
	s_add_i32 s90, s67, -32
	v_add_u32_e32 v84, s90, v107
	v_add_u32_e32 v85, 0, v84
	v_add_u32_e32 v86, 1, v84
	v_add_u32_e32 v87, 2, v84
	v_add_u32_e32 v88, 3, v84
	v_cmp_gt_u32_e64 s[30:31], s98, v85
	v_cmp_gt_u32_e64 s[36:37], s98, v86
	v_cmp_gt_u32_e64 s[78:79], s98, v87
	v_cmp_gt_u32_e64 s[50:51], s98, v88
	v_cndmask_b32_e64 v188, 0, v188, s[30:31]
	v_add_u32_e32 v85, 8, v84
	v_cmp_gt_u32_e64 s[30:31], s98, v85
	v_cndmask_b32_e64 v189, 0, v189, s[36:37]
	v_add_u32_e32 v86, 9, v84
	v_cmp_gt_u32_e64 s[36:37], s98, v86
	v_cndmask_b32_e64 v190, 0, v190, s[78:79]
	v_add_u32_e32 v87, 10, v84
	v_cmp_gt_u32_e64 s[78:79], s98, v87
	v_cndmask_b32_e64 v191, 0, v191, s[50:51]
	v_add_u32_e32 v88, 11, v84
	v_cmp_gt_u32_e64 s[50:51], s98, v88
	v_cndmask_b32_e64 v192, 0, v192, s[30:31]
	v_add_u32_e32 v85, 16, v84
	v_cmp_gt_u32_e64 s[30:31], s98, v85
	v_cndmask_b32_e64 v193, 0, v193, s[36:37]
	v_add_u32_e32 v86, 17, v84
	v_cmp_gt_u32_e64 s[36:37], s98, v86
	v_cndmask_b32_e64 v194, 0, v194, s[78:79]
	v_add_u32_e32 v87, 18, v84
	v_cmp_gt_u32_e64 s[78:79], s98, v87
	v_cndmask_b32_e64 v195, 0, v195, s[50:51]
	v_add_u32_e32 v88, 19, v84
	v_cmp_gt_u32_e64 s[50:51], s98, v88
	v_cndmask_b32_e64 v196, 0, v196, s[30:31]
	v_add_u32_e32 v85, 24, v84
	v_cmp_gt_u32_e64 s[30:31], s98, v85
	v_cndmask_b32_e64 v197, 0, v197, s[36:37]
	v_add_u32_e32 v86, 25, v84
	v_cmp_gt_u32_e64 s[36:37], s98, v86
	v_cndmask_b32_e64 v198, 0, v198, s[78:79]
	v_add_u32_e32 v87, 26, v84
	v_cmp_gt_u32_e64 s[78:79], s98, v87
	v_cndmask_b32_e64 v199, 0, v199, s[50:51]
	v_add_u32_e32 v88, 27, v84
	v_cmp_gt_u32_e64 s[50:51], s98, v88
	v_nop
	v_cndmask_b32_e64 v200, 0, v200, s[30:31]
	v_cndmask_b32_e64 v201, 0, v201, s[36:37]
	v_cndmask_b32_e64 v202, 0, v202, s[78:79]
	v_cndmask_b32_e64 v203, 0, v203, s[50:51]
	v_cvt_pk_bf16_f32 v64, v188, v189
	v_cvt_pk_bf16_f32 v65, v190, v191
	v_cvt_pk_bf16_f32 v66, v192, v193
	v_cvt_pk_bf16_f32 v67, v194, v195
	v_cvt_pk_bf16_f32 v68, v196, v197
	v_cvt_pk_bf16_f32 v69, v198, v199
	v_cvt_pk_bf16_f32 v70, v200, v201
	v_cvt_pk_bf16_f32 v71, v202, v203
	v_pk_add_f32 v[232:233], v[232:233], v[188:189]
	v_pk_add_f32 v[232:233], v[232:233], v[190:191]
	v_pk_add_f32 v[232:233], v[232:233], v[192:193]
	v_pk_add_f32 v[232:233], v[232:233], v[194:195]
	v_pk_add_f32 v[232:233], v[232:233], v[196:197]
	v_pk_add_f32 v[232:233], v[232:233], v[198:199]
	v_pk_add_f32 v[232:233], v[232:233], v[200:201]
	v_pk_add_f32 v[232:233], v[232:233], v[202:203]
	ds_read2_b32 v[188:189], v115 offset0:102 offset1:103
	ds_read2_b32 v[190:191], v115 offset0:104 offset1:105
	ds_read2_b32 v[192:193], v115 offset0:110 offset1:111
	ds_read2_b32 v[194:195], v115 offset0:112 offset1:113
	ds_read2_b32 v[196:197], v115 offset0:119 offset1:120
	ds_read2_b32 v[198:199], v115 offset0:121 offset1:122
	ds_read2_b32 v[200:201], v115 offset0:127 offset1:128
	ds_read2_b32 v[202:203], v115 offset0:129 offset1:130
	v_mfma_f32_32x32x16_bf16 v[0:15], v[64:67], v[72:75], v[0:15]
	v_mfma_f32_32x32x16_bf16 v[16:31], v[64:67], v[76:79], v[16:31]
	v_mfma_f32_32x32x16_bf16 v[0:15], v[68:71], v[220:223], v[0:15]
	v_mfma_f32_32x32x16_bf16 v[16:31], v[68:71], v[224:227], v[16:31]
	s_add_i32 s90, s67, 64
	v_add_u32_e32 v80, s90, v235
	v_add_u32_e32 v83, s90, v236
	v_add_u32_e32 v99, s90, v237
	v_add_u32_e32 v253, s90, v238
	v_add_u32_e32 v254, s90, v100
	v_add_u32_e32 v255, s90, v149
	v_med3_i32 v80, v80, 0, s99
	v_med3_i32 v83, v83, 0, s99
	v_med3_i32 v99, v99, 0, s99
	v_med3_i32 v253, v253, 0, s99
	v_med3_i32 v254, v254, 0, s99
	v_med3_i32 v255, v255, 0, s99
	v_mad_u32_u24 v80, v80, s100, v252
	v_mad_u32_u24 v83, v83, s100, v252
	v_mad_u32_u24 v99, v99, s100, v252
	v_mad_u32_u24 v253, v253, s100, v252
	v_mad_u32_u24 v254, v254, s100, v153
	v_mad_u32_u24 v255, v255, s100, v153
	global_load_dwordx4 v[116:119], v80, s[82:83]
	global_load_dwordx4 v[120:123], v83, s[82:83]
	global_load_dwordx4 v[124:127], v99, s[82:83]
	global_load_dwordx4 v[128:131], v253, s[82:83]
	global_load_dwordx4 v[132:135], v254, s[82:83] offset:768
	global_load_dwordx4 v[136:139], v255, s[82:83] offset:768
	global_load_dwordx4 v[140:143], v254, s[82:83] offset:832
	global_load_dwordx4 v[144:147], v255, s[82:83] offset:832
	ds_read_b64_tr_b16 v[72:73], v231
	ds_read_b64_tr_b16 v[74:75], v231 offset:512
	ds_read_b64_tr_b16 v[76:77], v231 offset:2048
	ds_read_b64_tr_b16 v[78:79], v231 offset:2560
	ds_read_b64_tr_b16 v[220:221], v231 offset:1024
	ds_read_b64_tr_b16 v[222:223], v231 offset:1536
	ds_read_b64_tr_b16 v[224:225], v231 offset:3072
	ds_read_b64_tr_b16 v[226:227], v231 offset:3584
	v_exp_f32_e32 v32, v32
	v_exp_f32_e32 v33, v33
	s_waitcnt vmcnt(8)
	ds_write_b128 v247, v[156:159]
	ds_write_b128 v247, v[160:163] offset:1024
	ds_write_b128 v247, v[164:167] offset:2048
	ds_write_b128 v247, v[168:171] offset:3072
	ds_read_b128 v[156:159], v248
	ds_read_b128 v[160:163], v249
	ds_read_b128 v[164:167], v250
	ds_read_b128 v[168:171], v251
	ds_write_b128 v112, v[172:175]
	ds_write_b128 v112, v[176:179] offset:1024
	ds_write_b128 v112, v[180:183] offset:2048
	ds_write_b128 v112, v[184:187] offset:3072
	v_exp_f32_e32 v34, v34
	v_exp_f32_e32 v35, v35
	s_waitcnt lgkmcnt(4)
	v_mfma_f32_32x32x16_bf16 v[188:203], v[156:159], v[48:51], v[188:203]
	v_exp_f32_e32 v36, v36
	v_exp_f32_e32 v37, v37
	v_exp_f32_e32 v38, v38
	v_mfma_f32_32x32x16_bf16 v[188:203], v[160:163], v[52:55], v[188:203]
	v_exp_f32_e32 v39, v39
	v_exp_f32_e32 v40, v40
	v_exp_f32_e32 v41, v41
	v_mfma_f32_32x32x16_bf16 v[188:203], v[164:167], v[56:59], v[188:203]
	v_exp_f32_e32 v42, v42
	v_exp_f32_e32 v43, v43
	v_exp_f32_e32 v44, v44
	v_mfma_f32_32x32x16_bf16 v[188:203], v[168:171], v[60:63], v[188:203]
	v_exp_f32_e32 v45, v45
	v_exp_f32_e32 v46, v46
	v_exp_f32_e32 v47, v47
	s_add_i32 s90, s67, 0
	v_add_u32_e32 v84, s90, v107
	v_add_u32_e32 v85, 0, v84
	v_add_u32_e32 v86, 1, v84
	v_add_u32_e32 v87, 2, v84
	v_add_u32_e32 v88, 3, v84
	v_cmp_gt_u32_e64 s[30:31], s98, v85
	v_cmp_gt_u32_e64 s[36:37], s98, v86
	v_cmp_gt_u32_e64 s[78:79], s98, v87
	v_cmp_gt_u32_e64 s[50:51], s98, v88
	v_cndmask_b32_e64 v32, 0, v32, s[30:31]
	v_add_u32_e32 v85, 8, v84
	v_cmp_gt_u32_e64 s[30:31], s98, v85
	v_cndmask_b32_e64 v33, 0, v33, s[36:37]
	v_add_u32_e32 v86, 9, v84
	v_cmp_gt_u32_e64 s[36:37], s98, v86
	v_cndmask_b32_e64 v34, 0, v34, s[78:79]
	v_add_u32_e32 v87, 10, v84
	v_cmp_gt_u32_e64 s[78:79], s98, v87
	v_cndmask_b32_e64 v35, 0, v35, s[50:51]
	v_add_u32_e32 v88, 11, v84
	v_cmp_gt_u32_e64 s[50:51], s98, v88
	v_cndmask_b32_e64 v36, 0, v36, s[30:31]
	v_add_u32_e32 v85, 16, v84
	v_cmp_gt_u32_e64 s[30:31], s98, v85
	v_cndmask_b32_e64 v37, 0, v37, s[36:37]
	v_add_u32_e32 v86, 17, v84
	v_cmp_gt_u32_e64 s[36:37], s98, v86
	v_cndmask_b32_e64 v38, 0, v38, s[78:79]
	v_add_u32_e32 v87, 18, v84
	v_cmp_gt_u32_e64 s[78:79], s98, v87
	v_cndmask_b32_e64 v39, 0, v39, s[50:51]
	v_add_u32_e32 v88, 19, v84
	v_cmp_gt_u32_e64 s[50:51], s98, v88
	v_cndmask_b32_e64 v40, 0, v40, s[30:31]
	v_add_u32_e32 v85, 24, v84
	v_cmp_gt_u32_e64 s[30:31], s98, v85
	v_cndmask_b32_e64 v41, 0, v41, s[36:37]
	v_add_u32_e32 v86, 25, v84
	v_cmp_gt_u32_e64 s[36:37], s98, v86
	v_cndmask_b32_e64 v42, 0, v42, s[78:79]
	v_add_u32_e32 v87, 26, v84
	v_cmp_gt_u32_e64 s[78:79], s98, v87
	v_cndmask_b32_e64 v43, 0, v43, s[50:51]
	v_add_u32_e32 v88, 27, v84
	v_cmp_gt_u32_e64 s[50:51], s98, v88
	v_nop
	v_cndmask_b32_e64 v44, 0, v44, s[30:31]
	v_cndmask_b32_e64 v45, 0, v45, s[36:37]
	v_cndmask_b32_e64 v46, 0, v46, s[78:79]
	v_cndmask_b32_e64 v47, 0, v47, s[50:51]
	v_cvt_pk_bf16_f32 v64, v32, v33
	v_cvt_pk_bf16_f32 v65, v34, v35
	v_cvt_pk_bf16_f32 v66, v36, v37
	v_cvt_pk_bf16_f32 v67, v38, v39
	v_cvt_pk_bf16_f32 v68, v40, v41
	v_cvt_pk_bf16_f32 v69, v42, v43
	v_cvt_pk_bf16_f32 v70, v44, v45
	v_cvt_pk_bf16_f32 v71, v46, v47
	v_pk_add_f32 v[232:233], v[232:233], v[32:33]
	v_pk_add_f32 v[232:233], v[232:233], v[34:35]
	v_pk_add_f32 v[232:233], v[232:233], v[36:37]
	v_pk_add_f32 v[232:233], v[232:233], v[38:39]
	v_pk_add_f32 v[232:233], v[232:233], v[40:41]
	v_pk_add_f32 v[232:233], v[232:233], v[42:43]
	v_pk_add_f32 v[232:233], v[232:233], v[44:45]
	v_pk_add_f32 v[232:233], v[232:233], v[46:47]
	ds_read2_b32 v[32:33], v115 offset0:136 offset1:137
	ds_read2_b32 v[34:35], v115 offset0:138 offset1:139
	ds_read2_b32 v[36:37], v115 offset0:144 offset1:145
	ds_read2_b32 v[38:39], v115 offset0:146 offset1:147
	ds_read2_b32 v[40:41], v115 offset0:153 offset1:154
	ds_read2_b32 v[42:43], v115 offset0:155 offset1:156
	ds_read2_b32 v[44:45], v115 offset0:161 offset1:162
	ds_read2_b32 v[46:47], v115 offset0:163 offset1:164
	v_mfma_f32_32x32x16_bf16 v[0:15], v[64:67], v[72:75], v[0:15]
	v_mfma_f32_32x32x16_bf16 v[16:31], v[64:67], v[76:79], v[16:31]
	v_mfma_f32_32x32x16_bf16 v[0:15], v[68:71], v[220:223], v[0:15]
	v_mfma_f32_32x32x16_bf16 v[16:31], v[68:71], v[224:227], v[16:31]
	s_add_i32 s90, s67, 96
	v_add_u32_e32 v80, s90, v235
	v_add_u32_e32 v83, s90, v236
	v_add_u32_e32 v99, s90, v237
	v_add_u32_e32 v253, s90, v238
	v_add_u32_e32 v254, s90, v100
	v_add_u32_e32 v255, s90, v149
	v_med3_i32 v80, v80, 0, s99
	v_med3_i32 v83, v83, 0, s99
	v_med3_i32 v99, v99, 0, s99
	v_med3_i32 v253, v253, 0, s99
	v_med3_i32 v254, v254, 0, s99
	v_med3_i32 v255, v255, 0, s99
	v_mad_u32_u24 v80, v80, s100, v252
	v_mad_u32_u24 v83, v83, s100, v252
	v_mad_u32_u24 v99, v99, s100, v252
	v_mad_u32_u24 v253, v253, s100, v252
	v_mad_u32_u24 v254, v254, s100, v153
	v_mad_u32_u24 v255, v255, s100, v153
	global_load_dwordx4 v[156:159], v80, s[82:83]
	global_load_dwordx4 v[160:163], v83, s[82:83]
	global_load_dwordx4 v[164:167], v99, s[82:83]
	global_load_dwordx4 v[168:171], v253, s[82:83]
	global_load_dwordx4 v[172:175], v254, s[82:83] offset:768
	global_load_dwordx4 v[176:179], v255, s[82:83] offset:768
	global_load_dwordx4 v[180:183], v254, s[82:83] offset:832
	global_load_dwordx4 v[184:187], v255, s[82:83] offset:832
	ds_read_b64_tr_b16 v[72:73], v231
	ds_read_b64_tr_b16 v[74:75], v231 offset:512
	ds_read_b64_tr_b16 v[76:77], v231 offset:2048
	ds_read_b64_tr_b16 v[78:79], v231 offset:2560
	ds_read_b64_tr_b16 v[220:221], v231 offset:1024
	ds_read_b64_tr_b16 v[222:223], v231 offset:1536
	ds_read_b64_tr_b16 v[224:225], v231 offset:3072
	ds_read_b64_tr_b16 v[226:227], v231 offset:3584
	v_exp_f32_e32 v188, v188
	v_exp_f32_e32 v189, v189
	s_waitcnt vmcnt(8)
	ds_write_b128 v247, v[116:119]
	ds_write_b128 v247, v[120:123] offset:1024
	ds_write_b128 v247, v[124:127] offset:2048
	ds_write_b128 v247, v[128:131] offset:3072
	ds_read_b128 v[116:119], v248
	ds_read_b128 v[120:123], v249
	ds_read_b128 v[124:127], v250
	ds_read_b128 v[128:131], v251
	ds_write_b128 v112, v[132:135]
	ds_write_b128 v112, v[136:139] offset:1024
	ds_write_b128 v112, v[140:143] offset:2048
	ds_write_b128 v112, v[144:147] offset:3072
	v_exp_f32_e32 v190, v190
	v_exp_f32_e32 v191, v191
	s_waitcnt lgkmcnt(4)
	v_mfma_f32_32x32x16_bf16 v[32:47], v[116:119], v[48:51], v[32:47]
	v_exp_f32_e32 v192, v192
	v_exp_f32_e32 v193, v193
	v_exp_f32_e32 v194, v194
	v_mfma_f32_32x32x16_bf16 v[32:47], v[120:123], v[52:55], v[32:47]
	v_exp_f32_e32 v195, v195
	v_exp_f32_e32 v196, v196
	v_exp_f32_e32 v197, v197
	v_mfma_f32_32x32x16_bf16 v[32:47], v[124:127], v[56:59], v[32:47]
	v_exp_f32_e32 v198, v198
	v_exp_f32_e32 v199, v199
	v_exp_f32_e32 v200, v200
	v_mfma_f32_32x32x16_bf16 v[32:47], v[128:131], v[60:63], v[32:47]
	v_exp_f32_e32 v201, v201
	v_exp_f32_e32 v202, v202
	v_exp_f32_e32 v203, v203
	s_add_i32 s90, s67, 32
	v_add_u32_e32 v84, s90, v107
	v_add_u32_e32 v85, 0, v84
	v_add_u32_e32 v86, 1, v84
	v_add_u32_e32 v87, 2, v84
	v_add_u32_e32 v88, 3, v84
	v_cmp_gt_u32_e64 s[30:31], s98, v85
	v_cmp_gt_u32_e64 s[36:37], s98, v86
	v_cmp_gt_u32_e64 s[78:79], s98, v87
	v_cmp_gt_u32_e64 s[50:51], s98, v88
	v_cndmask_b32_e64 v188, 0, v188, s[30:31]
	v_add_u32_e32 v85, 8, v84
	v_cmp_gt_u32_e64 s[30:31], s98, v85
	v_cndmask_b32_e64 v189, 0, v189, s[36:37]
	v_add_u32_e32 v86, 9, v84
	v_cmp_gt_u32_e64 s[36:37], s98, v86
	v_cndmask_b32_e64 v190, 0, v190, s[78:79]
	v_add_u32_e32 v87, 10, v84
	v_cmp_gt_u32_e64 s[78:79], s98, v87
	v_cndmask_b32_e64 v191, 0, v191, s[50:51]
	v_add_u32_e32 v88, 11, v84
	v_cmp_gt_u32_e64 s[50:51], s98, v88
	v_cndmask_b32_e64 v192, 0, v192, s[30:31]
	v_add_u32_e32 v85, 16, v84
	v_cmp_gt_u32_e64 s[30:31], s98, v85
	v_cndmask_b32_e64 v193, 0, v193, s[36:37]
	v_add_u32_e32 v86, 17, v84
	v_cmp_gt_u32_e64 s[36:37], s98, v86
	v_cndmask_b32_e64 v194, 0, v194, s[78:79]
	v_add_u32_e32 v87, 18, v84
	v_cmp_gt_u32_e64 s[78:79], s98, v87
	v_cndmask_b32_e64 v195, 0, v195, s[50:51]
	v_add_u32_e32 v88, 19, v84
	v_cmp_gt_u32_e64 s[50:51], s98, v88
	v_cndmask_b32_e64 v196, 0, v196, s[30:31]
	v_add_u32_e32 v85, 24, v84
	v_cmp_gt_u32_e64 s[30:31], s98, v85
	v_cndmask_b32_e64 v197, 0, v197, s[36:37]
	v_add_u32_e32 v86, 25, v84
	v_cmp_gt_u32_e64 s[36:37], s98, v86
	v_cndmask_b32_e64 v198, 0, v198, s[78:79]
	v_add_u32_e32 v87, 26, v84
	v_cmp_gt_u32_e64 s[78:79], s98, v87
	v_cndmask_b32_e64 v199, 0, v199, s[50:51]
	v_add_u32_e32 v88, 27, v84
	v_cmp_gt_u32_e64 s[50:51], s98, v88
	v_nop
	v_cndmask_b32_e64 v200, 0, v200, s[30:31]
	v_cndmask_b32_e64 v201, 0, v201, s[36:37]
	v_cndmask_b32_e64 v202, 0, v202, s[78:79]
	v_cndmask_b32_e64 v203, 0, v203, s[50:51]
	v_cvt_pk_bf16_f32 v64, v188, v189
	v_cvt_pk_bf16_f32 v65, v190, v191
	v_cvt_pk_bf16_f32 v66, v192, v193
	v_cvt_pk_bf16_f32 v67, v194, v195
	v_cvt_pk_bf16_f32 v68, v196, v197
	v_cvt_pk_bf16_f32 v69, v198, v199
	v_cvt_pk_bf16_f32 v70, v200, v201
	v_cvt_pk_bf16_f32 v71, v202, v203
	v_pk_add_f32 v[232:233], v[232:233], v[188:189]
	v_pk_add_f32 v[232:233], v[232:233], v[190:191]
	v_pk_add_f32 v[232:233], v[232:233], v[192:193]
	v_pk_add_f32 v[232:233], v[232:233], v[194:195]
	v_pk_add_f32 v[232:233], v[232:233], v[196:197]
	v_pk_add_f32 v[232:233], v[232:233], v[198:199]
	v_pk_add_f32 v[232:233], v[232:233], v[200:201]
	v_pk_add_f32 v[232:233], v[232:233], v[202:203]
	ds_read2_b32 v[188:189], v115 offset0:170 offset1:171
	ds_read2_b32 v[190:191], v115 offset0:172 offset1:173
	ds_read2_b32 v[192:193], v115 offset0:178 offset1:179
	ds_read2_b32 v[194:195], v115 offset0:180 offset1:181
	ds_read2_b32 v[196:197], v115 offset0:187 offset1:188
	ds_read2_b32 v[198:199], v115 offset0:189 offset1:190
	ds_read2_b32 v[200:201], v115 offset0:195 offset1:196
	ds_read2_b32 v[202:203], v115 offset0:197 offset1:198
	v_mfma_f32_32x32x16_bf16 v[0:15], v[64:67], v[72:75], v[0:15]
	v_mfma_f32_32x32x16_bf16 v[16:31], v[64:67], v[76:79], v[16:31]
	v_mfma_f32_32x32x16_bf16 v[0:15], v[68:71], v[220:223], v[0:15]
	v_mfma_f32_32x32x16_bf16 v[16:31], v[68:71], v[224:227], v[16:31]
	s_add_i32 s90, s67, 128
	v_add_u32_e32 v80, s90, v235
	v_add_u32_e32 v83, s90, v236
	v_add_u32_e32 v99, s90, v237
	v_add_u32_e32 v253, s90, v238
	v_add_u32_e32 v254, s90, v100
	v_add_u32_e32 v255, s90, v149
	v_med3_i32 v80, v80, 0, s99
	v_med3_i32 v83, v83, 0, s99
	v_med3_i32 v99, v99, 0, s99
	v_med3_i32 v253, v253, 0, s99
	v_med3_i32 v254, v254, 0, s99
	v_med3_i32 v255, v255, 0, s99
	v_mad_u32_u24 v80, v80, s100, v252
	v_mad_u32_u24 v83, v83, s100, v252
	v_mad_u32_u24 v99, v99, s100, v252
	v_mad_u32_u24 v253, v253, s100, v252
	v_mad_u32_u24 v254, v254, s100, v153
	v_mad_u32_u24 v255, v255, s100, v153
	global_load_dwordx4 v[116:119], v80, s[82:83]
	global_load_dwordx4 v[120:123], v83, s[82:83]
	global_load_dwordx4 v[124:127], v99, s[82:83]
	global_load_dwordx4 v[128:131], v253, s[82:83]
	global_load_dwordx4 v[132:135], v254, s[82:83] offset:768
	global_load_dwordx4 v[136:139], v255, s[82:83] offset:768
	global_load_dwordx4 v[140:143], v254, s[82:83] offset:832
	global_load_dwordx4 v[144:147], v255, s[82:83] offset:832
	ds_read_b64_tr_b16 v[72:73], v231
	ds_read_b64_tr_b16 v[74:75], v231 offset:512
	ds_read_b64_tr_b16 v[76:77], v231 offset:2048
	ds_read_b64_tr_b16 v[78:79], v231 offset:2560
	ds_read_b64_tr_b16 v[220:221], v231 offset:1024
	ds_read_b64_tr_b16 v[222:223], v231 offset:1536
	ds_read_b64_tr_b16 v[224:225], v231 offset:3072
	ds_read_b64_tr_b16 v[226:227], v231 offset:3584
	v_exp_f32_e32 v32, v32
	v_exp_f32_e32 v33, v33
	s_waitcnt vmcnt(8)
	ds_write_b128 v247, v[156:159]
	ds_write_b128 v247, v[160:163] offset:1024
	ds_write_b128 v247, v[164:167] offset:2048
	ds_write_b128 v247, v[168:171] offset:3072
	ds_read_b128 v[156:159], v248
	ds_read_b128 v[160:163], v249
	ds_read_b128 v[164:167], v250
	ds_read_b128 v[168:171], v251
	ds_write_b128 v112, v[172:175]
	ds_write_b128 v112, v[176:179] offset:1024
	ds_write_b128 v112, v[180:183] offset:2048
	ds_write_b128 v112, v[184:187] offset:3072
	v_exp_f32_e32 v34, v34
	v_exp_f32_e32 v35, v35
	s_waitcnt lgkmcnt(4)
	v_mfma_f32_32x32x16_bf16 v[188:203], v[156:159], v[48:51], v[188:203]
	v_exp_f32_e32 v36, v36
	v_exp_f32_e32 v37, v37
	v_exp_f32_e32 v38, v38
	v_mfma_f32_32x32x16_bf16 v[188:203], v[160:163], v[52:55], v[188:203]
	v_exp_f32_e32 v39, v39
	v_exp_f32_e32 v40, v40
	v_exp_f32_e32 v41, v41
	v_mfma_f32_32x32x16_bf16 v[188:203], v[164:167], v[56:59], v[188:203]
	v_exp_f32_e32 v42, v42
	v_exp_f32_e32 v43, v43
	v_exp_f32_e32 v44, v44
	v_mfma_f32_32x32x16_bf16 v[188:203], v[168:171], v[60:63], v[188:203]
	v_exp_f32_e32 v45, v45
	v_exp_f32_e32 v46, v46
	v_exp_f32_e32 v47, v47
	s_add_i32 s90, s67, 64
	v_add_u32_e32 v84, s90, v107
	v_add_u32_e32 v85, 0, v84
	v_add_u32_e32 v86, 1, v84
	v_add_u32_e32 v87, 2, v84
	v_add_u32_e32 v88, 3, v84
	v_cmp_gt_u32_e64 s[30:31], s98, v85
	v_cmp_gt_u32_e64 s[36:37], s98, v86
	v_cmp_gt_u32_e64 s[78:79], s98, v87
	v_cmp_gt_u32_e64 s[50:51], s98, v88
	v_cndmask_b32_e64 v32, 0, v32, s[30:31]
	v_add_u32_e32 v85, 8, v84
	v_cmp_gt_u32_e64 s[30:31], s98, v85
	v_cndmask_b32_e64 v33, 0, v33, s[36:37]
	v_add_u32_e32 v86, 9, v84
	v_cmp_gt_u32_e64 s[36:37], s98, v86
	v_cndmask_b32_e64 v34, 0, v34, s[78:79]
	v_add_u32_e32 v87, 10, v84
	v_cmp_gt_u32_e64 s[78:79], s98, v87
	v_cndmask_b32_e64 v35, 0, v35, s[50:51]
	v_add_u32_e32 v88, 11, v84
	v_cmp_gt_u32_e64 s[50:51], s98, v88
	v_cndmask_b32_e64 v36, 0, v36, s[30:31]
	v_add_u32_e32 v85, 16, v84
	v_cmp_gt_u32_e64 s[30:31], s98, v85
	v_cndmask_b32_e64 v37, 0, v37, s[36:37]
	v_add_u32_e32 v86, 17, v84
	v_cmp_gt_u32_e64 s[36:37], s98, v86
	v_cndmask_b32_e64 v38, 0, v38, s[78:79]
	v_add_u32_e32 v87, 18, v84
	v_cmp_gt_u32_e64 s[78:79], s98, v87
	v_cndmask_b32_e64 v39, 0, v39, s[50:51]
	v_add_u32_e32 v88, 19, v84
	v_cmp_gt_u32_e64 s[50:51], s98, v88
	v_cndmask_b32_e64 v40, 0, v40, s[30:31]
	v_add_u32_e32 v85, 24, v84
	v_cmp_gt_u32_e64 s[30:31], s98, v85
	v_cndmask_b32_e64 v41, 0, v41, s[36:37]
	v_add_u32_e32 v86, 25, v84
	v_cmp_gt_u32_e64 s[36:37], s98, v86
	v_cndmask_b32_e64 v42, 0, v42, s[78:79]
	v_add_u32_e32 v87, 26, v84
	v_cmp_gt_u32_e64 s[78:79], s98, v87
	v_cndmask_b32_e64 v43, 0, v43, s[50:51]
	v_add_u32_e32 v88, 27, v84
	v_cmp_gt_u32_e64 s[50:51], s98, v88
	v_nop
	v_cndmask_b32_e64 v44, 0, v44, s[30:31]
	v_cndmask_b32_e64 v45, 0, v45, s[36:37]
	v_cndmask_b32_e64 v46, 0, v46, s[78:79]
	v_cndmask_b32_e64 v47, 0, v47, s[50:51]
	v_cvt_pk_bf16_f32 v64, v32, v33
	v_cvt_pk_bf16_f32 v65, v34, v35
	v_cvt_pk_bf16_f32 v66, v36, v37
	v_cvt_pk_bf16_f32 v67, v38, v39
	v_cvt_pk_bf16_f32 v68, v40, v41
	v_cvt_pk_bf16_f32 v69, v42, v43
	v_cvt_pk_bf16_f32 v70, v44, v45
	v_cvt_pk_bf16_f32 v71, v46, v47
	v_pk_add_f32 v[232:233], v[232:233], v[32:33]
	v_pk_add_f32 v[232:233], v[232:233], v[34:35]
	v_pk_add_f32 v[232:233], v[232:233], v[36:37]
	v_pk_add_f32 v[232:233], v[232:233], v[38:39]
	v_pk_add_f32 v[232:233], v[232:233], v[40:41]
	v_pk_add_f32 v[232:233], v[232:233], v[42:43]
	v_pk_add_f32 v[232:233], v[232:233], v[44:45]
	v_pk_add_f32 v[232:233], v[232:233], v[46:47]
	ds_read2_b32 v[32:33], v115 offset0:204 offset1:205
	ds_read2_b32 v[34:35], v115 offset0:206 offset1:207
	ds_read2_b32 v[36:37], v115 offset0:212 offset1:213
	ds_read2_b32 v[38:39], v115 offset0:214 offset1:215
	ds_read2_b32 v[40:41], v115 offset0:221 offset1:222
	ds_read2_b32 v[42:43], v115 offset0:223 offset1:224
	ds_read2_b32 v[44:45], v115 offset0:229 offset1:230
	ds_read2_b32 v[46:47], v115 offset0:231 offset1:232
	v_mfma_f32_32x32x16_bf16 v[0:15], v[64:67], v[72:75], v[0:15]
	v_mfma_f32_32x32x16_bf16 v[16:31], v[64:67], v[76:79], v[16:31]
	v_mfma_f32_32x32x16_bf16 v[0:15], v[68:71], v[220:223], v[0:15]
	v_mfma_f32_32x32x16_bf16 v[16:31], v[68:71], v[224:227], v[16:31]
	s_add_i32 s90, s67, 160
	v_add_u32_e32 v80, s90, v235
	v_add_u32_e32 v83, s90, v236
	v_add_u32_e32 v99, s90, v237
	v_add_u32_e32 v253, s90, v238
	v_add_u32_e32 v254, s90, v100
	v_add_u32_e32 v255, s90, v149
	v_med3_i32 v80, v80, 0, s99
	v_med3_i32 v83, v83, 0, s99
	v_med3_i32 v99, v99, 0, s99
	v_med3_i32 v253, v253, 0, s99
	v_med3_i32 v254, v254, 0, s99
	v_med3_i32 v255, v255, 0, s99
	v_mad_u32_u24 v80, v80, s100, v252
	v_mad_u32_u24 v83, v83, s100, v252
	v_mad_u32_u24 v99, v99, s100, v252
	v_mad_u32_u24 v253, v253, s100, v252
	v_mad_u32_u24 v254, v254, s100, v153
	v_mad_u32_u24 v255, v255, s100, v153
	global_load_dwordx4 v[156:159], v80, s[82:83]
	global_load_dwordx4 v[160:163], v83, s[82:83]
	global_load_dwordx4 v[164:167], v99, s[82:83]
	global_load_dwordx4 v[168:171], v253, s[82:83]
	global_load_dwordx4 v[172:175], v254, s[82:83] offset:768
	global_load_dwordx4 v[176:179], v255, s[82:83] offset:768
	global_load_dwordx4 v[180:183], v254, s[82:83] offset:832
	global_load_dwordx4 v[184:187], v255, s[82:83] offset:832
	ds_read_b64_tr_b16 v[72:73], v231
	ds_read_b64_tr_b16 v[74:75], v231 offset:512
	ds_read_b64_tr_b16 v[76:77], v231 offset:2048
	ds_read_b64_tr_b16 v[78:79], v231 offset:2560
	ds_read_b64_tr_b16 v[220:221], v231 offset:1024
	ds_read_b64_tr_b16 v[222:223], v231 offset:1536
	ds_read_b64_tr_b16 v[224:225], v231 offset:3072
	ds_read_b64_tr_b16 v[226:227], v231 offset:3584
	v_exp_f32_e32 v188, v188
	v_exp_f32_e32 v189, v189
	s_waitcnt vmcnt(8)
	ds_write_b128 v247, v[116:119]
	ds_write_b128 v247, v[120:123] offset:1024
	ds_write_b128 v247, v[124:127] offset:2048
	ds_write_b128 v247, v[128:131] offset:3072
	ds_read_b128 v[116:119], v248
	ds_read_b128 v[120:123], v249
	ds_read_b128 v[124:127], v250
	ds_read_b128 v[128:131], v251
	ds_write_b128 v112, v[132:135]
	ds_write_b128 v112, v[136:139] offset:1024
	ds_write_b128 v112, v[140:143] offset:2048
	ds_write_b128 v112, v[144:147] offset:3072
	v_exp_f32_e32 v190, v190
	v_exp_f32_e32 v191, v191
	s_waitcnt lgkmcnt(4)
	v_mfma_f32_32x32x16_bf16 v[32:47], v[116:119], v[48:51], v[32:47]
	v_exp_f32_e32 v192, v192
	v_exp_f32_e32 v193, v193
	v_exp_f32_e32 v194, v194
	v_mfma_f32_32x32x16_bf16 v[32:47], v[120:123], v[52:55], v[32:47]
	v_exp_f32_e32 v195, v195
	v_exp_f32_e32 v196, v196
	v_exp_f32_e32 v197, v197
	v_mfma_f32_32x32x16_bf16 v[32:47], v[124:127], v[56:59], v[32:47]
	v_exp_f32_e32 v198, v198
	v_exp_f32_e32 v199, v199
	v_exp_f32_e32 v200, v200
	v_mfma_f32_32x32x16_bf16 v[32:47], v[128:131], v[60:63], v[32:47]
	v_exp_f32_e32 v201, v201
	v_exp_f32_e32 v202, v202
	v_exp_f32_e32 v203, v203
	s_add_i32 s90, s67, 96
	v_add_u32_e32 v84, s90, v107
	v_add_u32_e32 v85, 0, v84
	v_add_u32_e32 v86, 1, v84
	v_add_u32_e32 v87, 2, v84
	v_add_u32_e32 v88, 3, v84
	v_cmp_gt_u32_e64 s[30:31], s98, v85
	v_cmp_gt_u32_e64 s[36:37], s98, v86
	v_cmp_gt_u32_e64 s[78:79], s98, v87
	v_cmp_gt_u32_e64 s[50:51], s98, v88
	v_cndmask_b32_e64 v188, 0, v188, s[30:31]
	v_add_u32_e32 v85, 8, v84
	v_cmp_gt_u32_e64 s[30:31], s98, v85
	v_cndmask_b32_e64 v189, 0, v189, s[36:37]
	v_add_u32_e32 v86, 9, v84
	v_cmp_gt_u32_e64 s[36:37], s98, v86
	v_cndmask_b32_e64 v190, 0, v190, s[78:79]
	v_add_u32_e32 v87, 10, v84
	v_cmp_gt_u32_e64 s[78:79], s98, v87
	v_cndmask_b32_e64 v191, 0, v191, s[50:51]
	v_add_u32_e32 v88, 11, v84
	v_cmp_gt_u32_e64 s[50:51], s98, v88
	v_cndmask_b32_e64 v192, 0, v192, s[30:31]
	v_add_u32_e32 v85, 16, v84
	v_cmp_gt_u32_e64 s[30:31], s98, v85
	v_cndmask_b32_e64 v193, 0, v193, s[36:37]
	v_add_u32_e32 v86, 17, v84
	v_cmp_gt_u32_e64 s[36:37], s98, v86
	v_cndmask_b32_e64 v194, 0, v194, s[78:79]
	v_add_u32_e32 v87, 18, v84
	v_cmp_gt_u32_e64 s[78:79], s98, v87
	v_cndmask_b32_e64 v195, 0, v195, s[50:51]
	v_add_u32_e32 v88, 19, v84
	v_cmp_gt_u32_e64 s[50:51], s98, v88
	v_cndmask_b32_e64 v196, 0, v196, s[30:31]
	v_add_u32_e32 v85, 24, v84
	v_cmp_gt_u32_e64 s[30:31], s98, v85
	v_cndmask_b32_e64 v197, 0, v197, s[36:37]
	v_add_u32_e32 v86, 25, v84
	v_cmp_gt_u32_e64 s[36:37], s98, v86
	v_cndmask_b32_e64 v198, 0, v198, s[78:79]
	v_add_u32_e32 v87, 26, v84
	v_cmp_gt_u32_e64 s[78:79], s98, v87
	v_cndmask_b32_e64 v199, 0, v199, s[50:51]
	v_add_u32_e32 v88, 27, v84
	v_cmp_gt_u32_e64 s[50:51], s98, v88
	v_nop
	v_cndmask_b32_e64 v200, 0, v200, s[30:31]
	v_cndmask_b32_e64 v201, 0, v201, s[36:37]
	v_cndmask_b32_e64 v202, 0, v202, s[78:79]
	v_cndmask_b32_e64 v203, 0, v203, s[50:51]
	v_cvt_pk_bf16_f32 v64, v188, v189
	v_cvt_pk_bf16_f32 v65, v190, v191
	v_cvt_pk_bf16_f32 v66, v192, v193
	v_cvt_pk_bf16_f32 v67, v194, v195
	v_cvt_pk_bf16_f32 v68, v196, v197
	v_cvt_pk_bf16_f32 v69, v198, v199
	v_cvt_pk_bf16_f32 v70, v200, v201
	v_cvt_pk_bf16_f32 v71, v202, v203
	v_pk_add_f32 v[232:233], v[232:233], v[188:189]
	v_pk_add_f32 v[232:233], v[232:233], v[190:191]
	v_pk_add_f32 v[232:233], v[232:233], v[192:193]
	v_pk_add_f32 v[232:233], v[232:233], v[194:195]
	v_pk_add_f32 v[232:233], v[232:233], v[196:197]
	v_pk_add_f32 v[232:233], v[232:233], v[198:199]
	v_pk_add_f32 v[232:233], v[232:233], v[200:201]
	v_pk_add_f32 v[232:233], v[232:233], v[202:203]
	v_add_u32_e32 v115, 952, v115
	ds_read2_b32 v[188:189], v115 offset0:0 offset1:1
	ds_read2_b32 v[190:191], v115 offset0:2 offset1:3
	ds_read2_b32 v[192:193], v115 offset0:8 offset1:9
	ds_read2_b32 v[194:195], v115 offset0:10 offset1:11
	ds_read2_b32 v[196:197], v115 offset0:17 offset1:18
	ds_read2_b32 v[198:199], v115 offset0:19 offset1:20
	ds_read2_b32 v[200:201], v115 offset0:25 offset1:26
	ds_read2_b32 v[202:203], v115 offset0:27 offset1:28
	v_mfma_f32_32x32x16_bf16 v[0:15], v[64:67], v[72:75], v[0:15]
	v_mfma_f32_32x32x16_bf16 v[16:31], v[64:67], v[76:79], v[16:31]
	v_mfma_f32_32x32x16_bf16 v[0:15], v[68:71], v[220:223], v[0:15]
	v_mfma_f32_32x32x16_bf16 v[16:31], v[68:71], v[224:227], v[16:31]
	s_add_i32 s90, s67, 192
	v_add_u32_e32 v80, s90, v235
	v_add_u32_e32 v83, s90, v236
	v_add_u32_e32 v99, s90, v237
	v_add_u32_e32 v253, s90, v238
	v_add_u32_e32 v254, s90, v100
	v_add_u32_e32 v255, s90, v149
	v_med3_i32 v80, v80, 0, s99
	v_med3_i32 v83, v83, 0, s99
	v_med3_i32 v99, v99, 0, s99
	v_med3_i32 v253, v253, 0, s99
	v_med3_i32 v254, v254, 0, s99
	v_med3_i32 v255, v255, 0, s99
	v_mad_u32_u24 v80, v80, s100, v252
	v_mad_u32_u24 v83, v83, s100, v252
	v_mad_u32_u24 v99, v99, s100, v252
	v_mad_u32_u24 v253, v253, s100, v252
	v_mad_u32_u24 v254, v254, s100, v153
	v_mad_u32_u24 v255, v255, s100, v153
	global_load_dwordx4 v[116:119], v80, s[82:83]
	global_load_dwordx4 v[120:123], v83, s[82:83]
	global_load_dwordx4 v[124:127], v99, s[82:83]
	global_load_dwordx4 v[128:131], v253, s[82:83]
	global_load_dwordx4 v[132:135], v254, s[82:83] offset:768
	global_load_dwordx4 v[136:139], v255, s[82:83] offset:768
	global_load_dwordx4 v[140:143], v254, s[82:83] offset:832
	global_load_dwordx4 v[144:147], v255, s[82:83] offset:832
	ds_read_b64_tr_b16 v[72:73], v231
	ds_read_b64_tr_b16 v[74:75], v231 offset:512
	ds_read_b64_tr_b16 v[76:77], v231 offset:2048
	ds_read_b64_tr_b16 v[78:79], v231 offset:2560
	ds_read_b64_tr_b16 v[220:221], v231 offset:1024
	ds_read_b64_tr_b16 v[222:223], v231 offset:1536
	ds_read_b64_tr_b16 v[224:225], v231 offset:3072
	ds_read_b64_tr_b16 v[226:227], v231 offset:3584
	v_exp_f32_e32 v32, v32
	v_exp_f32_e32 v33, v33
	s_waitcnt vmcnt(8)
	ds_write_b128 v247, v[156:159]
	ds_write_b128 v247, v[160:163] offset:1024
	ds_write_b128 v247, v[164:167] offset:2048
	ds_write_b128 v247, v[168:171] offset:3072
	ds_read_b128 v[156:159], v248
	ds_read_b128 v[160:163], v249
	ds_read_b128 v[164:167], v250
	ds_read_b128 v[168:171], v251
	ds_write_b128 v112, v[172:175]
	ds_write_b128 v112, v[176:179] offset:1024
	ds_write_b128 v112, v[180:183] offset:2048
	ds_write_b128 v112, v[184:187] offset:3072
	v_exp_f32_e32 v34, v34
	v_exp_f32_e32 v35, v35
	s_waitcnt lgkmcnt(4)
	v_mfma_f32_32x32x16_bf16 v[188:203], v[156:159], v[48:51], v[188:203]
	v_exp_f32_e32 v36, v36
	v_exp_f32_e32 v37, v37
	v_exp_f32_e32 v38, v38
	v_mfma_f32_32x32x16_bf16 v[188:203], v[160:163], v[52:55], v[188:203]
	v_exp_f32_e32 v39, v39
	v_exp_f32_e32 v40, v40
	v_exp_f32_e32 v41, v41
	v_mfma_f32_32x32x16_bf16 v[188:203], v[164:167], v[56:59], v[188:203]
	v_exp_f32_e32 v42, v42
	v_exp_f32_e32 v43, v43
	v_exp_f32_e32 v44, v44
	v_mfma_f32_32x32x16_bf16 v[188:203], v[168:171], v[60:63], v[188:203]
	v_exp_f32_e32 v45, v45
	v_exp_f32_e32 v46, v46
	v_exp_f32_e32 v47, v47
	s_add_i32 s90, s67, 128
	v_add_u32_e32 v84, s90, v107
	v_add_u32_e32 v85, 0, v84
	v_add_u32_e32 v86, 1, v84
	v_add_u32_e32 v87, 2, v84
	v_add_u32_e32 v88, 3, v84
	v_cmp_gt_u32_e64 s[30:31], s98, v85
	v_cmp_gt_u32_e64 s[36:37], s98, v86
	v_cmp_gt_u32_e64 s[78:79], s98, v87
	v_cmp_gt_u32_e64 s[50:51], s98, v88
	v_cndmask_b32_e64 v32, 0, v32, s[30:31]
	v_add_u32_e32 v85, 8, v84
	v_cmp_gt_u32_e64 s[30:31], s98, v85
	v_cndmask_b32_e64 v33, 0, v33, s[36:37]
	v_add_u32_e32 v86, 9, v84
	v_cmp_gt_u32_e64 s[36:37], s98, v86
	v_cndmask_b32_e64 v34, 0, v34, s[78:79]
	v_add_u32_e32 v87, 10, v84
	v_cmp_gt_u32_e64 s[78:79], s98, v87
	v_cndmask_b32_e64 v35, 0, v35, s[50:51]
	v_add_u32_e32 v88, 11, v84
	v_cmp_gt_u32_e64 s[50:51], s98, v88
	v_cndmask_b32_e64 v36, 0, v36, s[30:31]
	v_add_u32_e32 v85, 16, v84
	v_cmp_gt_u32_e64 s[30:31], s98, v85
	v_cndmask_b32_e64 v37, 0, v37, s[36:37]
	v_add_u32_e32 v86, 17, v84
	v_cmp_gt_u32_e64 s[36:37], s98, v86
	v_cndmask_b32_e64 v38, 0, v38, s[78:79]
	v_add_u32_e32 v87, 18, v84
	v_cmp_gt_u32_e64 s[78:79], s98, v87
	v_cndmask_b32_e64 v39, 0, v39, s[50:51]
	v_add_u32_e32 v88, 19, v84
	v_cmp_gt_u32_e64 s[50:51], s98, v88
	v_cndmask_b32_e64 v40, 0, v40, s[30:31]
	v_add_u32_e32 v85, 24, v84
	v_cmp_gt_u32_e64 s[30:31], s98, v85
	v_cndmask_b32_e64 v41, 0, v41, s[36:37]
	v_add_u32_e32 v86, 25, v84
	v_cmp_gt_u32_e64 s[36:37], s98, v86
	v_cndmask_b32_e64 v42, 0, v42, s[78:79]
	v_add_u32_e32 v87, 26, v84
	v_cmp_gt_u32_e64 s[78:79], s98, v87
	v_cndmask_b32_e64 v43, 0, v43, s[50:51]
	v_add_u32_e32 v88, 27, v84
	v_cmp_gt_u32_e64 s[50:51], s98, v88
	v_nop
	v_cndmask_b32_e64 v44, 0, v44, s[30:31]
	v_cndmask_b32_e64 v45, 0, v45, s[36:37]
	v_cndmask_b32_e64 v46, 0, v46, s[78:79]
	v_cndmask_b32_e64 v47, 0, v47, s[50:51]
	v_cvt_pk_bf16_f32 v64, v32, v33
	v_cvt_pk_bf16_f32 v65, v34, v35
	v_cvt_pk_bf16_f32 v66, v36, v37
	v_cvt_pk_bf16_f32 v67, v38, v39
	v_cvt_pk_bf16_f32 v68, v40, v41
	v_cvt_pk_bf16_f32 v69, v42, v43
	v_cvt_pk_bf16_f32 v70, v44, v45
	v_cvt_pk_bf16_f32 v71, v46, v47
	v_pk_add_f32 v[232:233], v[232:233], v[32:33]
	v_pk_add_f32 v[232:233], v[232:233], v[34:35]
	v_pk_add_f32 v[232:233], v[232:233], v[36:37]
	v_pk_add_f32 v[232:233], v[232:233], v[38:39]
	v_pk_add_f32 v[232:233], v[232:233], v[40:41]
	v_pk_add_f32 v[232:233], v[232:233], v[42:43]
	v_pk_add_f32 v[232:233], v[232:233], v[44:45]
	v_pk_add_f32 v[232:233], v[232:233], v[46:47]
	ds_read2_b32 v[32:33], v115 offset0:34 offset1:35
	ds_read2_b32 v[34:35], v115 offset0:36 offset1:37
	ds_read2_b32 v[36:37], v115 offset0:42 offset1:43
	ds_read2_b32 v[38:39], v115 offset0:44 offset1:45
	ds_read2_b32 v[40:41], v115 offset0:51 offset1:52
	ds_read2_b32 v[42:43], v115 offset0:53 offset1:54
	ds_read2_b32 v[44:45], v115 offset0:59 offset1:60
	ds_read2_b32 v[46:47], v115 offset0:61 offset1:62
	v_mfma_f32_32x32x16_bf16 v[0:15], v[64:67], v[72:75], v[0:15]
	v_mfma_f32_32x32x16_bf16 v[16:31], v[64:67], v[76:79], v[16:31]
	v_mfma_f32_32x32x16_bf16 v[0:15], v[68:71], v[220:223], v[0:15]
	v_mfma_f32_32x32x16_bf16 v[16:31], v[68:71], v[224:227], v[16:31]
	s_add_i32 s90, s67, 224
	v_add_u32_e32 v80, s90, v235
	v_add_u32_e32 v83, s90, v236
	v_add_u32_e32 v99, s90, v237
	v_add_u32_e32 v253, s90, v238
	v_add_u32_e32 v254, s90, v100
	v_add_u32_e32 v255, s90, v149
	v_med3_i32 v80, v80, 0, s99
	v_med3_i32 v83, v83, 0, s99
	v_med3_i32 v99, v99, 0, s99
	v_med3_i32 v253, v253, 0, s99
	v_med3_i32 v254, v254, 0, s99
	v_med3_i32 v255, v255, 0, s99
	v_mad_u32_u24 v80, v80, s100, v252
	v_mad_u32_u24 v83, v83, s100, v252
	v_mad_u32_u24 v99, v99, s100, v252
	v_mad_u32_u24 v253, v253, s100, v252
	v_mad_u32_u24 v254, v254, s100, v153
	v_mad_u32_u24 v255, v255, s100, v153
	global_load_dwordx4 v[156:159], v80, s[82:83]
	global_load_dwordx4 v[160:163], v83, s[82:83]
	global_load_dwordx4 v[164:167], v99, s[82:83]
	global_load_dwordx4 v[168:171], v253, s[82:83]
	global_load_dwordx4 v[172:175], v254, s[82:83] offset:768
	global_load_dwordx4 v[176:179], v255, s[82:83] offset:768
	global_load_dwordx4 v[180:183], v254, s[82:83] offset:832
	global_load_dwordx4 v[184:187], v255, s[82:83] offset:832
	ds_read_b64_tr_b16 v[72:73], v231
	ds_read_b64_tr_b16 v[74:75], v231 offset:512
	ds_read_b64_tr_b16 v[76:77], v231 offset:2048
	ds_read_b64_tr_b16 v[78:79], v231 offset:2560
	ds_read_b64_tr_b16 v[220:221], v231 offset:1024
	ds_read_b64_tr_b16 v[222:223], v231 offset:1536
	ds_read_b64_tr_b16 v[224:225], v231 offset:3072
	ds_read_b64_tr_b16 v[226:227], v231 offset:3584
	v_exp_f32_e32 v188, v188
	v_exp_f32_e32 v189, v189
	s_waitcnt vmcnt(8)
	ds_write_b128 v247, v[116:119]
	ds_write_b128 v247, v[120:123] offset:1024
	ds_write_b128 v247, v[124:127] offset:2048
	ds_write_b128 v247, v[128:131] offset:3072
	ds_read_b128 v[116:119], v248
	ds_read_b128 v[120:123], v249
	ds_read_b128 v[124:127], v250
	ds_read_b128 v[128:131], v251
	ds_write_b128 v112, v[132:135]
	ds_write_b128 v112, v[136:139] offset:1024
	ds_write_b128 v112, v[140:143] offset:2048
	ds_write_b128 v112, v[144:147] offset:3072
	v_exp_f32_e32 v190, v190
	v_exp_f32_e32 v191, v191
	s_waitcnt lgkmcnt(4)
	v_mfma_f32_32x32x16_bf16 v[32:47], v[116:119], v[48:51], v[32:47]
	v_exp_f32_e32 v192, v192
	v_exp_f32_e32 v193, v193
	v_exp_f32_e32 v194, v194
	v_mfma_f32_32x32x16_bf16 v[32:47], v[120:123], v[52:55], v[32:47]
	v_exp_f32_e32 v195, v195
	v_exp_f32_e32 v196, v196
	v_exp_f32_e32 v197, v197
	v_mfma_f32_32x32x16_bf16 v[32:47], v[124:127], v[56:59], v[32:47]
	v_exp_f32_e32 v198, v198
	v_exp_f32_e32 v199, v199
	v_exp_f32_e32 v200, v200
	v_mfma_f32_32x32x16_bf16 v[32:47], v[128:131], v[60:63], v[32:47]
	v_exp_f32_e32 v201, v201
	v_exp_f32_e32 v202, v202
	v_exp_f32_e32 v203, v203
	s_add_i32 s90, s67, 160
	v_add_u32_e32 v84, s90, v107
	v_add_u32_e32 v85, 0, v84
	v_add_u32_e32 v86, 1, v84
	v_add_u32_e32 v87, 2, v84
	v_add_u32_e32 v88, 3, v84
	v_cmp_gt_u32_e64 s[30:31], s98, v85
	v_cmp_gt_u32_e64 s[36:37], s98, v86
	v_cmp_gt_u32_e64 s[78:79], s98, v87
	v_cmp_gt_u32_e64 s[50:51], s98, v88
	v_cndmask_b32_e64 v188, 0, v188, s[30:31]
	v_add_u32_e32 v85, 8, v84
	v_cmp_gt_u32_e64 s[30:31], s98, v85
	v_cndmask_b32_e64 v189, 0, v189, s[36:37]
	v_add_u32_e32 v86, 9, v84
	v_cmp_gt_u32_e64 s[36:37], s98, v86
	v_cndmask_b32_e64 v190, 0, v190, s[78:79]
	v_add_u32_e32 v87, 10, v84
	v_cmp_gt_u32_e64 s[78:79], s98, v87
	v_cndmask_b32_e64 v191, 0, v191, s[50:51]
	v_add_u32_e32 v88, 11, v84
	v_cmp_gt_u32_e64 s[50:51], s98, v88
	v_cndmask_b32_e64 v192, 0, v192, s[30:31]
	v_add_u32_e32 v85, 16, v84
	v_cmp_gt_u32_e64 s[30:31], s98, v85
	v_cndmask_b32_e64 v193, 0, v193, s[36:37]
	v_add_u32_e32 v86, 17, v84
	v_cmp_gt_u32_e64 s[36:37], s98, v86
	v_cndmask_b32_e64 v194, 0, v194, s[78:79]
	v_add_u32_e32 v87, 18, v84
	v_cmp_gt_u32_e64 s[78:79], s98, v87
	v_cndmask_b32_e64 v195, 0, v195, s[50:51]
	v_add_u32_e32 v88, 19, v84
	v_cmp_gt_u32_e64 s[50:51], s98, v88
	v_cndmask_b32_e64 v196, 0, v196, s[30:31]
	v_add_u32_e32 v85, 24, v84
	v_cmp_gt_u32_e64 s[30:31], s98, v85
	v_cndmask_b32_e64 v197, 0, v197, s[36:37]
	v_add_u32_e32 v86, 25, v84
	v_cmp_gt_u32_e64 s[36:37], s98, v86
	v_cndmask_b32_e64 v198, 0, v198, s[78:79]
	v_add_u32_e32 v87, 26, v84
	v_cmp_gt_u32_e64 s[78:79], s98, v87
	v_cndmask_b32_e64 v199, 0, v199, s[50:51]
	v_add_u32_e32 v88, 27, v84
	v_cmp_gt_u32_e64 s[50:51], s98, v88
	v_nop
	v_cndmask_b32_e64 v200, 0, v200, s[30:31]
	v_cndmask_b32_e64 v201, 0, v201, s[36:37]
	v_cndmask_b32_e64 v202, 0, v202, s[78:79]
	v_cndmask_b32_e64 v203, 0, v203, s[50:51]
	v_cvt_pk_bf16_f32 v64, v188, v189
	v_cvt_pk_bf16_f32 v65, v190, v191
	v_cvt_pk_bf16_f32 v66, v192, v193
	v_cvt_pk_bf16_f32 v67, v194, v195
	v_cvt_pk_bf16_f32 v68, v196, v197
	v_cvt_pk_bf16_f32 v69, v198, v199
	v_cvt_pk_bf16_f32 v70, v200, v201
	v_cvt_pk_bf16_f32 v71, v202, v203
	v_pk_add_f32 v[232:233], v[232:233], v[188:189]
	v_pk_add_f32 v[232:233], v[232:233], v[190:191]
	v_pk_add_f32 v[232:233], v[232:233], v[192:193]
	v_pk_add_f32 v[232:233], v[232:233], v[194:195]
	v_pk_add_f32 v[232:233], v[232:233], v[196:197]
	v_pk_add_f32 v[232:233], v[232:233], v[198:199]
	v_pk_add_f32 v[232:233], v[232:233], v[200:201]
	v_pk_add_f32 v[232:233], v[232:233], v[202:203]
	ds_read2_b32 v[188:189], v115 offset0:68 offset1:69
	ds_read2_b32 v[190:191], v115 offset0:70 offset1:71
	ds_read2_b32 v[192:193], v115 offset0:76 offset1:77
	ds_read2_b32 v[194:195], v115 offset0:78 offset1:79
	ds_read2_b32 v[196:197], v115 offset0:85 offset1:86
	ds_read2_b32 v[198:199], v115 offset0:87 offset1:88
	ds_read2_b32 v[200:201], v115 offset0:93 offset1:94
	ds_read2_b32 v[202:203], v115 offset0:95 offset1:96
	v_mfma_f32_32x32x16_bf16 v[0:15], v[64:67], v[72:75], v[0:15]
	v_mfma_f32_32x32x16_bf16 v[16:31], v[64:67], v[76:79], v[16:31]
	v_mfma_f32_32x32x16_bf16 v[0:15], v[68:71], v[220:223], v[0:15]
	v_mfma_f32_32x32x16_bf16 v[16:31], v[68:71], v[224:227], v[16:31]
	s_add_i32 s90, s67, 256
	v_add_u32_e32 v80, s90, v235
	v_add_u32_e32 v83, s90, v236
	v_add_u32_e32 v99, s90, v237
	v_add_u32_e32 v253, s90, v238
	v_add_u32_e32 v254, s90, v100
	v_add_u32_e32 v255, s90, v149
	v_med3_i32 v80, v80, 0, s99
	v_med3_i32 v83, v83, 0, s99
	v_med3_i32 v99, v99, 0, s99
	v_med3_i32 v253, v253, 0, s99
	v_med3_i32 v254, v254, 0, s99
	v_med3_i32 v255, v255, 0, s99
	v_mad_u32_u24 v80, v80, s100, v252
	v_mad_u32_u24 v83, v83, s100, v252
	v_mad_u32_u24 v99, v99, s100, v252
	v_mad_u32_u24 v253, v253, s100, v252
	v_mad_u32_u24 v254, v254, s100, v153
	v_mad_u32_u24 v255, v255, s100, v153
	global_load_dwordx4 v[116:119], v80, s[82:83]
	global_load_dwordx4 v[120:123], v83, s[82:83]
	global_load_dwordx4 v[124:127], v99, s[82:83]
	global_load_dwordx4 v[128:131], v253, s[82:83]
	global_load_dwordx4 v[132:135], v254, s[82:83] offset:768
	global_load_dwordx4 v[136:139], v255, s[82:83] offset:768
	global_load_dwordx4 v[140:143], v254, s[82:83] offset:832
	global_load_dwordx4 v[144:147], v255, s[82:83] offset:832
	ds_read_b64_tr_b16 v[72:73], v231
	ds_read_b64_tr_b16 v[74:75], v231 offset:512
	ds_read_b64_tr_b16 v[76:77], v231 offset:2048
	ds_read_b64_tr_b16 v[78:79], v231 offset:2560
	ds_read_b64_tr_b16 v[220:221], v231 offset:1024
	ds_read_b64_tr_b16 v[222:223], v231 offset:1536
	ds_read_b64_tr_b16 v[224:225], v231 offset:3072
	ds_read_b64_tr_b16 v[226:227], v231 offset:3584
	v_exp_f32_e32 v32, v32
	v_exp_f32_e32 v33, v33
	s_waitcnt vmcnt(8)
	ds_write_b128 v247, v[156:159]
	ds_write_b128 v247, v[160:163] offset:1024
	ds_write_b128 v247, v[164:167] offset:2048
	ds_write_b128 v247, v[168:171] offset:3072
	ds_read_b128 v[156:159], v248
	ds_read_b128 v[160:163], v249
	ds_read_b128 v[164:167], v250
	ds_read_b128 v[168:171], v251
	ds_write_b128 v112, v[172:175]
	ds_write_b128 v112, v[176:179] offset:1024
	ds_write_b128 v112, v[180:183] offset:2048
	ds_write_b128 v112, v[184:187] offset:3072
	v_exp_f32_e32 v34, v34
	v_exp_f32_e32 v35, v35
	s_waitcnt lgkmcnt(4)
	v_mfma_f32_32x32x16_bf16 v[188:203], v[156:159], v[48:51], v[188:203]
	v_exp_f32_e32 v36, v36
	v_exp_f32_e32 v37, v37
	v_exp_f32_e32 v38, v38
	v_mfma_f32_32x32x16_bf16 v[188:203], v[160:163], v[52:55], v[188:203]
	v_exp_f32_e32 v39, v39
	v_exp_f32_e32 v40, v40
	v_exp_f32_e32 v41, v41
	v_mfma_f32_32x32x16_bf16 v[188:203], v[164:167], v[56:59], v[188:203]
	v_exp_f32_e32 v42, v42
	v_exp_f32_e32 v43, v43
	v_exp_f32_e32 v44, v44
	v_mfma_f32_32x32x16_bf16 v[188:203], v[168:171], v[60:63], v[188:203]
	v_exp_f32_e32 v45, v45
	v_exp_f32_e32 v46, v46
	v_exp_f32_e32 v47, v47
	s_add_i32 s90, s67, 192
	v_add_u32_e32 v84, s90, v107
	v_add_u32_e32 v85, 0, v84
	v_add_u32_e32 v86, 1, v84
	v_add_u32_e32 v87, 2, v84
	v_add_u32_e32 v88, 3, v84
	v_cmp_gt_u32_e64 s[30:31], s98, v85
	v_cmp_gt_u32_e64 s[36:37], s98, v86
	v_cmp_gt_u32_e64 s[78:79], s98, v87
	v_cmp_gt_u32_e64 s[50:51], s98, v88
	v_cndmask_b32_e64 v32, 0, v32, s[30:31]
	v_add_u32_e32 v85, 8, v84
	v_cmp_gt_u32_e64 s[30:31], s98, v85
	v_cndmask_b32_e64 v33, 0, v33, s[36:37]
	v_add_u32_e32 v86, 9, v84
	v_cmp_gt_u32_e64 s[36:37], s98, v86
	v_cndmask_b32_e64 v34, 0, v34, s[78:79]
	v_add_u32_e32 v87, 10, v84
	v_cmp_gt_u32_e64 s[78:79], s98, v87
	v_cndmask_b32_e64 v35, 0, v35, s[50:51]
	v_add_u32_e32 v88, 11, v84
	v_cmp_gt_u32_e64 s[50:51], s98, v88
	v_cndmask_b32_e64 v36, 0, v36, s[30:31]
	v_add_u32_e32 v85, 16, v84
	v_cmp_gt_u32_e64 s[30:31], s98, v85
	v_cndmask_b32_e64 v37, 0, v37, s[36:37]
	v_add_u32_e32 v86, 17, v84
	v_cmp_gt_u32_e64 s[36:37], s98, v86
	v_cndmask_b32_e64 v38, 0, v38, s[78:79]
	v_add_u32_e32 v87, 18, v84
	v_cmp_gt_u32_e64 s[78:79], s98, v87
	v_cndmask_b32_e64 v39, 0, v39, s[50:51]
	v_add_u32_e32 v88, 19, v84
	v_cmp_gt_u32_e64 s[50:51], s98, v88
	v_cndmask_b32_e64 v40, 0, v40, s[30:31]
	v_add_u32_e32 v85, 24, v84
	v_cmp_gt_u32_e64 s[30:31], s98, v85
	v_cndmask_b32_e64 v41, 0, v41, s[36:37]
	v_add_u32_e32 v86, 25, v84
	v_cmp_gt_u32_e64 s[36:37], s98, v86
	v_cndmask_b32_e64 v42, 0, v42, s[78:79]
	v_add_u32_e32 v87, 26, v84
	v_cmp_gt_u32_e64 s[78:79], s98, v87
	v_cndmask_b32_e64 v43, 0, v43, s[50:51]
	v_add_u32_e32 v88, 27, v84
	v_cmp_gt_u32_e64 s[50:51], s98, v88
	v_nop
	v_cndmask_b32_e64 v44, 0, v44, s[30:31]
	v_cndmask_b32_e64 v45, 0, v45, s[36:37]
	v_cndmask_b32_e64 v46, 0, v46, s[78:79]
	v_cndmask_b32_e64 v47, 0, v47, s[50:51]
	v_cvt_pk_bf16_f32 v64, v32, v33
	v_cvt_pk_bf16_f32 v65, v34, v35
	v_cvt_pk_bf16_f32 v66, v36, v37
	v_cvt_pk_bf16_f32 v67, v38, v39
	v_cvt_pk_bf16_f32 v68, v40, v41
	v_cvt_pk_bf16_f32 v69, v42, v43
	v_cvt_pk_bf16_f32 v70, v44, v45
	v_cvt_pk_bf16_f32 v71, v46, v47
	v_pk_add_f32 v[232:233], v[232:233], v[32:33]
	v_pk_add_f32 v[232:233], v[232:233], v[34:35]
	v_pk_add_f32 v[232:233], v[232:233], v[36:37]
	v_pk_add_f32 v[232:233], v[232:233], v[38:39]
	v_pk_add_f32 v[232:233], v[232:233], v[40:41]
	v_pk_add_f32 v[232:233], v[232:233], v[42:43]
	v_pk_add_f32 v[232:233], v[232:233], v[44:45]
	v_pk_add_f32 v[232:233], v[232:233], v[46:47]
	ds_read2_b32 v[32:33], v115 offset0:102 offset1:103
	ds_read2_b32 v[34:35], v115 offset0:104 offset1:105
	ds_read2_b32 v[36:37], v115 offset0:110 offset1:111
	ds_read2_b32 v[38:39], v115 offset0:112 offset1:113
	ds_read2_b32 v[40:41], v115 offset0:119 offset1:120
	ds_read2_b32 v[42:43], v115 offset0:121 offset1:122
	ds_read2_b32 v[44:45], v115 offset0:127 offset1:128
	ds_read2_b32 v[46:47], v115 offset0:129 offset1:130
	v_mfma_f32_32x32x16_bf16 v[0:15], v[64:67], v[72:75], v[0:15]
	v_mfma_f32_32x32x16_bf16 v[16:31], v[64:67], v[76:79], v[16:31]
	v_mfma_f32_32x32x16_bf16 v[0:15], v[68:71], v[220:223], v[0:15]
	v_mfma_f32_32x32x16_bf16 v[16:31], v[68:71], v[224:227], v[16:31]
	s_add_i32 s90, s67, 288
	v_add_u32_e32 v80, s90, v235
	v_add_u32_e32 v83, s90, v236
	v_add_u32_e32 v99, s90, v237
	v_add_u32_e32 v253, s90, v238
	v_add_u32_e32 v254, s90, v100
	v_add_u32_e32 v255, s90, v149
	v_med3_i32 v80, v80, 0, s99
	v_med3_i32 v83, v83, 0, s99
	v_med3_i32 v99, v99, 0, s99
	v_med3_i32 v253, v253, 0, s99
	v_med3_i32 v254, v254, 0, s99
	v_med3_i32 v255, v255, 0, s99
	v_mad_u32_u24 v80, v80, s100, v252
	v_mad_u32_u24 v83, v83, s100, v252
	v_mad_u32_u24 v99, v99, s100, v252
	v_mad_u32_u24 v253, v253, s100, v252
	v_mad_u32_u24 v254, v254, s100, v153
	v_mad_u32_u24 v255, v255, s100, v153
	global_load_dwordx4 v[156:159], v80, s[82:83]
	global_load_dwordx4 v[160:163], v83, s[82:83]
	global_load_dwordx4 v[164:167], v99, s[82:83]
	global_load_dwordx4 v[168:171], v253, s[82:83]
	global_load_dwordx4 v[172:175], v254, s[82:83] offset:768
	global_load_dwordx4 v[176:179], v255, s[82:83] offset:768
	global_load_dwordx4 v[180:183], v254, s[82:83] offset:832
	global_load_dwordx4 v[184:187], v255, s[82:83] offset:832
	ds_read_b64_tr_b16 v[72:73], v231
	ds_read_b64_tr_b16 v[74:75], v231 offset:512
	ds_read_b64_tr_b16 v[76:77], v231 offset:2048
	ds_read_b64_tr_b16 v[78:79], v231 offset:2560
	ds_read_b64_tr_b16 v[220:221], v231 offset:1024
	ds_read_b64_tr_b16 v[222:223], v231 offset:1536
	ds_read_b64_tr_b16 v[224:225], v231 offset:3072
	ds_read_b64_tr_b16 v[226:227], v231 offset:3584
	v_exp_f32_e32 v188, v188
	v_exp_f32_e32 v189, v189
	s_waitcnt vmcnt(8)
	ds_write_b128 v247, v[116:119]
	ds_write_b128 v247, v[120:123] offset:1024
	ds_write_b128 v247, v[124:127] offset:2048
	ds_write_b128 v247, v[128:131] offset:3072
	ds_read_b128 v[116:119], v248
	ds_read_b128 v[120:123], v249
	ds_read_b128 v[124:127], v250
	ds_read_b128 v[128:131], v251
	ds_write_b128 v112, v[132:135]
	ds_write_b128 v112, v[136:139] offset:1024
	ds_write_b128 v112, v[140:143] offset:2048
	ds_write_b128 v112, v[144:147] offset:3072
	v_exp_f32_e32 v190, v190
	v_exp_f32_e32 v191, v191
	s_waitcnt lgkmcnt(4)
	v_mfma_f32_32x32x16_bf16 v[32:47], v[116:119], v[48:51], v[32:47]
	v_exp_f32_e32 v192, v192
	v_exp_f32_e32 v193, v193
	v_exp_f32_e32 v194, v194
	v_mfma_f32_32x32x16_bf16 v[32:47], v[120:123], v[52:55], v[32:47]
	v_exp_f32_e32 v195, v195
	v_exp_f32_e32 v196, v196
	v_exp_f32_e32 v197, v197
	v_mfma_f32_32x32x16_bf16 v[32:47], v[124:127], v[56:59], v[32:47]
	v_exp_f32_e32 v198, v198
	v_exp_f32_e32 v199, v199
	v_exp_f32_e32 v200, v200
	v_mfma_f32_32x32x16_bf16 v[32:47], v[128:131], v[60:63], v[32:47]
	v_exp_f32_e32 v201, v201
	v_exp_f32_e32 v202, v202
	v_exp_f32_e32 v203, v203
	s_add_i32 s90, s67, 224
	v_add_u32_e32 v84, s90, v107
	v_add_u32_e32 v85, 0, v84
	v_add_u32_e32 v86, 1, v84
	v_add_u32_e32 v87, 2, v84
	v_add_u32_e32 v88, 3, v84
	v_cmp_gt_u32_e64 s[30:31], s98, v85
	v_cmp_gt_u32_e64 s[36:37], s98, v86
	v_cmp_gt_u32_e64 s[78:79], s98, v87
	v_cmp_gt_u32_e64 s[50:51], s98, v88
	v_cndmask_b32_e64 v188, 0, v188, s[30:31]
	v_add_u32_e32 v85, 8, v84
	v_cmp_gt_u32_e64 s[30:31], s98, v85
	v_cndmask_b32_e64 v189, 0, v189, s[36:37]
	v_add_u32_e32 v86, 9, v84
	v_cmp_gt_u32_e64 s[36:37], s98, v86
	v_cndmask_b32_e64 v190, 0, v190, s[78:79]
	v_add_u32_e32 v87, 10, v84
	v_cmp_gt_u32_e64 s[78:79], s98, v87
	v_cndmask_b32_e64 v191, 0, v191, s[50:51]
	v_add_u32_e32 v88, 11, v84
	v_cmp_gt_u32_e64 s[50:51], s98, v88
	v_cndmask_b32_e64 v192, 0, v192, s[30:31]
	v_add_u32_e32 v85, 16, v84
	v_cmp_gt_u32_e64 s[30:31], s98, v85
	v_cndmask_b32_e64 v193, 0, v193, s[36:37]
	v_add_u32_e32 v86, 17, v84
	v_cmp_gt_u32_e64 s[36:37], s98, v86
	v_cndmask_b32_e64 v194, 0, v194, s[78:79]
	v_add_u32_e32 v87, 18, v84
	v_cmp_gt_u32_e64 s[78:79], s98, v87
	v_cndmask_b32_e64 v195, 0, v195, s[50:51]
	v_add_u32_e32 v88, 19, v84
	v_cmp_gt_u32_e64 s[50:51], s98, v88
	v_cndmask_b32_e64 v196, 0, v196, s[30:31]
	v_add_u32_e32 v85, 24, v84
	v_cmp_gt_u32_e64 s[30:31], s98, v85
	v_cndmask_b32_e64 v197, 0, v197, s[36:37]
	v_add_u32_e32 v86, 25, v84
	v_cmp_gt_u32_e64 s[36:37], s98, v86
	v_cndmask_b32_e64 v198, 0, v198, s[78:79]
	v_add_u32_e32 v87, 26, v84
	v_cmp_gt_u32_e64 s[78:79], s98, v87
	v_cndmask_b32_e64 v199, 0, v199, s[50:51]
	v_add_u32_e32 v88, 27, v84
	v_cmp_gt_u32_e64 s[50:51], s98, v88
	v_nop
	v_cndmask_b32_e64 v200, 0, v200, s[30:31]
	v_cndmask_b32_e64 v201, 0, v201, s[36:37]
	v_cndmask_b32_e64 v202, 0, v202, s[78:79]
	v_cndmask_b32_e64 v203, 0, v203, s[50:51]
	v_cvt_pk_bf16_f32 v64, v188, v189
	v_cvt_pk_bf16_f32 v65, v190, v191
	v_cvt_pk_bf16_f32 v66, v192, v193
	v_cvt_pk_bf16_f32 v67, v194, v195
	v_cvt_pk_bf16_f32 v68, v196, v197
	v_cvt_pk_bf16_f32 v69, v198, v199
	v_cvt_pk_bf16_f32 v70, v200, v201
	v_cvt_pk_bf16_f32 v71, v202, v203
	v_pk_add_f32 v[232:233], v[232:233], v[188:189]
	v_pk_add_f32 v[232:233], v[232:233], v[190:191]
	v_pk_add_f32 v[232:233], v[232:233], v[192:193]
	v_pk_add_f32 v[232:233], v[232:233], v[194:195]
	v_pk_add_f32 v[232:233], v[232:233], v[196:197]
	v_pk_add_f32 v[232:233], v[232:233], v[198:199]
	v_pk_add_f32 v[232:233], v[232:233], v[200:201]
	v_pk_add_f32 v[232:233], v[232:233], v[202:203]
	ds_read2_b32 v[188:189], v115 offset0:136 offset1:137
	ds_read2_b32 v[190:191], v115 offset0:138 offset1:139
	ds_read2_b32 v[192:193], v115 offset0:144 offset1:145
	ds_read2_b32 v[194:195], v115 offset0:146 offset1:147
	ds_read2_b32 v[196:197], v115 offset0:153 offset1:154
	ds_read2_b32 v[198:199], v115 offset0:155 offset1:156
	ds_read2_b32 v[200:201], v115 offset0:161 offset1:162
	ds_read2_b32 v[202:203], v115 offset0:163 offset1:164
	v_mfma_f32_32x32x16_bf16 v[0:15], v[64:67], v[72:75], v[0:15]
	v_mfma_f32_32x32x16_bf16 v[16:31], v[64:67], v[76:79], v[16:31]
	v_mfma_f32_32x32x16_bf16 v[0:15], v[68:71], v[220:223], v[0:15]
	v_mfma_f32_32x32x16_bf16 v[16:31], v[68:71], v[224:227], v[16:31]
	s_add_i32 s90, s67, 320
	v_add_u32_e32 v80, s90, v235
	v_add_u32_e32 v83, s90, v236
	v_add_u32_e32 v99, s90, v237
	v_add_u32_e32 v253, s90, v238
	v_add_u32_e32 v254, s90, v100
	v_add_u32_e32 v255, s90, v149
	v_med3_i32 v80, v80, 0, s99
	v_med3_i32 v83, v83, 0, s99
	v_med3_i32 v99, v99, 0, s99
	v_med3_i32 v253, v253, 0, s99
	v_med3_i32 v254, v254, 0, s99
	v_med3_i32 v255, v255, 0, s99
	v_mad_u32_u24 v80, v80, s100, v252
	v_mad_u32_u24 v83, v83, s100, v252
	v_mad_u32_u24 v99, v99, s100, v252
	v_mad_u32_u24 v253, v253, s100, v252
	v_mad_u32_u24 v254, v254, s100, v153
	v_mad_u32_u24 v255, v255, s100, v153
	global_load_dwordx4 v[116:119], v80, s[82:83]
	global_load_dwordx4 v[120:123], v83, s[82:83]
	global_load_dwordx4 v[124:127], v99, s[82:83]
	global_load_dwordx4 v[128:131], v253, s[82:83]
	global_load_dwordx4 v[132:135], v254, s[82:83] offset:768
	global_load_dwordx4 v[136:139], v255, s[82:83] offset:768
	global_load_dwordx4 v[140:143], v254, s[82:83] offset:832
	global_load_dwordx4 v[144:147], v255, s[82:83] offset:832
	ds_read_b64_tr_b16 v[72:73], v231
	ds_read_b64_tr_b16 v[74:75], v231 offset:512
	ds_read_b64_tr_b16 v[76:77], v231 offset:2048
	ds_read_b64_tr_b16 v[78:79], v231 offset:2560
	ds_read_b64_tr_b16 v[220:221], v231 offset:1024
	ds_read_b64_tr_b16 v[222:223], v231 offset:1536
	ds_read_b64_tr_b16 v[224:225], v231 offset:3072
	ds_read_b64_tr_b16 v[226:227], v231 offset:3584
	v_exp_f32_e32 v32, v32
	v_exp_f32_e32 v33, v33
	s_waitcnt vmcnt(8)
	ds_write_b128 v247, v[156:159]
	ds_write_b128 v247, v[160:163] offset:1024
	ds_write_b128 v247, v[164:167] offset:2048
	ds_write_b128 v247, v[168:171] offset:3072
	ds_read_b128 v[156:159], v248
	ds_read_b128 v[160:163], v249
	ds_read_b128 v[164:167], v250
	ds_read_b128 v[168:171], v251
	ds_write_b128 v112, v[172:175]
	ds_write_b128 v112, v[176:179] offset:1024
	ds_write_b128 v112, v[180:183] offset:2048
	ds_write_b128 v112, v[184:187] offset:3072
	v_exp_f32_e32 v34, v34
	v_exp_f32_e32 v35, v35
	s_waitcnt lgkmcnt(4)
	v_mfma_f32_32x32x16_bf16 v[188:203], v[156:159], v[48:51], v[188:203]
	v_exp_f32_e32 v36, v36
	v_exp_f32_e32 v37, v37
	v_exp_f32_e32 v38, v38
	v_mfma_f32_32x32x16_bf16 v[188:203], v[160:163], v[52:55], v[188:203]
	v_exp_f32_e32 v39, v39
	v_exp_f32_e32 v40, v40
	v_exp_f32_e32 v41, v41
	v_mfma_f32_32x32x16_bf16 v[188:203], v[164:167], v[56:59], v[188:203]
	v_exp_f32_e32 v42, v42
	v_exp_f32_e32 v43, v43
	v_exp_f32_e32 v44, v44
	v_mfma_f32_32x32x16_bf16 v[188:203], v[168:171], v[60:63], v[188:203]
	v_exp_f32_e32 v45, v45
	v_exp_f32_e32 v46, v46
	v_exp_f32_e32 v47, v47
	s_add_i32 s90, s67, 256
	v_add_u32_e32 v84, s90, v107
	v_add_u32_e32 v85, 0, v84
	v_add_u32_e32 v86, 1, v84
	v_add_u32_e32 v87, 2, v84
	v_add_u32_e32 v88, 3, v84
	v_cmp_gt_u32_e64 s[30:31], s98, v85
	v_cmp_gt_u32_e64 s[36:37], s98, v86
	v_cmp_gt_u32_e64 s[78:79], s98, v87
	v_cmp_gt_u32_e64 s[50:51], s98, v88
	v_cndmask_b32_e64 v32, 0, v32, s[30:31]
	v_add_u32_e32 v85, 8, v84
	v_cmp_gt_u32_e64 s[30:31], s98, v85
	v_cndmask_b32_e64 v33, 0, v33, s[36:37]
	v_add_u32_e32 v86, 9, v84
	v_cmp_gt_u32_e64 s[36:37], s98, v86
	v_cndmask_b32_e64 v34, 0, v34, s[78:79]
	v_add_u32_e32 v87, 10, v84
	v_cmp_gt_u32_e64 s[78:79], s98, v87
	v_cndmask_b32_e64 v35, 0, v35, s[50:51]
	v_add_u32_e32 v88, 11, v84
	v_cmp_gt_u32_e64 s[50:51], s98, v88
	v_cndmask_b32_e64 v36, 0, v36, s[30:31]
	v_add_u32_e32 v85, 16, v84
	v_cmp_gt_u32_e64 s[30:31], s98, v85
	v_cndmask_b32_e64 v37, 0, v37, s[36:37]
	v_add_u32_e32 v86, 17, v84
	v_cmp_gt_u32_e64 s[36:37], s98, v86
	v_cndmask_b32_e64 v38, 0, v38, s[78:79]
	v_add_u32_e32 v87, 18, v84
	v_cmp_gt_u32_e64 s[78:79], s98, v87
	v_cndmask_b32_e64 v39, 0, v39, s[50:51]
	v_add_u32_e32 v88, 19, v84
	v_cmp_gt_u32_e64 s[50:51], s98, v88
	v_cndmask_b32_e64 v40, 0, v40, s[30:31]
	v_add_u32_e32 v85, 24, v84
	v_cmp_gt_u32_e64 s[30:31], s98, v85
	v_cndmask_b32_e64 v41, 0, v41, s[36:37]
	v_add_u32_e32 v86, 25, v84
	v_cmp_gt_u32_e64 s[36:37], s98, v86
	v_cndmask_b32_e64 v42, 0, v42, s[78:79]
	v_add_u32_e32 v87, 26, v84
	v_cmp_gt_u32_e64 s[78:79], s98, v87
	v_cndmask_b32_e64 v43, 0, v43, s[50:51]
	v_add_u32_e32 v88, 27, v84
	v_cmp_gt_u32_e64 s[50:51], s98, v88
	v_nop
	v_cndmask_b32_e64 v44, 0, v44, s[30:31]
	v_cndmask_b32_e64 v45, 0, v45, s[36:37]
	v_cndmask_b32_e64 v46, 0, v46, s[78:79]
	v_cndmask_b32_e64 v47, 0, v47, s[50:51]
	v_cvt_pk_bf16_f32 v64, v32, v33
	v_cvt_pk_bf16_f32 v65, v34, v35
	v_cvt_pk_bf16_f32 v66, v36, v37
	v_cvt_pk_bf16_f32 v67, v38, v39
	v_cvt_pk_bf16_f32 v68, v40, v41
	v_cvt_pk_bf16_f32 v69, v42, v43
	v_cvt_pk_bf16_f32 v70, v44, v45
	v_cvt_pk_bf16_f32 v71, v46, v47
	v_pk_add_f32 v[232:233], v[232:233], v[32:33]
	v_pk_add_f32 v[232:233], v[232:233], v[34:35]
	v_pk_add_f32 v[232:233], v[232:233], v[36:37]
	v_pk_add_f32 v[232:233], v[232:233], v[38:39]
	v_pk_add_f32 v[232:233], v[232:233], v[40:41]
	v_pk_add_f32 v[232:233], v[232:233], v[42:43]
	v_pk_add_f32 v[232:233], v[232:233], v[44:45]
	v_pk_add_f32 v[232:233], v[232:233], v[46:47]
	ds_read2_b32 v[32:33], v115 offset0:170 offset1:171
	ds_read2_b32 v[34:35], v115 offset0:172 offset1:173
	ds_read2_b32 v[36:37], v115 offset0:178 offset1:179
	ds_read2_b32 v[38:39], v115 offset0:180 offset1:181
	ds_read2_b32 v[40:41], v115 offset0:187 offset1:188
	ds_read2_b32 v[42:43], v115 offset0:189 offset1:190
	ds_read2_b32 v[44:45], v115 offset0:195 offset1:196
	ds_read2_b32 v[46:47], v115 offset0:197 offset1:198
	v_mfma_f32_32x32x16_bf16 v[0:15], v[64:67], v[72:75], v[0:15]
	v_mfma_f32_32x32x16_bf16 v[16:31], v[64:67], v[76:79], v[16:31]
	v_mfma_f32_32x32x16_bf16 v[0:15], v[68:71], v[220:223], v[0:15]
	v_mfma_f32_32x32x16_bf16 v[16:31], v[68:71], v[224:227], v[16:31]
	s_add_i32 s90, s67, 352
	v_add_u32_e32 v80, s90, v235
	v_add_u32_e32 v83, s90, v236
	v_add_u32_e32 v99, s90, v237
	v_add_u32_e32 v253, s90, v238
	v_add_u32_e32 v254, s90, v100
	v_add_u32_e32 v255, s90, v149
	v_med3_i32 v80, v80, 0, s99
	v_med3_i32 v83, v83, 0, s99
	v_med3_i32 v99, v99, 0, s99
	v_med3_i32 v253, v253, 0, s99
	v_med3_i32 v254, v254, 0, s99
	v_med3_i32 v255, v255, 0, s99
	v_mad_u32_u24 v80, v80, s100, v252
	v_mad_u32_u24 v83, v83, s100, v252
	v_mad_u32_u24 v99, v99, s100, v252
	v_mad_u32_u24 v253, v253, s100, v252
	v_mad_u32_u24 v254, v254, s100, v153
	v_mad_u32_u24 v255, v255, s100, v153
	global_load_dwordx4 v[156:159], v80, s[82:83]
	global_load_dwordx4 v[160:163], v83, s[82:83]
	global_load_dwordx4 v[164:167], v99, s[82:83]
	global_load_dwordx4 v[168:171], v253, s[82:83]
	global_load_dwordx4 v[172:175], v254, s[82:83] offset:768
	global_load_dwordx4 v[176:179], v255, s[82:83] offset:768
	global_load_dwordx4 v[180:183], v254, s[82:83] offset:832
	global_load_dwordx4 v[184:187], v255, s[82:83] offset:832
	ds_read_b64_tr_b16 v[72:73], v231
	ds_read_b64_tr_b16 v[74:75], v231 offset:512
	ds_read_b64_tr_b16 v[76:77], v231 offset:2048
	ds_read_b64_tr_b16 v[78:79], v231 offset:2560
	ds_read_b64_tr_b16 v[220:221], v231 offset:1024
	ds_read_b64_tr_b16 v[222:223], v231 offset:1536
	ds_read_b64_tr_b16 v[224:225], v231 offset:3072
	ds_read_b64_tr_b16 v[226:227], v231 offset:3584
	v_exp_f32_e32 v188, v188
	v_exp_f32_e32 v189, v189
	s_waitcnt vmcnt(8)
	ds_write_b128 v247, v[116:119]
	ds_write_b128 v247, v[120:123] offset:1024
	ds_write_b128 v247, v[124:127] offset:2048
	ds_write_b128 v247, v[128:131] offset:3072
	ds_read_b128 v[116:119], v248
	ds_read_b128 v[120:123], v249
	ds_read_b128 v[124:127], v250
	ds_read_b128 v[128:131], v251
	ds_write_b128 v112, v[132:135]
	ds_write_b128 v112, v[136:139] offset:1024
	ds_write_b128 v112, v[140:143] offset:2048
	ds_write_b128 v112, v[144:147] offset:3072
	v_exp_f32_e32 v190, v190
	v_exp_f32_e32 v191, v191
	s_waitcnt lgkmcnt(4)
	v_mfma_f32_32x32x16_bf16 v[32:47], v[116:119], v[48:51], v[32:47]
	v_exp_f32_e32 v192, v192
	v_exp_f32_e32 v193, v193
	v_exp_f32_e32 v194, v194
	v_mfma_f32_32x32x16_bf16 v[32:47], v[120:123], v[52:55], v[32:47]
	v_exp_f32_e32 v195, v195
	v_exp_f32_e32 v196, v196
	v_exp_f32_e32 v197, v197
	v_mfma_f32_32x32x16_bf16 v[32:47], v[124:127], v[56:59], v[32:47]
	v_exp_f32_e32 v198, v198
	v_exp_f32_e32 v199, v199
	v_exp_f32_e32 v200, v200
	v_mfma_f32_32x32x16_bf16 v[32:47], v[128:131], v[60:63], v[32:47]
	v_exp_f32_e32 v201, v201
	v_exp_f32_e32 v202, v202
	v_exp_f32_e32 v203, v203
	s_add_i32 s90, s67, 288
	v_add_u32_e32 v84, s90, v107
	v_add_u32_e32 v85, 0, v84
	v_add_u32_e32 v86, 1, v84
	v_add_u32_e32 v87, 2, v84
	v_add_u32_e32 v88, 3, v84
	v_cmp_gt_u32_e64 s[30:31], s98, v85
	v_cmp_gt_u32_e64 s[36:37], s98, v86
	v_cmp_gt_u32_e64 s[78:79], s98, v87
	v_cmp_gt_u32_e64 s[50:51], s98, v88
	v_cndmask_b32_e64 v188, 0, v188, s[30:31]
	v_add_u32_e32 v85, 8, v84
	v_cmp_gt_u32_e64 s[30:31], s98, v85
	v_cndmask_b32_e64 v189, 0, v189, s[36:37]
	v_add_u32_e32 v86, 9, v84
	v_cmp_gt_u32_e64 s[36:37], s98, v86
	v_cndmask_b32_e64 v190, 0, v190, s[78:79]
	v_add_u32_e32 v87, 10, v84
	v_cmp_gt_u32_e64 s[78:79], s98, v87
	v_cndmask_b32_e64 v191, 0, v191, s[50:51]
	v_add_u32_e32 v88, 11, v84
	v_cmp_gt_u32_e64 s[50:51], s98, v88
	v_cndmask_b32_e64 v192, 0, v192, s[30:31]
	v_add_u32_e32 v85, 16, v84
	v_cmp_gt_u32_e64 s[30:31], s98, v85
	v_cndmask_b32_e64 v193, 0, v193, s[36:37]
	v_add_u32_e32 v86, 17, v84
	v_cmp_gt_u32_e64 s[36:37], s98, v86
	v_cndmask_b32_e64 v194, 0, v194, s[78:79]
	v_add_u32_e32 v87, 18, v84
	v_cmp_gt_u32_e64 s[78:79], s98, v87
	v_cndmask_b32_e64 v195, 0, v195, s[50:51]
	v_add_u32_e32 v88, 19, v84
	v_cmp_gt_u32_e64 s[50:51], s98, v88
	v_cndmask_b32_e64 v196, 0, v196, s[30:31]
	v_add_u32_e32 v85, 24, v84
	v_cmp_gt_u32_e64 s[30:31], s98, v85
	v_cndmask_b32_e64 v197, 0, v197, s[36:37]
	v_add_u32_e32 v86, 25, v84
	v_cmp_gt_u32_e64 s[36:37], s98, v86
	v_cndmask_b32_e64 v198, 0, v198, s[78:79]
	v_add_u32_e32 v87, 26, v84
	v_cmp_gt_u32_e64 s[78:79], s98, v87
	v_cndmask_b32_e64 v199, 0, v199, s[50:51]
	v_add_u32_e32 v88, 27, v84
	v_cmp_gt_u32_e64 s[50:51], s98, v88
	v_nop
	v_cndmask_b32_e64 v200, 0, v200, s[30:31]
	v_cndmask_b32_e64 v201, 0, v201, s[36:37]
	v_cndmask_b32_e64 v202, 0, v202, s[78:79]
	v_cndmask_b32_e64 v203, 0, v203, s[50:51]
	v_cvt_pk_bf16_f32 v64, v188, v189
	v_cvt_pk_bf16_f32 v65, v190, v191
	v_cvt_pk_bf16_f32 v66, v192, v193
	v_cvt_pk_bf16_f32 v67, v194, v195
	v_cvt_pk_bf16_f32 v68, v196, v197
	v_cvt_pk_bf16_f32 v69, v198, v199
	v_cvt_pk_bf16_f32 v70, v200, v201
	v_cvt_pk_bf16_f32 v71, v202, v203
	v_pk_add_f32 v[232:233], v[232:233], v[188:189]
	v_pk_add_f32 v[232:233], v[232:233], v[190:191]
	v_pk_add_f32 v[232:233], v[232:233], v[192:193]
	v_pk_add_f32 v[232:233], v[232:233], v[194:195]
	v_pk_add_f32 v[232:233], v[232:233], v[196:197]
	v_pk_add_f32 v[232:233], v[232:233], v[198:199]
	v_pk_add_f32 v[232:233], v[232:233], v[200:201]
	v_pk_add_f32 v[232:233], v[232:233], v[202:203]
	ds_read2_b32 v[188:189], v115 offset0:204 offset1:205
	ds_read2_b32 v[190:191], v115 offset0:206 offset1:207
	ds_read2_b32 v[192:193], v115 offset0:212 offset1:213
	ds_read2_b32 v[194:195], v115 offset0:214 offset1:215
	ds_read2_b32 v[196:197], v115 offset0:221 offset1:222
	ds_read2_b32 v[198:199], v115 offset0:223 offset1:224
	ds_read2_b32 v[200:201], v115 offset0:229 offset1:230
	ds_read2_b32 v[202:203], v115 offset0:231 offset1:232
	v_mfma_f32_32x32x16_bf16 v[0:15], v[64:67], v[72:75], v[0:15]
	v_mfma_f32_32x32x16_bf16 v[16:31], v[64:67], v[76:79], v[16:31]
	v_mfma_f32_32x32x16_bf16 v[0:15], v[68:71], v[220:223], v[0:15]
	v_mfma_f32_32x32x16_bf16 v[16:31], v[68:71], v[224:227], v[16:31]
	s_add_i32 s90, s67, 384
	v_add_u32_e32 v80, s90, v235
	v_add_u32_e32 v83, s90, v236
	v_add_u32_e32 v99, s90, v237
	v_add_u32_e32 v253, s90, v238
	v_add_u32_e32 v254, s90, v100
	v_add_u32_e32 v255, s90, v149
	v_med3_i32 v80, v80, 0, s99
	v_med3_i32 v83, v83, 0, s99
	v_med3_i32 v99, v99, 0, s99
	v_med3_i32 v253, v253, 0, s99
	v_med3_i32 v254, v254, 0, s99
	v_med3_i32 v255, v255, 0, s99
	v_mad_u32_u24 v80, v80, s100, v252
	v_mad_u32_u24 v83, v83, s100, v252
	v_mad_u32_u24 v99, v99, s100, v252
	v_mad_u32_u24 v253, v253, s100, v252
	v_mad_u32_u24 v254, v254, s100, v153
	v_mad_u32_u24 v255, v255, s100, v153
	global_load_dwordx4 v[116:119], v80, s[82:83]
	global_load_dwordx4 v[120:123], v83, s[82:83]
	global_load_dwordx4 v[124:127], v99, s[82:83]
	global_load_dwordx4 v[128:131], v253, s[82:83]
	global_load_dwordx4 v[132:135], v254, s[82:83] offset:768
	global_load_dwordx4 v[136:139], v255, s[82:83] offset:768
	global_load_dwordx4 v[140:143], v254, s[82:83] offset:832
	global_load_dwordx4 v[144:147], v255, s[82:83] offset:832
	ds_read_b64_tr_b16 v[72:73], v231
	ds_read_b64_tr_b16 v[74:75], v231 offset:512
	ds_read_b64_tr_b16 v[76:77], v231 offset:2048
	ds_read_b64_tr_b16 v[78:79], v231 offset:2560
	ds_read_b64_tr_b16 v[220:221], v231 offset:1024
	ds_read_b64_tr_b16 v[222:223], v231 offset:1536
	ds_read_b64_tr_b16 v[224:225], v231 offset:3072
	ds_read_b64_tr_b16 v[226:227], v231 offset:3584
	v_exp_f32_e32 v32, v32
	v_exp_f32_e32 v33, v33
	s_waitcnt vmcnt(8)
	ds_write_b128 v247, v[156:159]
	ds_write_b128 v247, v[160:163] offset:1024
	ds_write_b128 v247, v[164:167] offset:2048
	ds_write_b128 v247, v[168:171] offset:3072
	ds_read_b128 v[156:159], v248
	ds_read_b128 v[160:163], v249
	ds_read_b128 v[164:167], v250
	ds_read_b128 v[168:171], v251
	ds_write_b128 v112, v[172:175]
	ds_write_b128 v112, v[176:179] offset:1024
	ds_write_b128 v112, v[180:183] offset:2048
	ds_write_b128 v112, v[184:187] offset:3072
	v_exp_f32_e32 v34, v34
	v_exp_f32_e32 v35, v35
	s_waitcnt lgkmcnt(4)
	v_mfma_f32_32x32x16_bf16 v[188:203], v[156:159], v[48:51], v[188:203]
	v_exp_f32_e32 v36, v36
	v_exp_f32_e32 v37, v37
	v_exp_f32_e32 v38, v38
	v_mfma_f32_32x32x16_bf16 v[188:203], v[160:163], v[52:55], v[188:203]
	v_exp_f32_e32 v39, v39
	v_exp_f32_e32 v40, v40
	v_exp_f32_e32 v41, v41
	v_mfma_f32_32x32x16_bf16 v[188:203], v[164:167], v[56:59], v[188:203]
	v_exp_f32_e32 v42, v42
	v_exp_f32_e32 v43, v43
	v_exp_f32_e32 v44, v44
	v_mfma_f32_32x32x16_bf16 v[188:203], v[168:171], v[60:63], v[188:203]
	v_exp_f32_e32 v45, v45
	v_exp_f32_e32 v46, v46
	v_exp_f32_e32 v47, v47
	s_add_i32 s90, s67, 320
	v_add_u32_e32 v84, s90, v107
	v_add_u32_e32 v85, 0, v84
	v_add_u32_e32 v86, 1, v84
	v_add_u32_e32 v87, 2, v84
	v_add_u32_e32 v88, 3, v84
	v_cmp_gt_u32_e64 s[30:31], s98, v85
	v_cmp_gt_u32_e64 s[36:37], s98, v86
	v_cmp_gt_u32_e64 s[78:79], s98, v87
	v_cmp_gt_u32_e64 s[50:51], s98, v88
	v_cndmask_b32_e64 v32, 0, v32, s[30:31]
	v_add_u32_e32 v85, 8, v84
	v_cmp_gt_u32_e64 s[30:31], s98, v85
	v_cndmask_b32_e64 v33, 0, v33, s[36:37]
	v_add_u32_e32 v86, 9, v84
	v_cmp_gt_u32_e64 s[36:37], s98, v86
	v_cndmask_b32_e64 v34, 0, v34, s[78:79]
	v_add_u32_e32 v87, 10, v84
	v_cmp_gt_u32_e64 s[78:79], s98, v87
	v_cndmask_b32_e64 v35, 0, v35, s[50:51]
	v_add_u32_e32 v88, 11, v84
	v_cmp_gt_u32_e64 s[50:51], s98, v88
	v_cndmask_b32_e64 v36, 0, v36, s[30:31]
	v_add_u32_e32 v85, 16, v84
	v_cmp_gt_u32_e64 s[30:31], s98, v85
	v_cndmask_b32_e64 v37, 0, v37, s[36:37]
	v_add_u32_e32 v86, 17, v84
	v_cmp_gt_u32_e64 s[36:37], s98, v86
	v_cndmask_b32_e64 v38, 0, v38, s[78:79]
	v_add_u32_e32 v87, 18, v84
	v_cmp_gt_u32_e64 s[78:79], s98, v87
	v_cndmask_b32_e64 v39, 0, v39, s[50:51]
	v_add_u32_e32 v88, 19, v84
	v_cmp_gt_u32_e64 s[50:51], s98, v88
	v_cndmask_b32_e64 v40, 0, v40, s[30:31]
	v_add_u32_e32 v85, 24, v84
	v_cmp_gt_u32_e64 s[30:31], s98, v85
	v_cndmask_b32_e64 v41, 0, v41, s[36:37]
	v_add_u32_e32 v86, 25, v84
	v_cmp_gt_u32_e64 s[36:37], s98, v86
	v_cndmask_b32_e64 v42, 0, v42, s[78:79]
	v_add_u32_e32 v87, 26, v84
	v_cmp_gt_u32_e64 s[78:79], s98, v87
	v_cndmask_b32_e64 v43, 0, v43, s[50:51]
	v_add_u32_e32 v88, 27, v84
	v_cmp_gt_u32_e64 s[50:51], s98, v88
	v_nop
	v_cndmask_b32_e64 v44, 0, v44, s[30:31]
	v_cndmask_b32_e64 v45, 0, v45, s[36:37]
	v_cndmask_b32_e64 v46, 0, v46, s[78:79]
	v_cndmask_b32_e64 v47, 0, v47, s[50:51]
	v_cvt_pk_bf16_f32 v64, v32, v33
	v_cvt_pk_bf16_f32 v65, v34, v35
	v_cvt_pk_bf16_f32 v66, v36, v37
	v_cvt_pk_bf16_f32 v67, v38, v39
	v_cvt_pk_bf16_f32 v68, v40, v41
	v_cvt_pk_bf16_f32 v69, v42, v43
	v_cvt_pk_bf16_f32 v70, v44, v45
	v_cvt_pk_bf16_f32 v71, v46, v47
	v_pk_add_f32 v[232:233], v[232:233], v[32:33]
	v_pk_add_f32 v[232:233], v[232:233], v[34:35]
	v_pk_add_f32 v[232:233], v[232:233], v[36:37]
	v_pk_add_f32 v[232:233], v[232:233], v[38:39]
	v_pk_add_f32 v[232:233], v[232:233], v[40:41]
	v_pk_add_f32 v[232:233], v[232:233], v[42:43]
	v_pk_add_f32 v[232:233], v[232:233], v[44:45]
	v_pk_add_f32 v[232:233], v[232:233], v[46:47]
	v_add_u32_e32 v115, 952, v115
	ds_read2_b32 v[32:33], v115 offset0:0 offset1:1
	ds_read2_b32 v[34:35], v115 offset0:2 offset1:3
	ds_read2_b32 v[36:37], v115 offset0:8 offset1:9
	ds_read2_b32 v[38:39], v115 offset0:10 offset1:11
	ds_read2_b32 v[40:41], v115 offset0:17 offset1:18
	ds_read2_b32 v[42:43], v115 offset0:19 offset1:20
	ds_read2_b32 v[44:45], v115 offset0:25 offset1:26
	ds_read2_b32 v[46:47], v115 offset0:27 offset1:28
	v_mfma_f32_32x32x16_bf16 v[0:15], v[64:67], v[72:75], v[0:15]
	v_mfma_f32_32x32x16_bf16 v[16:31], v[64:67], v[76:79], v[16:31]
	v_mfma_f32_32x32x16_bf16 v[0:15], v[68:71], v[220:223], v[0:15]
	v_mfma_f32_32x32x16_bf16 v[16:31], v[68:71], v[224:227], v[16:31]
	s_add_i32 s90, s67, 416
	v_add_u32_e32 v80, s90, v235
	v_add_u32_e32 v83, s90, v236
	v_add_u32_e32 v99, s90, v237
	v_add_u32_e32 v253, s90, v238
	v_add_u32_e32 v254, s90, v100
	v_add_u32_e32 v255, s90, v149
	v_med3_i32 v80, v80, 0, s99
	v_med3_i32 v83, v83, 0, s99
	v_med3_i32 v99, v99, 0, s99
	v_med3_i32 v253, v253, 0, s99
	v_med3_i32 v254, v254, 0, s99
	v_med3_i32 v255, v255, 0, s99
	v_mad_u32_u24 v80, v80, s100, v252
	v_mad_u32_u24 v83, v83, s100, v252
	v_mad_u32_u24 v99, v99, s100, v252
	v_mad_u32_u24 v253, v253, s100, v252
	v_mad_u32_u24 v254, v254, s100, v153
	v_mad_u32_u24 v255, v255, s100, v153
	global_load_dwordx4 v[156:159], v80, s[82:83]
	global_load_dwordx4 v[160:163], v83, s[82:83]
	global_load_dwordx4 v[164:167], v99, s[82:83]
	global_load_dwordx4 v[168:171], v253, s[82:83]
	global_load_dwordx4 v[172:175], v254, s[82:83] offset:768
	global_load_dwordx4 v[176:179], v255, s[82:83] offset:768
	global_load_dwordx4 v[180:183], v254, s[82:83] offset:832
	global_load_dwordx4 v[184:187], v255, s[82:83] offset:832
	ds_read_b64_tr_b16 v[72:73], v231
	ds_read_b64_tr_b16 v[74:75], v231 offset:512
	ds_read_b64_tr_b16 v[76:77], v231 offset:2048
	ds_read_b64_tr_b16 v[78:79], v231 offset:2560
	ds_read_b64_tr_b16 v[220:221], v231 offset:1024
	ds_read_b64_tr_b16 v[222:223], v231 offset:1536
	ds_read_b64_tr_b16 v[224:225], v231 offset:3072
	ds_read_b64_tr_b16 v[226:227], v231 offset:3584
	v_exp_f32_e32 v188, v188
	v_exp_f32_e32 v189, v189
	s_waitcnt vmcnt(8)
	ds_write_b128 v247, v[116:119]
	ds_write_b128 v247, v[120:123] offset:1024
	ds_write_b128 v247, v[124:127] offset:2048
	ds_write_b128 v247, v[128:131] offset:3072
	ds_read_b128 v[116:119], v248
	ds_read_b128 v[120:123], v249
	ds_read_b128 v[124:127], v250
	ds_read_b128 v[128:131], v251
	ds_write_b128 v112, v[132:135]
	ds_write_b128 v112, v[136:139] offset:1024
	ds_write_b128 v112, v[140:143] offset:2048
	ds_write_b128 v112, v[144:147] offset:3072
	v_exp_f32_e32 v190, v190
	v_exp_f32_e32 v191, v191
	s_waitcnt lgkmcnt(4)
	v_mfma_f32_32x32x16_bf16 v[32:47], v[116:119], v[48:51], v[32:47]
	v_exp_f32_e32 v192, v192
	v_exp_f32_e32 v193, v193
	v_exp_f32_e32 v194, v194
	v_mfma_f32_32x32x16_bf16 v[32:47], v[120:123], v[52:55], v[32:47]
	v_exp_f32_e32 v195, v195
	v_exp_f32_e32 v196, v196
	v_exp_f32_e32 v197, v197
	v_mfma_f32_32x32x16_bf16 v[32:47], v[124:127], v[56:59], v[32:47]
	v_exp_f32_e32 v198, v198
	v_exp_f32_e32 v199, v199
	v_exp_f32_e32 v200, v200
	v_mfma_f32_32x32x16_bf16 v[32:47], v[128:131], v[60:63], v[32:47]
	v_exp_f32_e32 v201, v201
	v_exp_f32_e32 v202, v202
	v_exp_f32_e32 v203, v203
	s_add_i32 s90, s67, 352
	v_add_u32_e32 v84, s90, v107
	v_add_u32_e32 v85, 0, v84
	v_add_u32_e32 v86, 1, v84
	v_add_u32_e32 v87, 2, v84
	v_add_u32_e32 v88, 3, v84
	v_cmp_gt_u32_e64 s[30:31], s98, v85
	v_cmp_gt_u32_e64 s[36:37], s98, v86
	v_cmp_gt_u32_e64 s[78:79], s98, v87
	v_cmp_gt_u32_e64 s[50:51], s98, v88
	v_cndmask_b32_e64 v188, 0, v188, s[30:31]
	v_add_u32_e32 v85, 8, v84
	v_cmp_gt_u32_e64 s[30:31], s98, v85
	v_cndmask_b32_e64 v189, 0, v189, s[36:37]
	v_add_u32_e32 v86, 9, v84
	v_cmp_gt_u32_e64 s[36:37], s98, v86
	v_cndmask_b32_e64 v190, 0, v190, s[78:79]
	v_add_u32_e32 v87, 10, v84
	v_cmp_gt_u32_e64 s[78:79], s98, v87
	v_cndmask_b32_e64 v191, 0, v191, s[50:51]
	v_add_u32_e32 v88, 11, v84
	v_cmp_gt_u32_e64 s[50:51], s98, v88
	v_cndmask_b32_e64 v192, 0, v192, s[30:31]
	v_add_u32_e32 v85, 16, v84
	v_cmp_gt_u32_e64 s[30:31], s98, v85
	v_cndmask_b32_e64 v193, 0, v193, s[36:37]
	v_add_u32_e32 v86, 17, v84
	v_cmp_gt_u32_e64 s[36:37], s98, v86
	v_cndmask_b32_e64 v194, 0, v194, s[78:79]
	v_add_u32_e32 v87, 18, v84
	v_cmp_gt_u32_e64 s[78:79], s98, v87
	v_cndmask_b32_e64 v195, 0, v195, s[50:51]
	v_add_u32_e32 v88, 19, v84
	v_cmp_gt_u32_e64 s[50:51], s98, v88
	v_cndmask_b32_e64 v196, 0, v196, s[30:31]
	v_add_u32_e32 v85, 24, v84
	v_cmp_gt_u32_e64 s[30:31], s98, v85
	v_cndmask_b32_e64 v197, 0, v197, s[36:37]
	v_add_u32_e32 v86, 25, v84
	v_cmp_gt_u32_e64 s[36:37], s98, v86
	v_cndmask_b32_e64 v198, 0, v198, s[78:79]
	v_add_u32_e32 v87, 26, v84
	v_cmp_gt_u32_e64 s[78:79], s98, v87
	v_cndmask_b32_e64 v199, 0, v199, s[50:51]
	v_add_u32_e32 v88, 27, v84
	v_cmp_gt_u32_e64 s[50:51], s98, v88
	v_nop
	v_cndmask_b32_e64 v200, 0, v200, s[30:31]
	v_cndmask_b32_e64 v201, 0, v201, s[36:37]
	v_cndmask_b32_e64 v202, 0, v202, s[78:79]
	v_cndmask_b32_e64 v203, 0, v203, s[50:51]
	v_cvt_pk_bf16_f32 v64, v188, v189
	v_cvt_pk_bf16_f32 v65, v190, v191
	v_cvt_pk_bf16_f32 v66, v192, v193
	v_cvt_pk_bf16_f32 v67, v194, v195
	v_cvt_pk_bf16_f32 v68, v196, v197
	v_cvt_pk_bf16_f32 v69, v198, v199
	v_cvt_pk_bf16_f32 v70, v200, v201
	v_cvt_pk_bf16_f32 v71, v202, v203
	v_pk_add_f32 v[232:233], v[232:233], v[188:189]
	v_pk_add_f32 v[232:233], v[232:233], v[190:191]
	v_pk_add_f32 v[232:233], v[232:233], v[192:193]
	v_pk_add_f32 v[232:233], v[232:233], v[194:195]
	v_pk_add_f32 v[232:233], v[232:233], v[196:197]
	v_pk_add_f32 v[232:233], v[232:233], v[198:199]
	v_pk_add_f32 v[232:233], v[232:233], v[200:201]
	v_pk_add_f32 v[232:233], v[232:233], v[202:203]
	ds_read2_b32 v[188:189], v115 offset0:34 offset1:35
	ds_read2_b32 v[190:191], v115 offset0:36 offset1:37
	ds_read2_b32 v[192:193], v115 offset0:42 offset1:43
	ds_read2_b32 v[194:195], v115 offset0:44 offset1:45
	ds_read2_b32 v[196:197], v115 offset0:51 offset1:52
	ds_read2_b32 v[198:199], v115 offset0:53 offset1:54
	ds_read2_b32 v[200:201], v115 offset0:59 offset1:60
	ds_read2_b32 v[202:203], v115 offset0:61 offset1:62
	v_mfma_f32_32x32x16_bf16 v[0:15], v[64:67], v[72:75], v[0:15]
	v_mfma_f32_32x32x16_bf16 v[16:31], v[64:67], v[76:79], v[16:31]
	v_mfma_f32_32x32x16_bf16 v[0:15], v[68:71], v[220:223], v[0:15]
	v_mfma_f32_32x32x16_bf16 v[16:31], v[68:71], v[224:227], v[16:31]
	s_add_i32 s90, s67, 448
	v_add_u32_e32 v80, s90, v235
	v_add_u32_e32 v83, s90, v236
	v_add_u32_e32 v99, s90, v237
	v_add_u32_e32 v253, s90, v238
	v_add_u32_e32 v254, s90, v100
	v_add_u32_e32 v255, s90, v149
	v_med3_i32 v80, v80, 0, s99
	v_med3_i32 v83, v83, 0, s99
	v_med3_i32 v99, v99, 0, s99
	v_med3_i32 v253, v253, 0, s99
	v_med3_i32 v254, v254, 0, s99
	v_med3_i32 v255, v255, 0, s99
	v_mad_u32_u24 v80, v80, s100, v252
	v_mad_u32_u24 v83, v83, s100, v252
	v_mad_u32_u24 v99, v99, s100, v252
	v_mad_u32_u24 v253, v253, s100, v252
	v_mad_u32_u24 v254, v254, s100, v153
	v_mad_u32_u24 v255, v255, s100, v153
	global_load_dwordx4 v[116:119], v80, s[82:83]
	global_load_dwordx4 v[120:123], v83, s[82:83]
	global_load_dwordx4 v[124:127], v99, s[82:83]
	global_load_dwordx4 v[128:131], v253, s[82:83]
	global_load_dwordx4 v[132:135], v254, s[82:83] offset:768
	global_load_dwordx4 v[136:139], v255, s[82:83] offset:768
	global_load_dwordx4 v[140:143], v254, s[82:83] offset:832
	global_load_dwordx4 v[144:147], v255, s[82:83] offset:832
	ds_read_b64_tr_b16 v[72:73], v231
	ds_read_b64_tr_b16 v[74:75], v231 offset:512
	ds_read_b64_tr_b16 v[76:77], v231 offset:2048
	ds_read_b64_tr_b16 v[78:79], v231 offset:2560
	ds_read_b64_tr_b16 v[220:221], v231 offset:1024
	ds_read_b64_tr_b16 v[222:223], v231 offset:1536
	ds_read_b64_tr_b16 v[224:225], v231 offset:3072
	ds_read_b64_tr_b16 v[226:227], v231 offset:3584
	v_exp_f32_e32 v32, v32
	v_exp_f32_e32 v33, v33
	s_waitcnt vmcnt(8)
	ds_write_b128 v247, v[156:159]
	ds_write_b128 v247, v[160:163] offset:1024
	ds_write_b128 v247, v[164:167] offset:2048
	ds_write_b128 v247, v[168:171] offset:3072
	ds_read_b128 v[156:159], v248
	ds_read_b128 v[160:163], v249
	ds_read_b128 v[164:167], v250
	ds_read_b128 v[168:171], v251
	ds_write_b128 v112, v[172:175]
	ds_write_b128 v112, v[176:179] offset:1024
	ds_write_b128 v112, v[180:183] offset:2048
	ds_write_b128 v112, v[184:187] offset:3072
	v_exp_f32_e32 v34, v34
	v_exp_f32_e32 v35, v35
	s_waitcnt lgkmcnt(4)
	v_mfma_f32_32x32x16_bf16 v[188:203], v[156:159], v[48:51], v[188:203]
	v_exp_f32_e32 v36, v36
	v_exp_f32_e32 v37, v37
	v_exp_f32_e32 v38, v38
	v_mfma_f32_32x32x16_bf16 v[188:203], v[160:163], v[52:55], v[188:203]
	v_exp_f32_e32 v39, v39
	v_exp_f32_e32 v40, v40
	v_exp_f32_e32 v41, v41
	v_mfma_f32_32x32x16_bf16 v[188:203], v[164:167], v[56:59], v[188:203]
	v_exp_f32_e32 v42, v42
	v_exp_f32_e32 v43, v43
	v_exp_f32_e32 v44, v44
	v_mfma_f32_32x32x16_bf16 v[188:203], v[168:171], v[60:63], v[188:203]
	v_exp_f32_e32 v45, v45
	v_exp_f32_e32 v46, v46
	v_exp_f32_e32 v47, v47
	s_add_i32 s90, s67, 384
	v_add_u32_e32 v84, s90, v107
	v_add_u32_e32 v85, 0, v84
	v_add_u32_e32 v86, 1, v84
	v_add_u32_e32 v87, 2, v84
	v_add_u32_e32 v88, 3, v84
	v_cmp_gt_u32_e64 s[30:31], s98, v85
	v_cmp_gt_u32_e64 s[36:37], s98, v86
	v_cmp_gt_u32_e64 s[78:79], s98, v87
	v_cmp_gt_u32_e64 s[50:51], s98, v88
	v_cndmask_b32_e64 v32, 0, v32, s[30:31]
	v_add_u32_e32 v85, 8, v84
	v_cmp_gt_u32_e64 s[30:31], s98, v85
	v_cndmask_b32_e64 v33, 0, v33, s[36:37]
	v_add_u32_e32 v86, 9, v84
	v_cmp_gt_u32_e64 s[36:37], s98, v86
	v_cndmask_b32_e64 v34, 0, v34, s[78:79]
	v_add_u32_e32 v87, 10, v84
	v_cmp_gt_u32_e64 s[78:79], s98, v87
	v_cndmask_b32_e64 v35, 0, v35, s[50:51]
	v_add_u32_e32 v88, 11, v84
	v_cmp_gt_u32_e64 s[50:51], s98, v88
	v_cndmask_b32_e64 v36, 0, v36, s[30:31]
	v_add_u32_e32 v85, 16, v84
	v_cmp_gt_u32_e64 s[30:31], s98, v85
	v_cndmask_b32_e64 v37, 0, v37, s[36:37]
	v_add_u32_e32 v86, 17, v84
	v_cmp_gt_u32_e64 s[36:37], s98, v86
	v_cndmask_b32_e64 v38, 0, v38, s[78:79]
	v_add_u32_e32 v87, 18, v84
	v_cmp_gt_u32_e64 s[78:79], s98, v87
	v_cndmask_b32_e64 v39, 0, v39, s[50:51]
	v_add_u32_e32 v88, 19, v84
	v_cmp_gt_u32_e64 s[50:51], s98, v88
	v_cndmask_b32_e64 v40, 0, v40, s[30:31]
	v_add_u32_e32 v85, 24, v84
	v_cmp_gt_u32_e64 s[30:31], s98, v85
	v_cndmask_b32_e64 v41, 0, v41, s[36:37]
	v_add_u32_e32 v86, 25, v84
	v_cmp_gt_u32_e64 s[36:37], s98, v86
	v_cndmask_b32_e64 v42, 0, v42, s[78:79]
	v_add_u32_e32 v87, 26, v84
	v_cmp_gt_u32_e64 s[78:79], s98, v87
	v_cndmask_b32_e64 v43, 0, v43, s[50:51]
	v_add_u32_e32 v88, 27, v84
	v_cmp_gt_u32_e64 s[50:51], s98, v88
	v_nop
	v_cndmask_b32_e64 v44, 0, v44, s[30:31]
	v_cndmask_b32_e64 v45, 0, v45, s[36:37]
	v_cndmask_b32_e64 v46, 0, v46, s[78:79]
	v_cndmask_b32_e64 v47, 0, v47, s[50:51]
	v_cvt_pk_bf16_f32 v64, v32, v33
	v_cvt_pk_bf16_f32 v65, v34, v35
	v_cvt_pk_bf16_f32 v66, v36, v37
	v_cvt_pk_bf16_f32 v67, v38, v39
	v_cvt_pk_bf16_f32 v68, v40, v41
	v_cvt_pk_bf16_f32 v69, v42, v43
	v_cvt_pk_bf16_f32 v70, v44, v45
	v_cvt_pk_bf16_f32 v71, v46, v47
	v_pk_add_f32 v[232:233], v[232:233], v[32:33]
	v_pk_add_f32 v[232:233], v[232:233], v[34:35]
	v_pk_add_f32 v[232:233], v[232:233], v[36:37]
	v_pk_add_f32 v[232:233], v[232:233], v[38:39]
	v_pk_add_f32 v[232:233], v[232:233], v[40:41]
	v_pk_add_f32 v[232:233], v[232:233], v[42:43]
	v_pk_add_f32 v[232:233], v[232:233], v[44:45]
	v_pk_add_f32 v[232:233], v[232:233], v[46:47]
	ds_read2_b32 v[32:33], v115 offset0:68 offset1:69
	ds_read2_b32 v[34:35], v115 offset0:70 offset1:71
	ds_read2_b32 v[36:37], v115 offset0:76 offset1:77
	ds_read2_b32 v[38:39], v115 offset0:78 offset1:79
	ds_read2_b32 v[40:41], v115 offset0:85 offset1:86
	ds_read2_b32 v[42:43], v115 offset0:87 offset1:88
	ds_read2_b32 v[44:45], v115 offset0:93 offset1:94
	ds_read2_b32 v[46:47], v115 offset0:95 offset1:96
	v_mfma_f32_32x32x16_bf16 v[0:15], v[64:67], v[72:75], v[0:15]
	v_mfma_f32_32x32x16_bf16 v[16:31], v[64:67], v[76:79], v[16:31]
	v_mfma_f32_32x32x16_bf16 v[0:15], v[68:71], v[220:223], v[0:15]
	v_mfma_f32_32x32x16_bf16 v[16:31], v[68:71], v[224:227], v[16:31]
	s_add_i32 s90, s67, 480
	v_add_u32_e32 v80, s90, v235
	v_add_u32_e32 v83, s90, v236
	v_add_u32_e32 v99, s90, v237
	v_add_u32_e32 v253, s90, v238
	v_add_u32_e32 v254, s90, v100
	v_add_u32_e32 v255, s90, v149
	v_med3_i32 v80, v80, 0, s99
	v_med3_i32 v83, v83, 0, s99
	v_med3_i32 v99, v99, 0, s99
	v_med3_i32 v253, v253, 0, s99
	v_med3_i32 v254, v254, 0, s99
	v_med3_i32 v255, v255, 0, s99
	v_mad_u32_u24 v80, v80, s100, v252
	v_mad_u32_u24 v83, v83, s100, v252
	v_mad_u32_u24 v99, v99, s100, v252
	v_mad_u32_u24 v253, v253, s100, v252
	v_mad_u32_u24 v254, v254, s100, v153
	v_mad_u32_u24 v255, v255, s100, v153
	global_load_dwordx4 v[156:159], v80, s[82:83]
	global_load_dwordx4 v[160:163], v83, s[82:83]
	global_load_dwordx4 v[164:167], v99, s[82:83]
	global_load_dwordx4 v[168:171], v253, s[82:83]
	global_load_dwordx4 v[172:175], v254, s[82:83] offset:768
	global_load_dwordx4 v[176:179], v255, s[82:83] offset:768
	global_load_dwordx4 v[180:183], v254, s[82:83] offset:832
	global_load_dwordx4 v[184:187], v255, s[82:83] offset:832
	ds_read_b64_tr_b16 v[72:73], v231
	ds_read_b64_tr_b16 v[74:75], v231 offset:512
	ds_read_b64_tr_b16 v[76:77], v231 offset:2048
	ds_read_b64_tr_b16 v[78:79], v231 offset:2560
	ds_read_b64_tr_b16 v[220:221], v231 offset:1024
	ds_read_b64_tr_b16 v[222:223], v231 offset:1536
	ds_read_b64_tr_b16 v[224:225], v231 offset:3072
	ds_read_b64_tr_b16 v[226:227], v231 offset:3584
	v_exp_f32_e32 v188, v188
	v_exp_f32_e32 v189, v189
	s_waitcnt vmcnt(8)
	ds_write_b128 v247, v[116:119]
	ds_write_b128 v247, v[120:123] offset:1024
	ds_write_b128 v247, v[124:127] offset:2048
	ds_write_b128 v247, v[128:131] offset:3072
	ds_read_b128 v[116:119], v248
	ds_read_b128 v[120:123], v249
	ds_read_b128 v[124:127], v250
	ds_read_b128 v[128:131], v251
	ds_write_b128 v112, v[132:135]
	ds_write_b128 v112, v[136:139] offset:1024
	ds_write_b128 v112, v[140:143] offset:2048
	ds_write_b128 v112, v[144:147] offset:3072
	v_exp_f32_e32 v190, v190
	v_exp_f32_e32 v191, v191
	s_waitcnt lgkmcnt(4)
	v_mfma_f32_32x32x16_bf16 v[32:47], v[116:119], v[48:51], v[32:47]
	v_exp_f32_e32 v192, v192
	v_exp_f32_e32 v193, v193
	v_exp_f32_e32 v194, v194
	v_mfma_f32_32x32x16_bf16 v[32:47], v[120:123], v[52:55], v[32:47]
	v_exp_f32_e32 v195, v195
	v_exp_f32_e32 v196, v196
	v_exp_f32_e32 v197, v197
	v_mfma_f32_32x32x16_bf16 v[32:47], v[124:127], v[56:59], v[32:47]
	v_exp_f32_e32 v198, v198
	v_exp_f32_e32 v199, v199
	v_exp_f32_e32 v200, v200
	v_mfma_f32_32x32x16_bf16 v[32:47], v[128:131], v[60:63], v[32:47]
	v_exp_f32_e32 v201, v201
	v_exp_f32_e32 v202, v202
	v_exp_f32_e32 v203, v203
	s_add_i32 s90, s67, 416
	v_add_u32_e32 v84, s90, v107
	v_add_u32_e32 v85, 0, v84
	v_add_u32_e32 v86, 1, v84
	v_add_u32_e32 v87, 2, v84
	v_add_u32_e32 v88, 3, v84
	v_cmp_gt_u32_e64 s[30:31], s98, v85
	v_cmp_gt_u32_e64 s[36:37], s98, v86
	v_cmp_gt_u32_e64 s[78:79], s98, v87
	v_cmp_gt_u32_e64 s[50:51], s98, v88
	v_cndmask_b32_e64 v188, 0, v188, s[30:31]
	v_add_u32_e32 v85, 8, v84
	v_cmp_gt_u32_e64 s[30:31], s98, v85
	v_cndmask_b32_e64 v189, 0, v189, s[36:37]
	v_add_u32_e32 v86, 9, v84
	v_cmp_gt_u32_e64 s[36:37], s98, v86
	v_cndmask_b32_e64 v190, 0, v190, s[78:79]
	v_add_u32_e32 v87, 10, v84
	v_cmp_gt_u32_e64 s[78:79], s98, v87
	v_cndmask_b32_e64 v191, 0, v191, s[50:51]
	v_add_u32_e32 v88, 11, v84
	v_cmp_gt_u32_e64 s[50:51], s98, v88
	v_cndmask_b32_e64 v192, 0, v192, s[30:31]
	v_add_u32_e32 v85, 16, v84
	v_cmp_gt_u32_e64 s[30:31], s98, v85
	v_cndmask_b32_e64 v193, 0, v193, s[36:37]
	v_add_u32_e32 v86, 17, v84
	v_cmp_gt_u32_e64 s[36:37], s98, v86
	v_cndmask_b32_e64 v194, 0, v194, s[78:79]
	v_add_u32_e32 v87, 18, v84
	v_cmp_gt_u32_e64 s[78:79], s98, v87
	v_cndmask_b32_e64 v195, 0, v195, s[50:51]
	v_add_u32_e32 v88, 19, v84
	v_cmp_gt_u32_e64 s[50:51], s98, v88
	v_cndmask_b32_e64 v196, 0, v196, s[30:31]
	v_add_u32_e32 v85, 24, v84
	v_cmp_gt_u32_e64 s[30:31], s98, v85
	v_cndmask_b32_e64 v197, 0, v197, s[36:37]
	v_add_u32_e32 v86, 25, v84
	v_cmp_gt_u32_e64 s[36:37], s98, v86
	v_cndmask_b32_e64 v198, 0, v198, s[78:79]
	v_add_u32_e32 v87, 26, v84
	v_cmp_gt_u32_e64 s[78:79], s98, v87
	v_cndmask_b32_e64 v199, 0, v199, s[50:51]
	v_add_u32_e32 v88, 27, v84
	v_cmp_gt_u32_e64 s[50:51], s98, v88
	v_nop
	v_cndmask_b32_e64 v200, 0, v200, s[30:31]
	v_cndmask_b32_e64 v201, 0, v201, s[36:37]
	v_cndmask_b32_e64 v202, 0, v202, s[78:79]
	v_cndmask_b32_e64 v203, 0, v203, s[50:51]
	v_cvt_pk_bf16_f32 v64, v188, v189
	v_cvt_pk_bf16_f32 v65, v190, v191
	v_cvt_pk_bf16_f32 v66, v192, v193
	v_cvt_pk_bf16_f32 v67, v194, v195
	v_cvt_pk_bf16_f32 v68, v196, v197
	v_cvt_pk_bf16_f32 v69, v198, v199
	v_cvt_pk_bf16_f32 v70, v200, v201
	v_cvt_pk_bf16_f32 v71, v202, v203
	v_pk_add_f32 v[232:233], v[232:233], v[188:189]
	v_pk_add_f32 v[232:233], v[232:233], v[190:191]
	v_pk_add_f32 v[232:233], v[232:233], v[192:193]
	v_pk_add_f32 v[232:233], v[232:233], v[194:195]
	v_pk_add_f32 v[232:233], v[232:233], v[196:197]
	v_pk_add_f32 v[232:233], v[232:233], v[198:199]
	v_pk_add_f32 v[232:233], v[232:233], v[200:201]
	v_pk_add_f32 v[232:233], v[232:233], v[202:203]
	ds_read2_b32 v[188:189], v115 offset0:102 offset1:103
	ds_read2_b32 v[190:191], v115 offset0:104 offset1:105
	ds_read2_b32 v[192:193], v115 offset0:110 offset1:111
	ds_read2_b32 v[194:195], v115 offset0:112 offset1:113
	ds_read2_b32 v[196:197], v115 offset0:119 offset1:120
	ds_read2_b32 v[198:199], v115 offset0:121 offset1:122
	ds_read2_b32 v[200:201], v115 offset0:127 offset1:128
	ds_read2_b32 v[202:203], v115 offset0:129 offset1:130
	v_mfma_f32_32x32x16_bf16 v[0:15], v[64:67], v[72:75], v[0:15]
	v_mfma_f32_32x32x16_bf16 v[16:31], v[64:67], v[76:79], v[16:31]
	v_mfma_f32_32x32x16_bf16 v[0:15], v[68:71], v[220:223], v[0:15]
	v_mfma_f32_32x32x16_bf16 v[16:31], v[68:71], v[224:227], v[16:31]
	s_add_i32 s90, s67, 512
	v_add_u32_e32 v80, s90, v235
	v_add_u32_e32 v83, s90, v236
	v_add_u32_e32 v99, s90, v237
	v_add_u32_e32 v253, s90, v238
	v_add_u32_e32 v254, s90, v100
	v_add_u32_e32 v255, s90, v149
	v_med3_i32 v80, v80, 0, s99
	v_med3_i32 v83, v83, 0, s99
	v_med3_i32 v99, v99, 0, s99
	v_med3_i32 v253, v253, 0, s99
	v_med3_i32 v254, v254, 0, s99
	v_med3_i32 v255, v255, 0, s99
	v_mad_u32_u24 v80, v80, s100, v252
	v_mad_u32_u24 v83, v83, s100, v252
	v_mad_u32_u24 v99, v99, s100, v252
	v_mad_u32_u24 v253, v253, s100, v252
	v_mad_u32_u24 v254, v254, s100, v153
	v_mad_u32_u24 v255, v255, s100, v153
	global_load_dwordx4 v[116:119], v80, s[82:83]
	global_load_dwordx4 v[120:123], v83, s[82:83]
	global_load_dwordx4 v[124:127], v99, s[82:83]
	global_load_dwordx4 v[128:131], v253, s[82:83]
	global_load_dwordx4 v[132:135], v254, s[82:83] offset:768
	global_load_dwordx4 v[136:139], v255, s[82:83] offset:768
	global_load_dwordx4 v[140:143], v254, s[82:83] offset:832
	global_load_dwordx4 v[144:147], v255, s[82:83] offset:832
	ds_read_b64_tr_b16 v[72:73], v231
	ds_read_b64_tr_b16 v[74:75], v231 offset:512
	ds_read_b64_tr_b16 v[76:77], v231 offset:2048
	ds_read_b64_tr_b16 v[78:79], v231 offset:2560
	ds_read_b64_tr_b16 v[220:221], v231 offset:1024
	ds_read_b64_tr_b16 v[222:223], v231 offset:1536
	ds_read_b64_tr_b16 v[224:225], v231 offset:3072
	ds_read_b64_tr_b16 v[226:227], v231 offset:3584
	v_exp_f32_e32 v32, v32
	v_exp_f32_e32 v33, v33
	s_waitcnt vmcnt(8)
	ds_write_b128 v247, v[156:159]
	ds_write_b128 v247, v[160:163] offset:1024
	ds_write_b128 v247, v[164:167] offset:2048
	ds_write_b128 v247, v[168:171] offset:3072
	ds_read_b128 v[156:159], v248
	ds_read_b128 v[160:163], v249
	ds_read_b128 v[164:167], v250
	ds_read_b128 v[168:171], v251
	ds_write_b128 v112, v[172:175]
	ds_write_b128 v112, v[176:179] offset:1024
	ds_write_b128 v112, v[180:183] offset:2048
	ds_write_b128 v112, v[184:187] offset:3072
	v_exp_f32_e32 v34, v34
	v_exp_f32_e32 v35, v35
	s_waitcnt lgkmcnt(4)
	v_mfma_f32_32x32x16_bf16 v[188:203], v[156:159], v[48:51], v[188:203]
	v_exp_f32_e32 v36, v36
	v_exp_f32_e32 v37, v37
	v_exp_f32_e32 v38, v38
	v_mfma_f32_32x32x16_bf16 v[188:203], v[160:163], v[52:55], v[188:203]
	v_exp_f32_e32 v39, v39
	v_exp_f32_e32 v40, v40
	v_exp_f32_e32 v41, v41
	v_mfma_f32_32x32x16_bf16 v[188:203], v[164:167], v[56:59], v[188:203]
	v_exp_f32_e32 v42, v42
	v_exp_f32_e32 v43, v43
	v_exp_f32_e32 v44, v44
	v_mfma_f32_32x32x16_bf16 v[188:203], v[168:171], v[60:63], v[188:203]
	v_exp_f32_e32 v45, v45
	v_exp_f32_e32 v46, v46
	v_exp_f32_e32 v47, v47
	s_add_i32 s90, s67, 448
	v_add_u32_e32 v84, s90, v107
	v_add_u32_e32 v85, 0, v84
	v_add_u32_e32 v86, 1, v84
	v_add_u32_e32 v87, 2, v84
	v_add_u32_e32 v88, 3, v84
	v_cmp_gt_u32_e64 s[30:31], s98, v85
	v_cmp_gt_u32_e64 s[36:37], s98, v86
	v_cmp_gt_u32_e64 s[78:79], s98, v87
	v_cmp_gt_u32_e64 s[50:51], s98, v88
	v_cndmask_b32_e64 v32, 0, v32, s[30:31]
	v_add_u32_e32 v85, 8, v84
	v_cmp_gt_u32_e64 s[30:31], s98, v85
	v_cndmask_b32_e64 v33, 0, v33, s[36:37]
	v_add_u32_e32 v86, 9, v84
	v_cmp_gt_u32_e64 s[36:37], s98, v86
	v_cndmask_b32_e64 v34, 0, v34, s[78:79]
	v_add_u32_e32 v87, 10, v84
	v_cmp_gt_u32_e64 s[78:79], s98, v87
	v_cndmask_b32_e64 v35, 0, v35, s[50:51]
	v_add_u32_e32 v88, 11, v84
	v_cmp_gt_u32_e64 s[50:51], s98, v88
	v_cndmask_b32_e64 v36, 0, v36, s[30:31]
	v_add_u32_e32 v85, 16, v84
	v_cmp_gt_u32_e64 s[30:31], s98, v85
	v_cndmask_b32_e64 v37, 0, v37, s[36:37]
	v_add_u32_e32 v86, 17, v84
	v_cmp_gt_u32_e64 s[36:37], s98, v86
	v_cndmask_b32_e64 v38, 0, v38, s[78:79]
	v_add_u32_e32 v87, 18, v84
	v_cmp_gt_u32_e64 s[78:79], s98, v87
	v_cndmask_b32_e64 v39, 0, v39, s[50:51]
	v_add_u32_e32 v88, 19, v84
	v_cmp_gt_u32_e64 s[50:51], s98, v88
	v_cndmask_b32_e64 v40, 0, v40, s[30:31]
	v_add_u32_e32 v85, 24, v84
	v_cmp_gt_u32_e64 s[30:31], s98, v85
	v_cndmask_b32_e64 v41, 0, v41, s[36:37]
	v_add_u32_e32 v86, 25, v84
	v_cmp_gt_u32_e64 s[36:37], s98, v86
	v_cndmask_b32_e64 v42, 0, v42, s[78:79]
	v_add_u32_e32 v87, 26, v84
	v_cmp_gt_u32_e64 s[78:79], s98, v87
	v_cndmask_b32_e64 v43, 0, v43, s[50:51]
	v_add_u32_e32 v88, 27, v84
	v_cmp_gt_u32_e64 s[50:51], s98, v88
	v_nop
	v_cndmask_b32_e64 v44, 0, v44, s[30:31]
	v_cndmask_b32_e64 v45, 0, v45, s[36:37]
	v_cndmask_b32_e64 v46, 0, v46, s[78:79]
	v_cndmask_b32_e64 v47, 0, v47, s[50:51]
	v_cvt_pk_bf16_f32 v64, v32, v33
	v_cvt_pk_bf16_f32 v65, v34, v35
	v_cvt_pk_bf16_f32 v66, v36, v37
	v_cvt_pk_bf16_f32 v67, v38, v39
	v_cvt_pk_bf16_f32 v68, v40, v41
	v_cvt_pk_bf16_f32 v69, v42, v43
	v_cvt_pk_bf16_f32 v70, v44, v45
	v_cvt_pk_bf16_f32 v71, v46, v47
	v_pk_add_f32 v[232:233], v[232:233], v[32:33]
	v_pk_add_f32 v[232:233], v[232:233], v[34:35]
	v_pk_add_f32 v[232:233], v[232:233], v[36:37]
	v_pk_add_f32 v[232:233], v[232:233], v[38:39]
	v_pk_add_f32 v[232:233], v[232:233], v[40:41]
	v_pk_add_f32 v[232:233], v[232:233], v[42:43]
	v_pk_add_f32 v[232:233], v[232:233], v[44:45]
	v_pk_add_f32 v[232:233], v[232:233], v[46:47]
	ds_read2_b32 v[32:33], v115 offset0:136 offset1:137
	ds_read2_b32 v[34:35], v115 offset0:138 offset1:139
	ds_read2_b32 v[36:37], v115 offset0:144 offset1:145
	ds_read2_b32 v[38:39], v115 offset0:146 offset1:147
	ds_read2_b32 v[40:41], v115 offset0:153 offset1:154
	ds_read2_b32 v[42:43], v115 offset0:155 offset1:156
	ds_read2_b32 v[44:45], v115 offset0:161 offset1:162
	ds_read2_b32 v[46:47], v115 offset0:163 offset1:164
	v_mfma_f32_32x32x16_bf16 v[0:15], v[64:67], v[72:75], v[0:15]
	v_mfma_f32_32x32x16_bf16 v[16:31], v[64:67], v[76:79], v[16:31]
	v_mfma_f32_32x32x16_bf16 v[0:15], v[68:71], v[220:223], v[0:15]
	v_mfma_f32_32x32x16_bf16 v[16:31], v[68:71], v[224:227], v[16:31]
	s_add_i32 s90, s67, 544
	v_add_u32_e32 v80, s90, v235
	v_add_u32_e32 v83, s90, v236
	v_add_u32_e32 v99, s90, v237
	v_add_u32_e32 v253, s90, v238
	v_add_u32_e32 v254, s90, v100
	v_add_u32_e32 v255, s90, v149
	v_med3_i32 v80, v80, 0, s99
	v_med3_i32 v83, v83, 0, s99
	v_med3_i32 v99, v99, 0, s99
	v_med3_i32 v253, v253, 0, s99
	v_med3_i32 v254, v254, 0, s99
	v_med3_i32 v255, v255, 0, s99
	v_mad_u32_u24 v80, v80, s100, v252
	v_mad_u32_u24 v83, v83, s100, v252
	v_mad_u32_u24 v99, v99, s100, v252
	v_mad_u32_u24 v253, v253, s100, v252
	v_mad_u32_u24 v254, v254, s100, v153
	v_mad_u32_u24 v255, v255, s100, v153
	global_load_dwordx4 v[156:159], v80, s[82:83]
	global_load_dwordx4 v[160:163], v83, s[82:83]
	global_load_dwordx4 v[164:167], v99, s[82:83]
	global_load_dwordx4 v[168:171], v253, s[82:83]
	global_load_dwordx4 v[172:175], v254, s[82:83] offset:768
	global_load_dwordx4 v[176:179], v255, s[82:83] offset:768
	global_load_dwordx4 v[180:183], v254, s[82:83] offset:832
	global_load_dwordx4 v[184:187], v255, s[82:83] offset:832
	ds_read_b64_tr_b16 v[72:73], v231
	ds_read_b64_tr_b16 v[74:75], v231 offset:512
	ds_read_b64_tr_b16 v[76:77], v231 offset:2048
	ds_read_b64_tr_b16 v[78:79], v231 offset:2560
	ds_read_b64_tr_b16 v[220:221], v231 offset:1024
	ds_read_b64_tr_b16 v[222:223], v231 offset:1536
	ds_read_b64_tr_b16 v[224:225], v231 offset:3072
	ds_read_b64_tr_b16 v[226:227], v231 offset:3584
	v_exp_f32_e32 v188, v188
	v_exp_f32_e32 v189, v189
	s_waitcnt vmcnt(8)
	ds_write_b128 v247, v[116:119]
	ds_write_b128 v247, v[120:123] offset:1024
	ds_write_b128 v247, v[124:127] offset:2048
	ds_write_b128 v247, v[128:131] offset:3072
	ds_read_b128 v[116:119], v248
	ds_read_b128 v[120:123], v249
	ds_read_b128 v[124:127], v250
	ds_read_b128 v[128:131], v251
	ds_write_b128 v112, v[132:135]
	ds_write_b128 v112, v[136:139] offset:1024
	ds_write_b128 v112, v[140:143] offset:2048
	ds_write_b128 v112, v[144:147] offset:3072
	v_exp_f32_e32 v190, v190
	v_exp_f32_e32 v191, v191
	s_waitcnt lgkmcnt(4)
	v_mfma_f32_32x32x16_bf16 v[32:47], v[116:119], v[48:51], v[32:47]
	v_exp_f32_e32 v192, v192
	v_exp_f32_e32 v193, v193
	v_exp_f32_e32 v194, v194
	v_mfma_f32_32x32x16_bf16 v[32:47], v[120:123], v[52:55], v[32:47]
	v_exp_f32_e32 v195, v195
	v_exp_f32_e32 v196, v196
	v_exp_f32_e32 v197, v197
	v_mfma_f32_32x32x16_bf16 v[32:47], v[124:127], v[56:59], v[32:47]
	v_exp_f32_e32 v198, v198
	v_exp_f32_e32 v199, v199
	v_exp_f32_e32 v200, v200
	v_mfma_f32_32x32x16_bf16 v[32:47], v[128:131], v[60:63], v[32:47]
	v_exp_f32_e32 v201, v201
	v_exp_f32_e32 v202, v202
	v_exp_f32_e32 v203, v203
	s_add_i32 s90, s67, 480
	v_add_u32_e32 v84, s90, v107
	v_add_u32_e32 v85, 0, v84
	v_add_u32_e32 v86, 1, v84
	v_add_u32_e32 v87, 2, v84
	v_add_u32_e32 v88, 3, v84
	v_cmp_gt_u32_e64 s[30:31], s98, v85
	v_cmp_gt_u32_e64 s[36:37], s98, v86
	v_cmp_gt_u32_e64 s[78:79], s98, v87
	v_cmp_gt_u32_e64 s[50:51], s98, v88
	v_cndmask_b32_e64 v188, 0, v188, s[30:31]
	v_add_u32_e32 v85, 8, v84
	v_cmp_gt_u32_e64 s[30:31], s98, v85
	v_cndmask_b32_e64 v189, 0, v189, s[36:37]
	v_add_u32_e32 v86, 9, v84
	v_cmp_gt_u32_e64 s[36:37], s98, v86
	v_cndmask_b32_e64 v190, 0, v190, s[78:79]
	v_add_u32_e32 v87, 10, v84
	v_cmp_gt_u32_e64 s[78:79], s98, v87
	v_cndmask_b32_e64 v191, 0, v191, s[50:51]
	v_add_u32_e32 v88, 11, v84
	v_cmp_gt_u32_e64 s[50:51], s98, v88
	v_cndmask_b32_e64 v192, 0, v192, s[30:31]
	v_add_u32_e32 v85, 16, v84
	v_cmp_gt_u32_e64 s[30:31], s98, v85
	v_cndmask_b32_e64 v193, 0, v193, s[36:37]
	v_add_u32_e32 v86, 17, v84
	v_cmp_gt_u32_e64 s[36:37], s98, v86
	v_cndmask_b32_e64 v194, 0, v194, s[78:79]
	v_add_u32_e32 v87, 18, v84
	v_cmp_gt_u32_e64 s[78:79], s98, v87
	v_cndmask_b32_e64 v195, 0, v195, s[50:51]
	v_add_u32_e32 v88, 19, v84
	v_cmp_gt_u32_e64 s[50:51], s98, v88
	v_cndmask_b32_e64 v196, 0, v196, s[30:31]
	v_add_u32_e32 v85, 24, v84
	v_cmp_gt_u32_e64 s[30:31], s98, v85
	v_cndmask_b32_e64 v197, 0, v197, s[36:37]
	v_add_u32_e32 v86, 25, v84
	v_cmp_gt_u32_e64 s[36:37], s98, v86
	v_cndmask_b32_e64 v198, 0, v198, s[78:79]
	v_add_u32_e32 v87, 26, v84
	v_cmp_gt_u32_e64 s[78:79], s98, v87
	v_cndmask_b32_e64 v199, 0, v199, s[50:51]
	v_add_u32_e32 v88, 27, v84
	v_cmp_gt_u32_e64 s[50:51], s98, v88
	v_nop
	v_cndmask_b32_e64 v200, 0, v200, s[30:31]
	v_cndmask_b32_e64 v201, 0, v201, s[36:37]
	v_cndmask_b32_e64 v202, 0, v202, s[78:79]
	v_cndmask_b32_e64 v203, 0, v203, s[50:51]
	v_cvt_pk_bf16_f32 v64, v188, v189
	v_cvt_pk_bf16_f32 v65, v190, v191
	v_cvt_pk_bf16_f32 v66, v192, v193
	v_cvt_pk_bf16_f32 v67, v194, v195
	v_cvt_pk_bf16_f32 v68, v196, v197
	v_cvt_pk_bf16_f32 v69, v198, v199
	v_cvt_pk_bf16_f32 v70, v200, v201
	v_cvt_pk_bf16_f32 v71, v202, v203
	v_pk_add_f32 v[232:233], v[232:233], v[188:189]
	v_pk_add_f32 v[232:233], v[232:233], v[190:191]
	v_pk_add_f32 v[232:233], v[232:233], v[192:193]
	v_pk_add_f32 v[232:233], v[232:233], v[194:195]
	v_pk_add_f32 v[232:233], v[232:233], v[196:197]
	v_pk_add_f32 v[232:233], v[232:233], v[198:199]
	v_pk_add_f32 v[232:233], v[232:233], v[200:201]
	v_pk_add_f32 v[232:233], v[232:233], v[202:203]
	ds_read2_b32 v[188:189], v115 offset0:170 offset1:171
	ds_read2_b32 v[190:191], v115 offset0:172 offset1:173
	ds_read2_b32 v[192:193], v115 offset0:178 offset1:179
	ds_read2_b32 v[194:195], v115 offset0:180 offset1:181
	ds_read2_b32 v[196:197], v115 offset0:187 offset1:188
	ds_read2_b32 v[198:199], v115 offset0:189 offset1:190
	ds_read2_b32 v[200:201], v115 offset0:195 offset1:196
	ds_read2_b32 v[202:203], v115 offset0:197 offset1:198
	v_mfma_f32_32x32x16_bf16 v[0:15], v[64:67], v[72:75], v[0:15]
	v_mfma_f32_32x32x16_bf16 v[16:31], v[64:67], v[76:79], v[16:31]
	v_mfma_f32_32x32x16_bf16 v[0:15], v[68:71], v[220:223], v[0:15]
	v_mfma_f32_32x32x16_bf16 v[16:31], v[68:71], v[224:227], v[16:31]
	s_add_i32 s90, s67, -256
	v_add_u32_e32 v80, s90, v239
	v_add_u32_e32 v83, s90, v240
	v_add_u32_e32 v99, s90, v241
	v_add_u32_e32 v253, s90, v242
	v_add_u32_e32 v254, s90, v101
	v_add_u32_e32 v255, s90, v150
	v_med3_i32 v80, v80, 0, s99
	v_med3_i32 v83, v83, 0, s99
	v_med3_i32 v99, v99, 0, s99
	v_med3_i32 v253, v253, 0, s99
	v_med3_i32 v254, v254, 0, s99
	v_med3_i32 v255, v255, 0, s99
	v_mad_u32_u24 v80, v80, s100, v252
	v_mad_u32_u24 v83, v83, s100, v252
	v_mad_u32_u24 v99, v99, s100, v252
	v_mad_u32_u24 v253, v253, s100, v252
	v_mad_u32_u24 v254, v254, s100, v153
	v_mad_u32_u24 v255, v255, s100, v153
	global_load_dwordx4 v[116:119], v80, s[82:83]
	global_load_dwordx4 v[120:123], v83, s[82:83]
	global_load_dwordx4 v[124:127], v99, s[82:83]
	global_load_dwordx4 v[128:131], v253, s[82:83]
	global_load_dwordx4 v[132:135], v254, s[82:83] offset:768
	global_load_dwordx4 v[136:139], v255, s[82:83] offset:768
	global_load_dwordx4 v[140:143], v254, s[82:83] offset:832
	global_load_dwordx4 v[144:147], v255, s[82:83] offset:832
	ds_read_b64_tr_b16 v[72:73], v231
	ds_read_b64_tr_b16 v[74:75], v231 offset:512
	ds_read_b64_tr_b16 v[76:77], v231 offset:2048
	ds_read_b64_tr_b16 v[78:79], v231 offset:2560
	ds_read_b64_tr_b16 v[220:221], v231 offset:1024
	ds_read_b64_tr_b16 v[222:223], v231 offset:1536
	ds_read_b64_tr_b16 v[224:225], v231 offset:3072
	ds_read_b64_tr_b16 v[226:227], v231 offset:3584
	v_exp_f32_e32 v32, v32
	v_exp_f32_e32 v33, v33
	s_waitcnt vmcnt(8)
	ds_write_b128 v247, v[156:159]
	ds_write_b128 v247, v[160:163] offset:1024
	ds_write_b128 v247, v[164:167] offset:2048
	ds_write_b128 v247, v[168:171] offset:3072
	ds_read_b128 v[156:159], v248
	ds_read_b128 v[160:163], v249
	ds_read_b128 v[164:167], v250
	ds_read_b128 v[168:171], v251
	ds_write_b128 v112, v[172:175]
	ds_write_b128 v112, v[176:179] offset:1024
	ds_write_b128 v112, v[180:183] offset:2048
	ds_write_b128 v112, v[184:187] offset:3072
	v_exp_f32_e32 v34, v34
	v_exp_f32_e32 v35, v35
	s_waitcnt lgkmcnt(4)
	v_mfma_f32_32x32x16_bf16 v[188:203], v[156:159], v[48:51], v[188:203]
	v_exp_f32_e32 v36, v36
	v_exp_f32_e32 v37, v37
	v_exp_f32_e32 v38, v38
	v_mfma_f32_32x32x16_bf16 v[188:203], v[160:163], v[52:55], v[188:203]
	v_exp_f32_e32 v39, v39
	v_exp_f32_e32 v40, v40
	v_exp_f32_e32 v41, v41
	v_mfma_f32_32x32x16_bf16 v[188:203], v[164:167], v[56:59], v[188:203]
	v_exp_f32_e32 v42, v42
	v_exp_f32_e32 v43, v43
	v_exp_f32_e32 v44, v44
	v_mfma_f32_32x32x16_bf16 v[188:203], v[168:171], v[60:63], v[188:203]
	v_exp_f32_e32 v45, v45
	v_exp_f32_e32 v46, v46
	v_exp_f32_e32 v47, v47
	s_add_i32 s90, s67, 512
	v_add_u32_e32 v84, s90, v107
	v_add_u32_e32 v85, 0, v84
	v_add_u32_e32 v86, 1, v84
	v_add_u32_e32 v87, 2, v84
	v_add_u32_e32 v88, 3, v84
	v_cmp_gt_u32_e64 s[30:31], s98, v85
	v_cmp_gt_u32_e64 s[36:37], s98, v86
	v_cmp_gt_u32_e64 s[78:79], s98, v87
	v_cmp_gt_u32_e64 s[50:51], s98, v88
	v_cndmask_b32_e64 v32, 0, v32, s[30:31]
	v_add_u32_e32 v85, 8, v84
	v_cmp_gt_u32_e64 s[30:31], s98, v85
	v_cndmask_b32_e64 v33, 0, v33, s[36:37]
	v_add_u32_e32 v86, 9, v84
	v_cmp_gt_u32_e64 s[36:37], s98, v86
	v_cndmask_b32_e64 v34, 0, v34, s[78:79]
	v_add_u32_e32 v87, 10, v84
	v_cmp_gt_u32_e64 s[78:79], s98, v87
	v_cndmask_b32_e64 v35, 0, v35, s[50:51]
	v_add_u32_e32 v88, 11, v84
	v_cmp_gt_u32_e64 s[50:51], s98, v88
	v_cndmask_b32_e64 v36, 0, v36, s[30:31]
	v_add_u32_e32 v85, 16, v84
	v_cmp_gt_u32_e64 s[30:31], s98, v85
	v_cndmask_b32_e64 v37, 0, v37, s[36:37]
	v_add_u32_e32 v86, 17, v84
	v_cmp_gt_u32_e64 s[36:37], s98, v86
	v_cndmask_b32_e64 v38, 0, v38, s[78:79]
	v_add_u32_e32 v87, 18, v84
	v_cmp_gt_u32_e64 s[78:79], s98, v87
	v_cndmask_b32_e64 v39, 0, v39, s[50:51]
	v_add_u32_e32 v88, 19, v84
	v_cmp_gt_u32_e64 s[50:51], s98, v88
	v_cndmask_b32_e64 v40, 0, v40, s[30:31]
	v_add_u32_e32 v85, 24, v84
	v_cmp_gt_u32_e64 s[30:31], s98, v85
	v_cndmask_b32_e64 v41, 0, v41, s[36:37]
	v_add_u32_e32 v86, 25, v84
	v_cmp_gt_u32_e64 s[36:37], s98, v86
	v_cndmask_b32_e64 v42, 0, v42, s[78:79]
	v_add_u32_e32 v87, 26, v84
	v_cmp_gt_u32_e64 s[78:79], s98, v87
	v_cndmask_b32_e64 v43, 0, v43, s[50:51]
	v_add_u32_e32 v88, 27, v84
	v_cmp_gt_u32_e64 s[50:51], s98, v88
	v_nop
	v_cndmask_b32_e64 v44, 0, v44, s[30:31]
	v_cndmask_b32_e64 v45, 0, v45, s[36:37]
	v_cndmask_b32_e64 v46, 0, v46, s[78:79]
	v_cndmask_b32_e64 v47, 0, v47, s[50:51]
	v_cvt_pk_bf16_f32 v64, v32, v33
	v_cvt_pk_bf16_f32 v65, v34, v35
	v_cvt_pk_bf16_f32 v66, v36, v37
	v_cvt_pk_bf16_f32 v67, v38, v39
	v_cvt_pk_bf16_f32 v68, v40, v41
	v_cvt_pk_bf16_f32 v69, v42, v43
	v_cvt_pk_bf16_f32 v70, v44, v45
	v_cvt_pk_bf16_f32 v71, v46, v47
	v_pk_add_f32 v[232:233], v[232:233], v[32:33]
	v_pk_add_f32 v[232:233], v[232:233], v[34:35]
	v_pk_add_f32 v[232:233], v[232:233], v[36:37]
	v_pk_add_f32 v[232:233], v[232:233], v[38:39]
	v_pk_add_f32 v[232:233], v[232:233], v[40:41]
	v_pk_add_f32 v[232:233], v[232:233], v[42:43]
	v_pk_add_f32 v[232:233], v[232:233], v[44:45]
	v_pk_add_f32 v[232:233], v[232:233], v[46:47]
	v_mov_b32_e32 v115, v229
	ds_read2_b32 v[32:33], v115 offset0:0 offset1:1
	ds_read2_b32 v[34:35], v115 offset0:2 offset1:3
	ds_read2_b32 v[36:37], v115 offset0:8 offset1:9
	ds_read2_b32 v[38:39], v115 offset0:10 offset1:11
	ds_read2_b32 v[40:41], v115 offset0:16 offset1:17
	ds_read2_b32 v[42:43], v115 offset0:18 offset1:19
	ds_read2_b32 v[44:45], v115 offset0:24 offset1:25
	ds_read2_b32 v[46:47], v115 offset0:26 offset1:27
	v_mfma_f32_32x32x16_bf16 v[0:15], v[64:67], v[72:75], v[0:15]
	v_mfma_f32_32x32x16_bf16 v[16:31], v[64:67], v[76:79], v[16:31]
	v_mfma_f32_32x32x16_bf16 v[0:15], v[68:71], v[220:223], v[0:15]
	v_mfma_f32_32x32x16_bf16 v[16:31], v[68:71], v[224:227], v[16:31]
	s_add_i32 s90, s67, -128
	v_add_u32_e32 v80, s90, v239
	v_add_u32_e32 v83, s90, v240
	v_add_u32_e32 v99, s90, v241
	v_add_u32_e32 v253, s90, v242
	v_add_u32_e32 v254, s90, v101
	v_add_u32_e32 v255, s90, v150
	v_med3_i32 v80, v80, 0, s99
	v_med3_i32 v83, v83, 0, s99
	v_med3_i32 v99, v99, 0, s99
	v_med3_i32 v253, v253, 0, s99
	v_med3_i32 v254, v254, 0, s99
	v_med3_i32 v255, v255, 0, s99
	v_mad_u32_u24 v80, v80, s100, v252
	v_mad_u32_u24 v83, v83, s100, v252
	v_mad_u32_u24 v99, v99, s100, v252
	v_mad_u32_u24 v253, v253, s100, v252
	v_mad_u32_u24 v254, v254, s100, v153
	v_mad_u32_u24 v255, v255, s100, v153
	global_load_dwordx4 v[156:159], v80, s[82:83]
	global_load_dwordx4 v[160:163], v83, s[82:83]
	global_load_dwordx4 v[164:167], v99, s[82:83]
	global_load_dwordx4 v[168:171], v253, s[82:83]
	global_load_dwordx4 v[172:175], v254, s[82:83] offset:768
	global_load_dwordx4 v[176:179], v255, s[82:83] offset:768
	global_load_dwordx4 v[180:183], v254, s[82:83] offset:832
	global_load_dwordx4 v[184:187], v255, s[82:83] offset:832
	ds_read_b64_tr_b16 v[72:73], v231
	ds_read_b64_tr_b16 v[74:75], v231 offset:512
	ds_read_b64_tr_b16 v[76:77], v231 offset:2048
	ds_read_b64_tr_b16 v[78:79], v231 offset:2560
	ds_read_b64_tr_b16 v[220:221], v231 offset:1024
	ds_read_b64_tr_b16 v[222:223], v231 offset:1536
	ds_read_b64_tr_b16 v[224:225], v231 offset:3072
	ds_read_b64_tr_b16 v[226:227], v231 offset:3584
	v_exp_f32_e32 v188, v188
	v_exp_f32_e32 v189, v189
	s_waitcnt vmcnt(8)
	ds_write_b128 v247, v[116:119]
	ds_write_b128 v247, v[120:123] offset:1024
	ds_write_b128 v247, v[124:127] offset:2048
	ds_write_b128 v247, v[128:131] offset:3072
	ds_read_b128 v[116:119], v248
	ds_read_b128 v[120:123], v249
	ds_read_b128 v[124:127], v250
	ds_read_b128 v[128:131], v251
	ds_write_b128 v112, v[132:135]
	ds_write_b128 v112, v[136:139] offset:1024
	ds_write_b128 v112, v[140:143] offset:2048
	ds_write_b128 v112, v[144:147] offset:3072
	v_exp_f32_e32 v190, v190
	v_exp_f32_e32 v191, v191
	s_waitcnt lgkmcnt(4)
	v_mfma_f32_32x32x16_bf16 v[32:47], v[116:119], v[48:51], v[32:47]
	v_exp_f32_e32 v192, v192
	v_exp_f32_e32 v193, v193
	v_exp_f32_e32 v194, v194
	v_mfma_f32_32x32x16_bf16 v[32:47], v[120:123], v[52:55], v[32:47]
	v_exp_f32_e32 v195, v195
	v_exp_f32_e32 v196, v196
	v_exp_f32_e32 v197, v197
	v_mfma_f32_32x32x16_bf16 v[32:47], v[124:127], v[56:59], v[32:47]
	v_exp_f32_e32 v198, v198
	v_exp_f32_e32 v199, v199
	v_exp_f32_e32 v200, v200
	v_mfma_f32_32x32x16_bf16 v[32:47], v[128:131], v[60:63], v[32:47]
	v_exp_f32_e32 v201, v201
	v_exp_f32_e32 v202, v202
	v_exp_f32_e32 v203, v203
	s_add_i32 s90, s67, 544
	v_add_u32_e32 v84, s90, v107
	v_add_u32_e32 v85, 0, v84
	v_add_u32_e32 v86, 1, v84
	v_add_u32_e32 v87, 2, v84
	v_add_u32_e32 v88, 3, v84
	v_cmp_gt_u32_e64 s[30:31], s98, v85
	v_cmp_gt_u32_e64 s[36:37], s98, v86
	v_cmp_gt_u32_e64 s[78:79], s98, v87
	v_cmp_gt_u32_e64 s[50:51], s98, v88
	v_cndmask_b32_e64 v188, 0, v188, s[30:31]
	v_add_u32_e32 v85, 8, v84
	v_cmp_gt_u32_e64 s[30:31], s98, v85
	v_cndmask_b32_e64 v189, 0, v189, s[36:37]
	v_add_u32_e32 v86, 9, v84
	v_cmp_gt_u32_e64 s[36:37], s98, v86
	v_cndmask_b32_e64 v190, 0, v190, s[78:79]
	v_add_u32_e32 v87, 10, v84
	v_cmp_gt_u32_e64 s[78:79], s98, v87
	v_cndmask_b32_e64 v191, 0, v191, s[50:51]
	v_add_u32_e32 v88, 11, v84
	v_cmp_gt_u32_e64 s[50:51], s98, v88
	v_cndmask_b32_e64 v192, 0, v192, s[30:31]
	v_add_u32_e32 v85, 16, v84
	v_cmp_gt_u32_e64 s[30:31], s98, v85
	v_cndmask_b32_e64 v193, 0, v193, s[36:37]
	v_add_u32_e32 v86, 17, v84
	v_cmp_gt_u32_e64 s[36:37], s98, v86
	v_cndmask_b32_e64 v194, 0, v194, s[78:79]
	v_add_u32_e32 v87, 18, v84
	v_cmp_gt_u32_e64 s[78:79], s98, v87
	v_cndmask_b32_e64 v195, 0, v195, s[50:51]
	v_add_u32_e32 v88, 19, v84
	v_cmp_gt_u32_e64 s[50:51], s98, v88
	v_cndmask_b32_e64 v196, 0, v196, s[30:31]
	v_add_u32_e32 v85, 24, v84
	v_cmp_gt_u32_e64 s[30:31], s98, v85
	v_cndmask_b32_e64 v197, 0, v197, s[36:37]
	v_add_u32_e32 v86, 25, v84
	v_cmp_gt_u32_e64 s[36:37], s98, v86
	v_cndmask_b32_e64 v198, 0, v198, s[78:79]
	v_add_u32_e32 v87, 26, v84
	v_cmp_gt_u32_e64 s[78:79], s98, v87
	v_cndmask_b32_e64 v199, 0, v199, s[50:51]
	v_add_u32_e32 v88, 27, v84
	v_cmp_gt_u32_e64 s[50:51], s98, v88
	v_nop
	v_cndmask_b32_e64 v200, 0, v200, s[30:31]
	v_cndmask_b32_e64 v201, 0, v201, s[36:37]
	v_cndmask_b32_e64 v202, 0, v202, s[78:79]
	v_cndmask_b32_e64 v203, 0, v203, s[50:51]
	v_cvt_pk_bf16_f32 v64, v188, v189
	v_cvt_pk_bf16_f32 v65, v190, v191
	v_cvt_pk_bf16_f32 v66, v192, v193
	v_cvt_pk_bf16_f32 v67, v194, v195
	v_cvt_pk_bf16_f32 v68, v196, v197
	v_cvt_pk_bf16_f32 v69, v198, v199
	v_cvt_pk_bf16_f32 v70, v200, v201
	v_cvt_pk_bf16_f32 v71, v202, v203
	v_pk_add_f32 v[232:233], v[232:233], v[188:189]
	v_pk_add_f32 v[232:233], v[232:233], v[190:191]
	v_pk_add_f32 v[232:233], v[232:233], v[192:193]
	v_pk_add_f32 v[232:233], v[232:233], v[194:195]
	v_pk_add_f32 v[232:233], v[232:233], v[196:197]
	v_pk_add_f32 v[232:233], v[232:233], v[198:199]
	v_pk_add_f32 v[232:233], v[232:233], v[200:201]
	v_pk_add_f32 v[232:233], v[232:233], v[202:203]
	ds_read2_b32 v[188:189], v115 offset0:32 offset1:33
	ds_read2_b32 v[190:191], v115 offset0:34 offset1:35
	ds_read2_b32 v[192:193], v115 offset0:40 offset1:41
	ds_read2_b32 v[194:195], v115 offset0:42 offset1:43
	ds_read2_b32 v[196:197], v115 offset0:48 offset1:49
	ds_read2_b32 v[198:199], v115 offset0:50 offset1:51
	ds_read2_b32 v[200:201], v115 offset0:56 offset1:57
	ds_read2_b32 v[202:203], v115 offset0:58 offset1:59
	v_mfma_f32_32x32x16_bf16 v[0:15], v[64:67], v[72:75], v[0:15]
	v_mfma_f32_32x32x16_bf16 v[16:31], v[64:67], v[76:79], v[16:31]
	v_mfma_f32_32x32x16_bf16 v[0:15], v[68:71], v[220:223], v[0:15]
	v_mfma_f32_32x32x16_bf16 v[16:31], v[68:71], v[224:227], v[16:31]
	s_add_i32 s90, s67, 0
	v_add_u32_e32 v80, s90, v239
	v_add_u32_e32 v83, s90, v240
	v_add_u32_e32 v99, s90, v241
	v_add_u32_e32 v253, s90, v242
	v_add_u32_e32 v254, s90, v101
	v_add_u32_e32 v255, s90, v150
	v_med3_i32 v80, v80, 0, s99
	v_med3_i32 v83, v83, 0, s99
	v_med3_i32 v99, v99, 0, s99
	v_med3_i32 v253, v253, 0, s99
	v_med3_i32 v254, v254, 0, s99
	v_med3_i32 v255, v255, 0, s99
	v_mad_u32_u24 v80, v80, s100, v252
	v_mad_u32_u24 v83, v83, s100, v252
	v_mad_u32_u24 v99, v99, s100, v252
	v_mad_u32_u24 v253, v253, s100, v252
	v_mad_u32_u24 v254, v254, s100, v153
	v_mad_u32_u24 v255, v255, s100, v153
	global_load_dwordx4 v[116:119], v80, s[82:83]
	global_load_dwordx4 v[120:123], v83, s[82:83]
	global_load_dwordx4 v[124:127], v99, s[82:83]
	global_load_dwordx4 v[128:131], v253, s[82:83]
	global_load_dwordx4 v[132:135], v254, s[82:83] offset:768
	global_load_dwordx4 v[136:139], v255, s[82:83] offset:768
	global_load_dwordx4 v[140:143], v254, s[82:83] offset:832
	global_load_dwordx4 v[144:147], v255, s[82:83] offset:832
	ds_read_b64_tr_b16 v[72:73], v231
	ds_read_b64_tr_b16 v[74:75], v231 offset:512
	ds_read_b64_tr_b16 v[76:77], v231 offset:2048
	ds_read_b64_tr_b16 v[78:79], v231 offset:2560
	ds_read_b64_tr_b16 v[220:221], v231 offset:1024
	ds_read_b64_tr_b16 v[222:223], v231 offset:1536
	ds_read_b64_tr_b16 v[224:225], v231 offset:3072
	ds_read_b64_tr_b16 v[226:227], v231 offset:3584
	v_exp_f32_e32 v32, v32
	v_exp_f32_e32 v33, v33
	s_waitcnt vmcnt(8)
	ds_write_b128 v247, v[156:159]
	ds_write_b128 v247, v[160:163] offset:1024
	ds_write_b128 v247, v[164:167] offset:2048
	ds_write_b128 v247, v[168:171] offset:3072
	ds_read_b128 v[156:159], v248
	ds_read_b128 v[160:163], v249
	ds_read_b128 v[164:167], v250
	ds_read_b128 v[168:171], v251
	ds_write_b128 v112, v[172:175]
	ds_write_b128 v112, v[176:179] offset:1024
	ds_write_b128 v112, v[180:183] offset:2048
	ds_write_b128 v112, v[184:187] offset:3072
	v_exp_f32_e32 v34, v34
	v_exp_f32_e32 v35, v35
	s_waitcnt lgkmcnt(4)
	v_mfma_f32_32x32x16_bf16 v[188:203], v[156:159], v[48:51], v[188:203]
	v_exp_f32_e32 v36, v36
	v_exp_f32_e32 v37, v37
	v_exp_f32_e32 v38, v38
	v_mfma_f32_32x32x16_bf16 v[188:203], v[160:163], v[52:55], v[188:203]
	v_exp_f32_e32 v39, v39
	v_exp_f32_e32 v40, v40
	v_exp_f32_e32 v41, v41
	v_mfma_f32_32x32x16_bf16 v[188:203], v[164:167], v[56:59], v[188:203]
	v_exp_f32_e32 v42, v42
	v_exp_f32_e32 v43, v43
	v_exp_f32_e32 v44, v44
	v_mfma_f32_32x32x16_bf16 v[188:203], v[168:171], v[60:63], v[188:203]
	v_exp_f32_e32 v45, v45
	v_exp_f32_e32 v46, v46
	v_exp_f32_e32 v47, v47
	s_add_i32 s90, s67, -256
	v_lshlrev_b32_e32 v84, 2, v107
	v_add_u32_e32 v84, s90, v84
	v_add_u32_e32 v85, 0, v84
	v_add_u32_e32 v86, 4, v84
	v_add_u32_e32 v87, 8, v84
	v_add_u32_e32 v88, 12, v84
	v_cmp_gt_u32_e64 s[30:31], s98, v85
	v_cmp_gt_u32_e64 s[36:37], s98, v86
	v_cmp_gt_u32_e64 s[78:79], s98, v87
	v_cmp_gt_u32_e64 s[50:51], s98, v88
	v_cndmask_b32_e64 v32, 0, v32, s[30:31]
	v_add_u32_e32 v85, 32, v84
	v_cmp_gt_u32_e64 s[30:31], s98, v85
	v_cndmask_b32_e64 v33, 0, v33, s[36:37]
	v_add_u32_e32 v86, 36, v84
	v_cmp_gt_u32_e64 s[36:37], s98, v86
	v_cndmask_b32_e64 v34, 0, v34, s[78:79]
	v_add_u32_e32 v87, 40, v84
	v_cmp_gt_u32_e64 s[78:79], s98, v87
	v_cndmask_b32_e64 v35, 0, v35, s[50:51]
	v_add_u32_e32 v88, 44, v84
	v_cmp_gt_u32_e64 s[50:51], s98, v88
	v_cndmask_b32_e64 v36, 0, v36, s[30:31]
	v_add_u32_e32 v85, 64, v84
	v_cmp_gt_u32_e64 s[30:31], s98, v85
	v_cndmask_b32_e64 v37, 0, v37, s[36:37]
	v_add_u32_e32 v86, 68, v84
	v_cmp_gt_u32_e64 s[36:37], s98, v86
	v_cndmask_b32_e64 v38, 0, v38, s[78:79]
	v_add_u32_e32 v87, 72, v84
	v_cmp_gt_u32_e64 s[78:79], s98, v87
	v_cndmask_b32_e64 v39, 0, v39, s[50:51]
	v_add_u32_e32 v88, 76, v84
	v_cmp_gt_u32_e64 s[50:51], s98, v88
	v_cndmask_b32_e64 v40, 0, v40, s[30:31]
	v_add_u32_e32 v85, 96, v84
	v_cmp_gt_u32_e64 s[30:31], s98, v85
	v_cndmask_b32_e64 v41, 0, v41, s[36:37]
	v_add_u32_e32 v86, 100, v84
	v_cmp_gt_u32_e64 s[36:37], s98, v86
	v_cndmask_b32_e64 v42, 0, v42, s[78:79]
	v_add_u32_e32 v87, 104, v84
	v_cmp_gt_u32_e64 s[78:79], s98, v87
	v_cndmask_b32_e64 v43, 0, v43, s[50:51]
	v_add_u32_e32 v88, 108, v84
	v_cmp_gt_u32_e64 s[50:51], s98, v88
	v_nop
	v_cndmask_b32_e64 v44, 0, v44, s[30:31]
	v_cndmask_b32_e64 v45, 0, v45, s[36:37]
	v_cndmask_b32_e64 v46, 0, v46, s[78:79]
	v_cndmask_b32_e64 v47, 0, v47, s[50:51]
	v_cvt_pk_bf16_f32 v64, v32, v33
	v_cvt_pk_bf16_f32 v65, v34, v35
	v_cvt_pk_bf16_f32 v66, v36, v37
	v_cvt_pk_bf16_f32 v67, v38, v39
	v_cvt_pk_bf16_f32 v68, v40, v41
	v_cvt_pk_bf16_f32 v69, v42, v43
	v_cvt_pk_bf16_f32 v70, v44, v45
	v_cvt_pk_bf16_f32 v71, v46, v47
	v_pk_add_f32 v[232:233], v[232:233], v[32:33]
	v_pk_add_f32 v[232:233], v[232:233], v[34:35]
	v_pk_add_f32 v[232:233], v[232:233], v[36:37]
	v_pk_add_f32 v[232:233], v[232:233], v[38:39]
	v_pk_add_f32 v[232:233], v[232:233], v[40:41]
	v_pk_add_f32 v[232:233], v[232:233], v[42:43]
	v_pk_add_f32 v[232:233], v[232:233], v[44:45]
	v_pk_add_f32 v[232:233], v[232:233], v[46:47]
	ds_read2_b32 v[32:33], v115 offset0:64 offset1:65
	ds_read2_b32 v[34:35], v115 offset0:66 offset1:67
	ds_read2_b32 v[36:37], v115 offset0:72 offset1:73
	ds_read2_b32 v[38:39], v115 offset0:74 offset1:75
	ds_read2_b32 v[40:41], v115 offset0:80 offset1:81
	ds_read2_b32 v[42:43], v115 offset0:82 offset1:83
	ds_read2_b32 v[44:45], v115 offset0:88 offset1:89
	ds_read2_b32 v[46:47], v115 offset0:90 offset1:91
	v_mfma_f32_32x32x16_bf16 v[0:15], v[64:67], v[72:75], v[0:15]
	v_mfma_f32_32x32x16_bf16 v[16:31], v[64:67], v[76:79], v[16:31]
	v_mfma_f32_32x32x16_bf16 v[0:15], v[68:71], v[220:223], v[0:15]
	v_mfma_f32_32x32x16_bf16 v[16:31], v[68:71], v[224:227], v[16:31]
	s_add_i32 s90, s67, 128
	v_add_u32_e32 v80, s90, v239
	v_add_u32_e32 v83, s90, v240
	v_add_u32_e32 v99, s90, v241
	v_add_u32_e32 v253, s90, v242
	v_add_u32_e32 v254, s90, v101
	v_add_u32_e32 v255, s90, v150
	v_med3_i32 v80, v80, 0, s99
	v_med3_i32 v83, v83, 0, s99
	v_med3_i32 v99, v99, 0, s99
	v_med3_i32 v253, v253, 0, s99
	v_med3_i32 v254, v254, 0, s99
	v_med3_i32 v255, v255, 0, s99
	v_mad_u32_u24 v80, v80, s100, v252
	v_mad_u32_u24 v83, v83, s100, v252
	v_mad_u32_u24 v99, v99, s100, v252
	v_mad_u32_u24 v253, v253, s100, v252
	v_mad_u32_u24 v254, v254, s100, v153
	v_mad_u32_u24 v255, v255, s100, v153
	global_load_dwordx4 v[156:159], v80, s[82:83]
	global_load_dwordx4 v[160:163], v83, s[82:83]
	global_load_dwordx4 v[164:167], v99, s[82:83]
	global_load_dwordx4 v[168:171], v253, s[82:83]
	global_load_dwordx4 v[172:175], v254, s[82:83] offset:768
	global_load_dwordx4 v[176:179], v255, s[82:83] offset:768
	global_load_dwordx4 v[180:183], v254, s[82:83] offset:832
	global_load_dwordx4 v[184:187], v255, s[82:83] offset:832
	ds_read_b64_tr_b16 v[72:73], v231
	ds_read_b64_tr_b16 v[74:75], v231 offset:512
	ds_read_b64_tr_b16 v[76:77], v231 offset:2048
	ds_read_b64_tr_b16 v[78:79], v231 offset:2560
	ds_read_b64_tr_b16 v[220:221], v231 offset:1024
	ds_read_b64_tr_b16 v[222:223], v231 offset:1536
	ds_read_b64_tr_b16 v[224:225], v231 offset:3072
	ds_read_b64_tr_b16 v[226:227], v231 offset:3584
	v_exp_f32_e32 v188, v188
	v_exp_f32_e32 v189, v189
	s_waitcnt vmcnt(8)
	ds_write_b128 v247, v[116:119]
	ds_write_b128 v247, v[120:123] offset:1024
	ds_write_b128 v247, v[124:127] offset:2048
	ds_write_b128 v247, v[128:131] offset:3072
	ds_read_b128 v[116:119], v248
	ds_read_b128 v[120:123], v249
	ds_read_b128 v[124:127], v250
	ds_read_b128 v[128:131], v251
	ds_write_b128 v112, v[132:135]
	ds_write_b128 v112, v[136:139] offset:1024
	ds_write_b128 v112, v[140:143] offset:2048
	ds_write_b128 v112, v[144:147] offset:3072
	v_exp_f32_e32 v190, v190
	v_exp_f32_e32 v191, v191
	s_waitcnt lgkmcnt(4)
	v_mfma_f32_32x32x16_bf16 v[32:47], v[116:119], v[48:51], v[32:47]
	v_exp_f32_e32 v192, v192
	v_exp_f32_e32 v193, v193
	v_exp_f32_e32 v194, v194
	v_mfma_f32_32x32x16_bf16 v[32:47], v[120:123], v[52:55], v[32:47]
	v_exp_f32_e32 v195, v195
	v_exp_f32_e32 v196, v196
	v_exp_f32_e32 v197, v197
	v_mfma_f32_32x32x16_bf16 v[32:47], v[124:127], v[56:59], v[32:47]
	v_exp_f32_e32 v198, v198
	v_exp_f32_e32 v199, v199
	v_exp_f32_e32 v200, v200
	v_mfma_f32_32x32x16_bf16 v[32:47], v[128:131], v[60:63], v[32:47]
	v_exp_f32_e32 v201, v201
	v_exp_f32_e32 v202, v202
	v_exp_f32_e32 v203, v203
	s_add_i32 s90, s67, -128
	v_lshlrev_b32_e32 v84, 2, v107
	v_add_u32_e32 v84, s90, v84
	v_add_u32_e32 v85, 0, v84
	v_add_u32_e32 v86, 4, v84
	v_add_u32_e32 v87, 8, v84
	v_add_u32_e32 v88, 12, v84
	v_cmp_gt_u32_e64 s[30:31], s98, v85
	v_cmp_gt_u32_e64 s[36:37], s98, v86
	v_cmp_gt_u32_e64 s[78:79], s98, v87
	v_cmp_gt_u32_e64 s[50:51], s98, v88
	v_cndmask_b32_e64 v188, 0, v188, s[30:31]
	v_add_u32_e32 v85, 32, v84
	v_cmp_gt_u32_e64 s[30:31], s98, v85
	v_cndmask_b32_e64 v189, 0, v189, s[36:37]
	v_add_u32_e32 v86, 36, v84
	v_cmp_gt_u32_e64 s[36:37], s98, v86
	v_cndmask_b32_e64 v190, 0, v190, s[78:79]
	v_add_u32_e32 v87, 40, v84
	v_cmp_gt_u32_e64 s[78:79], s98, v87
	v_cndmask_b32_e64 v191, 0, v191, s[50:51]
	v_add_u32_e32 v88, 44, v84
	v_cmp_gt_u32_e64 s[50:51], s98, v88
	v_cndmask_b32_e64 v192, 0, v192, s[30:31]
	v_add_u32_e32 v85, 64, v84
	v_cmp_gt_u32_e64 s[30:31], s98, v85
	v_cndmask_b32_e64 v193, 0, v193, s[36:37]
	v_add_u32_e32 v86, 68, v84
	v_cmp_gt_u32_e64 s[36:37], s98, v86
	v_cndmask_b32_e64 v194, 0, v194, s[78:79]
	v_add_u32_e32 v87, 72, v84
	v_cmp_gt_u32_e64 s[78:79], s98, v87
	v_cndmask_b32_e64 v195, 0, v195, s[50:51]
	v_add_u32_e32 v88, 76, v84
	v_cmp_gt_u32_e64 s[50:51], s98, v88
	v_cndmask_b32_e64 v196, 0, v196, s[30:31]
	v_add_u32_e32 v85, 96, v84
	v_cmp_gt_u32_e64 s[30:31], s98, v85
	v_cndmask_b32_e64 v197, 0, v197, s[36:37]
	v_add_u32_e32 v86, 100, v84
	v_cmp_gt_u32_e64 s[36:37], s98, v86
	v_cndmask_b32_e64 v198, 0, v198, s[78:79]
	v_add_u32_e32 v87, 104, v84
	v_cmp_gt_u32_e64 s[78:79], s98, v87
	v_cndmask_b32_e64 v199, 0, v199, s[50:51]
	v_add_u32_e32 v88, 108, v84
	v_cmp_gt_u32_e64 s[50:51], s98, v88
	v_nop
	v_cndmask_b32_e64 v200, 0, v200, s[30:31]
	v_cndmask_b32_e64 v201, 0, v201, s[36:37]
	v_cndmask_b32_e64 v202, 0, v202, s[78:79]
	v_cndmask_b32_e64 v203, 0, v203, s[50:51]
	v_cvt_pk_bf16_f32 v64, v188, v189
	v_cvt_pk_bf16_f32 v65, v190, v191
	v_cvt_pk_bf16_f32 v66, v192, v193
	v_cvt_pk_bf16_f32 v67, v194, v195
	v_cvt_pk_bf16_f32 v68, v196, v197
	v_cvt_pk_bf16_f32 v69, v198, v199
	v_cvt_pk_bf16_f32 v70, v200, v201
	v_cvt_pk_bf16_f32 v71, v202, v203
	v_pk_add_f32 v[232:233], v[232:233], v[188:189]
	v_pk_add_f32 v[232:233], v[232:233], v[190:191]
	v_pk_add_f32 v[232:233], v[232:233], v[192:193]
	v_pk_add_f32 v[232:233], v[232:233], v[194:195]
	v_pk_add_f32 v[232:233], v[232:233], v[196:197]
	v_pk_add_f32 v[232:233], v[232:233], v[198:199]
	v_pk_add_f32 v[232:233], v[232:233], v[200:201]
	v_pk_add_f32 v[232:233], v[232:233], v[202:203]
	ds_read2_b32 v[188:189], v115 offset0:96 offset1:97
	ds_read2_b32 v[190:191], v115 offset0:98 offset1:99
	ds_read2_b32 v[192:193], v115 offset0:104 offset1:105
	ds_read2_b32 v[194:195], v115 offset0:106 offset1:107
	ds_read2_b32 v[196:197], v115 offset0:112 offset1:113
	ds_read2_b32 v[198:199], v115 offset0:114 offset1:115
	ds_read2_b32 v[200:201], v115 offset0:120 offset1:121
	ds_read2_b32 v[202:203], v115 offset0:122 offset1:123
	v_mfma_f32_32x32x16_bf16 v[0:15], v[64:67], v[72:75], v[0:15]
	v_mfma_f32_32x32x16_bf16 v[16:31], v[64:67], v[76:79], v[16:31]
	v_mfma_f32_32x32x16_bf16 v[0:15], v[68:71], v[220:223], v[0:15]
	v_mfma_f32_32x32x16_bf16 v[16:31], v[68:71], v[224:227], v[16:31]
	s_add_i32 s90, s67, 256
	v_add_u32_e32 v80, s90, v239
	v_add_u32_e32 v83, s90, v240
	v_add_u32_e32 v99, s90, v241
	v_add_u32_e32 v253, s90, v242
	v_add_u32_e32 v254, s90, v101
	v_add_u32_e32 v255, s90, v150
	v_med3_i32 v80, v80, 0, s99
	v_med3_i32 v83, v83, 0, s99
	v_med3_i32 v99, v99, 0, s99
	v_med3_i32 v253, v253, 0, s99
	v_med3_i32 v254, v254, 0, s99
	v_med3_i32 v255, v255, 0, s99
	v_mad_u32_u24 v80, v80, s100, v252
	v_mad_u32_u24 v83, v83, s100, v252
	v_mad_u32_u24 v99, v99, s100, v252
	v_mad_u32_u24 v253, v253, s100, v252
	v_mad_u32_u24 v254, v254, s100, v153
	v_mad_u32_u24 v255, v255, s100, v153
	global_load_dwordx4 v[116:119], v80, s[82:83]
	global_load_dwordx4 v[120:123], v83, s[82:83]
	global_load_dwordx4 v[124:127], v99, s[82:83]
	global_load_dwordx4 v[128:131], v253, s[82:83]
	global_load_dwordx4 v[132:135], v254, s[82:83] offset:768
	global_load_dwordx4 v[136:139], v255, s[82:83] offset:768
	global_load_dwordx4 v[140:143], v254, s[82:83] offset:832
	global_load_dwordx4 v[144:147], v255, s[82:83] offset:832
	ds_read_b64_tr_b16 v[72:73], v231
	ds_read_b64_tr_b16 v[74:75], v231 offset:512
	ds_read_b64_tr_b16 v[76:77], v231 offset:2048
	ds_read_b64_tr_b16 v[78:79], v231 offset:2560
	ds_read_b64_tr_b16 v[220:221], v231 offset:1024
	ds_read_b64_tr_b16 v[222:223], v231 offset:1536
	ds_read_b64_tr_b16 v[224:225], v231 offset:3072
	ds_read_b64_tr_b16 v[226:227], v231 offset:3584
	v_exp_f32_e32 v32, v32
	v_exp_f32_e32 v33, v33
	s_waitcnt vmcnt(8)
	ds_write_b128 v247, v[156:159]
	ds_write_b128 v247, v[160:163] offset:1024
	ds_write_b128 v247, v[164:167] offset:2048
	ds_write_b128 v247, v[168:171] offset:3072
	ds_read_b128 v[156:159], v248
	ds_read_b128 v[160:163], v249
	ds_read_b128 v[164:167], v250
	ds_read_b128 v[168:171], v251
	ds_write_b128 v112, v[172:175]
	ds_write_b128 v112, v[176:179] offset:1024
	ds_write_b128 v112, v[180:183] offset:2048
	ds_write_b128 v112, v[184:187] offset:3072
	v_exp_f32_e32 v34, v34
	v_exp_f32_e32 v35, v35
	s_waitcnt lgkmcnt(4)
	v_mfma_f32_32x32x16_bf16 v[188:203], v[156:159], v[48:51], v[188:203]
	v_exp_f32_e32 v36, v36
	v_exp_f32_e32 v37, v37
	v_exp_f32_e32 v38, v38
	v_mfma_f32_32x32x16_bf16 v[188:203], v[160:163], v[52:55], v[188:203]
	v_exp_f32_e32 v39, v39
	v_exp_f32_e32 v40, v40
	v_exp_f32_e32 v41, v41
	v_mfma_f32_32x32x16_bf16 v[188:203], v[164:167], v[56:59], v[188:203]
	v_exp_f32_e32 v42, v42
	v_exp_f32_e32 v43, v43
	v_exp_f32_e32 v44, v44
	v_mfma_f32_32x32x16_bf16 v[188:203], v[168:171], v[60:63], v[188:203]
	v_exp_f32_e32 v45, v45
	v_exp_f32_e32 v46, v46
	v_exp_f32_e32 v47, v47
	s_add_i32 s90, s67, 0
	v_lshlrev_b32_e32 v84, 2, v107
	v_add_u32_e32 v84, s90, v84
	v_add_u32_e32 v85, 0, v84
	v_add_u32_e32 v86, 4, v84
	v_add_u32_e32 v87, 8, v84
	v_add_u32_e32 v88, 12, v84
	v_cmp_gt_u32_e64 s[30:31], s98, v85
	v_cmp_gt_u32_e64 s[36:37], s98, v86
	v_cmp_gt_u32_e64 s[78:79], s98, v87
	v_cmp_gt_u32_e64 s[50:51], s98, v88
	v_cndmask_b32_e64 v32, 0, v32, s[30:31]
	v_add_u32_e32 v85, 32, v84
	v_cmp_gt_u32_e64 s[30:31], s98, v85
	v_cndmask_b32_e64 v33, 0, v33, s[36:37]
	v_add_u32_e32 v86, 36, v84
	v_cmp_gt_u32_e64 s[36:37], s98, v86
	v_cndmask_b32_e64 v34, 0, v34, s[78:79]
	v_add_u32_e32 v87, 40, v84
	v_cmp_gt_u32_e64 s[78:79], s98, v87
	v_cndmask_b32_e64 v35, 0, v35, s[50:51]
	v_add_u32_e32 v88, 44, v84
	v_cmp_gt_u32_e64 s[50:51], s98, v88
	v_cndmask_b32_e64 v36, 0, v36, s[30:31]
	v_add_u32_e32 v85, 64, v84
	v_cmp_gt_u32_e64 s[30:31], s98, v85
	v_cndmask_b32_e64 v37, 0, v37, s[36:37]
	v_add_u32_e32 v86, 68, v84
	v_cmp_gt_u32_e64 s[36:37], s98, v86
	v_cndmask_b32_e64 v38, 0, v38, s[78:79]
	v_add_u32_e32 v87, 72, v84
	v_cmp_gt_u32_e64 s[78:79], s98, v87
	v_cndmask_b32_e64 v39, 0, v39, s[50:51]
	v_add_u32_e32 v88, 76, v84
	v_cmp_gt_u32_e64 s[50:51], s98, v88
	v_cndmask_b32_e64 v40, 0, v40, s[30:31]
	v_add_u32_e32 v85, 96, v84
	v_cmp_gt_u32_e64 s[30:31], s98, v85
	v_cndmask_b32_e64 v41, 0, v41, s[36:37]
	v_add_u32_e32 v86, 100, v84
	v_cmp_gt_u32_e64 s[36:37], s98, v86
	v_cndmask_b32_e64 v42, 0, v42, s[78:79]
	v_add_u32_e32 v87, 104, v84
	v_cmp_gt_u32_e64 s[78:79], s98, v87
	v_cndmask_b32_e64 v43, 0, v43, s[50:51]
	v_add_u32_e32 v88, 108, v84
	v_cmp_gt_u32_e64 s[50:51], s98, v88
	v_nop
	v_cndmask_b32_e64 v44, 0, v44, s[30:31]
	v_cndmask_b32_e64 v45, 0, v45, s[36:37]
	v_cndmask_b32_e64 v46, 0, v46, s[78:79]
	v_cndmask_b32_e64 v47, 0, v47, s[50:51]
	v_cvt_pk_bf16_f32 v64, v32, v33
	v_cvt_pk_bf16_f32 v65, v34, v35
	v_cvt_pk_bf16_f32 v66, v36, v37
	v_cvt_pk_bf16_f32 v67, v38, v39
	v_cvt_pk_bf16_f32 v68, v40, v41
	v_cvt_pk_bf16_f32 v69, v42, v43
	v_cvt_pk_bf16_f32 v70, v44, v45
	v_cvt_pk_bf16_f32 v71, v46, v47
	v_pk_add_f32 v[232:233], v[232:233], v[32:33]
	v_pk_add_f32 v[232:233], v[232:233], v[34:35]
	v_pk_add_f32 v[232:233], v[232:233], v[36:37]
	v_pk_add_f32 v[232:233], v[232:233], v[38:39]
	v_pk_add_f32 v[232:233], v[232:233], v[40:41]
	v_pk_add_f32 v[232:233], v[232:233], v[42:43]
	v_pk_add_f32 v[232:233], v[232:233], v[44:45]
	v_pk_add_f32 v[232:233], v[232:233], v[46:47]
	ds_read2_b32 v[32:33], v115 offset0:128 offset1:129
	ds_read2_b32 v[34:35], v115 offset0:130 offset1:131
	ds_read2_b32 v[36:37], v115 offset0:136 offset1:137
	ds_read2_b32 v[38:39], v115 offset0:138 offset1:139
	ds_read2_b32 v[40:41], v115 offset0:144 offset1:145
	ds_read2_b32 v[42:43], v115 offset0:146 offset1:147
	ds_read2_b32 v[44:45], v115 offset0:152 offset1:153
	ds_read2_b32 v[46:47], v115 offset0:154 offset1:155
	v_mfma_f32_32x32x16_bf16 v[0:15], v[64:67], v[72:75], v[0:15]
	v_mfma_f32_32x32x16_bf16 v[16:31], v[64:67], v[76:79], v[16:31]
	v_mfma_f32_32x32x16_bf16 v[0:15], v[68:71], v[220:223], v[0:15]
	v_mfma_f32_32x32x16_bf16 v[16:31], v[68:71], v[224:227], v[16:31]
	s_add_i32 s90, s67, 384
	v_add_u32_e32 v80, s90, v239
	v_add_u32_e32 v83, s90, v240
	v_add_u32_e32 v99, s90, v241
	v_add_u32_e32 v253, s90, v242
	v_add_u32_e32 v254, s90, v101
	v_add_u32_e32 v255, s90, v150
	v_med3_i32 v80, v80, 0, s99
	v_med3_i32 v83, v83, 0, s99
	v_med3_i32 v99, v99, 0, s99
	v_med3_i32 v253, v253, 0, s99
	v_med3_i32 v254, v254, 0, s99
	v_med3_i32 v255, v255, 0, s99
	v_mad_u32_u24 v80, v80, s100, v252
	v_mad_u32_u24 v83, v83, s100, v252
	v_mad_u32_u24 v99, v99, s100, v252
	v_mad_u32_u24 v253, v253, s100, v252
	v_mad_u32_u24 v254, v254, s100, v153
	v_mad_u32_u24 v255, v255, s100, v153
	global_load_dwordx4 v[156:159], v80, s[82:83]
	global_load_dwordx4 v[160:163], v83, s[82:83]
	global_load_dwordx4 v[164:167], v99, s[82:83]
	global_load_dwordx4 v[168:171], v253, s[82:83]
	global_load_dwordx4 v[172:175], v254, s[82:83] offset:768
	global_load_dwordx4 v[176:179], v255, s[82:83] offset:768
	global_load_dwordx4 v[180:183], v254, s[82:83] offset:832
	global_load_dwordx4 v[184:187], v255, s[82:83] offset:832
	ds_read_b64_tr_b16 v[72:73], v231
	ds_read_b64_tr_b16 v[74:75], v231 offset:512
	ds_read_b64_tr_b16 v[76:77], v231 offset:2048
	ds_read_b64_tr_b16 v[78:79], v231 offset:2560
	ds_read_b64_tr_b16 v[220:221], v231 offset:1024
	ds_read_b64_tr_b16 v[222:223], v231 offset:1536
	ds_read_b64_tr_b16 v[224:225], v231 offset:3072
	ds_read_b64_tr_b16 v[226:227], v231 offset:3584
	v_exp_f32_e32 v188, v188
	v_exp_f32_e32 v189, v189
	s_waitcnt vmcnt(8)
	ds_write_b128 v247, v[116:119]
	ds_write_b128 v247, v[120:123] offset:1024
	ds_write_b128 v247, v[124:127] offset:2048
	ds_write_b128 v247, v[128:131] offset:3072
	ds_read_b128 v[116:119], v248
	ds_read_b128 v[120:123], v249
	ds_read_b128 v[124:127], v250
	ds_read_b128 v[128:131], v251
	ds_write_b128 v112, v[132:135]
	ds_write_b128 v112, v[136:139] offset:1024
	ds_write_b128 v112, v[140:143] offset:2048
	ds_write_b128 v112, v[144:147] offset:3072
	v_exp_f32_e32 v190, v190
	v_exp_f32_e32 v191, v191
	s_waitcnt lgkmcnt(4)
	v_mfma_f32_32x32x16_bf16 v[32:47], v[116:119], v[48:51], v[32:47]
	v_exp_f32_e32 v192, v192
	v_exp_f32_e32 v193, v193
	v_exp_f32_e32 v194, v194
	v_mfma_f32_32x32x16_bf16 v[32:47], v[120:123], v[52:55], v[32:47]
	v_exp_f32_e32 v195, v195
	v_exp_f32_e32 v196, v196
	v_exp_f32_e32 v197, v197
	v_mfma_f32_32x32x16_bf16 v[32:47], v[124:127], v[56:59], v[32:47]
	v_exp_f32_e32 v198, v198
	v_exp_f32_e32 v199, v199
	v_exp_f32_e32 v200, v200
	v_mfma_f32_32x32x16_bf16 v[32:47], v[128:131], v[60:63], v[32:47]
	v_exp_f32_e32 v201, v201
	v_exp_f32_e32 v202, v202
	v_exp_f32_e32 v203, v203
	s_add_i32 s90, s67, 128
	v_lshlrev_b32_e32 v84, 2, v107
	v_add_u32_e32 v84, s90, v84
	v_add_u32_e32 v85, 0, v84
	v_add_u32_e32 v86, 4, v84
	v_add_u32_e32 v87, 8, v84
	v_add_u32_e32 v88, 12, v84
	v_cmp_gt_u32_e64 s[30:31], s98, v85
	v_cmp_gt_u32_e64 s[36:37], s98, v86
	v_cmp_gt_u32_e64 s[78:79], s98, v87
	v_cmp_gt_u32_e64 s[50:51], s98, v88
	v_cndmask_b32_e64 v188, 0, v188, s[30:31]
	v_add_u32_e32 v85, 32, v84
	v_cmp_gt_u32_e64 s[30:31], s98, v85
	v_cndmask_b32_e64 v189, 0, v189, s[36:37]
	v_add_u32_e32 v86, 36, v84
	v_cmp_gt_u32_e64 s[36:37], s98, v86
	v_cndmask_b32_e64 v190, 0, v190, s[78:79]
	v_add_u32_e32 v87, 40, v84
	v_cmp_gt_u32_e64 s[78:79], s98, v87
	v_cndmask_b32_e64 v191, 0, v191, s[50:51]
	v_add_u32_e32 v88, 44, v84
	v_cmp_gt_u32_e64 s[50:51], s98, v88
	v_cndmask_b32_e64 v192, 0, v192, s[30:31]
	v_add_u32_e32 v85, 64, v84
	v_cmp_gt_u32_e64 s[30:31], s98, v85
	v_cndmask_b32_e64 v193, 0, v193, s[36:37]
	v_add_u32_e32 v86, 68, v84
	v_cmp_gt_u32_e64 s[36:37], s98, v86
	v_cndmask_b32_e64 v194, 0, v194, s[78:79]
	v_add_u32_e32 v87, 72, v84
	v_cmp_gt_u32_e64 s[78:79], s98, v87
	v_cndmask_b32_e64 v195, 0, v195, s[50:51]
	v_add_u32_e32 v88, 76, v84
	v_cmp_gt_u32_e64 s[50:51], s98, v88
	v_cndmask_b32_e64 v196, 0, v196, s[30:31]
	v_add_u32_e32 v85, 96, v84
	v_cmp_gt_u32_e64 s[30:31], s98, v85
	v_cndmask_b32_e64 v197, 0, v197, s[36:37]
	v_add_u32_e32 v86, 100, v84
	v_cmp_gt_u32_e64 s[36:37], s98, v86
	v_cndmask_b32_e64 v198, 0, v198, s[78:79]
	v_add_u32_e32 v87, 104, v84
	v_cmp_gt_u32_e64 s[78:79], s98, v87
	v_cndmask_b32_e64 v199, 0, v199, s[50:51]
	v_add_u32_e32 v88, 108, v84
	v_cmp_gt_u32_e64 s[50:51], s98, v88
	v_nop
	v_cndmask_b32_e64 v200, 0, v200, s[30:31]
	v_cndmask_b32_e64 v201, 0, v201, s[36:37]
	v_cndmask_b32_e64 v202, 0, v202, s[78:79]
	v_cndmask_b32_e64 v203, 0, v203, s[50:51]
	v_cvt_pk_bf16_f32 v64, v188, v189
	v_cvt_pk_bf16_f32 v65, v190, v191
	v_cvt_pk_bf16_f32 v66, v192, v193
	v_cvt_pk_bf16_f32 v67, v194, v195
	v_cvt_pk_bf16_f32 v68, v196, v197
	v_cvt_pk_bf16_f32 v69, v198, v199
	v_cvt_pk_bf16_f32 v70, v200, v201
	v_cvt_pk_bf16_f32 v71, v202, v203
	v_pk_add_f32 v[232:233], v[232:233], v[188:189]
	v_pk_add_f32 v[232:233], v[232:233], v[190:191]
	v_pk_add_f32 v[232:233], v[232:233], v[192:193]
	v_pk_add_f32 v[232:233], v[232:233], v[194:195]
	v_pk_add_f32 v[232:233], v[232:233], v[196:197]
	v_pk_add_f32 v[232:233], v[232:233], v[198:199]
	v_pk_add_f32 v[232:233], v[232:233], v[200:201]
	v_pk_add_f32 v[232:233], v[232:233], v[202:203]
	ds_read2_b32 v[188:189], v115 offset0:160 offset1:161
	ds_read2_b32 v[190:191], v115 offset0:162 offset1:163
	ds_read2_b32 v[192:193], v115 offset0:168 offset1:169
	ds_read2_b32 v[194:195], v115 offset0:170 offset1:171
	ds_read2_b32 v[196:197], v115 offset0:176 offset1:177
	ds_read2_b32 v[198:199], v115 offset0:178 offset1:179
	ds_read2_b32 v[200:201], v115 offset0:184 offset1:185
	ds_read2_b32 v[202:203], v115 offset0:186 offset1:187
	v_mfma_f32_32x32x16_bf16 v[0:15], v[64:67], v[72:75], v[0:15]
	v_mfma_f32_32x32x16_bf16 v[16:31], v[64:67], v[76:79], v[16:31]
	v_mfma_f32_32x32x16_bf16 v[0:15], v[68:71], v[220:223], v[0:15]
	v_mfma_f32_32x32x16_bf16 v[16:31], v[68:71], v[224:227], v[16:31]
	s_add_i32 s90, s67, 512
	v_add_u32_e32 v80, s90, v239
	v_add_u32_e32 v83, s90, v240
	v_add_u32_e32 v99, s90, v241
	v_add_u32_e32 v253, s90, v242
	v_add_u32_e32 v254, s90, v101
	v_add_u32_e32 v255, s90, v150
	v_med3_i32 v80, v80, 0, s99
	v_med3_i32 v83, v83, 0, s99
	v_med3_i32 v99, v99, 0, s99
	v_med3_i32 v253, v253, 0, s99
	v_med3_i32 v254, v254, 0, s99
	v_med3_i32 v255, v255, 0, s99
	v_mad_u32_u24 v80, v80, s100, v252
	v_mad_u32_u24 v83, v83, s100, v252
	v_mad_u32_u24 v99, v99, s100, v252
	v_mad_u32_u24 v253, v253, s100, v252
	v_mad_u32_u24 v254, v254, s100, v153
	v_mad_u32_u24 v255, v255, s100, v153
	global_load_dwordx4 v[116:119], v80, s[82:83]
	global_load_dwordx4 v[120:123], v83, s[82:83]
	global_load_dwordx4 v[124:127], v99, s[82:83]
	global_load_dwordx4 v[128:131], v253, s[82:83]
	global_load_dwordx4 v[132:135], v254, s[82:83] offset:768
	global_load_dwordx4 v[136:139], v255, s[82:83] offset:768
	global_load_dwordx4 v[140:143], v254, s[82:83] offset:832
	global_load_dwordx4 v[144:147], v255, s[82:83] offset:832
	ds_read_b64_tr_b16 v[72:73], v231
	ds_read_b64_tr_b16 v[74:75], v231 offset:512
	ds_read_b64_tr_b16 v[76:77], v231 offset:2048
	ds_read_b64_tr_b16 v[78:79], v231 offset:2560
	ds_read_b64_tr_b16 v[220:221], v231 offset:1024
	ds_read_b64_tr_b16 v[222:223], v231 offset:1536
	ds_read_b64_tr_b16 v[224:225], v231 offset:3072
	ds_read_b64_tr_b16 v[226:227], v231 offset:3584
	v_exp_f32_e32 v32, v32
	v_exp_f32_e32 v33, v33
	s_waitcnt vmcnt(8)
	ds_write_b128 v247, v[156:159]
	ds_write_b128 v247, v[160:163] offset:1024
	ds_write_b128 v247, v[164:167] offset:2048
	ds_write_b128 v247, v[168:171] offset:3072
	ds_read_b128 v[156:159], v248
	ds_read_b128 v[160:163], v249
	ds_read_b128 v[164:167], v250
	ds_read_b128 v[168:171], v251
	ds_write_b128 v112, v[172:175]
	ds_write_b128 v112, v[176:179] offset:1024
	ds_write_b128 v112, v[180:183] offset:2048
	ds_write_b128 v112, v[184:187] offset:3072
	v_exp_f32_e32 v34, v34
	v_exp_f32_e32 v35, v35
	s_waitcnt lgkmcnt(4)
	v_mfma_f32_32x32x16_bf16 v[188:203], v[156:159], v[48:51], v[188:203]
	v_exp_f32_e32 v36, v36
	v_exp_f32_e32 v37, v37
	v_exp_f32_e32 v38, v38
	v_mfma_f32_32x32x16_bf16 v[188:203], v[160:163], v[52:55], v[188:203]
	v_exp_f32_e32 v39, v39
	v_exp_f32_e32 v40, v40
	v_exp_f32_e32 v41, v41
	v_mfma_f32_32x32x16_bf16 v[188:203], v[164:167], v[56:59], v[188:203]
	v_exp_f32_e32 v42, v42
	v_exp_f32_e32 v43, v43
	v_exp_f32_e32 v44, v44
	v_mfma_f32_32x32x16_bf16 v[188:203], v[168:171], v[60:63], v[188:203]
	v_exp_f32_e32 v45, v45
	v_exp_f32_e32 v46, v46
	v_exp_f32_e32 v47, v47
	s_add_i32 s90, s67, 256
	v_lshlrev_b32_e32 v84, 2, v107
	v_add_u32_e32 v84, s90, v84
	v_add_u32_e32 v85, 0, v84
	v_add_u32_e32 v86, 4, v84
	v_add_u32_e32 v87, 8, v84
	v_add_u32_e32 v88, 12, v84
	v_cmp_gt_u32_e64 s[30:31], s98, v85
	v_cmp_gt_u32_e64 s[36:37], s98, v86
	v_cmp_gt_u32_e64 s[78:79], s98, v87
	v_cmp_gt_u32_e64 s[50:51], s98, v88
	v_cndmask_b32_e64 v32, 0, v32, s[30:31]
	v_add_u32_e32 v85, 32, v84
	v_cmp_gt_u32_e64 s[30:31], s98, v85
	v_cndmask_b32_e64 v33, 0, v33, s[36:37]
	v_add_u32_e32 v86, 36, v84
	v_cmp_gt_u32_e64 s[36:37], s98, v86
	v_cndmask_b32_e64 v34, 0, v34, s[78:79]
	v_add_u32_e32 v87, 40, v84
	v_cmp_gt_u32_e64 s[78:79], s98, v87
	v_cndmask_b32_e64 v35, 0, v35, s[50:51]
	v_add_u32_e32 v88, 44, v84
	v_cmp_gt_u32_e64 s[50:51], s98, v88
	v_cndmask_b32_e64 v36, 0, v36, s[30:31]
	v_add_u32_e32 v85, 64, v84
	v_cmp_gt_u32_e64 s[30:31], s98, v85
	v_cndmask_b32_e64 v37, 0, v37, s[36:37]
	v_add_u32_e32 v86, 68, v84
	v_cmp_gt_u32_e64 s[36:37], s98, v86
	v_cndmask_b32_e64 v38, 0, v38, s[78:79]
	v_add_u32_e32 v87, 72, v84
	v_cmp_gt_u32_e64 s[78:79], s98, v87
	v_cndmask_b32_e64 v39, 0, v39, s[50:51]
	v_add_u32_e32 v88, 76, v84
	v_cmp_gt_u32_e64 s[50:51], s98, v88
	v_cndmask_b32_e64 v40, 0, v40, s[30:31]
	v_add_u32_e32 v85, 96, v84
	v_cmp_gt_u32_e64 s[30:31], s98, v85
	v_cndmask_b32_e64 v41, 0, v41, s[36:37]
	v_add_u32_e32 v86, 100, v84
	v_cmp_gt_u32_e64 s[36:37], s98, v86
	v_cndmask_b32_e64 v42, 0, v42, s[78:79]
	v_add_u32_e32 v87, 104, v84
	v_cmp_gt_u32_e64 s[78:79], s98, v87
	v_cndmask_b32_e64 v43, 0, v43, s[50:51]
	v_add_u32_e32 v88, 108, v84
	v_cmp_gt_u32_e64 s[50:51], s98, v88
	v_nop
	v_cndmask_b32_e64 v44, 0, v44, s[30:31]
	v_cndmask_b32_e64 v45, 0, v45, s[36:37]
	v_cndmask_b32_e64 v46, 0, v46, s[78:79]
	v_cndmask_b32_e64 v47, 0, v47, s[50:51]
	v_cvt_pk_bf16_f32 v64, v32, v33
	v_cvt_pk_bf16_f32 v65, v34, v35
	v_cvt_pk_bf16_f32 v66, v36, v37
	v_cvt_pk_bf16_f32 v67, v38, v39
	v_cvt_pk_bf16_f32 v68, v40, v41
	v_cvt_pk_bf16_f32 v69, v42, v43
	v_cvt_pk_bf16_f32 v70, v44, v45
	v_cvt_pk_bf16_f32 v71, v46, v47
	v_pk_add_f32 v[232:233], v[232:233], v[32:33]
	v_pk_add_f32 v[232:233], v[232:233], v[34:35]
	v_pk_add_f32 v[232:233], v[232:233], v[36:37]
	v_pk_add_f32 v[232:233], v[232:233], v[38:39]
	v_pk_add_f32 v[232:233], v[232:233], v[40:41]
	v_pk_add_f32 v[232:233], v[232:233], v[42:43]
	v_pk_add_f32 v[232:233], v[232:233], v[44:45]
	v_pk_add_f32 v[232:233], v[232:233], v[46:47]
	ds_read2_b32 v[32:33], v115 offset0:192 offset1:193
	ds_read2_b32 v[34:35], v115 offset0:194 offset1:195
	ds_read2_b32 v[36:37], v115 offset0:200 offset1:201
	ds_read2_b32 v[38:39], v115 offset0:202 offset1:203
	ds_read2_b32 v[40:41], v115 offset0:208 offset1:209
	ds_read2_b32 v[42:43], v115 offset0:210 offset1:211
	ds_read2_b32 v[44:45], v115 offset0:216 offset1:217
	ds_read2_b32 v[46:47], v115 offset0:218 offset1:219
	v_mfma_f32_32x32x16_bf16 v[0:15], v[64:67], v[72:75], v[0:15]
	v_mfma_f32_32x32x16_bf16 v[16:31], v[64:67], v[76:79], v[16:31]
	v_mfma_f32_32x32x16_bf16 v[0:15], v[68:71], v[220:223], v[0:15]
	v_mfma_f32_32x32x16_bf16 v[16:31], v[68:71], v[224:227], v[16:31]
	s_add_i32 s90, s67, 640
	v_add_u32_e32 v80, s90, v239
	v_add_u32_e32 v83, s90, v240
	v_add_u32_e32 v99, s90, v241
	v_add_u32_e32 v253, s90, v242
	v_add_u32_e32 v254, s90, v101
	v_add_u32_e32 v255, s90, v150
	v_med3_i32 v80, v80, 0, s99
	v_med3_i32 v83, v83, 0, s99
	v_med3_i32 v99, v99, 0, s99
	v_med3_i32 v253, v253, 0, s99
	v_med3_i32 v254, v254, 0, s99
	v_med3_i32 v255, v255, 0, s99
	v_mad_u32_u24 v80, v80, s100, v252
	v_mad_u32_u24 v83, v83, s100, v252
	v_mad_u32_u24 v99, v99, s100, v252
	v_mad_u32_u24 v253, v253, s100, v252
	v_mad_u32_u24 v254, v254, s100, v153
	v_mad_u32_u24 v255, v255, s100, v153
	global_load_dwordx4 v[156:159], v80, s[82:83]
	global_load_dwordx4 v[160:163], v83, s[82:83]
	global_load_dwordx4 v[164:167], v99, s[82:83]
	global_load_dwordx4 v[168:171], v253, s[82:83]
	global_load_dwordx4 v[172:175], v254, s[82:83] offset:768
	global_load_dwordx4 v[176:179], v255, s[82:83] offset:768
	global_load_dwordx4 v[180:183], v254, s[82:83] offset:832
	global_load_dwordx4 v[184:187], v255, s[82:83] offset:832
	ds_read_b64_tr_b16 v[72:73], v231
	ds_read_b64_tr_b16 v[74:75], v231 offset:512
	ds_read_b64_tr_b16 v[76:77], v231 offset:2048
	ds_read_b64_tr_b16 v[78:79], v231 offset:2560
	ds_read_b64_tr_b16 v[220:221], v231 offset:1024
	ds_read_b64_tr_b16 v[222:223], v231 offset:1536
	ds_read_b64_tr_b16 v[224:225], v231 offset:3072
	ds_read_b64_tr_b16 v[226:227], v231 offset:3584
	v_exp_f32_e32 v188, v188
	v_exp_f32_e32 v189, v189
	s_waitcnt vmcnt(8)
	ds_write_b128 v247, v[116:119]
	ds_write_b128 v247, v[120:123] offset:1024
	ds_write_b128 v247, v[124:127] offset:2048
	ds_write_b128 v247, v[128:131] offset:3072
	ds_read_b128 v[116:119], v248
	ds_read_b128 v[120:123], v249
	ds_read_b128 v[124:127], v250
	ds_read_b128 v[128:131], v251
	ds_write_b128 v112, v[132:135]
	ds_write_b128 v112, v[136:139] offset:1024
	ds_write_b128 v112, v[140:143] offset:2048
	ds_write_b128 v112, v[144:147] offset:3072
	v_exp_f32_e32 v190, v190
	v_exp_f32_e32 v191, v191
	s_waitcnt lgkmcnt(4)
	v_mfma_f32_32x32x16_bf16 v[32:47], v[116:119], v[48:51], v[32:47]
	v_exp_f32_e32 v192, v192
	v_exp_f32_e32 v193, v193
	v_exp_f32_e32 v194, v194
	v_mfma_f32_32x32x16_bf16 v[32:47], v[120:123], v[52:55], v[32:47]
	v_exp_f32_e32 v195, v195
	v_exp_f32_e32 v196, v196
	v_exp_f32_e32 v197, v197
	v_mfma_f32_32x32x16_bf16 v[32:47], v[124:127], v[56:59], v[32:47]
	v_exp_f32_e32 v198, v198
	v_exp_f32_e32 v199, v199
	v_exp_f32_e32 v200, v200
	v_mfma_f32_32x32x16_bf16 v[32:47], v[128:131], v[60:63], v[32:47]
	v_exp_f32_e32 v201, v201
	v_exp_f32_e32 v202, v202
	v_exp_f32_e32 v203, v203
	s_add_i32 s90, s67, 384
	v_lshlrev_b32_e32 v84, 2, v107
	v_add_u32_e32 v84, s90, v84
	v_add_u32_e32 v85, 0, v84
	v_add_u32_e32 v86, 4, v84
	v_add_u32_e32 v87, 8, v84
	v_add_u32_e32 v88, 12, v84
	v_cmp_gt_u32_e64 s[30:31], s98, v85
	v_cmp_gt_u32_e64 s[36:37], s98, v86
	v_cmp_gt_u32_e64 s[78:79], s98, v87
	v_cmp_gt_u32_e64 s[50:51], s98, v88
	v_cndmask_b32_e64 v188, 0, v188, s[30:31]
	v_add_u32_e32 v85, 32, v84
	v_cmp_gt_u32_e64 s[30:31], s98, v85
	v_cndmask_b32_e64 v189, 0, v189, s[36:37]
	v_add_u32_e32 v86, 36, v84
	v_cmp_gt_u32_e64 s[36:37], s98, v86
	v_cndmask_b32_e64 v190, 0, v190, s[78:79]
	v_add_u32_e32 v87, 40, v84
	v_cmp_gt_u32_e64 s[78:79], s98, v87
	v_cndmask_b32_e64 v191, 0, v191, s[50:51]
	v_add_u32_e32 v88, 44, v84
	v_cmp_gt_u32_e64 s[50:51], s98, v88
	v_cndmask_b32_e64 v192, 0, v192, s[30:31]
	v_add_u32_e32 v85, 64, v84
	v_cmp_gt_u32_e64 s[30:31], s98, v85
	v_cndmask_b32_e64 v193, 0, v193, s[36:37]
	v_add_u32_e32 v86, 68, v84
	v_cmp_gt_u32_e64 s[36:37], s98, v86
	v_cndmask_b32_e64 v194, 0, v194, s[78:79]
	v_add_u32_e32 v87, 72, v84
	v_cmp_gt_u32_e64 s[78:79], s98, v87
	v_cndmask_b32_e64 v195, 0, v195, s[50:51]
	v_add_u32_e32 v88, 76, v84
	v_cmp_gt_u32_e64 s[50:51], s98, v88
	v_cndmask_b32_e64 v196, 0, v196, s[30:31]
	v_add_u32_e32 v85, 96, v84
	v_cmp_gt_u32_e64 s[30:31], s98, v85
	v_cndmask_b32_e64 v197, 0, v197, s[36:37]
	v_add_u32_e32 v86, 100, v84
	v_cmp_gt_u32_e64 s[36:37], s98, v86
	v_cndmask_b32_e64 v198, 0, v198, s[78:79]
	v_add_u32_e32 v87, 104, v84
	v_cmp_gt_u32_e64 s[78:79], s98, v87
	v_cndmask_b32_e64 v199, 0, v199, s[50:51]
	v_add_u32_e32 v88, 108, v84
	v_cmp_gt_u32_e64 s[50:51], s98, v88
	v_nop
	v_cndmask_b32_e64 v200, 0, v200, s[30:31]
	v_cndmask_b32_e64 v201, 0, v201, s[36:37]
	v_cndmask_b32_e64 v202, 0, v202, s[78:79]
	v_cndmask_b32_e64 v203, 0, v203, s[50:51]
	v_cvt_pk_bf16_f32 v64, v188, v189
	v_cvt_pk_bf16_f32 v65, v190, v191
	v_cvt_pk_bf16_f32 v66, v192, v193
	v_cvt_pk_bf16_f32 v67, v194, v195
	v_cvt_pk_bf16_f32 v68, v196, v197
	v_cvt_pk_bf16_f32 v69, v198, v199
	v_cvt_pk_bf16_f32 v70, v200, v201
	v_cvt_pk_bf16_f32 v71, v202, v203
	v_pk_add_f32 v[232:233], v[232:233], v[188:189]
	v_pk_add_f32 v[232:233], v[232:233], v[190:191]
	v_pk_add_f32 v[232:233], v[232:233], v[192:193]
	v_pk_add_f32 v[232:233], v[232:233], v[194:195]
	v_pk_add_f32 v[232:233], v[232:233], v[196:197]
	v_pk_add_f32 v[232:233], v[232:233], v[198:199]
	v_pk_add_f32 v[232:233], v[232:233], v[200:201]
	v_pk_add_f32 v[232:233], v[232:233], v[202:203]
	ds_read2_b32 v[188:189], v115 offset0:224 offset1:225
	ds_read2_b32 v[190:191], v115 offset0:226 offset1:227
	ds_read2_b32 v[192:193], v115 offset0:232 offset1:233
	ds_read2_b32 v[194:195], v115 offset0:234 offset1:235
	ds_read2_b32 v[196:197], v115 offset0:240 offset1:241
	ds_read2_b32 v[198:199], v115 offset0:242 offset1:243
	ds_read2_b32 v[200:201], v115 offset0:248 offset1:249
	ds_read2_b32 v[202:203], v115 offset0:250 offset1:251
	v_mfma_f32_32x32x16_bf16 v[0:15], v[64:67], v[72:75], v[0:15]
	v_mfma_f32_32x32x16_bf16 v[16:31], v[64:67], v[76:79], v[16:31]
	v_mfma_f32_32x32x16_bf16 v[0:15], v[68:71], v[220:223], v[0:15]
	v_mfma_f32_32x32x16_bf16 v[16:31], v[68:71], v[224:227], v[16:31]
	s_add_i32 s90, s67, -1024
	v_add_u32_e32 v80, s90, v243
	v_add_u32_e32 v83, s90, v244
	v_add_u32_e32 v99, s90, v245
	v_add_u32_e32 v253, s90, v246
	v_add_u32_e32 v254, s90, v148
	v_add_u32_e32 v255, s90, v151
	v_med3_i32 v80, v80, 0, s99
	v_med3_i32 v83, v83, 0, s99
	v_med3_i32 v99, v99, 0, s99
	v_med3_i32 v253, v253, 0, s99
	v_med3_i32 v254, v254, 0, s99
	v_med3_i32 v255, v255, 0, s99
	v_mad_u32_u24 v80, v80, s100, v252
	v_mad_u32_u24 v83, v83, s100, v252
	v_mad_u32_u24 v99, v99, s100, v252
	v_mad_u32_u24 v253, v253, s100, v252
	v_mad_u32_u24 v254, v254, s100, v153
	v_mad_u32_u24 v255, v255, s100, v153
	global_load_dwordx4 v[116:119], v80, s[82:83]
	global_load_dwordx4 v[120:123], v83, s[82:83]
	global_load_dwordx4 v[124:127], v99, s[82:83]
	global_load_dwordx4 v[128:131], v253, s[82:83]
	global_load_dwordx4 v[132:135], v254, s[82:83] offset:768
	global_load_dwordx4 v[136:139], v255, s[82:83] offset:768
	global_load_dwordx4 v[140:143], v254, s[82:83] offset:832
	global_load_dwordx4 v[144:147], v255, s[82:83] offset:832
	ds_read_b64_tr_b16 v[72:73], v231
	ds_read_b64_tr_b16 v[74:75], v231 offset:512
	ds_read_b64_tr_b16 v[76:77], v231 offset:2048
	ds_read_b64_tr_b16 v[78:79], v231 offset:2560
	ds_read_b64_tr_b16 v[220:221], v231 offset:1024
	ds_read_b64_tr_b16 v[222:223], v231 offset:1536
	ds_read_b64_tr_b16 v[224:225], v231 offset:3072
	ds_read_b64_tr_b16 v[226:227], v231 offset:3584
	v_exp_f32_e32 v32, v32
	v_exp_f32_e32 v33, v33
	s_waitcnt vmcnt(8)
	ds_write_b128 v247, v[156:159]
	ds_write_b128 v247, v[160:163] offset:1024
	ds_write_b128 v247, v[164:167] offset:2048
	ds_write_b128 v247, v[168:171] offset:3072
	ds_read_b128 v[156:159], v248
	ds_read_b128 v[160:163], v249
	ds_read_b128 v[164:167], v250
	ds_read_b128 v[168:171], v251
	ds_write_b128 v112, v[172:175]
	ds_write_b128 v112, v[176:179] offset:1024
	ds_write_b128 v112, v[180:183] offset:2048
	ds_write_b128 v112, v[184:187] offset:3072
	v_exp_f32_e32 v34, v34
	v_exp_f32_e32 v35, v35
	s_waitcnt lgkmcnt(4)
	v_mfma_f32_32x32x16_bf16 v[188:203], v[156:159], v[48:51], v[188:203]
	v_exp_f32_e32 v36, v36
	v_exp_f32_e32 v37, v37
	v_exp_f32_e32 v38, v38
	v_mfma_f32_32x32x16_bf16 v[188:203], v[160:163], v[52:55], v[188:203]
	v_exp_f32_e32 v39, v39
	v_exp_f32_e32 v40, v40
	v_exp_f32_e32 v41, v41
	v_mfma_f32_32x32x16_bf16 v[188:203], v[164:167], v[56:59], v[188:203]
	v_exp_f32_e32 v42, v42
	v_exp_f32_e32 v43, v43
	v_exp_f32_e32 v44, v44
	v_mfma_f32_32x32x16_bf16 v[188:203], v[168:171], v[60:63], v[188:203]
	v_exp_f32_e32 v45, v45
	v_exp_f32_e32 v46, v46
	v_exp_f32_e32 v47, v47
	s_add_i32 s90, s67, 512
	v_lshlrev_b32_e32 v84, 2, v107
	v_add_u32_e32 v84, s90, v84
	v_add_u32_e32 v85, 0, v84
	v_add_u32_e32 v86, 4, v84
	v_add_u32_e32 v87, 8, v84
	v_add_u32_e32 v88, 12, v84
	v_cmp_gt_u32_e64 s[30:31], s98, v85
	v_cmp_gt_u32_e64 s[36:37], s98, v86
	v_cmp_gt_u32_e64 s[78:79], s98, v87
	v_cmp_gt_u32_e64 s[50:51], s98, v88
	v_cndmask_b32_e64 v32, 0, v32, s[30:31]
	v_add_u32_e32 v85, 32, v84
	v_cmp_gt_u32_e64 s[30:31], s98, v85
	v_cndmask_b32_e64 v33, 0, v33, s[36:37]
	v_add_u32_e32 v86, 36, v84
	v_cmp_gt_u32_e64 s[36:37], s98, v86
	v_cndmask_b32_e64 v34, 0, v34, s[78:79]
	v_add_u32_e32 v87, 40, v84
	v_cmp_gt_u32_e64 s[78:79], s98, v87
	v_cndmask_b32_e64 v35, 0, v35, s[50:51]
	v_add_u32_e32 v88, 44, v84
	v_cmp_gt_u32_e64 s[50:51], s98, v88
	v_cndmask_b32_e64 v36, 0, v36, s[30:31]
	v_add_u32_e32 v85, 64, v84
	v_cmp_gt_u32_e64 s[30:31], s98, v85
	v_cndmask_b32_e64 v37, 0, v37, s[36:37]
	v_add_u32_e32 v86, 68, v84
	v_cmp_gt_u32_e64 s[36:37], s98, v86
	v_cndmask_b32_e64 v38, 0, v38, s[78:79]
	v_add_u32_e32 v87, 72, v84
	v_cmp_gt_u32_e64 s[78:79], s98, v87
	v_cndmask_b32_e64 v39, 0, v39, s[50:51]
	v_add_u32_e32 v88, 76, v84
	v_cmp_gt_u32_e64 s[50:51], s98, v88
	v_cndmask_b32_e64 v40, 0, v40, s[30:31]
	v_add_u32_e32 v85, 96, v84
	v_cmp_gt_u32_e64 s[30:31], s98, v85
	v_cndmask_b32_e64 v41, 0, v41, s[36:37]
	v_add_u32_e32 v86, 100, v84
	v_cmp_gt_u32_e64 s[36:37], s98, v86
	v_cndmask_b32_e64 v42, 0, v42, s[78:79]
	v_add_u32_e32 v87, 104, v84
	v_cmp_gt_u32_e64 s[78:79], s98, v87
	v_cndmask_b32_e64 v43, 0, v43, s[50:51]
	v_add_u32_e32 v88, 108, v84
	v_cmp_gt_u32_e64 s[50:51], s98, v88
	v_nop
	v_cndmask_b32_e64 v44, 0, v44, s[30:31]
	v_cndmask_b32_e64 v45, 0, v45, s[36:37]
	v_cndmask_b32_e64 v46, 0, v46, s[78:79]
	v_cndmask_b32_e64 v47, 0, v47, s[50:51]
	v_cvt_pk_bf16_f32 v64, v32, v33
	v_cvt_pk_bf16_f32 v65, v34, v35
	v_cvt_pk_bf16_f32 v66, v36, v37
	v_cvt_pk_bf16_f32 v67, v38, v39
	v_cvt_pk_bf16_f32 v68, v40, v41
	v_cvt_pk_bf16_f32 v69, v42, v43
	v_cvt_pk_bf16_f32 v70, v44, v45
	v_cvt_pk_bf16_f32 v71, v46, v47
	v_pk_add_f32 v[232:233], v[232:233], v[32:33]
	v_pk_add_f32 v[232:233], v[232:233], v[34:35]
	v_pk_add_f32 v[232:233], v[232:233], v[36:37]
	v_pk_add_f32 v[232:233], v[232:233], v[38:39]
	v_pk_add_f32 v[232:233], v[232:233], v[40:41]
	v_pk_add_f32 v[232:233], v[232:233], v[42:43]
	v_pk_add_f32 v[232:233], v[232:233], v[44:45]
	v_pk_add_f32 v[232:233], v[232:233], v[46:47]
	v_mov_b32_e32 v115, v230
	ds_read2_b32 v[32:33], v115 offset0:0 offset1:1
	ds_read2_b32 v[34:35], v115 offset0:2 offset1:3
	ds_read2_b32 v[36:37], v115 offset0:8 offset1:9
	ds_read2_b32 v[38:39], v115 offset0:10 offset1:11
	ds_read2_b32 v[40:41], v115 offset0:16 offset1:17
	ds_read2_b32 v[42:43], v115 offset0:18 offset1:19
	ds_read2_b32 v[44:45], v115 offset0:24 offset1:25
	ds_read2_b32 v[46:47], v115 offset0:26 offset1:27
	v_mfma_f32_32x32x16_bf16 v[0:15], v[64:67], v[72:75], v[0:15]
	v_mfma_f32_32x32x16_bf16 v[16:31], v[64:67], v[76:79], v[16:31]
	v_mfma_f32_32x32x16_bf16 v[0:15], v[68:71], v[220:223], v[0:15]
	v_mfma_f32_32x32x16_bf16 v[16:31], v[68:71], v[224:227], v[16:31]
	s_add_i32 s90, s67, -512
	v_add_u32_e32 v80, s90, v243
	v_add_u32_e32 v83, s90, v244
	v_add_u32_e32 v99, s90, v245
	v_add_u32_e32 v253, s90, v246
	v_add_u32_e32 v254, s90, v148
	v_add_u32_e32 v255, s90, v151
	v_med3_i32 v80, v80, 0, s99
	v_med3_i32 v83, v83, 0, s99
	v_med3_i32 v99, v99, 0, s99
	v_med3_i32 v253, v253, 0, s99
	v_med3_i32 v254, v254, 0, s99
	v_med3_i32 v255, v255, 0, s99
	v_mad_u32_u24 v80, v80, s100, v252
	v_mad_u32_u24 v83, v83, s100, v252
	v_mad_u32_u24 v99, v99, s100, v252
	v_mad_u32_u24 v253, v253, s100, v252
	v_mad_u32_u24 v254, v254, s100, v153
	v_mad_u32_u24 v255, v255, s100, v153
	global_load_dwordx4 v[156:159], v80, s[82:83]
	global_load_dwordx4 v[160:163], v83, s[82:83]
	global_load_dwordx4 v[164:167], v99, s[82:83]
	global_load_dwordx4 v[168:171], v253, s[82:83]
	global_load_dwordx4 v[172:175], v254, s[82:83] offset:768
	global_load_dwordx4 v[176:179], v255, s[82:83] offset:768
	global_load_dwordx4 v[180:183], v254, s[82:83] offset:832
	global_load_dwordx4 v[184:187], v255, s[82:83] offset:832
	ds_read_b64_tr_b16 v[72:73], v231
	ds_read_b64_tr_b16 v[74:75], v231 offset:512
	ds_read_b64_tr_b16 v[76:77], v231 offset:2048
	ds_read_b64_tr_b16 v[78:79], v231 offset:2560
	ds_read_b64_tr_b16 v[220:221], v231 offset:1024
	ds_read_b64_tr_b16 v[222:223], v231 offset:1536
	ds_read_b64_tr_b16 v[224:225], v231 offset:3072
	ds_read_b64_tr_b16 v[226:227], v231 offset:3584
	v_exp_f32_e32 v188, v188
	v_exp_f32_e32 v189, v189
	s_waitcnt vmcnt(8)
	ds_write_b128 v247, v[116:119]
	ds_write_b128 v247, v[120:123] offset:1024
	ds_write_b128 v247, v[124:127] offset:2048
	ds_write_b128 v247, v[128:131] offset:3072
	ds_read_b128 v[116:119], v248
	ds_read_b128 v[120:123], v249
	ds_read_b128 v[124:127], v250
	ds_read_b128 v[128:131], v251
	ds_write_b128 v112, v[132:135]
	ds_write_b128 v112, v[136:139] offset:1024
	ds_write_b128 v112, v[140:143] offset:2048
	ds_write_b128 v112, v[144:147] offset:3072
	v_exp_f32_e32 v190, v190
	v_exp_f32_e32 v191, v191
	s_waitcnt lgkmcnt(4)
	v_mfma_f32_32x32x16_bf16 v[32:47], v[116:119], v[48:51], v[32:47]
	v_exp_f32_e32 v192, v192
	v_exp_f32_e32 v193, v193
	v_exp_f32_e32 v194, v194
	v_mfma_f32_32x32x16_bf16 v[32:47], v[120:123], v[52:55], v[32:47]
	v_exp_f32_e32 v195, v195
	v_exp_f32_e32 v196, v196
	v_exp_f32_e32 v197, v197
	v_mfma_f32_32x32x16_bf16 v[32:47], v[124:127], v[56:59], v[32:47]
	v_exp_f32_e32 v198, v198
	v_exp_f32_e32 v199, v199
	v_exp_f32_e32 v200, v200
	v_mfma_f32_32x32x16_bf16 v[32:47], v[128:131], v[60:63], v[32:47]
	v_exp_f32_e32 v201, v201
	v_exp_f32_e32 v202, v202
	v_exp_f32_e32 v203, v203
	s_add_i32 s90, s67, 640
	v_lshlrev_b32_e32 v84, 2, v107
	v_add_u32_e32 v84, s90, v84
	v_add_u32_e32 v85, 0, v84
	v_add_u32_e32 v86, 4, v84
	v_add_u32_e32 v87, 8, v84
	v_add_u32_e32 v88, 12, v84
	v_cmp_gt_u32_e64 s[30:31], s98, v85
	v_cmp_gt_u32_e64 s[36:37], s98, v86
	v_cmp_gt_u32_e64 s[78:79], s98, v87
	v_cmp_gt_u32_e64 s[50:51], s98, v88
	v_cndmask_b32_e64 v188, 0, v188, s[30:31]
	v_add_u32_e32 v85, 32, v84
	v_cmp_gt_u32_e64 s[30:31], s98, v85
	v_cndmask_b32_e64 v189, 0, v189, s[36:37]
	v_add_u32_e32 v86, 36, v84
	v_cmp_gt_u32_e64 s[36:37], s98, v86
	v_cndmask_b32_e64 v190, 0, v190, s[78:79]
	v_add_u32_e32 v87, 40, v84
	v_cmp_gt_u32_e64 s[78:79], s98, v87
	v_cndmask_b32_e64 v191, 0, v191, s[50:51]
	v_add_u32_e32 v88, 44, v84
	v_cmp_gt_u32_e64 s[50:51], s98, v88
	v_cndmask_b32_e64 v192, 0, v192, s[30:31]
	v_add_u32_e32 v85, 64, v84
	v_cmp_gt_u32_e64 s[30:31], s98, v85
	v_cndmask_b32_e64 v193, 0, v193, s[36:37]
	v_add_u32_e32 v86, 68, v84
	v_cmp_gt_u32_e64 s[36:37], s98, v86
	v_cndmask_b32_e64 v194, 0, v194, s[78:79]
	v_add_u32_e32 v87, 72, v84
	v_cmp_gt_u32_e64 s[78:79], s98, v87
	v_cndmask_b32_e64 v195, 0, v195, s[50:51]
	v_add_u32_e32 v88, 76, v84
	v_cmp_gt_u32_e64 s[50:51], s98, v88
	v_cndmask_b32_e64 v196, 0, v196, s[30:31]
	v_add_u32_e32 v85, 96, v84
	v_cmp_gt_u32_e64 s[30:31], s98, v85
	v_cndmask_b32_e64 v197, 0, v197, s[36:37]
	v_add_u32_e32 v86, 100, v84
	v_cmp_gt_u32_e64 s[36:37], s98, v86
	v_cndmask_b32_e64 v198, 0, v198, s[78:79]
	v_add_u32_e32 v87, 104, v84
	v_cmp_gt_u32_e64 s[78:79], s98, v87
	v_cndmask_b32_e64 v199, 0, v199, s[50:51]
	v_add_u32_e32 v88, 108, v84
	v_cmp_gt_u32_e64 s[50:51], s98, v88
	v_nop
	v_cndmask_b32_e64 v200, 0, v200, s[30:31]
	v_cndmask_b32_e64 v201, 0, v201, s[36:37]
	v_cndmask_b32_e64 v202, 0, v202, s[78:79]
	v_cndmask_b32_e64 v203, 0, v203, s[50:51]
	v_cvt_pk_bf16_f32 v64, v188, v189
	v_cvt_pk_bf16_f32 v65, v190, v191
	v_cvt_pk_bf16_f32 v66, v192, v193
	v_cvt_pk_bf16_f32 v67, v194, v195
	v_cvt_pk_bf16_f32 v68, v196, v197
	v_cvt_pk_bf16_f32 v69, v198, v199
	v_cvt_pk_bf16_f32 v70, v200, v201
	v_cvt_pk_bf16_f32 v71, v202, v203
	v_pk_add_f32 v[232:233], v[232:233], v[188:189]
	v_pk_add_f32 v[232:233], v[232:233], v[190:191]
	v_pk_add_f32 v[232:233], v[232:233], v[192:193]
	v_pk_add_f32 v[232:233], v[232:233], v[194:195]
	v_pk_add_f32 v[232:233], v[232:233], v[196:197]
	v_pk_add_f32 v[232:233], v[232:233], v[198:199]
	v_pk_add_f32 v[232:233], v[232:233], v[200:201]
	v_pk_add_f32 v[232:233], v[232:233], v[202:203]
	ds_read2_b32 v[188:189], v115 offset0:32 offset1:33
	ds_read2_b32 v[190:191], v115 offset0:34 offset1:35
	ds_read2_b32 v[192:193], v115 offset0:40 offset1:41
	ds_read2_b32 v[194:195], v115 offset0:42 offset1:43
	ds_read2_b32 v[196:197], v115 offset0:48 offset1:49
	ds_read2_b32 v[198:199], v115 offset0:50 offset1:51
	ds_read2_b32 v[200:201], v115 offset0:56 offset1:57
	ds_read2_b32 v[202:203], v115 offset0:58 offset1:59
	v_mfma_f32_32x32x16_bf16 v[0:15], v[64:67], v[72:75], v[0:15]
	v_mfma_f32_32x32x16_bf16 v[16:31], v[64:67], v[76:79], v[16:31]
	v_mfma_f32_32x32x16_bf16 v[0:15], v[68:71], v[220:223], v[0:15]
	v_mfma_f32_32x32x16_bf16 v[16:31], v[68:71], v[224:227], v[16:31]
	s_add_i32 s90, s67, 0
	v_add_u32_e32 v80, s90, v243
	v_add_u32_e32 v83, s90, v244
	v_add_u32_e32 v99, s90, v245
	v_add_u32_e32 v253, s90, v246
	v_add_u32_e32 v254, s90, v148
	v_add_u32_e32 v255, s90, v151
	v_med3_i32 v80, v80, 0, s99
	v_med3_i32 v83, v83, 0, s99
	v_med3_i32 v99, v99, 0, s99
	v_med3_i32 v253, v253, 0, s99
	v_med3_i32 v254, v254, 0, s99
	v_med3_i32 v255, v255, 0, s99
	v_mad_u32_u24 v80, v80, s100, v252
	v_mad_u32_u24 v83, v83, s100, v252
	v_mad_u32_u24 v99, v99, s100, v252
	v_mad_u32_u24 v253, v253, s100, v252
	v_mad_u32_u24 v254, v254, s100, v153
	v_mad_u32_u24 v255, v255, s100, v153
	global_load_dwordx4 v[116:119], v80, s[82:83]
	global_load_dwordx4 v[120:123], v83, s[82:83]
	global_load_dwordx4 v[124:127], v99, s[82:83]
	global_load_dwordx4 v[128:131], v253, s[82:83]
	global_load_dwordx4 v[132:135], v254, s[82:83] offset:768
	global_load_dwordx4 v[136:139], v255, s[82:83] offset:768
	global_load_dwordx4 v[140:143], v254, s[82:83] offset:832
	global_load_dwordx4 v[144:147], v255, s[82:83] offset:832
	ds_read_b64_tr_b16 v[72:73], v231
	ds_read_b64_tr_b16 v[74:75], v231 offset:512
	ds_read_b64_tr_b16 v[76:77], v231 offset:2048
	ds_read_b64_tr_b16 v[78:79], v231 offset:2560
	ds_read_b64_tr_b16 v[220:221], v231 offset:1024
	ds_read_b64_tr_b16 v[222:223], v231 offset:1536
	ds_read_b64_tr_b16 v[224:225], v231 offset:3072
	ds_read_b64_tr_b16 v[226:227], v231 offset:3584
	v_exp_f32_e32 v32, v32
	v_exp_f32_e32 v33, v33
	s_waitcnt vmcnt(8)
	ds_write_b128 v247, v[156:159]
	ds_write_b128 v247, v[160:163] offset:1024
	ds_write_b128 v247, v[164:167] offset:2048
	ds_write_b128 v247, v[168:171] offset:3072
	ds_read_b128 v[156:159], v248
	ds_read_b128 v[160:163], v249
	ds_read_b128 v[164:167], v250
	ds_read_b128 v[168:171], v251
	ds_write_b128 v112, v[172:175]
	ds_write_b128 v112, v[176:179] offset:1024
	ds_write_b128 v112, v[180:183] offset:2048
	ds_write_b128 v112, v[184:187] offset:3072
	v_exp_f32_e32 v34, v34
	v_exp_f32_e32 v35, v35
	s_waitcnt lgkmcnt(4)
	v_mfma_f32_32x32x16_bf16 v[188:203], v[156:159], v[48:51], v[188:203]
	v_exp_f32_e32 v36, v36
	v_exp_f32_e32 v37, v37
	v_exp_f32_e32 v38, v38
	v_mfma_f32_32x32x16_bf16 v[188:203], v[160:163], v[52:55], v[188:203]
	v_exp_f32_e32 v39, v39
	v_exp_f32_e32 v40, v40
	v_exp_f32_e32 v41, v41
	v_mfma_f32_32x32x16_bf16 v[188:203], v[164:167], v[56:59], v[188:203]
	v_exp_f32_e32 v42, v42
	v_exp_f32_e32 v43, v43
	v_exp_f32_e32 v44, v44
	v_mfma_f32_32x32x16_bf16 v[188:203], v[168:171], v[60:63], v[188:203]
	v_exp_f32_e32 v45, v45
	v_exp_f32_e32 v46, v46
	v_exp_f32_e32 v47, v47
	s_add_i32 s90, s67, -1024
	v_lshlrev_b32_e32 v84, 4, v107
	v_add_u32_e32 v84, s90, v84
	v_add_u32_e32 v85, 0, v84
	v_add_u32_e32 v86, 16, v84
	v_add_u32_e32 v87, 32, v84
	v_add_u32_e32 v88, 48, v84
	v_cmp_gt_u32_e64 s[30:31], s98, v85
	v_cmp_gt_u32_e64 s[36:37], s98, v86
	v_cmp_gt_u32_e64 s[78:79], s98, v87
	v_cmp_gt_u32_e64 s[50:51], s98, v88
	v_cndmask_b32_e64 v32, 0, v32, s[30:31]
	v_add_u32_e32 v85, 128, v84
	v_cmp_gt_u32_e64 s[30:31], s98, v85
	v_cndmask_b32_e64 v33, 0, v33, s[36:37]
	v_add_u32_e32 v86, 144, v84
	v_cmp_gt_u32_e64 s[36:37], s98, v86
	v_cndmask_b32_e64 v34, 0, v34, s[78:79]
	v_add_u32_e32 v87, 160, v84
	v_cmp_gt_u32_e64 s[78:79], s98, v87
	v_cndmask_b32_e64 v35, 0, v35, s[50:51]
	v_add_u32_e32 v88, 176, v84
	v_cmp_gt_u32_e64 s[50:51], s98, v88
	v_cndmask_b32_e64 v36, 0, v36, s[30:31]
	v_add_u32_e32 v85, 256, v84
	v_cmp_gt_u32_e64 s[30:31], s98, v85
	v_cndmask_b32_e64 v37, 0, v37, s[36:37]
	v_add_u32_e32 v86, 272, v84
	v_cmp_gt_u32_e64 s[36:37], s98, v86
	v_cndmask_b32_e64 v38, 0, v38, s[78:79]
	v_add_u32_e32 v87, 288, v84
	v_cmp_gt_u32_e64 s[78:79], s98, v87
	v_cndmask_b32_e64 v39, 0, v39, s[50:51]
	v_add_u32_e32 v88, 304, v84
	v_cmp_gt_u32_e64 s[50:51], s98, v88
	v_cndmask_b32_e64 v40, 0, v40, s[30:31]
	v_add_u32_e32 v85, 384, v84
	v_cmp_gt_u32_e64 s[30:31], s98, v85
	v_cndmask_b32_e64 v41, 0, v41, s[36:37]
	v_add_u32_e32 v86, 400, v84
	v_cmp_gt_u32_e64 s[36:37], s98, v86
	v_cndmask_b32_e64 v42, 0, v42, s[78:79]
	v_add_u32_e32 v87, 416, v84
	v_cmp_gt_u32_e64 s[78:79], s98, v87
	v_cndmask_b32_e64 v43, 0, v43, s[50:51]
	v_add_u32_e32 v88, 432, v84
	v_cmp_gt_u32_e64 s[50:51], s98, v88
	v_nop
	v_cndmask_b32_e64 v44, 0, v44, s[30:31]
	v_cndmask_b32_e64 v45, 0, v45, s[36:37]
	v_cndmask_b32_e64 v46, 0, v46, s[78:79]
	v_cndmask_b32_e64 v47, 0, v47, s[50:51]
	v_cvt_pk_bf16_f32 v64, v32, v33
	v_cvt_pk_bf16_f32 v65, v34, v35
	v_cvt_pk_bf16_f32 v66, v36, v37
	v_cvt_pk_bf16_f32 v67, v38, v39
	v_cvt_pk_bf16_f32 v68, v40, v41
	v_cvt_pk_bf16_f32 v69, v42, v43
	v_cvt_pk_bf16_f32 v70, v44, v45
	v_cvt_pk_bf16_f32 v71, v46, v47
	v_pk_add_f32 v[232:233], v[232:233], v[32:33]
	v_pk_add_f32 v[232:233], v[232:233], v[34:35]
	v_pk_add_f32 v[232:233], v[232:233], v[36:37]
	v_pk_add_f32 v[232:233], v[232:233], v[38:39]
	v_pk_add_f32 v[232:233], v[232:233], v[40:41]
	v_pk_add_f32 v[232:233], v[232:233], v[42:43]
	v_pk_add_f32 v[232:233], v[232:233], v[44:45]
	v_pk_add_f32 v[232:233], v[232:233], v[46:47]
	ds_read2_b32 v[32:33], v115 offset0:64 offset1:65
	ds_read2_b32 v[34:35], v115 offset0:66 offset1:67
	ds_read2_b32 v[36:37], v115 offset0:72 offset1:73
	ds_read2_b32 v[38:39], v115 offset0:74 offset1:75
	ds_read2_b32 v[40:41], v115 offset0:80 offset1:81
	ds_read2_b32 v[42:43], v115 offset0:82 offset1:83
	ds_read2_b32 v[44:45], v115 offset0:88 offset1:89
	ds_read2_b32 v[46:47], v115 offset0:90 offset1:91
	v_mfma_f32_32x32x16_bf16 v[0:15], v[64:67], v[72:75], v[0:15]
	v_mfma_f32_32x32x16_bf16 v[16:31], v[64:67], v[76:79], v[16:31]
	v_mfma_f32_32x32x16_bf16 v[0:15], v[68:71], v[220:223], v[0:15]
	v_mfma_f32_32x32x16_bf16 v[16:31], v[68:71], v[224:227], v[16:31]
	s_add_i32 s90, s67, 512
	v_add_u32_e32 v80, s90, v243
	v_add_u32_e32 v83, s90, v244
	v_add_u32_e32 v99, s90, v245
	v_add_u32_e32 v253, s90, v246
	v_add_u32_e32 v254, s90, v148
	v_add_u32_e32 v255, s90, v151
	v_med3_i32 v80, v80, 0, s99
	v_med3_i32 v83, v83, 0, s99
	v_med3_i32 v99, v99, 0, s99
	v_med3_i32 v253, v253, 0, s99
	v_med3_i32 v254, v254, 0, s99
	v_med3_i32 v255, v255, 0, s99
	v_mad_u32_u24 v80, v80, s100, v252
	v_mad_u32_u24 v83, v83, s100, v252
	v_mad_u32_u24 v99, v99, s100, v252
	v_mad_u32_u24 v253, v253, s100, v252
	v_mad_u32_u24 v254, v254, s100, v153
	v_mad_u32_u24 v255, v255, s100, v153
	global_load_dwordx4 v[156:159], v80, s[82:83]
	global_load_dwordx4 v[160:163], v83, s[82:83]
	global_load_dwordx4 v[164:167], v99, s[82:83]
	global_load_dwordx4 v[168:171], v253, s[82:83]
	global_load_dwordx4 v[172:175], v254, s[82:83] offset:768
	global_load_dwordx4 v[176:179], v255, s[82:83] offset:768
	global_load_dwordx4 v[180:183], v254, s[82:83] offset:832
	global_load_dwordx4 v[184:187], v255, s[82:83] offset:832
	ds_read_b64_tr_b16 v[72:73], v231
	ds_read_b64_tr_b16 v[74:75], v231 offset:512
	ds_read_b64_tr_b16 v[76:77], v231 offset:2048
	ds_read_b64_tr_b16 v[78:79], v231 offset:2560
	ds_read_b64_tr_b16 v[220:221], v231 offset:1024
	ds_read_b64_tr_b16 v[222:223], v231 offset:1536
	ds_read_b64_tr_b16 v[224:225], v231 offset:3072
	ds_read_b64_tr_b16 v[226:227], v231 offset:3584
	v_exp_f32_e32 v188, v188
	v_exp_f32_e32 v189, v189
	s_waitcnt vmcnt(8)
	ds_write_b128 v247, v[116:119]
	ds_write_b128 v247, v[120:123] offset:1024
	ds_write_b128 v247, v[124:127] offset:2048
	ds_write_b128 v247, v[128:131] offset:3072
	ds_read_b128 v[116:119], v248
	ds_read_b128 v[120:123], v249
	ds_read_b128 v[124:127], v250
	ds_read_b128 v[128:131], v251
	ds_write_b128 v112, v[132:135]
	ds_write_b128 v112, v[136:139] offset:1024
	ds_write_b128 v112, v[140:143] offset:2048
	ds_write_b128 v112, v[144:147] offset:3072
	v_exp_f32_e32 v190, v190
	v_exp_f32_e32 v191, v191
	s_waitcnt lgkmcnt(4)
	v_mfma_f32_32x32x16_bf16 v[32:47], v[116:119], v[48:51], v[32:47]
	v_exp_f32_e32 v192, v192
	v_exp_f32_e32 v193, v193
	v_exp_f32_e32 v194, v194
	v_mfma_f32_32x32x16_bf16 v[32:47], v[120:123], v[52:55], v[32:47]
	v_exp_f32_e32 v195, v195
	v_exp_f32_e32 v196, v196
	v_exp_f32_e32 v197, v197
	v_mfma_f32_32x32x16_bf16 v[32:47], v[124:127], v[56:59], v[32:47]
	v_exp_f32_e32 v198, v198
	v_exp_f32_e32 v199, v199
	v_exp_f32_e32 v200, v200
	v_mfma_f32_32x32x16_bf16 v[32:47], v[128:131], v[60:63], v[32:47]
	v_exp_f32_e32 v201, v201
	v_exp_f32_e32 v202, v202
	v_exp_f32_e32 v203, v203
	s_add_i32 s90, s67, -512
	v_lshlrev_b32_e32 v84, 4, v107
	v_add_u32_e32 v84, s90, v84
	v_add_u32_e32 v85, 0, v84
	v_add_u32_e32 v86, 16, v84
	v_add_u32_e32 v87, 32, v84
	v_add_u32_e32 v88, 48, v84
	v_cmp_gt_u32_e64 s[30:31], s98, v85
	v_cmp_gt_u32_e64 s[36:37], s98, v86
	v_cmp_gt_u32_e64 s[78:79], s98, v87
	v_cmp_gt_u32_e64 s[50:51], s98, v88
	v_cndmask_b32_e64 v188, 0, v188, s[30:31]
	v_add_u32_e32 v85, 128, v84
	v_cmp_gt_u32_e64 s[30:31], s98, v85
	v_cndmask_b32_e64 v189, 0, v189, s[36:37]
	v_add_u32_e32 v86, 144, v84
	v_cmp_gt_u32_e64 s[36:37], s98, v86
	v_cndmask_b32_e64 v190, 0, v190, s[78:79]
	v_add_u32_e32 v87, 160, v84
	v_cmp_gt_u32_e64 s[78:79], s98, v87
	v_cndmask_b32_e64 v191, 0, v191, s[50:51]
	v_add_u32_e32 v88, 176, v84
	v_cmp_gt_u32_e64 s[50:51], s98, v88
	v_cndmask_b32_e64 v192, 0, v192, s[30:31]
	v_add_u32_e32 v85, 256, v84
	v_cmp_gt_u32_e64 s[30:31], s98, v85
	v_cndmask_b32_e64 v193, 0, v193, s[36:37]
	v_add_u32_e32 v86, 272, v84
	v_cmp_gt_u32_e64 s[36:37], s98, v86
	v_cndmask_b32_e64 v194, 0, v194, s[78:79]
	v_add_u32_e32 v87, 288, v84
	v_cmp_gt_u32_e64 s[78:79], s98, v87
	v_cndmask_b32_e64 v195, 0, v195, s[50:51]
	v_add_u32_e32 v88, 304, v84
	v_cmp_gt_u32_e64 s[50:51], s98, v88
	v_cndmask_b32_e64 v196, 0, v196, s[30:31]
	v_add_u32_e32 v85, 384, v84
	v_cmp_gt_u32_e64 s[30:31], s98, v85
	v_cndmask_b32_e64 v197, 0, v197, s[36:37]
	v_add_u32_e32 v86, 400, v84
	v_cmp_gt_u32_e64 s[36:37], s98, v86
	v_cndmask_b32_e64 v198, 0, v198, s[78:79]
	v_add_u32_e32 v87, 416, v84
	v_cmp_gt_u32_e64 s[78:79], s98, v87
	v_cndmask_b32_e64 v199, 0, v199, s[50:51]
	v_add_u32_e32 v88, 432, v84
	v_cmp_gt_u32_e64 s[50:51], s98, v88
	v_nop
	v_cndmask_b32_e64 v200, 0, v200, s[30:31]
	v_cndmask_b32_e64 v201, 0, v201, s[36:37]
	v_cndmask_b32_e64 v202, 0, v202, s[78:79]
	v_cndmask_b32_e64 v203, 0, v203, s[50:51]
	v_cvt_pk_bf16_f32 v64, v188, v189
	v_cvt_pk_bf16_f32 v65, v190, v191
	v_cvt_pk_bf16_f32 v66, v192, v193
	v_cvt_pk_bf16_f32 v67, v194, v195
	v_cvt_pk_bf16_f32 v68, v196, v197
	v_cvt_pk_bf16_f32 v69, v198, v199
	v_cvt_pk_bf16_f32 v70, v200, v201
	v_cvt_pk_bf16_f32 v71, v202, v203
	v_pk_add_f32 v[232:233], v[232:233], v[188:189]
	v_pk_add_f32 v[232:233], v[232:233], v[190:191]
	v_pk_add_f32 v[232:233], v[232:233], v[192:193]
	v_pk_add_f32 v[232:233], v[232:233], v[194:195]
	v_pk_add_f32 v[232:233], v[232:233], v[196:197]
	v_pk_add_f32 v[232:233], v[232:233], v[198:199]
	v_pk_add_f32 v[232:233], v[232:233], v[200:201]
	v_pk_add_f32 v[232:233], v[232:233], v[202:203]
	ds_read2_b32 v[188:189], v115 offset0:96 offset1:97
	ds_read2_b32 v[190:191], v115 offset0:98 offset1:99
	ds_read2_b32 v[192:193], v115 offset0:104 offset1:105
	ds_read2_b32 v[194:195], v115 offset0:106 offset1:107
	ds_read2_b32 v[196:197], v115 offset0:112 offset1:113
	ds_read2_b32 v[198:199], v115 offset0:114 offset1:115
	ds_read2_b32 v[200:201], v115 offset0:120 offset1:121
	ds_read2_b32 v[202:203], v115 offset0:122 offset1:123
	v_mfma_f32_32x32x16_bf16 v[0:15], v[64:67], v[72:75], v[0:15]
	v_mfma_f32_32x32x16_bf16 v[16:31], v[64:67], v[76:79], v[16:31]
	v_mfma_f32_32x32x16_bf16 v[0:15], v[68:71], v[220:223], v[0:15]
	v_mfma_f32_32x32x16_bf16 v[16:31], v[68:71], v[224:227], v[16:31]
	s_add_i32 s90, s67, 1024
	v_add_u32_e32 v80, s90, v243
	v_add_u32_e32 v83, s90, v244
	v_add_u32_e32 v99, s90, v245
	v_add_u32_e32 v253, s90, v246
	v_add_u32_e32 v254, s90, v148
	v_add_u32_e32 v255, s90, v151
	v_med3_i32 v80, v80, 0, s99
	v_med3_i32 v83, v83, 0, s99
	v_med3_i32 v99, v99, 0, s99
	v_med3_i32 v253, v253, 0, s99
	v_med3_i32 v254, v254, 0, s99
	v_med3_i32 v255, v255, 0, s99
	v_mad_u32_u24 v80, v80, s100, v252
	v_mad_u32_u24 v83, v83, s100, v252
	v_mad_u32_u24 v99, v99, s100, v252
	v_mad_u32_u24 v253, v253, s100, v252
	v_mad_u32_u24 v254, v254, s100, v153
	v_mad_u32_u24 v255, v255, s100, v153
	global_load_dwordx4 v[116:119], v80, s[82:83]
	global_load_dwordx4 v[120:123], v83, s[82:83]
	global_load_dwordx4 v[124:127], v99, s[82:83]
	global_load_dwordx4 v[128:131], v253, s[82:83]
	global_load_dwordx4 v[132:135], v254, s[82:83] offset:768
	global_load_dwordx4 v[136:139], v255, s[82:83] offset:768
	global_load_dwordx4 v[140:143], v254, s[82:83] offset:832
	global_load_dwordx4 v[144:147], v255, s[82:83] offset:832
	ds_read_b64_tr_b16 v[72:73], v231
	ds_read_b64_tr_b16 v[74:75], v231 offset:512
	ds_read_b64_tr_b16 v[76:77], v231 offset:2048
	ds_read_b64_tr_b16 v[78:79], v231 offset:2560
	ds_read_b64_tr_b16 v[220:221], v231 offset:1024
	ds_read_b64_tr_b16 v[222:223], v231 offset:1536
	ds_read_b64_tr_b16 v[224:225], v231 offset:3072
	ds_read_b64_tr_b16 v[226:227], v231 offset:3584
	v_exp_f32_e32 v32, v32
	v_exp_f32_e32 v33, v33
	s_waitcnt vmcnt(8)
	ds_write_b128 v247, v[156:159]
	ds_write_b128 v247, v[160:163] offset:1024
	ds_write_b128 v247, v[164:167] offset:2048
	ds_write_b128 v247, v[168:171] offset:3072
	ds_read_b128 v[156:159], v248
	ds_read_b128 v[160:163], v249
	ds_read_b128 v[164:167], v250
	ds_read_b128 v[168:171], v251
	ds_write_b128 v112, v[172:175]
	ds_write_b128 v112, v[176:179] offset:1024
	ds_write_b128 v112, v[180:183] offset:2048
	ds_write_b128 v112, v[184:187] offset:3072
	v_exp_f32_e32 v34, v34
	v_exp_f32_e32 v35, v35
	s_waitcnt lgkmcnt(4)
	v_mfma_f32_32x32x16_bf16 v[188:203], v[156:159], v[48:51], v[188:203]
	v_exp_f32_e32 v36, v36
	v_exp_f32_e32 v37, v37
	v_exp_f32_e32 v38, v38
	v_mfma_f32_32x32x16_bf16 v[188:203], v[160:163], v[52:55], v[188:203]
	v_exp_f32_e32 v39, v39
	v_exp_f32_e32 v40, v40
	v_exp_f32_e32 v41, v41
	v_mfma_f32_32x32x16_bf16 v[188:203], v[164:167], v[56:59], v[188:203]
	v_exp_f32_e32 v42, v42
	v_exp_f32_e32 v43, v43
	v_exp_f32_e32 v44, v44
	v_mfma_f32_32x32x16_bf16 v[188:203], v[168:171], v[60:63], v[188:203]
	v_exp_f32_e32 v45, v45
	v_exp_f32_e32 v46, v46
	v_exp_f32_e32 v47, v47
	s_add_i32 s90, s67, 0
	v_lshlrev_b32_e32 v84, 4, v107
	v_add_u32_e32 v84, s90, v84
	v_add_u32_e32 v85, 0, v84
	v_add_u32_e32 v86, 16, v84
	v_add_u32_e32 v87, 32, v84
	v_add_u32_e32 v88, 48, v84
	v_cmp_gt_u32_e64 s[30:31], s98, v85
	v_cmp_gt_u32_e64 s[36:37], s98, v86
	v_cmp_gt_u32_e64 s[78:79], s98, v87
	v_cmp_gt_u32_e64 s[50:51], s98, v88
	v_cndmask_b32_e64 v32, 0, v32, s[30:31]
	v_add_u32_e32 v85, 128, v84
	v_cmp_gt_u32_e64 s[30:31], s98, v85
	v_cndmask_b32_e64 v33, 0, v33, s[36:37]
	v_add_u32_e32 v86, 144, v84
	v_cmp_gt_u32_e64 s[36:37], s98, v86
	v_cndmask_b32_e64 v34, 0, v34, s[78:79]
	v_add_u32_e32 v87, 160, v84
	v_cmp_gt_u32_e64 s[78:79], s98, v87
	v_cndmask_b32_e64 v35, 0, v35, s[50:51]
	v_add_u32_e32 v88, 176, v84
	v_cmp_gt_u32_e64 s[50:51], s98, v88
	v_cndmask_b32_e64 v36, 0, v36, s[30:31]
	v_add_u32_e32 v85, 256, v84
	v_cmp_gt_u32_e64 s[30:31], s98, v85
	v_cndmask_b32_e64 v37, 0, v37, s[36:37]
	v_add_u32_e32 v86, 272, v84
	v_cmp_gt_u32_e64 s[36:37], s98, v86
	v_cndmask_b32_e64 v38, 0, v38, s[78:79]
	v_add_u32_e32 v87, 288, v84
	v_cmp_gt_u32_e64 s[78:79], s98, v87
	v_cndmask_b32_e64 v39, 0, v39, s[50:51]
	v_add_u32_e32 v88, 304, v84
	v_cmp_gt_u32_e64 s[50:51], s98, v88
	v_cndmask_b32_e64 v40, 0, v40, s[30:31]
	v_add_u32_e32 v85, 384, v84
	v_cmp_gt_u32_e64 s[30:31], s98, v85
	v_cndmask_b32_e64 v41, 0, v41, s[36:37]
	v_add_u32_e32 v86, 400, v84
	v_cmp_gt_u32_e64 s[36:37], s98, v86
	v_cndmask_b32_e64 v42, 0, v42, s[78:79]
	v_add_u32_e32 v87, 416, v84
	v_cmp_gt_u32_e64 s[78:79], s98, v87
	v_cndmask_b32_e64 v43, 0, v43, s[50:51]
	v_add_u32_e32 v88, 432, v84
	v_cmp_gt_u32_e64 s[50:51], s98, v88
	v_nop
	v_cndmask_b32_e64 v44, 0, v44, s[30:31]
	v_cndmask_b32_e64 v45, 0, v45, s[36:37]
	v_cndmask_b32_e64 v46, 0, v46, s[78:79]
	v_cndmask_b32_e64 v47, 0, v47, s[50:51]
	v_cvt_pk_bf16_f32 v64, v32, v33
	v_cvt_pk_bf16_f32 v65, v34, v35
	v_cvt_pk_bf16_f32 v66, v36, v37
	v_cvt_pk_bf16_f32 v67, v38, v39
	v_cvt_pk_bf16_f32 v68, v40, v41
	v_cvt_pk_bf16_f32 v69, v42, v43
	v_cvt_pk_bf16_f32 v70, v44, v45
	v_cvt_pk_bf16_f32 v71, v46, v47
	v_pk_add_f32 v[232:233], v[232:233], v[32:33]
	v_pk_add_f32 v[232:233], v[232:233], v[34:35]
	v_pk_add_f32 v[232:233], v[232:233], v[36:37]
	v_pk_add_f32 v[232:233], v[232:233], v[38:39]
	v_pk_add_f32 v[232:233], v[232:233], v[40:41]
	v_pk_add_f32 v[232:233], v[232:233], v[42:43]
	v_pk_add_f32 v[232:233], v[232:233], v[44:45]
	v_pk_add_f32 v[232:233], v[232:233], v[46:47]
	ds_read2_b32 v[32:33], v115 offset0:128 offset1:129
	ds_read2_b32 v[34:35], v115 offset0:130 offset1:131
	ds_read2_b32 v[36:37], v115 offset0:136 offset1:137
	ds_read2_b32 v[38:39], v115 offset0:138 offset1:139
	ds_read2_b32 v[40:41], v115 offset0:144 offset1:145
	ds_read2_b32 v[42:43], v115 offset0:146 offset1:147
	ds_read2_b32 v[44:45], v115 offset0:152 offset1:153
	ds_read2_b32 v[46:47], v115 offset0:154 offset1:155
	v_mfma_f32_32x32x16_bf16 v[0:15], v[64:67], v[72:75], v[0:15]
	v_mfma_f32_32x32x16_bf16 v[16:31], v[64:67], v[76:79], v[16:31]
	v_mfma_f32_32x32x16_bf16 v[0:15], v[68:71], v[220:223], v[0:15]
	v_mfma_f32_32x32x16_bf16 v[16:31], v[68:71], v[224:227], v[16:31]
	ds_read_b64_tr_b16 v[72:73], v231
	ds_read_b64_tr_b16 v[74:75], v231 offset:512
	ds_read_b64_tr_b16 v[76:77], v231 offset:2048
	ds_read_b64_tr_b16 v[78:79], v231 offset:2560
	ds_read_b64_tr_b16 v[220:221], v231 offset:1024
	ds_read_b64_tr_b16 v[222:223], v231 offset:1536
	ds_read_b64_tr_b16 v[224:225], v231 offset:3072
	ds_read_b64_tr_b16 v[226:227], v231 offset:3584
	v_exp_f32_e32 v188, v188
	v_exp_f32_e32 v189, v189
	s_waitcnt vmcnt(0)
	ds_write_b128 v247, v[116:119]
	ds_write_b128 v247, v[120:123] offset:1024
	ds_write_b128 v247, v[124:127] offset:2048
	ds_write_b128 v247, v[128:131] offset:3072
	ds_read_b128 v[116:119], v248
	ds_read_b128 v[120:123], v249
	ds_read_b128 v[124:127], v250
	ds_read_b128 v[128:131], v251
	ds_write_b128 v112, v[132:135]
	ds_write_b128 v112, v[136:139] offset:1024
	ds_write_b128 v112, v[140:143] offset:2048
	ds_write_b128 v112, v[144:147] offset:3072
	v_exp_f32_e32 v190, v190
	v_exp_f32_e32 v191, v191
	s_waitcnt lgkmcnt(4)
	v_mfma_f32_32x32x16_bf16 v[32:47], v[116:119], v[48:51], v[32:47]
	v_exp_f32_e32 v192, v192
	v_exp_f32_e32 v193, v193
	v_exp_f32_e32 v194, v194
	v_mfma_f32_32x32x16_bf16 v[32:47], v[120:123], v[52:55], v[32:47]
	v_exp_f32_e32 v195, v195
	v_exp_f32_e32 v196, v196
	v_exp_f32_e32 v197, v197
	v_mfma_f32_32x32x16_bf16 v[32:47], v[124:127], v[56:59], v[32:47]
	v_exp_f32_e32 v198, v198
	v_exp_f32_e32 v199, v199
	v_exp_f32_e32 v200, v200
	v_mfma_f32_32x32x16_bf16 v[32:47], v[128:131], v[60:63], v[32:47]
	v_exp_f32_e32 v201, v201
	v_exp_f32_e32 v202, v202
	v_exp_f32_e32 v203, v203
	s_add_i32 s90, s67, 512
	v_lshlrev_b32_e32 v84, 4, v107
	v_add_u32_e32 v84, s90, v84
	v_add_u32_e32 v85, 0, v84
	v_add_u32_e32 v86, 16, v84
	v_add_u32_e32 v87, 32, v84
	v_add_u32_e32 v88, 48, v84
	v_cmp_gt_u32_e64 s[30:31], s98, v85
	v_cmp_gt_u32_e64 s[36:37], s98, v86
	v_cmp_gt_u32_e64 s[78:79], s98, v87
	v_cmp_gt_u32_e64 s[50:51], s98, v88
	v_cndmask_b32_e64 v188, 0, v188, s[30:31]
	v_add_u32_e32 v85, 128, v84
	v_cmp_gt_u32_e64 s[30:31], s98, v85
	v_cndmask_b32_e64 v189, 0, v189, s[36:37]
	v_add_u32_e32 v86, 144, v84
	v_cmp_gt_u32_e64 s[36:37], s98, v86
	v_cndmask_b32_e64 v190, 0, v190, s[78:79]
	v_add_u32_e32 v87, 160, v84
	v_cmp_gt_u32_e64 s[78:79], s98, v87
	v_cndmask_b32_e64 v191, 0, v191, s[50:51]
	v_add_u32_e32 v88, 176, v84
	v_cmp_gt_u32_e64 s[50:51], s98, v88
	v_cndmask_b32_e64 v192, 0, v192, s[30:31]
	v_add_u32_e32 v85, 256, v84
	v_cmp_gt_u32_e64 s[30:31], s98, v85
	v_cndmask_b32_e64 v193, 0, v193, s[36:37]
	v_add_u32_e32 v86, 272, v84
	v_cmp_gt_u32_e64 s[36:37], s98, v86
	v_cndmask_b32_e64 v194, 0, v194, s[78:79]
	v_add_u32_e32 v87, 288, v84
	v_cmp_gt_u32_e64 s[78:79], s98, v87
	v_cndmask_b32_e64 v195, 0, v195, s[50:51]
	v_add_u32_e32 v88, 304, v84
	v_cmp_gt_u32_e64 s[50:51], s98, v88
	v_cndmask_b32_e64 v196, 0, v196, s[30:31]
	v_add_u32_e32 v85, 384, v84
	v_cmp_gt_u32_e64 s[30:31], s98, v85
	v_cndmask_b32_e64 v197, 0, v197, s[36:37]
	v_add_u32_e32 v86, 400, v84
	v_cmp_gt_u32_e64 s[36:37], s98, v86
	v_cndmask_b32_e64 v198, 0, v198, s[78:79]
	v_add_u32_e32 v87, 416, v84
	v_cmp_gt_u32_e64 s[78:79], s98, v87
	v_cndmask_b32_e64 v199, 0, v199, s[50:51]
	v_add_u32_e32 v88, 432, v84
	v_cmp_gt_u32_e64 s[50:51], s98, v88
	v_nop
	v_cndmask_b32_e64 v200, 0, v200, s[30:31]
	v_cndmask_b32_e64 v201, 0, v201, s[36:37]
	v_cndmask_b32_e64 v202, 0, v202, s[78:79]
	v_cndmask_b32_e64 v203, 0, v203, s[50:51]
	v_cvt_pk_bf16_f32 v64, v188, v189
	v_cvt_pk_bf16_f32 v65, v190, v191
	v_cvt_pk_bf16_f32 v66, v192, v193
	v_cvt_pk_bf16_f32 v67, v194, v195
	v_cvt_pk_bf16_f32 v68, v196, v197
	v_cvt_pk_bf16_f32 v69, v198, v199
	v_cvt_pk_bf16_f32 v70, v200, v201
	v_cvt_pk_bf16_f32 v71, v202, v203
	v_pk_add_f32 v[232:233], v[232:233], v[188:189]
	v_pk_add_f32 v[232:233], v[232:233], v[190:191]
	v_pk_add_f32 v[232:233], v[232:233], v[192:193]
	v_pk_add_f32 v[232:233], v[232:233], v[194:195]
	v_pk_add_f32 v[232:233], v[232:233], v[196:197]
	v_pk_add_f32 v[232:233], v[232:233], v[198:199]
	v_pk_add_f32 v[232:233], v[232:233], v[200:201]
	v_pk_add_f32 v[232:233], v[232:233], v[202:203]
	v_mfma_f32_32x32x16_bf16 v[0:15], v[64:67], v[72:75], v[0:15]
	v_mfma_f32_32x32x16_bf16 v[16:31], v[64:67], v[76:79], v[16:31]
	v_mfma_f32_32x32x16_bf16 v[0:15], v[68:71], v[220:223], v[0:15]
	v_mfma_f32_32x32x16_bf16 v[16:31], v[68:71], v[224:227], v[16:31]
	ds_read_b64_tr_b16 v[72:73], v231
	ds_read_b64_tr_b16 v[74:75], v231 offset:512
	ds_read_b64_tr_b16 v[76:77], v231 offset:2048
	ds_read_b64_tr_b16 v[78:79], v231 offset:2560
	ds_read_b64_tr_b16 v[220:221], v231 offset:1024
	ds_read_b64_tr_b16 v[222:223], v231 offset:1536
	ds_read_b64_tr_b16 v[224:225], v231 offset:3072
	ds_read_b64_tr_b16 v[226:227], v231 offset:3584
	s_waitcnt lgkmcnt(0)
; __device__ __forceinline__ int crow(int r, int hi) { return (r & 3) + 8 * (r >> 2) + 4 * hi; }
; __device__ __forceinline__ void dil_unit(LAS unsigned char* lds, bf16_t* proj, int seq, int hd, int T0, int rho) {
;     ...
;     for (int rr = 0; rr < 16; ++rr) {
;         const int j = crow(rr, hi);
;         const float il = __builtin_amdgcn_rcpf(__shfl(l, j));
	v_exp_f32_e32 v32, v32
	v_exp_f32_e32 v33, v33
	v_exp_f32_e32 v34, v34
	v_exp_f32_e32 v35, v35
	v_exp_f32_e32 v36, v36
	v_exp_f32_e32 v37, v37
	v_exp_f32_e32 v38, v38
	v_exp_f32_e32 v39, v39
	v_exp_f32_e32 v40, v40
	v_exp_f32_e32 v41, v41
	v_exp_f32_e32 v42, v42
	v_exp_f32_e32 v43, v43
	v_exp_f32_e32 v44, v44
	v_exp_f32_e32 v45, v45
	v_exp_f32_e32 v46, v46
	v_exp_f32_e32 v47, v47
	s_add_i32 s90, s67, 1024
	v_lshlrev_b32_e32 v84, 4, v107
	v_add_u32_e32 v84, s90, v84
	v_add_u32_e32 v85, 0, v84
	v_add_u32_e32 v86, 16, v84
	v_add_u32_e32 v87, 32, v84
	v_add_u32_e32 v88, 48, v84
	v_cmp_gt_u32_e64 s[30:31], s98, v85
	v_cmp_gt_u32_e64 s[36:37], s98, v86
	v_cmp_gt_u32_e64 s[78:79], s98, v87
	v_cmp_gt_u32_e64 s[50:51], s98, v88
	v_cndmask_b32_e64 v32, 0, v32, s[30:31]
	v_add_u32_e32 v85, 128, v84
	v_cmp_gt_u32_e64 s[30:31], s98, v85
	v_cndmask_b32_e64 v33, 0, v33, s[36:37]
	v_add_u32_e32 v86, 144, v84
	v_cmp_gt_u32_e64 s[36:37], s98, v86
	v_cndmask_b32_e64 v34, 0, v34, s[78:79]
	v_add_u32_e32 v87, 160, v84
	v_cmp_gt_u32_e64 s[78:79], s98, v87
	v_cndmask_b32_e64 v35, 0, v35, s[50:51]
	v_add_u32_e32 v88, 176, v84
	v_cmp_gt_u32_e64 s[50:51], s98, v88
	v_cndmask_b32_e64 v36, 0, v36, s[30:31]
	v_add_u32_e32 v85, 256, v84
	v_cmp_gt_u32_e64 s[30:31], s98, v85
	v_cndmask_b32_e64 v37, 0, v37, s[36:37]
	v_add_u32_e32 v86, 272, v84
	v_cmp_gt_u32_e64 s[36:37], s98, v86
	v_cndmask_b32_e64 v38, 0, v38, s[78:79]
	v_add_u32_e32 v87, 288, v84
	v_cmp_gt_u32_e64 s[78:79], s98, v87
	v_cndmask_b32_e64 v39, 0, v39, s[50:51]
	v_add_u32_e32 v88, 304, v84
	v_cmp_gt_u32_e64 s[50:51], s98, v88
	v_cndmask_b32_e64 v40, 0, v40, s[30:31]
	v_add_u32_e32 v85, 384, v84
	v_cmp_gt_u32_e64 s[30:31], s98, v85
	v_cndmask_b32_e64 v41, 0, v41, s[36:37]
	v_add_u32_e32 v86, 400, v84
	v_cmp_gt_u32_e64 s[36:37], s98, v86
	v_cndmask_b32_e64 v42, 0, v42, s[78:79]
	v_add_u32_e32 v87, 416, v84
	v_cmp_gt_u32_e64 s[78:79], s98, v87
	v_cndmask_b32_e64 v43, 0, v43, s[50:51]
	v_add_u32_e32 v88, 432, v84
	v_cmp_gt_u32_e64 s[50:51], s98, v88
	v_nop
	v_cndmask_b32_e64 v44, 0, v44, s[30:31]
	v_cndmask_b32_e64 v45, 0, v45, s[36:37]
	v_cndmask_b32_e64 v46, 0, v46, s[78:79]
	v_cndmask_b32_e64 v47, 0, v47, s[50:51]
	v_cvt_pk_bf16_f32 v64, v32, v33
	v_cvt_pk_bf16_f32 v65, v34, v35
	v_cvt_pk_bf16_f32 v66, v36, v37
	v_cvt_pk_bf16_f32 v67, v38, v39
	v_cvt_pk_bf16_f32 v68, v40, v41
	v_cvt_pk_bf16_f32 v69, v42, v43
	v_cvt_pk_bf16_f32 v70, v44, v45
	v_cvt_pk_bf16_f32 v71, v46, v47
	v_pk_add_f32 v[232:233], v[232:233], v[32:33]
	v_pk_add_f32 v[232:233], v[232:233], v[34:35]
	v_pk_add_f32 v[232:233], v[232:233], v[36:37]
	v_pk_add_f32 v[232:233], v[232:233], v[38:39]
	v_pk_add_f32 v[232:233], v[232:233], v[40:41]
	v_pk_add_f32 v[232:233], v[232:233], v[42:43]
	v_pk_add_f32 v[232:233], v[232:233], v[44:45]
	v_pk_add_f32 v[232:233], v[232:233], v[46:47]
	v_mfma_f32_32x32x16_bf16 v[0:15], v[64:67], v[72:75], v[0:15]
	v_mfma_f32_32x32x16_bf16 v[16:31], v[64:67], v[76:79], v[16:31]
	v_mfma_f32_32x32x16_bf16 v[0:15], v[68:71], v[220:223], v[0:15]
	v_mfma_f32_32x32x16_bf16 v[16:31], v[68:71], v[224:227], v[16:31]
	v_add_f32_e32 v113, v232, v233
	v_or_b32_e32 v114, 1, v107
	v_or_b32_e32 v97, 2, v107
	v_or_b32_e32 v96, 3, v107
	v_or_b32_e32 v95, 8, v107
	v_or_b32_e32 v94, 9, v107
	v_or_b32_e32 v93, 10, v107
	v_or_b32_e32 v92, 11, v107
	v_or_b32_e32 v91, 16, v107
	v_or_b32_e32 v90, 17, v107
	v_or_b32_e32 v89, 18, v107
	v_or_b32_e32 v88, 19, v107
	v_or_b32_e32 v87, 24, v107
	v_or_b32_e32 v86, 25, v107
	v_or_b32_e32 v85, 26, v107
	v_or_b32_e32 v84, 27, v107
	s_nop 11
	s_branch .LBB0_1265
